# all global-address flat_load/flat_store rewritten as global_load/global_store so LDS and scalar waits no longer stall on outstanding vector memory ops
# speedup vs baseline: 1.0051x; 1.0051x over previous
.LBB0_27:
	v_add_u32_e32 v1, s38, v32
	v_add_u32_e32 v2, s35, v32
	v_cmp_lt_i32_e32 vcc, s6, v1
	v_add_u32_e32 v0, 0xfffff000, v32
	v_add_u32_e32 v3, s33, v32
	v_cndmask_b32_e32 v88, v1, v32, vcc
	v_cmp_lt_i32_e32 vcc, s6, v2
	v_ashrrev_i32_e32 v4, 10, v0
	v_add_u32_e32 v1, 1, v4
	v_cndmask_b32_e32 v46, v2, v32, vcc
	v_cmp_lt_i32_e32 vcc, s6, v3
	v_add_u32_e32 v6, 0xfffff000, v88
	v_ashrrev_i32_e32 v5, 10, v6
	v_cndmask_b32_e32 v44, v3, v32, vcc
	v_cmp_gt_i32_e32 vcc, s2, v32
	s_waitcnt lgkmcnt(0)
	v_mov_b32_e32 v12, s87
	v_mov_b32_e32 v13, s85
	v_cndmask_b32_e64 v4, v1, 0, vcc
	v_mov_b32_e32 v14, s86
	v_mov_b32_e32 v15, s84
	v_cndmask_b32_e32 v1, 0, v33, vcc
	v_cndmask_b32_e32 v0, v0, v32, vcc
	v_add_u32_e32 v10, 1, v5
	v_mul_hi_i32_i24_e32 v5, 0x9000, v4
	v_mul_i32_i24_e32 v4, 0x9000, v4
	v_cndmask_b32_e32 v3, v12, v13, vcc
	v_cndmask_b32_e32 v2, v14, v15, vcc
	v_lshlrev_b64 v[0:1], 12, v[0:1]
	v_lshl_add_u64 v[4:5], s[60:61], 0, v[4:5]
	v_lshl_add_u64 v[0:1], v[2:3], 0, v[0:1]
	v_lshl_add_u64 v[90:91], v[4:5], 0, s[30:31]
	v_lshl_add_u64 v[92:93], v[4:5], 0, v[152:153]
	v_lshl_add_u64 v[0:1], v[0:1], 0, v[152:153]
	v_lshl_add_u64 v[4:5], v[90:91], 0, v[152:153]
	global_load_dwordx4 v[154:157], v[92:93], off offset:1024
	global_load_dwordx4 v[158:161], v[92:93], off offset:2048
	global_load_dwordx4 v[162:165], v[92:93], off offset:3072
	global_load_dwordx4 v[48:51], v[92:93], off
	global_load_dwordx4 v[166:169], v[4:5], off offset:1024
	global_load_dwordx4 v[170:173], v[4:5], off offset:2048
	global_load_dwordx4 v[174:177], v[4:5], off offset:3072
	global_load_dwordx4 v[52:55], v[4:5], off
	global_load_dwordx4 v[56:59], v[0:1], off
	v_add_u32_e32 v16, 0xfffff000, v44
	v_add_u32_e32 v8, 0xfffff000, v46
	v_ashrrev_i32_e32 v9, 10, v16
	v_ashrrev_i32_e32 v89, 31, v88
	v_ashrrev_i32_e32 v47, 31, v46
	v_ashrrev_i32_e32 v7, 10, v8
	v_cmp_gt_i32_e32 vcc, s2, v46
	v_add_u32_e32 v9, 1, v9
	v_cmp_gt_i32_e64 s[8:9], s2, v44
	v_cmp_gt_i32_e64 s[10:11], s2, v88
	v_ashrrev_i32_e32 v45, 31, v44
	v_add_u32_e32 v7, 1, v7
	v_cndmask_b32_e64 v100, v9, 0, s[8:9]
	v_cndmask_b32_e64 v3, 0, v89, s[10:11]
	v_cndmask_b32_e64 v2, v6, v88, s[10:11]
	v_cndmask_b32_e32 v9, 0, v47, vcc
	v_cndmask_b32_e32 v8, v8, v46, vcc
	v_cndmask_b32_e64 v98, v10, 0, s[10:11]
	v_cndmask_b32_e64 v99, v7, 0, vcc
	v_cndmask_b32_e64 v7, v12, v13, s[10:11]
	v_cndmask_b32_e64 v6, v14, v15, s[10:11]
	v_cndmask_b32_e32 v11, v12, v13, vcc
	v_cndmask_b32_e32 v10, v14, v15, vcc
	v_cndmask_b32_e64 v5, 0, v45, s[8:9]
	v_cndmask_b32_e64 v4, v16, v44, s[8:9]
	v_lshlrev_b64 v[2:3], 12, v[2:3]
	v_lshlrev_b64 v[8:9], 12, v[8:9]
	v_cndmask_b32_e64 v13, v12, v13, s[8:9]
	v_cndmask_b32_e64 v12, v14, v15, s[8:9]
	v_lshlrev_b64 v[4:5], 12, v[4:5]
	global_load_dwordx4 v[60:63], v[0:1], off offset:1024
	global_load_dwordx4 v[64:67], v[0:1], off offset:2048
	global_load_dwordx4 v[68:71], v[0:1], off offset:3072
	v_lshl_add_u64 v[0:1], v[6:7], 0, v[2:3]
	v_lshl_add_u64 v[2:3], v[10:11], 0, v[8:9]
	v_mov_b32_e32 v39, v153
	v_lshl_add_u64 v[4:5], v[12:13], 0, v[4:5]
	v_lshl_add_u64 v[0:1], v[0:1], 0, v[152:153]
	v_lshl_add_u64 v[2:3], v[2:3], 0, v[152:153]
	v_lshl_add_u64 v[94:95], v[90:91], 0, v[38:39]
	v_lshl_add_u64 v[96:97], v[4:5], 0, v[152:153]
	global_load_dwordx4 v[72:75], v[0:1], off
	global_load_dwordx4 v[76:79], v[0:1], off offset:1024
	global_load_dwordx4 v[80:83], v[0:1], off offset:2048
	global_load_dwordx4 v[84:87], v[0:1], off offset:3072
	global_load_dwordx4 v[28:31], v[2:3], off
	global_load_dwordx4 v[24:27], v[2:3], off offset:1024
	global_load_dwordx4 v[20:23], v[2:3], off offset:2048
	global_load_dwordx4 v[16:19], v[2:3], off offset:3072
	global_load_dwordx4 v[12:15], v[96:97], off
	global_load_dwordx4 v[8:11], v[96:97], off offset:1024
	global_load_dwordx4 v[4:7], v[96:97], off offset:2048
	s_nop 0
	global_load_dwordx4 v[0:3], v[96:97], off offset:3072
	v_mov_b32_e32 v41, v153
	v_mov_b32_e32 v43, v153
	v_lshlrev_b64 v[46:47], 11, v[46:47]
	v_lshl_add_u64 v[32:33], v[32:33], 0, s[96:97]
	v_cmp_lt_i32_e32 vcc, s6, v32
	s_or_b64 s[16:17], vcc, s[16:17]
	s_waitcnt vmcnt(0) lgkmcnt(0)
	v_pk_add_f32 v[54:55], v[54:55], 1.0 op_sel_hi:[1,0]
	v_pk_add_f32 v[52:53], v[52:53], 1.0 op_sel_hi:[1,0]
	v_pk_fma_f32 v[50:51], v[58:59], v[54:55], v[50:51]
	v_pk_fma_f32 v[48:49], v[56:57], v[52:53], v[48:49]
	v_lshl_add_u64 v[56:57], v[90:91], 0, v[40:41]
	v_cvt_pk_bf16_f32 v48, v48, v49
	v_cvt_pk_bf16_f32 v49, v50, v51
	global_store_dwordx2 v[36:37], v[48:49], off
	v_mov_b64_e32 v[48:49], v[166:167]
	v_mov_b64_e32 v[50:51], v[168:169]
	s_nop 0
	v_mov_b64_e32 v[52:53], v[154:155]
	v_mov_b64_e32 v[54:55], v[156:157]
	v_pk_add_f32 v[50:51], v[50:51], 1.0 op_sel_hi:[1,0]
	v_pk_add_f32 v[48:49], v[48:49], 1.0 op_sel_hi:[1,0]
	v_pk_fma_f32 v[50:51], v[62:63], v[50:51], v[54:55]
	v_pk_fma_f32 v[48:49], v[60:61], v[48:49], v[52:53]
	s_nop 0
	v_cvt_pk_bf16_f32 v48, v48, v49
	v_cvt_pk_bf16_f32 v49, v50, v51
	global_store_dwordx2 v[36:37], v[48:49], off offset:512
	v_mov_b64_e32 v[48:49], v[170:171]
	v_mov_b64_e32 v[50:51], v[172:173]
	s_nop 0
	v_mov_b64_e32 v[52:53], v[158:159]
	v_mov_b64_e32 v[54:55], v[160:161]
	v_lshl_add_u64 v[56:57], v[90:91], 0, v[42:43]
	v_pk_add_f32 v[50:51], v[50:51], 1.0 op_sel_hi:[1,0]
	v_pk_add_f32 v[48:49], v[48:49], 1.0 op_sel_hi:[1,0]
	v_pk_fma_f32 v[50:51], v[66:67], v[50:51], v[54:55]
	v_pk_fma_f32 v[48:49], v[64:65], v[48:49], v[52:53]
	s_nop 0
	v_cvt_pk_bf16_f32 v48, v48, v49
	v_cvt_pk_bf16_f32 v49, v50, v51
	global_store_dwordx2 v[36:37], v[48:49], off offset:1024
	v_mov_b64_e32 v[48:49], v[174:175]
	v_mov_b64_e32 v[50:51], v[176:177]
	s_nop 0
	v_mov_b64_e32 v[52:53], v[162:163]
	v_mov_b64_e32 v[54:55], v[164:165]
	v_mul_hi_i32_i24_e32 v57, 0x9000, v98
	v_mul_i32_i24_e32 v56, 0x9000, v98
	v_lshl_add_u64 v[56:57], s[60:61], 0, v[56:57]
	v_lshl_add_u64 v[58:59], v[56:57], 0, s[30:31]
	v_lshl_add_u64 v[60:61], v[58:59], 0, v[152:153]
	v_lshl_add_u64 v[56:57], v[56:57], 0, v[152:153]
	v_lshl_add_u64 v[62:63], v[58:59], 0, v[38:39]
	v_pk_add_f32 v[50:51], v[50:51], 1.0 op_sel_hi:[1,0]
	v_pk_add_f32 v[48:49], v[48:49], 1.0 op_sel_hi:[1,0]
	v_pk_fma_f32 v[50:51], v[70:71], v[50:51], v[54:55]
	v_pk_fma_f32 v[48:49], v[68:69], v[48:49], v[52:53]
	s_nop 0
	v_cvt_pk_bf16_f32 v48, v48, v49
	v_cvt_pk_bf16_f32 v49, v50, v51
	global_store_dwordx2 v[36:37], v[48:49], off offset:1536
	global_load_dwordx4 v[154:157], v[60:61], off offset:1024
	global_load_dwordx4 v[158:161], v[60:61], off offset:2048
	global_load_dwordx4 v[162:165], v[60:61], off offset:3072
	global_load_dwordx4 v[48:51], v[60:61], off
	s_nop 0
	global_load_dwordx4 v[166:169], v[56:57], off offset:1024
	global_load_dwordx4 v[170:173], v[56:57], off offset:2048
	global_load_dwordx4 v[174:177], v[56:57], off offset:3072
	global_load_dwordx4 v[52:55], v[56:57], off
	v_lshlrev_b64 v[60:61], 11, v[88:89]
	v_lshl_add_u64 v[60:61], v[34:35], 0, v[60:61]
	v_lshl_add_u64 v[36:37], v[36:37], 0, s[22:23]
	s_waitcnt vmcnt(0) lgkmcnt(0)
	v_pk_add_f32 v[50:51], v[50:51], 1.0 op_sel_hi:[1,0]
	v_pk_add_f32 v[48:49], v[48:49], 1.0 op_sel_hi:[1,0]
	v_pk_fma_f32 v[50:51], v[74:75], v[50:51], v[54:55]
	v_pk_fma_f32 v[48:49], v[72:73], v[48:49], v[52:53]
	s_nop 0
	v_cvt_pk_bf16_f32 v48, v48, v49
	v_cvt_pk_bf16_f32 v49, v50, v51
	global_store_dwordx2 v[60:61], v[48:49], off
	v_mov_b64_e32 v[48:49], v[154:155]
	v_mov_b64_e32 v[50:51], v[156:157]
	s_nop 0
	v_mov_b64_e32 v[52:53], v[166:167]
	v_mov_b64_e32 v[54:55], v[168:169]
	v_lshl_add_u64 v[62:63], v[58:59], 0, v[40:41]
	v_lshl_add_u64 v[58:59], v[58:59], 0, v[42:43]
	v_pk_add_f32 v[50:51], v[50:51], 1.0 op_sel_hi:[1,0]
	v_pk_add_f32 v[48:49], v[48:49], 1.0 op_sel_hi:[1,0]
	v_pk_fma_f32 v[50:51], v[78:79], v[50:51], v[54:55]
	v_pk_fma_f32 v[48:49], v[76:77], v[48:49], v[52:53]
	s_nop 0
	v_cvt_pk_bf16_f32 v48, v48, v49
	v_cvt_pk_bf16_f32 v49, v50, v51
	global_store_dwordx2 v[60:61], v[48:49], off offset:512
	v_mov_b64_e32 v[48:49], v[158:159]
	v_mov_b64_e32 v[50:51], v[160:161]
	s_nop 0
	v_mov_b64_e32 v[52:53], v[170:171]
	v_mov_b64_e32 v[54:55], v[172:173]
	v_pk_add_f32 v[50:51], v[50:51], 1.0 op_sel_hi:[1,0]
	v_pk_add_f32 v[48:49], v[48:49], 1.0 op_sel_hi:[1,0]
	v_pk_fma_f32 v[50:51], v[82:83], v[50:51], v[54:55]
	v_pk_fma_f32 v[48:49], v[80:81], v[48:49], v[52:53]
	s_nop 0
	v_cvt_pk_bf16_f32 v48, v48, v49
	v_cvt_pk_bf16_f32 v49, v50, v51
	global_store_dwordx2 v[60:61], v[48:49], off offset:1024
	v_mov_b64_e32 v[48:49], v[162:163]
	v_mov_b64_e32 v[50:51], v[164:165]
	s_nop 0
	v_mov_b64_e32 v[52:53], v[174:175]
	v_mov_b64_e32 v[54:55], v[176:177]
	v_mul_hi_i32_i24_e32 v57, 0x9000, v99
	v_mul_i32_i24_e32 v56, 0x9000, v99
	v_lshl_add_u64 v[56:57], s[60:61], 0, v[56:57]
	v_lshl_add_u64 v[58:59], v[56:57], 0, s[30:31]
	v_lshl_add_u64 v[62:63], v[58:59], 0, v[152:153]
	v_lshl_add_u64 v[56:57], v[56:57], 0, v[152:153]
	v_pk_add_f32 v[50:51], v[50:51], 1.0 op_sel_hi:[1,0]
	v_pk_add_f32 v[48:49], v[48:49], 1.0 op_sel_hi:[1,0]
	v_pk_fma_f32 v[50:51], v[86:87], v[50:51], v[54:55]
	v_pk_fma_f32 v[48:49], v[84:85], v[48:49], v[52:53]
	s_nop 0
	v_cvt_pk_bf16_f32 v48, v48, v49
	v_cvt_pk_bf16_f32 v49, v50, v51
	global_store_dwordx2 v[60:61], v[48:49], off offset:1536
	global_load_dwordx4 v[154:157], v[62:63], off offset:1024
	global_load_dwordx4 v[158:161], v[62:63], off offset:2048
	global_load_dwordx4 v[162:165], v[62:63], off offset:3072
	global_load_dwordx4 v[48:51], v[62:63], off
	s_nop 0
	global_load_dwordx4 v[166:169], v[56:57], off offset:1024
	global_load_dwordx4 v[170:173], v[56:57], off offset:2048
	global_load_dwordx4 v[174:177], v[56:57], off offset:3072
	global_load_dwordx4 v[52:55], v[56:57], off
	v_lshl_add_u64 v[60:61], v[34:35], 0, v[46:47]
	v_lshl_add_u64 v[46:47], v[58:59], 0, v[38:39]
	s_waitcnt vmcnt(0) lgkmcnt(0)
	v_pk_add_f32 v[50:51], v[50:51], 1.0 op_sel_hi:[1,0]
	v_pk_add_f32 v[48:49], v[48:49], 1.0 op_sel_hi:[1,0]
	v_pk_fma_f32 v[30:31], v[30:31], v[50:51], v[54:55]
	v_pk_fma_f32 v[28:29], v[28:29], v[48:49], v[52:53]
	v_lshl_add_u64 v[50:51], v[58:59], 0, v[40:41]
	v_cvt_pk_bf16_f32 v28, v28, v29
	v_cvt_pk_bf16_f32 v29, v30, v31
	global_store_dwordx2 v[60:61], v[28:29], off
	v_mov_b64_e32 v[28:29], v[154:155]
	v_mov_b64_e32 v[30:31], v[156:157]
	s_nop 0
	v_mov_b64_e32 v[46:47], v[166:167]
	v_mov_b64_e32 v[48:49], v[168:169]
	v_pk_add_f32 v[30:31], v[30:31], 1.0 op_sel_hi:[1,0]
	v_pk_add_f32 v[28:29], v[28:29], 1.0 op_sel_hi:[1,0]
	v_pk_fma_f32 v[26:27], v[26:27], v[30:31], v[48:49]
	v_pk_fma_f32 v[24:25], v[24:25], v[28:29], v[46:47]
	v_lshl_add_u64 v[46:47], v[58:59], 0, v[42:43]
	v_cvt_pk_bf16_f32 v24, v24, v25
	v_cvt_pk_bf16_f32 v25, v26, v27
	global_store_dwordx2 v[60:61], v[24:25], off offset:512
	v_mov_b64_e32 v[24:25], v[158:159]
	v_mov_b64_e32 v[26:27], v[160:161]
	s_nop 0
	v_mov_b64_e32 v[28:29], v[170:171]
	v_mov_b64_e32 v[30:31], v[172:173]
	v_pk_add_f32 v[26:27], v[26:27], 1.0 op_sel_hi:[1,0]
	v_pk_add_f32 v[24:25], v[24:25], 1.0 op_sel_hi:[1,0]
	v_pk_fma_f32 v[22:23], v[22:23], v[26:27], v[30:31]
	v_pk_fma_f32 v[20:21], v[20:21], v[24:25], v[28:29]
	v_mul_hi_i32_i24_e32 v29, 0x9000, v100
	v_cvt_pk_bf16_f32 v20, v20, v21
	v_cvt_pk_bf16_f32 v21, v22, v23
	global_store_dwordx2 v[60:61], v[20:21], off offset:1024
	v_mov_b64_e32 v[20:21], v[162:163]
	v_mov_b64_e32 v[22:23], v[164:165]
	s_nop 0
	v_mov_b64_e32 v[24:25], v[174:175]
	v_mov_b64_e32 v[26:27], v[176:177]
	v_mul_i32_i24_e32 v28, 0x9000, v100
	v_lshl_add_u64 v[28:29], s[60:61], 0, v[28:29]
	v_lshl_add_u64 v[30:31], v[28:29], 0, s[30:31]
	v_lshl_add_u64 v[46:47], v[30:31], 0, v[152:153]
	v_lshl_add_u64 v[28:29], v[28:29], 0, v[152:153]
	v_pk_add_f32 v[22:23], v[22:23], 1.0 op_sel_hi:[1,0]
	v_pk_add_f32 v[20:21], v[20:21], 1.0 op_sel_hi:[1,0]
	v_pk_fma_f32 v[18:19], v[18:19], v[22:23], v[26:27]
	v_pk_fma_f32 v[16:17], v[16:17], v[20:21], v[24:25]
	v_lshlrev_b64 v[24:25], 11, v[44:45]
	v_cvt_pk_bf16_f32 v16, v16, v17
	v_cvt_pk_bf16_f32 v17, v18, v19
	global_store_dwordx2 v[60:61], v[16:17], off offset:1536
	global_load_dwordx4 v[154:157], v[46:47], off offset:1024
	global_load_dwordx4 v[158:161], v[46:47], off offset:2048
	global_load_dwordx4 v[162:165], v[46:47], off offset:3072
	global_load_dwordx4 v[16:19], v[46:47], off
	s_nop 0
	global_load_dwordx4 v[166:169], v[28:29], off offset:1024
	global_load_dwordx4 v[170:173], v[28:29], off offset:2048
	global_load_dwordx4 v[174:177], v[28:29], off offset:3072
	global_load_dwordx4 v[20:23], v[28:29], off
	v_lshl_add_u64 v[24:25], v[34:35], 0, v[24:25]
	v_lshl_add_u64 v[26:27], v[30:31], 0, v[38:39]
	s_waitcnt vmcnt(0) lgkmcnt(0)
	v_pk_add_f32 v[18:19], v[18:19], 1.0 op_sel_hi:[1,0]
	v_pk_add_f32 v[16:17], v[16:17], 1.0 op_sel_hi:[1,0]
	v_pk_fma_f32 v[14:15], v[14:15], v[18:19], v[22:23]
	v_pk_fma_f32 v[12:13], v[12:13], v[16:17], v[20:21]
	v_lshl_add_u64 v[20:21], v[30:31], 0, v[40:41]
	v_cvt_pk_bf16_f32 v12, v12, v13
	v_cvt_pk_bf16_f32 v13, v14, v15
	global_store_dwordx2 v[24:25], v[12:13], off
	v_mov_b64_e32 v[12:13], v[154:155]
	v_mov_b64_e32 v[14:15], v[156:157]
	s_nop 0
	v_mov_b64_e32 v[16:17], v[166:167]
	v_mov_b64_e32 v[18:19], v[168:169]
	v_pk_add_f32 v[14:15], v[14:15], 1.0 op_sel_hi:[1,0]
	v_pk_add_f32 v[12:13], v[12:13], 1.0 op_sel_hi:[1,0]
	v_pk_fma_f32 v[10:11], v[10:11], v[14:15], v[18:19]
	v_pk_fma_f32 v[8:9], v[8:9], v[12:13], v[16:17]
	v_lshl_add_u64 v[16:17], v[30:31], 0, v[42:43]
	v_cvt_pk_bf16_f32 v8, v8, v9
	v_cvt_pk_bf16_f32 v9, v10, v11
	global_store_dwordx2 v[24:25], v[8:9], off offset:512
	v_mov_b64_e32 v[8:9], v[158:159]
	v_mov_b64_e32 v[10:11], v[160:161]
	s_nop 0
	v_mov_b64_e32 v[12:13], v[170:171]
	v_mov_b64_e32 v[14:15], v[172:173]
	v_pk_add_f32 v[10:11], v[10:11], 1.0 op_sel_hi:[1,0]
	v_pk_add_f32 v[8:9], v[8:9], 1.0 op_sel_hi:[1,0]
	v_pk_fma_f32 v[6:7], v[6:7], v[10:11], v[14:15]
	v_pk_fma_f32 v[4:5], v[4:5], v[8:9], v[12:13]
	s_nop 0
	v_cvt_pk_bf16_f32 v4, v4, v5
	v_cvt_pk_bf16_f32 v5, v6, v7
	global_store_dwordx2 v[24:25], v[4:5], off offset:1024
	v_mov_b64_e32 v[4:5], v[162:163]
	v_mov_b64_e32 v[6:7], v[164:165]
	s_nop 0
	v_mov_b64_e32 v[8:9], v[174:175]
	v_mov_b64_e32 v[10:11], v[176:177]
	v_pk_add_f32 v[6:7], v[6:7], 1.0 op_sel_hi:[1,0]
	v_pk_add_f32 v[4:5], v[4:5], 1.0 op_sel_hi:[1,0]
	v_pk_fma_f32 v[2:3], v[2:3], v[6:7], v[10:11]
	v_pk_fma_f32 v[0:1], v[0:1], v[4:5], v[8:9]
	s_nop 0
	v_cvt_pk_bf16_f32 v0, v0, v1
	v_cvt_pk_bf16_f32 v1, v2, v3
	global_store_dwordx2 v[24:25], v[0:1], off offset:1536
	s_andn2_b64 exec, exec, s[16:17]
	s_cbranch_execnz .LBB0_27

.LBB0_51:
	global_load_dwordx4 v[154:157], v[74:75], off
	global_load_dwordx4 v[158:161], v[76:77], off
	global_load_dwordx4 v[162:165], v[74:75], off offset:1024
	global_load_dwordx4 v[166:169], v[76:77], off offset:1024
	global_load_dwordx4 v[170:173], v[74:75], off offset:2048
	global_load_dwordx4 v[174:177], v[76:77], off offset:2048
	global_load_dwordx4 v[178:181], v[74:75], off offset:3072
	global_load_dwordx4 v[182:185], v[76:77], off offset:3072
	v_add_u32_e32 v0, 0xfffff000, v64
	v_ashrrev_i32_e32 v0, 10, v0
	v_add_u32_e32 v0, 1, v0
	v_cmp_lt_i32_e32 vcc, s33, v64
	s_mov_b32 s2, 0x1000000
	global_load_dwordx4 v[186:189], v[86:87], off offset:1024
	global_load_dwordx4 v[190:193], v[86:87], off offset:2048
	global_load_dwordx4 v[194:197], v[86:87], off offset:3072
	global_load_dwordx4 v[8:11], v[86:87], off
	v_cndmask_b32_e32 v4, 0, v0, vcc
	v_add_u32_e32 v0, s38, v64
	v_cmp_lt_i32_e32 vcc, s6, v0
	v_ashrrev_i32_e32 v5, 31, v4
	v_lshl_add_u64 v[88:89], v[4:5], 0, s[28:29]
	v_cndmask_b32_e32 v0, v0, v64, vcc
	v_add_u32_e32 v1, 0xfffff000, v0
	v_ashrrev_i32_e32 v1, 10, v1
	v_add_u32_e32 v1, 1, v1
	v_cmp_lt_i32_e32 vcc, s33, v0
	v_mad_u64_u32 v[4:5], s[4:5], v88, s7, v[78:79]
	s_nop 0
	v_cndmask_b32_e32 v2, 0, v1, vcc
	v_add_u32_e32 v1, s35, v64
	v_cmp_lt_i32_e32 vcc, s6, v1
	v_mad_i32_i24 v5, v89, s7, v5
	global_load_dwordx4 v[198:201], v[4:5], off offset:1024
	global_load_dwordx4 v[202:205], v[4:5], off offset:2048
	global_load_dwordx4 v[224:227], v[4:5], off offset:3072
	global_load_dwordx4 v[12:15], v[4:5], off
	v_cndmask_b32_e32 v40, v1, v64, vcc
	v_add_u32_e32 v1, 0xfffff000, v40
	v_ashrrev_i32_e32 v1, 10, v1
	v_add_u32_e32 v1, 1, v1
	v_cmp_lt_i32_e32 vcc, s33, v40
	v_ashrrev_i32_e32 v3, 31, v2
	v_lshl_add_u64 v[92:93], v[2:3], 0, s[28:29]
	v_cndmask_b32_e32 v42, 0, v1, vcc
	v_add_u32_e32 v1, s26, v64
	v_cmp_lt_i32_e32 vcc, s6, v1
	s_mov_b64 s[8:9], 0x1000000
	v_mad_u64_u32 v[48:49], s[4:5], v92, s7, v[78:79]
	v_cndmask_b32_e32 v20, v1, v64, vcc
	v_add_u32_e32 v1, 0xfffff000, v20
	v_ashrrev_i32_e32 v1, 10, v1
	v_add_u32_e32 v1, 1, v1
	v_cmp_lt_i32_e32 vcc, s33, v20
	v_lshlrev_b32_e32 v152, 1, v66
	v_mad_i32_i24 v49, v93, s7, v49
	v_cndmask_b32_e32 v22, 0, v1, vcc
	v_add_co_u32_e32 v6, vcc, s2, v84
	s_brev_b32 s2, 64
	s_nop 0
	v_addc_co_u32_e32 v7, vcc, 0, v85, vcc
	v_add_co_u32_e32 v24, vcc, s2, v84
	global_load_dwordx2 v[228:229], v[6:7], off offset:512
	global_load_dwordx2 v[230:231], v[6:7], off offset:1024
	global_load_dwordx2 v[232:233], v[6:7], off offset:1536
	global_load_dwordx2 v[16:17], v[6:7], off
	s_nop 0
	v_addc_co_u32_e32 v25, vcc, 0, v85, vcc
	global_load_dwordx2 v[234:235], v[24:25], off offset:512
	global_load_dwordx2 v[236:237], v[24:25], off offset:1024
	global_load_dwordx2 v[238:239], v[24:25], off offset:1536
	global_load_dwordx2 v[26:27], v[24:25], off
	v_lshlrev_b32_e32 v104, 1, v68
	v_mov_b32_e32 v105, v153
	v_lshlrev_b32_e32 v106, 1, v70
	v_mov_b32_e32 v107, v153
	v_lshlrev_b32_e32 v120, 1, v72
	v_mov_b32_e32 v121, v153
	v_ashrrev_i32_e32 v41, 31, v40
	v_ashrrev_i32_e32 v43, 31, v42
	v_lshlrev_b64 v[96:97], 11, v[40:41]
	v_lshl_add_u64 v[98:99], v[42:43], 0, s[28:29]
	v_lshl_add_u64 v[42:43], s[56:57], 0, v[96:97]
	v_ashrrev_i32_e32 v21, 31, v20
	v_ashrrev_i32_e32 v23, 31, v22
	s_mov_b32 s2, 0x3727c5ac
	s_waitcnt vmcnt(0) lgkmcnt(0)
	v_lshlrev_b32_e32 v18, 16, v16
	v_and_b32_e32 v19, 0xffff0000, v16
	v_lshlrev_b32_e32 v16, 16, v17
	v_and_b32_e32 v17, 0xffff0000, v17
	v_lshlrev_b32_e32 v28, 16, v26
	v_and_b32_e32 v29, 0xffff0000, v26
	v_lshlrev_b32_e32 v26, 16, v27
	v_and_b32_e32 v27, 0xffff0000, v27
	v_pk_add_f32 v[18:19], v[18:19], v[28:29]
	v_pk_add_f32 v[16:17], v[16:17], v[26:27]
	v_pk_mul_f32 v[12:13], v[12:13], v[18:19]
	v_pk_mul_f32 v[14:15], v[14:15], v[16:17]
	v_pk_fma_f32 v[8:9], v[8:9], s[42:43], v[12:13] op_sel_hi:[1,0,1]
	v_pk_fma_f32 v[10:11], v[10:11], s[42:43], v[14:15] op_sel_hi:[1,0,1]
	v_mov_b32_e32 v14, v8
	v_pk_mov_b32 v[12:13], v[8:9], v[10:11] op_sel:[1,0]
	v_mov_b32_e32 v15, v11
	v_pk_add_f32 v[12:13], v[12:13], v[14:15]
	s_nop 0
	v_add_f32_e32 v1, v12, v13
	v_mov_b64_e32 v[12:13], v[186:187]
	v_mov_b64_e32 v[14:15], v[188:189]
	v_mov_b64_e32 v[16:17], v[198:199]
	v_mov_b64_e32 v[18:19], v[200:201]
	v_mov_b64_e32 v[26:27], v[228:229]
	v_mov_b64_e32 v[32:33], v[234:235]
	v_add_f32_e32 v28, 0, v1
	v_ashrrev_i32_e32 v1, 31, v0
	v_lshlrev_b64 v[90:91], 11, v[0:1]
	v_lshlrev_b64 v[2:3], 12, v[0:1]
	v_lshlrev_b32_e32 v30, 16, v26
	v_and_b32_e32 v31, 0xffff0000, v26
	v_lshlrev_b32_e32 v26, 16, v27
	v_and_b32_e32 v27, 0xffff0000, v27
	v_lshlrev_b32_e32 v34, 16, v32
	v_and_b32_e32 v35, 0xffff0000, v32
	v_lshlrev_b32_e32 v32, 16, v33
	v_and_b32_e32 v33, 0xffff0000, v33
	v_pk_add_f32 v[30:31], v[30:31], v[34:35]
	v_pk_add_f32 v[26:27], v[26:27], v[32:33]
	v_pk_mul_f32 v[16:17], v[16:17], v[30:31]
	v_pk_mul_f32 v[18:19], v[18:19], v[26:27]
	v_pk_fma_f32 v[12:13], v[12:13], s[42:43], v[16:17] op_sel_hi:[1,0,1]
	v_pk_fma_f32 v[14:15], v[14:15], s[42:43], v[18:19] op_sel_hi:[1,0,1]
	v_mov_b32_e32 v18, v12
	v_pk_mov_b32 v[16:17], v[12:13], v[14:15] op_sel:[1,0]
	v_mov_b32_e32 v19, v15
	v_pk_add_f32 v[16:17], v[16:17], v[18:19]
	s_nop 0
	v_pk_add_f32 v[30:31], v[16:17], v[16:17] op_sel:[0,1] op_sel_hi:[1,0]
	v_mov_b64_e32 v[16:17], v[190:191]
	v_mov_b64_e32 v[18:19], v[192:193]
	v_mov_b64_e32 v[32:33], v[202:203]
	v_mov_b64_e32 v[34:35], v[204:205]
	v_mov_b64_e32 v[26:27], v[230:231]
	v_mov_b64_e32 v[38:39], v[236:237]
	v_lshlrev_b32_e32 v36, 16, v26
	v_and_b32_e32 v37, 0xffff0000, v26
	v_lshlrev_b32_e32 v44, 16, v38
	v_and_b32_e32 v45, 0xffff0000, v38
	v_lshlrev_b32_e32 v26, 16, v27
	v_and_b32_e32 v27, 0xffff0000, v27
	v_lshlrev_b32_e32 v38, 16, v39
	v_and_b32_e32 v39, 0xffff0000, v39
	v_pk_add_f32 v[36:37], v[36:37], v[44:45]
	v_pk_add_f32 v[26:27], v[26:27], v[38:39]
	v_pk_mul_f32 v[32:33], v[32:33], v[36:37]
	v_pk_mul_f32 v[26:27], v[34:35], v[26:27]
	v_pk_fma_f32 v[16:17], v[16:17], s[42:43], v[32:33] op_sel_hi:[1,0,1]
	v_mov_b64_e32 v[32:33], v[194:195]
	v_mov_b64_e32 v[34:35], v[196:197]
	v_mov_b64_e32 v[36:37], v[224:225]
	v_mov_b64_e32 v[38:39], v[226:227]
	s_nop 0
	v_mov_b64_e32 v[4:5], v[232:233]
	v_pk_fma_f32 v[18:19], v[18:19], s[42:43], v[26:27] op_sel_hi:[1,0,1]
	v_mov_b64_e32 v[24:25], v[238:239]
	v_add_f32_e32 v44, v16, v17
	v_add_f32_e32 v46, v18, v19
	v_lshlrev_b32_e32 v6, 16, v4
	v_and_b32_e32 v7, 0xffff0000, v4
	v_lshlrev_b32_e32 v26, 16, v24
	v_and_b32_e32 v27, 0xffff0000, v24
	v_lshlrev_b32_e32 v4, 16, v5
	v_and_b32_e32 v5, 0xffff0000, v5
	v_lshlrev_b32_e32 v24, 16, v25
	v_and_b32_e32 v25, 0xffff0000, v25
	v_pk_add_f32 v[6:7], v[6:7], v[26:27]
	v_pk_add_f32 v[4:5], v[4:5], v[24:25]
	v_pk_mul_f32 v[6:7], v[36:37], v[6:7]
	v_pk_mul_f32 v[4:5], v[38:39], v[4:5]
	v_pk_fma_f32 v[24:25], v[32:33], s[42:43], v[6:7] op_sel_hi:[1,0,1]
	v_pk_fma_f32 v[26:27], v[34:35], s[42:43], v[4:5] op_sel_hi:[1,0,1]
	v_mov_b32_e32 v29, v24
	v_mov_b32_e32 v31, v25
	v_pk_add_f32 v[4:5], v[28:29], v[30:31]
	v_mov_b32_e32 v45, v26
	v_mov_b32_e32 v47, v27
	v_lshl_add_u64 v[28:29], s[56:57], 0, v[90:91]
	v_pk_add_f32 v[6:7], v[44:45], v[46:47]
	v_lshl_add_u64 v[44:45], v[28:29], 0, s[8:9]
	v_pk_add_f32 v[4:5], v[4:5], v[6:7]
	v_lshl_add_u64 v[52:53], v[28:29], 0, v[152:153]
	v_lshl_add_u64 v[34:35], v[44:45], 0, v[152:153]
	v_add_f32_e32 v122, v4, v5
	global_load_dwordx4 v[186:189], v[48:49], off offset:1024
	global_load_dwordx4 v[190:193], v[48:49], off offset:2048
	global_load_dwordx4 v[194:197], v[48:49], off offset:3072
	global_load_dwordx4 v[4:7], v[48:49], off
	global_load_dwordx2 v[228:229], v[52:53], off offset:512
	global_load_dwordx2 v[230:231], v[52:53], off offset:1024
	global_load_dwordx2 v[232:233], v[52:53], off offset:1536
	global_load_dwordx2 v[28:29], v[52:53], off
	v_lshl_add_u64 v[32:33], v[80:81], 0, v[2:3]
	global_load_dwordx2 v[234:235], v[34:35], off offset:512
	global_load_dwordx2 v[236:237], v[34:35], off offset:1024
	global_load_dwordx2 v[238:239], v[34:35], off offset:1536
	global_load_dwordx2 v[34:35], v[34:35], off
	v_lshl_add_u64 v[38:39], v[44:45], 0, v[104:105]
	global_load_dwordx4 v[198:201], v[32:33], off offset:1024
	global_load_dwordx4 v[202:205], v[32:33], off offset:2048
	global_load_dwordx4 v[224:227], v[32:33], off offset:3072
	global_load_dwordx4 v[0:3], v[32:33], off
	v_lshl_add_u64 v[54:55], v[44:45], 0, v[106:107]
	v_lshl_add_u64 v[44:45], v[44:45], 0, v[120:121]
	s_waitcnt vmcnt(0) lgkmcnt(0)
	v_lshlrev_b32_e32 v30, 16, v28
	v_and_b32_e32 v31, 0xffff0000, v28
	v_lshlrev_b32_e32 v28, 16, v29
	v_and_b32_e32 v29, 0xffff0000, v29
	v_lshlrev_b32_e32 v36, 16, v34
	v_and_b32_e32 v37, 0xffff0000, v34
	v_lshlrev_b32_e32 v34, 16, v35
	v_and_b32_e32 v35, 0xffff0000, v35
	v_pk_add_f32 v[30:31], v[30:31], v[36:37]
	v_pk_add_f32 v[28:29], v[28:29], v[34:35]
	v_pk_mul_f32 v[4:5], v[4:5], v[30:31]
	v_pk_mul_f32 v[6:7], v[6:7], v[28:29]
	v_pk_fma_f32 v[28:29], v[0:1], s[42:43], v[4:5] op_sel_hi:[1,0,1]
	v_pk_fma_f32 v[30:31], v[2:3], s[42:43], v[6:7] op_sel_hi:[1,0,1]
	v_mov_b32_e32 v2, v28
	v_pk_mov_b32 v[0:1], v[28:29], v[30:31] op_sel:[1,0]
	v_mov_b32_e32 v3, v31
	v_pk_add_f32 v[0:1], v[0:1], v[2:3]
	s_nop 0
	v_add_f32_e32 v0, v0, v1
	v_add_f32_e32 v46, 0, v0
	v_mov_b64_e32 v[0:1], v[198:199]
	v_mov_b64_e32 v[2:3], v[200:201]
	v_mov_b64_e32 v[4:5], v[186:187]
	v_mov_b64_e32 v[6:7], v[188:189]
	v_mov_b64_e32 v[34:35], v[228:229]
	v_lshlrev_b32_e32 v36, 16, v34
	v_mov_b64_e32 v[38:39], v[234:235]
	v_and_b32_e32 v37, 0xffff0000, v34
	v_lshlrev_b32_e32 v34, 16, v35
	v_and_b32_e32 v35, 0xffff0000, v35
	v_lshlrev_b32_e32 v50, 16, v38
	v_and_b32_e32 v51, 0xffff0000, v38
	v_lshlrev_b32_e32 v38, 16, v39
	v_and_b32_e32 v39, 0xffff0000, v39
	v_pk_add_f32 v[36:37], v[36:37], v[50:51]
	v_pk_add_f32 v[34:35], v[34:35], v[38:39]
	v_pk_mul_f32 v[4:5], v[4:5], v[36:37]
	v_pk_mul_f32 v[6:7], v[6:7], v[34:35]
	v_pk_fma_f32 v[38:39], v[0:1], s[42:43], v[4:5] op_sel_hi:[1,0,1]
	v_pk_fma_f32 v[60:61], v[2:3], s[42:43], v[6:7] op_sel_hi:[1,0,1]
	v_mov_b32_e32 v2, v38
	v_pk_mov_b32 v[0:1], v[38:39], v[60:61] op_sel:[1,0]
	v_mov_b32_e32 v3, v61
	v_pk_add_f32 v[0:1], v[0:1], v[2:3]
	s_nop 0
	v_pk_add_f32 v[50:51], v[0:1], v[0:1] op_sel:[0,1] op_sel_hi:[1,0]
	v_mov_b64_e32 v[0:1], v[202:203]
	v_mov_b64_e32 v[2:3], v[204:205]
	v_mov_b64_e32 v[4:5], v[190:191]
	v_mov_b64_e32 v[6:7], v[192:193]
	v_mov_b64_e32 v[34:35], v[230:231]
	v_lshlrev_b32_e32 v36, 16, v34
	v_mov_b64_e32 v[54:55], v[236:237]
	v_and_b32_e32 v37, 0xffff0000, v34
	v_lshlrev_b32_e32 v34, 16, v35
	v_and_b32_e32 v35, 0xffff0000, v35
	v_lshlrev_b32_e32 v56, 16, v54
	v_and_b32_e32 v57, 0xffff0000, v54
	v_lshlrev_b32_e32 v54, 16, v55
	v_and_b32_e32 v55, 0xffff0000, v55
	v_pk_add_f32 v[34:35], v[34:35], v[54:55]
	v_pk_add_f32 v[36:37], v[36:37], v[56:57]
	v_pk_mul_f32 v[6:7], v[6:7], v[34:35]
	v_pk_mul_f32 v[4:5], v[4:5], v[36:37]
	v_pk_fma_f32 v[36:37], v[2:3], s[42:43], v[6:7] op_sel_hi:[1,0,1]
	v_pk_fma_f32 v[34:35], v[0:1], s[42:43], v[4:5] op_sel_hi:[1,0,1]
	v_mov_b64_e32 v[0:1], v[224:225]
	v_mov_b64_e32 v[2:3], v[226:227]
	v_mov_b64_e32 v[4:5], v[194:195]
	v_mov_b64_e32 v[6:7], v[196:197]
	s_nop 0
	v_mov_b64_e32 v[52:53], v[232:233]
	v_add_f32_e32 v54, v34, v35
	v_mov_b64_e32 v[44:45], v[238:239]
	v_add_f32_e32 v56, v36, v37
	v_lshlrev_b32_e32 v48, 16, v52
	v_and_b32_e32 v49, 0xffff0000, v52
	v_lshlrev_b32_e32 v58, 16, v44
	v_and_b32_e32 v59, 0xffff0000, v44
	v_lshlrev_b32_e32 v52, 16, v53
	v_and_b32_e32 v53, 0xffff0000, v53
	v_lshlrev_b32_e32 v44, 16, v45
	v_and_b32_e32 v45, 0xffff0000, v45
	v_pk_add_f32 v[48:49], v[48:49], v[58:59]
	v_pk_add_f32 v[44:45], v[52:53], v[44:45]
	v_pk_mul_f32 v[4:5], v[4:5], v[48:49]
	v_pk_mul_f32 v[6:7], v[6:7], v[44:45]
	v_pk_fma_f32 v[62:63], v[0:1], s[42:43], v[4:5] op_sel_hi:[1,0,1]
	v_pk_fma_f32 v[118:119], v[2:3], s[42:43], v[6:7] op_sel_hi:[1,0,1]
	v_mov_b32_e32 v47, v62
	v_mov_b32_e32 v51, v63
	v_pk_add_f32 v[0:1], v[46:47], v[50:51]
	v_mov_b32_e32 v55, v118
	v_mov_b32_e32 v57, v119
	v_lshl_add_u64 v[44:45], v[42:43], 0, s[8:9]
	v_mad_u64_u32 v[46:47], s[4:5], v98, s7, v[78:79]
	v_pk_add_f32 v[2:3], v[54:55], v[56:57]
	v_mad_i32_i24 v47, v99, s7, v47
	v_lshl_add_u64 v[42:43], v[42:43], 0, v[152:153]
	v_lshl_add_u64 v[52:53], v[44:45], 0, v[152:153]
	v_pk_add_f32 v[0:1], v[0:1], v[2:3]
	global_load_dwordx4 v[186:189], v[46:47], off offset:1024
	global_load_dwordx4 v[190:193], v[46:47], off offset:2048
	global_load_dwordx4 v[194:197], v[46:47], off offset:3072
	global_load_dwordx4 v[4:7], v[46:47], off
	global_load_dwordx2 v[228:229], v[42:43], off offset:512
	global_load_dwordx2 v[230:231], v[42:43], off offset:1024
	global_load_dwordx2 v[232:233], v[42:43], off offset:1536
	global_load_dwordx2 v[48:49], v[42:43], off
	v_add_f32_e32 v126, v0, v1
	global_load_dwordx2 v[234:235], v[52:53], off offset:512
	global_load_dwordx2 v[236:237], v[52:53], off offset:1024
	global_load_dwordx2 v[238:239], v[52:53], off offset:1536
	global_load_dwordx2 v[52:53], v[52:53], off
	v_lshlrev_b64 v[0:1], 12, v[40:41]
	v_lshl_add_u64 v[40:41], v[80:81], 0, v[0:1]
	global_load_dwordx4 v[198:201], v[40:41], off offset:1024
	global_load_dwordx4 v[202:205], v[40:41], off offset:2048
	global_load_dwordx4 v[224:227], v[40:41], off offset:3072
	global_load_dwordx4 v[0:3], v[40:41], off
	v_lshl_add_u64 v[56:57], v[44:45], 0, v[104:105]
	v_lshl_add_u64 v[102:103], v[44:45], 0, v[106:107]
	v_lshl_add_u64 v[44:45], v[44:45], 0, v[120:121]
	s_waitcnt vmcnt(0) lgkmcnt(0)
	v_lshlrev_b32_e32 v50, 16, v48
	v_and_b32_e32 v51, 0xffff0000, v48
	v_lshlrev_b32_e32 v48, 16, v49
	v_and_b32_e32 v49, 0xffff0000, v49
	v_lshlrev_b32_e32 v54, 16, v52
	v_and_b32_e32 v55, 0xffff0000, v52
	v_lshlrev_b32_e32 v52, 16, v53
	v_and_b32_e32 v53, 0xffff0000, v53
	v_pk_add_f32 v[50:51], v[50:51], v[54:55]
	v_pk_add_f32 v[48:49], v[48:49], v[52:53]
	v_pk_mul_f32 v[4:5], v[4:5], v[50:51]
	v_pk_mul_f32 v[6:7], v[6:7], v[48:49]
	v_pk_fma_f32 v[50:51], v[0:1], s[42:43], v[4:5] op_sel_hi:[1,0,1]
	v_pk_fma_f32 v[52:53], v[2:3], s[42:43], v[6:7] op_sel_hi:[1,0,1]
	v_mov_b32_e32 v2, v50
	v_pk_mov_b32 v[0:1], v[50:51], v[52:53] op_sel:[1,0]
	v_mov_b32_e32 v3, v53
	v_pk_add_f32 v[0:1], v[0:1], v[2:3]
	s_nop 0
	v_add_f32_e32 v0, v0, v1
	v_add_f32_e32 v94, 0, v0
	v_mov_b64_e32 v[0:1], v[198:199]
	v_mov_b64_e32 v[2:3], v[200:201]
	v_mov_b64_e32 v[4:5], v[186:187]
	v_mov_b64_e32 v[6:7], v[188:189]
	v_mov_b64_e32 v[48:49], v[228:229]
	v_lshlrev_b32_e32 v54, 16, v48
	v_mov_b64_e32 v[56:57], v[234:235]
	v_and_b32_e32 v55, 0xffff0000, v48
	v_lshlrev_b32_e32 v48, 16, v49
	v_and_b32_e32 v49, 0xffff0000, v49
	v_lshlrev_b32_e32 v58, 16, v56
	v_and_b32_e32 v59, 0xffff0000, v56
	v_lshlrev_b32_e32 v56, 16, v57
	v_and_b32_e32 v57, 0xffff0000, v57
	v_pk_add_f32 v[54:55], v[54:55], v[58:59]
	v_pk_add_f32 v[48:49], v[48:49], v[56:57]
	v_pk_mul_f32 v[4:5], v[4:5], v[54:55]
	v_pk_mul_f32 v[6:7], v[6:7], v[48:49]
	v_pk_fma_f32 v[56:57], v[0:1], s[42:43], v[4:5] op_sel_hi:[1,0,1]
	v_pk_fma_f32 v[58:59], v[2:3], s[42:43], v[6:7] op_sel_hi:[1,0,1]
	v_mov_b32_e32 v2, v56
	v_pk_mov_b32 v[0:1], v[56:57], v[58:59] op_sel:[1,0]
	v_mov_b32_e32 v3, v59
	v_pk_add_f32 v[0:1], v[0:1], v[2:3]
	s_nop 0
	v_pk_add_f32 v[100:101], v[0:1], v[0:1] op_sel:[0,1] op_sel_hi:[1,0]
	v_mov_b64_e32 v[0:1], v[202:203]
	v_mov_b64_e32 v[2:3], v[204:205]
	v_mov_b64_e32 v[4:5], v[190:191]
	v_mov_b64_e32 v[6:7], v[192:193]
	v_mov_b64_e32 v[48:49], v[230:231]
	v_lshlrev_b32_e32 v54, 16, v48
	v_mov_b64_e32 v[102:103], v[236:237]
	v_and_b32_e32 v55, 0xffff0000, v48
	v_lshlrev_b32_e32 v48, 16, v49
	v_and_b32_e32 v49, 0xffff0000, v49
	v_lshlrev_b32_e32 v108, 16, v102
	v_and_b32_e32 v109, 0xffff0000, v102
	v_lshlrev_b32_e32 v102, 16, v103
	v_and_b32_e32 v103, 0xffff0000, v103
	v_pk_add_f32 v[48:49], v[48:49], v[102:103]
	v_pk_add_f32 v[54:55], v[54:55], v[108:109]
	v_pk_mul_f32 v[6:7], v[6:7], v[48:49]
	v_pk_mul_f32 v[4:5], v[4:5], v[54:55]
	v_pk_fma_f32 v[116:117], v[2:3], s[42:43], v[6:7] op_sel_hi:[1,0,1]
	v_pk_fma_f32 v[54:55], v[0:1], s[42:43], v[4:5] op_sel_hi:[1,0,1]
	v_mov_b64_e32 v[0:1], v[224:225]
	v_mov_b64_e32 v[2:3], v[226:227]
	v_mov_b64_e32 v[4:5], v[194:195]
	v_mov_b64_e32 v[6:7], v[196:197]
	s_nop 0
	v_mov_b64_e32 v[42:43], v[232:233]
	v_add_f32_e32 v102, v54, v55
	v_mov_b64_e32 v[44:45], v[238:239]
	v_add_f32_e32 v108, v116, v117
	v_lshlrev_b32_e32 v46, 16, v42
	v_and_b32_e32 v47, 0xffff0000, v42
	v_lshlrev_b32_e32 v42, 16, v43
	v_and_b32_e32 v43, 0xffff0000, v43
	v_lshlrev_b32_e32 v48, 16, v44
	v_and_b32_e32 v49, 0xffff0000, v44
	v_lshlrev_b32_e32 v44, 16, v45
	v_and_b32_e32 v45, 0xffff0000, v45
	v_pk_add_f32 v[42:43], v[42:43], v[44:45]
	v_pk_add_f32 v[44:45], v[46:47], v[48:49]
	v_pk_mul_f32 v[6:7], v[6:7], v[42:43]
	v_pk_mul_f32 v[4:5], v[4:5], v[44:45]
	v_pk_fma_f32 v[48:49], v[2:3], s[42:43], v[6:7] op_sel_hi:[1,0,1]
	v_pk_fma_f32 v[46:47], v[0:1], s[42:43], v[4:5] op_sel_hi:[1,0,1]
	v_mov_b32_e32 v103, v48
	v_mov_b32_e32 v95, v46
	v_mov_b32_e32 v101, v47
	v_mov_b32_e32 v109, v49
	v_pk_add_f32 v[0:1], v[94:95], v[100:101]
	v_pk_add_f32 v[2:3], v[102:103], v[108:109]
	v_lshlrev_b64 v[94:95], 11, v[20:21]
	v_pk_add_f32 v[0:1], v[0:1], v[2:3]
	v_lshl_add_u64 v[100:101], v[22:23], 0, s[28:29]
	v_add_f32_e32 v125, v0, v1
	v_lshlrev_b64 v[0:1], 12, v[20:21]
	v_lshl_add_u64 v[20:21], s[56:57], 0, v[94:95]
	v_lshl_add_u64 v[22:23], v[20:21], 0, s[8:9]
	v_mad_u64_u32 v[128:129], s[4:5], v100, s7, v[78:79]
	v_mad_i32_i24 v129, v101, s7, v129
	v_lshl_add_u64 v[20:21], v[20:21], 0, v[152:153]
	v_lshl_add_u64 v[108:109], v[22:23], 0, v[152:153]
	global_load_dwordx4 v[186:189], v[128:129], off offset:1024
	global_load_dwordx4 v[190:193], v[128:129], off offset:2048
	global_load_dwordx4 v[194:197], v[128:129], off offset:3072
	global_load_dwordx4 v[4:7], v[128:129], off
	global_load_dwordx2 v[228:229], v[20:21], off offset:512
	global_load_dwordx2 v[230:231], v[20:21], off offset:1024
	global_load_dwordx2 v[232:233], v[20:21], off offset:1536
	global_load_dwordx2 v[42:43], v[20:21], off
	v_lshl_add_u64 v[102:103], v[80:81], 0, v[0:1]
	global_load_dwordx2 v[234:235], v[108:109], off offset:512
	global_load_dwordx2 v[236:237], v[108:109], off offset:1024
	global_load_dwordx2 v[238:239], v[108:109], off offset:1536
	global_load_dwordx2 v[108:109], v[108:109], off
	v_lshl_add_u64 v[104:105], v[22:23], 0, v[104:105]
	global_load_dwordx4 v[198:201], v[102:103], off offset:1024
	global_load_dwordx4 v[202:205], v[102:103], off offset:2048
	global_load_dwordx4 v[224:227], v[102:103], off offset:3072
	global_load_dwordx4 v[0:3], v[102:103], off
	v_lshl_add_u64 v[106:107], v[22:23], 0, v[106:107]
	v_lshl_add_u64 v[22:23], v[22:23], 0, v[120:121]
	v_readlane_b32 s4, v254, 33
	v_readlane_b32 s5, v254, 34
	s_waitcnt vmcnt(0) lgkmcnt(0)
	v_lshlrev_b32_e32 v44, 16, v42
	v_and_b32_e32 v45, 0xffff0000, v42
	v_lshlrev_b32_e32 v42, 16, v43
	v_and_b32_e32 v43, 0xffff0000, v43
	v_lshlrev_b32_e32 v110, 16, v108
	v_and_b32_e32 v111, 0xffff0000, v108
	v_lshlrev_b32_e32 v108, 16, v109
	v_and_b32_e32 v109, 0xffff0000, v109
	v_pk_add_f32 v[44:45], v[44:45], v[110:111]
	v_pk_add_f32 v[42:43], v[42:43], v[108:109]
	v_pk_mul_f32 v[4:5], v[4:5], v[44:45]
	v_pk_mul_f32 v[6:7], v[6:7], v[42:43]
	v_pk_fma_f32 v[44:45], v[0:1], s[42:43], v[4:5] op_sel_hi:[1,0,1]
	v_pk_fma_f32 v[114:115], v[2:3], s[42:43], v[6:7] op_sel_hi:[1,0,1]
	v_mov_b32_e32 v2, v44
	v_pk_mov_b32 v[0:1], v[44:45], v[114:115] op_sel:[1,0]
	v_mov_b32_e32 v3, v115
	v_pk_add_f32 v[0:1], v[0:1], v[2:3]
	s_nop 0
	v_add_f32_e32 v0, v0, v1
	v_add_f32_e32 v130, 0, v0
	v_mov_b64_e32 v[0:1], v[198:199]
	v_mov_b64_e32 v[2:3], v[200:201]
	v_mov_b64_e32 v[4:5], v[186:187]
	v_mov_b64_e32 v[6:7], v[188:189]
	v_mov_b64_e32 v[42:43], v[228:229]
	v_lshlrev_b32_e32 v108, 16, v42
	v_mov_b64_e32 v[104:105], v[234:235]
	v_and_b32_e32 v109, 0xffff0000, v42
	v_lshlrev_b32_e32 v42, 16, v43
	v_and_b32_e32 v43, 0xffff0000, v43
	v_lshlrev_b32_e32 v110, 16, v104
	v_and_b32_e32 v111, 0xffff0000, v104
	v_lshlrev_b32_e32 v104, 16, v105
	v_and_b32_e32 v105, 0xffff0000, v105
	v_pk_add_f32 v[108:109], v[108:109], v[110:111]
	v_pk_add_f32 v[42:43], v[42:43], v[104:105]
	v_pk_mul_f32 v[4:5], v[4:5], v[108:109]
	v_pk_mul_f32 v[6:7], v[6:7], v[42:43]
	v_pk_fma_f32 v[42:43], v[0:1], s[42:43], v[4:5] op_sel_hi:[1,0,1]
	v_pk_fma_f32 v[112:113], v[2:3], s[42:43], v[6:7] op_sel_hi:[1,0,1]
	v_mov_b32_e32 v2, v42
	v_pk_mov_b32 v[0:1], v[42:43], v[112:113] op_sel:[1,0]
	v_mov_b32_e32 v3, v113
	v_pk_add_f32 v[0:1], v[0:1], v[2:3]
	s_nop 0
	v_pk_add_f32 v[132:133], v[0:1], v[0:1] op_sel:[0,1] op_sel_hi:[1,0]
	v_mov_b64_e32 v[0:1], v[202:203]
	v_mov_b64_e32 v[2:3], v[204:205]
	v_mov_b64_e32 v[4:5], v[190:191]
	v_mov_b64_e32 v[6:7], v[192:193]
	v_mov_b64_e32 v[104:105], v[230:231]
	v_lshlrev_b32_e32 v108, 16, v104
	v_mov_b64_e32 v[106:107], v[236:237]
	v_and_b32_e32 v109, 0xffff0000, v104
	v_lshlrev_b32_e32 v104, 16, v105
	v_and_b32_e32 v105, 0xffff0000, v105
	v_lshlrev_b32_e32 v110, 16, v106
	v_and_b32_e32 v111, 0xffff0000, v106
	v_lshlrev_b32_e32 v106, 16, v107
	v_and_b32_e32 v107, 0xffff0000, v107
	v_pk_add_f32 v[104:105], v[104:105], v[106:107]
	v_pk_add_f32 v[106:107], v[108:109], v[110:111]
	v_pk_mul_f32 v[6:7], v[6:7], v[104:105]
	v_pk_mul_f32 v[4:5], v[4:5], v[106:107]
	v_pk_fma_f32 v[110:111], v[2:3], s[42:43], v[6:7] op_sel_hi:[1,0,1]
	v_pk_fma_f32 v[108:109], v[0:1], s[42:43], v[4:5] op_sel_hi:[1,0,1]
	v_mov_b64_e32 v[0:1], v[224:225]
	v_mov_b64_e32 v[2:3], v[226:227]
	v_mov_b64_e32 v[4:5], v[194:195]
	v_mov_b64_e32 v[6:7], v[196:197]
	s_nop 0
	v_mov_b64_e32 v[20:21], v[232:233]
	v_add_f32_e32 v134, v108, v109
	v_mov_b64_e32 v[22:23], v[238:239]
	v_add_f32_e32 v136, v110, v111
	v_lshlrev_b32_e32 v104, 16, v20
	v_and_b32_e32 v105, 0xffff0000, v20
	v_lshlrev_b32_e32 v20, 16, v21
	v_and_b32_e32 v21, 0xffff0000, v21
	v_lshlrev_b32_e32 v106, 16, v22
	v_and_b32_e32 v107, 0xffff0000, v22
	v_lshlrev_b32_e32 v22, 16, v23
	v_and_b32_e32 v23, 0xffff0000, v23
	v_pk_add_f32 v[20:21], v[20:21], v[22:23]
	v_pk_add_f32 v[22:23], v[104:105], v[106:107]
	v_pk_mul_f32 v[6:7], v[6:7], v[20:21]
	v_pk_mul_f32 v[4:5], v[4:5], v[22:23]
	v_pk_fma_f32 v[106:107], v[2:3], s[42:43], v[6:7] op_sel_hi:[1,0,1]
	v_pk_fma_f32 v[104:105], v[0:1], s[42:43], v[4:5] op_sel_hi:[1,0,1]
	v_mov_b32_e32 v135, v106
	v_mov_b32_e32 v131, v104
	v_mov_b32_e32 v133, v105
	v_mov_b32_e32 v137, v107
	v_pk_add_f32 v[0:1], v[130:131], v[132:133]
	v_pk_add_f32 v[2:3], v[134:135], v[136:137]
	ds_bpermute_b32 v22, v67, v126
	v_pk_add_f32 v[0:1], v[0:1], v[2:3]
	s_waitcnt lgkmcnt(0)
	v_add_f32_e32 v22, v126, v22
	v_add_f32_e32 v65, v0, v1
	ds_bpermute_b32 v0, v67, v122
	ds_bpermute_b32 v23, v69, v22
	s_waitcnt lgkmcnt(1)
	v_add_f32_e32 v0, v122, v0
	ds_bpermute_b32 v1, v69, v0
	s_waitcnt lgkmcnt(1)
	v_add_f32_e32 v22, v22, v23
	ds_bpermute_b32 v23, v71, v22
	s_waitcnt lgkmcnt(1)
	v_add_f32_e32 v0, v0, v1
	ds_bpermute_b32 v1, v71, v0
	s_waitcnt lgkmcnt(1)
	v_add_f32_e32 v22, v22, v23
	ds_bpermute_b32 v23, v73, v22
	s_waitcnt lgkmcnt(1)
	v_add_f32_e32 v0, v0, v1
	ds_bpermute_b32 v1, v73, v0
	s_waitcnt lgkmcnt(1)
	v_add_f32_e32 v22, v22, v23
	ds_bpermute_b32 v23, v123, v22
	s_waitcnt lgkmcnt(1)
	v_add_f32_e32 v0, v0, v1
	ds_bpermute_b32 v1, v123, v0
	s_waitcnt lgkmcnt(1)
	v_add_f32_e32 v22, v22, v23
	ds_bpermute_b32 v23, v124, v22
	s_waitcnt lgkmcnt(1)
	v_add_f32_e32 v0, v0, v1
	ds_bpermute_b32 v1, v124, v0
	s_waitcnt lgkmcnt(1)
	v_add_f32_e32 v122, v22, v23
	v_fmamk_f32 v29, v122, 0xba800000, v29
	v_fmac_f32_e32 v28, 0xba800000, v122
	v_fmamk_f32 v31, v122, 0xba800000, v31
	s_waitcnt lgkmcnt(0)
	v_add_f32_e32 v20, v0, v1
	v_fmamk_f32 v9, v20, 0xba800000, v9
	v_fmac_f32_e32 v8, 0xba800000, v20
	v_fmamk_f32 v11, v20, 0xba800000, v11
	v_fmac_f32_e32 v10, 0xba800000, v20
	v_pk_mul_f32 v[0:1], v[10:11], v[10:11]
	v_pk_mul_f32 v[2:3], v[8:9], v[8:9]
	v_fmamk_f32 v13, v20, 0xba800000, v13
	v_pk_mov_b32 v[4:5], v[2:3], v[0:1] op_sel:[1,0]
	v_mov_b32_e32 v3, v1
	v_pk_add_f32 v[0:1], v[4:5], v[2:3]
	v_fmac_f32_e32 v12, 0xba800000, v20
	v_fmamk_f32 v15, v20, 0xba800000, v15
	v_fmac_f32_e32 v14, 0xba800000, v20
	v_pk_add_f32 v[0:1], v[0:1], v[0:1] op_sel_hi:[0,1]
	v_pk_mul_f32 v[2:3], v[14:15], v[14:15]
	v_pk_mul_f32 v[4:5], v[12:13], v[12:13]
	v_fmac_f32_e32 v16, 0xba800000, v20
	v_pk_mov_b32 v[6:7], v[4:5], v[2:3] op_sel:[1,0]
	v_mov_b32_e32 v5, v3
	v_fmamk_f32 v17, v20, 0xba800000, v17
	v_fmac_f32_e32 v18, 0xba800000, v20
	v_mul_f32_e32 v0, v16, v16
	v_pk_add_f32 v[2:3], v[6:7], v[4:5]
	v_fmamk_f32 v19, v20, 0xba800000, v19
	v_pk_fma_f32 v[4:5], v[16:17], v[16:17], v[0:1] op_sel_hi:[1,1,0]
	v_mul_f32_e32 v0, v18, v18
	v_pk_add_f32 v[2:3], v[2:3], v[2:3] op_sel_hi:[0,1]
	v_pk_fma_f32 v[6:7], v[18:19], v[18:19], v[0:1] op_sel_hi:[1,1,0]
	v_fmamk_f32 v27, v20, 0xba800000, v27
	v_fmac_f32_e32 v26, 0xba800000, v20
	v_fmamk_f32 v25, v20, 0xba800000, v25
	v_fmac_f32_e32 v24, 0xba800000, v20
	v_mul_f32_e32 v4, v24, v24
	v_mul_f32_e32 v6, v25, v25
	v_mul_f32_e32 v0, v26, v26
	v_mul_f32_e32 v2, v27, v27
	v_pk_add_f32 v[4:5], v[4:5], v[6:7]
	v_pk_add_f32 v[0:1], v[0:1], v[2:3]
	v_fmac_f32_e32 v30, 0xba800000, v122
	v_pk_add_f32 v[20:21], v[4:5], v[0:1]
	v_mov_b64_e32 v[0:1], v[154:155]
	v_mov_b64_e32 v[2:3], v[156:157]
	v_mov_b64_e32 v[4:5], v[158:159]
	v_mov_b64_e32 v[6:7], v[160:161]
	v_pk_mul_f32 v[22:23], v[30:31], v[30:31]
	v_pk_mul_f32 v[120:121], v[28:29], v[28:29]
	v_fmamk_f32 v39, v122, 0xba800000, v39
	v_pk_mov_b32 v[126:127], v[120:121], v[22:23] op_sel:[1,0]
	v_mov_b32_e32 v121, v23
	v_pk_add_f32 v[22:23], v[126:127], v[120:121]
	v_fmac_f32_e32 v38, 0xba800000, v122
	v_fmamk_f32 v61, v122, 0xba800000, v61
	v_fmac_f32_e32 v60, 0xba800000, v122
	v_pk_add_f32 v[22:23], v[22:23], v[22:23] op_sel_hi:[0,1]
	v_pk_mul_f32 v[120:121], v[60:61], v[60:61]
	v_pk_mul_f32 v[126:127], v[38:39], v[38:39]
	v_fmac_f32_e32 v34, 0xba800000, v122
	v_pk_mov_b32 v[128:129], v[126:127], v[120:121] op_sel:[1,0]
	v_mov_b32_e32 v127, v121
	v_fmamk_f32 v35, v122, 0xba800000, v35
	v_fmac_f32_e32 v36, 0xba800000, v122
	v_mul_f32_e32 v22, v34, v34
	v_pk_add_f32 v[120:121], v[128:129], v[126:127]
	v_fmamk_f32 v37, v122, 0xba800000, v37
	v_pk_fma_f32 v[126:127], v[34:35], v[34:35], v[22:23] op_sel_hi:[1,1,0]
	v_mul_f32_e32 v22, v36, v36
	v_pk_add_f32 v[120:121], v[120:121], v[120:121] op_sel_hi:[0,1]
	v_pk_fma_f32 v[128:129], v[36:37], v[36:37], v[22:23] op_sel_hi:[1,1,0]
	v_fmamk_f32 v119, v122, 0xba800000, v119
	v_fmac_f32_e32 v118, 0xba800000, v122
	v_fmamk_f32 v63, v122, 0xba800000, v63
	v_fmac_f32_e32 v62, 0xba800000, v122
	v_mul_f32_e32 v126, v62, v62
	v_mul_f32_e32 v128, v63, v63
	v_mul_f32_e32 v22, v118, v118
	v_mul_f32_e32 v120, v119, v119
	v_pk_add_f32 v[126:127], v[126:127], v[128:129]
	v_pk_add_f32 v[22:23], v[22:23], v[120:121]
	v_mov_b32_e32 v121, v20
	v_pk_add_f32 v[22:23], v[126:127], v[22:23]
	s_nop 0
	v_mov_b32_e32 v120, v22
	v_mov_b32_e32 v20, v23
	v_pk_add_f32 v[20:21], v[120:121], v[20:21]
	ds_bpermute_b32 v23, v67, v21
	ds_bpermute_b32 v22, v67, v20
	v_mov_b64_e32 v[120:121], s[2:3]
	s_mov_b32 s2, 0x3a800000
	s_waitcnt lgkmcnt(0)
	v_pk_add_f32 v[20:21], v[20:21], v[22:23]
	ds_bpermute_b32 v23, v69, v21
	ds_bpermute_b32 v22, v69, v20
	s_waitcnt lgkmcnt(0)
	v_pk_add_f32 v[20:21], v[20:21], v[22:23]
	ds_bpermute_b32 v23, v71, v21
	ds_bpermute_b32 v22, v71, v20
	s_waitcnt lgkmcnt(0)
	v_pk_add_f32 v[20:21], v[20:21], v[22:23]
	ds_bpermute_b32 v23, v73, v21
	ds_bpermute_b32 v22, v73, v20
	s_waitcnt lgkmcnt(0)
	v_pk_add_f32 v[20:21], v[20:21], v[22:23]
	ds_bpermute_b32 v23, v123, v21
	ds_bpermute_b32 v22, v123, v20
	s_waitcnt lgkmcnt(0)
	v_pk_add_f32 v[20:21], v[20:21], v[22:23]
	ds_bpermute_b32 v23, v124, v21
	ds_bpermute_b32 v22, v124, v20
	s_waitcnt lgkmcnt(0)
	v_pk_add_f32 v[20:21], v[20:21], v[22:23]
	s_nop 0
	v_pk_fma_f32 v[126:127], v[20:21], s[2:3], v[120:121] op_sel_hi:[1,0,0]
	s_nop 0
	v_mul_f32_e32 v20, 0x4b800000, v127
	v_cmp_gt_f32_e64 s[8:9], s68, v127
	v_cmp_gt_f32_e32 vcc, s68, v126
	s_nop 0
	v_cndmask_b32_e64 v20, v127, v20, s[8:9]
	v_rsq_f32_e32 v20, v20
	s_nop 0
	v_mul_f32_e32 v21, 0x45800000, v20
	v_cndmask_b32_e64 v122, v20, v21, s[8:9]
	v_pk_mul_f32 v[8:9], v[8:9], v[122:123] op_sel_hi:[1,0]
	v_pk_mul_f32 v[10:11], v[10:11], v[122:123] op_sel_hi:[1,0]
	v_pk_fma_f32 v[20:21], v[0:1], v[8:9], v[4:5]
	v_pk_fma_f32 v[22:23], v[2:3], v[10:11], v[6:7]
	global_store_dwordx4 v[86:87], v[20:23], off
	v_mov_b64_e32 v[0:1], v[162:163]
	v_mov_b64_e32 v[2:3], v[164:165]
	v_mov_b64_e32 v[4:5], v[166:167]
	v_mov_b64_e32 v[6:7], v[168:169]
	v_pk_mul_f32 v[8:9], v[14:15], v[122:123] op_sel_hi:[1,0]
	v_pk_mul_f32 v[10:11], v[12:13], v[122:123] op_sel_hi:[1,0]
	v_pk_fma_f32 v[14:15], v[2:3], v[8:9], v[6:7]
	v_pk_fma_f32 v[12:13], v[0:1], v[10:11], v[4:5]
	global_store_dwordx4 v[86:87], v[12:15], off offset:1024
	v_mov_b64_e32 v[0:1], v[170:171]
	v_mov_b64_e32 v[2:3], v[172:173]
	v_mov_b64_e32 v[4:5], v[174:175]
	v_mov_b64_e32 v[6:7], v[176:177]
	v_pk_mul_f32 v[8:9], v[18:19], v[122:123] op_sel_hi:[1,0]
	v_pk_mul_f32 v[10:11], v[16:17], v[122:123] op_sel_hi:[1,0]
	v_pk_mul_f32 v[18:19], v[24:25], v[122:123] op_sel_hi:[1,0]
	v_pk_mul_f32 v[16:17], v[26:27], v[122:123] op_sel_hi:[1,0]
	v_pk_fma_f32 v[4:5], v[0:1], v[10:11], v[4:5]
	v_pk_fma_f32 v[6:7], v[2:3], v[8:9], v[6:7]
	global_store_dwordx4 v[86:87], v[4:7], off offset:2048
	v_mov_b64_e32 v[0:1], v[178:179]
	v_mov_b64_e32 v[2:3], v[180:181]
	v_mov_b64_e32 v[8:9], v[182:183]
	v_mov_b64_e32 v[10:11], v[184:185]
	v_pk_fma_f32 v[0:1], v[0:1], v[18:19], v[8:9]
	v_mul_f32_e32 v8, 0x4b800000, v126
	v_cndmask_b32_e32 v8, v126, v8, vcc
	v_rsq_f32_e32 v8, v8
	v_pk_fma_f32 v[2:3], v[2:3], v[16:17], v[10:11]
	global_store_dwordx4 v[86:87], v[0:3], off offset:3072
	v_mul_f32_e32 v9, 0x45800000, v8
	v_cndmask_b32_e32 v122, v8, v9, vcc
	v_mov_b64_e32 v[8:9], v[154:155]
	v_mov_b64_e32 v[10:11], v[156:157]
	v_mov_b64_e32 v[16:17], v[158:159]
	v_mov_b64_e32 v[18:19], v[160:161]
	v_pk_mul_f32 v[24:25], v[30:31], v[122:123] op_sel_hi:[1,0]
	v_pk_mul_f32 v[26:27], v[28:29], v[122:123] op_sel_hi:[1,0]
	v_pk_mul_f32 v[30:31], v[60:61], v[122:123] op_sel_hi:[1,0]
	v_pk_mul_f32 v[28:29], v[38:39], v[122:123] op_sel_hi:[1,0]
	v_pk_mul_f32 v[36:37], v[36:37], v[122:123] op_sel_hi:[1,0]
	v_pk_mul_f32 v[34:35], v[34:35], v[122:123] op_sel_hi:[1,0]
	v_pk_mul_f32 v[38:39], v[118:119], v[122:123] op_sel_hi:[1,0]
	v_pk_mul_f32 v[60:61], v[62:63], v[122:123] op_sel_hi:[1,0]
	ds_bpermute_b32 v62, v67, v65
	s_waitcnt lgkmcnt(0)
	v_add_f32_e32 v62, v65, v62
	ds_bpermute_b32 v63, v69, v62
	s_waitcnt lgkmcnt(0)
	v_add_f32_e32 v62, v62, v63
	ds_bpermute_b32 v63, v71, v62
	s_waitcnt lgkmcnt(0)
	v_add_f32_e32 v62, v62, v63
	ds_bpermute_b32 v63, v73, v62
	s_waitcnt lgkmcnt(0)
	v_add_f32_e32 v62, v62, v63
	ds_bpermute_b32 v63, v123, v62
	s_waitcnt lgkmcnt(0)
	v_add_f32_e32 v62, v62, v63
	ds_bpermute_b32 v63, v124, v62
	s_waitcnt lgkmcnt(0)
	v_add_f32_e32 v65, v62, v63
	v_fmamk_f32 v45, v65, 0xba800000, v45
	v_fmac_f32_e32 v44, 0xba800000, v65
	v_fmamk_f32 v115, v65, 0xba800000, v115
	v_fmac_f32_e32 v114, 0xba800000, v65
	v_pk_mul_f32 v[62:63], v[114:115], v[114:115]
	v_pk_mul_f32 v[118:119], v[44:45], v[44:45]
	v_fmamk_f32 v43, v65, 0xba800000, v43
	v_pk_mov_b32 v[126:127], v[118:119], v[62:63] op_sel:[1,0]
	v_mov_b32_e32 v119, v63
	v_pk_add_f32 v[62:63], v[126:127], v[118:119]
	v_fmac_f32_e32 v42, 0xba800000, v65
	v_fmamk_f32 v113, v65, 0xba800000, v113
	v_fmac_f32_e32 v112, 0xba800000, v65
	v_pk_add_f32 v[62:63], v[62:63], v[62:63] op_sel_hi:[0,1]
	v_pk_mul_f32 v[118:119], v[112:113], v[112:113]
	v_pk_mul_f32 v[126:127], v[42:43], v[42:43]
	v_fmac_f32_e32 v108, 0xba800000, v65
	v_pk_mov_b32 v[128:129], v[126:127], v[118:119] op_sel:[1,0]
	v_mov_b32_e32 v127, v119
	v_fmamk_f32 v109, v65, 0xba800000, v109
	v_fmac_f32_e32 v110, 0xba800000, v65
	v_mul_f32_e32 v62, v108, v108
	v_pk_add_f32 v[118:119], v[128:129], v[126:127]
	v_fmamk_f32 v111, v65, 0xba800000, v111
	v_pk_fma_f32 v[126:127], v[108:109], v[108:109], v[62:63] op_sel_hi:[1,1,0]
	v_mul_f32_e32 v62, v110, v110
	v_pk_add_f32 v[118:119], v[118:119], v[118:119] op_sel_hi:[0,1]
	v_pk_fma_f32 v[128:129], v[110:111], v[110:111], v[62:63] op_sel_hi:[1,1,0]
	v_fmamk_f32 v107, v65, 0xba800000, v107
	v_fmac_f32_e32 v106, 0xba800000, v65
	v_fmamk_f32 v105, v65, 0xba800000, v105
	v_fmac_f32_e32 v104, 0xba800000, v65
	v_mul_f32_e32 v126, v104, v104
	v_mul_f32_e32 v128, v105, v105
	v_mul_f32_e32 v62, v106, v106
	v_pk_fma_f32 v[8:9], v[8:9], v[26:27], v[16:17]
	v_pk_fma_f32 v[10:11], v[10:11], v[24:25], v[18:19]
	global_store_dwordx4 v[32:33], v[8:11], off
	v_mov_b64_e32 v[16:17], v[162:163]
	v_mov_b64_e32 v[18:19], v[164:165]
	v_mov_b64_e32 v[24:25], v[166:167]
	v_mov_b64_e32 v[26:27], v[168:169]
	v_mul_f32_e32 v118, v107, v107
	v_pk_add_f32 v[126:127], v[126:127], v[128:129]
	v_pk_add_f32 v[62:63], v[62:63], v[118:119]
	v_pk_fma_f32 v[28:29], v[16:17], v[28:29], v[24:25]
	v_pk_fma_f32 v[30:31], v[18:19], v[30:31], v[26:27]
	global_store_dwordx4 v[32:33], v[28:31], off offset:1024
	v_mov_b64_e32 v[16:17], v[170:171]
	v_mov_b64_e32 v[18:19], v[172:173]
	v_mov_b64_e32 v[24:25], v[174:175]
	v_mov_b64_e32 v[26:27], v[176:177]
	v_pk_add_f32 v[62:63], v[126:127], v[62:63]
	v_pk_fma_f32 v[24:25], v[16:17], v[34:35], v[24:25]
	v_pk_fma_f32 v[26:27], v[18:19], v[36:37], v[26:27]
	global_store_dwordx4 v[32:33], v[24:27], off offset:2048
	v_mov_b64_e32 v[16:17], v[178:179]
	v_mov_b64_e32 v[18:19], v[180:181]
	v_mov_b64_e32 v[34:35], v[182:183]
	v_mov_b64_e32 v[36:37], v[184:185]
	v_mov_b32_e32 v118, v62
	v_pk_fma_f32 v[16:17], v[16:17], v[60:61], v[34:35]
	v_pk_fma_f32 v[18:19], v[18:19], v[38:39], v[36:37]
	global_store_dwordx4 v[32:33], v[16:19], off offset:3072
	ds_bpermute_b32 v32, v67, v125
	s_waitcnt lgkmcnt(0)
	v_add_f32_e32 v32, v125, v32
	ds_bpermute_b32 v33, v69, v32
	s_waitcnt lgkmcnt(0)
	v_add_f32_e32 v32, v32, v33
	ds_bpermute_b32 v33, v71, v32
	s_waitcnt lgkmcnt(0)
	v_add_f32_e32 v32, v32, v33
	ds_bpermute_b32 v33, v73, v32
	s_waitcnt lgkmcnt(0)
	v_add_f32_e32 v32, v32, v33
	ds_bpermute_b32 v33, v123, v32
	s_waitcnt lgkmcnt(0)
	v_add_f32_e32 v32, v32, v33
	ds_bpermute_b32 v33, v124, v32
	s_waitcnt lgkmcnt(0)
	v_add_f32_e32 v60, v32, v33
	v_fmamk_f32 v51, v60, 0xba800000, v51
	v_fmac_f32_e32 v50, 0xba800000, v60
	v_fmamk_f32 v53, v60, 0xba800000, v53
	v_fmac_f32_e32 v52, 0xba800000, v60
	v_pk_mul_f32 v[32:33], v[52:53], v[52:53]
	v_pk_mul_f32 v[34:35], v[50:51], v[50:51]
	v_fmamk_f32 v57, v60, 0xba800000, v57
	v_pk_mov_b32 v[36:37], v[34:35], v[32:33] op_sel:[1,0]
	v_mov_b32_e32 v35, v33
	v_pk_add_f32 v[32:33], v[36:37], v[34:35]
	v_fmac_f32_e32 v56, 0xba800000, v60
	v_fmamk_f32 v59, v60, 0xba800000, v59
	v_fmac_f32_e32 v58, 0xba800000, v60
	v_pk_add_f32 v[32:33], v[32:33], v[32:33] op_sel_hi:[0,1]
	v_pk_mul_f32 v[34:35], v[58:59], v[58:59]
	v_pk_mul_f32 v[36:37], v[56:57], v[56:57]
	v_fmac_f32_e32 v54, 0xba800000, v60
	v_pk_mov_b32 v[38:39], v[36:37], v[34:35] op_sel:[1,0]
	v_mov_b32_e32 v37, v35
	v_fmamk_f32 v55, v60, 0xba800000, v55
	v_fmac_f32_e32 v116, 0xba800000, v60
	v_mul_f32_e32 v32, v54, v54
	v_pk_add_f32 v[34:35], v[38:39], v[36:37]
	v_fmamk_f32 v117, v60, 0xba800000, v117
	v_pk_fma_f32 v[36:37], v[54:55], v[54:55], v[32:33] op_sel_hi:[1,1,0]
	v_mul_f32_e32 v32, v116, v116
	v_pk_add_f32 v[34:35], v[34:35], v[34:35] op_sel_hi:[0,1]
	v_pk_fma_f32 v[38:39], v[116:117], v[116:117], v[32:33] op_sel_hi:[1,1,0]
	v_fmamk_f32 v49, v60, 0xba800000, v49
	v_fmac_f32_e32 v48, 0xba800000, v60
	v_fmamk_f32 v47, v60, 0xba800000, v47
	v_fmac_f32_e32 v46, 0xba800000, v60
	v_mul_f32_e32 v36, v46, v46
	v_mul_f32_e32 v38, v47, v47
	v_mul_f32_e32 v32, v48, v48
	v_mul_f32_e32 v34, v49, v49
	v_pk_add_f32 v[36:37], v[36:37], v[38:39]
	v_pk_add_f32 v[32:33], v[32:33], v[34:35]
	s_nop 0
	v_pk_add_f32 v[60:61], v[36:37], v[32:33]
	v_mov_b64_e32 v[32:33], v[154:155]
	v_mov_b64_e32 v[34:35], v[156:157]
	v_mov_b64_e32 v[36:37], v[158:159]
	v_mov_b64_e32 v[38:39], v[160:161]
	v_mov_b32_e32 v119, v60
	v_mov_b32_e32 v60, v63
	v_pk_add_f32 v[60:61], v[118:119], v[60:61]
	ds_bpermute_b32 v63, v67, v61
	ds_bpermute_b32 v62, v67, v60
	s_waitcnt lgkmcnt(0)
	v_pk_add_f32 v[60:61], v[60:61], v[62:63]
	ds_bpermute_b32 v63, v69, v61
	ds_bpermute_b32 v62, v69, v60
	s_waitcnt lgkmcnt(0)
	v_pk_add_f32 v[60:61], v[60:61], v[62:63]
	ds_bpermute_b32 v63, v71, v61
	ds_bpermute_b32 v62, v71, v60
	s_waitcnt lgkmcnt(0)
	v_pk_add_f32 v[60:61], v[60:61], v[62:63]
	ds_bpermute_b32 v63, v73, v61
	ds_bpermute_b32 v62, v73, v60
	s_waitcnt lgkmcnt(0)
	v_pk_add_f32 v[60:61], v[60:61], v[62:63]
	ds_bpermute_b32 v63, v123, v61
	ds_bpermute_b32 v62, v123, v60
	s_waitcnt lgkmcnt(0)
	v_pk_add_f32 v[60:61], v[60:61], v[62:63]
	ds_bpermute_b32 v63, v124, v61
	ds_bpermute_b32 v62, v124, v60
	s_waitcnt lgkmcnt(0)
	v_pk_add_f32 v[60:61], v[60:61], v[62:63]
	s_nop 0
	v_pk_fma_f32 v[118:119], v[60:61], s[2:3], v[120:121] op_sel_hi:[1,0,0]
	s_nop 0
	v_mul_f32_e32 v60, 0x4b800000, v119
	v_cmp_gt_f32_e64 s[8:9], s68, v119
	v_cmp_gt_f32_e32 vcc, s68, v118
	s_nop 0
	v_cndmask_b32_e64 v60, v119, v60, s[8:9]
	v_rsq_f32_e32 v60, v60
	s_nop 0
	v_mul_f32_e32 v61, 0x45800000, v60
	v_cndmask_b32_e64 v120, v60, v61, s[8:9]
	v_pk_mul_f32 v[52:53], v[52:53], v[120:121] op_sel_hi:[1,0]
	v_pk_mul_f32 v[50:51], v[50:51], v[120:121] op_sel_hi:[1,0]
	v_pk_mul_f32 v[46:47], v[46:47], v[120:121] op_sel_hi:[1,0]
	v_pk_fma_f32 v[60:61], v[32:33], v[50:51], v[36:37]
	v_pk_fma_f32 v[62:63], v[34:35], v[52:53], v[38:39]
	global_store_dwordx4 v[40:41], v[60:63], off
	v_mov_b64_e32 v[32:33], v[162:163]
	v_mov_b64_e32 v[34:35], v[164:165]
	v_mov_b64_e32 v[36:37], v[166:167]
	v_mov_b64_e32 v[38:39], v[168:169]
	v_pk_mul_f32 v[50:51], v[58:59], v[120:121] op_sel_hi:[1,0]
	v_pk_mul_f32 v[52:53], v[56:57], v[120:121] op_sel_hi:[1,0]
	v_pk_fma_f32 v[58:59], v[34:35], v[50:51], v[38:39]
	v_pk_fma_f32 v[56:57], v[32:33], v[52:53], v[36:37]
	global_store_dwordx4 v[40:41], v[56:59], off offset:1024
	v_mov_b64_e32 v[32:33], v[170:171]
	v_mov_b64_e32 v[34:35], v[172:173]
	v_mov_b64_e32 v[36:37], v[174:175]
	v_mov_b64_e32 v[38:39], v[176:177]
	v_pk_mul_f32 v[50:51], v[116:117], v[120:121] op_sel_hi:[1,0]
	v_pk_mul_f32 v[52:53], v[54:55], v[120:121] op_sel_hi:[1,0]
	v_pk_fma_f32 v[54:55], v[34:35], v[50:51], v[38:39]
	v_pk_fma_f32 v[52:53], v[32:33], v[52:53], v[36:37]
	global_store_dwordx4 v[40:41], v[52:55], off offset:2048
	v_mov_b64_e32 v[32:33], v[178:179]
	v_mov_b64_e32 v[34:35], v[180:181]
	v_mov_b64_e32 v[36:37], v[182:183]
	v_mov_b64_e32 v[38:39], v[184:185]
	v_pk_mul_f32 v[50:51], v[48:49], v[120:121] op_sel_hi:[1,0]
	v_pk_fma_f32 v[48:49], v[32:33], v[46:47], v[36:37]
	v_mul_f32_e32 v32, 0x4b800000, v118
	v_cndmask_b32_e32 v32, v118, v32, vcc
	v_rsq_f32_e32 v32, v32
	v_pk_fma_f32 v[50:51], v[34:35], v[50:51], v[38:39]
	global_store_dwordx4 v[40:41], v[48:51], off offset:3072
	v_mul_f32_e32 v33, 0x45800000, v32
	v_cndmask_b32_e32 v116, v32, v33, vcc
	v_mov_b64_e32 v[32:33], v[154:155]
	v_mov_b64_e32 v[34:35], v[156:157]
	v_mov_b64_e32 v[36:37], v[158:159]
	v_mov_b64_e32 v[38:39], v[160:161]
	v_pk_mul_f32 v[40:41], v[114:115], v[116:117] op_sel_hi:[1,0]
	v_pk_mul_f32 v[44:45], v[44:45], v[116:117] op_sel_hi:[1,0]
	v_pk_mul_f32 v[112:113], v[112:113], v[116:117] op_sel_hi:[1,0]
	v_pk_mul_f32 v[110:111], v[110:111], v[116:117] op_sel_hi:[1,0]
	v_pk_mul_f32 v[108:109], v[108:109], v[116:117] op_sel_hi:[1,0]
	s_andn2_b64 vcc, exec, s[4:5]
	v_pk_fma_f32 v[44:45], v[32:33], v[44:45], v[36:37]
	v_pk_fma_f32 v[46:47], v[34:35], v[40:41], v[38:39]
	global_store_dwordx4 v[102:103], v[44:47], off
	v_mov_b64_e32 v[32:33], v[162:163]
	v_mov_b64_e32 v[34:35], v[164:165]
	v_mov_b64_e32 v[36:37], v[166:167]
	v_mov_b64_e32 v[38:39], v[168:169]
	v_pk_mul_f32 v[40:41], v[42:43], v[116:117] op_sel_hi:[1,0]
	v_pk_fma_f32 v[42:43], v[34:35], v[112:113], v[38:39]
	v_pk_fma_f32 v[40:41], v[32:33], v[40:41], v[36:37]
	global_store_dwordx4 v[102:103], v[40:43], off offset:1024
	v_mov_b64_e32 v[32:33], v[170:171]
	v_mov_b64_e32 v[34:35], v[172:173]
	v_mov_b64_e32 v[36:37], v[174:175]
	v_mov_b64_e32 v[38:39], v[176:177]
	v_pk_fma_f32 v[36:37], v[32:33], v[108:109], v[36:37]
	v_pk_fma_f32 v[38:39], v[34:35], v[110:111], v[38:39]
	global_store_dwordx4 v[102:103], v[36:39], off offset:2048
	v_pk_mul_f32 v[108:109], v[106:107], v[116:117] op_sel_hi:[1,0]
	v_pk_mul_f32 v[110:111], v[104:105], v[116:117] op_sel_hi:[1,0]
	v_mov_b64_e32 v[32:33], v[178:179]
	v_mov_b64_e32 v[34:35], v[180:181]
	v_mov_b64_e32 v[104:105], v[182:183]
	v_mov_b64_e32 v[106:107], v[184:185]
	v_pk_fma_f32 v[32:33], v[32:33], v[110:111], v[104:105]
	v_pk_fma_f32 v[34:35], v[34:35], v[108:109], v[106:107]
	global_store_dwordx4 v[102:103], v[32:35], off offset:3072
	s_cbranch_vccnz .LBB0_50
	v_mad_u64_u32 v[104:105], s[4:5], v88, s7, 0
	v_mad_u64_u32 v[102:103], s[4:5], v92, s7, 0
	v_mad_i32_i24 v105, v89, s7, v105
	v_mad_i32_i24 v103, v93, s7, v103
	v_mad_u64_u32 v[92:93], s[4:5], v98, s7, 0
	v_mad_u64_u32 v[88:89], s[4:5], v100, s7, 0
	v_mad_i32_i24 v93, v99, s7, v93
	v_lshl_add_u64 v[98:99], s[60:61], 0, v[104:105]
	s_mov_b64 s[4:5], 0x6000
	s_mov_b64 s[8:9], 0x7000
	v_mad_i32_i24 v89, v101, s7, v89
	v_lshl_add_u64 v[100:101], v[98:99], 0, s[4:5]
	v_lshl_add_u64 v[98:99], v[98:99], 0, s[8:9]
	v_lshlrev_b32_e32 v152, 2, v66
	v_lshl_add_u64 v[104:105], v[100:101], 0, v[152:153]
	v_lshl_add_u64 v[108:109], v[98:99], 0, v[152:153]
	global_load_dwordx4 v[186:189], v[104:105], off offset:1024
	global_load_dwordx4 v[190:193], v[104:105], off offset:2048
	global_load_dwordx4 v[194:197], v[104:105], off offset:3072
	global_load_dwordx4 v[104:107], v[104:105], off
	s_nop 0
	global_load_dwordx4 v[198:201], v[108:109], off offset:1024
	global_load_dwordx4 v[202:205], v[108:109], off offset:2048
	global_load_dwordx4 v[224:227], v[108:109], off offset:3072
	global_load_dwordx4 v[108:111], v[108:109], off
	s_waitcnt vmcnt(0) lgkmcnt(0)
	v_pk_add_f32 v[110:111], v[110:111], 1.0 op_sel_hi:[1,0]
	v_pk_add_f32 v[108:109], v[108:109], 1.0 op_sel_hi:[1,0]
	v_pk_fma_f32 v[22:23], v[22:23], v[110:111], v[106:107]
	v_pk_fma_f32 v[20:21], v[20:21], v[108:109], v[104:105]
	s_nop 0
	v_cvt_pk_bf16_f32 v20, v20, v21
	v_cvt_pk_bf16_f32 v21, v22, v23
	global_store_dwordx2 v[84:85], v[20:21], off
	v_lshlrev_b32_e32 v20, 2, v68
	v_mov_b32_e32 v21, v153
	v_lshl_add_u64 v[22:23], v[100:101], 0, v[20:21]
	v_mov_b64_e32 v[104:105], v[186:187]
	v_mov_b64_e32 v[106:107], v[188:189]
	v_lshl_add_u64 v[22:23], v[98:99], 0, v[20:21]
	v_mov_b64_e32 v[108:109], v[198:199]
	v_mov_b64_e32 v[110:111], v[200:201]
	v_pk_add_f32 v[22:23], v[110:111], 1.0 op_sel_hi:[1,0]
	v_pk_add_f32 v[108:109], v[108:109], 1.0 op_sel_hi:[1,0]
	v_pk_fma_f32 v[14:15], v[14:15], v[22:23], v[106:107]
	v_pk_fma_f32 v[12:13], v[12:13], v[108:109], v[104:105]
	s_nop 0
	v_cvt_pk_bf16_f32 v12, v12, v13
	v_cvt_pk_bf16_f32 v13, v14, v15
	global_store_dwordx2 v[84:85], v[12:13], off offset:512
	v_lshlrev_b32_e32 v12, 2, v70
	v_mov_b32_e32 v13, v153
	v_lshl_add_u64 v[14:15], v[100:101], 0, v[12:13]
	v_mov_b64_e32 v[104:105], v[190:191]
	v_mov_b64_e32 v[106:107], v[192:193]
	v_lshl_add_u64 v[14:15], v[98:99], 0, v[12:13]
	v_mov_b64_e32 v[108:109], v[202:203]
	v_mov_b64_e32 v[110:111], v[204:205]
	v_pk_add_f32 v[14:15], v[110:111], 1.0 op_sel_hi:[1,0]
	v_pk_add_f32 v[22:23], v[108:109], 1.0 op_sel_hi:[1,0]
	v_pk_fma_f32 v[6:7], v[6:7], v[14:15], v[106:107]
	v_pk_fma_f32 v[4:5], v[4:5], v[22:23], v[104:105]
	s_nop 0
	v_cvt_pk_bf16_f32 v4, v4, v5
	v_cvt_pk_bf16_f32 v5, v6, v7
	global_store_dwordx2 v[84:85], v[4:5], off offset:1024
	v_lshlrev_b32_e32 v4, 2, v72
	v_mov_b32_e32 v5, v153
	v_lshl_add_u64 v[6:7], v[100:101], 0, v[4:5]
	v_mov_b64_e32 v[104:105], v[194:195]
	v_mov_b64_e32 v[106:107], v[196:197]
	v_lshl_add_u64 v[6:7], v[98:99], 0, v[4:5]
	v_mov_b64_e32 v[98:99], v[224:225]
	v_mov_b64_e32 v[100:101], v[226:227]
	v_pk_add_f32 v[6:7], v[100:101], 1.0 op_sel_hi:[1,0]
	v_pk_add_f32 v[14:15], v[98:99], 1.0 op_sel_hi:[1,0]
	v_pk_fma_f32 v[2:3], v[2:3], v[6:7], v[106:107]
	v_pk_fma_f32 v[0:1], v[0:1], v[14:15], v[104:105]
	s_nop 0
	v_cvt_pk_bf16_f32 v0, v0, v1
	v_cvt_pk_bf16_f32 v1, v2, v3
	global_store_dwordx2 v[84:85], v[0:1], off offset:1536
	v_lshl_add_u64 v[0:1], s[60:61], 0, v[102:103]
	v_lshl_add_u64 v[2:3], v[0:1], 0, s[4:5]
	v_lshl_add_u64 v[0:1], v[0:1], 0, s[8:9]
	v_lshl_add_u64 v[6:7], v[2:3], 0, v[152:153]
	global_load_dwordx4 v[186:189], v[6:7], off offset:1024
	global_load_dwordx4 v[190:193], v[6:7], off offset:2048
	global_load_dwordx4 v[194:197], v[6:7], off offset:3072
	global_load_dwordx4 v[98:101], v[6:7], off
	v_lshl_add_u64 v[6:7], v[0:1], 0, v[152:153]
	global_load_dwordx4 v[198:201], v[6:7], off offset:1024
	global_load_dwordx4 v[202:205], v[6:7], off offset:2048
	global_load_dwordx4 v[224:227], v[6:7], off offset:3072
	global_load_dwordx4 v[102:105], v[6:7], off
	s_waitcnt vmcnt(0) lgkmcnt(0)
	v_pk_add_f32 v[6:7], v[104:105], 1.0 op_sel_hi:[1,0]
	v_pk_add_f32 v[14:15], v[102:103], 1.0 op_sel_hi:[1,0]
	v_pk_fma_f32 v[6:7], v[10:11], v[6:7], v[100:101]
	v_pk_fma_f32 v[8:9], v[8:9], v[14:15], v[98:99]
	v_lshl_add_u64 v[10:11], v[82:83], 0, v[90:91]
	v_cvt_pk_bf16_f32 v8, v8, v9
	v_cvt_pk_bf16_f32 v9, v6, v7
	global_store_dwordx2 v[10:11], v[8:9], off
	v_lshl_add_u64 v[6:7], v[2:3], 0, v[20:21]
	v_lshl_add_u64 v[14:15], v[0:1], 0, v[20:21]
	v_mov_b64_e32 v[6:7], v[186:187]
	v_mov_b64_e32 v[8:9], v[188:189]
	s_nop 0
	v_mov_b64_e32 v[98:99], v[198:199]
	v_mov_b64_e32 v[100:101], v[200:201]
	v_pk_add_f32 v[14:15], v[100:101], 1.0 op_sel_hi:[1,0]
	v_pk_add_f32 v[22:23], v[98:99], 1.0 op_sel_hi:[1,0]
	v_pk_fma_f32 v[8:9], v[30:31], v[14:15], v[8:9]
	v_pk_fma_f32 v[6:7], v[28:29], v[22:23], v[6:7]
	v_lshl_add_u64 v[14:15], v[0:1], 0, v[12:13]
	v_cvt_pk_bf16_f32 v6, v6, v7
	v_cvt_pk_bf16_f32 v7, v8, v9
	global_store_dwordx2 v[10:11], v[6:7], off offset:512
	v_lshl_add_u64 v[6:7], v[2:3], 0, v[12:13]
	v_mov_b64_e32 v[6:7], v[190:191]
	v_mov_b64_e32 v[8:9], v[192:193]
	v_lshl_add_u64 v[2:3], v[2:3], 0, v[4:5]
	v_mov_b64_e32 v[28:29], v[202:203]
	v_mov_b64_e32 v[30:31], v[204:205]
	v_lshl_add_u64 v[0:1], v[0:1], 0, v[4:5]
	v_pk_add_f32 v[14:15], v[30:31], 1.0 op_sel_hi:[1,0]
	v_pk_add_f32 v[22:23], v[28:29], 1.0 op_sel_hi:[1,0]
	v_pk_fma_f32 v[8:9], v[26:27], v[14:15], v[8:9]
	v_pk_fma_f32 v[6:7], v[24:25], v[22:23], v[6:7]
	s_nop 0
	v_cvt_pk_bf16_f32 v6, v6, v7
	v_cvt_pk_bf16_f32 v7, v8, v9
	global_store_dwordx2 v[10:11], v[6:7], off offset:1024
	v_mov_b64_e32 v[6:7], v[194:195]
	v_mov_b64_e32 v[8:9], v[196:197]
	s_nop 0
	v_mov_b64_e32 v[0:1], v[224:225]
	v_mov_b64_e32 v[2:3], v[226:227]
	v_pk_add_f32 v[2:3], v[2:3], 1.0 op_sel_hi:[1,0]
	v_pk_add_f32 v[0:1], v[0:1], 1.0 op_sel_hi:[1,0]
	v_pk_fma_f32 v[2:3], v[18:19], v[2:3], v[8:9]
	v_pk_fma_f32 v[0:1], v[16:17], v[0:1], v[6:7]
	v_lshl_add_u64 v[18:19], v[82:83], 0, v[94:95]
	v_cvt_pk_bf16_f32 v0, v0, v1
	v_cvt_pk_bf16_f32 v1, v2, v3
	global_store_dwordx2 v[10:11], v[0:1], off offset:1536
	v_lshl_add_u64 v[0:1], s[60:61], 0, v[92:93]
	v_lshl_add_u64 v[2:3], v[0:1], 0, s[4:5]
	v_lshl_add_u64 v[0:1], v[0:1], 0, s[8:9]
	v_lshl_add_u64 v[6:7], v[2:3], 0, v[152:153]
	v_lshl_add_u64 v[10:11], v[0:1], 0, v[152:153]
	global_load_dwordx4 v[186:189], v[6:7], off offset:1024
	global_load_dwordx4 v[190:193], v[6:7], off offset:2048
	global_load_dwordx4 v[194:197], v[6:7], off offset:3072
	global_load_dwordx4 v[6:9], v[6:7], off
	s_nop 0
	global_load_dwordx4 v[198:201], v[10:11], off offset:1024
	global_load_dwordx4 v[202:205], v[10:11], off offset:2048
	global_load_dwordx4 v[224:227], v[10:11], off offset:3072
	global_load_dwordx4 v[14:17], v[10:11], off
	s_waitcnt vmcnt(0) lgkmcnt(0)
	v_pk_add_f32 v[10:11], v[16:17], 1.0 op_sel_hi:[1,0]
	v_pk_add_f32 v[14:15], v[14:15], 1.0 op_sel_hi:[1,0]
	v_pk_fma_f32 v[8:9], v[62:63], v[10:11], v[8:9]
	v_pk_fma_f32 v[6:7], v[60:61], v[14:15], v[6:7]
	v_lshl_add_u64 v[10:11], v[82:83], 0, v[96:97]
	v_cvt_pk_bf16_f32 v6, v6, v7
	v_cvt_pk_bf16_f32 v7, v8, v9
	global_store_dwordx2 v[10:11], v[6:7], off
	v_lshl_add_u64 v[6:7], v[2:3], 0, v[20:21]
	v_lshl_add_u64 v[14:15], v[0:1], 0, v[20:21]
	v_mov_b64_e32 v[6:7], v[186:187]
	v_mov_b64_e32 v[8:9], v[188:189]
	s_nop 0
	v_mov_b64_e32 v[14:15], v[198:199]
	v_mov_b64_e32 v[16:17], v[200:201]
	v_pk_add_f32 v[16:17], v[16:17], 1.0 op_sel_hi:[1,0]
	v_pk_add_f32 v[14:15], v[14:15], 1.0 op_sel_hi:[1,0]
	v_pk_fma_f32 v[8:9], v[58:59], v[16:17], v[8:9]
	v_pk_fma_f32 v[6:7], v[56:57], v[14:15], v[6:7]
	v_lshl_add_u64 v[14:15], v[0:1], 0, v[12:13]
	v_cvt_pk_bf16_f32 v6, v6, v7
	v_cvt_pk_bf16_f32 v7, v8, v9
	global_store_dwordx2 v[10:11], v[6:7], off offset:512
	v_lshl_add_u64 v[6:7], v[2:3], 0, v[12:13]
	v_mov_b64_e32 v[6:7], v[190:191]
	v_mov_b64_e32 v[8:9], v[192:193]
	v_lshl_add_u64 v[2:3], v[2:3], 0, v[4:5]
	v_mov_b64_e32 v[14:15], v[202:203]
	v_mov_b64_e32 v[16:17], v[204:205]
	v_lshl_add_u64 v[0:1], v[0:1], 0, v[4:5]
	v_pk_add_f32 v[16:17], v[16:17], 1.0 op_sel_hi:[1,0]
	v_pk_add_f32 v[14:15], v[14:15], 1.0 op_sel_hi:[1,0]
	v_pk_fma_f32 v[8:9], v[54:55], v[16:17], v[8:9]
	v_pk_fma_f32 v[6:7], v[52:53], v[14:15], v[6:7]
	s_nop 0
	v_cvt_pk_bf16_f32 v6, v6, v7
	v_cvt_pk_bf16_f32 v7, v8, v9
	global_store_dwordx2 v[10:11], v[6:7], off offset:1024
	v_mov_b64_e32 v[6:7], v[194:195]
	v_mov_b64_e32 v[8:9], v[196:197]
	s_nop 0
	v_mov_b64_e32 v[0:1], v[224:225]
	v_mov_b64_e32 v[2:3], v[226:227]
	v_pk_add_f32 v[2:3], v[2:3], 1.0 op_sel_hi:[1,0]
	v_pk_add_f32 v[0:1], v[0:1], 1.0 op_sel_hi:[1,0]
	v_pk_fma_f32 v[2:3], v[50:51], v[2:3], v[8:9]
	v_pk_fma_f32 v[0:1], v[48:49], v[0:1], v[6:7]
	s_nop 0
	v_cvt_pk_bf16_f32 v0, v0, v1
	v_cvt_pk_bf16_f32 v1, v2, v3
	global_store_dwordx2 v[10:11], v[0:1], off offset:1536
	v_lshl_add_u64 v[0:1], s[60:61], 0, v[88:89]
	v_lshl_add_u64 v[2:3], v[0:1], 0, s[4:5]
	v_lshl_add_u64 v[0:1], v[0:1], 0, s[8:9]
	v_lshl_add_u64 v[6:7], v[2:3], 0, v[152:153]
	v_lshl_add_u64 v[10:11], v[0:1], 0, v[152:153]
	global_load_dwordx4 v[186:189], v[6:7], off offset:1024
	global_load_dwordx4 v[190:193], v[6:7], off offset:2048
	global_load_dwordx4 v[194:197], v[6:7], off offset:3072
	global_load_dwordx4 v[6:9], v[6:7], off
	s_nop 0
	global_load_dwordx4 v[198:201], v[10:11], off offset:1024
	global_load_dwordx4 v[202:205], v[10:11], off offset:2048
	global_load_dwordx4 v[224:227], v[10:11], off offset:3072
	global_load_dwordx4 v[14:17], v[10:11], off
	s_waitcnt vmcnt(0) lgkmcnt(0)
	v_pk_add_f32 v[10:11], v[16:17], 1.0 op_sel_hi:[1,0]
	v_pk_add_f32 v[14:15], v[14:15], 1.0 op_sel_hi:[1,0]
	v_pk_fma_f32 v[8:9], v[46:47], v[10:11], v[8:9]
	v_pk_fma_f32 v[6:7], v[44:45], v[14:15], v[6:7]
	v_lshl_add_u64 v[10:11], v[0:1], 0, v[20:21]
	v_cvt_pk_bf16_f32 v6, v6, v7
	v_cvt_pk_bf16_f32 v7, v8, v9
	global_store_dwordx2 v[18:19], v[6:7], off
	v_lshl_add_u64 v[6:7], v[2:3], 0, v[20:21]
	v_mov_b64_e32 v[6:7], v[186:187]
	v_mov_b64_e32 v[8:9], v[188:189]
	s_nop 0
	v_mov_b64_e32 v[14:15], v[198:199]
	v_mov_b64_e32 v[16:17], v[200:201]
	v_pk_add_f32 v[10:11], v[16:17], 1.0 op_sel_hi:[1,0]
	v_pk_add_f32 v[14:15], v[14:15], 1.0 op_sel_hi:[1,0]
	v_pk_fma_f32 v[8:9], v[42:43], v[10:11], v[8:9]
	v_pk_fma_f32 v[6:7], v[40:41], v[14:15], v[6:7]
	v_lshl_add_u64 v[10:11], v[0:1], 0, v[12:13]
	v_cvt_pk_bf16_f32 v6, v6, v7
	v_cvt_pk_bf16_f32 v7, v8, v9
	global_store_dwordx2 v[18:19], v[6:7], off offset:512
	v_lshl_add_u64 v[6:7], v[2:3], 0, v[12:13]
	v_mov_b64_e32 v[6:7], v[190:191]
	v_mov_b64_e32 v[8:9], v[192:193]
	v_lshl_add_u64 v[2:3], v[2:3], 0, v[4:5]
	v_mov_b64_e32 v[10:11], v[202:203]
	v_mov_b64_e32 v[12:13], v[204:205]
	v_lshl_add_u64 v[0:1], v[0:1], 0, v[4:5]
	v_pk_add_f32 v[12:13], v[12:13], 1.0 op_sel_hi:[1,0]
	v_pk_add_f32 v[10:11], v[10:11], 1.0 op_sel_hi:[1,0]
	v_pk_fma_f32 v[8:9], v[38:39], v[12:13], v[8:9]
	v_pk_fma_f32 v[6:7], v[36:37], v[10:11], v[6:7]
	s_nop 0
	v_cvt_pk_bf16_f32 v6, v6, v7
	v_cvt_pk_bf16_f32 v7, v8, v9
	global_store_dwordx2 v[18:19], v[6:7], off offset:1024
	v_mov_b64_e32 v[6:7], v[194:195]
	v_mov_b64_e32 v[8:9], v[196:197]
	s_nop 0
	v_mov_b64_e32 v[0:1], v[224:225]
	v_mov_b64_e32 v[2:3], v[226:227]
	v_pk_add_f32 v[2:3], v[2:3], 1.0 op_sel_hi:[1,0]
	v_pk_add_f32 v[0:1], v[0:1], 1.0 op_sel_hi:[1,0]
	v_pk_fma_f32 v[2:3], v[34:35], v[2:3], v[8:9]
	v_pk_fma_f32 v[0:1], v[32:33], v[0:1], v[6:7]
	s_nop 0
	v_cvt_pk_bf16_f32 v0, v0, v1
	v_cvt_pk_bf16_f32 v1, v2, v3
	global_store_dwordx2 v[18:19], v[0:1], off offset:1536
	s_branch .LBB0_50

.LBB0_70:
	s_and_b32 s35, s2, 3
	v_readlane_b32 s2, v254, 37
	s_or_b32 s2, s35, s2
	s_lshl_b64 s[4:5], s[2:3], 2
	v_readlane_b32 s76, v252, 15
	v_readlane_b32 s77, v252, 16
	s_add_u32 s14, s76, s4
	v_mov_b32_e32 v157, v206
	s_addc_u32 s15, s77, s5
	global_load_dword v1, v153, s[14:15]
	s_mov_b32 s13, 0xbfb8aa3b
	s_mov_b32 s16, 0x42ce8ed0
	s_mov_b32 s17, 0xc2b17218
	v_mov_b32_e32 v5, 0x7f800000
	v_readlane_b32 s78, v252, 17
	v_readlane_b32 s79, v252, 18
	v_mov_b32_e32 v6, 0x42000000
	v_ashrrev_i32_e32 v0, 6, v157
	v_and_b32_e32 v115, 15, v157
	v_lshl_or_b32 v92, v0, 4, v115
	v_readlane_b32 s88, v252, 27
	v_add_u32_e32 v191, 0x200, v157
	v_add_u32_e32 v193, 0x400, v157
	v_add_u32_e32 v195, 0x600, v157
	v_lshlrev_b32_e32 v16, 4, v157
	v_ashrrev_i32_e32 v189, 4, v157
	v_ashrrev_i32_e32 v190, 4, v191
	v_ashrrev_i32_e32 v192, 4, v193
	v_ashrrev_i32_e32 v194, 4, v195
	v_readlane_b32 s89, v252, 28
	v_and_b32_e32 v32, 0xf0, v16
	v_bfe_u32 v62, v157, 4, 2
	s_mov_b32 s89, s3
	v_mov_b32_e32 v33, v153
	v_lshlrev_b32_e32 v152, 4, v62
	v_add_u32_e32 v52, 0, v32
	v_add_u32_e32 v36, 0xa00, v157
	v_add_u32_e32 v40, 0xc00, v157
	v_add_u32_e32 v46, 0xe00, v157
	v_mul_u32_u24_e32 v49, 0x110, v115
	v_add3_u32 v197, 0, v152, v49
	v_lshlrev_b32_e32 v196, 2, v62
	v_readlane_b32 s85, v252, 24
	v_readlane_b32 s86, v252, 25
	v_readlane_b32 s87, v252, 26
	v_readlane_b32 s80, v252, 19
	v_readlane_b32 s81, v252, 20
	v_lshlrev_b32_e32 v198, 2, v157
	v_and_b32_e32 v199, 0x7c, v198
	v_readlane_b32 s76, v254, 3
	v_readlane_b32 s80, v254, 5
	s_mov_b32 s2, 0
	v_lshl_add_u32 v114, v199, 1, 0
	v_readlane_b32 s77, v254, 4
	v_readlane_b32 s81, v254, 6
	v_readlane_b32 s82, v252, 21
	v_readlane_b32 s83, v252, 22
	v_readlane_b32 s84, v252, 23
	v_readlane_b32 s90, v252, 29
	v_readlane_b32 s91, v252, 30
	s_waitcnt vmcnt(0)
	v_mul_f32_e32 v2, 0xbfb8aa3b, v1
	v_fma_f32 v3, v1, s13, -v2
	v_rndne_f32_e32 v4, v2
	v_fmac_f32_e32 v3, 0xb2a5705f, v1
	v_sub_f32_e32 v2, v2, v4
	v_add_f32_e32 v2, v2, v3
	v_exp_f32_e32 v2, v2
	v_cvt_i32_f32_e32 v3, v4
	v_cmp_nlt_f32_e32 vcc, s16, v1
	v_ldexp_f32 v2, v2, v3
	s_nop 0
	v_cndmask_b32_e32 v2, 0, v2, vcc
	v_cmp_ngt_f32_e32 vcc, s17, v1
	s_nop 1
	v_cndmask_b32_e32 v1, v5, v2, vcc
	v_add_f32_e32 v1, 1.0, v1
	v_cmp_gt_f32_e32 vcc, s68, v1
	s_and_b64 s[14:15], vcc, exec
	s_cselect_b32 s11, 32, 0
	v_ldexp_f32 v1, v1, s11
	v_log_f32_e32 v1, v1
	s_add_u32 s4, s78, s4
	v_cndmask_b32_e32 v2, 0, v6, vcc
	s_addc_u32 s5, s79, s5
	v_sub_f32_e32 v177, v1, v2
	global_load_dword v1, v153, s[4:5]
	v_readlane_b32 s14, v255, 11
	v_readlane_b32 s15, v255, 12
	v_readlane_b32 s11, v254, 42
	v_readlane_b32 s78, v254, 7
	v_readlane_b32 s79, v254, 8
	s_waitcnt vmcnt(0)
	v_mul_f32_e32 v2, 0xbfb8aa3b, v1
	v_fma_f32 v3, v1, s13, -v2
	v_rndne_f32_e32 v4, v2
	v_fmac_f32_e32 v3, 0xb2a5705f, v1
	v_sub_f32_e32 v2, v2, v4
	v_add_f32_e32 v2, v2, v3
	v_exp_f32_e32 v2, v2
	v_cvt_i32_f32_e32 v3, v4
	v_cmp_nlt_f32_e32 vcc, s16, v1
	v_ldexp_f32 v2, v2, v3
	s_nop 0
	v_cndmask_b32_e32 v2, 0, v2, vcc
	v_cmp_ngt_f32_e32 vcc, s17, v1
	s_nop 1
	v_cndmask_b32_e32 v1, v5, v2, vcc
	v_add_f32_e32 v1, 1.0, v1
	v_cmp_gt_f32_e32 vcc, s68, v1
	s_and_b64 s[4:5], vcc, exec
	s_cselect_b32 s4, 32, 0
	v_ldexp_f32 v1, v1, s4
	v_log_f32_e32 v1, v1
	s_movk_i32 s4, 0x1100
	s_lshl_b32 s71, s33, 7
	v_mul_lo_u32 v48, v0, s4
	s_add_i32 s4, s12, s71
	v_add_u32_e32 v112, s4, v92
	v_cndmask_b32_e32 v2, 0, v6, vcc
	v_ashrrev_i32_e32 v113, 31, v112
	v_sub_f32_e32 v188, v1, v2
	v_lshlrev_b64 v[0:1], 10, v[112:113]
	s_ashr_i32 s13, s12, 31
	v_lshl_add_u64 v[0:1], s[14:15], 0, v[0:1]
	s_lshl_b32 s88, s35, 8
	s_lshl_b64 s[12:13], s[12:13], 11
	v_readlane_b32 s14, v254, 39
	v_readlane_b32 s15, v254, 40
	s_add_u32 s14, s14, s88
	v_add_u32_e32 v16, s4, v189
	v_add_u32_e32 v20, s4, v190
	v_add_u32_e32 v24, s4, v192
	v_add_u32_e32 v30, s4, v194
	s_addc_u32 s15, s15, 0
	v_ashrrev_i32_e32 v17, 31, v16
	v_ashrrev_i32_e32 v21, 31, v20
	v_ashrrev_i32_e32 v25, 31, v24
	v_ashrrev_i32_e32 v31, 31, v30
	v_lshl_add_u64 v[0:1], v[0:1], 0, s[88:89]
	v_lshl_add_u64 v[28:29], s[14:15], 0, v[32:33]
	v_lshlrev_b64 v[16:17], 10, v[16:17]
	v_lshlrev_b64 v[20:21], 10, v[20:21]
	v_lshlrev_b64 v[24:25], 10, v[24:25]
	v_lshlrev_b64 v[30:31], 10, v[30:31]
	v_lshl_add_u64 v[12:13], v[0:1], 0, v[152:153]
	v_lshl_add_u64 v[16:17], v[28:29], 0, v[16:17]
	v_lshl_add_u64 v[20:21], v[28:29], 0, v[20:21]
	v_lshl_add_u64 v[24:25], v[28:29], 0, v[24:25]
	v_lshl_add_u64 v[28:29], v[28:29], 0, v[30:31]
	global_load_dwordx4 v[0:3], v[12:13], off
	global_load_dwordx4 v[4:7], v[12:13], off offset:64
	global_load_dwordx4 v[8:11], v[12:13], off offset:128
	s_nop 0
	global_load_dwordx4 v[12:15], v[12:13], off offset:192
	v_readlane_b32 s4, v254, 41
	global_load_dwordx4 v[16:19], v[16:17], off
	s_mul_i32 s5, s10, s88
	global_load_dwordx4 v[20:23], v[20:21], off
	s_add_u32 s4, s4, s12
	global_load_dwordx4 v[24:27], v[24:25], off
	s_addc_u32 s11, s11, s13
	global_load_dwordx4 v[28:31], v[28:29], off
	s_lshl_b32 s5, s5, 1
	s_add_u32 s12, s4, s5
	v_mad_u64_u32 v[54:55], s[4:5], v189, s73, v[52:53]
	v_mad_u64_u32 v[56:57], s[4:5], v190, s73, v[52:53]
	v_mad_u64_u32 v[58:59], s[4:5], v192, s73, v[52:53]
	v_mad_u64_u32 v[60:61], s[4:5], v194, s73, v[52:53]
	s_addc_u32 s11, s11, 0
	s_lshl_b32 s4, s33, 8
	s_add_u32 s4, s12, s4
	s_addc_u32 s5, s11, 0
	v_lshl_add_u64 v[44:45], s[4:5], 0, v[32:33]
	v_add_u32_e32 v32, 0x800, v157
	v_ashrrev_i32_e32 v53, 4, v32
	v_ashrrev_i32_e32 v55, 4, v36
	v_ashrrev_i32_e32 v57, 4, v40
	v_ashrrev_i32_e32 v59, 4, v46
	v_mad_i64_i32 v[32:33], s[4:5], s10, v53, 0
	v_mad_i64_i32 v[36:37], s[4:5], s10, v55, 0
	v_mad_i64_i32 v[40:41], s[4:5], s10, v57, 0
	v_mad_i64_i32 v[46:47], s[4:5], s10, v59, 0
	v_lshl_add_u64 v[32:33], v[32:33], 1, v[44:45]
	v_lshl_add_u64 v[36:37], v[36:37], 1, v[44:45]
	v_lshl_add_u64 v[40:41], v[40:41], 1, v[44:45]
	s_sub_i32 s85, s9, s33
	s_ashr_i32 s9, s8, 31
	s_add_i32 s74, s33, 1
	s_xor_b32 s86, s71, 0x380
	s_waitcnt vmcnt(0) lgkmcnt(0)
	ds_write_b128 v54, v[16:19]
	v_mad_i64_i32 v[16:17], s[4:5], s10, v189, 0
	ds_write_b128 v56, v[20:23]
	ds_write_b128 v58, v[24:27]
	v_mad_i64_i32 v[20:21], s[4:5], s10, v190, 0
	ds_write_b128 v60, v[28:31]
	v_mad_i64_i32 v[24:25], s[4:5], s10, v192, 0
	v_mad_i64_i32 v[28:29], s[4:5], s10, v194, 0
	v_readlane_b32 s4, v253, 47
	s_waitcnt lgkmcnt(0)
	s_barrier
	v_add3_u32 v61, s4, v48, v49
	ds_read_b128 v[48:51], v197
	ds_read_b128 v[66:69], v197 offset:64
	s_waitcnt lgkmcnt(1)
	v_mfma_f32_16x16x32_bf16 v[48:51], v[48:51], v[0:3], 0
	v_lshl_add_u32 v64, v62, 3, v61
	v_sub_u32_e32 v62, v92, v196
	v_sub_u32_e32 v63, 0, v62
	s_waitcnt lgkmcnt(0)
	v_mfma_f32_16x16x32_bf16 v[48:51], v[66:69], v[4:7], v[48:51]
	ds_read_b128 v[66:69], v197 offset:128
	v_max_i32_e32 v63, v62, v63
	v_cvt_f32_u32_e32 v63, v63
	v_cmp_gt_i32_e32 vcc, 0, v62
	s_waitcnt lgkmcnt(0)
	v_mfma_f32_16x16x32_bf16 v[48:51], v[66:69], v[8:11], v[48:51]
	ds_read_b128 v[66:69], v197 offset:192
	v_cndmask_b32_e32 v62, v177, v188, vcc
	v_mul_f32_e64 v62, -v62, v63
	v_xad_u32 v63, v196, -1, v92
	v_sub_u32_e32 v65, 0, v63
	v_max_i32_e32 v65, v63, v65
	v_cvt_f32_u32_e32 v65, v65
	v_cmp_gt_i32_e32 vcc, 0, v63
	s_waitcnt lgkmcnt(0)
	v_mfma_f32_16x16x32_bf16 v[48:51], v[66:69], v[12:15], v[48:51]
	v_cndmask_b32_e32 v63, v177, v188, vcc
	v_mul_f32_e64 v63, -v63, v65
	v_exp_f32_e32 v62, v62
	v_exp_f32_e32 v63, v63
	v_lshl_add_u64 v[16:17], v[16:17], 1, v[44:45]
	v_lshl_add_u64 v[20:21], v[20:21], 1, v[44:45]
	v_lshl_add_u64 v[24:25], v[24:25], 1, v[44:45]
	s_nop 0
	v_pk_mul_f32 v[48:49], v[62:63], v[48:49]
	v_or_b32_e32 v62, 2, v196
	v_sub_u32_e32 v62, v92, v62
	v_sub_u32_e32 v63, 0, v62
	v_max_i32_e32 v63, v62, v63
	v_cvt_f32_u32_e32 v63, v63
	v_cmp_gt_i32_e32 vcc, 0, v62
	v_lshl_add_u64 v[28:29], v[28:29], 1, v[44:45]
	v_lshl_add_u64 v[44:45], v[46:47], 1, v[44:45]
	v_cndmask_b32_e32 v62, v177, v188, vcc
	v_mul_f32_e64 v62, -v62, v63
	v_or_b32_e32 v63, 3, v196
	v_sub_u32_e32 v63, v92, v63
	v_sub_u32_e32 v65, 0, v63
	v_max_i32_e32 v65, v63, v65
	v_cvt_f32_u32_e32 v65, v65
	v_cmp_gt_i32_e32 vcc, 0, v63
	v_exp_f32_e32 v62, v62
	v_cvt_pk_bf16_f32 v48, v48, v49
	v_cndmask_b32_e32 v63, v177, v188, vcc
	v_mul_f32_e64 v63, -v63, v65
	v_exp_f32_e32 v63, v63
	global_load_dwordx4 v[16:19], v[16:17], off
	v_pk_mul_f32 v[50:51], v[62:63], v[50:51]
	s_nop 0
	v_cvt_pk_bf16_f32 v49, v50, v51
	global_load_dwordx4 v[20:23], v[20:21], off
	v_or_b32_e32 v62, 16, v196
	global_load_dwordx4 v[24:27], v[24:25], off
	v_sub_u32_e32 v62, v92, v62
	global_load_dwordx4 v[28:31], v[28:29], off
	v_sub_u32_e32 v63, 0, v62
	global_load_dwordx4 v[32:35], v[32:33], off
	v_max_i32_e32 v63, v62, v63
	global_load_dwordx4 v[36:39], v[36:37], off
	v_cvt_f32_u32_e32 v63, v63
	global_load_dwordx4 v[40:43], v[40:41], off
	v_cmp_gt_i32_e32 vcc, 0, v62
	global_load_dwordx4 v[44:47], v[44:45], off
	ds_write_b64 v64, v[48:49]
	ds_read_b128 v[48:51], v197 offset:4352
	ds_read_b128 v[66:69], v197 offset:4416
	s_waitcnt lgkmcnt(0)
	v_mfma_f32_16x16x32_bf16 v[48:51], v[48:51], v[0:3], 0
	v_cndmask_b32_e32 v62, v177, v188, vcc
	v_mul_f32_e64 v62, -v62, v63
	v_or_b32_e32 v63, 17, v196
	v_mfma_f32_16x16x32_bf16 v[48:51], v[66:69], v[4:7], v[48:51]
	ds_read_b128 v[66:69], v197 offset:4480
	v_sub_u32_e32 v63, v92, v63
	v_sub_u32_e32 v65, 0, v63
	s_waitcnt lgkmcnt(0)
	v_mfma_f32_16x16x32_bf16 v[48:51], v[66:69], v[8:11], v[48:51]
	ds_read_b128 v[66:69], v197 offset:4544
	v_max_i32_e32 v65, v63, v65
	v_cvt_f32_u32_e32 v65, v65
	v_cmp_gt_i32_e32 vcc, 0, v63
	s_waitcnt lgkmcnt(0)
	v_mfma_f32_16x16x32_bf16 v[48:51], v[66:69], v[12:15], v[48:51]
	v_cndmask_b32_e32 v63, v177, v188, vcc
	v_mul_f32_e64 v63, -v63, v65
	v_exp_f32_e32 v62, v62
	v_exp_f32_e32 v63, v63
	s_nop 3
	v_pk_mul_f32 v[48:49], v[62:63], v[48:49]
	v_or_b32_e32 v62, 18, v196
	v_sub_u32_e32 v62, v92, v62
	v_sub_u32_e32 v63, 0, v62
	v_max_i32_e32 v63, v62, v63
	v_cvt_f32_u32_e32 v63, v63
	v_cmp_gt_i32_e32 vcc, 0, v62
	v_cvt_pk_bf16_f32 v48, v48, v49
	s_nop 0
	v_cndmask_b32_e32 v62, v177, v188, vcc
	v_mul_f32_e64 v62, -v62, v63
	v_or_b32_e32 v63, 19, v196
	v_sub_u32_e32 v63, v92, v63
	v_sub_u32_e32 v65, 0, v63
	v_max_i32_e32 v65, v63, v65
	v_cvt_f32_u32_e32 v65, v65
	v_cmp_gt_i32_e32 vcc, 0, v63
	v_exp_f32_e32 v62, v62
	s_nop 0
	v_cndmask_b32_e32 v63, v177, v188, vcc
	v_mul_f32_e64 v63, -v63, v65
	v_exp_f32_e32 v63, v63
	s_nop 0
	v_pk_mul_f32 v[50:51], v[62:63], v[50:51]
	s_nop 0
	v_cvt_pk_bf16_f32 v49, v50, v51
	ds_write_b64 v64, v[48:49] offset:32
	ds_read_b128 v[48:51], v197 offset:8704
	ds_read_b128 v[66:69], v197 offset:8768
	s_waitcnt lgkmcnt(0)
	v_mfma_f32_16x16x32_bf16 v[48:51], v[48:51], v[0:3], 0
	v_or_b32_e32 v62, 32, v196
	v_sub_u32_e32 v62, v92, v62
	v_sub_u32_e32 v63, 0, v62
	v_mfma_f32_16x16x32_bf16 v[48:51], v[66:69], v[4:7], v[48:51]
	ds_read_b128 v[66:69], v197 offset:8832
	v_max_i32_e32 v63, v62, v63
	v_cvt_f32_u32_e32 v63, v63
	v_cmp_gt_i32_e32 vcc, 0, v62
	s_waitcnt lgkmcnt(0)
	v_mfma_f32_16x16x32_bf16 v[48:51], v[66:69], v[8:11], v[48:51]
	v_cndmask_b32_e32 v62, v177, v188, vcc
	ds_read_b128 v[66:69], v197 offset:8896
	v_mul_f32_e64 v62, -v62, v63
	v_or_b32_e32 v63, 33, v196
	v_sub_u32_e32 v63, v92, v63
	v_sub_u32_e32 v65, 0, v63
	v_max_i32_e32 v65, v63, v65
	v_cvt_f32_u32_e32 v65, v65
	v_cmp_gt_i32_e32 vcc, 0, v63
	s_waitcnt lgkmcnt(0)
	v_mfma_f32_16x16x32_bf16 v[48:51], v[66:69], v[12:15], v[48:51]
	v_cndmask_b32_e32 v63, v177, v188, vcc
	v_mul_f32_e64 v63, -v63, v65
	v_exp_f32_e32 v62, v62
	v_exp_f32_e32 v63, v63
	s_nop 3
	v_pk_mul_f32 v[48:49], v[62:63], v[48:49]
	v_or_b32_e32 v62, 34, v196
	v_sub_u32_e32 v62, v92, v62
	v_sub_u32_e32 v63, 0, v62
	v_max_i32_e32 v63, v62, v63
	v_cvt_f32_u32_e32 v63, v63
	v_cmp_gt_i32_e32 vcc, 0, v62
	v_cvt_pk_bf16_f32 v48, v48, v49
	s_nop 0
	v_cndmask_b32_e32 v62, v177, v188, vcc
	v_mul_f32_e64 v62, -v62, v63
	v_or_b32_e32 v63, 35, v196
	v_sub_u32_e32 v63, v92, v63
	v_sub_u32_e32 v65, 0, v63
	v_max_i32_e32 v65, v63, v65
	v_cvt_f32_u32_e32 v65, v65
	v_cmp_gt_i32_e32 vcc, 0, v63
	v_exp_f32_e32 v62, v62
	s_nop 0
	v_cndmask_b32_e32 v63, v177, v188, vcc
	v_mul_f32_e64 v63, -v63, v65
	v_exp_f32_e32 v63, v63
	s_nop 0
	v_pk_mul_f32 v[50:51], v[62:63], v[50:51]
	s_nop 0
	v_cvt_pk_bf16_f32 v49, v50, v51
	ds_write_b64 v64, v[48:49] offset:64
	ds_read_b128 v[48:51], v197 offset:13056
	ds_read_b128 v[66:69], v197 offset:13120
	s_waitcnt lgkmcnt(0)
	v_mfma_f32_16x16x32_bf16 v[48:51], v[48:51], v[0:3], 0
	v_or_b32_e32 v62, 48, v196
	v_sub_u32_e32 v62, v92, v62
	v_sub_u32_e32 v63, 0, v62
	v_mfma_f32_16x16x32_bf16 v[48:51], v[66:69], v[4:7], v[48:51]
	ds_read_b128 v[66:69], v197 offset:13184
	v_max_i32_e32 v63, v62, v63
	v_cvt_f32_u32_e32 v63, v63
	v_cmp_gt_i32_e32 vcc, 0, v62
	s_waitcnt lgkmcnt(0)
	v_mfma_f32_16x16x32_bf16 v[48:51], v[66:69], v[8:11], v[48:51]
	v_cndmask_b32_e32 v62, v177, v188, vcc
	ds_read_b128 v[66:69], v197 offset:13248
	v_mul_f32_e64 v62, -v62, v63
	v_or_b32_e32 v63, 49, v196
	v_sub_u32_e32 v63, v92, v63
	v_sub_u32_e32 v65, 0, v63
	v_max_i32_e32 v65, v63, v65
	v_cvt_f32_u32_e32 v65, v65
	v_cmp_gt_i32_e32 vcc, 0, v63
	s_waitcnt lgkmcnt(0)
	v_mfma_f32_16x16x32_bf16 v[48:51], v[66:69], v[12:15], v[48:51]
	v_cndmask_b32_e32 v63, v177, v188, vcc
	v_mul_f32_e64 v63, -v63, v65
	v_exp_f32_e32 v62, v62
	v_exp_f32_e32 v63, v63
	s_nop 3
	v_pk_mul_f32 v[48:49], v[62:63], v[48:49]
	v_or_b32_e32 v62, 50, v196
	v_sub_u32_e32 v62, v92, v62
	v_sub_u32_e32 v63, 0, v62
	v_max_i32_e32 v63, v62, v63
	v_cvt_f32_u32_e32 v63, v63
	v_cmp_gt_i32_e32 vcc, 0, v62
	v_cvt_pk_bf16_f32 v48, v48, v49
	s_nop 0
	v_cndmask_b32_e32 v62, v177, v188, vcc
	v_mul_f32_e64 v62, -v62, v63
	v_or_b32_e32 v63, 51, v196
	v_sub_u32_e32 v63, v92, v63
	v_sub_u32_e32 v65, 0, v63
	v_max_i32_e32 v65, v63, v65
	v_cvt_f32_u32_e32 v65, v65
	v_cmp_gt_i32_e32 vcc, 0, v63
	v_exp_f32_e32 v62, v62
	s_nop 0
	v_cndmask_b32_e32 v63, v177, v188, vcc
	v_mul_f32_e64 v63, -v63, v65
	v_exp_f32_e32 v63, v63
	s_nop 0
	v_pk_mul_f32 v[50:51], v[62:63], v[50:51]
	s_nop 0
	v_cvt_pk_bf16_f32 v49, v50, v51
	ds_write_b64 v64, v[48:49] offset:96
	ds_read_b128 v[48:51], v197 offset:17408
	ds_read_b128 v[66:69], v197 offset:17472
	s_waitcnt lgkmcnt(0)
	v_mfma_f32_16x16x32_bf16 v[48:51], v[48:51], v[0:3], 0
	v_or_b32_e32 v62, 64, v196
	v_sub_u32_e32 v62, v92, v62
	v_sub_u32_e32 v63, 0, v62
	v_mfma_f32_16x16x32_bf16 v[48:51], v[66:69], v[4:7], v[48:51]
	ds_read_b128 v[66:69], v197 offset:17536
	v_max_i32_e32 v63, v62, v63
	v_cvt_f32_u32_e32 v63, v63
	v_cmp_gt_i32_e32 vcc, 0, v62
	s_waitcnt lgkmcnt(0)
	v_mfma_f32_16x16x32_bf16 v[48:51], v[66:69], v[8:11], v[48:51]
	v_cndmask_b32_e32 v62, v177, v188, vcc
	ds_read_b128 v[66:69], v197 offset:17600
	v_mul_f32_e64 v62, -v62, v63
	v_or_b32_e32 v63, 0x41, v196
	v_sub_u32_e32 v63, v92, v63
	v_sub_u32_e32 v65, 0, v63
	v_max_i32_e32 v65, v63, v65
	v_cvt_f32_u32_e32 v65, v65
	v_cmp_gt_i32_e32 vcc, 0, v63
	s_waitcnt lgkmcnt(0)
	v_mfma_f32_16x16x32_bf16 v[48:51], v[66:69], v[12:15], v[48:51]
	v_cndmask_b32_e32 v63, v177, v188, vcc
	v_mul_f32_e64 v63, -v63, v65
	v_exp_f32_e32 v62, v62
	v_exp_f32_e32 v63, v63
	s_nop 3
	v_pk_mul_f32 v[48:49], v[62:63], v[48:49]
	v_or_b32_e32 v62, 0x42, v196
	v_sub_u32_e32 v62, v92, v62
	v_sub_u32_e32 v63, 0, v62
	v_max_i32_e32 v63, v62, v63
	v_cvt_f32_u32_e32 v63, v63
	v_cmp_gt_i32_e32 vcc, 0, v62
	v_cvt_pk_bf16_f32 v48, v48, v49
	s_nop 0
	v_cndmask_b32_e32 v62, v177, v188, vcc
	v_mul_f32_e64 v62, -v62, v63
	v_or_b32_e32 v63, 0x43, v196
	v_sub_u32_e32 v63, v92, v63
	v_sub_u32_e32 v65, 0, v63
	v_max_i32_e32 v65, v63, v65
	v_cvt_f32_u32_e32 v65, v65
	v_cmp_gt_i32_e32 vcc, 0, v63
	v_exp_f32_e32 v62, v62
	s_nop 0
	v_cndmask_b32_e32 v63, v177, v188, vcc
	v_mul_f32_e64 v63, -v63, v65
	v_exp_f32_e32 v63, v63
	s_nop 0
	v_pk_mul_f32 v[50:51], v[62:63], v[50:51]
	s_nop 0
	v_cvt_pk_bf16_f32 v49, v50, v51
	ds_write_b64 v64, v[48:49] offset:128
	ds_read_b128 v[48:51], v197 offset:21760
	ds_read_b128 v[66:69], v197 offset:21824
	s_waitcnt lgkmcnt(0)
	v_mfma_f32_16x16x32_bf16 v[48:51], v[48:51], v[0:3], 0
	v_or_b32_e32 v62, 0x50, v196
	v_sub_u32_e32 v62, v92, v62
	v_sub_u32_e32 v63, 0, v62
	v_mfma_f32_16x16x32_bf16 v[48:51], v[66:69], v[4:7], v[48:51]
	ds_read_b128 v[66:69], v197 offset:21888
	v_max_i32_e32 v63, v62, v63
	v_cvt_f32_u32_e32 v63, v63
	v_cmp_gt_i32_e32 vcc, 0, v62
	s_waitcnt lgkmcnt(0)
	v_mfma_f32_16x16x32_bf16 v[48:51], v[66:69], v[8:11], v[48:51]
	v_cndmask_b32_e32 v62, v177, v188, vcc
	ds_read_b128 v[66:69], v197 offset:21952
	v_mul_f32_e64 v62, -v62, v63
	v_or_b32_e32 v63, 0x51, v196
	v_sub_u32_e32 v63, v92, v63
	v_sub_u32_e32 v65, 0, v63
	v_max_i32_e32 v65, v63, v65
	v_cvt_f32_u32_e32 v65, v65
	v_cmp_gt_i32_e32 vcc, 0, v63
	s_waitcnt lgkmcnt(0)
	v_mfma_f32_16x16x32_bf16 v[48:51], v[66:69], v[12:15], v[48:51]
	v_cndmask_b32_e32 v63, v177, v188, vcc
	v_mul_f32_e64 v63, -v63, v65
	v_exp_f32_e32 v62, v62
	v_exp_f32_e32 v63, v63
	s_nop 3
	v_pk_mul_f32 v[48:49], v[62:63], v[48:49]
	v_or_b32_e32 v62, 0x52, v196
	v_sub_u32_e32 v62, v92, v62
	v_sub_u32_e32 v63, 0, v62
	v_max_i32_e32 v63, v62, v63
	v_cvt_f32_u32_e32 v63, v63
	v_cmp_gt_i32_e32 vcc, 0, v62
	v_cvt_pk_bf16_f32 v48, v48, v49
	s_nop 0
	v_cndmask_b32_e32 v62, v177, v188, vcc
	v_mul_f32_e64 v62, -v62, v63
	v_or_b32_e32 v63, 0x53, v196
	v_sub_u32_e32 v63, v92, v63
	v_sub_u32_e32 v65, 0, v63
	v_max_i32_e32 v65, v63, v65
	v_cvt_f32_u32_e32 v65, v65
	v_cmp_gt_i32_e32 vcc, 0, v63
	v_exp_f32_e32 v62, v62
	s_nop 0
	v_cndmask_b32_e32 v63, v177, v188, vcc
	v_mul_f32_e64 v63, -v63, v65
	v_exp_f32_e32 v63, v63
	s_nop 0
	v_pk_mul_f32 v[50:51], v[62:63], v[50:51]
	s_nop 0
	v_cvt_pk_bf16_f32 v49, v50, v51
	ds_write_b64 v64, v[48:49] offset:160
	ds_read_b128 v[48:51], v197 offset:26112
	ds_read_b128 v[66:69], v197 offset:26176
	s_waitcnt lgkmcnt(0)
	v_mfma_f32_16x16x32_bf16 v[48:51], v[48:51], v[0:3], 0
	v_or_b32_e32 v62, 0x60, v196
	v_sub_u32_e32 v62, v92, v62
	v_sub_u32_e32 v63, 0, v62
	v_mfma_f32_16x16x32_bf16 v[48:51], v[66:69], v[4:7], v[48:51]
	ds_read_b128 v[66:69], v197 offset:26240
	v_max_i32_e32 v63, v62, v63
	v_cvt_f32_u32_e32 v63, v63
	v_cmp_gt_i32_e32 vcc, 0, v62
	s_waitcnt lgkmcnt(0)
	v_mfma_f32_16x16x32_bf16 v[48:51], v[66:69], v[8:11], v[48:51]
	v_cndmask_b32_e32 v62, v177, v188, vcc
	ds_read_b128 v[66:69], v197 offset:26304
	v_mul_f32_e64 v62, -v62, v63
	v_or_b32_e32 v63, 0x61, v196
	v_sub_u32_e32 v63, v92, v63
	v_sub_u32_e32 v65, 0, v63
	v_max_i32_e32 v65, v63, v65
	v_cvt_f32_u32_e32 v65, v65
	v_cmp_gt_i32_e32 vcc, 0, v63
	s_waitcnt lgkmcnt(0)
	v_mfma_f32_16x16x32_bf16 v[48:51], v[66:69], v[12:15], v[48:51]
	v_cndmask_b32_e32 v63, v177, v188, vcc
	v_mul_f32_e64 v63, -v63, v65
	v_exp_f32_e32 v62, v62
	v_exp_f32_e32 v63, v63
	s_nop 3
	v_pk_mul_f32 v[48:49], v[62:63], v[48:49]
	v_or_b32_e32 v62, 0x62, v196
	v_sub_u32_e32 v62, v92, v62
	v_sub_u32_e32 v63, 0, v62
	v_max_i32_e32 v63, v62, v63
	v_cvt_f32_u32_e32 v63, v63
	v_cmp_gt_i32_e32 vcc, 0, v62
	v_cvt_pk_bf16_f32 v48, v48, v49
	s_nop 0
	v_cndmask_b32_e32 v62, v177, v188, vcc
	v_mul_f32_e64 v62, -v62, v63
	v_or_b32_e32 v63, 0x63, v196
	v_sub_u32_e32 v63, v92, v63
	v_sub_u32_e32 v65, 0, v63
	v_max_i32_e32 v65, v63, v65
	v_cvt_f32_u32_e32 v65, v65
	v_cmp_gt_i32_e32 vcc, 0, v63
	v_exp_f32_e32 v62, v62
	s_nop 0
	v_cndmask_b32_e32 v63, v177, v188, vcc
	v_mul_f32_e64 v63, -v63, v65
	v_exp_f32_e32 v63, v63
	s_nop 0
	v_pk_mul_f32 v[50:51], v[62:63], v[50:51]
	s_nop 0
	v_cvt_pk_bf16_f32 v49, v50, v51
	ds_write_b64 v64, v[48:49] offset:192
	ds_read_b128 v[48:51], v197 offset:30464
	ds_read_b128 v[66:69], v197 offset:30528
	s_waitcnt lgkmcnt(0)
	v_mfma_f32_16x16x32_bf16 v[48:51], v[48:51], v[0:3], 0
	v_or_b32_e32 v62, 0x70, v196
	v_sub_u32_e32 v62, v92, v62
	v_sub_u32_e32 v63, 0, v62
	v_mfma_f32_16x16x32_bf16 v[48:51], v[66:69], v[4:7], v[48:51]
	ds_read_b128 v[66:69], v197 offset:30592
	v_max_i32_e32 v63, v62, v63
	v_cvt_f32_u32_e32 v63, v63
	v_cmp_gt_i32_e32 vcc, 0, v62
	s_waitcnt lgkmcnt(0)
	v_mfma_f32_16x16x32_bf16 v[48:51], v[66:69], v[8:11], v[48:51]
	v_cndmask_b32_e32 v62, v177, v188, vcc
	ds_read_b128 v[66:69], v197 offset:30656
	v_mul_f32_e64 v62, -v62, v63
	v_or_b32_e32 v63, 0x71, v196
	v_sub_u32_e32 v63, v92, v63
	v_sub_u32_e32 v65, 0, v63
	v_max_i32_e32 v65, v63, v65
	v_cvt_f32_u32_e32 v65, v65
	v_cmp_gt_i32_e32 vcc, 0, v63
	s_waitcnt lgkmcnt(0)
	v_mfma_f32_16x16x32_bf16 v[48:51], v[66:69], v[12:15], v[48:51]
	v_cndmask_b32_e32 v63, v177, v188, vcc
	v_mul_f32_e64 v63, -v63, v65
	v_exp_f32_e32 v62, v62
	v_exp_f32_e32 v63, v63
	s_nop 3
	v_pk_mul_f32 v[48:49], v[62:63], v[48:49]
	v_or_b32_e32 v62, 0x72, v196
	v_sub_u32_e32 v62, v92, v62
	v_sub_u32_e32 v63, 0, v62
	v_max_i32_e32 v63, v62, v63
	v_cvt_f32_u32_e32 v63, v63
	v_cmp_gt_i32_e32 vcc, 0, v62
	v_cvt_pk_bf16_f32 v48, v48, v49
	s_nop 0
	v_cndmask_b32_e32 v62, v177, v188, vcc
	v_mul_f32_e64 v62, -v62, v63
	v_or_b32_e32 v63, 0x73, v196
	v_sub_u32_e32 v63, v92, v63
	v_sub_u32_e32 v65, 0, v63
	v_max_i32_e32 v65, v63, v65
	v_cvt_f32_u32_e32 v65, v65
	v_cmp_gt_i32_e32 vcc, 0, v63
	v_exp_f32_e32 v62, v62
	s_nop 0
	v_cndmask_b32_e32 v63, v177, v188, vcc
	v_mul_f32_e64 v63, -v63, v65
	v_exp_f32_e32 v63, v63
	s_nop 0
	v_pk_mul_f32 v[50:51], v[62:63], v[50:51]
	s_nop 0
	v_cvt_pk_bf16_f32 v49, v50, v51
	ds_write_b64 v64, v[48:49] offset:224
	s_waitcnt lgkmcnt(0)
	s_barrier
	s_waitcnt vmcnt(0)
	ds_write_b128 v54, v[16:19]
	ds_write_b128 v56, v[20:23]
	ds_write_b128 v58, v[24:27]
	ds_write_b128 v60, v[28:31]
	v_mad_u64_u32 v[16:17], s[4:5], v53, s73, v[52:53]
	ds_write_b128 v16, v[32:35]
	v_mad_u64_u32 v[16:17], s[4:5], v55, s73, v[52:53]
	ds_write_b128 v16, v[36:39]
	v_mad_u64_u32 v[16:17], s[4:5], v57, s73, v[52:53]
	ds_write_b128 v16, v[40:43]
	v_mad_u64_u32 v[16:17], s[4:5], v59, s73, v[52:53]
	ds_write_b128 v16, v[44:47]
	v_add_u32_e32 v16, v61, v152
	ds_read_b128 v[88:91], v16
	ds_read_b128 v[84:87], v16 offset:64
	ds_read_b128 v[80:83], v16 offset:128
	ds_read_b128 v[76:79], v16 offset:192
	s_waitcnt lgkmcnt(0)
	s_barrier
	ds_read_b128 v[16:19], v197
	ds_read_b128 v[20:23], v197 offset:64
	s_waitcnt lgkmcnt(1)
	v_mfma_f32_16x16x32_bf16 v[16:19], v[16:19], v[88:91], 0
	ds_read_b128 v[24:27], v197 offset:4416
	ds_read_b128 v[28:31], v197 offset:8768
	ds_read_b128 v[32:35], v197 offset:13120
	s_waitcnt lgkmcnt(3)
	v_mfma_f32_16x16x32_bf16 v[16:19], v[20:23], v[84:87], v[16:19]
	ds_read_b128 v[20:23], v197 offset:128
	ds_read_b128 v[36:39], v197 offset:17472
	ds_read_b128 v[40:43], v197 offset:21824
	s_waitcnt lgkmcnt(2)
	v_mfma_f32_16x16x32_bf16 v[16:19], v[20:23], v[80:83], v[16:19]
	ds_read_b128 v[20:23], v197 offset:192
	ds_read_b128 v[44:47], v197 offset:26176
	ds_read_b128 v[48:51], v197 offset:30528
	s_waitcnt lgkmcnt(2)
	v_mfma_f32_16x16x32_bf16 v[16:19], v[20:23], v[76:79], v[16:19]
	ds_read_b128 v[20:23], v197 offset:4352
	s_lshl_b64 s[4:5], s[8:9], 18
	s_not_b32 s8, s33
	s_waitcnt lgkmcnt(0)
	v_mfma_f32_16x16x32_bf16 v[20:23], v[20:23], v[88:91], 0
	s_add_i32 s87, s92, s8
	s_add_u32 s89, s22, s4
	s_addc_u32 s93, s23, s5
	v_mfma_f32_16x16x32_bf16 v[20:23], v[24:27], v[84:87], v[20:23]
	ds_read_b128 v[24:27], v197 offset:4480
	s_add_i32 s96, s71, 0xffffff80
	s_sub_i32 s95, s92, s33
	s_waitcnt lgkmcnt(0)
	v_mfma_f32_16x16x32_bf16 v[20:23], v[24:27], v[80:83], v[20:23]
	ds_read_b128 v[24:27], v197 offset:4544
	s_mov_b64 s[8:9], -1
	ds_read_b128 v[52:55], v197 offset:34880
	s_waitcnt lgkmcnt(1)
	v_mfma_f32_16x16x32_bf16 v[20:23], v[24:27], v[76:79], v[20:23]
	ds_read_b128 v[24:27], v197 offset:8704
	ds_read_b128 v[56:59], v197 offset:39232
	ds_read_b128 v[60:63], v197 offset:43584
	s_waitcnt lgkmcnt(2)
	v_mfma_f32_16x16x32_bf16 v[24:27], v[24:27], v[88:91], 0
	ds_read_b128 v[64:67], v197 offset:47936
	ds_read_b128 v[68:71], v197 offset:52288
	ds_read_b128 v[72:75], v197 offset:56640
	v_mfma_f32_16x16x32_bf16 v[24:27], v[28:31], v[84:87], v[24:27]
	ds_read_b128 v[28:31], v197 offset:8832
	ds_read_b128 v[94:97], v197 offset:60992
	s_waitcnt lgkmcnt(1)
	v_mfma_f32_16x16x32_bf16 v[24:27], v[28:31], v[80:83], v[24:27]
	ds_read_b128 v[28:31], v197 offset:8896
	s_waitcnt lgkmcnt(0)
	v_mfma_f32_16x16x32_bf16 v[24:27], v[28:31], v[76:79], v[24:27]
	ds_read_b128 v[28:31], v197 offset:13056
	s_waitcnt lgkmcnt(0)
	v_mfma_f32_16x16x32_bf16 v[28:31], v[28:31], v[88:91], 0
	v_mfma_f32_16x16x32_bf16 v[28:31], v[32:35], v[84:87], v[28:31]
	ds_read_b128 v[32:35], v197 offset:13184
	s_waitcnt lgkmcnt(0)
	v_mfma_f32_16x16x32_bf16 v[28:31], v[32:35], v[80:83], v[28:31]
	ds_read_b128 v[32:35], v197 offset:13248
	s_waitcnt lgkmcnt(0)
	v_mfma_f32_16x16x32_bf16 v[28:31], v[32:35], v[76:79], v[28:31]
	ds_read_b128 v[32:35], v197 offset:17408
	s_waitcnt lgkmcnt(0)
	v_mfma_f32_16x16x32_bf16 v[32:35], v[32:35], v[88:91], 0
	v_mfma_f32_16x16x32_bf16 v[32:35], v[36:39], v[84:87], v[32:35]
	ds_read_b128 v[36:39], v197 offset:17536
	s_waitcnt lgkmcnt(0)
	v_mfma_f32_16x16x32_bf16 v[32:35], v[36:39], v[80:83], v[32:35]
	ds_read_b128 v[36:39], v197 offset:17600
	s_waitcnt lgkmcnt(0)
	v_mfma_f32_16x16x32_bf16 v[32:35], v[36:39], v[76:79], v[32:35]
	ds_read_b128 v[36:39], v197 offset:21760
	s_waitcnt lgkmcnt(0)
	v_mfma_f32_16x16x32_bf16 v[36:39], v[36:39], v[88:91], 0
	v_mfma_f32_16x16x32_bf16 v[36:39], v[40:43], v[84:87], v[36:39]
	ds_read_b128 v[40:43], v197 offset:21888
	s_waitcnt lgkmcnt(0)
	v_mfma_f32_16x16x32_bf16 v[36:39], v[40:43], v[80:83], v[36:39]
	ds_read_b128 v[40:43], v197 offset:21952
	s_waitcnt lgkmcnt(0)
	v_mfma_f32_16x16x32_bf16 v[36:39], v[40:43], v[76:79], v[36:39]
	ds_read_b128 v[40:43], v197 offset:26112
	s_waitcnt lgkmcnt(0)
	v_mfma_f32_16x16x32_bf16 v[40:43], v[40:43], v[88:91], 0
	v_mfma_f32_16x16x32_bf16 v[40:43], v[44:47], v[84:87], v[40:43]
	ds_read_b128 v[44:47], v197 offset:26240
	s_waitcnt lgkmcnt(0)
	v_mfma_f32_16x16x32_bf16 v[40:43], v[44:47], v[80:83], v[40:43]
	ds_read_b128 v[44:47], v197 offset:26304
	s_waitcnt lgkmcnt(0)
	v_mfma_f32_16x16x32_bf16 v[40:43], v[44:47], v[76:79], v[40:43]
	ds_read_b128 v[44:47], v197 offset:30464
	s_waitcnt lgkmcnt(0)
	v_mfma_f32_16x16x32_bf16 v[44:47], v[44:47], v[88:91], 0
	v_mfma_f32_16x16x32_bf16 v[44:47], v[48:51], v[84:87], v[44:47]
	ds_read_b128 v[48:51], v197 offset:30592
	s_waitcnt lgkmcnt(0)
	v_mfma_f32_16x16x32_bf16 v[44:47], v[48:51], v[80:83], v[44:47]
	ds_read_b128 v[48:51], v197 offset:30656
	s_waitcnt lgkmcnt(0)
	v_mfma_f32_16x16x32_bf16 v[44:47], v[48:51], v[76:79], v[44:47]
	ds_read_b128 v[48:51], v197 offset:34816
	s_waitcnt lgkmcnt(0)
	v_mfma_f32_16x16x32_bf16 v[48:51], v[48:51], v[88:91], 0
	v_mfma_f32_16x16x32_bf16 v[48:51], v[52:55], v[84:87], v[48:51]
	ds_read_b128 v[52:55], v197 offset:34944
	s_waitcnt lgkmcnt(0)
	v_mfma_f32_16x16x32_bf16 v[48:51], v[52:55], v[80:83], v[48:51]
	ds_read_b128 v[52:55], v197 offset:35008
	s_waitcnt lgkmcnt(0)
	v_mfma_f32_16x16x32_bf16 v[48:51], v[52:55], v[76:79], v[48:51]
	ds_read_b128 v[52:55], v197 offset:39168
	s_waitcnt lgkmcnt(0)
	v_mfma_f32_16x16x32_bf16 v[52:55], v[52:55], v[88:91], 0
	v_mfma_f32_16x16x32_bf16 v[52:55], v[56:59], v[84:87], v[52:55]
	ds_read_b128 v[56:59], v197 offset:39296
	s_waitcnt lgkmcnt(0)
	v_mfma_f32_16x16x32_bf16 v[52:55], v[56:59], v[80:83], v[52:55]
	ds_read_b128 v[56:59], v197 offset:39360
	s_waitcnt lgkmcnt(0)
	v_mfma_f32_16x16x32_bf16 v[52:55], v[56:59], v[76:79], v[52:55]
	ds_read_b128 v[56:59], v197 offset:43520
	s_waitcnt lgkmcnt(0)
	v_mfma_f32_16x16x32_bf16 v[56:59], v[56:59], v[88:91], 0
	v_mfma_f32_16x16x32_bf16 v[56:59], v[60:63], v[84:87], v[56:59]
	ds_read_b128 v[60:63], v197 offset:43648
	s_waitcnt lgkmcnt(0)
	v_mfma_f32_16x16x32_bf16 v[56:59], v[60:63], v[80:83], v[56:59]
	ds_read_b128 v[60:63], v197 offset:43712
	s_waitcnt lgkmcnt(0)
	v_mfma_f32_16x16x32_bf16 v[56:59], v[60:63], v[76:79], v[56:59]
	ds_read_b128 v[60:63], v197 offset:47872
	s_waitcnt lgkmcnt(0)
	v_mfma_f32_16x16x32_bf16 v[60:63], v[60:63], v[88:91], 0
	v_mfma_f32_16x16x32_bf16 v[60:63], v[64:67], v[84:87], v[60:63]
	ds_read_b128 v[64:67], v197 offset:48000
	s_waitcnt lgkmcnt(0)
	v_mfma_f32_16x16x32_bf16 v[60:63], v[64:67], v[80:83], v[60:63]
	ds_read_b128 v[64:67], v197 offset:48064
	s_waitcnt lgkmcnt(0)
	v_mfma_f32_16x16x32_bf16 v[60:63], v[64:67], v[76:79], v[60:63]
	ds_read_b128 v[64:67], v197 offset:52224
	s_waitcnt lgkmcnt(0)
	v_mfma_f32_16x16x32_bf16 v[64:67], v[64:67], v[88:91], 0
	v_mfma_f32_16x16x32_bf16 v[64:67], v[68:71], v[84:87], v[64:67]
	ds_read_b128 v[68:71], v197 offset:52352
	s_waitcnt lgkmcnt(0)
	v_mfma_f32_16x16x32_bf16 v[64:67], v[68:71], v[80:83], v[64:67]
	ds_read_b128 v[68:71], v197 offset:52416
	s_waitcnt lgkmcnt(0)
	v_mfma_f32_16x16x32_bf16 v[64:67], v[68:71], v[76:79], v[64:67]
	ds_read_b128 v[68:71], v197 offset:56576
	s_waitcnt lgkmcnt(0)
	v_mfma_f32_16x16x32_bf16 v[68:71], v[68:71], v[88:91], 0
	v_mfma_f32_16x16x32_bf16 v[68:71], v[72:75], v[84:87], v[68:71]
	ds_read_b128 v[72:75], v197 offset:56704
	s_waitcnt lgkmcnt(0)
	v_mfma_f32_16x16x32_bf16 v[68:71], v[72:75], v[80:83], v[68:71]
	ds_read_b128 v[72:75], v197 offset:56768
	s_waitcnt lgkmcnt(0)
	v_mfma_f32_16x16x32_bf16 v[68:71], v[72:75], v[76:79], v[68:71]
	ds_read_b128 v[72:75], v197 offset:60928
	s_waitcnt lgkmcnt(0)
	v_mfma_f32_16x16x32_bf16 v[72:75], v[72:75], v[88:91], 0
	v_mfma_f32_16x16x32_bf16 v[72:75], v[94:97], v[84:87], v[72:75]
	ds_read_b128 v[94:97], v197 offset:61056
	s_waitcnt lgkmcnt(0)
	v_mfma_f32_16x16x32_bf16 v[72:75], v[94:97], v[80:83], v[72:75]
	ds_read_b128 v[94:97], v197 offset:61120
	s_waitcnt lgkmcnt(0)
	v_mfma_f32_16x16x32_bf16 v[72:75], v[94:97], v[76:79], v[72:75]
	ds_read_b128 v[94:97], v197 offset:65280
	s_waitcnt lgkmcnt(0)
	v_mfma_f32_16x16x32_bf16 v[88:91], v[94:97], v[88:91], 0
	ds_read_b128 v[94:97], v197 offset:65344
	s_waitcnt lgkmcnt(0)
	v_mfma_f32_16x16x32_bf16 v[84:87], v[94:97], v[84:87], v[88:91]
	s_nop 4
	ds_read_b128 v[88:91], v197 offset:65408
	s_waitcnt lgkmcnt(0)
	v_mfma_f32_16x16x32_bf16 v[80:83], v[88:91], v[80:83], v[84:87]
	s_nop 2
	ds_read_b128 v[84:87], v197 offset:65472
	s_waitcnt lgkmcnt(0)
	v_mfma_f32_16x16x32_bf16 v[76:79], v[84:87], v[76:79], v[80:83]
	s_nop 2
	v_sub_u32_e32 v80, 0x80, v92
	v_cvt_f32_i32_e32 v80, v80
	v_mul_f32_e64 v81, v80, -v188
	v_cmp_gt_f32_e32 vcc, s75, v81
	s_nop 1
	v_cndmask_b32_e32 v81, 0, v212, vcc
	v_fma_f32 v80, v80, -v188, v81
	v_exp_f32_e32 v80, v80
	v_cndmask_b32_e32 v81, 0, v213, vcc
	v_ldexp_f32 v200, v80, v81
	v_add_u32_e32 v80, 1, v92
	v_cvt_f32_i32_e32 v80, v80
	v_mul_f32_e64 v81, -v177, v80
	v_cmp_gt_f32_e32 vcc, s75, v81
	s_nop 1
	v_cndmask_b32_e32 v81, 0, v212, vcc
	v_fma_f32 v80, -v177, v80, v81
	v_exp_f32_e32 v80, v80
	v_cndmask_b32_e32 v81, 0, v213, vcc
	v_ldexp_f32 v201, v80, v81
	s_branch .LBB0_73

.LBB0_77:
	v_add_u32_e32 v120, s5, v157
	v_ashrrev_i32_e32 v121, 31, v120
	v_lshlrev_b64 v[150:151], 4, v[120:121]
	s_and_b64 vcc, exec, s[64:65]
	v_add_u32_e32 v122, 0x200, v120
	v_add_u32_e32 v124, 0x400, v120
	v_add_u32_e32 v126, 0x600, v120
	v_add_u32_e32 v128, 0x800, v120
	v_add_u32_e32 v130, 0xa00, v120
	v_add_u32_e32 v132, 0xc00, v120
	v_add_u32_e32 v134, 0xe00, v120
	s_mov_b64 s[10:11], -1
	s_cbranch_vccz .LBB0_79
	v_add_u32_e32 v146, 0x200, v120
	v_ashrrev_i32_e32 v147, 31, v146
	v_add_u32_e32 v148, 0x400, v120
	v_add_u32_e32 v142, 0x600, v120
	v_lshl_add_u64 v[80:81], s[20:21], 0, v[150:151]
	v_lshl_add_u64 v[82:83], v[146:147], 4, s[20:21]
	v_ashrrev_i32_e32 v149, 31, v148
	v_ashrrev_i32_e32 v143, 31, v142
	v_add_u32_e32 v144, 0x800, v120
	v_add_u32_e32 v138, 0xa00, v120
	global_load_dwordx4 v[108:111], v[80:81], off
	global_load_dwordx4 v[104:107], v[82:83], off
	v_lshl_add_u64 v[80:81], v[148:149], 4, s[20:21]
	v_lshl_add_u64 v[82:83], v[142:143], 4, s[20:21]
	v_ashrrev_i32_e32 v145, 31, v144
	v_ashrrev_i32_e32 v139, 31, v138
	v_add_u32_e32 v140, 0xc00, v120
	v_add_u32_e32 v136, 0xe00, v120
	global_load_dwordx4 v[100:103], v[80:81], off
	global_load_dwordx4 v[96:99], v[82:83], off
	v_lshl_add_u64 v[80:81], v[144:145], 4, s[20:21]
	v_lshl_add_u64 v[82:83], v[138:139], 4, s[20:21]
	v_ashrrev_i32_e32 v141, 31, v140
	v_ashrrev_i32_e32 v137, 31, v136
	global_load_dwordx4 v[92:95], v[80:81], off
	global_load_dwordx4 v[88:91], v[82:83], off
	v_lshl_add_u64 v[80:81], v[140:141], 4, s[20:21]
	v_lshl_add_u64 v[82:83], v[136:137], 4, s[20:21]
	global_load_dwordx4 v[84:87], v[80:81], off
	s_nop 0
	global_load_dwordx4 v[80:83], v[82:83], off
	s_mov_b64 s[10:11], 0
.LBB0_79:
	s_andn2_b64 vcc, exec, s[10:11]
	s_cbranch_vccnz .LBB0_76
	s_waitcnt vmcnt(0) lgkmcnt(0)
	v_lshl_add_u64 v[80:81], s[22:23], 0, v[150:151]
	v_ashrrev_i32_e32 v123, 31, v122
	global_load_dwordx4 v[108:111], v[80:81], off
	v_lshl_add_u64 v[80:81], v[122:123], 4, s[22:23]
	v_ashrrev_i32_e32 v125, 31, v124
	global_load_dwordx4 v[104:107], v[80:81], off
	v_lshl_add_u64 v[80:81], v[124:125], 4, s[22:23]
	v_ashrrev_i32_e32 v127, 31, v126
	global_load_dwordx4 v[100:103], v[80:81], off
	v_lshl_add_u64 v[80:81], v[126:127], 4, s[22:23]
	v_ashrrev_i32_e32 v129, 31, v128
	global_load_dwordx4 v[96:99], v[80:81], off
	v_lshl_add_u64 v[80:81], v[128:129], 4, s[22:23]
	v_ashrrev_i32_e32 v131, 31, v130
	global_load_dwordx4 v[92:95], v[80:81], off
	v_lshl_add_u64 v[80:81], v[130:131], 4, s[22:23]
	v_ashrrev_i32_e32 v133, 31, v132
	global_load_dwordx4 v[88:91], v[80:81], off
	v_lshl_add_u64 v[80:81], v[132:133], 4, s[22:23]
	v_ashrrev_i32_e32 v135, 31, v134
	global_load_dwordx4 v[84:87], v[80:81], off
	v_lshl_add_u64 v[80:81], v[134:135], 4, s[22:23]
	global_load_dwordx4 v[80:83], v[80:81], off
	v_mov_b32_e32 v117, v116
	s_andn2_b64 vcc, exec, s[40:41]
	s_waitcnt vmcnt(0) lgkmcnt(0)
	v_pk_mul_f32 v[110:111], v[116:117], v[110:111]
	v_pk_mul_f32 v[108:109], v[118:119], v[108:109]
	v_pk_mul_f32 v[106:107], v[116:117], v[106:107]
	v_pk_mul_f32 v[104:105], v[116:117], v[104:105]
	v_pk_mul_f32 v[102:103], v[116:117], v[102:103]
	v_pk_mul_f32 v[100:101], v[116:117], v[100:101]
	v_pk_mul_f32 v[98:99], v[116:117], v[98:99]
	v_pk_mul_f32 v[96:97], v[116:117], v[96:97]
	v_pk_mul_f32 v[94:95], v[116:117], v[94:95]
	v_pk_mul_f32 v[92:93], v[116:117], v[92:93]
	v_pk_mul_f32 v[90:91], v[116:117], v[90:91]
	v_pk_mul_f32 v[88:89], v[116:117], v[88:89]
	v_pk_mul_f32 v[86:87], v[116:117], v[86:87]
	v_pk_mul_f32 v[84:85], v[116:117], v[84:85]
	v_pk_mul_f32 v[82:83], v[116:117], v[82:83]
	v_pk_mul_f32 v[80:81], v[116:117], v[80:81]
	s_cbranch_vccnz .LBB0_75
	v_lshlrev_b64 v[136:137], 3, v[120:121]
	v_lshlrev_b64 v[138:139], 3, v[122:123]
	v_lshlrev_b64 v[140:141], 3, v[124:125]
	v_lshlrev_b64 v[142:143], 3, v[126:127]
	v_lshlrev_b64 v[144:145], 3, v[128:129]
	v_lshlrev_b64 v[146:147], 3, v[130:131]
	v_lshlrev_b64 v[148:149], 3, v[132:133]
	v_lshlrev_b64 v[150:151], 3, v[134:135]
	s_mov_b32 s5, 0
	s_mov_b32 s94, s96
	s_mov_b32 s97, 0
	s_branch .LBB0_84

.LBB0_83:
	v_lshl_add_u64 v[158:159], s[26:27], 0, v[136:137]
	global_load_dwordx2 v[202:203], v[158:159], off
	v_lshl_add_u64 v[158:159], s[26:27], 0, v[138:139]
	global_load_dwordx2 v[204:205], v[158:159], off
	v_lshl_add_u64 v[158:159], s[26:27], 0, v[140:141]
	global_load_dwordx2 v[226:227], v[158:159], off
	v_lshl_add_u64 v[158:159], s[26:27], 0, v[142:143]
	global_load_dwordx2 v[228:229], v[158:159], off
	v_lshl_add_u64 v[158:159], s[26:27], 0, v[144:145]
	global_load_dwordx2 v[232:233], v[158:159], off
	v_lshl_add_u64 v[158:159], s[26:27], 0, v[146:147]
	v_lshl_add_u64 v[160:161], s[26:27], 0, v[148:149]
	v_lshl_add_u64 v[162:163], s[26:27], 0, v[150:151]
	global_load_dwordx2 v[234:235], v[158:159], off
	global_load_dwordx2 v[236:237], v[160:161], off
	global_load_dwordx2 v[238:239], v[162:163], off
	v_lshl_add_u64 v[158:159], s[50:51], 0, v[136:137]
	v_lshl_add_u64 v[160:161], s[50:51], 0, v[138:139]
	v_lshl_add_u64 v[162:163], s[50:51], 0, v[140:141]
	v_lshl_add_u64 v[164:165], s[50:51], 0, v[142:143]
	global_load_dwordx2 v[240:241], v[158:159], off
	global_load_dwordx2 v[242:243], v[160:161], off
	global_load_dwordx2 v[244:245], v[162:163], off
	global_load_dwordx2 v[246:247], v[164:165], off
	v_lshl_add_u64 v[158:159], s[50:51], 0, v[144:145]
	v_lshl_add_u64 v[160:161], s[50:51], 0, v[146:147]
	v_lshl_add_u64 v[162:163], s[50:51], 0, v[148:149]
	v_lshl_add_u64 v[164:165], s[50:51], 0, v[150:151]
	global_load_dwordx2 v[248:249], v[158:159], off
	global_load_dwordx2 v[224:225], v[160:161], off
	global_load_dwordx2 v[154:155], v[162:163], off
	global_load_dwordx2 v[216:217], v[164:165], off
	v_lshl_add_u64 v[158:159], s[66:67], 0, v[136:137]
	v_lshl_add_u64 v[160:161], s[66:67], 0, v[138:139]
	v_lshl_add_u64 v[162:163], s[66:67], 0, v[140:141]
	v_lshl_add_u64 v[164:165], s[66:67], 0, v[142:143]
	global_load_dwordx2 v[218:219], v[158:159], off
	global_load_dwordx2 v[220:221], v[160:161], off
	global_load_dwordx2 v[186:187], v[162:163], off
	global_load_dwordx2 v[184:185], v[164:165], off
	v_lshl_add_u64 v[158:159], s[66:67], 0, v[144:145]
	v_lshl_add_u64 v[160:161], s[66:67], 0, v[146:147]
	v_lshl_add_u64 v[162:163], s[66:67], 0, v[148:149]
	v_lshl_add_u64 v[164:165], s[66:67], 0, v[150:151]
	global_load_dwordx2 v[182:183], v[158:159], off
	global_load_dwordx2 v[180:181], v[160:161], off
	global_load_dwordx2 v[178:179], v[162:163], off
	global_load_dwordx2 v[174:175], v[164:165], off
	v_lshl_add_u64 v[158:159], s[16:17], 0, v[136:137]
	v_lshl_add_u64 v[160:161], s[16:17], 0, v[138:139]
	v_lshl_add_u64 v[162:163], s[16:17], 0, v[140:141]
	v_lshl_add_u64 v[164:165], s[16:17], 0, v[142:143]
	global_load_dwordx2 v[172:173], v[158:159], off
	global_load_dwordx2 v[170:171], v[160:161], off
	global_load_dwordx2 v[168:169], v[162:163], off
	global_load_dwordx2 v[166:167], v[164:165], off
	v_lshl_add_u64 v[158:159], s[16:17], 0, v[144:145]
	v_lshl_add_u64 v[160:161], s[16:17], 0, v[146:147]
	v_lshl_add_u64 v[214:215], s[16:17], 0, v[148:149]
	v_lshl_add_u64 v[210:211], s[16:17], 0, v[150:151]
	global_load_dwordx2 v[164:165], v[158:159], off
	global_load_dwordx2 v[162:163], v[160:161], off
	s_nop 0
	global_load_dwordx2 v[160:161], v[214:215], off
	global_load_dwordx2 v[158:159], v[210:211], off
	v_cmp_gt_f32_e32 vcc, s75, v123
	s_and_b64 s[36:37], vcc, exec
	s_cselect_b32 s2, 0xffffffc0, 0
	v_cndmask_b32_e32 v127, 0, v212, vcc
	v_add_f32_e32 v123, v123, v127
	v_exp_f32_e32 v123, v123
	v_cmp_gt_f32_e32 vcc, s75, v121
	v_ldexp_f32 v123, v123, s2
	v_cndmask_b32_e64 v156, 0, v123, s[12:13]
	v_cndmask_b32_e32 v123, 0, v212, vcc
	v_add_f32_e32 v121, v121, v123
	v_exp_f32_e32 v121, v121
	s_and_b64 s[12:13], vcc, exec
	s_cselect_b32 s2, 0xffffffc0, 0
	v_cmp_gt_f32_e32 vcc, s75, v117
	v_ldexp_f32 v121, v121, s2
	v_cndmask_b32_e64 v176, 0, v121, s[10:11]
	v_cndmask_b32_e32 v121, 0, v212, vcc
	v_add_f32_e32 v117, v117, v121
	v_exp_f32_e32 v117, v117
	s_and_b64 s[10:11], vcc, exec
	s_cselect_b32 s2, 0xffffffc0, 0
	v_cmp_gt_f32_e32 vcc, s75, v125
	v_ldexp_f32 v230, v117, s2
	s_and_b64 s[10:11], vcc, exec
	v_cndmask_b32_e32 v121, 0, v212, vcc
	v_add_f32_e32 v121, v125, v121
	v_exp_f32_e32 v121, v121
	s_cselect_b32 s2, 0xffffffc0, 0
	s_addk_i32 s97, 0x200
	s_addk_i32 s94, 0xfe00
	v_ldexp_f32 v117, v121, s2
	v_cndmask_b32_e64 v152, 0, v117, s[14:15]
	s_add_i32 s2, s5, 1
	s_cmp_lt_i32 s2, s4
	s_waitcnt vmcnt(0) lgkmcnt(0)
	v_lshlrev_b32_e32 v210, 16, v202
	v_and_b32_e32 v211, 0xffff0000, v202
	v_lshlrev_b32_e32 v202, 16, v203
	v_and_b32_e32 v203, 0xffff0000, v203
	v_pk_fma_f32 v[110:111], v[230:231], v[202:203], v[110:111] op_sel_hi:[0,1,1]
	v_lshlrev_b32_e32 v202, 16, v204
	v_and_b32_e32 v203, 0xffff0000, v204
	v_pk_fma_f32 v[104:105], v[230:231], v[202:203], v[104:105] op_sel_hi:[0,1,1]
	v_lshlrev_b32_e32 v202, 16, v226
	v_and_b32_e32 v203, 0xffff0000, v226
	v_pk_fma_f32 v[100:101], v[230:231], v[202:203], v[100:101] op_sel_hi:[0,1,1]
	v_lshlrev_b32_e32 v202, 16, v228
	v_and_b32_e32 v203, 0xffff0000, v228
	v_pk_fma_f32 v[96:97], v[230:231], v[202:203], v[96:97] op_sel_hi:[0,1,1]
	v_lshlrev_b32_e32 v202, 16, v232
	v_and_b32_e32 v203, 0xffff0000, v232
	v_pk_fma_f32 v[92:93], v[230:231], v[202:203], v[92:93] op_sel_hi:[0,1,1]
	v_lshlrev_b32_e32 v202, 16, v234
	v_and_b32_e32 v203, 0xffff0000, v234
	v_pk_fma_f32 v[88:89], v[230:231], v[202:203], v[88:89] op_sel_hi:[0,1,1]
	v_lshlrev_b32_e32 v202, 16, v236
	v_and_b32_e32 v203, 0xffff0000, v236
	v_pk_fma_f32 v[84:85], v[230:231], v[202:203], v[84:85] op_sel_hi:[0,1,1]
	v_lshlrev_b32_e32 v202, 16, v238
	v_and_b32_e32 v203, 0xffff0000, v238
	v_pk_fma_f32 v[108:109], v[230:231], v[210:211], v[108:109] op_sel_hi:[0,1,1]
	v_lshlrev_b32_e32 v204, 16, v205
	v_and_b32_e32 v205, 0xffff0000, v205
	v_pk_fma_f32 v[80:81], v[230:231], v[202:203], v[80:81] op_sel_hi:[0,1,1]
	v_lshlrev_b32_e32 v202, 16, v240
	v_and_b32_e32 v203, 0xffff0000, v240
	v_pk_fma_f32 v[106:107], v[230:231], v[204:205], v[106:107] op_sel_hi:[0,1,1]
	v_lshlrev_b32_e32 v204, 16, v227
	v_and_b32_e32 v205, 0xffff0000, v227
	v_pk_fma_f32 v[108:109], v[176:177], v[202:203], v[108:109] op_sel_hi:[0,1,1]
	v_lshlrev_b32_e32 v202, 16, v242
	v_and_b32_e32 v203, 0xffff0000, v242
	v_pk_fma_f32 v[102:103], v[230:231], v[204:205], v[102:103] op_sel_hi:[0,1,1]
	v_lshlrev_b32_e32 v204, 16, v229
	v_and_b32_e32 v205, 0xffff0000, v229
	v_pk_fma_f32 v[104:105], v[176:177], v[202:203], v[104:105] op_sel_hi:[0,1,1]
	v_lshlrev_b32_e32 v202, 16, v244
	v_and_b32_e32 v203, 0xffff0000, v244
	v_pk_fma_f32 v[98:99], v[230:231], v[204:205], v[98:99] op_sel_hi:[0,1,1]
	v_lshlrev_b32_e32 v204, 16, v233
	v_and_b32_e32 v205, 0xffff0000, v233
	v_pk_fma_f32 v[100:101], v[176:177], v[202:203], v[100:101] op_sel_hi:[0,1,1]
	v_lshlrev_b32_e32 v202, 16, v246
	v_and_b32_e32 v203, 0xffff0000, v246
	v_pk_fma_f32 v[94:95], v[230:231], v[204:205], v[94:95] op_sel_hi:[0,1,1]
	v_lshlrev_b32_e32 v204, 16, v235
	v_and_b32_e32 v205, 0xffff0000, v235
	v_pk_fma_f32 v[96:97], v[176:177], v[202:203], v[96:97] op_sel_hi:[0,1,1]
	v_lshlrev_b32_e32 v202, 16, v248
	v_and_b32_e32 v203, 0xffff0000, v248
	v_pk_fma_f32 v[90:91], v[230:231], v[204:205], v[90:91] op_sel_hi:[0,1,1]
	v_lshlrev_b32_e32 v204, 16, v237
	v_and_b32_e32 v205, 0xffff0000, v237
	v_pk_fma_f32 v[92:93], v[176:177], v[202:203], v[92:93] op_sel_hi:[0,1,1]
	v_lshlrev_b32_e32 v202, 16, v224
	v_and_b32_e32 v203, 0xffff0000, v224
	v_pk_fma_f32 v[86:87], v[230:231], v[204:205], v[86:87] op_sel_hi:[0,1,1]
	v_pk_fma_f32 v[88:89], v[176:177], v[202:203], v[88:89] op_sel_hi:[0,1,1]
	v_lshlrev_b32_e32 v202, 16, v154
	v_and_b32_e32 v203, 0xffff0000, v154
	v_lshlrev_b32_e32 v154, 16, v155
	v_and_b32_e32 v155, 0xffff0000, v155
	v_pk_fma_f32 v[86:87], v[176:177], v[154:155], v[86:87] op_sel_hi:[0,1,1]
	v_lshlrev_b32_e32 v154, 16, v216
	v_and_b32_e32 v155, 0xffff0000, v216
	v_pk_fma_f32 v[80:81], v[176:177], v[154:155], v[80:81] op_sel_hi:[0,1,1]
	v_lshlrev_b32_e32 v154, 16, v218
	v_and_b32_e32 v155, 0xffff0000, v218
	v_pk_fma_f32 v[108:109], v[156:157], v[154:155], v[108:109] op_sel_hi:[0,1,1]
	v_lshlrev_b32_e32 v154, 16, v220
	v_and_b32_e32 v155, 0xffff0000, v220
	v_pk_fma_f32 v[104:105], v[156:157], v[154:155], v[104:105] op_sel_hi:[0,1,1]
	v_lshlrev_b32_e32 v154, 16, v186
	v_and_b32_e32 v155, 0xffff0000, v186
	v_pk_fma_f32 v[100:101], v[156:157], v[154:155], v[100:101] op_sel_hi:[0,1,1]
	v_lshlrev_b32_e32 v154, 16, v184
	v_and_b32_e32 v155, 0xffff0000, v184
	v_pk_fma_f32 v[96:97], v[156:157], v[154:155], v[96:97] op_sel_hi:[0,1,1]
	v_lshlrev_b32_e32 v154, 16, v182
	v_and_b32_e32 v155, 0xffff0000, v182
	v_pk_fma_f32 v[92:93], v[156:157], v[154:155], v[92:93] op_sel_hi:[0,1,1]
	v_lshlrev_b32_e32 v154, 16, v180
	v_and_b32_e32 v155, 0xffff0000, v180
	v_pk_fma_f32 v[84:85], v[176:177], v[202:203], v[84:85] op_sel_hi:[0,1,1]
	v_pk_fma_f32 v[88:89], v[156:157], v[154:155], v[88:89] op_sel_hi:[0,1,1]
	v_lshlrev_b32_e32 v154, 16, v178
	v_and_b32_e32 v155, 0xffff0000, v178
	v_lshlrev_b32_e32 v204, 16, v239
	v_and_b32_e32 v205, 0xffff0000, v239
	v_pk_fma_f32 v[84:85], v[156:157], v[154:155], v[84:85] op_sel_hi:[0,1,1]
	v_lshlrev_b32_e32 v154, 16, v174
	v_and_b32_e32 v155, 0xffff0000, v174
	v_pk_fma_f32 v[82:83], v[230:231], v[204:205], v[82:83] op_sel_hi:[0,1,1]
	v_lshlrev_b32_e32 v204, 16, v241
	v_and_b32_e32 v205, 0xffff0000, v241
	v_pk_fma_f32 v[80:81], v[156:157], v[154:155], v[80:81] op_sel_hi:[0,1,1]
	v_lshlrev_b32_e32 v154, 16, v172
	v_and_b32_e32 v155, 0xffff0000, v172
	v_pk_fma_f32 v[110:111], v[176:177], v[204:205], v[110:111] op_sel_hi:[0,1,1]
	v_lshlrev_b32_e32 v204, 16, v243
	v_and_b32_e32 v205, 0xffff0000, v243
	v_pk_fma_f32 v[108:109], v[152:153], v[154:155], v[108:109] op_sel_hi:[0,1,1]
	v_lshlrev_b32_e32 v154, 16, v170
	v_and_b32_e32 v155, 0xffff0000, v170
	v_pk_fma_f32 v[106:107], v[176:177], v[204:205], v[106:107] op_sel_hi:[0,1,1]
	v_lshlrev_b32_e32 v204, 16, v245
	v_and_b32_e32 v205, 0xffff0000, v245
	v_pk_fma_f32 v[104:105], v[152:153], v[154:155], v[104:105] op_sel_hi:[0,1,1]
	v_lshlrev_b32_e32 v154, 16, v168
	v_and_b32_e32 v155, 0xffff0000, v168
	v_pk_fma_f32 v[102:103], v[176:177], v[204:205], v[102:103] op_sel_hi:[0,1,1]
	v_lshlrev_b32_e32 v204, 16, v247
	v_and_b32_e32 v205, 0xffff0000, v247
	v_pk_fma_f32 v[100:101], v[152:153], v[154:155], v[100:101] op_sel_hi:[0,1,1]
	v_lshlrev_b32_e32 v154, 16, v166
	v_and_b32_e32 v155, 0xffff0000, v166
	v_pk_fma_f32 v[98:99], v[176:177], v[204:205], v[98:99] op_sel_hi:[0,1,1]
	v_lshlrev_b32_e32 v204, 16, v249
	v_and_b32_e32 v205, 0xffff0000, v249
	v_lshlrev_b32_e32 v202, 16, v217
	v_and_b32_e32 v203, 0xffff0000, v217
	v_pk_fma_f32 v[96:97], v[152:153], v[154:155], v[96:97] op_sel_hi:[0,1,1]
	v_lshlrev_b32_e32 v154, 16, v164
	v_and_b32_e32 v155, 0xffff0000, v164
	v_pk_fma_f32 v[94:95], v[176:177], v[204:205], v[94:95] op_sel_hi:[0,1,1]
	v_lshlrev_b32_e32 v204, 16, v225
	v_and_b32_e32 v205, 0xffff0000, v225
	v_pk_fma_f32 v[82:83], v[176:177], v[202:203], v[82:83] op_sel_hi:[0,1,1]
	v_lshlrev_b32_e32 v202, 16, v219
	v_and_b32_e32 v203, 0xffff0000, v219
	v_pk_fma_f32 v[92:93], v[152:153], v[154:155], v[92:93] op_sel_hi:[0,1,1]
	v_lshlrev_b32_e32 v154, 16, v162
	v_and_b32_e32 v155, 0xffff0000, v162
	v_pk_fma_f32 v[90:91], v[176:177], v[204:205], v[90:91] op_sel_hi:[0,1,1]
	v_pk_fma_f32 v[110:111], v[156:157], v[202:203], v[110:111] op_sel_hi:[0,1,1]
	v_lshlrev_b32_e32 v202, 16, v221
	v_and_b32_e32 v203, 0xffff0000, v221
	v_lshlrev_b32_e32 v186, 16, v187
	v_and_b32_e32 v187, 0xffff0000, v187
	v_lshlrev_b32_e32 v184, 16, v185
	v_and_b32_e32 v185, 0xffff0000, v185
	v_lshlrev_b32_e32 v182, 16, v183
	v_and_b32_e32 v183, 0xffff0000, v183
	v_lshlrev_b32_e32 v180, 16, v181
	v_and_b32_e32 v181, 0xffff0000, v181
	v_lshlrev_b32_e32 v178, 16, v179
	v_and_b32_e32 v179, 0xffff0000, v179
	v_lshlrev_b32_e32 v174, 16, v175
	v_and_b32_e32 v175, 0xffff0000, v175
	v_pk_fma_f32 v[88:89], v[152:153], v[154:155], v[88:89] op_sel_hi:[0,1,1]
	v_lshlrev_b32_e32 v154, 16, v160
	v_and_b32_e32 v155, 0xffff0000, v160
	v_pk_fma_f32 v[106:107], v[156:157], v[202:203], v[106:107] op_sel_hi:[0,1,1]
	v_pk_fma_f32 v[102:103], v[156:157], v[186:187], v[102:103] op_sel_hi:[0,1,1]
	v_pk_fma_f32 v[98:99], v[156:157], v[184:185], v[98:99] op_sel_hi:[0,1,1]
	v_pk_fma_f32 v[94:95], v[156:157], v[182:183], v[94:95] op_sel_hi:[0,1,1]
	v_pk_fma_f32 v[90:91], v[156:157], v[180:181], v[90:91] op_sel_hi:[0,1,1]
	v_pk_fma_f32 v[86:87], v[156:157], v[178:179], v[86:87] op_sel_hi:[0,1,1]
	v_pk_fma_f32 v[82:83], v[156:157], v[174:175], v[82:83] op_sel_hi:[0,1,1]
	v_lshlrev_b32_e32 v172, 16, v173
	v_and_b32_e32 v173, 0xffff0000, v173
	v_lshlrev_b32_e32 v170, 16, v171
	v_and_b32_e32 v171, 0xffff0000, v171
	v_lshlrev_b32_e32 v168, 16, v169
	v_and_b32_e32 v169, 0xffff0000, v169
	v_lshlrev_b32_e32 v166, 16, v167
	v_and_b32_e32 v167, 0xffff0000, v167
	v_lshlrev_b32_e32 v164, 16, v165
	v_and_b32_e32 v165, 0xffff0000, v165
	v_lshlrev_b32_e32 v162, 16, v163
	v_and_b32_e32 v163, 0xffff0000, v163
	v_lshlrev_b32_e32 v160, 16, v161
	v_and_b32_e32 v161, 0xffff0000, v161
	v_pk_fma_f32 v[84:85], v[152:153], v[154:155], v[84:85] op_sel_hi:[0,1,1]
	v_lshlrev_b32_e32 v154, 16, v158
	v_and_b32_e32 v155, 0xffff0000, v158
	v_lshlrev_b32_e32 v158, 16, v159
	v_and_b32_e32 v159, 0xffff0000, v159
	v_pk_fma_f32 v[110:111], v[152:153], v[172:173], v[110:111] op_sel_hi:[0,1,1]
	v_pk_fma_f32 v[106:107], v[152:153], v[170:171], v[106:107] op_sel_hi:[0,1,1]
	v_pk_fma_f32 v[102:103], v[152:153], v[168:169], v[102:103] op_sel_hi:[0,1,1]
	v_pk_fma_f32 v[98:99], v[152:153], v[166:167], v[98:99] op_sel_hi:[0,1,1]
	v_pk_fma_f32 v[94:95], v[152:153], v[164:165], v[94:95] op_sel_hi:[0,1,1]
	v_pk_fma_f32 v[90:91], v[152:153], v[162:163], v[90:91] op_sel_hi:[0,1,1]
	v_pk_fma_f32 v[86:87], v[152:153], v[160:161], v[86:87] op_sel_hi:[0,1,1]
	v_pk_fma_f32 v[82:83], v[152:153], v[158:159], v[82:83] op_sel_hi:[0,1,1]
	v_pk_fma_f32 v[80:81], v[152:153], v[154:155], v[80:81] op_sel_hi:[0,1,1]
	s_cbranch_scc0 .LBB0_75

.LBB0_99:
	v_mov_b32_e32 v0, v17
	v_mov_b32_e32 v1, v18
	v_mov_b32_e32 v2, v16
	v_mov_b32_e32 v3, v19
	v_pk_add_f32 v[0:1], v[0:1], v[2:3]
	v_mov_b32_e32 v2, v21
	v_mov_b32_e32 v3, v22
	v_mov_b32_e32 v4, v20
	v_mov_b32_e32 v5, v23
	v_pk_add_f32 v[2:3], v[2:3], v[4:5]
	v_add_f32_e32 v0, v0, v1
	v_pk_add_f32 v[2:3], v[2:3], v[2:3] op_sel:[0,1] op_sel_hi:[1,0]
	v_add_f32_e32 v0, 0, v0
	v_add_f32_e32 v4, v24, v25
	v_add_f32_e32 v6, v26, v27
	v_mov_b32_e32 v1, v28
	v_mov_b32_e32 v3, v29
	v_mov_b32_e32 v5, v30
	v_mov_b32_e32 v7, v31
	v_pk_add_f32 v[0:1], v[0:1], v[2:3]
	v_pk_add_f32 v[2:3], v[4:5], v[6:7]
	v_mov_b32_e32 v4, v32
	v_pk_add_f32 v[0:1], v[0:1], v[2:3]
	v_mov_b32_e32 v2, v33
	v_mov_b32_e32 v3, v34
	v_mov_b32_e32 v5, v35
	v_pk_add_f32 v[2:3], v[2:3], v[4:5]
	v_pk_add_f32 v[0:1], v[0:1], v[0:1] op_sel:[0,1] op_sel_hi:[1,0]
	v_pk_add_f32 v[2:3], v[2:3], v[2:3] op_sel:[0,1] op_sel_hi:[1,0]
	v_add_f32_e32 v4, v36, v37
	v_add_f32_e32 v6, v38, v39
	v_mov_b32_e32 v1, v40
	v_mov_b32_e32 v3, v41
	v_mov_b32_e32 v5, v42
	v_mov_b32_e32 v7, v43
	v_pk_add_f32 v[0:1], v[0:1], v[2:3]
	v_pk_add_f32 v[2:3], v[4:5], v[6:7]
	v_mov_b32_e32 v4, v44
	v_pk_add_f32 v[0:1], v[0:1], v[2:3]
	v_mov_b32_e32 v2, v45
	v_mov_b32_e32 v3, v46
	v_mov_b32_e32 v5, v47
	v_pk_add_f32 v[2:3], v[2:3], v[4:5]
	v_pk_add_f32 v[0:1], v[0:1], v[0:1] op_sel:[0,1] op_sel_hi:[1,0]
	v_pk_add_f32 v[2:3], v[2:3], v[2:3] op_sel:[0,1] op_sel_hi:[1,0]
	v_add_f32_e32 v4, v48, v49
	v_add_f32_e32 v6, v50, v51
	v_mov_b32_e32 v1, v52
	v_mov_b32_e32 v3, v53
	v_mov_b32_e32 v5, v54
	v_mov_b32_e32 v7, v55
	v_pk_add_f32 v[0:1], v[0:1], v[2:3]
	v_pk_add_f32 v[2:3], v[4:5], v[6:7]
	v_mov_b32_e32 v4, v56
	v_pk_add_f32 v[0:1], v[0:1], v[2:3]
	v_mov_b32_e32 v2, v57
	v_mov_b32_e32 v3, v58
	v_mov_b32_e32 v5, v59
	v_pk_add_f32 v[2:3], v[2:3], v[4:5]
	v_pk_add_f32 v[0:1], v[0:1], v[0:1] op_sel:[0,1] op_sel_hi:[1,0]
	v_pk_add_f32 v[2:3], v[2:3], v[2:3] op_sel:[0,1] op_sel_hi:[1,0]
	v_add_f32_e32 v4, v60, v61
	v_add_f32_e32 v6, v62, v63
	v_mov_b32_e32 v1, v64
	v_mov_b32_e32 v3, v65
	v_mov_b32_e32 v5, v66
	v_mov_b32_e32 v7, v67
	v_pk_add_f32 v[0:1], v[0:1], v[2:3]
	v_pk_add_f32 v[2:3], v[4:5], v[6:7]
	v_mov_b32_e32 v4, v68
	v_pk_add_f32 v[0:1], v[0:1], v[2:3]
	v_mov_b32_e32 v2, v69
	v_mov_b32_e32 v3, v70
	v_mov_b32_e32 v5, v71
	v_pk_add_f32 v[2:3], v[2:3], v[4:5]
	v_pk_add_f32 v[0:1], v[0:1], v[0:1] op_sel:[0,1] op_sel_hi:[1,0]
	v_pk_add_f32 v[2:3], v[2:3], v[2:3] op_sel:[0,1] op_sel_hi:[1,0]
	v_add_f32_e32 v4, v72, v73
	v_add_f32_e32 v6, v74, v75
	v_mov_b32_e32 v1, v76
	v_mov_b32_e32 v3, v77
	v_mov_b32_e32 v5, v78
	v_mov_b32_e32 v7, v79
	v_pk_add_f32 v[0:1], v[0:1], v[2:3]
	v_pk_add_f32 v[2:3], v[4:5], v[6:7]
	v_readlane_b32 s4, v255, 13
	v_pk_add_f32 v[0:1], v[0:1], v[2:3]
	v_and_b32_e32 v2, 64, v209
	v_add_f32_e32 v0, v0, v1
	v_xor_b32_e32 v1, 16, v209
	v_add_u32_e32 v2, 64, v2
	v_cmp_lt_i32_e32 vcc, v1, v2
	v_readlane_b32 s5, v255, 14
	s_lshl_b32 s2, s88, 1
	v_cndmask_b32_e32 v1, v209, v1, vcc
	v_lshlrev_b32_e32 v84, 2, v1
	ds_bpermute_b32 v1, v84, v0
	v_lshlrev_b32_e32 v152, 1, v196
	s_mov_b32 s67, s63
	s_mov_b32 s71, s43
	s_movk_i32 s74, 0x7f
	s_waitcnt lgkmcnt(0)
	v_add_f32_e32 v0, v0, v1
	v_xor_b32_e32 v1, 32, v209
	v_cmp_lt_i32_e32 vcc, v1, v2
	s_mov_b64 s[82:83], 0x10000
	s_nop 0
	v_cndmask_b32_e32 v1, v209, v1, vcc
	v_lshlrev_b32_e32 v85, 2, v1
	ds_bpermute_b32 v1, v85, v0
	s_waitcnt lgkmcnt(0)
	v_add_f32_e32 v86, v0, v1
	v_fmamk_f32 v83, v86, 0xbb800000, v17
	v_fmamk_f32 v82, v86, 0xbb800000, v16
	v_fmamk_f32 v19, v86, 0xbb800000, v19
	v_fmac_f32_e32 v18, 0xbb800000, v86
	v_pk_mul_f32 v[0:1], v[18:19], v[18:19]
	v_pk_mul_f32 v[2:3], v[82:83], v[82:83]
	v_fmamk_f32 v81, v86, 0xbb800000, v21
	v_pk_mov_b32 v[4:5], v[2:3], v[0:1] op_sel:[1,0]
	v_mov_b32_e32 v3, v1
	v_pk_add_f32 v[0:1], v[4:5], v[2:3]
	v_fmamk_f32 v80, v86, 0xbb800000, v20
	v_fmamk_f32 v23, v86, 0xbb800000, v23
	v_fmac_f32_e32 v22, 0xbb800000, v86
	v_pk_add_f32 v[0:1], v[0:1], v[0:1] op_sel_hi:[0,1]
	v_pk_mul_f32 v[2:3], v[22:23], v[22:23]
	v_pk_mul_f32 v[4:5], v[80:81], v[80:81]
	v_fmamk_f32 v24, v86, 0xbb800000, v24
	v_pk_mov_b32 v[6:7], v[4:5], v[2:3] op_sel:[1,0]
	v_mov_b32_e32 v5, v3
	v_fmamk_f32 v25, v86, 0xbb800000, v25
	v_fmac_f32_e32 v26, 0xbb800000, v86
	v_mul_f32_e32 v0, v24, v24
	v_pk_add_f32 v[2:3], v[6:7], v[4:5]
	v_fmamk_f32 v27, v86, 0xbb800000, v27
	v_pk_fma_f32 v[4:5], v[24:25], v[24:25], v[0:1] op_sel_hi:[1,1,0]
	v_mul_f32_e32 v0, v26, v26
	v_pk_add_f32 v[2:3], v[2:3], v[2:3] op_sel_hi:[0,1]
	v_pk_fma_f32 v[6:7], v[26:27], v[26:27], v[0:1] op_sel_hi:[1,1,0]
	v_fmamk_f32 v11, v86, 0xbb800000, v31
	v_fmamk_f32 v10, v86, 0xbb800000, v30
	v_fmamk_f32 v29, v86, 0xbb800000, v29
	v_fmac_f32_e32 v28, 0xbb800000, v86
	v_mul_f32_e32 v4, v28, v28
	v_mul_f32_e32 v6, v29, v29
	v_mul_f32_e32 v0, v10, v10
	v_mul_f32_e32 v2, v11, v11
	v_pk_add_f32 v[4:5], v[4:5], v[6:7]
	v_pk_add_f32 v[0:1], v[0:1], v[2:3]
	v_fmamk_f32 v21, v86, 0xbb800000, v33
	v_pk_add_f32 v[0:1], v[4:5], v[0:1]
	v_fmamk_f32 v20, v86, 0xbb800000, v32
	v_fmamk_f32 v35, v86, 0xbb800000, v35
	v_fmac_f32_e32 v34, 0xbb800000, v86
	v_pk_add_f32 v[0:1], v[0:1], v[0:1] op_sel_hi:[0,1]
	v_pk_mul_f32 v[2:3], v[34:35], v[34:35]
	v_pk_mul_f32 v[4:5], v[20:21], v[20:21]
	v_fmamk_f32 v16, v86, 0xbb800000, v36
	v_pk_mov_b32 v[6:7], v[4:5], v[2:3] op_sel:[1,0]
	v_mov_b32_e32 v5, v3
	v_fmamk_f32 v17, v86, 0xbb800000, v37
	v_fmac_f32_e32 v38, 0xbb800000, v86
	v_mul_f32_e32 v0, v16, v16
	v_pk_add_f32 v[2:3], v[6:7], v[4:5]
	v_fmamk_f32 v39, v86, 0xbb800000, v39
	v_pk_fma_f32 v[6:7], v[16:17], v[16:17], v[0:1] op_sel_hi:[1,1,0]
	v_mul_f32_e32 v0, v38, v38
	v_pk_add_f32 v[2:3], v[2:3], v[2:3] op_sel_hi:[0,1]
	v_pk_fma_f32 v[8:9], v[38:39], v[38:39], v[0:1] op_sel_hi:[1,1,0]
	v_fmamk_f32 v5, v86, 0xbb800000, v43
	v_fmamk_f32 v4, v86, 0xbb800000, v42
	v_fmamk_f32 v41, v86, 0xbb800000, v41
	v_fmac_f32_e32 v40, 0xbb800000, v86
	v_mul_f32_e32 v6, v40, v40
	v_mul_f32_e32 v8, v41, v41
	v_mul_f32_e32 v2, v4, v4
	v_mul_f32_e32 v0, v5, v5
	v_pk_add_f32 v[6:7], v[6:7], v[8:9]
	v_pk_add_f32 v[0:1], v[2:3], v[0:1]
	v_fmamk_f32 v15, v86, 0xbb800000, v45
	v_pk_add_f32 v[0:1], v[6:7], v[0:1]
	v_fmamk_f32 v14, v86, 0xbb800000, v44
	v_fmamk_f32 v47, v86, 0xbb800000, v47
	v_fmac_f32_e32 v46, 0xbb800000, v86
	v_pk_add_f32 v[0:1], v[0:1], v[0:1] op_sel_hi:[0,1]
	v_pk_mul_f32 v[2:3], v[46:47], v[46:47]
	v_pk_mul_f32 v[6:7], v[14:15], v[14:15]
	v_fmamk_f32 v12, v86, 0xbb800000, v48
	v_pk_mov_b32 v[8:9], v[6:7], v[2:3] op_sel:[1,0]
	v_mov_b32_e32 v7, v3
	v_fmamk_f32 v13, v86, 0xbb800000, v49
	v_fmac_f32_e32 v50, 0xbb800000, v86
	v_mul_f32_e32 v0, v12, v12
	v_pk_add_f32 v[2:3], v[8:9], v[6:7]
	v_fmamk_f32 v51, v86, 0xbb800000, v51
	v_pk_fma_f32 v[8:9], v[12:13], v[12:13], v[0:1] op_sel_hi:[1,1,0]
	v_mul_f32_e32 v0, v50, v50
	v_pk_add_f32 v[6:7], v[2:3], v[2:3] op_sel_hi:[0,1]
	v_pk_fma_f32 v[30:31], v[50:51], v[50:51], v[0:1] op_sel_hi:[1,1,0]
	v_fmamk_f32 v3, v86, 0xbb800000, v55
	v_fmamk_f32 v2, v86, 0xbb800000, v54
	v_fmamk_f32 v53, v86, 0xbb800000, v53
	v_fmac_f32_e32 v52, 0xbb800000, v86
	v_mul_f32_e32 v8, v52, v52
	v_mul_f32_e32 v30, v53, v53
	v_mul_f32_e32 v6, v2, v2
	v_mul_f32_e32 v0, v3, v3
	v_pk_add_f32 v[8:9], v[8:9], v[30:31]
	v_pk_add_f32 v[0:1], v[6:7], v[0:1]
	v_fmamk_f32 v59, v86, 0xbb800000, v59
	v_pk_add_f32 v[0:1], v[8:9], v[0:1]
	v_fmamk_f32 v9, v86, 0xbb800000, v57
	v_fmamk_f32 v8, v86, 0xbb800000, v56
	v_fmac_f32_e32 v58, 0xbb800000, v86
	v_pk_add_f32 v[30:31], v[0:1], v[0:1] op_sel_hi:[0,1]
	v_pk_mul_f32 v[0:1], v[58:59], v[58:59]
	v_pk_mul_f32 v[6:7], v[8:9], v[8:9]
	v_lshlrev_b64 v[44:45], 11, v[112:113]
	v_pk_mov_b32 v[32:33], v[6:7], v[0:1] op_sel:[1,0]
	v_mov_b32_e32 v7, v1
	v_pk_add_f32 v[0:1], v[32:33], v[6:7]
	v_fmamk_f32 v6, v86, 0xbb800000, v60
	v_lshl_add_u64 v[44:45], s[4:5], 0, v[44:45]
	v_pk_add_f32 v[32:33], v[0:1], v[0:1] op_sel_hi:[0,1]
	v_fmamk_f32 v7, v86, 0xbb800000, v61
	v_fmac_f32_e32 v62, 0xbb800000, v86
	v_mul_f32_e32 v0, v6, v6
	v_lshl_add_u64 v[44:45], v[44:45], 0, s[2:3]
	v_fmamk_f32 v63, v86, 0xbb800000, v63
	v_pk_fma_f32 v[36:37], v[6:7], v[6:7], v[0:1] op_sel_hi:[1,1,0]
	v_mul_f32_e32 v0, v62, v62
	v_lshl_add_u64 v[44:45], v[44:45], 0, v[152:153]
	v_pk_fma_f32 v[42:43], v[62:63], v[62:63], v[0:1] op_sel_hi:[1,1,0]
	v_fmamk_f32 v1, v86, 0xbb800000, v67
	v_fmamk_f32 v0, v86, 0xbb800000, v66
	v_fmamk_f32 v65, v86, 0xbb800000, v65
	global_load_dwordx2 v[56:57], v[44:45], off
	global_load_dwordx2 v[60:61], v[44:45], off offset:32
	v_fmac_f32_e32 v64, 0xbb800000, v86
	v_mul_f32_e32 v36, v64, v64
	v_mul_f32_e32 v42, v65, v65
	v_mul_f32_e32 v32, v0, v0
	v_mul_f32_e32 v30, v1, v1
	v_pk_add_f32 v[36:37], v[36:37], v[42:43]
	v_pk_add_f32 v[30:31], v[32:33], v[30:31]
	v_fmamk_f32 v71, v86, 0xbb800000, v71
	v_pk_add_f32 v[30:31], v[36:37], v[30:31]
	v_fmamk_f32 v37, v86, 0xbb800000, v69
	v_fmamk_f32 v36, v86, 0xbb800000, v68
	v_fmac_f32_e32 v70, 0xbb800000, v86
	v_pk_add_f32 v[42:43], v[30:31], v[30:31] op_sel_hi:[0,1]
	v_pk_mul_f32 v[30:31], v[70:71], v[70:71]
	v_pk_mul_f32 v[32:33], v[36:37], v[36:37]
	v_fmac_f32_e32 v74, 0xbb800000, v86
	v_pk_mov_b32 v[48:49], v[32:33], v[30:31] op_sel:[1,0]
	v_mov_b32_e32 v33, v31
	v_pk_add_f32 v[30:31], v[48:49], v[32:33]
	v_fmamk_f32 v32, v86, 0xbb800000, v72
	v_pk_add_f32 v[48:49], v[30:31], v[30:31] op_sel_hi:[0,1]
	v_fmamk_f32 v33, v86, 0xbb800000, v73
	v_mul_f32_e32 v30, v32, v32
	v_fmamk_f32 v75, v86, 0xbb800000, v75
	v_pk_fma_f32 v[54:55], v[32:33], v[32:33], v[30:31] op_sel_hi:[1,1,0]
	v_mul_f32_e32 v30, v74, v74
	v_pk_fma_f32 v[66:67], v[74:75], v[74:75], v[30:31] op_sel_hi:[1,1,0]
	v_fmamk_f32 v31, v86, 0xbb800000, v79
	v_fmamk_f32 v30, v86, 0xbb800000, v78
	v_fmamk_f32 v77, v86, 0xbb800000, v77
	v_fmac_f32_e32 v76, 0xbb800000, v86
	global_load_dwordx2 v[68:69], v[44:45], off offset:64
	v_mul_f32_e32 v54, v76, v76
	v_mul_f32_e32 v66, v77, v77
	v_mul_f32_e32 v48, v30, v30
	v_mul_f32_e32 v42, v31, v31
	v_pk_add_f32 v[54:55], v[54:55], v[66:67]
	v_pk_add_f32 v[42:43], v[48:49], v[42:43]
	global_load_dwordx2 v[66:67], v[44:45], off offset:96
	v_pk_add_f32 v[42:43], v[54:55], v[42:43]
	global_load_dwordx2 v[72:73], v[44:45], off offset:128
	v_add_f32_e32 v42, v42, v43
	ds_bpermute_b32 v43, v84, v42
	s_mov_b32 s2, 0x7f00000
	s_waitcnt lgkmcnt(0)
	v_add_f32_e32 v42, v42, v43
	ds_bpermute_b32 v43, v85, v42
	s_waitcnt lgkmcnt(0)
	v_add_f32_e32 v42, v42, v43
	v_mov_b32_e32 v43, 0x3727c5ac
	v_fmamk_f32 v42, v42, 0x3b800000, v43
	v_mul_f32_e32 v43, 0x4b800000, v42
	v_cmp_gt_f32_e32 vcc, s68, v42
	s_waitcnt vmcnt(0)
	v_lshlrev_b32_e32 v100, 16, v56
	v_cndmask_b32_e32 v42, v42, v43, vcc
	v_rsq_f32_e32 v98, v42
	global_load_dwordx2 v[78:79], v[44:45], off offset:160
	global_load_dwordx2 v[84:85], v[44:45], off offset:192
	global_load_dwordx2 v[86:87], v[44:45], off offset:224
	global_load_dwordx2 v[88:89], v[44:45], off offset:256
	global_load_dwordx2 v[90:91], v[44:45], off offset:288
	global_load_dwordx2 v[92:93], v[44:45], off offset:320
	global_load_dwordx2 v[94:95], v[44:45], off offset:352
	global_load_dwordx2 v[96:97], v[44:45], off offset:384
	global_load_dwordx2 v[54:55], v[44:45], off offset:416
	global_load_dwordx2 v[48:49], v[44:45], off offset:448
	global_load_dwordx2 v[42:43], v[44:45], off offset:480
	v_or_b32_e32 v45, s88, v196
	v_and_b32_e32 v101, 0xffff0000, v56
	v_mul_f32_e32 v99, 0x45800000, v98
	v_cndmask_b32_e32 v44, v98, v99, vcc
	v_pk_mul_f32 v[82:83], v[82:83], v[44:45] op_sel_hi:[1,0]
	v_pk_mul_f32 v[18:19], v[18:19], v[44:45] op_sel_hi:[1,0]
	v_lshlrev_b32_e32 v56, 16, v57
	v_and_b32_e32 v57, 0xffff0000, v57
	v_lshlrev_b64 v[98:99], 12, v[112:113]
	v_pk_mul_f32 v[18:19], v[18:19], v[56:57]
	v_pk_mul_f32 v[56:57], v[82:83], v[100:101]
	v_lshlrev_b32_e32 v152, 1, v45
	v_cvt_pk_bf16_f32 v56, v56, v57
	v_cvt_pk_bf16_f32 v57, v18, v19
	v_lshl_add_u64 v[18:19], s[56:57], 0, v[98:99]
	v_lshl_add_u64 v[18:19], v[18:19], 0, v[152:153]
	global_store_dwordx2 v[18:19], v[56:57], off
	v_pk_mul_f32 v[18:19], v[80:81], v[44:45] op_sel_hi:[1,0]
	v_lshlrev_b32_e32 v56, 16, v60
	v_and_b32_e32 v57, 0xffff0000, v60
	v_pk_mul_f32 v[18:19], v[18:19], v[56:57]
	v_pk_mul_f32 v[22:23], v[22:23], v[44:45] op_sel_hi:[1,0]
	v_cvt_pk_bf16_f32 v56, v18, v19
	v_lshl_add_u64 v[18:19], s[18:19], 0, v[98:99]
	v_lshlrev_b32_e32 v60, 16, v61
	v_and_b32_e32 v61, 0xffff0000, v61
	v_lshl_add_u64 v[18:19], v[18:19], 0, v[152:153]
	v_pk_mul_f32 v[22:23], v[22:23], v[60:61]
	v_add_co_u32_e32 v18, vcc, s2, v18
	v_cvt_pk_bf16_f32 v57, v22, v23
	s_nop 0
	v_addc_co_u32_e32 v19, vcc, 0, v19, vcc
	global_store_dwordx2 v[18:19], v[56:57], off offset:32
	v_pk_mul_f32 v[22:23], v[24:25], v[44:45] op_sel_hi:[1,0]
	v_pk_mul_f32 v[24:25], v[26:27], v[44:45] op_sel_hi:[1,0]
	v_lshlrev_b32_e32 v26, 16, v68
	v_and_b32_e32 v27, 0xffff0000, v68
	v_lshlrev_b32_e32 v56, 16, v69
	v_and_b32_e32 v57, 0xffff0000, v69
	v_pk_mul_f32 v[24:25], v[24:25], v[56:57]
	v_pk_mul_f32 v[22:23], v[22:23], v[26:27]
	v_pk_mul_f32 v[10:11], v[10:11], v[44:45] op_sel_hi:[1,0]
	v_cvt_pk_bf16_f32 v22, v22, v23
	v_cvt_pk_bf16_f32 v23, v24, v25
	global_store_dwordx2 v[18:19], v[22:23], off offset:64
	v_pk_mul_f32 v[22:23], v[28:29], v[44:45] op_sel_hi:[1,0]
	v_lshlrev_b32_e32 v24, 16, v66
	v_and_b32_e32 v25, 0xffff0000, v66
	v_lshlrev_b32_e32 v26, 16, v67
	v_and_b32_e32 v27, 0xffff0000, v67
	v_pk_mul_f32 v[10:11], v[10:11], v[26:27]
	v_pk_mul_f32 v[22:23], v[22:23], v[24:25]
	v_lshlrev_b32_e32 v24, 16, v73
	v_cvt_pk_bf16_f32 v22, v22, v23
	v_cvt_pk_bf16_f32 v23, v10, v11
	global_store_dwordx2 v[18:19], v[22:23], off offset:96
	v_pk_mul_f32 v[10:11], v[20:21], v[44:45] op_sel_hi:[1,0]
	v_pk_mul_f32 v[20:21], v[34:35], v[44:45] op_sel_hi:[1,0]
	v_lshlrev_b32_e32 v22, 16, v72
	v_and_b32_e32 v23, 0xffff0000, v72
	v_and_b32_e32 v25, 0xffff0000, v73
	v_pk_mul_f32 v[20:21], v[20:21], v[24:25]
	v_pk_mul_f32 v[10:11], v[10:11], v[22:23]
	v_pk_mul_f32 v[4:5], v[4:5], v[44:45] op_sel_hi:[1,0]
	v_cvt_pk_bf16_f32 v10, v10, v11
	v_cvt_pk_bf16_f32 v11, v20, v21
	global_store_dwordx2 v[18:19], v[10:11], off offset:128
	v_pk_mul_f32 v[10:11], v[16:17], v[44:45] op_sel_hi:[1,0]
	v_pk_mul_f32 v[16:17], v[38:39], v[44:45] op_sel_hi:[1,0]
	s_waitcnt vmcnt(0) lgkmcnt(0)
	v_lshlrev_b32_e32 v20, 16, v78
	v_and_b32_e32 v21, 0xffff0000, v78
	v_lshlrev_b32_e32 v22, 16, v79
	v_and_b32_e32 v23, 0xffff0000, v79
	v_pk_mul_f32 v[16:17], v[16:17], v[22:23]
	v_pk_mul_f32 v[10:11], v[10:11], v[20:21]
	v_lshlrev_b32_e32 v20, 16, v85
	v_cvt_pk_bf16_f32 v10, v10, v11
	v_cvt_pk_bf16_f32 v11, v16, v17
	global_store_dwordx2 v[18:19], v[10:11], off offset:160
	v_pk_mul_f32 v[10:11], v[40:41], v[44:45] op_sel_hi:[1,0]
	v_lshlrev_b32_e32 v16, 16, v84
	v_and_b32_e32 v17, 0xffff0000, v84
	v_and_b32_e32 v21, 0xffff0000, v85
	v_pk_mul_f32 v[4:5], v[4:5], v[20:21]
	v_pk_mul_f32 v[10:11], v[10:11], v[16:17]
	v_lshlrev_b32_e32 v16, 16, v87
	v_cvt_pk_bf16_f32 v10, v10, v11
	v_cvt_pk_bf16_f32 v11, v4, v5
	global_store_dwordx2 v[18:19], v[10:11], off offset:192
	v_pk_mul_f32 v[4:5], v[14:15], v[44:45] op_sel_hi:[1,0]
	v_pk_mul_f32 v[10:11], v[46:47], v[44:45] op_sel_hi:[1,0]
	v_lshlrev_b32_e32 v14, 16, v86
	v_and_b32_e32 v15, 0xffff0000, v86
	v_and_b32_e32 v17, 0xffff0000, v87
	v_pk_mul_f32 v[10:11], v[10:11], v[16:17]
	v_pk_mul_f32 v[4:5], v[4:5], v[14:15]
	v_lshlrev_b32_e32 v14, 16, v89
	v_cvt_pk_bf16_f32 v4, v4, v5
	v_cvt_pk_bf16_f32 v5, v10, v11
	global_store_dwordx2 v[18:19], v[4:5], off offset:224
	v_pk_mul_f32 v[4:5], v[12:13], v[44:45] op_sel_hi:[1,0]
	v_pk_mul_f32 v[10:11], v[50:51], v[44:45] op_sel_hi:[1,0]
	v_lshlrev_b32_e32 v12, 16, v88
	v_and_b32_e32 v13, 0xffff0000, v88
	v_and_b32_e32 v15, 0xffff0000, v89
	v_pk_mul_f32 v[10:11], v[10:11], v[14:15]
	v_pk_mul_f32 v[4:5], v[4:5], v[12:13]
	v_pk_mul_f32 v[2:3], v[2:3], v[44:45] op_sel_hi:[1,0]
	v_cvt_pk_bf16_f32 v4, v4, v5
	v_cvt_pk_bf16_f32 v5, v10, v11
	global_store_dwordx2 v[18:19], v[4:5], off offset:256
	v_pk_mul_f32 v[4:5], v[52:53], v[44:45] op_sel_hi:[1,0]
	v_lshlrev_b32_e32 v10, 16, v90
	v_and_b32_e32 v11, 0xffff0000, v90
	v_lshlrev_b32_e32 v12, 16, v91
	v_and_b32_e32 v13, 0xffff0000, v91
	v_pk_mul_f32 v[2:3], v[2:3], v[12:13]
	v_pk_mul_f32 v[4:5], v[4:5], v[10:11]
	v_lshlrev_b32_e32 v10, 16, v93
	v_cvt_pk_bf16_f32 v4, v4, v5
	v_cvt_pk_bf16_f32 v5, v2, v3
	global_store_dwordx2 v[18:19], v[4:5], off offset:288
	v_pk_mul_f32 v[2:3], v[8:9], v[44:45] op_sel_hi:[1,0]
	v_pk_mul_f32 v[4:5], v[58:59], v[44:45] op_sel_hi:[1,0]
	v_lshlrev_b32_e32 v8, 16, v92
	v_and_b32_e32 v9, 0xffff0000, v92
	v_and_b32_e32 v11, 0xffff0000, v93
	v_pk_mul_f32 v[4:5], v[4:5], v[10:11]
	v_pk_mul_f32 v[2:3], v[2:3], v[8:9]
	v_lshlrev_b32_e32 v8, 16, v95
	v_cvt_pk_bf16_f32 v2, v2, v3
	v_cvt_pk_bf16_f32 v3, v4, v5
	global_store_dwordx2 v[18:19], v[2:3], off offset:320
	v_pk_mul_f32 v[2:3], v[6:7], v[44:45] op_sel_hi:[1,0]
	v_pk_mul_f32 v[4:5], v[62:63], v[44:45] op_sel_hi:[1,0]
	v_lshlrev_b32_e32 v6, 16, v94
	v_and_b32_e32 v7, 0xffff0000, v94
	v_and_b32_e32 v9, 0xffff0000, v95
	v_pk_mul_f32 v[4:5], v[4:5], v[8:9]
	v_pk_mul_f32 v[2:3], v[2:3], v[6:7]
	v_pk_mul_f32 v[0:1], v[0:1], v[44:45] op_sel_hi:[1,0]
	v_cvt_pk_bf16_f32 v2, v2, v3
	v_cvt_pk_bf16_f32 v3, v4, v5
	global_store_dwordx2 v[18:19], v[2:3], off offset:352
	v_pk_mul_f32 v[2:3], v[64:65], v[44:45] op_sel_hi:[1,0]
	v_lshlrev_b32_e32 v4, 16, v96
	v_and_b32_e32 v5, 0xffff0000, v96
	v_lshlrev_b32_e32 v6, 16, v97
	v_and_b32_e32 v7, 0xffff0000, v97
	v_pk_mul_f32 v[0:1], v[0:1], v[6:7]
	v_pk_mul_f32 v[2:3], v[2:3], v[4:5]
	v_lshlrev_b32_e32 v4, 16, v54
	v_cvt_pk_bf16_f32 v2, v2, v3
	v_cvt_pk_bf16_f32 v3, v0, v1
	global_store_dwordx2 v[18:19], v[2:3], off offset:384
	v_pk_mul_f32 v[0:1], v[36:37], v[44:45] op_sel_hi:[1,0]
	v_pk_mul_f32 v[2:3], v[70:71], v[44:45] op_sel_hi:[1,0]
	v_and_b32_e32 v5, 0xffff0000, v54
	v_lshlrev_b32_e32 v6, 16, v55
	v_and_b32_e32 v7, 0xffff0000, v55
	v_pk_mul_f32 v[2:3], v[2:3], v[6:7]
	v_pk_mul_f32 v[0:1], v[0:1], v[4:5]
	v_lshlrev_b32_e32 v4, 16, v48
	v_cvt_pk_bf16_f32 v0, v0, v1
	v_cvt_pk_bf16_f32 v1, v2, v3
	global_store_dwordx2 v[18:19], v[0:1], off offset:416
	v_pk_mul_f32 v[0:1], v[32:33], v[44:45] op_sel_hi:[1,0]
	v_pk_mul_f32 v[2:3], v[74:75], v[44:45] op_sel_hi:[1,0]
	v_and_b32_e32 v5, 0xffff0000, v48
	v_lshlrev_b32_e32 v6, 16, v49
	v_and_b32_e32 v7, 0xffff0000, v49
	v_pk_mul_f32 v[2:3], v[2:3], v[6:7]
	v_pk_mul_f32 v[0:1], v[0:1], v[4:5]
	v_lshlrev_b32_e32 v4, 16, v42
	v_cvt_pk_bf16_f32 v0, v0, v1
	v_cvt_pk_bf16_f32 v1, v2, v3
	global_store_dwordx2 v[18:19], v[0:1], off offset:448
	v_pk_mul_f32 v[0:1], v[76:77], v[44:45] op_sel_hi:[1,0]
	v_pk_mul_f32 v[2:3], v[30:31], v[44:45] op_sel_hi:[1,0]
	v_and_b32_e32 v5, 0xffff0000, v42
	v_lshlrev_b32_e32 v6, 16, v43
	v_and_b32_e32 v7, 0xffff0000, v43
	v_pk_mul_f32 v[2:3], v[2:3], v[6:7]
	v_pk_mul_f32 v[0:1], v[0:1], v[4:5]
	s_andn2_b64 vcc, exec, s[64:65]
	v_cvt_pk_bf16_f32 v0, v0, v1
	v_cvt_pk_bf16_f32 v1, v2, v3
	global_store_dwordx2 v[18:19], v[0:1], off offset:480
	s_cbranch_vccnz .LBB0_64
	s_ashr_i32 s2, s92, 2
	s_and_b32 s2, s2, -2
	v_readlane_b32 s4, v254, 22
	s_add_i32 s4, s2, s4
	s_ashr_i32 s5, s4, 31
	s_ashr_i32 s93, s92, 31
	s_lshl_b64 s[4:5], s[4:5], 19
	s_lshl_b32 s2, s35, 17
	s_lshl_b64 s[8:9], s[92:93], 18
	s_add_u32 s8, s58, s8
	s_addc_u32 s9, s59, s9
	s_lshl_b32 s12, s33, 17
	s_add_u32 s8, s8, s12
	s_addc_u32 s9, s9, 0
	s_cmp_eq_u32 s33, 0
	s_cselect_b64 vcc, -1, 0
	s_and_b64 s[10:11], vcc, exec
	s_cselect_b32 s10, 1, -1
	s_mov_b32 s11, 0x2900000
	s_cselect_b32 s14, s11, 0x3900000
	s_add_i32 s10, s10, s92
	s_ashr_i32 s11, s10, 31
	s_lshl_b64 s[10:11], s[10:11], 18
	v_cndmask_b32_e32 v0, v188, v177, vcc
	s_add_u32 s10, s58, s10
	v_mul_f32_e32 v1, 0xc3000000, v0
	s_addc_u32 s11, s59, s11
	v_cmp_gt_f32_e32 vcc, s75, v1
	s_add_u32 s10, s10, s12
	v_lshlrev_b32_e32 v152, 2, v199
	v_cndmask_b32_e32 v1, 0, v212, vcc
	s_addc_u32 s11, s11, 0
	v_lshl_add_u64 v[2:3], s[8:9], 0, v[152:153]
	s_movk_i32 s8, 0x204
	v_ashrrev_i32_e32 v10, 5, v157
	v_fmac_f32_e32 v1, 0xc3000000, v0
	s_and_b64 s[12:13], vcc, exec
	v_mul_lo_u32 v24, v10, s8
	v_ashrrev_i32_e32 v10, 5, v191
	v_exp_f32_e32 v0, v1
	s_cselect_b32 s12, 0xffffffc0, 0
	v_mul_lo_u32 v25, v10, s8
	v_ashrrev_i32_e32 v10, 5, v193
	s_or_b32 s2, s4, s2
	v_mul_lo_u32 v26, v10, s8
	v_ashrrev_i32_e32 v10, 5, v195
	s_add_u32 s2, s14, s2
	v_mul_lo_u32 v27, v10, s8
	v_lshlrev_b32_e32 v16, 8, v189
	v_lshlrev_b32_e32 v14, 8, v190
	v_lshlrev_b32_e32 v12, 8, v192
	v_lshlrev_b32_e32 v10, 8, v194
	s_addc_u32 s4, 0, s5
	v_and_b32_e32 v8, 60, v198
	v_ashrrev_i32_e32 v17, 31, v16
	v_ashrrev_i32_e32 v15, 31, v14
	v_ashrrev_i32_e32 v13, 31, v12
	v_ashrrev_i32_e32 v11, 31, v10
	v_lshl_or_b32 v22, v115, 4, s2
	v_mov_b32_e32 v23, s4
	v_readlane_b32 s4, v254, 18
	v_ldexp_f32 v0, v0, s12
	v_add_u32_e32 v1, 0, v152
	v_mad_u32_u24 v9, v8, s8, 0
	v_lshl_add_u64 v[10:11], v[10:11], 2, v[22:23]
	v_readlane_b32 s5, v254, 19
	v_lshl_add_u64 v[12:13], v[12:13], 2, v[22:23]
	v_lshl_add_u64 v[14:15], v[14:15], 2, v[22:23]
	v_lshl_add_u64 v[16:17], v[16:17], 2, v[22:23]
	v_lshl_add_u64 v[4:5], s[10:11], 0, v[152:153]
	v_mov_b32_e32 v6, v0
	v_mov_b32_e32 v7, v0
	v_lshl_add_u32 v18, v189, 2, v9
	v_and_b32_e32 v8, 0xffffff80, v198
	v_lshl_add_u32 v19, v190, 2, v9
	v_lshl_add_u32 v20, v192, 2, v9
	v_lshl_add_u32 v21, v194, 2, v9
	v_lshl_add_u64 v[10:11], s[4:5], 0, v[10:11]
	v_lshl_add_u64 v[12:13], s[4:5], 0, v[12:13]
	v_lshl_add_u64 v[14:15], s[4:5], 0, v[14:15]
	v_lshl_add_u64 v[16:17], s[4:5], 0, v[16:17]
	s_mov_b64 s[8:9], 0
	v_add_u32_e32 v22, v1, v24
	v_add_u32_e32 v23, v1, v25
	v_add_u32_e32 v24, v1, v26
	v_add_u32_e32 v25, v1, v27
.LBB0_101:
	v_ashrrev_i32_e32 v9, 31, v8
	v_add_u32_e32 v34, 0x800, v8
	v_lshlrev_b64 v[30:31], 2, v[8:9]
	v_ashrrev_i32_e32 v35, 31, v34
	v_add_u32_e32 v42, 0x1000, v8
	v_lshl_add_u64 v[26:27], v[2:3], 0, v[30:31]
	v_lshl_add_u64 v[30:31], v[4:5], 0, v[30:31]
	v_lshlrev_b64 v[38:39], 2, v[34:35]
	v_ashrrev_i32_e32 v43, 31, v42
	v_add_u32_e32 v50, 0x1800, v8
	s_waitcnt lgkmcnt(0)
	s_barrier
	global_load_dwordx4 v[26:29], v[26:27], off
	v_lshl_add_u64 v[34:35], v[2:3], 0, v[38:39]
	global_load_dwordx4 v[30:33], v[30:31], off
	v_lshl_add_u64 v[38:39], v[4:5], 0, v[38:39]
	v_lshlrev_b64 v[46:47], 2, v[42:43]
	v_ashrrev_i32_e32 v51, 31, v50
	global_load_dwordx4 v[34:37], v[34:35], off
	v_lshl_add_u64 v[42:43], v[2:3], 0, v[46:47]
	global_load_dwordx4 v[38:41], v[38:39], off
	v_lshl_add_u64 v[46:47], v[4:5], 0, v[46:47]
	v_lshlrev_b64 v[54:55], 2, v[50:51]
	global_load_dwordx4 v[42:45], v[42:43], off
	v_lshl_add_u64 v[50:51], v[2:3], 0, v[54:55]
	global_load_dwordx4 v[46:49], v[46:47], off
	v_lshl_add_u64 v[54:55], v[4:5], 0, v[54:55]
	global_load_dwordx4 v[50:53], v[50:51], off
	v_mov_b32_e32 v1, v0
	global_load_dwordx4 v[54:57], v[54:55], off
	v_add_u32_e32 v8, 0x2000, v8
	s_waitcnt vmcnt(0) lgkmcnt(0)
	v_pk_fma_f32 v[28:29], v[0:1], v[28:29], v[32:33]
	v_pk_fma_f32 v[26:27], v[6:7], v[26:27], v[30:31]
	ds_write2_b32 v22, v26, v27 offset1:1
	ds_write2_b32 v22, v28, v29 offset0:2 offset1:3
	v_lshl_add_u64 v[30:31], v[16:17], 0, s[8:9]
	v_pk_fma_f32 v[26:27], v[0:1], v[36:37], v[40:41]
	v_pk_fma_f32 v[28:29], v[6:7], v[34:35], v[38:39]
	ds_write2_b32 v23, v28, v29 offset1:1
	ds_write2_b32 v23, v26, v27 offset0:2 offset1:3
	v_pk_fma_f32 v[26:27], v[0:1], v[44:45], v[48:49]
	v_pk_fma_f32 v[28:29], v[6:7], v[42:43], v[46:47]
	ds_write2_b32 v24, v28, v29 offset1:1
	ds_write2_b32 v24, v26, v27 offset0:2 offset1:3
	v_pk_fma_f32 v[26:27], v[0:1], v[52:53], v[56:57]
	v_pk_fma_f32 v[28:29], v[6:7], v[50:51], v[54:55]
	v_add_u32_e32 v1, 0x400, v18
	ds_write2_b32 v25, v28, v29 offset1:1
	ds_write2_b32 v25, v26, v27 offset0:2 offset1:3
	s_waitcnt lgkmcnt(0)
	s_barrier
	ds_read2_b32 v[26:27], v18 offset1:129
	ds_read2_b32 v[28:29], v1 offset0:2 offset1:131
	v_add_u32_e32 v1, 0x400, v19
	s_waitcnt lgkmcnt(0)
	global_store_dwordx4 v[30:31], v[26:29], off
	ds_read2_b32 v[26:27], v19 offset1:129
	ds_read2_b32 v[28:29], v1 offset0:2 offset1:131
	v_lshl_add_u64 v[30:31], v[14:15], 0, s[8:9]
	v_add_u32_e32 v1, 0x400, v20
	s_waitcnt lgkmcnt(0)
	global_store_dwordx4 v[30:31], v[26:29], off
	ds_read2_b32 v[26:27], v20 offset1:129
	ds_read2_b32 v[28:29], v1 offset0:2 offset1:131
	v_lshl_add_u64 v[30:31], v[12:13], 0, s[8:9]
	v_add_u32_e32 v1, 0x400, v21
	s_waitcnt lgkmcnt(0)
	global_store_dwordx4 v[30:31], v[26:29], off
	ds_read2_b32 v[26:27], v21 offset1:129
	ds_read2_b32 v[28:29], v1 offset0:2 offset1:131
	v_lshl_add_u64 v[30:31], v[10:11], 0, s[8:9]
	s_add_u32 s8, s8, 0x100
	s_addc_u32 s9, s9, 0
	s_cmpk_lg_i32 s8, 0x400
	s_waitcnt lgkmcnt(0)
	global_store_dwordx4 v[30:31], v[26:29], off
	s_cbranch_scc1 .LBB0_101
	s_branch .LBB0_64

.LBB0_104:
	v_add_u32_e32 v30, s16, v51
	v_add_u32_e32 v31, v30, v56
	v_add_u32_e32 v29, s16, v56
	ds_read_b128 v[38:41], v31
	ds_read_b128 v[56:59], v31 offset:64
	v_add_u32_e32 v31, v29, v50
	ds_read_b128 v[60:63], v31 offset:9216
	s_waitcnt lgkmcnt(2)
	v_mfma_f32_16x16x32_bf16 v[38:41], v[38:41], v[0:3], 0
	v_add_u32_e32 v36, v29, v49
	s_lshl_b32 s2, s5, 1
	s_lshl_b32 s98, s62, 1
	s_add_i32 s98, s98, 0x100
	s_add_i32 s99, s4, 1
	s_cmpk_lt_i32 s4, 0x100
	s_cselect_b32 s99, s98, s99
	s_cselect_b32 s98, s62, 0
	s_cmpk_gt_i32 s98, 0x7f
	s_cselect_b32 s99, 0x200, s99
	s_and_b32 s98, s4, 0x101
	s_cmpk_eq_i32 s98, 0x101
	s_cselect_b32 s99, 0x200, s99
	s_add_i32 s98, s4, s34
	s_cmpk_eq_i32 s34, 0x100
	s_cselect_b32 s4, s99, s98
	s_waitcnt lgkmcnt(1)
	v_mfma_f32_16x16x32_bf16 v[38:41], v[56:59], v[4:7], v[38:41]
	s_cmpk_gt_i32 s4, 0x1ff
	s_mov_b64 s[22:23], s[44:45]
	s_waitcnt lgkmcnt(0)
	v_mfma_f32_16x16x32_bf16 v[38:41], v[60:63], v[8:11], v[38:41]
	ds_read_b128 v[48:51], v36
	ds_read_b128 v[56:59], v36 offset:64
	ds_read_b128 v[60:63], v31 offset:10496
	v_add_u32_e32 v36, v29, v47
	v_add_u32_e32 v29, v29, v46
	s_waitcnt lgkmcnt(2)
	v_mfma_f32_16x16x32_bf16 v[48:51], v[48:51], v[0:3], 0
	s_waitcnt lgkmcnt(1)
	v_mfma_f32_16x16x32_bf16 v[48:51], v[56:59], v[4:7], v[48:51]
	s_waitcnt lgkmcnt(0)
	v_mfma_f32_16x16x32_bf16 v[48:51], v[60:63], v[8:11], v[48:51]
	ds_read_b128 v[56:59], v36
	ds_read_b128 v[60:63], v36 offset:64
	ds_read_b128 v[64:67], v31 offset:11776
	s_waitcnt lgkmcnt(2)
	v_mfma_f32_16x16x32_bf16 v[56:59], v[56:59], v[0:3], 0
	s_waitcnt lgkmcnt(1)
	v_mfma_f32_16x16x32_bf16 v[56:59], v[60:63], v[4:7], v[56:59]
	s_waitcnt lgkmcnt(0)
	v_mfma_f32_16x16x32_bf16 v[56:59], v[64:67], v[8:11], v[56:59]
	ds_read_b128 v[60:63], v29
	ds_read_b128 v[64:67], v29 offset:64
	ds_read_b128 v[68:71], v31 offset:13056
	s_waitcnt lgkmcnt(2)
	v_mfma_f32_16x16x32_bf16 v[0:3], v[60:63], v[0:3], 0
	s_waitcnt lgkmcnt(1)
	v_mfma_f32_16x16x32_bf16 v[0:3], v[64:67], v[4:7], v[0:3]
	v_max_f32_e32 v6, v50, v50
	s_waitcnt lgkmcnt(0)
	v_mfma_f32_16x16x32_bf16 v[2:5], v[68:71], v[8:11], v[0:3]
	s_nop 4
	v_max_f32_e32 v0, v41, v41
	v_max_f32_e32 v1, v40, v40
	v_max_f32_e32 v0, v1, v0
	v_max_f32_e32 v1, v51, v51
	v_max_f32_e32 v1, v6, v1
	v_max3_f32 v0, v38, v39, v0
	v_max3_f32 v1, v48, v49, v1
	v_max3_f32 v0, v0, s70, v1
	v_max_f32_e32 v1, v59, v59
	v_max_f32_e32 v6, v58, v58
	v_max_f32_e32 v1, v6, v1
	v_max_f32_e32 v6, v5, v5
	v_max_f32_e32 v7, v4, v4
	v_max_f32_e32 v6, v7, v6
	v_max3_f32 v1, v56, v57, v1
	v_max3_f32 v6, v2, v3, v6
	v_max3_f32 v0, v0, v1, v6
	ds_bpermute_b32 v1, v37, v0
	s_waitcnt lgkmcnt(0)
	v_max_f32_e32 v1, v1, v1
	v_max_f32_e32 v0, v0, v1
	ds_bpermute_b32 v1, v35, v0
	s_waitcnt lgkmcnt(0)
	v_max3_f32 v1, v45, v0, v1
	v_sub_f32_e32 v6, v38, v1
	v_sub_f32_e32 v8, v48, v1
	v_exp_f32_e32 v29, v6
	v_sub_f32_e32 v6, v39, v1
	v_exp_f32_e32 v43, v8
	v_sub_f32_e32 v8, v49, v1
	v_exp_f32_e32 v31, v6
	v_sub_f32_e32 v6, v40, v1
	v_exp_f32_e32 v44, v8
	v_sub_f32_e32 v8, v50, v1
	v_sub_f32_e32 v0, v45, v1
	v_exp_f32_e32 v36, v6
	v_sub_f32_e32 v6, v41, v1
	v_exp_f32_e32 v45, v8
	v_sub_f32_e32 v8, v51, v1
	v_exp_f32_e32 v42, v6
	v_exp_f32_e32 v46, v8
	v_cvt_pk_bf16_f32 v6, v29, v31
	v_cvt_pk_bf16_f32 v8, v43, v44
	v_cvt_pk_bf16_f32 v7, v36, v42
	v_cvt_pk_bf16_f32 v9, v45, v46
	ds_write2_b64 v52, v[6:7], v[8:9] offset1:4
	v_sub_f32_e32 v6, v56, v1
	v_exp_f32_e32 v47, v6
	v_sub_f32_e32 v6, v57, v1
	v_sub_f32_e32 v2, v2, v1
	v_exp_f32_e32 v48, v6
	v_sub_f32_e32 v6, v58, v1
	v_exp_f32_e32 v51, v2
	v_sub_f32_e32 v2, v3, v1
	v_exp_f32_e32 v49, v6
	v_sub_f32_e32 v6, v59, v1
	v_exp_f32_e32 v53, v2
	v_sub_f32_e32 v2, v4, v1
	v_sub_f32_e32 v1, v5, v1
	v_exp_f32_e32 v50, v6
	v_exp_f32_e32 v54, v2
	v_exp_f32_e32 v1, v1
	v_exp_f32_e32 v0, v0
	v_cvt_pk_bf16_f32 v6, v47, v48
	v_cvt_pk_bf16_f32 v7, v49, v50
	v_cvt_pk_bf16_f32 v2, v51, v53
	v_cvt_pk_bf16_f32 v3, v54, v1
	ds_write2_b64 v52, v[6:7], v[2:3] offset0:8 offset1:12
	v_pk_mul_f32 v[6:7], v[16:17], v[0:1] op_sel_hi:[1,0]
	v_pk_mul_f32 v[16:17], v[26:27], v[0:1] op_sel_hi:[1,0]
	v_add_u32_e32 v26, v30, v152
	v_pk_mul_f32 v[4:5], v[14:15], v[0:1] op_sel_hi:[1,0]
	v_pk_mul_f32 v[2:3], v[12:13], v[0:1] op_sel_hi:[1,0]
	v_pk_mul_f32 v[8:9], v[18:19], v[0:1] op_sel_hi:[1,0]
	v_pk_mul_f32 v[12:13], v[22:23], v[0:1] op_sel_hi:[1,0]
	v_pk_mul_f32 v[10:11], v[20:21], v[0:1] op_sel_hi:[1,0]
	v_pk_mul_f32 v[14:15], v[24:25], v[0:1] op_sel_hi:[1,0]
	ds_read_b128 v[18:21], v55 offset:47104
	ds_read_b128 v[22:25], v55 offset:47168
	ds_read_b128 v[38:41], v26 offset:14336
	s_waitcnt lgkmcnt(0)
	v_mfma_f32_16x16x32_bf16 v[2:5], v[38:41], v[18:21], v[2:5]
	ds_read_b128 v[38:41], v26 offset:14400
	s_waitcnt lgkmcnt(0)
	v_mfma_f32_16x16x32_bf16 v[2:5], v[38:41], v[22:25], v[2:5]
	ds_read_b128 v[38:41], v26 offset:16640
	s_waitcnt lgkmcnt(0)
	v_mfma_f32_16x16x32_bf16 v[6:9], v[38:41], v[18:21], v[6:9]
	ds_read_b128 v[38:41], v26 offset:16704
	s_waitcnt lgkmcnt(0)
	v_mfma_f32_16x16x32_bf16 v[6:9], v[38:41], v[22:25], v[6:9]
	ds_read_b128 v[38:41], v26 offset:18944
	s_waitcnt lgkmcnt(0)
	v_mfma_f32_16x16x32_bf16 v[10:13], v[38:41], v[18:21], v[10:13]
	ds_read_b128 v[38:41], v26 offset:19008
	s_waitcnt lgkmcnt(0)
	v_mfma_f32_16x16x32_bf16 v[10:13], v[38:41], v[22:25], v[10:13]
	ds_read_b128 v[38:41], v26 offset:21248
	s_waitcnt lgkmcnt(0)
	v_mfma_f32_16x16x32_bf16 v[14:17], v[38:41], v[18:21], v[14:17]
	ds_read_b128 v[18:21], v26 offset:21312
	s_waitcnt lgkmcnt(0)
	s_barrier
	v_mfma_f32_16x16x32_bf16 v[14:17], v[18:21], v[22:25], v[14:17]
	v_add_f32_e32 v18, 0, v29
	v_add_f32_e32 v18, v31, v18
	v_add_f32_e32 v18, v36, v18
	v_add_f32_e32 v18, v42, v18
	v_add_f32_e32 v18, v43, v18
	v_add_f32_e32 v18, v44, v18
	v_add_f32_e32 v18, v45, v18
	v_add_f32_e32 v18, v46, v18
	v_add_f32_e32 v18, v47, v18
	v_add_f32_e32 v18, v48, v18
	v_add_f32_e32 v18, v49, v18
	v_add_f32_e32 v18, v50, v18
	v_add_f32_e32 v18, v51, v18
	v_add_f32_e32 v18, v53, v18
	v_add_f32_e32 v18, v54, v18
	v_add_f32_e32 v1, v1, v18
	v_fmac_f32_e32 v1, v28, v0
	ds_bpermute_b32 v0, v37, v1
	s_waitcnt lgkmcnt(0)
	v_add_f32_e32 v0, v1, v0
	ds_bpermute_b32 v1, v35, v0
	v_mov_b32_e32 v35, v153
	s_waitcnt lgkmcnt(0)
	v_add_f32_e32 v0, v0, v1
	v_div_scale_f32 v1, s[8:9], v0, v0, 1.0
	v_rcp_f32_e32 v18, v1
	s_nop 0
	v_fma_f32 v19, -v1, v18, 1.0
	v_fmac_f32_e32 v18, v19, v18
	v_div_scale_f32 v19, vcc, 1.0, v0, 1.0
	v_mul_f32_e32 v20, v19, v18
	v_fma_f32 v21, -v1, v20, v19
	v_fmac_f32_e32 v20, v21, v18
	v_fma_f32 v1, -v1, v20, v19
	v_div_fmas_f32 v1, v1, v18, v20
	v_div_fixup_f32 v0, v1, v0, 1.0
	v_lshlrev_b64 v[18:19], 12, v[32:33]
	v_pk_mul_f32 v[4:5], v[4:5], v[0:1] op_sel_hi:[1,0]
	v_pk_mul_f32 v[2:3], v[2:3], v[0:1] op_sel_hi:[1,0]
	v_pk_mul_f32 v[6:7], v[6:7], v[0:1] op_sel_hi:[1,0]
	v_cvt_pk_bf16_f32 v2, v2, v3
	v_cvt_pk_bf16_f32 v3, v4, v5
	v_lshl_add_u64 v[4:5], s[18:19], 0, v[18:19]
	v_lshl_add_u64 v[4:5], v[4:5], 0, s[2:3]
	v_lshl_add_u64 v[4:5], v[4:5], 0, v[34:35]
	s_mov_b32 s2, 0x7f00000
	v_add_co_u32_e32 v4, vcc, s2, v4
	v_cvt_pk_bf16_f32 v6, v6, v7
	s_nop 0
	v_addc_co_u32_e32 v5, vcc, 0, v5, vcc
	global_store_dwordx2 v[4:5], v[2:3], off offset:3072
	v_pk_mul_f32 v[2:3], v[8:9], v[0:1] op_sel_hi:[1,0]
	s_nop 0
	v_cvt_pk_bf16_f32 v7, v2, v3
	global_store_dwordx2 v[4:5], v[6:7], off offset:3104
	v_pk_mul_f32 v[2:3], v[12:13], v[0:1] op_sel_hi:[1,0]
	v_pk_mul_f32 v[6:7], v[10:11], v[0:1] op_sel_hi:[1,0]
	s_nop 0
	v_cvt_pk_bf16_f32 v6, v6, v7
	v_cvt_pk_bf16_f32 v7, v2, v3
	v_pk_mul_f32 v[2:3], v[16:17], v[0:1] op_sel_hi:[1,0]
	v_pk_mul_f32 v[0:1], v[14:15], v[0:1] op_sel_hi:[1,0]
	global_store_dwordx2 v[4:5], v[6:7], off offset:3136
	v_cvt_pk_bf16_f32 v0, v0, v1
	v_cvt_pk_bf16_f32 v1, v2, v3
	global_store_dwordx2 v[4:5], v[0:1], off offset:3168
	s_cbranch_scc1 .LBB0_116

.LBB0_109:
	v_ashrrev_i32_e32 v22, 6, v20
	v_and_b32_e32 v21, 15, v20
	v_readlane_b32 s16, v254, 43
	v_lshl_or_b32 v0, v22, 4, v21
	v_readlane_b32 s17, v254, 44
	s_and_b32 s9, s2, 7
	v_add_u32_e32 v32, s5, v0
	v_mov_b64_e32 v[0:1], s[16:17]
	s_movk_i32 s2, 0x600
	v_ashrrev_i32_e32 v15, 3, v20
	v_mad_i64_i32 v[0:1], s[16:17], v32, s2, v[0:1]
	v_add_u32_e32 v12, s8, v15
	s_mul_i32 s2, s9, 0xc0
	v_ashrrev_i32_e32 v13, 31, v12
	v_readlane_b32 s16, v254, 45
	v_lshl_add_u64 v[0:1], v[0:1], 0, s[2:3]
	v_lshlrev_b64 v[16:17], 10, v[12:13]
	v_readlane_b32 s17, v254, 46
	s_lshl_b32 s5, s9, 6
	s_lshl_b32 s2, s9, 7
	s_ashr_i32 s9, s8, 31
	v_lshl_add_u64 v[12:13], s[16:17], 0, v[16:17]
	s_lshl_b64 s[16:17], s[8:9], 10
	v_lshlrev_b32_e32 v28, 3, v20
	s_add_u32 s22, s63, s16
	v_readlane_b32 s9, v254, 47
	v_add_u32_e32 v24, s5, v15
	v_and_b32_e32 v14, 56, v28
	s_addc_u32 s23, s9, s17
	v_mad_i64_i32 v[26:27], s[24:25], v24, s21, 0
	v_bfe_u32 v23, v20, 4, 2
	v_bfe_u32 v25, v20, 2, 6
	v_lshl_add_u64 v[12:13], v[12:13], 0, s[2:3]
	v_lshlrev_b32_e32 v18, 1, v14
	v_mov_b32_e32 v19, v153
	v_lshl_add_u64 v[26:27], v[26:27], 1, s[22:23]
	v_lshlrev_b32_e32 v152, 4, v23
	v_lshl_add_u64 v[12:13], v[12:13], 0, v[18:19]
	v_lshl_add_u64 v[30:31], v[26:27], 0, v[18:19]
	v_add_u32_e32 v18, s8, v25
	v_lshl_add_u64 v[8:9], v[0:1], 0, v[152:153]
	v_ashrrev_i32_e32 v19, 31, v18
	v_readlane_b32 s8, v254, 48
	global_load_dwordx4 v[0:3], v[8:9], off
	global_load_dwordx4 v[4:7], v[8:9], off offset:64
	s_nop 0
	global_load_dwordx4 v[8:11], v[8:9], off offset:128
	v_lshlrev_b64 v[18:19], 6, v[18:19]
	v_readlane_b32 s9, v254, 49
	v_and_b32_e32 v33, 24, v28
	v_lshlrev_b32_e32 v28, 1, v33
	v_lshl_add_u64 v[26:27], s[8:9], 0, v[18:19]
	v_mov_b32_e32 v29, v153
	s_movk_i32 s8, 0x48
	v_lshl_add_u64 v[34:35], v[26:27], 0, v[28:29]
	v_mad_u64_u32 v[36:37], s[8:9], v15, s8, v[14:15]
	global_load_dwordx4 v[26:29], v[12:13], off
	global_load_dwordx4 v[38:41], v[30:31], off
	s_nop 0
	global_load_dwordx4 v[12:15], v[34:35], off
	s_movk_i32 s8, 0x100
	v_mad_u32_u24 v48, v25, 40, v33
	v_lshl_add_u32 v25, v36, 1, 0
	v_cmp_gt_i32_e32 vcc, s8, v20
	s_waitcnt vmcnt(0) lgkmcnt(0)
	ds_write_b128 v25, v[26:29]
	ds_write_b128 v25, v[38:41] offset:14336
	s_and_saveexec_b64 s[8:9], vcc
	v_lshl_add_u32 v25, v48, 1, 0
	ds_write_b128 v25, v[12:15] offset:9216
	s_or_b64 exec, exec, s[8:9]
	v_and_b32_e32 v14, 64, v209
	s_movk_i32 s8, 0x900
	v_xor_b32_e32 v13, 16, v209
	v_add_u32_e32 v14, 64, v14
	v_mul_lo_u32 v12, v22, s8
	v_cmp_lt_i32_e64 s[8:9], v13, v14
	v_mul_u32_u24_e32 v51, 0x90, v21
	v_add3_u32 v53, 0, v12, v51
	v_cndmask_b32_e64 v13, v209, v13, s[8:9]
	v_lshlrev_b32_e32 v37, 2, v13
	v_xor_b32_e32 v13, 32, v209
	v_cmp_lt_i32_e64 s[8:9], v13, v14
	v_mov_b32_e32 v12, 0x900
	v_and_b32_e32 v14, 7, v20
	v_cndmask_b32_e64 v13, v209, v13, s[8:9]
	s_movk_i32 s8, 0x90
	v_mad_u32_u24 v49, v21, s8, v12
	v_mov_b32_e32 v12, 0x1200
	v_mad_u32_u24 v47, v21, s8, v12
	v_mov_b32_e32 v12, 0x1b00
	v_lshlrev_b32_e32 v35, 2, v13
	v_mad_u32_u24 v46, v21, s8, v12
	v_lshl_add_u64 v[12:13], v[16:17], 0, s[2:3]
	v_lshlrev_b32_e32 v14, 4, v14
	v_mov_b32_e32 v15, v153
	v_lshl_add_u64 v[12:13], v[12:13], 0, v[14:15]
	v_lshl_add_u64 v[38:39], s[10:11], 0, v[12:13]
	v_lshlrev_b32_e32 v16, 1, v24
	v_mov_b64_e32 v[12:13], s[16:17]
	v_mad_i64_i32 v[12:13], s[8:9], v16, s21, v[12:13]
	v_lshl_add_u64 v[12:13], v[12:13], 0, v[14:15]
	v_lshl_add_u64 v[40:41], s[12:13], 0, v[12:13]
	v_and_b32_e32 v12, 3, v20
	v_lshlrev_b32_e32 v12, 4, v12
	v_mov_b32_e32 v13, v153
	v_lshl_add_u64 v[12:13], v[18:19], 0, v[12:13]
	v_mov_b32_e32 v54, 0
	v_ashrrev_i32_e32 v33, 31, v32
	v_lshlrev_b32_e32 v34, 3, v23
	s_lshr_b32 s20, s21, 6
	v_mul_u32_u24_e32 v50, 0x50, v21
	s_mov_b32 s2, 1
	v_lshl_add_u64 v[42:43], s[14:15], 0, v[12:13]
	v_mov_b32_e32 v45, 0xf149f2ca
	v_mov_b32_e32 v12, 0
	v_mov_b32_e32 v13, v54
	v_mov_b32_e32 v14, v54
	v_mov_b32_e32 v15, v54
	v_mov_b32_e32 v16, 0
	v_mov_b32_e32 v17, v54
	v_mov_b32_e32 v18, v54
	v_mov_b32_e32 v19, v54
	v_mov_b32_e32 v20, 0
	v_mov_b32_e32 v21, v54
	v_mov_b32_e32 v22, v54
	v_mov_b32_e32 v23, v54
	v_mov_b32_e32 v24, 0
	v_mov_b32_e32 v25, v54
	v_mov_b32_e32 v26, v54
	v_mov_b32_e32 v27, v54
	s_waitcnt lgkmcnt(0)
	s_barrier

.LBB0_125:
	v_cmp_gt_i32_e32 vcc, s14, v87
	global_load_dwordx4 v[4:7], v[44:45], off offset:16
	global_load_dwordx4 v[8:11], v[44:45], off
	v_cndmask_b32_e32 v0, v138, v250, vcc
	v_and_b32_e32 v102, v0, v52
	v_cndmask_b32_e32 v0, v244, v208, vcc
	v_cndmask_b32_e32 v100, v245, v222, vcc
	v_and_b32_e32 v53, v0, v52
	v_add_u32_e32 v101, -1, v100
	v_subrev_co_u32_e32 v0, vcc, 15, v102
	v_min_i32_e32 v1, v0, v101
	s_nop 0
	v_cndmask_b32_e64 v1, v1, 0, vcc
	v_cmp_lt_u32_e32 vcc, v0, v100
	v_add_u32_e32 v0, v1, v53
	v_ashrrev_i32_e32 v1, 31, v0
	v_lshlrev_b64 v[0:1], 10, v[0:1]
	v_lshl_add_u64 v[0:1], v[46:47], 0, v[0:1]
	v_cndmask_b32_e64 v68, 0, 1.0, vcc
	global_load_dwordx4 v[64:67], v[0:1], off
	v_subrev_co_u32_e32 v0, vcc, 14, v102
	v_min_i32_e32 v1, v0, v101
	s_nop 0
	v_cndmask_b32_e64 v1, v1, 0, vcc
	v_cmp_lt_u32_e32 vcc, v0, v100
	v_add_u32_e32 v0, v1, v53
	v_ashrrev_i32_e32 v1, 31, v0
	v_lshlrev_b64 v[0:1], 10, v[0:1]
	v_lshl_add_u64 v[0:1], v[46:47], 0, v[0:1]
	v_cndmask_b32_e64 v58, 0, 1.0, vcc
	global_load_dwordx4 v[32:35], v[0:1], off
	v_subrev_co_u32_e32 v0, vcc, 13, v102
	v_min_i32_e32 v1, v0, v101
	s_nop 0
	v_cndmask_b32_e64 v1, v1, 0, vcc
	v_cmp_lt_u32_e32 vcc, v0, v100
	v_add_u32_e32 v0, v1, v53
	v_ashrrev_i32_e32 v1, 31, v0
	v_lshlrev_b64 v[0:1], 10, v[0:1]
	v_lshl_add_u64 v[0:1], v[46:47], 0, v[0:1]
	global_load_dwordx4 v[28:31], v[0:1], off
	v_cndmask_b32_e64 v56, 0, 1.0, vcc
	v_subrev_co_u32_e32 v0, vcc, 12, v102
	v_min_i32_e32 v1, v0, v101
	s_nop 0
	v_cndmask_b32_e64 v1, v1, 0, vcc
	v_cmp_lt_u32_e32 vcc, v0, v100
	v_add_u32_e32 v0, v1, v53
	v_ashrrev_i32_e32 v1, 31, v0
	v_lshlrev_b64 v[0:1], 10, v[0:1]
	v_lshl_add_u64 v[0:1], v[46:47], 0, v[0:1]
	v_cndmask_b32_e64 v54, 0, 1.0, vcc
	global_load_dwordx4 v[24:27], v[0:1], off
	v_subrev_co_u32_e32 v0, vcc, 11, v102
	v_min_i32_e32 v1, v0, v101
	s_nop 0
	v_cndmask_b32_e64 v1, v1, 0, vcc
	v_cmp_lt_u32_e32 vcc, v0, v100
	v_add_u32_e32 v0, v1, v53
	v_ashrrev_i32_e32 v1, 31, v0
	v_lshlrev_b64 v[0:1], 10, v[0:1]
	v_lshl_add_u64 v[0:1], v[46:47], 0, v[0:1]
	v_cndmask_b32_e64 v42, 0, 1.0, vcc
	global_load_dwordx4 v[20:23], v[0:1], off
	v_subrev_co_u32_e32 v0, vcc, 10, v102
	v_min_i32_e32 v1, v0, v101
	s_nop 0
	v_cndmask_b32_e64 v1, v1, 0, vcc
	v_cmp_lt_u32_e32 vcc, v0, v100
	v_add_u32_e32 v0, v1, v53
	v_ashrrev_i32_e32 v1, 31, v0
	v_lshlrev_b64 v[0:1], 10, v[0:1]
	v_lshl_add_u64 v[0:1], v[46:47], 0, v[0:1]
	v_cndmask_b32_e64 v40, 0, 1.0, vcc
	global_load_dwordx4 v[16:19], v[0:1], off
	v_subrev_co_u32_e32 v0, vcc, 9, v102
	v_min_i32_e32 v1, v0, v101
	s_nop 0
	v_cndmask_b32_e64 v1, v1, 0, vcc
	v_cmp_lt_u32_e32 vcc, v0, v100
	v_add_u32_e32 v0, v1, v53
	v_ashrrev_i32_e32 v1, 31, v0
	v_lshlrev_b64 v[0:1], 10, v[0:1]
	v_lshl_add_u64 v[0:1], v[46:47], 0, v[0:1]
	v_cndmask_b32_e64 v38, 0, 1.0, vcc
	global_load_dwordx4 v[12:15], v[0:1], off
	v_subrev_co_u32_e32 v0, vcc, 8, v102
	v_min_i32_e32 v1, v0, v101
	s_nop 0
	v_cndmask_b32_e64 v1, v1, 0, vcc
	v_cmp_lt_u32_e32 vcc, v0, v100
	v_add_u32_e32 v0, v1, v53
	v_ashrrev_i32_e32 v1, 31, v0
	v_lshlrev_b64 v[0:1], 10, v[0:1]
	v_lshl_add_u64 v[0:1], v[46:47], 0, v[0:1]
	global_load_dwordx4 v[0:3], v[0:1], off
	v_cndmask_b32_e64 v36, 0, 1.0, vcc
	s_movk_i32 s2, 0x7ff
	s_waitcnt vmcnt(0) lgkmcnt(0)
	v_lshlrev_b32_e32 v60, 16, v66
	v_and_b32_e32 v61, 0xffff0000, v66
	v_lshlrev_b32_e32 v62, 16, v67
	v_and_b32_e32 v63, 0xffff0000, v67
	v_lshlrev_b32_e32 v66, 16, v64
	v_and_b32_e32 v67, 0xffff0000, v64
	v_lshlrev_b32_e32 v70, 16, v65
	v_and_b32_e32 v71, 0xffff0000, v65
	v_pk_mul_f32 v[60:61], v[68:69], v[60:61] op_sel_hi:[0,1]
	v_pk_mul_f32 v[62:63], v[68:69], v[62:63] op_sel_hi:[0,1]
	v_pk_mul_f32 v[64:65], v[68:69], v[66:67] op_sel_hi:[0,1]
	v_pk_mul_f32 v[66:67], v[68:69], v[70:71] op_sel_hi:[0,1]
	ds_read_b128 v[68:71], v89
	ds_read_b128 v[72:75], v89 offset:16
	s_waitcnt lgkmcnt(1)
	v_pk_fma_f32 v[64:65], v[64:65], v[68:69], v[8:9]
	s_waitcnt lgkmcnt(0)
	v_pk_fma_f32 v[76:77], v[60:61], v[72:73], v[4:5]
	v_lshlrev_b32_e32 v60, 16, v32
	v_and_b32_e32 v61, 0xffff0000, v32
	v_lshlrev_b32_e32 v32, 16, v33
	v_and_b32_e32 v33, 0xffff0000, v33
	v_pk_mul_f32 v[78:79], v[58:59], v[32:33] op_sel_hi:[0,1]
	v_lshlrev_b32_e32 v32, 16, v34
	v_and_b32_e32 v33, 0xffff0000, v34
	v_lshlrev_b32_e32 v34, 16, v35
	v_and_b32_e32 v35, 0xffff0000, v35
	v_pk_mul_f32 v[80:81], v[58:59], v[60:61] op_sel_hi:[0,1]
	v_pk_mul_f32 v[82:83], v[58:59], v[34:35] op_sel_hi:[0,1]
	v_pk_mul_f32 v[84:85], v[58:59], v[32:33] op_sel_hi:[0,1]
	ds_read_b128 v[32:35], v89 offset:2048
	ds_read_b128 v[58:61], v89 offset:2064
	v_pk_fma_f32 v[62:63], v[62:63], v[74:75], v[6:7]
	v_pk_fma_f32 v[66:67], v[66:67], v[70:71], v[10:11]
	s_waitcnt lgkmcnt(1)
	v_pk_fma_f32 v[64:65], v[80:81], v[32:33], v[64:65]
	s_waitcnt lgkmcnt(0)
	v_pk_fma_f32 v[104:105], v[82:83], v[60:61], v[62:63]
	v_lshlrev_b32_e32 v62, 16, v28
	v_and_b32_e32 v63, 0xffff0000, v28
	v_lshlrev_b32_e32 v28, 16, v29
	v_and_b32_e32 v29, 0xffff0000, v29
	v_pk_mul_f32 v[108:109], v[56:57], v[28:29] op_sel_hi:[0,1]
	v_lshlrev_b32_e32 v28, 16, v30
	v_and_b32_e32 v29, 0xffff0000, v30
	v_lshlrev_b32_e32 v30, 16, v31
	v_and_b32_e32 v31, 0xffff0000, v31
	v_pk_mul_f32 v[106:107], v[56:57], v[62:63] op_sel_hi:[0,1]
	v_pk_mul_f32 v[110:111], v[56:57], v[28:29] op_sel_hi:[0,1]
	v_pk_mul_f32 v[56:57], v[56:57], v[30:31] op_sel_hi:[0,1]
	ds_read_b128 v[28:31], v89 offset:4096
	v_pk_fma_f32 v[82:83], v[82:83], v[74:75], v[6:7]
	v_pk_fma_f32 v[114:115], v[74:75], v[56:57], v[6:7]
	v_pk_fma_f32 v[82:83], v[56:57], v[60:61], v[82:83]
	v_pk_fma_f32 v[66:67], v[78:79], v[34:35], v[66:67]
	s_waitcnt lgkmcnt(0)
	v_pk_fma_f32 v[112:113], v[106:107], v[28:29], v[64:65]
	ds_read_b128 v[62:65], v89 offset:4112
	v_pk_fma_f32 v[76:77], v[84:85], v[58:59], v[76:77]
	v_pk_fma_f32 v[78:79], v[70:71], v[78:79], v[10:11]
	v_pk_fma_f32 v[84:85], v[84:85], v[72:73], v[4:5]
	v_pk_fma_f32 v[66:67], v[108:109], v[30:31], v[66:67]
	s_waitcnt lgkmcnt(0)
	v_pk_fma_f32 v[104:105], v[56:57], v[64:65], v[104:105]
	v_lshlrev_b32_e32 v56, 16, v24
	v_and_b32_e32 v57, 0xffff0000, v24
	v_lshlrev_b32_e32 v24, 16, v25
	v_and_b32_e32 v25, 0xffff0000, v25
	v_pk_mul_f32 v[116:117], v[54:55], v[24:25] op_sel_hi:[0,1]
	v_lshlrev_b32_e32 v24, 16, v26
	v_and_b32_e32 v25, 0xffff0000, v26
	v_lshlrev_b32_e32 v26, 16, v27
	v_and_b32_e32 v27, 0xffff0000, v27
	v_pk_mul_f32 v[120:121], v[54:55], v[26:27] op_sel_hi:[0,1]
	v_pk_mul_f32 v[122:123], v[54:55], v[24:25] op_sel_hi:[0,1]
	ds_read_b128 v[24:27], v89 offset:6144
	v_pk_fma_f32 v[76:77], v[110:111], v[62:63], v[76:77]
	v_pk_fma_f32 v[78:79], v[108:109], v[34:35], v[78:79]
	v_pk_fma_f32 v[84:85], v[110:111], v[58:59], v[84:85]
	v_pk_fma_f32 v[108:109], v[70:71], v[108:109], v[10:11]
	v_pk_fma_f32 v[110:111], v[72:73], v[110:111], v[4:5]
	v_pk_fma_f32 v[74:75], v[74:75], v[120:121], v[6:7]
	v_pk_fma_f32 v[72:73], v[72:73], v[122:123], v[4:5]
	v_lshlrev_b32_e32 v4, 16, v20
	v_and_b32_e32 v5, 0xffff0000, v20
	v_lshlrev_b32_e32 v6, 16, v21
	v_and_b32_e32 v7, 0xffff0000, v21
	v_pk_mul_f32 v[118:119], v[54:55], v[56:57] op_sel_hi:[0,1]
	ds_read_b128 v[54:57], v89 offset:6160
	s_waitcnt lgkmcnt(1)
	v_pk_fma_f32 v[66:67], v[116:117], v[26:27], v[66:67]
	v_pk_fma_f32 v[78:79], v[116:117], v[30:31], v[78:79]
	v_pk_fma_f32 v[108:109], v[34:35], v[116:117], v[108:109]
	v_pk_fma_f32 v[70:71], v[70:71], v[116:117], v[10:11]
	v_pk_mul_f32 v[20:21], v[42:43], v[4:5] op_sel_hi:[0,1]
	v_pk_mul_f32 v[116:117], v[42:43], v[6:7] op_sel_hi:[0,1]
	v_lshlrev_b32_e32 v4, 16, v22
	v_and_b32_e32 v5, 0xffff0000, v22
	v_lshlrev_b32_e32 v6, 16, v23
	v_and_b32_e32 v7, 0xffff0000, v23
	v_pk_fma_f32 v[80:81], v[68:69], v[80:81], v[8:9]
	v_pk_mul_f32 v[22:23], v[42:43], v[4:5] op_sel_hi:[0,1]
	v_pk_mul_f32 v[42:43], v[42:43], v[6:7] op_sel_hi:[0,1]
	ds_read_b128 v[4:7], v89 offset:8192
	v_pk_fma_f32 v[80:81], v[106:107], v[32:33], v[80:81]
	v_pk_fma_f32 v[106:107], v[68:69], v[106:107], v[8:9]
	v_pk_fma_f32 v[68:69], v[68:69], v[118:119], v[8:9]
	ds_read_b128 v[8:11], v89 offset:8208
	v_pk_fma_f32 v[112:113], v[118:119], v[24:25], v[112:113]
	v_pk_fma_f32 v[80:81], v[118:119], v[28:29], v[80:81]
	v_pk_fma_f32 v[106:107], v[32:33], v[118:119], v[106:107]
	s_waitcnt lgkmcnt(2)
	v_pk_fma_f32 v[104:105], v[120:121], v[56:57], v[104:105]
	v_pk_fma_f32 v[82:83], v[120:121], v[64:65], v[82:83]
	v_pk_fma_f32 v[114:115], v[120:121], v[60:61], v[114:115]
	s_waitcnt lgkmcnt(1)
	v_pk_fma_f32 v[112:113], v[20:21], v[4:5], v[112:113]
	v_pk_fma_f32 v[80:81], v[20:21], v[24:25], v[80:81]
	v_pk_fma_f32 v[106:107], v[20:21], v[28:29], v[106:107]
	v_pk_fma_f32 v[32:33], v[32:33], v[20:21], v[68:69]
	v_lshlrev_b32_e32 v20, 16, v16
	v_and_b32_e32 v21, 0xffff0000, v16
	v_lshlrev_b32_e32 v16, 16, v17
	v_and_b32_e32 v17, 0xffff0000, v17
	v_pk_fma_f32 v[76:77], v[122:123], v[54:55], v[76:77]
	v_pk_fma_f32 v[84:85], v[122:123], v[62:63], v[84:85]
	v_pk_fma_f32 v[110:111], v[122:123], v[58:59], v[110:111]
	s_waitcnt lgkmcnt(0)
	v_pk_fma_f32 v[104:105], v[42:43], v[10:11], v[104:105]
	v_pk_fma_f32 v[82:83], v[42:43], v[56:57], v[82:83]
	v_pk_fma_f32 v[114:115], v[42:43], v[64:65], v[114:115]
	v_pk_fma_f32 v[42:43], v[60:61], v[42:43], v[74:75]
	v_pk_mul_f32 v[60:61], v[40:41], v[16:17] op_sel_hi:[0,1]
	v_lshlrev_b32_e32 v16, 16, v18
	v_and_b32_e32 v17, 0xffff0000, v18
	v_lshlrev_b32_e32 v18, 16, v19
	v_and_b32_e32 v19, 0xffff0000, v19
	v_pk_fma_f32 v[76:77], v[22:23], v[8:9], v[76:77]
	v_pk_fma_f32 v[84:85], v[22:23], v[54:55], v[84:85]
	v_pk_fma_f32 v[110:111], v[22:23], v[62:63], v[110:111]
	v_pk_fma_f32 v[34:35], v[34:35], v[116:117], v[70:71]
	v_pk_fma_f32 v[58:59], v[58:59], v[22:23], v[72:73]
	v_pk_mul_f32 v[68:69], v[40:41], v[20:21] op_sel_hi:[0,1]
	v_pk_mul_f32 v[70:71], v[40:41], v[18:19] op_sel_hi:[0,1]
	v_pk_mul_f32 v[40:41], v[40:41], v[16:17] op_sel_hi:[0,1]
	ds_read_b128 v[16:19], v89 offset:10240
	ds_read_b128 v[20:23], v89 offset:10256
	v_pk_fma_f32 v[66:67], v[116:117], v[6:7], v[66:67]
	v_pk_fma_f32 v[78:79], v[116:117], v[26:27], v[78:79]
	v_pk_fma_f32 v[108:109], v[116:117], v[30:31], v[108:109]
	v_pk_fma_f32 v[32:33], v[28:29], v[68:69], v[32:33]
	v_lshlrev_b32_e32 v28, 16, v12
	v_and_b32_e32 v29, 0xffff0000, v12
	v_lshlrev_b32_e32 v12, 16, v13
	v_and_b32_e32 v13, 0xffff0000, v13
	s_waitcnt lgkmcnt(1)
	v_pk_fma_f32 v[66:67], v[60:61], v[18:19], v[66:67]
	s_waitcnt lgkmcnt(0)
	v_pk_fma_f32 v[74:75], v[40:41], v[20:21], v[76:77]
	v_pk_fma_f32 v[76:77], v[70:71], v[22:23], v[104:105]
	v_pk_fma_f32 v[78:79], v[60:61], v[6:7], v[78:79]
	v_pk_fma_f32 v[104:105], v[68:69], v[24:25], v[106:107]
	v_pk_fma_f32 v[106:107], v[60:61], v[26:27], v[108:109]
	v_pk_fma_f32 v[34:35], v[30:31], v[60:61], v[34:35]
	v_pk_mul_f32 v[60:61], v[38:39], v[12:13] op_sel_hi:[0,1]
	v_lshlrev_b32_e32 v12, 16, v14
	v_and_b32_e32 v13, 0xffff0000, v14
	v_lshlrev_b32_e32 v14, 16, v15
	v_and_b32_e32 v15, 0xffff0000, v15
	v_pk_fma_f32 v[84:85], v[40:41], v[8:9], v[84:85]
	v_pk_fma_f32 v[108:109], v[40:41], v[54:55], v[110:111]
	v_pk_fma_f32 v[40:41], v[40:41], v[62:63], v[58:59]
	v_pk_mul_f32 v[58:59], v[38:39], v[28:29] op_sel_hi:[0,1]
	v_pk_mul_f32 v[62:63], v[38:39], v[12:13] op_sel_hi:[0,1]
	v_pk_mul_f32 v[38:39], v[38:39], v[14:15] op_sel_hi:[0,1]
	ds_read_b128 v[12:15], v89 offset:12288
	ds_read_b128 v[28:31], v89 offset:12304
	v_pk_fma_f32 v[82:83], v[70:71], v[10:11], v[82:83]
	v_pk_fma_f32 v[110:111], v[70:71], v[56:57], v[114:115]
	v_pk_fma_f32 v[42:43], v[70:71], v[64:65], v[42:43]
	v_pk_fma_f32 v[32:33], v[58:59], v[24:25], v[32:33]
	v_lshlrev_b32_e32 v24, 16, v0
	v_and_b32_e32 v25, 0xffff0000, v0
	v_lshlrev_b32_e32 v0, 16, v1
	v_and_b32_e32 v1, 0xffff0000, v1
	v_pk_fma_f32 v[72:73], v[68:69], v[16:17], v[112:113]
	v_pk_fma_f32 v[80:81], v[68:69], v[4:5], v[80:81]
	s_waitcnt lgkmcnt(0)
	v_pk_fma_f32 v[68:69], v[38:39], v[30:31], v[76:77]
	v_pk_fma_f32 v[70:71], v[62:63], v[28:29], v[74:75]
	v_pk_fma_f32 v[74:75], v[60:61], v[18:19], v[78:79]
	v_pk_fma_f32 v[76:77], v[62:63], v[20:21], v[84:85]
	v_pk_fma_f32 v[78:79], v[38:39], v[22:23], v[82:83]
	v_pk_fma_f32 v[84:85], v[38:39], v[10:11], v[110:111]
	v_pk_fma_f32 v[40:41], v[62:63], v[54:55], v[40:41]
	v_pk_fma_f32 v[38:39], v[38:39], v[56:57], v[42:43]
	v_pk_mul_f32 v[42:43], v[36:37], v[0:1] op_sel_hi:[0,1]
	v_pk_mul_f32 v[54:55], v[36:37], v[24:25] op_sel_hi:[0,1]
	v_lshlrev_b32_e32 v0, 16, v2
	v_and_b32_e32 v1, 0xffff0000, v2
	v_lshlrev_b32_e32 v2, 16, v3
	v_and_b32_e32 v3, 0xffff0000, v3
	v_pk_fma_f32 v[82:83], v[58:59], v[4:5], v[104:105]
	v_pk_fma_f32 v[34:35], v[60:61], v[26:27], v[34:35]
	v_pk_mul_f32 v[56:57], v[36:37], v[2:3] op_sel_hi:[0,1]
	v_pk_mul_f32 v[36:37], v[36:37], v[0:1] op_sel_hi:[0,1]
	ds_read_b128 v[0:3], v89 offset:14336
	ds_read_b128 v[24:27], v89 offset:14352
	v_pk_fma_f32 v[112:113], v[54:55], v[4:5], v[32:33]
	v_subrev_co_u32_e32 v4, vcc, 7, v102
	v_min_i32_e32 v5, v4, v101
	s_nop 0
	v_cndmask_b32_e64 v5, v5, 0, vcc
	v_cmp_lt_u32_e32 vcc, v4, v100
	v_add_u32_e32 v4, v5, v53
	v_ashrrev_i32_e32 v5, 31, v4
	v_pk_fma_f32 v[104:105], v[62:63], v[8:9], v[108:109]
	s_waitcnt lgkmcnt(0)
	v_pk_fma_f32 v[108:109], v[56:57], v[26:27], v[68:69]
	v_pk_fma_f32 v[116:117], v[36:37], v[8:9], v[40:41]
	v_cndmask_b32_e64 v68, 0, 1.0, vcc
	v_lshlrev_b64 v[4:5], 10, v[4:5]
	v_subrev_co_u32_e32 v8, vcc, 6, v102
	v_lshl_add_u64 v[4:5], v[46:47], 0, v[4:5]
	v_min_i32_e32 v9, v8, v101
	v_pk_fma_f32 v[64:65], v[60:61], v[14:15], v[66:67]
	v_pk_fma_f32 v[66:67], v[58:59], v[12:13], v[72:73]
	v_pk_fma_f32 v[72:73], v[58:59], v[16:17], v[80:81]
	v_pk_fma_f32 v[80:81], v[60:61], v[6:7], v[106:107]
	v_pk_fma_f32 v[110:111], v[42:43], v[6:7], v[34:35]
	global_load_dwordx4 v[4:7], v[4:5], off
	v_cndmask_b32_e64 v9, v9, 0, vcc
	v_cmp_lt_u32_e32 vcc, v8, v100
	v_add_u32_e32 v8, v9, v53
	v_ashrrev_i32_e32 v9, 31, v8
	v_lshlrev_b64 v[8:9], 10, v[8:9]
	v_cndmask_b32_e64 v86, 0, 1.0, vcc
	v_lshl_add_u64 v[8:9], v[46:47], 0, v[8:9]
	v_subrev_co_u32_e32 v32, vcc, 5, v102
	v_pk_fma_f32 v[114:115], v[56:57], v[10:11], v[38:39]
	global_load_dwordx4 v[8:11], v[8:9], off
	v_min_i32_e32 v33, v32, v101
	v_cndmask_b32_e64 v33, v33, 0, vcc
	v_cmp_lt_u32_e32 vcc, v32, v100
	v_add_u32_e32 v32, v33, v53
	v_ashrrev_i32_e32 v33, 31, v32
	v_pk_fma_f32 v[70:71], v[36:37], v[24:25], v[70:71]
	v_pk_fma_f32 v[76:77], v[36:37], v[28:29], v[76:77]
	v_pk_fma_f32 v[104:105], v[36:37], v[20:21], v[104:105]
	v_lshlrev_b64 v[32:33], 10, v[32:33]
	v_add_u32_e32 v36, -4, v102
	v_cndmask_b32_e64 v88, 0, 1.0, vcc
	v_lshl_add_u64 v[32:33], v[46:47], 0, v[32:33]
	v_subrev_co_u32_e32 v58, vcc, 1, v102
	v_min_i32_e32 v37, v36, v101
	global_load_dwordx4 v[32:35], v[32:33], off
	v_cndmask_b32_e64 v37, v37, 0, vcc
	v_cmp_lt_u32_e64 s[8:9], v36, v100
	v_add_u32_e32 v36, v37, v53
	v_ashrrev_i32_e32 v37, 31, v36
	v_lshlrev_b64 v[36:37], 10, v[36:37]
	v_lshl_add_u64 v[36:37], v[46:47], 0, v[36:37]
	global_load_dwordx4 v[36:39], v[36:37], off
	v_add_u32_e32 v40, -3, v102
	v_min_i32_e32 v41, v40, v101
	v_cndmask_b32_e64 v41, v41, 0, vcc
	v_cndmask_b32_e64 v90, 0, 1.0, s[8:9]
	v_cmp_lt_u32_e64 s[8:9], v40, v100
	v_add_u32_e32 v40, v41, v53
	v_pk_fma_f32 v[66:67], v[54:55], v[0:1], v[66:67]
	v_pk_fma_f32 v[72:73], v[54:55], v[12:13], v[72:73]
	v_pk_fma_f32 v[82:83], v[54:55], v[16:17], v[82:83]
	v_ashrrev_i32_e32 v41, 31, v40
	v_add_u32_e32 v54, -2, v102
	v_lshlrev_b64 v[40:41], 10, v[40:41]
	v_min_i32_e32 v55, v54, v101
	v_lshl_add_u64 v[40:41], v[46:47], 0, v[40:41]
	v_cndmask_b32_e64 v55, v55, 0, vcc
	v_pk_fma_f32 v[106:107], v[42:43], v[2:3], v[64:65]
	v_pk_fma_f32 v[74:75], v[42:43], v[14:15], v[74:75]
	v_pk_fma_f32 v[80:81], v[42:43], v[18:19], v[80:81]
	v_cndmask_b32_e64 v92, 0, 1.0, s[8:9]
	global_load_dwordx4 v[40:43], v[40:41], off
	v_cmp_lt_u32_e64 s[8:9], v54, v100
	v_add_u32_e32 v54, v55, v53
	v_ashrrev_i32_e32 v55, 31, v54
	v_lshlrev_b64 v[54:55], 10, v[54:55]
	v_lshl_add_u64 v[54:55], v[46:47], 0, v[54:55]
	v_min_i32_e32 v59, v58, v101
	v_pk_fma_f32 v[78:79], v[56:57], v[30:31], v[78:79]
	v_pk_fma_f32 v[84:85], v[56:57], v[22:23], v[84:85]
	global_load_dwordx4 v[54:57], v[54:55], off
	v_cndmask_b32_e64 v59, v59, 0, vcc
	v_cmp_lt_u32_e32 vcc, v58, v100
	v_add_u32_e32 v58, v59, v53
	v_ashrrev_i32_e32 v59, 31, v58
	v_lshlrev_b64 v[58:59], 10, v[58:59]
	v_lshl_add_u64 v[58:59], v[46:47], 0, v[58:59]
	global_load_dwordx4 v[58:61], v[58:59], off
	v_min_u32_e32 v62, v102, v101
	v_add_u32_e32 v62, v62, v53
	v_ashrrev_i32_e32 v63, 31, v62
	v_lshlrev_b64 v[62:63], 10, v[62:63]
	v_lshl_add_u64 v[62:63], v[46:47], 0, v[62:63]
	global_load_dwordx4 v[62:65], v[62:63], off
	v_cndmask_b32_e64 v94, 0, 1.0, s[8:9]
	v_cndmask_b32_e64 v96, 0, 1.0, vcc
	v_cmp_lt_u32_e32 vcc, v102, v100
	s_waitcnt vmcnt(0) lgkmcnt(0)
	v_lshlrev_b32_e32 v120, 16, v4
	v_and_b32_e32 v121, 0xffff0000, v4
	v_lshlrev_b32_e32 v4, 16, v5
	v_and_b32_e32 v5, 0xffff0000, v5
	v_pk_mul_f32 v[122:123], v[68:69], v[4:5] op_sel_hi:[0,1]
	v_lshlrev_b32_e32 v4, 16, v6
	v_and_b32_e32 v5, 0xffff0000, v6
	v_lshlrev_b32_e32 v6, 16, v7
	v_and_b32_e32 v7, 0xffff0000, v7
	v_pk_mul_f32 v[124:125], v[68:69], v[4:5] op_sel_hi:[0,1]
	v_pk_mul_f32 v[126:127], v[68:69], v[6:7] op_sel_hi:[0,1]
	ds_read_b128 v[4:7], v89 offset:16384
	v_pk_mul_f32 v[120:121], v[68:69], v[120:121] op_sel_hi:[0,1]
	v_pk_fma_f32 v[112:113], v[16:17], v[120:121], v[112:113]
	v_lshlrev_b32_e32 v16, 16, v8
	v_and_b32_e32 v17, 0xffff0000, v8
	v_lshlrev_b32_e32 v8, 16, v9
	v_and_b32_e32 v9, 0xffff0000, v9
	v_pk_fma_f32 v[22:23], v[22:23], v[126:127], v[114:115]
	v_pk_mul_f32 v[114:115], v[86:87], v[8:9] op_sel_hi:[0,1]
	v_lshlrev_b32_e32 v8, 16, v10
	v_and_b32_e32 v9, 0xffff0000, v10
	v_lshlrev_b32_e32 v10, 16, v11
	v_and_b32_e32 v11, 0xffff0000, v11
	v_pk_fma_f32 v[72:73], v[0:1], v[120:121], v[72:73]
	v_pk_fma_f32 v[74:75], v[2:3], v[122:123], v[74:75]
	v_pk_fma_f32 v[80:81], v[14:15], v[122:123], v[80:81]
	v_pk_fma_f32 v[82:83], v[12:13], v[120:121], v[82:83]
	v_pk_fma_f32 v[110:111], v[18:19], v[122:123], v[110:111]
	v_pk_fma_f32 v[20:21], v[20:21], v[124:125], v[116:117]
	v_pk_mul_f32 v[116:117], v[86:87], v[16:17] op_sel_hi:[0,1]
	ds_read_b128 v[16:19], v89 offset:18448
	s_waitcnt lgkmcnt(1)
	v_pk_fma_f32 v[106:107], v[122:123], v[6:7], v[106:107]
	v_pk_fma_f32 v[128:129], v[120:121], v[4:5], v[66:67]
	ds_read_b128 v[66:69], v89 offset:16400
	v_pk_mul_f32 v[120:121], v[86:87], v[10:11] op_sel_hi:[0,1]
	v_pk_mul_f32 v[122:123], v[86:87], v[8:9] op_sel_hi:[0,1]
	ds_read_b128 v[8:11], v89 offset:18432
	v_pk_fma_f32 v[14:15], v[14:15], v[114:115], v[110:111]
	v_pk_fma_f32 v[12:13], v[12:13], v[116:117], v[112:113]
	v_pk_fma_f32 v[110:111], v[30:31], v[120:121], v[22:23]
	v_pk_fma_f32 v[112:113], v[28:29], v[122:123], v[20:21]
	v_lshlrev_b32_e32 v20, 16, v32
	v_and_b32_e32 v21, 0xffff0000, v32
	v_lshlrev_b32_e32 v22, 16, v33
	v_and_b32_e32 v23, 0xffff0000, v33
	s_waitcnt lgkmcnt(0)
	v_pk_fma_f32 v[106:107], v[114:115], v[10:11], v[106:107]
	v_pk_fma_f32 v[74:75], v[6:7], v[114:115], v[74:75]
	v_pk_fma_f32 v[80:81], v[2:3], v[114:115], v[80:81]
	v_pk_mul_f32 v[32:33], v[88:89], v[20:21] op_sel_hi:[0,1]
	v_pk_mul_f32 v[114:115], v[88:89], v[22:23] op_sel_hi:[0,1]
	v_lshlrev_b32_e32 v20, 16, v34
	v_and_b32_e32 v21, 0xffff0000, v34
	v_lshlrev_b32_e32 v22, 16, v35
	v_and_b32_e32 v23, 0xffff0000, v35
	v_pk_fma_f32 v[70:71], v[124:125], v[66:67], v[70:71]
	v_pk_fma_f32 v[76:77], v[24:25], v[124:125], v[76:77]
	v_pk_fma_f32 v[84:85], v[30:31], v[126:127], v[84:85]
	v_pk_fma_f32 v[104:105], v[28:29], v[124:125], v[104:105]
	v_pk_fma_f32 v[124:125], v[116:117], v[8:9], v[128:129]
	v_pk_fma_f32 v[72:73], v[4:5], v[116:117], v[72:73]
	v_pk_fma_f32 v[82:83], v[0:1], v[116:117], v[82:83]
	v_pk_mul_f32 v[34:35], v[88:89], v[20:21] op_sel_hi:[0,1]
	v_pk_mul_f32 v[116:117], v[88:89], v[22:23] op_sel_hi:[0,1]
	ds_read_b128 v[20:23], v89 offset:20480
	ds_read_b128 v[28:31], v89 offset:20496
	v_pk_fma_f32 v[78:79], v[26:27], v[126:127], v[78:79]
	v_pk_fma_f32 v[104:105], v[24:25], v[122:123], v[104:105]
	v_pk_fma_f32 v[84:85], v[26:27], v[120:121], v[84:85]
	v_pk_fma_f32 v[0:1], v[0:1], v[32:33], v[12:13]
	v_pk_fma_f32 v[2:3], v[2:3], v[114:115], v[14:15]
	v_pk_fma_f32 v[12:13], v[24:25], v[34:35], v[112:113]
	v_pk_fma_f32 v[14:15], v[26:27], v[116:117], v[110:111]
	v_lshlrev_b32_e32 v24, 16, v36
	v_and_b32_e32 v25, 0xffff0000, v36
	v_lshlrev_b32_e32 v26, 16, v37
	v_and_b32_e32 v27, 0xffff0000, v37
	v_pk_fma_f32 v[108:109], v[126:127], v[68:69], v[108:109]
	v_pk_fma_f32 v[70:71], v[122:123], v[16:17], v[70:71]
	v_pk_fma_f32 v[76:77], v[122:123], v[66:67], v[76:77]
	v_pk_mul_f32 v[36:37], v[90:91], v[26:27] op_sel_hi:[0,1]
	v_pk_mul_f32 v[110:111], v[90:91], v[24:25] op_sel_hi:[0,1]
	v_lshlrev_b32_e32 v24, 16, v38
	v_and_b32_e32 v25, 0xffff0000, v38
	v_lshlrev_b32_e32 v26, 16, v39
	v_and_b32_e32 v27, 0xffff0000, v39
	v_pk_fma_f32 v[108:109], v[120:121], v[18:19], v[108:109]
	v_pk_fma_f32 v[78:79], v[120:121], v[68:69], v[78:79]
	s_waitcnt lgkmcnt(1)
	v_pk_fma_f32 v[120:121], v[32:33], v[20:21], v[124:125]
	s_waitcnt lgkmcnt(0)
	v_pk_fma_f32 v[70:71], v[34:35], v[28:29], v[70:71]
	v_pk_fma_f32 v[72:73], v[32:33], v[8:9], v[72:73]
	v_pk_fma_f32 v[76:77], v[34:35], v[16:17], v[76:77]
	v_pk_fma_f32 v[82:83], v[4:5], v[32:33], v[82:83]
	v_pk_fma_f32 v[104:105], v[66:67], v[34:35], v[104:105]
	v_pk_mul_f32 v[38:39], v[90:91], v[26:27] op_sel_hi:[0,1]
	v_pk_mul_f32 v[112:113], v[90:91], v[24:25] op_sel_hi:[0,1]
	ds_read_b128 v[24:27], v89 offset:22528
	ds_read_b128 v[32:35], v89 offset:22544
	v_pk_fma_f32 v[106:107], v[114:115], v[22:23], v[106:107]
	v_pk_fma_f32 v[108:109], v[116:117], v[30:31], v[108:109]
	v_pk_fma_f32 v[74:75], v[114:115], v[10:11], v[74:75]
	v_pk_fma_f32 v[78:79], v[116:117], v[18:19], v[78:79]
	v_pk_fma_f32 v[80:81], v[6:7], v[114:115], v[80:81]
	v_pk_fma_f32 v[84:85], v[68:69], v[116:117], v[84:85]
	s_waitcnt lgkmcnt(1)
	v_pk_fma_f32 v[106:107], v[36:37], v[26:27], v[106:107]
	s_waitcnt lgkmcnt(0)
	v_pk_fma_f32 v[108:109], v[38:39], v[34:35], v[108:109]
	v_pk_fma_f32 v[74:75], v[36:37], v[22:23], v[74:75]
	v_pk_fma_f32 v[78:79], v[38:39], v[30:31], v[78:79]
	v_pk_fma_f32 v[80:81], v[10:11], v[36:37], v[80:81]
	v_pk_fma_f32 v[84:85], v[38:39], v[18:19], v[84:85]
	v_pk_fma_f32 v[2:3], v[6:7], v[36:37], v[2:3]
	v_pk_fma_f32 v[0:1], v[4:5], v[110:111], v[0:1]
	v_pk_fma_f32 v[4:5], v[68:69], v[38:39], v[14:15]
	v_lshlrev_b32_e32 v36, 16, v42
	v_and_b32_e32 v37, 0xffff0000, v42
	v_lshlrev_b32_e32 v38, 16, v43
	v_and_b32_e32 v39, 0xffff0000, v43
	v_pk_fma_f32 v[6:7], v[66:67], v[112:113], v[12:13]
	v_pk_mul_f32 v[66:67], v[92:93], v[36:37] op_sel_hi:[0,1]
	v_pk_mul_f32 v[68:69], v[92:93], v[38:39] op_sel_hi:[0,1]
	ds_read_b128 v[36:39], v89 offset:24576
	v_lshlrev_b32_e32 v12, 16, v40
	v_and_b32_e32 v13, 0xffff0000, v40
	v_lshlrev_b32_e32 v14, 16, v41
	v_and_b32_e32 v15, 0xffff0000, v41
	v_pk_mul_f32 v[12:13], v[92:93], v[12:13] op_sel_hi:[0,1]
	v_pk_mul_f32 v[14:15], v[92:93], v[14:15] op_sel_hi:[0,1]
	v_pk_fma_f32 v[82:83], v[8:9], v[110:111], v[82:83]
	v_pk_fma_f32 v[8:9], v[8:9], v[12:13], v[0:1]
	v_pk_fma_f32 v[10:11], v[10:11], v[14:15], v[2:3]
	v_lshlrev_b32_e32 v0, 16, v54
	v_and_b32_e32 v1, 0xffff0000, v54
	v_lshlrev_b32_e32 v2, 16, v55
	v_and_b32_e32 v3, 0xffff0000, v55
	v_pk_fma_f32 v[114:115], v[110:111], v[24:25], v[120:121]
	v_pk_fma_f32 v[72:73], v[110:111], v[20:21], v[72:73]
	v_pk_fma_f32 v[104:105], v[112:113], v[16:17], v[104:105]
	ds_read_b128 v[40:43], v89 offset:24592
	v_pk_fma_f32 v[6:7], v[16:17], v[66:67], v[6:7]
	v_pk_fma_f32 v[4:5], v[18:19], v[68:69], v[4:5]
	v_pk_mul_f32 v[16:17], v[94:95], v[2:3] op_sel_hi:[0,1]
	v_pk_mul_f32 v[18:19], v[94:95], v[0:1] op_sel_hi:[0,1]
	v_lshlrev_b32_e32 v0, 16, v56
	v_and_b32_e32 v1, 0xffff0000, v56
	v_lshlrev_b32_e32 v2, 16, v57
	v_and_b32_e32 v3, 0xffff0000, v57
	s_waitcnt lgkmcnt(1)
	v_pk_fma_f32 v[106:107], v[14:15], v[38:39], v[106:107]
	v_pk_fma_f32 v[110:111], v[12:13], v[36:37], v[114:115]
	v_pk_fma_f32 v[72:73], v[12:13], v[24:25], v[72:73]
	v_pk_fma_f32 v[74:75], v[14:15], v[26:27], v[74:75]
	v_pk_fma_f32 v[80:81], v[14:15], v[22:23], v[80:81]
	v_pk_fma_f32 v[82:83], v[12:13], v[20:21], v[82:83]
	v_pk_mul_f32 v[54:55], v[94:95], v[2:3] op_sel_hi:[0,1]
	v_pk_mul_f32 v[56:57], v[94:95], v[0:1] op_sel_hi:[0,1]
	ds_read_b128 v[0:3], v89 offset:26624
	ds_read_b128 v[12:15], v89 offset:26640
	v_pk_fma_f32 v[70:71], v[112:113], v[32:33], v[70:71]
	v_pk_fma_f32 v[76:77], v[112:113], v[28:29], v[76:77]
	v_pk_fma_f32 v[10:11], v[22:23], v[16:17], v[10:11]
	v_pk_fma_f32 v[8:9], v[20:21], v[18:19], v[8:9]
	v_pk_fma_f32 v[20:21], v[54:55], v[30:31], v[4:5]
	v_pk_fma_f32 v[22:23], v[56:57], v[28:29], v[6:7]
	v_lshlrev_b32_e32 v4, 16, v58
	v_and_b32_e32 v5, 0xffff0000, v58
	v_lshlrev_b32_e32 v6, 16, v59
	v_and_b32_e32 v7, 0xffff0000, v59
	s_waitcnt lgkmcnt(2)
	v_pk_fma_f32 v[108:109], v[68:69], v[42:43], v[108:109]
	v_pk_fma_f32 v[70:71], v[66:67], v[40:41], v[70:71]
	v_pk_fma_f32 v[76:77], v[66:67], v[32:33], v[76:77]
	v_pk_fma_f32 v[78:79], v[68:69], v[34:35], v[78:79]
	v_pk_fma_f32 v[84:85], v[68:69], v[30:31], v[84:85]
	v_pk_fma_f32 v[104:105], v[66:67], v[28:29], v[104:105]
	v_pk_mul_f32 v[28:29], v[96:97], v[4:5] op_sel_hi:[0,1]
	v_pk_mul_f32 v[30:31], v[96:97], v[6:7] op_sel_hi:[0,1]
	v_lshlrev_b32_e32 v4, 16, v60
	v_and_b32_e32 v5, 0xffff0000, v60
	v_lshlrev_b32_e32 v6, 16, v61
	v_and_b32_e32 v7, 0xffff0000, v61
	s_waitcnt lgkmcnt(1)
	v_pk_fma_f32 v[68:69], v[16:17], v[2:3], v[106:107]
	s_waitcnt lgkmcnt(0)
	v_pk_fma_f32 v[70:71], v[56:57], v[12:13], v[70:71]
	v_pk_fma_f32 v[106:107], v[54:55], v[14:15], v[108:109]
	v_pk_fma_f32 v[78:79], v[54:55], v[42:43], v[78:79]
	v_pk_fma_f32 v[76:77], v[56:57], v[40:41], v[76:77]
	v_pk_fma_f32 v[104:105], v[56:57], v[32:33], v[104:105]
	v_pk_fma_f32 v[84:85], v[54:55], v[34:35], v[84:85]
	v_pk_mul_f32 v[54:55], v[96:97], v[4:5] op_sel_hi:[0,1]
	v_pk_mul_f32 v[56:57], v[96:97], v[6:7] op_sel_hi:[0,1]
	ds_read_b128 v[4:7], v89 offset:28672
	v_pk_fma_f32 v[66:67], v[18:19], v[0:1], v[110:111]
	v_pk_fma_f32 v[74:75], v[16:17], v[38:39], v[74:75]
	v_pk_fma_f32 v[72:73], v[18:19], v[36:37], v[72:73]
	v_pk_fma_f32 v[82:83], v[18:19], v[24:25], v[82:83]
	v_pk_fma_f32 v[80:81], v[16:17], v[26:27], v[80:81]
	ds_read_b128 v[16:19], v89 offset:28688
	v_cndmask_b32_e64 v118, 0, 1.0, vcc
	v_pk_fma_f32 v[24:25], v[28:29], v[24:25], v[8:9]
	v_lshlrev_b32_e32 v8, 16, v62
	v_and_b32_e32 v9, 0xffff0000, v62
	s_waitcnt lgkmcnt(1)
	v_pk_fma_f32 v[58:59], v[30:31], v[6:7], v[68:69]
	v_pk_fma_f32 v[74:75], v[30:31], v[2:3], v[74:75]
	v_pk_fma_f32 v[80:81], v[30:31], v[38:39], v[80:81]
	v_pk_fma_f32 v[82:83], v[28:29], v[36:37], v[82:83]
	v_pk_fma_f32 v[26:27], v[30:31], v[26:27], v[10:11]
	v_pk_fma_f32 v[30:31], v[56:57], v[34:35], v[20:21]
	v_lshlrev_b32_e32 v10, 16, v63
	v_and_b32_e32 v11, 0xffff0000, v63
	v_pk_mul_f32 v[34:35], v[118:119], v[8:9] op_sel_hi:[0,1]
	v_pk_fma_f32 v[60:61], v[28:29], v[4:5], v[66:67]
	s_waitcnt lgkmcnt(0)
	v_pk_fma_f32 v[66:67], v[56:57], v[18:19], v[106:107]
	v_pk_fma_f32 v[106:107], v[28:29], v[0:1], v[72:73]
	v_pk_fma_f32 v[28:29], v[54:55], v[32:33], v[22:23]
	v_pk_mul_f32 v[32:33], v[118:119], v[10:11] op_sel_hi:[0,1]
	v_lshlrev_b32_e32 v8, 16, v64
	v_and_b32_e32 v9, 0xffff0000, v64
	v_lshlrev_b32_e32 v10, 16, v65
	v_and_b32_e32 v11, 0xffff0000, v65
	v_pk_fma_f32 v[62:63], v[34:35], v[0:1], v[82:83]
	v_pk_fma_f32 v[82:83], v[34:35], v[36:37], v[24:25]
	v_or_b32_e32 v24, 1, v102
	v_pk_mul_f32 v[108:109], v[118:119], v[10:11] op_sel_hi:[0,1]
	v_pk_mul_f32 v[110:111], v[118:119], v[8:9] op_sel_hi:[0,1]
	ds_read_b128 v[8:11], v89 offset:30720
	ds_read_b128 v[20:23], v89 offset:30736
	v_min_u32_e32 v25, v24, v101
	v_cmp_lt_u32_e32 vcc, v24, v100
	v_add_u32_e32 v24, v25, v53
	v_ashrrev_i32_e32 v25, 31, v24
	v_lshlrev_b64 v[24:25], 10, v[24:25]
	v_pk_fma_f32 v[78:79], v[56:57], v[14:15], v[78:79]
	v_pk_fma_f32 v[84:85], v[56:57], v[42:43], v[84:85]
	v_lshl_add_u64 v[24:25], v[46:47], 0, v[24:25]
	v_pk_fma_f32 v[68:69], v[54:55], v[16:17], v[70:71]
	v_pk_fma_f32 v[76:77], v[54:55], v[12:13], v[76:77]
	v_pk_fma_f32 v[104:105], v[54:55], v[40:41], v[104:105]
	s_waitcnt lgkmcnt(1)
	v_pk_fma_f32 v[54:55], v[34:35], v[8:9], v[60:61]
	s_waitcnt lgkmcnt(0)
	v_pk_fma_f32 v[72:73], v[108:109], v[22:23], v[66:67]
	v_pk_fma_f32 v[60:61], v[108:109], v[18:19], v[78:79]
	v_pk_fma_f32 v[78:79], v[32:33], v[2:3], v[80:81]
	v_pk_fma_f32 v[80:81], v[108:109], v[14:15], v[84:85]
	v_pk_fma_f32 v[66:67], v[32:33], v[38:39], v[26:27]
	v_pk_fma_f32 v[84:85], v[110:111], v[40:41], v[28:29]
	global_load_dwordx4 v[24:27], v[24:25], off
	v_or_b32_e32 v28, 2, v102
	v_min_u32_e32 v29, v28, v101
	v_cndmask_b32_e64 v86, 0, 1.0, vcc
	v_cmp_lt_u32_e32 vcc, v28, v100
	v_add_u32_e32 v28, v29, v53
	v_ashrrev_i32_e32 v29, 31, v28
	v_lshlrev_b64 v[28:29], 10, v[28:29]
	v_lshl_add_u64 v[28:29], v[46:47], 0, v[28:29]
	v_pk_fma_f32 v[56:57], v[110:111], v[20:21], v[68:69]
	v_pk_fma_f32 v[68:69], v[108:109], v[42:43], v[30:31]
	global_load_dwordx4 v[28:31], v[28:29], off
	v_pk_fma_f32 v[70:71], v[32:33], v[10:11], v[58:59]
	v_pk_fma_f32 v[58:59], v[32:33], v[6:7], v[74:75]
	v_or_b32_e32 v32, 3, v102
	v_min_u32_e32 v33, v32, v101
	v_cndmask_b32_e64 v88, 0, 1.0, vcc
	v_cmp_lt_u32_e32 vcc, v32, v100
	v_add_u32_e32 v32, v33, v53
	v_ashrrev_i32_e32 v33, 31, v32
	v_lshlrev_b64 v[32:33], 10, v[32:33]
	v_lshl_add_u64 v[32:33], v[46:47], 0, v[32:33]
	v_pk_fma_f32 v[74:75], v[34:35], v[4:5], v[106:107]
	global_load_dwordx4 v[32:35], v[32:33], off
	v_add_u32_e32 v36, 4, v102
	v_min_u32_e32 v37, v36, v101
	v_cndmask_b32_e64 v90, 0, 1.0, vcc
	v_cmp_lt_u32_e32 vcc, v36, v100
	v_add_u32_e32 v36, v37, v53
	v_ashrrev_i32_e32 v37, 31, v36
	v_lshlrev_b64 v[36:37], 10, v[36:37]
	v_lshl_add_u64 v[36:37], v[46:47], 0, v[36:37]
	global_load_dwordx4 v[36:39], v[36:37], off
	v_add_u32_e32 v40, 5, v102
	v_min_u32_e32 v41, v40, v101
	v_cndmask_b32_e64 v92, 0, 1.0, vcc
	v_cmp_lt_u32_e32 vcc, v40, v100
	v_add_u32_e32 v40, v41, v53
	v_ashrrev_i32_e32 v41, 31, v40
	v_lshlrev_b64 v[40:41], 10, v[40:41]
	v_lshl_add_u64 v[40:41], v[46:47], 0, v[40:41]
	global_load_dwordx4 v[40:43], v[40:41], off
	v_add_u32_e32 v96, 6, v102
	v_min_u32_e32 v103, v96, v101
	v_pk_fma_f32 v[64:65], v[110:111], v[12:13], v[104:105]
	v_add_u32_e32 v104, v103, v53
	v_ashrrev_i32_e32 v105, 31, v104
	v_lshlrev_b64 v[104:105], 10, v[104:105]
	v_lshl_add_u64 v[104:105], v[46:47], 0, v[104:105]
	global_load_dwordx4 v[104:107], v[104:105], off
	v_add_u32_e32 v103, 7, v102
	v_min_u32_e32 v108, v103, v101
	v_add_u32_e32 v108, v108, v53
	v_ashrrev_i32_e32 v109, 31, v108
	v_lshlrev_b64 v[108:109], 10, v[108:109]
	v_cndmask_b32_e64 v94, 0, 1.0, vcc
	v_cmp_lt_u32_e32 vcc, v96, v100
	v_lshl_add_u64 v[108:109], v[46:47], 0, v[108:109]
	v_pk_fma_f32 v[76:77], v[110:111], v[16:17], v[76:77]
	v_cndmask_b32_e64 v96, 0, 1.0, vcc
	v_cmp_lt_u32_e32 vcc, v103, v100
	global_load_dwordx4 v[108:111], v[108:109], off
	v_add_u32_e32 v103, 8, v102
	v_min_u32_e32 v112, v103, v101
	v_add_u32_e32 v112, v112, v53
	v_ashrrev_i32_e32 v113, 31, v112
	v_lshlrev_b64 v[112:113], 10, v[112:113]
	v_lshl_add_u64 v[112:113], v[46:47], 0, v[112:113]
	global_load_dwordx4 v[112:115], v[112:113], off
	v_cndmask_b32_e64 v120, 0, 1.0, vcc
	v_cmp_lt_u32_e32 vcc, v103, v100
	s_waitcnt vmcnt(0) lgkmcnt(0)
	v_lshlrev_b32_e32 v116, 16, v24
	v_and_b32_e32 v117, 0xffff0000, v24
	v_lshlrev_b32_e32 v24, 16, v25
	v_and_b32_e32 v25, 0xffff0000, v25
	v_pk_mul_f32 v[126:127], v[86:87], v[24:25] op_sel_hi:[0,1]
	v_lshlrev_b32_e32 v24, 16, v26
	v_and_b32_e32 v25, 0xffff0000, v26
	v_lshlrev_b32_e32 v26, 16, v27
	v_and_b32_e32 v27, 0xffff0000, v27
	v_pk_mul_f32 v[128:129], v[86:87], v[24:25] op_sel_hi:[0,1]
	v_pk_mul_f32 v[130:131], v[86:87], v[26:27] op_sel_hi:[0,1]
	ds_read_b128 v[24:27], v89 offset:32768
	v_pk_mul_f32 v[124:125], v[86:87], v[116:117] op_sel_hi:[0,1]
	v_pk_fma_f32 v[82:83], v[0:1], v[124:125], v[82:83]
	v_pk_fma_f32 v[66:67], v[2:3], v[126:127], v[66:67]
	v_lshlrev_b32_e32 v0, 16, v28
	v_and_b32_e32 v1, 0xffff0000, v28
	v_lshlrev_b32_e32 v2, 16, v29
	v_and_b32_e32 v3, 0xffff0000, v29
	ds_read_b128 v[116:119], v89 offset:32784
	s_waitcnt lgkmcnt(1)
	v_pk_fma_f32 v[54:55], v[124:125], v[24:25], v[54:55]
	v_pk_fma_f32 v[74:75], v[8:9], v[124:125], v[74:75]
	v_pk_fma_f32 v[62:63], v[4:5], v[124:125], v[62:63]
	v_pk_mul_f32 v[28:29], v[88:89], v[2:3] op_sel_hi:[0,1]
	v_pk_mul_f32 v[124:125], v[88:89], v[0:1] op_sel_hi:[0,1]
	v_lshlrev_b32_e32 v0, 16, v30
	v_and_b32_e32 v1, 0xffff0000, v30
	v_lshlrev_b32_e32 v2, 16, v31
	v_and_b32_e32 v3, 0xffff0000, v31
	v_pk_fma_f32 v[70:71], v[126:127], v[26:27], v[70:71]
	v_pk_fma_f32 v[58:59], v[10:11], v[126:127], v[58:59]
	v_pk_fma_f32 v[78:79], v[6:7], v[126:127], v[78:79]
	v_pk_mul_f32 v[30:31], v[88:89], v[2:3] op_sel_hi:[0,1]
	v_pk_mul_f32 v[126:127], v[88:89], v[0:1] op_sel_hi:[0,1]
	ds_read_b128 v[0:3], v89 offset:34816
	v_pk_fma_f32 v[84:85], v[12:13], v[128:129], v[84:85]
	v_pk_fma_f32 v[68:69], v[14:15], v[130:131], v[68:69]
	ds_read_b128 v[12:15], v89 offset:34832
	v_pk_fma_f32 v[58:59], v[26:27], v[28:29], v[58:59]
	s_waitcnt lgkmcnt(1)
	v_pk_fma_f32 v[70:71], v[28:29], v[2:3], v[70:71]
	v_pk_fma_f32 v[78:79], v[10:11], v[28:29], v[78:79]
	v_pk_fma_f32 v[28:29], v[6:7], v[28:29], v[66:67]
	v_pk_fma_f32 v[66:67], v[4:5], v[124:125], v[82:83]
	v_lshlrev_b32_e32 v4, 16, v32
	v_and_b32_e32 v5, 0xffff0000, v32
	v_lshlrev_b32_e32 v6, 16, v33
	v_and_b32_e32 v7, 0xffff0000, v33
	v_pk_fma_f32 v[72:73], v[130:131], v[118:119], v[72:73]
	v_pk_fma_f32 v[60:61], v[22:23], v[130:131], v[60:61]
	v_pk_fma_f32 v[80:81], v[18:19], v[130:131], v[80:81]
	v_pk_mul_f32 v[32:33], v[90:91], v[4:5] op_sel_hi:[0,1]
	v_pk_mul_f32 v[82:83], v[90:91], v[6:7] op_sel_hi:[0,1]
	v_lshlrev_b32_e32 v4, 16, v34
	v_and_b32_e32 v5, 0xffff0000, v34
	v_lshlrev_b32_e32 v6, 16, v35
	v_and_b32_e32 v7, 0xffff0000, v35
	s_waitcnt lgkmcnt(0)
	v_pk_fma_f32 v[72:73], v[30:31], v[14:15], v[72:73]
	v_pk_fma_f32 v[60:61], v[30:31], v[118:119], v[60:61]
	v_pk_fma_f32 v[80:81], v[22:23], v[30:31], v[80:81]
	v_pk_fma_f32 v[30:31], v[18:19], v[30:31], v[68:69]
	v_pk_fma_f32 v[68:69], v[16:17], v[126:127], v[84:85]
	v_pk_mul_f32 v[34:35], v[90:91], v[4:5] op_sel_hi:[0,1]
	v_pk_mul_f32 v[84:85], v[90:91], v[6:7] op_sel_hi:[0,1]
	ds_read_b128 v[4:7], v89 offset:36864
	v_pk_fma_f32 v[64:65], v[16:17], v[128:129], v[64:65]
	ds_read_b128 v[16:19], v89 offset:36880
	v_pk_fma_f32 v[54:55], v[124:125], v[0:1], v[54:55]
	v_pk_fma_f32 v[74:75], v[24:25], v[124:125], v[74:75]
	v_pk_fma_f32 v[62:63], v[8:9], v[124:125], v[62:63]
	v_pk_fma_f32 v[56:57], v[128:129], v[116:117], v[56:57]
	v_pk_fma_f32 v[76:77], v[20:21], v[128:129], v[76:77]
	s_waitcnt lgkmcnt(1)
	v_pk_fma_f32 v[54:55], v[32:33], v[4:5], v[54:55]
	v_pk_fma_f32 v[74:75], v[32:33], v[0:1], v[74:75]
	v_pk_fma_f32 v[62:63], v[24:25], v[32:33], v[62:63]
	v_pk_fma_f32 v[32:33], v[8:9], v[32:33], v[66:67]
	v_pk_fma_f32 v[28:29], v[10:11], v[82:83], v[28:29]
	v_lshlrev_b32_e32 v8, 16, v36
	v_and_b32_e32 v9, 0xffff0000, v36
	v_lshlrev_b32_e32 v10, 16, v37
	v_and_b32_e32 v11, 0xffff0000, v37
	v_pk_fma_f32 v[56:57], v[126:127], v[12:13], v[56:57]
	v_pk_fma_f32 v[76:77], v[126:127], v[116:117], v[76:77]
	v_pk_fma_f32 v[64:65], v[20:21], v[126:127], v[64:65]
	v_pk_mul_f32 v[36:37], v[92:93], v[10:11] op_sel_hi:[0,1]
	v_pk_mul_f32 v[66:67], v[92:93], v[8:9] op_sel_hi:[0,1]
	v_lshlrev_b32_e32 v8, 16, v38
	v_and_b32_e32 v9, 0xffff0000, v38
	v_lshlrev_b32_e32 v10, 16, v39
	v_and_b32_e32 v11, 0xffff0000, v39
	s_waitcnt lgkmcnt(0)
	v_pk_fma_f32 v[56:57], v[34:35], v[16:17], v[56:57]
	v_pk_fma_f32 v[76:77], v[34:35], v[12:13], v[76:77]
	v_pk_fma_f32 v[64:65], v[116:117], v[34:35], v[64:65]
	v_pk_fma_f32 v[34:35], v[20:21], v[34:35], v[68:69]
	v_pk_mul_f32 v[38:39], v[92:93], v[10:11] op_sel_hi:[0,1]
	v_pk_mul_f32 v[68:69], v[92:93], v[8:9] op_sel_hi:[0,1]
	ds_read_b128 v[8:11], v89 offset:38912
	v_pk_fma_f32 v[30:31], v[22:23], v[84:85], v[30:31]
	ds_read_b128 v[20:23], v89 offset:38928
	v_pk_fma_f32 v[70:71], v[82:83], v[6:7], v[70:71]
	v_pk_fma_f32 v[58:59], v[82:83], v[2:3], v[58:59]
	v_pk_fma_f32 v[78:79], v[26:27], v[82:83], v[78:79]
	s_waitcnt lgkmcnt(1)
	v_pk_fma_f32 v[70:71], v[36:37], v[10:11], v[70:71]
	v_pk_fma_f32 v[58:59], v[36:37], v[6:7], v[58:59]
	v_pk_fma_f32 v[78:79], v[2:3], v[36:37], v[78:79]
	v_pk_fma_f32 v[36:37], v[26:27], v[36:37], v[28:29]
	v_pk_fma_f32 v[32:33], v[24:25], v[66:67], v[32:33]
	v_lshlrev_b32_e32 v24, 16, v40
	v_and_b32_e32 v25, 0xffff0000, v40
	v_lshlrev_b32_e32 v26, 16, v41
	v_and_b32_e32 v27, 0xffff0000, v41
	v_pk_fma_f32 v[72:73], v[84:85], v[18:19], v[72:73]
	v_pk_fma_f32 v[60:61], v[84:85], v[14:15], v[60:61]
	v_pk_fma_f32 v[80:81], v[118:119], v[84:85], v[80:81]
	v_pk_fma_f32 v[54:55], v[66:67], v[8:9], v[54:55]
	v_pk_fma_f32 v[74:75], v[66:67], v[4:5], v[74:75]
	v_pk_fma_f32 v[62:63], v[0:1], v[66:67], v[62:63]
	v_pk_mul_f32 v[40:41], v[94:95], v[24:25] op_sel_hi:[0,1]
	v_pk_mul_f32 v[66:67], v[94:95], v[26:27] op_sel_hi:[0,1]
	v_lshlrev_b32_e32 v24, 16, v42
	v_and_b32_e32 v25, 0xffff0000, v42
	v_lshlrev_b32_e32 v26, 16, v43
	v_and_b32_e32 v27, 0xffff0000, v43
	s_waitcnt lgkmcnt(0)
	v_pk_fma_f32 v[56:57], v[68:69], v[20:21], v[56:57]
	v_pk_fma_f32 v[72:73], v[38:39], v[22:23], v[72:73]
	v_pk_fma_f32 v[60:61], v[38:39], v[18:19], v[60:61]
	v_pk_fma_f32 v[76:77], v[68:69], v[16:17], v[76:77]
	v_pk_fma_f32 v[64:65], v[68:69], v[12:13], v[64:65]
	v_pk_fma_f32 v[80:81], v[38:39], v[14:15], v[80:81]
	v_pk_fma_f32 v[38:39], v[118:119], v[38:39], v[30:31]
	v_pk_fma_f32 v[34:35], v[116:117], v[68:69], v[34:35]
	v_pk_mul_f32 v[42:43], v[94:95], v[24:25] op_sel_hi:[0,1]
	v_pk_mul_f32 v[68:69], v[94:95], v[26:27] op_sel_hi:[0,1]
	ds_read_b128 v[24:27], v89 offset:40960
	ds_read_b128 v[28:31], v89 offset:40976
	v_pk_fma_f32 v[32:33], v[0:1], v[40:41], v[32:33]
	v_pk_fma_f32 v[36:37], v[2:3], v[66:67], v[36:37]
	v_lshlrev_b32_e32 v0, 16, v104
	v_and_b32_e32 v1, 0xffff0000, v104
	v_lshlrev_b32_e32 v2, 16, v105
	v_and_b32_e32 v3, 0xffff0000, v105
	s_waitcnt lgkmcnt(1)
	v_pk_fma_f32 v[54:55], v[40:41], v[24:25], v[54:55]
	s_waitcnt lgkmcnt(0)
	v_pk_fma_f32 v[56:57], v[42:43], v[28:29], v[56:57]
	v_pk_fma_f32 v[74:75], v[40:41], v[8:9], v[74:75]
	v_pk_fma_f32 v[76:77], v[42:43], v[20:21], v[76:77]
	v_pk_fma_f32 v[62:63], v[40:41], v[4:5], v[62:63]
	v_pk_fma_f32 v[64:65], v[42:43], v[16:17], v[64:65]
	v_pk_fma_f32 v[34:35], v[12:13], v[42:43], v[34:35]
	v_pk_mul_f32 v[40:41], v[96:97], v[2:3] op_sel_hi:[0,1]
	v_pk_mul_f32 v[42:43], v[96:97], v[0:1] op_sel_hi:[0,1]
	v_lshlrev_b32_e32 v0, 16, v106
	v_and_b32_e32 v1, 0xffff0000, v106
	v_lshlrev_b32_e32 v2, 16, v107
	v_and_b32_e32 v3, 0xffff0000, v107
	v_pk_fma_f32 v[70:71], v[66:67], v[26:27], v[70:71]
	v_pk_fma_f32 v[72:73], v[68:69], v[30:31], v[72:73]
	v_pk_fma_f32 v[58:59], v[66:67], v[10:11], v[58:59]
	v_pk_fma_f32 v[60:61], v[68:69], v[22:23], v[60:61]
	v_pk_fma_f32 v[78:79], v[66:67], v[6:7], v[78:79]
	v_pk_fma_f32 v[80:81], v[68:69], v[18:19], v[80:81]
	v_pk_fma_f32 v[38:39], v[14:15], v[68:69], v[38:39]
	v_pk_mul_f32 v[66:67], v[96:97], v[2:3] op_sel_hi:[0,1]
	v_pk_mul_f32 v[68:69], v[96:97], v[0:1] op_sel_hi:[0,1]
	ds_read_b128 v[0:3], v89 offset:43008
	ds_read_b128 v[12:15], v89 offset:43024
	v_pk_fma_f32 v[36:37], v[6:7], v[40:41], v[36:37]
	v_pk_fma_f32 v[32:33], v[4:5], v[42:43], v[32:33]
	v_lshlrev_b32_e32 v4, 16, v108
	v_and_b32_e32 v5, 0xffff0000, v108
	v_lshlrev_b32_e32 v6, 16, v109
	v_and_b32_e32 v7, 0xffff0000, v109
	s_waitcnt lgkmcnt(1)
	v_pk_fma_f32 v[54:55], v[42:43], v[0:1], v[54:55]
	v_pk_fma_f32 v[70:71], v[40:41], v[2:3], v[70:71]
	v_pk_fma_f32 v[58:59], v[40:41], v[26:27], v[58:59]
	v_pk_fma_f32 v[74:75], v[42:43], v[24:25], v[74:75]
	v_pk_fma_f32 v[62:63], v[42:43], v[8:9], v[62:63]
	v_pk_fma_f32 v[78:79], v[40:41], v[10:11], v[78:79]
	v_pk_mul_f32 v[40:41], v[120:121], v[4:5] op_sel_hi:[0,1]
	v_pk_mul_f32 v[42:43], v[120:121], v[6:7] op_sel_hi:[0,1]
	v_lshlrev_b32_e32 v4, 16, v110
	v_and_b32_e32 v5, 0xffff0000, v110
	v_lshlrev_b32_e32 v6, 16, v111
	v_and_b32_e32 v7, 0xffff0000, v111
	s_waitcnt lgkmcnt(0)
	v_pk_fma_f32 v[56:57], v[68:69], v[12:13], v[56:57]
	v_pk_fma_f32 v[72:73], v[66:67], v[14:15], v[72:73]
	v_pk_fma_f32 v[60:61], v[66:67], v[30:31], v[60:61]
	v_pk_fma_f32 v[76:77], v[68:69], v[28:29], v[76:77]
	v_pk_fma_f32 v[64:65], v[68:69], v[20:21], v[64:65]
	v_pk_fma_f32 v[80:81], v[66:67], v[22:23], v[80:81]
	v_pk_fma_f32 v[38:39], v[66:67], v[18:19], v[38:39]
	v_pk_fma_f32 v[34:35], v[68:69], v[16:17], v[34:35]
	v_pk_mul_f32 v[66:67], v[120:121], v[4:5] op_sel_hi:[0,1]
	v_pk_mul_f32 v[68:69], v[120:121], v[6:7] op_sel_hi:[0,1]
	ds_read_b128 v[4:7], v89 offset:45056
	ds_read_b128 v[16:19], v89 offset:45072
	v_cndmask_b32_e64 v122, 0, 1.0, vcc
	v_pk_fma_f32 v[32:33], v[40:41], v[8:9], v[32:33]
	v_lshlrev_b32_e32 v8, 16, v112
	v_and_b32_e32 v9, 0xffff0000, v112
	s_waitcnt lgkmcnt(1)
	v_pk_fma_f32 v[70:71], v[42:43], v[6:7], v[70:71]
	v_pk_fma_f32 v[58:59], v[42:43], v[2:3], v[58:59]
	v_pk_fma_f32 v[78:79], v[42:43], v[26:27], v[78:79]
	v_pk_fma_f32 v[36:37], v[42:43], v[10:11], v[36:37]
	v_lshlrev_b32_e32 v10, 16, v113
	v_and_b32_e32 v11, 0xffff0000, v113
	v_pk_mul_f32 v[42:43], v[122:123], v[8:9] op_sel_hi:[0,1]
	v_pk_fma_f32 v[54:55], v[40:41], v[4:5], v[54:55]
	v_pk_fma_f32 v[74:75], v[40:41], v[0:1], v[74:75]
	v_pk_fma_f32 v[62:63], v[40:41], v[24:25], v[62:63]
	v_pk_mul_f32 v[40:41], v[122:123], v[10:11] op_sel_hi:[0,1]
	v_lshlrev_b32_e32 v8, 16, v114
	v_and_b32_e32 v9, 0xffff0000, v114
	v_lshlrev_b32_e32 v10, 16, v115
	v_and_b32_e32 v11, 0xffff0000, v115
	v_pk_fma_f32 v[82:83], v[42:43], v[24:25], v[32:33]
	v_add_u32_e32 v24, 9, v102
	s_waitcnt lgkmcnt(0)
	v_pk_fma_f32 v[72:73], v[68:69], v[18:19], v[72:73]
	v_pk_fma_f32 v[60:61], v[68:69], v[14:15], v[60:61]
	v_pk_fma_f32 v[80:81], v[68:69], v[30:31], v[80:81]
	v_pk_fma_f32 v[34:35], v[66:67], v[20:21], v[34:35]
	v_pk_fma_f32 v[38:39], v[68:69], v[22:23], v[38:39]
	v_pk_mul_f32 v[68:69], v[122:123], v[10:11] op_sel_hi:[0,1]
	v_pk_mul_f32 v[84:85], v[122:123], v[8:9] op_sel_hi:[0,1]
	ds_read_b128 v[8:11], v89 offset:47104
	ds_read_b128 v[20:23], v89 offset:47120
	v_min_u32_e32 v25, v24, v101
	v_cmp_lt_u32_e32 vcc, v24, v100
	v_add_u32_e32 v24, v25, v53
	v_ashrrev_i32_e32 v25, 31, v24
	v_lshlrev_b64 v[24:25], 10, v[24:25]
	v_pk_fma_f32 v[56:57], v[66:67], v[16:17], v[56:57]
	v_pk_fma_f32 v[76:77], v[66:67], v[12:13], v[76:77]
	v_pk_fma_f32 v[64:65], v[66:67], v[28:29], v[64:65]
	v_lshl_add_u64 v[24:25], v[46:47], 0, v[24:25]
	s_waitcnt lgkmcnt(0)
	v_pk_fma_f32 v[56:57], v[84:85], v[20:21], v[56:57]
	v_pk_fma_f32 v[76:77], v[84:85], v[16:17], v[76:77]
	v_pk_fma_f32 v[64:65], v[84:85], v[12:13], v[64:65]
	v_pk_fma_f32 v[66:67], v[40:41], v[26:27], v[36:37]
	v_pk_fma_f32 v[84:85], v[84:85], v[28:29], v[34:35]
	global_load_dwordx4 v[24:27], v[24:25], off
	v_add_u32_e32 v28, 10, v102
	v_min_u32_e32 v29, v28, v101
	v_cndmask_b32_e64 v86, 0, 1.0, vcc
	v_cmp_lt_u32_e32 vcc, v28, v100
	v_add_u32_e32 v28, v29, v53
	v_ashrrev_i32_e32 v29, 31, v28
	v_lshlrev_b64 v[28:29], 10, v[28:29]
	v_lshl_add_u64 v[28:29], v[46:47], 0, v[28:29]
	v_pk_fma_f32 v[72:73], v[68:69], v[22:23], v[72:73]
	v_pk_fma_f32 v[60:61], v[68:69], v[18:19], v[60:61]
	v_pk_fma_f32 v[80:81], v[68:69], v[14:15], v[80:81]
	v_pk_fma_f32 v[68:69], v[68:69], v[30:31], v[38:39]
	global_load_dwordx4 v[28:31], v[28:29], off
	v_add_u32_e32 v32, 11, v102
	v_min_u32_e32 v33, v32, v101
	v_cndmask_b32_e64 v88, 0, 1.0, vcc
	v_cmp_lt_u32_e32 vcc, v32, v100
	v_add_u32_e32 v32, v33, v53
	v_ashrrev_i32_e32 v33, 31, v32
	v_lshlrev_b64 v[32:33], 10, v[32:33]
	v_lshl_add_u64 v[32:33], v[46:47], 0, v[32:33]
	global_load_dwordx4 v[32:35], v[32:33], off
	v_add_u32_e32 v36, 12, v102
	v_min_u32_e32 v37, v36, v101
	v_cndmask_b32_e64 v90, 0, 1.0, vcc
	v_cmp_lt_u32_e32 vcc, v36, v100
	v_add_u32_e32 v36, v37, v53
	v_ashrrev_i32_e32 v37, 31, v36
	v_lshlrev_b64 v[36:37], 10, v[36:37]
	v_lshl_add_u64 v[36:37], v[46:47], 0, v[36:37]
	global_load_dwordx4 v[36:39], v[36:37], off
	v_pk_fma_f32 v[70:71], v[40:41], v[10:11], v[70:71]
	v_pk_fma_f32 v[58:59], v[40:41], v[6:7], v[58:59]
	v_pk_fma_f32 v[78:79], v[40:41], v[2:3], v[78:79]
	v_add_u32_e32 v40, 13, v102
	v_min_u32_e32 v41, v40, v101
	v_cndmask_b32_e64 v92, 0, 1.0, vcc
	v_cmp_lt_u32_e32 vcc, v40, v100
	v_add_u32_e32 v40, v41, v53
	v_add_u32_e32 v96, 14, v102
	v_ashrrev_i32_e32 v41, 31, v40
	v_min_u32_e32 v103, v96, v101
	v_lshlrev_b64 v[40:41], 10, v[40:41]
	v_add_u32_e32 v104, v103, v53
	v_add_u32_e32 v103, 15, v102
	v_lshl_add_u64 v[40:41], v[46:47], 0, v[40:41]
	v_ashrrev_i32_e32 v105, 31, v104
	v_min_u32_e32 v108, v103, v101
	v_pk_fma_f32 v[54:55], v[42:43], v[8:9], v[54:55]
	v_pk_fma_f32 v[74:75], v[42:43], v[4:5], v[74:75]
	v_pk_fma_f32 v[62:63], v[42:43], v[0:1], v[62:63]
	global_load_dwordx4 v[40:43], v[40:41], off
	v_lshlrev_b64 v[104:105], 10, v[104:105]
	v_add_u32_e32 v108, v108, v53
	v_lshl_add_u64 v[104:105], v[46:47], 0, v[104:105]
	v_ashrrev_i32_e32 v109, 31, v108
	global_load_dwordx4 v[104:107], v[104:105], off
	v_lshlrev_b64 v[108:109], 10, v[108:109]
	v_lshl_add_u64 v[108:109], v[46:47], 0, v[108:109]
	v_cndmask_b32_e64 v94, 0, 1.0, vcc
	v_cmp_lt_u32_e32 vcc, v96, v100
	global_load_dwordx4 v[108:111], v[108:109], off
	s_waitcnt vmcnt(0) lgkmcnt(0)
	v_lshlrev_b32_e32 v116, 16, v24
	v_cndmask_b32_e64 v96, 0, 1.0, vcc
	v_cmp_lt_u32_e32 vcc, v103, v100
	v_add_u32_e32 v103, 16, v102
	v_min_u32_e32 v112, v103, v101
	v_add_u32_e32 v112, v112, v53
	v_ashrrev_i32_e32 v113, 31, v112
	v_lshlrev_b64 v[112:113], 10, v[112:113]
	v_lshl_add_u64 v[112:113], v[46:47], 0, v[112:113]
	global_load_dwordx4 v[112:115], v[112:113], off
	v_and_b32_e32 v117, 0xffff0000, v24
	v_lshlrev_b32_e32 v24, 16, v25
	v_and_b32_e32 v25, 0xffff0000, v25
	v_pk_mul_f32 v[126:127], v[86:87], v[24:25] op_sel_hi:[0,1]
	v_lshlrev_b32_e32 v24, 16, v26
	v_and_b32_e32 v25, 0xffff0000, v26
	v_lshlrev_b32_e32 v26, 16, v27
	v_and_b32_e32 v27, 0xffff0000, v27
	v_pk_mul_f32 v[128:129], v[86:87], v[24:25] op_sel_hi:[0,1]
	v_pk_mul_f32 v[130:131], v[86:87], v[26:27] op_sel_hi:[0,1]
	ds_read_b128 v[24:27], v89 offset:49152
	v_pk_mul_f32 v[124:125], v[86:87], v[116:117] op_sel_hi:[0,1]
	v_pk_fma_f32 v[82:83], v[0:1], v[124:125], v[82:83]
	v_pk_fma_f32 v[66:67], v[2:3], v[126:127], v[66:67]
	v_lshlrev_b32_e32 v0, 16, v28
	v_and_b32_e32 v1, 0xffff0000, v28
	v_lshlrev_b32_e32 v2, 16, v29
	v_and_b32_e32 v3, 0xffff0000, v29
	ds_read_b128 v[116:119], v89 offset:49168
	s_waitcnt lgkmcnt(0)
	v_pk_fma_f32 v[54:55], v[124:125], v[24:25], v[54:55]
	v_pk_fma_f32 v[74:75], v[8:9], v[124:125], v[74:75]
	v_pk_fma_f32 v[62:63], v[4:5], v[124:125], v[62:63]
	v_pk_mul_f32 v[28:29], v[88:89], v[2:3] op_sel_hi:[0,1]
	v_pk_mul_f32 v[124:125], v[88:89], v[0:1] op_sel_hi:[0,1]
	v_lshlrev_b32_e32 v0, 16, v30
	v_and_b32_e32 v1, 0xffff0000, v30
	v_lshlrev_b32_e32 v2, 16, v31
	v_and_b32_e32 v3, 0xffff0000, v31
	v_pk_fma_f32 v[70:71], v[126:127], v[26:27], v[70:71]
	v_pk_fma_f32 v[58:59], v[10:11], v[126:127], v[58:59]
	v_pk_fma_f32 v[78:79], v[6:7], v[126:127], v[78:79]
	v_pk_mul_f32 v[30:31], v[88:89], v[2:3] op_sel_hi:[0,1]
	v_pk_mul_f32 v[126:127], v[88:89], v[0:1] op_sel_hi:[0,1]
	ds_read_b128 v[0:3], v89 offset:51200
	v_pk_fma_f32 v[84:85], v[12:13], v[128:129], v[84:85]
	v_pk_fma_f32 v[68:69], v[14:15], v[130:131], v[68:69]
	ds_read_b128 v[12:15], v89 offset:51216
	v_pk_fma_f32 v[58:59], v[26:27], v[28:29], v[58:59]
	s_waitcnt lgkmcnt(0)
	v_pk_fma_f32 v[70:71], v[28:29], v[2:3], v[70:71]
	v_pk_fma_f32 v[78:79], v[10:11], v[28:29], v[78:79]
	v_pk_fma_f32 v[28:29], v[6:7], v[28:29], v[66:67]
	v_pk_fma_f32 v[66:67], v[4:5], v[124:125], v[82:83]
	v_lshlrev_b32_e32 v4, 16, v32
	v_and_b32_e32 v5, 0xffff0000, v32
	v_lshlrev_b32_e32 v6, 16, v33
	v_and_b32_e32 v7, 0xffff0000, v33
	v_pk_fma_f32 v[72:73], v[130:131], v[118:119], v[72:73]
	v_pk_fma_f32 v[60:61], v[22:23], v[130:131], v[60:61]
	v_pk_fma_f32 v[80:81], v[18:19], v[130:131], v[80:81]
	v_pk_mul_f32 v[32:33], v[90:91], v[4:5] op_sel_hi:[0,1]
	v_pk_mul_f32 v[82:83], v[90:91], v[6:7] op_sel_hi:[0,1]
	v_lshlrev_b32_e32 v4, 16, v34
	v_and_b32_e32 v5, 0xffff0000, v34
	v_lshlrev_b32_e32 v6, 16, v35
	v_and_b32_e32 v7, 0xffff0000, v35
	v_pk_fma_f32 v[64:65], v[16:17], v[128:129], v[64:65]
	v_pk_fma_f32 v[72:73], v[30:31], v[14:15], v[72:73]
	v_pk_fma_f32 v[60:61], v[30:31], v[118:119], v[60:61]
	v_pk_fma_f32 v[80:81], v[22:23], v[30:31], v[80:81]
	v_pk_fma_f32 v[30:31], v[18:19], v[30:31], v[68:69]
	v_pk_fma_f32 v[68:69], v[16:17], v[126:127], v[84:85]
	v_pk_mul_f32 v[34:35], v[90:91], v[4:5] op_sel_hi:[0,1]
	v_pk_mul_f32 v[84:85], v[90:91], v[6:7] op_sel_hi:[0,1]
	ds_read_b128 v[4:7], v89 offset:53248
	ds_read_b128 v[16:19], v89 offset:53264
	v_pk_fma_f32 v[56:57], v[128:129], v[116:117], v[56:57]
	v_pk_fma_f32 v[76:77], v[20:21], v[128:129], v[76:77]
	v_pk_fma_f32 v[54:55], v[124:125], v[0:1], v[54:55]
	v_pk_fma_f32 v[56:57], v[126:127], v[12:13], v[56:57]
	v_pk_fma_f32 v[74:75], v[24:25], v[124:125], v[74:75]
	v_pk_fma_f32 v[76:77], v[126:127], v[116:117], v[76:77]
	v_pk_fma_f32 v[62:63], v[8:9], v[124:125], v[62:63]
	v_pk_fma_f32 v[64:65], v[20:21], v[126:127], v[64:65]
	s_waitcnt lgkmcnt(0)
	v_pk_fma_f32 v[54:55], v[32:33], v[4:5], v[54:55]
	v_pk_fma_f32 v[56:57], v[34:35], v[16:17], v[56:57]
	v_pk_fma_f32 v[74:75], v[32:33], v[0:1], v[74:75]
	v_pk_fma_f32 v[76:77], v[34:35], v[12:13], v[76:77]
	v_pk_fma_f32 v[62:63], v[24:25], v[32:33], v[62:63]
	v_pk_fma_f32 v[64:65], v[116:117], v[34:35], v[64:65]
	v_pk_fma_f32 v[8:9], v[8:9], v[32:33], v[66:67]
	v_pk_fma_f32 v[32:33], v[20:21], v[34:35], v[68:69]
	v_pk_fma_f32 v[34:35], v[22:23], v[84:85], v[30:31]
	v_lshlrev_b32_e32 v20, 16, v36
	v_and_b32_e32 v21, 0xffff0000, v36
	v_lshlrev_b32_e32 v22, 16, v37
	v_and_b32_e32 v23, 0xffff0000, v37
	v_pk_mul_f32 v[36:37], v[92:93], v[22:23] op_sel_hi:[0,1]
	v_pk_mul_f32 v[66:67], v[92:93], v[20:21] op_sel_hi:[0,1]
	v_lshlrev_b32_e32 v20, 16, v38
	v_and_b32_e32 v21, 0xffff0000, v38
	v_lshlrev_b32_e32 v22, 16, v39
	v_and_b32_e32 v23, 0xffff0000, v39
	v_pk_fma_f32 v[10:11], v[10:11], v[82:83], v[28:29]
	v_pk_mul_f32 v[38:39], v[92:93], v[22:23] op_sel_hi:[0,1]
	v_pk_mul_f32 v[68:69], v[92:93], v[20:21] op_sel_hi:[0,1]
	ds_read_b128 v[20:23], v89 offset:55296
	ds_read_b128 v[28:31], v89 offset:55312
	v_pk_fma_f32 v[58:59], v[82:83], v[2:3], v[58:59]
	v_pk_fma_f32 v[70:71], v[82:83], v[6:7], v[70:71]
	v_pk_fma_f32 v[72:73], v[84:85], v[18:19], v[72:73]
	v_pk_fma_f32 v[60:61], v[84:85], v[14:15], v[60:61]
	v_pk_fma_f32 v[78:79], v[26:27], v[82:83], v[78:79]
	v_pk_fma_f32 v[80:81], v[118:119], v[84:85], v[80:81]
	s_waitcnt lgkmcnt(0)
	v_pk_fma_f32 v[54:55], v[66:67], v[20:21], v[54:55]
	v_pk_fma_f32 v[82:83], v[68:69], v[28:29], v[56:57]
	v_pk_fma_f32 v[84:85], v[36:37], v[6:7], v[58:59]
	v_pk_fma_f32 v[74:75], v[66:67], v[4:5], v[74:75]
	v_pk_fma_f32 v[76:77], v[68:69], v[16:17], v[76:77]
	v_pk_fma_f32 v[62:63], v[0:1], v[66:67], v[62:63]
	v_pk_fma_f32 v[64:65], v[68:69], v[12:13], v[64:65]
	v_pk_fma_f32 v[10:11], v[26:27], v[36:37], v[10:11]
	v_pk_fma_f32 v[8:9], v[24:25], v[66:67], v[8:9]
	v_pk_fma_f32 v[26:27], v[116:117], v[68:69], v[32:33]
	ds_read_b128 v[56:59], v89 offset:57344
	ds_read_b128 v[66:69], v89 offset:57360
	v_pk_fma_f32 v[24:25], v[118:119], v[38:39], v[34:35]
	v_lshlrev_b32_e32 v32, 16, v40
	v_and_b32_e32 v33, 0xffff0000, v40
	v_lshlrev_b32_e32 v34, 16, v41
	v_and_b32_e32 v35, 0xffff0000, v41
	v_pk_fma_f32 v[72:73], v[38:39], v[30:31], v[72:73]
	v_pk_fma_f32 v[60:61], v[38:39], v[18:19], v[60:61]
	v_pk_fma_f32 v[80:81], v[38:39], v[14:15], v[80:81]
	v_pk_mul_f32 v[32:33], v[94:95], v[32:33] op_sel_hi:[0,1]
	v_pk_mul_f32 v[34:35], v[94:95], v[34:35] op_sel_hi:[0,1]
	v_lshlrev_b32_e32 v38, 16, v43
	v_and_b32_e32 v39, 0xffff0000, v43
	v_pk_fma_f32 v[70:71], v[36:37], v[22:23], v[70:71]
	v_pk_fma_f32 v[78:79], v[2:3], v[36:37], v[78:79]
	v_lshlrev_b32_e32 v36, 16, v42
	v_and_b32_e32 v37, 0xffff0000, v42
	v_pk_mul_f32 v[38:39], v[94:95], v[38:39] op_sel_hi:[0,1]
	v_pk_fma_f32 v[0:1], v[0:1], v[32:33], v[8:9]
	v_pk_fma_f32 v[2:3], v[2:3], v[34:35], v[10:11]
	v_lshlrev_b32_e32 v8, 16, v104
	v_and_b32_e32 v9, 0xffff0000, v104
	v_lshlrev_b32_e32 v10, 16, v105
	v_and_b32_e32 v11, 0xffff0000, v105
	v_pk_mul_f32 v[36:37], v[94:95], v[36:37] op_sel_hi:[0,1]
	s_waitcnt lgkmcnt(0)
	v_pk_fma_f32 v[40:41], v[34:35], v[58:59], v[70:71]
	v_pk_fma_f32 v[42:43], v[32:33], v[56:57], v[54:55]
	v_pk_fma_f32 v[54:55], v[38:39], v[68:69], v[72:73]
	v_pk_fma_f32 v[72:73], v[32:33], v[20:21], v[74:75]
	v_pk_fma_f32 v[74:75], v[34:35], v[22:23], v[84:85]
	v_pk_fma_f32 v[78:79], v[34:35], v[6:7], v[78:79]
	v_pk_fma_f32 v[62:63], v[32:33], v[4:5], v[62:63]
	v_pk_mul_f32 v[32:33], v[96:97], v[10:11] op_sel_hi:[0,1]
	v_pk_mul_f32 v[34:35], v[96:97], v[8:9] op_sel_hi:[0,1]
	v_lshlrev_b32_e32 v8, 16, v106
	v_and_b32_e32 v9, 0xffff0000, v106
	v_lshlrev_b32_e32 v10, 16, v107
	v_and_b32_e32 v11, 0xffff0000, v107
	v_cndmask_b32_e64 v120, 0, 1.0, vcc
	v_pk_fma_f32 v[70:71], v[36:37], v[66:67], v[82:83]
	v_pk_fma_f32 v[76:77], v[36:37], v[28:29], v[76:77]
	v_pk_fma_f32 v[60:61], v[38:39], v[30:31], v[60:61]
	v_pk_fma_f32 v[80:81], v[38:39], v[18:19], v[80:81]
	v_pk_fma_f32 v[64:65], v[36:37], v[16:17], v[64:65]
	v_pk_fma_f32 v[26:27], v[12:13], v[36:37], v[26:27]
	v_pk_fma_f32 v[24:25], v[14:15], v[38:39], v[24:25]
	v_pk_mul_f32 v[36:37], v[96:97], v[10:11] op_sel_hi:[0,1]
	v_pk_mul_f32 v[38:39], v[96:97], v[8:9] op_sel_hi:[0,1]
	v_pk_fma_f32 v[82:83], v[6:7], v[32:33], v[2:3]
	v_pk_fma_f32 v[84:85], v[4:5], v[34:35], v[0:1]
	v_lshlrev_b32_e32 v0, 16, v108
	v_and_b32_e32 v1, 0xffff0000, v108
	v_lshlrev_b32_e32 v2, 16, v109
	v_and_b32_e32 v3, 0xffff0000, v109
	ds_read_b128 v[8:11], v89 offset:59392
	ds_read_b128 v[12:15], v89 offset:59408
	v_pk_fma_f32 v[18:19], v[36:37], v[18:19], v[24:25]
	v_pk_fma_f32 v[16:17], v[38:39], v[16:17], v[26:27]
	v_pk_mul_f32 v[24:25], v[120:121], v[0:1] op_sel_hi:[0,1]
	v_pk_mul_f32 v[26:27], v[120:121], v[2:3] op_sel_hi:[0,1]
	v_lshlrev_b32_e32 v0, 16, v110
	v_and_b32_e32 v1, 0xffff0000, v110
	v_lshlrev_b32_e32 v2, 16, v111
	v_and_b32_e32 v3, 0xffff0000, v111
	v_pk_mul_f32 v[104:105], v[120:121], v[0:1] op_sel_hi:[0,1]
	v_pk_mul_f32 v[106:107], v[120:121], v[2:3] op_sel_hi:[0,1]
	ds_read_b128 v[0:3], v89 offset:61440
	ds_read_b128 v[4:7], v89 offset:61456
	v_cmp_lt_u32_e32 vcc, v103, v100
	s_waitcnt lgkmcnt(0)
	v_pk_fma_f32 v[42:43], v[34:35], v[8:9], v[42:43]
	v_pk_fma_f32 v[40:41], v[32:33], v[10:11], v[40:41]
	v_pk_fma_f32 v[72:73], v[34:35], v[56:57], v[72:73]
	v_pk_fma_f32 v[62:63], v[34:35], v[20:21], v[62:63]
	v_cndmask_b32_e64 v122, 0, 1.0, vcc
	v_pk_fma_f32 v[70:71], v[38:39], v[12:13], v[70:71]
	v_pk_fma_f32 v[74:75], v[32:33], v[58:59], v[74:75]
	v_pk_fma_f32 v[76:77], v[38:39], v[66:67], v[76:77]
	v_pk_fma_f32 v[64:65], v[38:39], v[28:29], v[64:65]
	v_pk_fma_f32 v[34:35], v[26:27], v[2:3], v[40:41]
	v_pk_fma_f32 v[38:39], v[24:25], v[0:1], v[42:43]
	v_pk_fma_f32 v[40:41], v[24:25], v[8:9], v[72:73]
	v_pk_fma_f32 v[62:63], v[24:25], v[56:57], v[62:63]
	v_pk_fma_f32 v[20:21], v[24:25], v[20:21], v[84:85]
	s_waitcnt vmcnt(0)
	v_lshlrev_b32_e32 v24, 16, v112
	v_and_b32_e32 v25, 0xffff0000, v112
	v_pk_fma_f32 v[78:79], v[32:33], v[22:23], v[78:79]
	v_pk_fma_f32 v[42:43], v[26:27], v[10:11], v[74:75]
	v_pk_mul_f32 v[74:75], v[122:123], v[24:25] op_sel_hi:[0,1]
	v_lshlrev_b32_e32 v24, 16, v114
	v_and_b32_e32 v25, 0xffff0000, v114
	v_pk_fma_f32 v[54:55], v[36:37], v[14:15], v[54:55]
	v_pk_fma_f32 v[60:61], v[36:37], v[68:69], v[60:61]
	v_pk_fma_f32 v[80:81], v[36:37], v[30:31], v[80:81]
	v_pk_fma_f32 v[36:37], v[104:105], v[4:5], v[70:71]
	v_pk_fma_f32 v[70:71], v[26:27], v[58:59], v[78:79]
	v_pk_fma_f32 v[16:17], v[104:105], v[28:29], v[16:17]
	v_pk_mul_f32 v[78:79], v[122:123], v[24:25] op_sel_hi:[0,1]
	v_pk_fma_f32 v[64:65], v[104:105], v[66:67], v[64:65]
	v_pk_fma_f32 v[22:23], v[26:27], v[22:23], v[82:83]
	v_lshlrev_b32_e32 v26, 16, v113
	v_and_b32_e32 v27, 0xffff0000, v113
	v_pk_fma_f32 v[66:67], v[78:79], v[66:67], v[16:17]
	v_add_u32_e32 v16, 17, v102
	v_pk_fma_f32 v[32:33], v[106:107], v[6:7], v[54:55]
	v_pk_fma_f32 v[54:55], v[104:105], v[12:13], v[76:77]
	v_pk_mul_f32 v[76:77], v[122:123], v[26:27] op_sel_hi:[0,1]
	v_min_u32_e32 v17, v16, v101
	v_pk_fma_f32 v[28:29], v[76:77], v[2:3], v[42:43]
	v_pk_fma_f32 v[42:43], v[78:79], v[12:13], v[64:65]
	v_pk_fma_f32 v[64:65], v[74:75], v[56:57], v[20:21]
	v_cmp_lt_u32_e32 vcc, v16, v100
	v_add_u32_e32 v16, v17, v53
	v_add_u32_e32 v20, 18, v102
	v_ashrrev_i32_e32 v17, 31, v16
	v_min_u32_e32 v21, v20, v101
	v_lshlrev_b32_e32 v26, 16, v115
	v_and_b32_e32 v27, 0xffff0000, v115
	v_cndmask_b32_e64 v56, 0, 1.0, vcc
	v_lshlrev_b64 v[16:17], 10, v[16:17]
	v_cmp_lt_u32_e32 vcc, v20, v100
	v_add_u32_e32 v20, v21, v53
	v_pk_fma_f32 v[60:61], v[106:107], v[14:15], v[60:61]
	v_pk_fma_f32 v[72:73], v[106:107], v[68:69], v[80:81]
	v_pk_fma_f32 v[18:19], v[106:107], v[30:31], v[18:19]
	v_pk_mul_f32 v[80:81], v[122:123], v[26:27] op_sel_hi:[0,1]
	v_lshl_add_u64 v[16:17], v[46:47], 0, v[16:17]
	v_ashrrev_i32_e32 v21, 31, v20
	v_pk_fma_f32 v[24:25], v[80:81], v[6:7], v[60:61]
	v_pk_fma_f32 v[60:61], v[80:81], v[68:69], v[18:19]
	global_load_dwordx4 v[16:19], v[16:17], off
	v_lshlrev_b64 v[20:21], 10, v[20:21]
	v_lshl_add_u64 v[20:21], v[46:47], 0, v[20:21]
	v_pk_fma_f32 v[58:59], v[76:77], v[58:59], v[22:23]
	global_load_dwordx4 v[20:23], v[20:21], off
	v_pk_fma_f32 v[30:31], v[74:75], v[0:1], v[40:41]
	v_pk_fma_f32 v[26:27], v[78:79], v[4:5], v[54:55]
	v_pk_fma_f32 v[40:41], v[74:75], v[8:9], v[62:63]
	v_pk_fma_f32 v[54:55], v[76:77], v[10:11], v[70:71]
	v_pk_fma_f32 v[62:63], v[80:81], v[14:15], v[72:73]
	v_cndmask_b32_e64 v68, 0, 1.0, vcc
	v_ashrrev_i32_e32 v53, 31, v52
	v_add_u32_e32 v87, s38, v87
	s_waitcnt vmcnt(0) lgkmcnt(0)
	v_lshlrev_b32_e32 v70, 16, v16
	v_and_b32_e32 v71, 0xffff0000, v16
	v_lshlrev_b32_e32 v16, 16, v17
	v_and_b32_e32 v17, 0xffff0000, v17
	v_lshlrev_b32_e32 v72, 16, v18
	v_and_b32_e32 v73, 0xffff0000, v18
	v_lshlrev_b32_e32 v18, 16, v19
	v_and_b32_e32 v19, 0xffff0000, v19
	v_pk_mul_f32 v[70:71], v[56:57], v[70:71] op_sel_hi:[0,1]
	v_pk_mul_f32 v[16:17], v[56:57], v[16:17] op_sel_hi:[0,1]
	v_pk_mul_f32 v[72:73], v[56:57], v[72:73] op_sel_hi:[0,1]
	v_pk_mul_f32 v[18:19], v[56:57], v[18:19] op_sel_hi:[0,1]
	v_pk_fma_f32 v[54:55], v[2:3], v[16:17], v[54:55]
	v_pk_fma_f32 v[56:57], v[0:1], v[70:71], v[40:41]
	v_pk_fma_f32 v[40:41], v[6:7], v[18:19], v[62:63]
	v_pk_fma_f32 v[16:17], v[10:11], v[16:17], v[58:59]
	v_pk_fma_f32 v[10:11], v[12:13], v[72:73], v[66:67]
	v_pk_fma_f32 v[12:13], v[14:15], v[18:19], v[60:61]
	v_lshlrev_b32_e32 v18, 16, v21
	v_and_b32_e32 v19, 0xffff0000, v21
	v_lshlrev_b32_e32 v14, 16, v20
	v_and_b32_e32 v15, 0xffff0000, v20
	v_pk_mul_f32 v[18:19], v[68:69], v[18:19] op_sel_hi:[0,1]
	v_lshlrev_b32_e32 v20, 16, v22
	v_and_b32_e32 v21, 0xffff0000, v22
	v_lshlrev_b32_e32 v22, 16, v23
	v_and_b32_e32 v23, 0xffff0000, v23
	v_pk_mul_f32 v[62:63], v[68:69], v[20:21] op_sel_hi:[0,1]
	v_pk_fma_f32 v[58:59], v[2:3], v[18:19], v[16:17]
	v_pk_mov_b32 v[16:17], v[38:39], v[34:35] op_sel:[1,0]
	v_mov_b32_e32 v18, v38
	v_mov_b32_e32 v19, v35
	v_pk_mul_f32 v[20:21], v[68:69], v[22:23] op_sel_hi:[0,1]
	v_pk_fma_f32 v[22:23], v[4:5], v[62:63], v[10:11]
	v_pk_add_f32 v[16:17], v[16:17], v[18:19]
	v_mov_b32_e32 v18, v32
	v_mov_b32_e32 v19, v36
	v_mov_b32_e32 v62, v33
	v_mov_b32_e32 v63, v37
	v_pk_add_f32 v[18:19], v[18:19], v[62:63]
	v_add_f32_e32 v16, v16, v17
	v_add_f32_e32 v16, v16, v19
	v_add_f32_e32 v16, v18, v16
	ds_bpermute_b32 v17, v91, v16
	v_pk_fma_f32 v[8:9], v[8:9], v[70:71], v[64:65]
	v_mov_b32_e32 v66, v30
	v_mov_b32_e32 v67, v29
	v_pk_mul_f32 v[14:15], v[68:69], v[14:15] op_sel_hi:[0,1]
	s_waitcnt lgkmcnt(0)
	v_add_f32_e32 v16, v16, v17
	ds_bpermute_b32 v17, v93, v16
	v_mov_b32_e32 v68, v25
	v_mov_b32_e32 v69, v27
	v_pk_fma_f32 v[42:43], v[4:5], v[72:73], v[42:43]
	v_pk_fma_f32 v[60:61], v[0:1], v[14:15], v[8:9]
	s_waitcnt lgkmcnt(0)
	v_add_f32_e32 v16, v16, v17
	ds_bpermute_b32 v17, v95, v16
	v_pk_fma_f32 v[20:21], v[6:7], v[20:21], v[12:13]
	global_load_dwordx4 v[0:3], v[48:49], off offset:16
	global_load_dwordx4 v[4:7], v[48:49], off
	global_load_dwordx4 v[8:11], v[50:51], off offset:16
	global_load_dwordx4 v[12:15], v[50:51], off
	s_waitcnt lgkmcnt(0)
	v_add_f32_e32 v16, v16, v17
	ds_bpermute_b32 v17, v97, v16
	s_waitcnt lgkmcnt(0)
	v_add_f32_e32 v16, v16, v17
	ds_bpermute_b32 v17, v98, v16
	s_waitcnt lgkmcnt(0)
	v_add_f32_e32 v16, v16, v17
	ds_bpermute_b32 v17, v99, v16
	s_waitcnt lgkmcnt(0)
	v_add_f32_e32 v16, v16, v17
	v_fmamk_f32 v39, v16, 0xbb000000, v39
	v_fmac_f32_e32 v38, 0xbb000000, v16
	v_fmamk_f32 v35, v16, 0xbb000000, v35
	v_fmac_f32_e32 v34, 0xbb000000, v16
	v_fmamk_f32 v37, v16, 0xbb000000, v37
	v_fmac_f32_e32 v36, 0xbb000000, v16
	v_fmamk_f32 v33, v16, 0xbb000000, v33
	v_fmac_f32_e32 v32, 0xbb000000, v16
	v_pk_mul_f32 v[16:17], v[34:35], v[34:35]
	v_pk_mul_f32 v[18:19], v[38:39], v[38:39]
	s_nop 0
	v_pk_mov_b32 v[62:63], v[18:19], v[16:17] op_sel:[1,0]
	v_mov_b32_e32 v19, v17
	v_pk_add_f32 v[16:17], v[62:63], v[18:19]
	v_pk_mul_f32 v[18:19], v[32:33], v[32:33]
	v_pk_mul_f32 v[62:63], v[36:37], v[36:37]
	v_mov_b32_e32 v64, v18
	v_mov_b32_e32 v65, v62
	v_mov_b32_e32 v62, v19
	v_pk_add_f32 v[18:19], v[64:65], v[62:63]
	v_lshlrev_b64 v[62:63], 12, v[52:53]
	v_lshl_add_u64 v[62:63], s[18:19], 0, v[62:63]
	v_lshl_add_u64 v[64:65], v[62:63], 0, v[152:153]
	v_pk_mov_b32 v[62:63], v[30:31], v[28:29] op_sel:[1,0]
	s_nop 0
	v_pk_add_f32 v[62:63], v[62:63], v[66:67]
	v_mov_b32_e32 v66, v24
	v_mov_b32_e32 v67, v26
	v_pk_add_f32 v[66:67], v[66:67], v[68:69]
	v_add_f32_e32 v53, v62, v63
	v_add_f32_e32 v53, v53, v67
	v_add_f32_e32 v53, v66, v53
	ds_bpermute_b32 v62, v91, v53
	s_waitcnt lgkmcnt(0)
	v_add_f32_e32 v53, v53, v62
	ds_bpermute_b32 v62, v93, v53
	s_waitcnt lgkmcnt(0)
	v_add_f32_e32 v53, v53, v62
	ds_bpermute_b32 v62, v95, v53
	s_waitcnt lgkmcnt(0)
	v_add_f32_e32 v53, v53, v62
	ds_bpermute_b32 v62, v97, v53
	s_waitcnt lgkmcnt(0)
	v_add_f32_e32 v53, v53, v62
	ds_bpermute_b32 v62, v98, v53
	s_waitcnt lgkmcnt(0)
	v_add_f32_e32 v53, v53, v62
	ds_bpermute_b32 v62, v99, v53
	s_waitcnt lgkmcnt(0)
	v_add_f32_e32 v53, v53, v62
	v_fmamk_f32 v31, v53, 0xbb000000, v31
	v_fmac_f32_e32 v30, 0xbb000000, v53
	v_fmamk_f32 v29, v53, 0xbb000000, v29
	v_fmac_f32_e32 v28, 0xbb000000, v53
	v_pk_mul_f32 v[62:63], v[28:29], v[28:29]
	v_pk_mul_f32 v[66:67], v[30:31], v[30:31]
	v_fmamk_f32 v27, v53, 0xbb000000, v27
	v_fmac_f32_e32 v26, 0xbb000000, v53
	v_fmamk_f32 v25, v53, 0xbb000000, v25
	v_fmac_f32_e32 v24, 0xbb000000, v53
	v_pk_mov_b32 v[68:69], v[66:67], v[62:63] op_sel:[1,0]
	v_mov_b32_e32 v67, v63
	v_pk_add_f32 v[62:63], v[68:69], v[66:67]
	v_pk_mul_f32 v[66:67], v[24:25], v[24:25]
	v_pk_mul_f32 v[68:69], v[26:27], v[26:27]
	v_mov_b32_e32 v70, v66
	v_mov_b32_e32 v71, v68
	v_mov_b32_e32 v68, v67
	v_pk_add_f32 v[66:67], v[70:71], v[68:69]
	v_mov_b32_e32 v68, v62
	v_mov_b32_e32 v69, v16
	v_mov_b32_e32 v16, v63
	v_pk_add_f32 v[16:17], v[68:69], v[16:17]
	v_mov_b32_e32 v62, v67
	v_mov_b32_e32 v63, v19
	v_pk_add_f32 v[16:17], v[62:63], v[16:17]
	v_mov_b32_e32 v67, v18
	v_pk_add_f32 v[16:17], v[66:67], v[16:17]
	ds_bpermute_b32 v19, v91, v17
	ds_bpermute_b32 v18, v91, v16
	v_mov_b64_e32 v[62:63], s[16:17]
	s_waitcnt lgkmcnt(0)
	v_pk_add_f32 v[16:17], v[16:17], v[18:19]
	ds_bpermute_b32 v19, v93, v17
	ds_bpermute_b32 v18, v93, v16
	s_waitcnt lgkmcnt(0)
	v_pk_add_f32 v[16:17], v[16:17], v[18:19]
	ds_bpermute_b32 v19, v95, v17
	ds_bpermute_b32 v18, v95, v16
	s_waitcnt lgkmcnt(0)
	v_pk_add_f32 v[16:17], v[16:17], v[18:19]
	ds_bpermute_b32 v19, v97, v17
	ds_bpermute_b32 v18, v97, v16
	s_waitcnt lgkmcnt(0)
	v_pk_add_f32 v[16:17], v[16:17], v[18:19]
	ds_bpermute_b32 v19, v98, v17
	ds_bpermute_b32 v18, v98, v16
	s_waitcnt lgkmcnt(0)
	v_pk_add_f32 v[16:17], v[16:17], v[18:19]
	ds_bpermute_b32 v19, v99, v17
	ds_bpermute_b32 v18, v99, v16
	s_waitcnt lgkmcnt(0)
	v_pk_add_f32 v[16:17], v[16:17], v[18:19]
	s_nop 0
	v_pk_fma_f32 v[66:67], v[16:17], s[20:21], v[62:63] op_sel_hi:[1,0,0]
	s_nop 0
	v_mul_f32_e32 v16, 0x4b800000, v67
	v_cmp_gt_f32_e64 s[8:9], s68, v67
	v_cmp_gt_f32_e32 vcc, s68, v66
	s_nop 0
	v_cndmask_b32_e64 v16, v67, v16, s[8:9]
	v_rsq_f32_e32 v16, v16
	s_nop 0
	v_mul_f32_e32 v17, 0x45800000, v16
	v_cndmask_b32_e64 v16, v16, v17, s[8:9]
	v_pk_mul_f32 v[36:37], v[36:37], v[16:17] op_sel_hi:[1,0]
	v_pk_mul_f32 v[18:19], v[38:39], v[16:17] op_sel_hi:[1,0]
	v_pk_mul_f32 v[34:35], v[34:35], v[16:17] op_sel_hi:[1,0]
	v_pk_mul_f32 v[16:17], v[32:33], v[16:17] op_sel_hi:[1,0]
	s_waitcnt vmcnt(1)
	v_pk_fma_f32 v[32:33], v[0:1], v[36:37], v[8:9]
	s_waitcnt vmcnt(0)
	v_pk_fma_f32 v[18:19], v[4:5], v[18:19], v[12:13]
	v_mul_f32_e32 v37, 0xbfb8aa3b, v32
	v_exp_f32_e32 v37, v37
	v_mul_f32_e32 v36, 0xbfb8aa3b, v18
	v_exp_f32_e32 v36, v36
	v_pk_fma_f32 v[16:17], v[2:3], v[16:17], v[10:11]
	v_add_f32_e32 v37, 1.0, v37
	v_rcp_f32_e32 v38, v37
	v_mul_f32_e32 v37, 0xbfb8aa3b, v19
	v_exp_f32_e32 v37, v37
	v_add_f32_e32 v36, 1.0, v36
	v_rcp_f32_e32 v36, v36
	v_pk_fma_f32 v[34:35], v[6:7], v[34:35], v[14:15]
	v_add_f32_e32 v37, 1.0, v37
	v_rcp_f32_e32 v37, v37
	s_nop 0
	v_pk_mul_f32 v[18:19], v[18:19], v[36:37]
	v_mul_f32_e32 v36, 0xbfb8aa3b, v33
	v_exp_f32_e32 v36, v36
	v_mul_f32_e32 v37, 0xbfb8aa3b, v16
	v_exp_f32_e32 v37, v37
	v_add_f32_e32 v36, 1.0, v36
	v_rcp_f32_e32 v39, v36
	v_add_f32_e32 v37, 1.0, v37
	v_mul_f32_e32 v36, 0xbfb8aa3b, v34
	v_exp_f32_e32 v36, v36
	v_pk_mul_f32 v[32:33], v[32:33], v[38:39]
	v_rcp_f32_e32 v38, v37
	v_mul_f32_e32 v37, 0xbfb8aa3b, v35
	v_exp_f32_e32 v37, v37
	v_add_f32_e32 v36, 1.0, v36
	v_rcp_f32_e32 v36, v36
	v_add_f32_e32 v37, 1.0, v37
	v_rcp_f32_e32 v37, v37
	s_nop 0
	v_pk_mul_f32 v[34:35], v[34:35], v[36:37]
	v_mul_f32_e32 v36, 0xbfb8aa3b, v17
	v_exp_f32_e32 v36, v36
	s_nop 0
	v_add_f32_e32 v36, 1.0, v36
	v_rcp_f32_e32 v39, v36
	s_nop 0
	v_pk_mul_f32 v[36:37], v[16:17], v[38:39]
	v_cvt_pk_bf16_f32 v16, v18, v19
	v_cvt_pk_bf16_f32 v18, v32, v33
	v_add_co_u32_e64 v32, s[8:9], s15, v64
	v_cvt_pk_bf16_f32 v17, v34, v35
	v_cvt_pk_bf16_f32 v19, v36, v37
	v_addc_co_u32_e64 v33, s[8:9], 0, v65, s[8:9]
	global_store_dwordx4 v[32:33], v[16:19], off offset:2048
	s_nop 1
	v_mul_f32_e32 v16, 0x4b800000, v66
	v_cndmask_b32_e32 v16, v66, v16, vcc
	v_rsq_f32_e32 v16, v16
	s_nop 0
	v_mul_f32_e32 v17, 0x45800000, v16
	v_cndmask_b32_e32 v16, v16, v17, vcc
	v_pk_mul_f32 v[26:27], v[26:27], v[16:17] op_sel_hi:[1,0]
	v_pk_mul_f32 v[18:19], v[30:31], v[16:17] op_sel_hi:[1,0]
	v_pk_mul_f32 v[28:29], v[28:29], v[16:17] op_sel_hi:[1,0]
	v_pk_mul_f32 v[16:17], v[24:25], v[16:17] op_sel_hi:[1,0]
	v_pk_fma_f32 v[24:25], v[0:1], v[26:27], v[8:9]
	v_pk_fma_f32 v[18:19], v[4:5], v[18:19], v[12:13]
	v_mul_f32_e32 v27, 0xbfb8aa3b, v24
	v_exp_f32_e32 v27, v27
	v_mul_f32_e32 v26, 0xbfb8aa3b, v18
	v_exp_f32_e32 v26, v26
	v_pk_fma_f32 v[16:17], v[2:3], v[16:17], v[10:11]
	v_add_f32_e32 v27, 1.0, v27
	v_rcp_f32_e32 v30, v27
	v_mul_f32_e32 v27, 0xbfb8aa3b, v19
	v_exp_f32_e32 v27, v27
	v_add_f32_e32 v26, 1.0, v26
	v_rcp_f32_e32 v26, v26
	v_pk_fma_f32 v[28:29], v[6:7], v[28:29], v[14:15]
	v_add_f32_e32 v27, 1.0, v27
	v_rcp_f32_e32 v27, v27
	s_nop 0
	v_pk_mul_f32 v[18:19], v[18:19], v[26:27]
	v_mul_f32_e32 v26, 0xbfb8aa3b, v25
	v_exp_f32_e32 v26, v26
	v_mul_f32_e32 v27, 0xbfb8aa3b, v16
	v_exp_f32_e32 v27, v27
	v_add_f32_e32 v26, 1.0, v26
	v_rcp_f32_e32 v31, v26
	v_add_f32_e32 v27, 1.0, v27
	v_mul_f32_e32 v26, 0xbfb8aa3b, v28
	v_exp_f32_e32 v26, v26
	v_pk_mul_f32 v[24:25], v[24:25], v[30:31]
	v_rcp_f32_e32 v30, v27
	v_mul_f32_e32 v27, 0xbfb8aa3b, v29
	v_exp_f32_e32 v27, v27
	v_add_f32_e32 v26, 1.0, v26
	v_rcp_f32_e32 v26, v26
	v_add_f32_e32 v27, 1.0, v27
	v_rcp_f32_e32 v27, v27
	s_nop 0
	v_pk_mul_f32 v[26:27], v[28:29], v[26:27]
	v_mul_f32_e32 v28, 0xbfb8aa3b, v17
	v_exp_f32_e32 v28, v28
	s_nop 0
	v_add_f32_e32 v28, 1.0, v28
	v_rcp_f32_e32 v31, v28
	s_nop 0
	v_pk_mul_f32 v[28:29], v[16:17], v[30:31]
	v_cvt_pk_bf16_f32 v16, v18, v19
	v_cvt_pk_bf16_f32 v18, v24, v25
	v_add_u32_e32 v24, 1, v52
	v_ashrrev_i32_e32 v25, 31, v24
	v_lshlrev_b64 v[24:25], 12, v[24:25]
	v_lshl_add_u64 v[24:25], s[18:19], 0, v[24:25]
	v_lshl_add_u64 v[24:25], v[24:25], 0, v[152:153]
	v_add_co_u32_e32 v24, vcc, s15, v24
	v_cvt_pk_bf16_f32 v17, v26, v27
	v_cvt_pk_bf16_f32 v19, v28, v29
	v_addc_co_u32_e32 v25, vcc, 0, v25, vcc
	global_store_dwordx4 v[24:25], v[16:19], off offset:2048
	v_mov_b32_e32 v24, v41
	v_mov_b32_e32 v25, v43
	v_pk_mov_b32 v[16:17], v[56:57], v[54:55] op_sel:[1,0]
	v_mov_b32_e32 v18, v56
	v_mov_b32_e32 v19, v55
	v_pk_add_f32 v[16:17], v[16:17], v[18:19]
	v_mov_b32_e32 v18, v40
	v_mov_b32_e32 v19, v42
	v_pk_add_f32 v[18:19], v[18:19], v[24:25]
	v_add_f32_e32 v16, v16, v17
	v_add_f32_e32 v16, v19, v16
	v_add_f32_e32 v16, v18, v16
	ds_bpermute_b32 v17, v91, v16
	v_mov_b32_e32 v28, v60
	v_mov_b32_e32 v29, v59
	v_mov_b32_e32 v30, v21
	v_mov_b32_e32 v31, v23
	s_waitcnt lgkmcnt(0)
	v_add_f32_e32 v16, v16, v17
	ds_bpermute_b32 v17, v93, v16
	s_waitcnt lgkmcnt(0)
	v_add_f32_e32 v16, v16, v17
	ds_bpermute_b32 v17, v95, v16
	s_waitcnt lgkmcnt(0)
	v_add_f32_e32 v16, v16, v17
	ds_bpermute_b32 v17, v97, v16
	s_waitcnt lgkmcnt(0)
	v_add_f32_e32 v16, v16, v17
	ds_bpermute_b32 v17, v98, v16
	s_waitcnt lgkmcnt(0)
	v_add_f32_e32 v16, v16, v17
	ds_bpermute_b32 v17, v99, v16
	s_waitcnt lgkmcnt(0)
	v_add_f32_e32 v16, v16, v17
	v_fmamk_f32 v57, v16, 0xbb000000, v57
	v_fmac_f32_e32 v56, 0xbb000000, v16
	v_fmamk_f32 v55, v16, 0xbb000000, v55
	v_fmac_f32_e32 v54, 0xbb000000, v16
	v_fmamk_f32 v43, v16, 0xbb000000, v43
	v_fmac_f32_e32 v42, 0xbb000000, v16
	v_fmamk_f32 v41, v16, 0xbb000000, v41
	v_fmac_f32_e32 v40, 0xbb000000, v16
	v_pk_mul_f32 v[16:17], v[54:55], v[54:55]
	v_pk_mul_f32 v[18:19], v[56:57], v[56:57]
	s_nop 0
	v_pk_mov_b32 v[24:25], v[18:19], v[16:17] op_sel:[1,0]
	v_mov_b32_e32 v19, v17
	v_pk_add_f32 v[16:17], v[24:25], v[18:19]
	v_pk_mul_f32 v[18:19], v[40:41], v[40:41]
	v_pk_mul_f32 v[24:25], v[42:43], v[42:43]
	v_mov_b32_e32 v26, v18
	v_mov_b32_e32 v27, v24
	v_mov_b32_e32 v24, v19
	v_pk_add_f32 v[18:19], v[26:27], v[24:25]
	v_pk_mov_b32 v[26:27], v[60:61], v[58:59] op_sel:[1,0]
	v_add_u32_e32 v24, 2, v52
	v_pk_add_f32 v[26:27], v[26:27], v[28:29]
	v_mov_b32_e32 v28, v20
	v_mov_b32_e32 v29, v22
	v_pk_add_f32 v[28:29], v[28:29], v[30:31]
	v_add_f32_e32 v26, v26, v27
	v_add_f32_e32 v26, v29, v26
	v_add_f32_e32 v26, v28, v26
	ds_bpermute_b32 v27, v91, v26
	v_ashrrev_i32_e32 v25, 31, v24
	v_lshlrev_b64 v[24:25], 12, v[24:25]
	v_lshl_add_u64 v[24:25], s[18:19], 0, v[24:25]
	v_lshl_add_u64 v[24:25], v[24:25], 0, v[152:153]
	s_waitcnt lgkmcnt(0)
	v_add_f32_e32 v26, v26, v27
	ds_bpermute_b32 v27, v93, v26
	s_waitcnt lgkmcnt(0)
	v_add_f32_e32 v26, v26, v27
	ds_bpermute_b32 v27, v95, v26
	s_waitcnt lgkmcnt(0)
	v_add_f32_e32 v26, v26, v27
	ds_bpermute_b32 v27, v97, v26
	s_waitcnt lgkmcnt(0)
	v_add_f32_e32 v26, v26, v27
	ds_bpermute_b32 v27, v98, v26
	s_waitcnt lgkmcnt(0)
	v_add_f32_e32 v26, v26, v27
	ds_bpermute_b32 v27, v99, v26
	s_waitcnt lgkmcnt(0)
	v_add_f32_e32 v26, v26, v27
	v_fmamk_f32 v61, v26, 0xbb000000, v61
	v_fmac_f32_e32 v60, 0xbb000000, v26
	v_fmamk_f32 v59, v26, 0xbb000000, v59
	v_fmac_f32_e32 v58, 0xbb000000, v26
	v_fmamk_f32 v23, v26, 0xbb000000, v23
	v_fmac_f32_e32 v22, 0xbb000000, v26
	v_fmamk_f32 v21, v26, 0xbb000000, v21
	v_fmac_f32_e32 v20, 0xbb000000, v26
	v_pk_mul_f32 v[26:27], v[58:59], v[58:59]
	v_pk_mul_f32 v[28:29], v[60:61], v[60:61]
	s_nop 0
	v_pk_mov_b32 v[30:31], v[28:29], v[26:27] op_sel:[1,0]
	v_mov_b32_e32 v29, v27
	v_pk_add_f32 v[26:27], v[30:31], v[28:29]
	v_pk_mul_f32 v[28:29], v[20:21], v[20:21]
	v_pk_mul_f32 v[30:31], v[22:23], v[22:23]
	v_mov_b32_e32 v32, v28
	v_mov_b32_e32 v33, v30
	v_mov_b32_e32 v30, v29
	v_pk_add_f32 v[28:29], v[32:33], v[30:31]
	v_mov_b32_e32 v30, v26
	v_mov_b32_e32 v31, v16
	v_mov_b32_e32 v16, v27
	v_pk_add_f32 v[16:17], v[30:31], v[16:17]
	v_mov_b32_e32 v26, v29
	v_mov_b32_e32 v27, v19
	v_pk_add_f32 v[16:17], v[26:27], v[16:17]
	v_mov_b32_e32 v29, v18
	v_pk_add_f32 v[16:17], v[28:29], v[16:17]
	ds_bpermute_b32 v19, v91, v17
	ds_bpermute_b32 v18, v91, v16
	s_waitcnt lgkmcnt(0)
	v_pk_add_f32 v[16:17], v[16:17], v[18:19]
	ds_bpermute_b32 v19, v93, v17
	ds_bpermute_b32 v18, v93, v16
	s_waitcnt lgkmcnt(0)
	v_pk_add_f32 v[16:17], v[16:17], v[18:19]
	ds_bpermute_b32 v19, v95, v17
	ds_bpermute_b32 v18, v95, v16
	s_waitcnt lgkmcnt(0)
	v_pk_add_f32 v[16:17], v[16:17], v[18:19]
	ds_bpermute_b32 v19, v97, v17
	ds_bpermute_b32 v18, v97, v16
	s_waitcnt lgkmcnt(0)
	v_pk_add_f32 v[16:17], v[16:17], v[18:19]
	ds_bpermute_b32 v19, v98, v17
	ds_bpermute_b32 v18, v98, v16
	s_waitcnt lgkmcnt(0)
	v_pk_add_f32 v[16:17], v[16:17], v[18:19]
	ds_bpermute_b32 v19, v99, v17
	ds_bpermute_b32 v18, v99, v16
	s_waitcnt lgkmcnt(0)
	v_pk_add_f32 v[16:17], v[16:17], v[18:19]
	s_nop 0
	v_pk_fma_f32 v[26:27], v[16:17], s[20:21], v[62:63] op_sel_hi:[1,0,0]
	s_nop 0
	v_mul_f32_e32 v16, 0x4b800000, v27
	v_cmp_gt_f32_e64 s[8:9], s68, v27
	v_cmp_gt_f32_e32 vcc, s68, v26
	s_nop 0
	v_cndmask_b32_e64 v16, v27, v16, s[8:9]
	v_rsq_f32_e32 v16, v16
	s_nop 0
	v_mul_f32_e32 v17, 0x45800000, v16
	v_cndmask_b32_e64 v16, v16, v17, s[8:9]
	v_pk_mul_f32 v[18:19], v[56:57], v[16:17] op_sel_hi:[1,0]
	v_pk_mul_f32 v[30:31], v[42:43], v[16:17] op_sel_hi:[1,0]
	v_pk_fma_f32 v[18:19], v[4:5], v[18:19], v[12:13]
	v_pk_fma_f32 v[30:31], v[0:1], v[30:31], v[8:9]
	v_mul_f32_e32 v27, 0xbfb8aa3b, v18
	v_exp_f32_e32 v27, v27
	v_pk_mul_f32 v[28:29], v[54:55], v[16:17] op_sel_hi:[1,0]
	v_pk_mul_f32 v[16:17], v[40:41], v[16:17] op_sel_hi:[1,0]
	v_pk_fma_f32 v[28:29], v[6:7], v[28:29], v[14:15]
	v_add_f32_e32 v27, 1.0, v27
	v_rcp_f32_e32 v32, v27
	v_mul_f32_e32 v27, 0xbfb8aa3b, v30
	v_exp_f32_e32 v27, v27
	v_pk_fma_f32 v[16:17], v[2:3], v[16:17], v[10:11]
	v_add_co_u32_e64 v24, s[8:9], s15, v24
	v_add_f32_e32 v27, 1.0, v27
	v_rcp_f32_e32 v34, v27
	v_mul_f32_e32 v27, 0xbfb8aa3b, v19
	v_exp_f32_e32 v27, v27
	v_addc_co_u32_e64 v25, s[8:9], 0, v25, s[8:9]
	v_add_f32_e32 v27, 1.0, v27
	v_rcp_f32_e32 v33, v27
	v_mul_f32_e32 v27, 0xbfb8aa3b, v31
	v_exp_f32_e32 v27, v27
	v_pk_mul_f32 v[18:19], v[18:19], v[32:33]
	v_add_f32_e32 v27, 1.0, v27
	v_rcp_f32_e32 v35, v27
	v_mul_f32_e32 v27, 0xbfb8aa3b, v28
	v_exp_f32_e32 v27, v27
	v_pk_mul_f32 v[30:31], v[30:31], v[34:35]
	v_add_f32_e32 v27, 1.0, v27
	v_rcp_f32_e32 v32, v27
	v_mul_f32_e32 v27, 0xbfb8aa3b, v16
	v_exp_f32_e32 v27, v27
	s_nop 0
	v_add_f32_e32 v27, 1.0, v27
	v_rcp_f32_e32 v34, v27
	v_mul_f32_e32 v27, 0xbfb8aa3b, v29
	v_exp_f32_e32 v27, v27
	s_nop 0
	v_add_f32_e32 v27, 1.0, v27
	v_rcp_f32_e32 v33, v27
	v_mul_f32_e32 v27, 0xbfb8aa3b, v17
	v_exp_f32_e32 v27, v27
	v_pk_mul_f32 v[28:29], v[28:29], v[32:33]
	v_add_f32_e32 v27, 1.0, v27
	v_rcp_f32_e32 v35, v27
	s_nop 0
	v_pk_mul_f32 v[32:33], v[16:17], v[34:35]
	v_cvt_pk_bf16_f32 v16, v18, v19
	v_cvt_pk_bf16_f32 v17, v28, v29
	v_cvt_pk_bf16_f32 v18, v30, v31
	v_cvt_pk_bf16_f32 v19, v32, v33
	global_store_dwordx4 v[24:25], v[16:19], off offset:2048
	s_nop 1
	v_mul_f32_e32 v16, 0x4b800000, v26
	v_cndmask_b32_e32 v16, v26, v16, vcc
	v_rsq_f32_e32 v16, v16
	s_nop 0
	v_mul_f32_e32 v17, 0x45800000, v16
	v_cndmask_b32_e32 v16, v16, v17, vcc
	v_pk_mul_f32 v[18:19], v[60:61], v[16:17] op_sel_hi:[1,0]
	v_pk_mul_f32 v[24:25], v[58:59], v[16:17] op_sel_hi:[1,0]
	v_pk_fma_f32 v[4:5], v[4:5], v[18:19], v[12:13]
	v_pk_mul_f32 v[12:13], v[22:23], v[16:17] op_sel_hi:[1,0]
	v_pk_fma_f32 v[6:7], v[6:7], v[24:25], v[14:15]
	v_pk_fma_f32 v[0:1], v[0:1], v[12:13], v[8:9]
	v_pk_mul_f32 v[14:15], v[20:21], v[16:17] op_sel_hi:[1,0]
	v_mul_f32_e32 v9, 0xbfb8aa3b, v0
	v_exp_f32_e32 v9, v9
	v_pk_fma_f32 v[2:3], v[2:3], v[14:15], v[10:11]
	v_mul_f32_e32 v8, 0xbfb8aa3b, v4
	v_exp_f32_e32 v8, v8
	v_add_f32_e32 v9, 1.0, v9
	v_rcp_f32_e32 v10, v9
	v_mul_f32_e32 v9, 0xbfb8aa3b, v5
	v_exp_f32_e32 v9, v9
	v_add_f32_e32 v8, 1.0, v8
	v_rcp_f32_e32 v8, v8
	v_add_f32_e32 v9, 1.0, v9
	v_rcp_f32_e32 v9, v9
	s_nop 0
	v_pk_mul_f32 v[4:5], v[4:5], v[8:9]
	v_mul_f32_e32 v8, 0xbfb8aa3b, v1
	v_exp_f32_e32 v8, v8
	s_nop 0
	v_add_f32_e32 v8, 1.0, v8
	v_rcp_f32_e32 v11, v8
	s_nop 0
	v_pk_mul_f32 v[8:9], v[0:1], v[10:11]
	v_mul_f32_e32 v1, 0xbfb8aa3b, v2
	v_exp_f32_e32 v1, v1
	v_mul_f32_e32 v0, 0xbfb8aa3b, v6
	v_exp_f32_e32 v0, v0
	v_add_f32_e32 v1, 1.0, v1
	v_rcp_f32_e32 v10, v1
	v_mul_f32_e32 v1, 0xbfb8aa3b, v7
	v_exp_f32_e32 v1, v1
	v_add_f32_e32 v0, 1.0, v0
	v_rcp_f32_e32 v0, v0
	v_add_f32_e32 v1, 1.0, v1
	v_rcp_f32_e32 v1, v1
	s_nop 0
	v_pk_mul_f32 v[6:7], v[6:7], v[0:1]
	v_mul_f32_e32 v0, 0xbfb8aa3b, v3
	v_exp_f32_e32 v0, v0
	v_cvt_pk_bf16_f32 v1, v6, v7
	v_add_f32_e32 v0, 1.0, v0
	v_rcp_f32_e32 v11, v0
	v_cvt_pk_bf16_f32 v0, v4, v5
	v_add_u32_e32 v4, 3, v52
	v_ashrrev_i32_e32 v5, 31, v4
	v_lshlrev_b64 v[4:5], 12, v[4:5]
	v_lshl_add_u64 v[4:5], s[18:19], 0, v[4:5]
	v_lshl_add_u64 v[4:5], v[4:5], 0, v[152:153]
	v_add_co_u32_e32 v4, vcc, 0x7f00000, v4
	v_pk_mul_f32 v[10:11], v[2:3], v[10:11]
	s_nop 0
	v_addc_co_u32_e32 v5, vcc, 0, v5, vcc
	v_cmp_lt_i32_e32 vcc, s2, v87
	v_cvt_pk_bf16_f32 v2, v8, v9
	v_cvt_pk_bf16_f32 v3, v10, v11
	v_add_u32_e32 v52, s96, v52
	s_or_b64 s[12:13], vcc, s[12:13]
	global_store_dwordx4 v[4:5], v[0:3], off offset:2048
	s_andn2_b64 exec, exec, s[12:13]
	s_cbranch_execnz .LBB0_125

.LBB0_128:
	v_ashrrev_i32_e32 v5, 31, v4
	v_lshl_add_u64 v[10:11], v[4:5], 4, s[12:13]
	global_load_dwordx4 v[10:13], v[10:11], off
	s_waitcnt vmcnt(0) lgkmcnt(0)
	v_mov_b32_e32 v14, v11
	v_mov_b32_e32 v15, v12
	v_mov_b32_e32 v11, v13
	v_pk_add_f32 v[10:11], v[14:15], v[10:11]
	s_nop 0
	v_add_f32_e32 v5, v10, v11
	v_fmamk_f32 v5, v5, 0x3b800000, v207
	v_cmp_gt_f32_e32 vcc, s68, v5
	v_mul_f32_e32 v7, 0x4b800000, v5
	s_nop 0
	v_cndmask_b32_e32 v5, v5, v7, vcc
	v_rsq_f32_e32 v5, v5
	s_nop 0
	v_mul_f32_e32 v7, 0x45800000, v5
	v_cndmask_b32_e32 v14, v5, v7, vcc
	v_ashrrev_i32_e32 v5, 7, v4
	v_and_b32_e32 v5, -2, v5
	v_add_u32_e32 v10, s39, v5
	v_ashrrev_i32_e32 v11, 31, v10
	v_and_b32_e32 v5, 0xff00, v8
	v_lshlrev_b64 v[10:11], 18, v[10:11]
	v_lshl_add_u64 v[10:11], s[40:41], 0, v[10:11]
	v_lshlrev_b32_e32 v152, 2, v5
	v_lshl_add_u64 v[10:11], v[10:11], 0, v[152:153]
	v_mov_b32_e32 v7, v153
	v_lshl_add_u64 v[16:17], v[10:11], 0, v[6:7]
	global_load_dwordx4 v[10:13], v[16:17], off
	v_add_u32_e32 v4, s38, v4
	v_cmp_lt_i32_e32 vcc, s33, v4
	v_add_u32_e32 v8, s2, v8
	s_or_b64 s[10:11], vcc, s[10:11]
	s_waitcnt vmcnt(0) lgkmcnt(0)
	v_pk_mul_f32 v[10:11], v[10:11], v[14:15] op_sel_hi:[1,0]
	v_pk_mul_f32 v[12:13], v[12:13], v[14:15] op_sel_hi:[1,0]
	v_pk_mul_f32 v[10:11], v[0:1], v[10:11]
	v_pk_mul_f32 v[12:13], v[2:3], v[12:13]
	global_store_dwordx4 v[16:17], v[10:13], off
	s_andn2_b64 exec, exec, s[10:11]
	s_cbranch_execnz .LBB0_128

.LBB0_130:
	v_readlane_b32 s4, v251, 31
	v_readlane_b32 s5, v251, 32
	s_and_b64 vcc, exec, s[4:5]
	v_readlane_b32 s87, v254, 30
	v_readlane_b32 s86, v254, 29
	s_cbranch_vccz .LBB0_141
	v_readlane_b32 s10, v251, 33
	v_readlane_b32 s11, v251, 34
	s_and_b64 s[4:5], s[10:11], exec
	v_readlane_b32 s2, v251, 45
	v_readlane_b32 s4, v254, 30
	s_cselect_b32 s2, s2, s4
	v_readlane_b32 s4, v254, 29
	s_cselect_b32 s8, 3, s4
	v_readlane_b32 s4, v253, 25
	v_readlane_b32 s5, v253, 26
	s_and_b64 s[4:5], s[4:5], exec
	v_readlane_b32 s4, v253, 27
	s_cselect_b32 s87, s4, s2
	v_readlane_b32 s2, v253, 28
	v_mov_b32_e32 v2, v206
	s_cselect_b32 s86, s2, s8
	s_movk_i32 s2, 0x100
	s_nop 0
	v_cmp_gt_i32_e32 vcc, s2, v2
	s_and_b64 s[4:5], s[10:11], vcc
	s_and_saveexec_b64 s[8:9], s[4:5]
	s_cbranch_execz .LBB0_140
	v_lshl_add_u32 v0, s87, 8, v2
	s_cmp_lt_i32 s86, 4
	s_mov_b64 s[10:11], -1
	s_cbranch_scc1 .LBB0_136
	s_cmp_eq_u32 s86, 4
	v_mov_b32_e32 v1, 1.0
	s_cbranch_scc0 .LBB0_135
	v_readlane_b32 s4, v254, 50
	v_ashrrev_i32_e32 v1, 31, v0
	v_readlane_b32 s5, v254, 51
	s_nop 1
	v_lshl_add_u64 v[4:5], v[0:1], 4, s[4:5]
	global_load_dwordx4 v[4:7], v[4:5], off
	s_waitcnt vmcnt(0) lgkmcnt(0)
	v_mov_b32_e32 v8, v5
	v_mov_b32_e32 v9, v6
	v_mov_b32_e32 v5, v7
	v_pk_add_f32 v[4:5], v[8:9], v[4:5]
	s_nop 0
	v_add_f32_e32 v1, v4, v5
	v_fmamk_f32 v1, v1, 0x3b800000, v207
	v_mul_f32_e32 v3, 0x4b800000, v1
	v_cmp_gt_f32_e32 vcc, s68, v1
	s_nop 1
	v_cndmask_b32_e32 v1, v1, v3, vcc
	v_rsq_f32_e32 v1, v1
	s_nop 0
	v_mul_f32_e32 v3, 0x45800000, v1
	v_cndmask_b32_e32 v1, v1, v3, vcc

.LBB0_136:
	s_andn2_b64 vcc, exec, s[10:11]
	s_cbranch_vccnz .LBB0_139
	s_cmp_lg_u32 s86, 3
	v_mov_b32_e32 v1, 1.0
	s_cbranch_scc1 .LBB0_139
	v_ashrrev_i32_e32 v1, 31, v0
	v_readlane_b32 s4, v254, 54
	v_lshlrev_b64 v[0:1], 5, v[0:1]
	v_readlane_b32 s5, v254, 55
	s_nop 1
	v_lshl_add_u64 v[0:1], s[4:5], 0, v[0:1]
	global_load_dwordx4 v[4:7], v[0:1], off
	global_load_dwordx4 v[8:11], v[0:1], off offset:16
	s_waitcnt vmcnt(0) lgkmcnt(0)
	v_mov_b32_e32 v0, v4
	v_mov_b32_e32 v1, v8
	v_mov_b32_e32 v8, v5
	v_mov_b32_e32 v4, v6
	v_mov_b32_e32 v5, v10
	v_mov_b32_e32 v10, v7
	v_pk_add_f32 v[0:1], v[0:1], v[8:9]
	v_pk_add_f32 v[4:5], v[4:5], v[10:11]
	s_nop 0
	v_pk_add_f32 v[0:1], v[0:1], v[4:5]
	s_nop 0
	v_add_f32_e32 v0, v0, v1
	v_fmamk_f32 v0, v0, 0x3b000000, v207
	v_mul_f32_e32 v1, 0x4b800000, v0
	v_cmp_gt_f32_e32 vcc, s68, v0
	s_nop 1
	v_cndmask_b32_e32 v0, v0, v1, vcc
	v_rsq_f32_e32 v0, v0
	s_nop 0
	v_mul_f32_e32 v1, 0x45800000, v0
	v_cndmask_b32_e32 v0, v0, v1, vcc
	v_mul_f32_e32 v1, 0x3e16c740, v0

.LBB0_145:
	v_lshrrev_b32_e32 v8, 13, v6
	v_and_b32_e32 v8, 6, v8
	v_add_u32_e32 v152, s39, v8
	v_lshlrev_b64 v[8:9], 18, v[152:153]
	v_lshlrev_b32_e32 v10, 4, v6
	v_and_b32_e32 v12, 0xfc, v4
	s_waitcnt lgkmcnt(0)
	v_lshl_add_u64 v[8:9], s[88:89], 0, v[8:9]
	v_and_b32_e32 v152, 0x3fc00, v10
	v_lshl_add_u64 v[8:9], v[8:9], 0, v[152:153]
	v_lshlrev_b32_e32 v152, 2, v12
	v_lshl_add_u64 v[8:9], v[8:9], 0, v[152:153]
	global_load_dwordx4 v[8:11], v[8:9], off
	v_lshrrev_b32_e32 v3, 6, v6
	v_lshlrev_b32_e32 v152, 1, v12
	v_lshl_add_u64 v[6:7], v[6:7], 0, s[24:25]
	v_lshl_add_u64 v[4:5], v[4:5], 0, s[12:13]
	s_waitcnt vmcnt(0)
	v_cvt_pk_bf16_f32 v8, v8, v9
	v_cvt_pk_bf16_f32 v9, v10, v11
	v_mov_b64_e32 v[10:11], s[18:19]
	v_mad_u64_u32 v[10:11], s[4:5], v3, s2, v[10:11]
	v_lshl_add_u64 v[10:11], v[10:11], 0, v[152:153]
	v_add_co_u32_e32 v10, vcc, 0x10b00000, v10
	s_mov_b64 s[4:5], 0xffff
	s_nop 0
	v_addc_co_u32_e32 v11, vcc, 0, v11, vcc
	v_cmp_lt_u64_e32 vcc, s[4:5], v[6:7]
	s_or_b64 s[10:11], vcc, s[10:11]
	global_store_dwordx2 v[10:11], v[8:9], off offset:1024
	s_andn2_b64 exec, exec, s[10:11]
	s_cbranch_execnz .LBB0_145

.LBB0_153:
	v_alignbit_b32 v21, v13, v12, 5
	v_alignbit_b32 v20, v11, v10, 5
	v_lshrrev_b32_e32 v22, 8, v21
	v_lshrrev_b32_e32 v23, 8, v20
	v_lshl_add_u32 v152, v22, 1, s39
	v_lshl_add_u32 v16, v23, 1, s2
	v_mov_b32_e32 v17, v153
	v_and_b32_e32 v25, 0x1fe0, v12
	v_lshlrev_b64 v[18:19], 15, v[152:153]
	v_and_b32_e32 v24, 0x1fe0, v10
	v_lshlrev_b64 v[16:17], 15, v[16:17]
	s_waitcnt lgkmcnt(0)
	v_lshl_add_u64 v[18:19], s[90:91], 0, v[18:19]
	v_lshlrev_b32_e32 v152, 2, v25
	v_lshl_add_u64 v[16:17], s[90:91], 0, v[16:17]
	v_lshl_add_u64 v[18:19], v[18:19], 0, v[152:153]
	v_lshlrev_b32_e32 v152, 2, v24
	v_lshlrev_b32_e32 v24, 1, v12
	v_lshl_add_u64 v[16:17], v[16:17], 0, v[152:153]
	v_and_b32_e32 v152, 32, v24
	v_lshlrev_b32_e32 v24, 1, v10
	v_lshl_add_u64 v[18:19], v[18:19], 0, v[152:153]
	v_and_b32_e32 v152, 32, v24
	v_lshl_add_u64 v[16:17], v[16:17], 0, v[152:153]
	v_lshlrev_b32_e32 v152, 2, v3
	v_lshlrev_b32_e32 v24, 3, v12
	v_lshl_add_u64 v[18:19], v[18:19], 0, v[152:153]
	v_lshl_add_u64 v[16:17], v[16:17], 0, v[152:153]
	v_and_b32_e32 v152, 64, v24
	v_lshlrev_b32_e32 v24, 3, v10
	v_lshl_add_u64 v[18:19], v[18:19], 0, v[152:153]
	v_and_b32_e32 v152, 64, v24
	v_lshl_add_u64 v[16:17], v[16:17], 0, v[152:153]
	global_load_dword v18, v[18:19], off
	s_nop 0
	global_load_dword v16, v[16:17], off
	v_mul_u32_u24_e32 v17, 0x500, v22
	v_or_b32_sdwa v17, v17, v21 dst_sel:DWORD dst_unused:UNUSED_PAD src0_sel:DWORD src1_sel:BYTE_0
	v_add_u32_e32 v152, 0x1000, v17
	v_lshl_add_u64 v[14:15], v[14:15], 0, -2
	v_mov_b32_e32 v17, v153
	v_cmp_eq_u64_e32 vcc, 0, v[14:15]
	v_lshl_add_u64 v[10:11], v[10:11], 0, s[78:79]
	v_lshl_add_u64 v[12:13], v[12:13], 0, s[80:81]
	s_or_b64 s[10:11], vcc, s[10:11]
	s_waitcnt vmcnt(0)
	v_cvt_pk_bf16_f32 v24, v18, v16
	v_mul_u32_u24_e32 v16, 0x500, v23
	v_or_b32_sdwa v16, v16, v20 dst_sel:DWORD dst_unused:UNUSED_PAD src0_sel:DWORD src1_sel:BYTE_0
	v_add_u32_e32 v16, 0x1000, v16
	v_lshlrev_b64 v[18:19], 6, v[152:153]
	v_lshlrev_b64 v[16:17], 6, v[16:17]
	v_lshl_add_u64 v[18:19], v[4:5], 0, v[18:19]
	v_lshl_add_u64 v[16:17], v[4:5], 0, v[16:17]
	global_store_short v[18:19], v24, off
	global_store_short_d16_hi v[16:17], v24, off
	s_andn2_b64 exec, exec, s[10:11]
	s_cbranch_execnz .LBB0_153
	s_or_b64 exec, exec, s[10:11]
	v_mad_u64_u32 v[10:11], s[4:5], v8, s24, v[0:1]
	v_mul_lo_u32 v12, v8, s25
	v_mul_lo_u32 v13, v9, s24
	v_cmp_ne_u64_e32 vcc, v[6:7], v[8:9]
	v_add3_u32 v11, v13, v11, v12
	s_orn2_b64 s[10:11], vcc, exec

.LBB0_157:
	v_alignbit_b32 v3, v11, v10, 5
	v_lshrrev_b32_e32 v14, 8, v3
	v_lshl_add_u32 v152, v14, 1, s39
	v_and_b32_e32 v9, 0x1fe0, v10
	v_lshlrev_b64 v[12:13], 15, v[152:153]
	s_waitcnt lgkmcnt(0)
	v_lshl_add_u64 v[12:13], s[90:91], 0, v[12:13]
	v_lshlrev_b32_e32 v152, 2, v9
	v_lshlrev_b32_e32 v9, 1, v10
	v_lshl_add_u64 v[12:13], v[12:13], 0, v[152:153]
	v_and_b32_e32 v152, 32, v9
	v_and_b32_e32 v15, 16, v6
	v_lshl_add_u64 v[12:13], v[12:13], 0, v[152:153]
	v_mov_b32_e32 v9, v153
	v_lshl_add_u64 v[12:13], v[12:13], 0, v[8:9]
	v_lshlrev_b32_e32 v152, 2, v15
	v_lshl_add_u64 v[12:13], v[12:13], 0, v[152:153]
	global_load_dword v9, v[12:13], off
	v_mul_u32_u24_e32 v12, 0x500, v14
	s_movk_i32 s2, 0xff
	v_and_or_b32 v3, v3, s2, v12
	v_add_u32_e32 v152, 0x1000, v3
	v_lshl_add_u64 v[10:11], v[10:11], 0, s[24:25]
	s_mov_b64 s[4:5], 0x7fff
	v_lshlrev_b64 v[12:13], 6, v[152:153]
	v_cmp_lt_u64_e32 vcc, s[4:5], v[10:11]
	v_lshl_add_u64 v[12:13], v[4:5], 0, v[12:13]
	v_lshl_add_u64 v[6:7], v[6:7], 0, s[80:81]
	s_or_b64 s[8:9], vcc, s[8:9]
	s_waitcnt vmcnt(0)
	v_cvt_pk_bf16_f32 v9, v9, s0
	global_store_short v[12:13], v9, off
	s_andn2_b64 exec, exec, s[8:9]
	s_cbranch_execnz .LBB0_157

.LBB0_160:
	v_bfe_u32 v11, v0, 15, 1
	v_lshlrev_b32_e32 v5, 3, v11
	global_load_dwordx2 v[6:7], v5, s[0:1] offset:32
	v_lshrrev_b32_e32 v5, 17, v0
	v_and_b32_e32 v5, 6, v5
	v_add_u32_e32 v152, s39, v5
	v_lshrrev_b32_e32 v5, 9, v0
	v_bfe_u32 v10, v0, 8, 7
	v_lshlrev_b64 v[8:9], 9, v[152:153]
	v_and_b32_e32 v5, 0x180, v5
	v_or3_b32 v8, v8, v5, v10
	v_lshlrev_b64 v[8:9], 10, v[8:9]
	v_mov_b32_e32 v5, v153
	s_mov_b64 s[4:5], 0xfffff
	s_waitcnt vmcnt(0)
	v_lshl_add_u64 v[6:7], v[6:7], 0, v[8:9]
	v_lshl_add_u64 v[6:7], v[6:7], 0, v[4:5]
	global_load_dword v5, v[6:7], off
	v_and_b32_e32 v6, 0xf0000, v0
	v_lshlrev_b32_e32 v152, 2, v6
	v_lshl_add_u64 v[6:7], s[22:23], 0, v[152:153]
	v_lshlrev_b32_e32 v152, 17, v11
	v_lshl_add_u64 v[6:7], v[6:7], 0, v[152:153]
	v_lshl_add_u64 v[0:1], v[0:1], 0, s[24:25]
	v_lshl_add_u64 v[6:7], v[6:7], 0, v[2:3]
	v_lshlrev_b32_e32 v152, 2, v10
	v_cmp_lt_u64_e32 vcc, s[4:5], v[0:1]
	v_lshl_add_u64 v[6:7], v[6:7], 0, v[152:153]
	s_or_b64 s[10:11], vcc, s[10:11]
	s_waitcnt vmcnt(0)
	global_store_dword v[6:7], v5, off
	s_andn2_b64 exec, exec, s[10:11]
	s_cbranch_execnz .LBB0_160

.LBB0_167:
	s_and_b32 s5, s5, 3
	v_readlane_b32 s2, v254, 37
	s_or_b32 s2, s5, s2
	s_lshl_b64 s[16:17], s[2:3], 2
	v_readlane_b32 s76, v252, 15
	v_readlane_b32 s77, v252, 16
	s_add_u32 s20, s76, s16
	v_mov_b32_e32 v48, v206
	s_addc_u32 s21, s77, s17
	global_load_dword v32, v153, s[20:21]
	v_lshlrev_b32_e32 v0, 4, v48
	v_ashrrev_i32_e32 v49, 4, v48
	v_add_u32_e32 v2, 0x200, v48
	v_add_u32_e32 v3, 0x400, v48
	v_add_u32_e32 v4, 0x600, v48
	v_add_u32_e32 v5, 0x800, v48
	v_add_u32_e32 v6, 0xa00, v48
	v_add_u32_e32 v7, 0xc00, v48
	v_add_u32_e32 v8, 0xe00, v48
	v_and_b32_e32 v152, 0xf0, v0
	v_mad_i64_i32 v[0:1], s[20:21], s10, v49, 0
	v_ashrrev_i32_e32 v50, 4, v2
	v_ashrrev_i32_e32 v52, 4, v3
	v_ashrrev_i32_e32 v54, 4, v4
	v_ashrrev_i32_e32 v56, 4, v5
	v_ashrrev_i32_e32 v58, 4, v6
	v_ashrrev_i32_e32 v60, 4, v7
	v_ashrrev_i32_e32 v63, 4, v8
	v_readlane_b32 s78, v252, 17
	s_mul_i32 s13, s5, s10
	v_lshlrev_b64 v[16:17], 1, v[0:1]
	v_mad_i64_i32 v[0:1], s[20:21], s10, v50, 0
	v_mad_i64_i32 v[2:3], s[20:21], s10, v52, 0
	v_mad_i64_i32 v[4:5], s[20:21], s10, v54, 0
	v_mad_i64_i32 v[18:19], s[20:21], s10, v56, 0
	v_mad_i64_i32 v[20:21], s[20:21], s10, v58, 0
	v_mad_i64_i32 v[22:23], s[20:21], s10, v60, 0
	v_mad_i64_i32 v[24:25], s[10:11], s10, v63, 0
	v_readlane_b32 s79, v252, 18
	s_add_u32 s10, s78, s16
	s_addc_u32 s11, s79, s17
	s_ashr_i32 s9, s8, 31
	s_nop 0
	global_load_dword v64, v153, s[10:11]
	s_lshl_b64 s[10:11], s[8:9], 11
	s_lshl_b64 s[8:9], s[8:9], 10
	v_readlane_b32 s2, v254, 52
	s_add_u32 s2, s2, s8
	v_readlane_b32 s5, v254, 53
	s_addc_u32 s5, s5, s9
	s_lshl_b32 s8, s13, 8
	s_add_u32 s2, s2, s8
	s_addc_u32 s5, s5, 0
	s_lshl_b32 s16, s4, 8
	s_add_u32 s4, s2, s16
	s_addc_u32 s5, s5, 0
	v_lshlrev_b64 v[26:27], 1, v[0:1]
	v_lshlrev_b64 v[28:29], 1, v[2:3]
	v_lshl_add_u64 v[0:1], s[4:5], 0, v[152:153]
	v_lshlrev_b64 v[30:31], 1, v[4:5]
	v_lshl_add_u64 v[2:3], v[0:1], 0, v[16:17]
	v_lshl_add_u64 v[8:9], v[0:1], 0, v[26:27]
	v_lshl_add_u64 v[12:13], v[0:1], 0, v[28:29]
	v_lshl_add_u64 v[14:15], v[0:1], 0, v[30:31]
	global_load_dwordx4 v[4:7], v[2:3], off
	s_nop 0
	global_load_dwordx4 v[8:11], v[8:9], off
	s_nop 0
	global_load_dwordx4 v[0:3], v[12:13], off
	s_mov_b32 s17, 0xbfb8aa3b
	s_mov_b32 s20, 0x42ce8ed0
	s_mov_b32 s21, 0xc2b17218
	v_mov_b32_e32 v70, 0x7f800000
	v_add_u32_e32 v62, 0, v152
	v_ashrrev_i32_e32 v66, 6, v48
	v_and_b32_e32 v67, 15, v48
	v_bfe_u32 v68, v48, 4, 2
	v_readlane_b32 s80, v252, 19
	v_readlane_b32 s81, v252, 20
	v_lshl_or_b32 v69, v66, 5, v67
	v_readlane_b32 s82, v252, 21
	v_readlane_b32 s83, v252, 22
	v_lshlrev_b32_e32 v77, 3, v68
	v_readlane_b32 s76, v254, 3
	v_readlane_b32 s80, v254, 5
	v_readlane_b32 s78, v254, 7
	s_waitcnt vmcnt(0)
	v_mul_f32_e32 v12, 0xbfb8aa3b, v32
	v_fma_f32 v13, v32, s17, -v12
	v_rndne_f32_e32 v33, v12
	v_fmac_f32_e32 v13, 0xb2a5705f, v32
	v_sub_f32_e32 v12, v12, v33
	v_add_f32_e32 v12, v12, v13
	v_cvt_i32_f32_e32 v33, v33
	v_exp_f32_e32 v34, v12
	v_cmp_nlt_f32_e32 vcc, s20, v32
	v_cmp_ngt_f32_e64 s[8:9], s21, v32
	global_load_dwordx4 v[12:15], v[14:15], off
	v_ldexp_f32 v32, v34, v33
	v_cndmask_b32_e32 v32, 0, v32, vcc
	v_cndmask_b32_e64 v32, v70, v32, s[8:9]
	v_add_f32_e32 v65, 1.0, v32
	v_cmp_gt_f32_e32 vcc, s68, v65
	s_and_b64 s[4:5], vcc, exec
	v_readlane_b32 s4, v254, 41
	s_cselect_b32 s2, 32, 0
	s_add_u32 s4, s4, s10
	v_readlane_b32 s5, v254, 42
	s_addc_u32 s5, s5, s11
	s_lshl_b32 s8, s13, 9
	s_add_u32 s4, s4, s8
	s_addc_u32 s5, s5, 0
	s_add_u32 s4, s4, s16
	s_addc_u32 s5, s5, 0
	v_lshl_add_u64 v[32:33], s[4:5], 0, v[152:153]
	v_lshl_add_u64 v[16:17], v[32:33], 0, v[16:17]
	v_lshl_add_u64 v[26:27], v[32:33], 0, v[26:27]
	v_lshl_add_u64 v[28:29], v[32:33], 0, v[28:29]
	v_lshl_add_u64 v[30:31], v[32:33], 0, v[30:31]
	v_lshl_add_u64 v[34:35], v[18:19], 1, v[32:33]
	v_lshl_add_u64 v[36:37], v[20:21], 1, v[32:33]
	v_lshl_add_u64 v[40:41], v[22:23], 1, v[32:33]
	v_lshl_add_u64 v[44:45], v[24:25], 1, v[32:33]
	global_load_dwordx4 v[16:19], v[16:17], off
	s_nop 0
	global_load_dwordx4 v[20:23], v[26:27], off
	s_nop 0
	global_load_dwordx4 v[24:27], v[28:29], off
	s_nop 0
	global_load_dwordx4 v[28:31], v[30:31], off
	s_nop 0
	global_load_dwordx4 v[32:35], v[34:35], off
	s_nop 0
	global_load_dwordx4 v[36:39], v[36:37], off
	s_nop 0
	global_load_dwordx4 v[40:43], v[40:41], off
	s_nop 0
	global_load_dwordx4 v[44:47], v[44:45], off
	v_mad_u64_u32 v[48:49], s[4:5], v49, s73, v[62:63]
	v_mad_u64_u32 v[50:51], s[4:5], v50, s73, v[62:63]
	v_mad_u64_u32 v[52:53], s[4:5], v52, s73, v[62:63]
	v_mul_f32_e32 v49, 0xbfb8aa3b, v64
	v_fma_f32 v51, v64, s17, -v49
	v_rndne_f32_e32 v53, v49
	v_fmac_f32_e32 v51, 0xb2a5705f, v64
	v_sub_f32_e32 v49, v49, v53
	v_add_f32_e32 v49, v49, v51
	v_cvt_i32_f32_e32 v53, v53
	v_exp_f32_e32 v49, v49
	v_cmp_nlt_f32_e64 s[8:9], s20, v64
	v_cmp_ngt_f32_e64 s[10:11], s21, v64
	v_mad_u64_u32 v[54:55], s[4:5], v54, s73, v[62:63]
	v_ldexp_f32 v49, v49, v53
	v_cndmask_b32_e64 v49, 0, v49, s[8:9]
	v_cndmask_b32_e64 v49, v70, v49, s[10:11]
	v_mov_b32_e32 v55, 0x42000000
	v_add_f32_e32 v49, 1.0, v49
	v_cndmask_b32_e32 v51, 0, v55, vcc
	v_cmp_gt_f32_e32 vcc, s68, v49
	s_and_b64 s[4:5], vcc, exec
	v_ldexp_f32 v53, v65, s2
	s_cselect_b32 s2, 32, 0
	s_waitcnt lgkmcnt(0)
	ds_write_b128 v48, v[4:7]
	ds_write_b128 v50, v[8:11]
	v_ldexp_f32 v4, v49, s2
	v_log_f32_e32 v53, v53
	v_log_f32_e32 v4, v4
	v_mad_u64_u32 v[56:57], s[4:5], v56, s73, v[62:63]
	v_mad_u64_u32 v[58:59], s[4:5], v58, s73, v[62:63]
	v_mad_u64_u32 v[60:61], s[4:5], v60, s73, v[62:63]
	v_mad_u64_u32 v[62:63], s[4:5], v63, s73, v[62:63]
	s_ashr_i32 s13, s12, 31
	ds_write_b128 v52, v[0:3]
	s_waitcnt vmcnt(0)
	ds_write_b128 v54, v[12:15]
	s_lshl_b64 s[4:5], s[12:13], 18
	v_lshlrev_b32_e32 v3, 7, v67
	v_cndmask_b32_e32 v55, 0, v55, vcc
	v_lshl_add_u32 v0, v68, 4, 0
	v_mul_lo_u32 v1, v69, s73
	v_mul_u32_u24_e32 v2, 0x110, v67
	v_lshl_or_b32 v78, v66, 12, v3
	s_add_u32 s2, s58, s4
	v_lshlrev_b32_e32 v76, 2, v68
	v_xor_b32_e32 v80, 0x7f, v77
	v_or_b32_e32 v81, 1, v77
	v_xor_b32_e32 v82, 0x7e, v77
	v_or_b32_e32 v83, 2, v77
	v_xor_b32_e32 v84, 0x7d, v77
	v_or_b32_e32 v85, 3, v77
	v_xor_b32_e32 v86, 0x7c, v77
	v_or_b32_e32 v87, 4, v77
	v_xor_b32_e32 v88, 0x7b, v77
	v_or_b32_e32 v89, 5, v77
	v_xor_b32_e32 v90, 0x7a, v77
	v_or_b32_e32 v91, 6, v77
	v_xor_b32_e32 v92, 0x79, v77
	v_sub_f32_e32 v93, v53, v51
	v_sub_f32_e32 v94, v4, v55
	v_or_b32_e32 v95, 7, v77
	v_xor_b32_e32 v96, 0x78, v77
	v_or_b32_e32 v97, 32, v77
	v_xor_b32_e32 v98, 0x5f, v77
	v_or_b32_e32 v99, 33, v77
	v_xor_b32_e32 v100, 0x5e, v77
	v_or_b32_e32 v101, 34, v77
	v_xor_b32_e32 v102, 0x5d, v77
	v_or_b32_e32 v103, 35, v77
	v_xor_b32_e32 v104, 0x5c, v77
	v_or_b32_e32 v105, 36, v77
	v_xor_b32_e32 v106, 0x5b, v77
	v_or_b32_e32 v107, 37, v77
	v_xor_b32_e32 v108, 0x5a, v77
	v_or_b32_e32 v109, 38, v77
	v_xor_b32_e32 v110, 0x59, v77
	v_or_b32_e32 v111, 39, v77
	v_xor_b32_e32 v112, 0x58, v77
	v_or_b32_e32 v113, 64, v77
	v_xor_b32_e32 v114, 63, v77
	v_or_b32_e32 v115, 0x41, v77
	v_xor_b32_e32 v116, 62, v77
	v_or_b32_e32 v117, 0x42, v77
	v_xor_b32_e32 v118, 61, v77
	v_or_b32_e32 v119, 0x43, v77
	v_xor_b32_e32 v120, 60, v77
	v_or_b32_e32 v121, 0x44, v77
	v_xor_b32_e32 v122, 59, v77
	v_or_b32_e32 v123, 0x45, v77
	v_xor_b32_e32 v124, 58, v77
	v_or_b32_e32 v125, 0x46, v77
	v_xor_b32_e32 v126, 57, v77
	v_or_b32_e32 v127, 0x47, v77
	v_xor_b32_e32 v128, 56, v77
	v_or_b32_e32 v129, 0x60, v77
	v_xor_b32_e32 v130, 31, v77
	v_or_b32_e32 v131, 0x61, v77
	v_xor_b32_e32 v132, 30, v77
	v_or_b32_e32 v133, 0x62, v77
	v_xor_b32_e32 v134, 29, v77
	v_or_b32_e32 v135, 0x63, v77
	v_xor_b32_e32 v136, 28, v77
	v_or_b32_e32 v137, 0x64, v77
	v_xor_b32_e32 v138, 27, v77
	v_or_b32_e32 v139, 0x65, v77
	v_xor_b32_e32 v140, 26, v77
	v_or_b32_e32 v141, 0x66, v77
	v_xor_b32_e32 v142, 25, v77
	v_or_b32_e32 v143, 0x67, v77
	v_xor_b32_e32 v144, 24, v77
	v_ashrrev_i32_e32 v79, 31, v78
	s_addc_u32 s13, s59, s5
	s_mov_b64 s[10:11], 0
	s_mov_b64 s[8:9], -1
	v_add_u32_e32 v145, v0, v1
	v_add_u32_e32 v146, v0, v2
	v_readlane_b32 s77, v254, 4
	v_readlane_b32 s81, v254, 6
	v_readlane_b32 s79, v254, 8
	s_mov_b64 s[82:83], 0x10000
	v_readlane_b32 s84, v252, 23
	v_readlane_b32 s85, v252, 24
	v_readlane_b32 s86, v252, 25
	v_readlane_b32 s87, v252, 26
	v_readlane_b32 s88, v252, 27
	v_readlane_b32 s89, v252, 28
	v_readlane_b32 s90, v252, 29
	v_readlane_b32 s91, v252, 30
	ds_write_b128 v48, v[16:19] offset:34816
	ds_write_b128 v50, v[20:23] offset:34816
	ds_write_b128 v52, v[24:27] offset:34816
	ds_write_b128 v54, v[28:31] offset:34816
	ds_write_b128 v56, v[32:35] offset:34816
	ds_write_b128 v58, v[36:39] offset:34816
	ds_write_b128 v60, v[40:43] offset:34816
	ds_write_b128 v62, v[44:47] offset:34816
	s_waitcnt lgkmcnt(0)
	s_barrier
	s_branch .LBB0_169

.LBB0_169:
	v_cndmask_b32_e64 v0, v77, v80, s[8:9]
	v_cndmask_b32_e64 v147, v94, v93, s[8:9]
	v_cvt_f32_ubyte0_e32 v0, v0
	v_mul_f32_e64 v0, -v147, v0
	v_exp_f32_e32 v8, v0
	v_cndmask_b32_e64 v0, v81, v82, s[8:9]
	v_cvt_f32_ubyte0_e32 v0, v0
	v_mul_f32_e64 v0, -v147, v0
	v_exp_f32_e32 v9, v0
	v_cndmask_b32_e64 v0, v83, v84, s[8:9]
	v_cvt_f32_ubyte0_e32 v0, v0
	v_mul_f32_e64 v0, -v147, v0
	v_exp_f32_e32 v10, v0
	v_cndmask_b32_e64 v0, v85, v86, s[8:9]
	v_cvt_f32_ubyte0_e32 v0, v0
	v_mul_f32_e64 v0, -v147, v0
	v_exp_f32_e32 v11, v0
	v_cndmask_b32_e64 v0, v87, v88, s[8:9]
	v_cvt_f32_ubyte0_e32 v0, v0
	v_mul_f32_e64 v0, -v147, v0
	v_exp_f32_e32 v12, v0
	v_cndmask_b32_e64 v0, v89, v90, s[8:9]
	v_cvt_f32_ubyte0_e32 v0, v0
	v_mul_f32_e64 v0, -v147, v0
	v_exp_f32_e32 v13, v0
	v_cndmask_b32_e64 v0, v91, v92, s[8:9]
	v_cvt_f32_ubyte0_e32 v0, v0
	v_mul_f32_e64 v0, -v147, v0
	v_exp_f32_e32 v14, v0
	v_cndmask_b32_e64 v0, v95, v96, s[8:9]
	v_cvt_f32_ubyte0_e32 v0, v0
	v_mul_f32_e64 v0, -v147, v0
	v_exp_f32_e32 v15, v0
	ds_read_b128 v[0:3], v145 offset:34816
	ds_read_b128 v[64:67], v146 offset:30464
	s_lshl_b64 s[4:5], s[10:11], 2
	s_add_u32 s10, s2, s4
	s_addc_u32 s11, s13, s5
	s_waitcnt lgkmcnt(0)
	v_lshlrev_b32_e32 v4, 16, v0
	v_and_b32_e32 v5, 0xffff0000, v0
	v_pk_mul_f32 v[4:5], v[8:9], v[4:5]
	s_andn2_b64 vcc, exec, s[14:15]
	v_cvt_pk_bf16_f32 v0, v4, v5
	v_lshlrev_b32_e32 v4, 16, v1
	v_and_b32_e32 v5, 0xffff0000, v1
	v_pk_mul_f32 v[4:5], v[10:11], v[4:5]
	s_mov_b64 s[16:17], -1
	v_cvt_pk_bf16_f32 v1, v4, v5
	v_lshlrev_b32_e32 v4, 16, v2
	v_and_b32_e32 v5, 0xffff0000, v2
	v_pk_mul_f32 v[4:5], v[12:13], v[4:5]
	s_nop 0
	v_cvt_pk_bf16_f32 v2, v4, v5
	v_lshlrev_b32_e32 v4, 16, v3
	v_and_b32_e32 v5, 0xffff0000, v3
	v_pk_mul_f32 v[4:5], v[14:15], v[4:5]
	s_nop 0
	v_cvt_pk_bf16_f32 v3, v4, v5
	ds_read_b128 v[4:7], v145 offset:39168
	s_waitcnt lgkmcnt(0)
	v_lshlrev_b32_e32 v16, 16, v4
	v_and_b32_e32 v17, 0xffff0000, v4
	v_pk_mul_f32 v[8:9], v[8:9], v[16:17]
	s_nop 0
	v_cvt_pk_bf16_f32 v4, v8, v9
	v_lshlrev_b32_e32 v8, 16, v5
	v_and_b32_e32 v9, 0xffff0000, v5
	v_pk_mul_f32 v[8:9], v[10:11], v[8:9]
	s_nop 0
	v_cvt_pk_bf16_f32 v5, v8, v9
	v_lshlrev_b32_e32 v8, 16, v6
	v_and_b32_e32 v9, 0xffff0000, v6
	v_pk_mul_f32 v[8:9], v[12:13], v[8:9]
	s_nop 0
	v_cvt_pk_bf16_f32 v6, v8, v9
	v_lshlrev_b32_e32 v8, 16, v7
	v_and_b32_e32 v9, 0xffff0000, v7
	v_pk_mul_f32 v[8:9], v[14:15], v[8:9]
	ds_read_b128 v[12:15], v146 offset:26112
	v_cvt_pk_bf16_f32 v7, v8, v9
	ds_read_b128 v[8:11], v146
	s_waitcnt lgkmcnt(0)
	v_mfma_f32_16x16x32_bf16 v[56:59], v[8:11], v[0:3], 0
	v_mfma_f32_16x16x32_bf16 v[60:63], v[8:11], v[4:7], 0
	ds_read_b128 v[8:11], v146 offset:4352
	s_waitcnt lgkmcnt(0)
	v_mfma_f32_16x16x32_bf16 v[48:51], v[8:11], v[0:3], 0
	v_mfma_f32_16x16x32_bf16 v[52:55], v[8:11], v[4:7], 0
	ds_read_b128 v[8:11], v146 offset:8704
	s_waitcnt lgkmcnt(0)
	v_mfma_f32_16x16x32_bf16 v[40:43], v[8:11], v[0:3], 0
	v_mfma_f32_16x16x32_bf16 v[44:47], v[8:11], v[4:7], 0
	ds_read_b128 v[8:11], v146 offset:13056
	s_waitcnt lgkmcnt(0)
	v_mfma_f32_16x16x32_bf16 v[32:35], v[8:11], v[0:3], 0
	v_mfma_f32_16x16x32_bf16 v[36:39], v[8:11], v[4:7], 0
	ds_read_b128 v[8:11], v146 offset:17408
	s_waitcnt lgkmcnt(0)
	v_mfma_f32_16x16x32_bf16 v[24:27], v[8:11], v[0:3], 0
	v_mfma_f32_16x16x32_bf16 v[28:31], v[8:11], v[4:7], 0
	ds_read_b128 v[8:11], v146 offset:21760
	s_waitcnt lgkmcnt(0)
	v_mfma_f32_16x16x32_bf16 v[16:19], v[8:11], v[0:3], 0
	v_mfma_f32_16x16x32_bf16 v[20:23], v[8:11], v[4:7], 0
	v_mfma_f32_16x16x32_bf16 v[8:11], v[12:15], v[0:3], 0
	v_mfma_f32_16x16x32_bf16 v[12:15], v[12:15], v[4:7], 0
	v_mfma_f32_16x16x32_bf16 v[0:3], v[64:67], v[0:3], 0
	v_mfma_f32_16x16x32_bf16 v[4:7], v[64:67], v[4:7], 0
	v_cndmask_b32_e64 v64, v97, v98, s[8:9]
	v_cvt_f32_ubyte0_e32 v64, v64
	v_mul_f32_e64 v64, -v147, v64
	v_exp_f32_e32 v68, v64
	v_cndmask_b32_e64 v64, v99, v100, s[8:9]
	v_cvt_f32_ubyte0_e32 v64, v64
	v_mul_f32_e64 v64, -v147, v64
	v_exp_f32_e32 v69, v64
	v_cndmask_b32_e64 v64, v101, v102, s[8:9]
	v_cvt_f32_ubyte0_e32 v64, v64
	v_mul_f32_e64 v64, -v147, v64
	v_exp_f32_e32 v70, v64
	v_cndmask_b32_e64 v64, v103, v104, s[8:9]
	v_cvt_f32_ubyte0_e32 v64, v64
	v_mul_f32_e64 v64, -v147, v64
	v_exp_f32_e32 v71, v64
	v_cndmask_b32_e64 v64, v105, v106, s[8:9]
	v_cvt_f32_ubyte0_e32 v64, v64
	v_mul_f32_e64 v64, -v147, v64
	v_exp_f32_e32 v72, v64
	v_cndmask_b32_e64 v64, v107, v108, s[8:9]
	v_cvt_f32_ubyte0_e32 v64, v64
	v_mul_f32_e64 v64, -v147, v64
	v_exp_f32_e32 v73, v64
	v_cndmask_b32_e64 v64, v109, v110, s[8:9]
	v_cvt_f32_ubyte0_e32 v64, v64
	v_mul_f32_e64 v64, -v147, v64
	v_exp_f32_e32 v74, v64
	v_cndmask_b32_e64 v64, v111, v112, s[8:9]
	v_cvt_f32_ubyte0_e32 v64, v64
	v_mul_f32_e64 v64, -v147, v64
	v_exp_f32_e32 v75, v64
	ds_read_b128 v[64:67], v145 offset:34880
	s_waitcnt lgkmcnt(0)
	v_lshlrev_b32_e32 v148, 16, v64
	v_and_b32_e32 v149, 0xffff0000, v64
	v_pk_mul_f32 v[148:149], v[68:69], v[148:149]
	s_nop 0
	v_cvt_pk_bf16_f32 v64, v148, v149
	v_lshlrev_b32_e32 v148, 16, v65
	v_and_b32_e32 v149, 0xffff0000, v65
	v_pk_mul_f32 v[148:149], v[70:71], v[148:149]
	s_nop 0
	v_cvt_pk_bf16_f32 v65, v148, v149
	v_lshlrev_b32_e32 v148, 16, v66
	v_and_b32_e32 v149, 0xffff0000, v66
	v_pk_mul_f32 v[148:149], v[72:73], v[148:149]
	s_nop 0
	v_cvt_pk_bf16_f32 v66, v148, v149
	v_lshlrev_b32_e32 v148, 16, v67
	v_and_b32_e32 v149, 0xffff0000, v67
	v_pk_mul_f32 v[148:149], v[74:75], v[148:149]
	s_nop 0
	v_cvt_pk_bf16_f32 v67, v148, v149
	ds_read_b128 v[148:151], v145 offset:39232
	s_waitcnt lgkmcnt(0)
	v_lshlrev_b32_e32 v156, 16, v148
	v_and_b32_e32 v157, 0xffff0000, v148
	v_lshlrev_b32_e32 v148, 16, v149
	v_and_b32_e32 v149, 0xffff0000, v149
	v_pk_mul_f32 v[68:69], v[68:69], v[156:157]
	v_pk_mul_f32 v[70:71], v[70:71], v[148:149]
	v_cvt_pk_bf16_f32 v68, v68, v69
	v_cvt_pk_bf16_f32 v69, v70, v71
	v_lshlrev_b32_e32 v70, 16, v150
	v_and_b32_e32 v71, 0xffff0000, v150
	v_pk_mul_f32 v[70:71], v[72:73], v[70:71]
	v_lshlrev_b32_e32 v72, 16, v151
	v_and_b32_e32 v73, 0xffff0000, v151
	v_pk_mul_f32 v[72:73], v[74:75], v[72:73]
	v_cvt_pk_bf16_f32 v70, v70, v71
	v_cvt_pk_bf16_f32 v71, v72, v73
	ds_read_b128 v[72:75], v146 offset:64
	s_waitcnt lgkmcnt(0)
	v_mfma_f32_16x16x32_bf16 v[56:59], v[72:75], v[64:67], v[56:59]
	v_mfma_f32_16x16x32_bf16 v[60:63], v[72:75], v[68:71], v[60:63]
	ds_read_b128 v[72:75], v146 offset:4416
	s_waitcnt lgkmcnt(0)
	v_mfma_f32_16x16x32_bf16 v[48:51], v[72:75], v[64:67], v[48:51]
	v_mfma_f32_16x16x32_bf16 v[52:55], v[72:75], v[68:71], v[52:55]
	ds_read_b128 v[72:75], v146 offset:8768
	s_waitcnt lgkmcnt(0)
	v_mfma_f32_16x16x32_bf16 v[40:43], v[72:75], v[64:67], v[40:43]
	v_mfma_f32_16x16x32_bf16 v[44:47], v[72:75], v[68:71], v[44:47]
	ds_read_b128 v[72:75], v146 offset:13120
	s_waitcnt lgkmcnt(0)
	v_mfma_f32_16x16x32_bf16 v[32:35], v[72:75], v[64:67], v[32:35]
	v_mfma_f32_16x16x32_bf16 v[36:39], v[72:75], v[68:71], v[36:39]
	ds_read_b128 v[72:75], v146 offset:17472
	s_waitcnt lgkmcnt(0)
	v_mfma_f32_16x16x32_bf16 v[24:27], v[72:75], v[64:67], v[24:27]
	v_mfma_f32_16x16x32_bf16 v[28:31], v[72:75], v[68:71], v[28:31]
	ds_read_b128 v[72:75], v146 offset:21824
	s_waitcnt lgkmcnt(0)
	v_mfma_f32_16x16x32_bf16 v[16:19], v[72:75], v[64:67], v[16:19]
	v_mfma_f32_16x16x32_bf16 v[20:23], v[72:75], v[68:71], v[20:23]
	ds_read_b128 v[72:75], v146 offset:26176
	s_waitcnt lgkmcnt(0)
	v_mfma_f32_16x16x32_bf16 v[8:11], v[72:75], v[64:67], v[8:11]
	v_mfma_f32_16x16x32_bf16 v[12:15], v[72:75], v[68:71], v[12:15]
	ds_read_b128 v[72:75], v146 offset:30528
	s_waitcnt lgkmcnt(0)
	v_mfma_f32_16x16x32_bf16 v[0:3], v[72:75], v[64:67], v[0:3]
	v_cndmask_b32_e64 v64, v113, v114, s[8:9]
	v_cvt_f32_ubyte0_e32 v64, v64
	v_mul_f32_e64 v64, -v147, v64
	v_mfma_f32_16x16x32_bf16 v[4:7], v[72:75], v[68:71], v[4:7]
	v_exp_f32_e32 v72, v64
	v_cndmask_b32_e64 v64, v115, v116, s[8:9]
	v_cvt_f32_ubyte0_e32 v64, v64
	v_mul_f32_e64 v64, -v147, v64
	v_exp_f32_e32 v73, v64
	v_cndmask_b32_e64 v64, v117, v118, s[8:9]
	v_cvt_f32_ubyte0_e32 v64, v64
	v_mul_f32_e64 v64, -v147, v64
	v_exp_f32_e32 v74, v64
	v_cndmask_b32_e64 v64, v119, v120, s[8:9]
	v_cvt_f32_ubyte0_e32 v64, v64
	v_mul_f32_e64 v64, -v147, v64
	v_exp_f32_e32 v75, v64
	v_cndmask_b32_e64 v64, v121, v122, s[8:9]
	v_cvt_f32_ubyte0_e32 v64, v64
	v_mul_f32_e64 v64, -v147, v64
	v_exp_f32_e32 v148, v64
	v_cndmask_b32_e64 v64, v123, v124, s[8:9]
	v_cvt_f32_ubyte0_e32 v64, v64
	v_mul_f32_e64 v64, -v147, v64
	v_exp_f32_e32 v149, v64
	v_cndmask_b32_e64 v64, v125, v126, s[8:9]
	v_cvt_f32_ubyte0_e32 v64, v64
	v_mul_f32_e64 v64, -v147, v64
	v_exp_f32_e32 v150, v64
	v_cndmask_b32_e64 v64, v127, v128, s[8:9]
	v_cvt_f32_ubyte0_e32 v64, v64
	v_mul_f32_e64 v64, -v147, v64
	v_exp_f32_e32 v151, v64
	ds_read_b128 v[64:67], v145 offset:34944
	s_waitcnt lgkmcnt(0)
	v_lshlrev_b32_e32 v68, 16, v64
	v_and_b32_e32 v69, 0xffff0000, v64
	v_pk_mul_f32 v[68:69], v[72:73], v[68:69]
	s_nop 0
	v_cvt_pk_bf16_f32 v64, v68, v69
	v_lshlrev_b32_e32 v68, 16, v65
	v_and_b32_e32 v69, 0xffff0000, v65
	v_pk_mul_f32 v[68:69], v[74:75], v[68:69]
	s_nop 0
	v_cvt_pk_bf16_f32 v65, v68, v69
	v_lshlrev_b32_e32 v68, 16, v66
	v_and_b32_e32 v69, 0xffff0000, v66
	v_pk_mul_f32 v[68:69], v[148:149], v[68:69]
	s_nop 0
	v_cvt_pk_bf16_f32 v66, v68, v69
	v_lshlrev_b32_e32 v68, 16, v67
	v_and_b32_e32 v69, 0xffff0000, v67
	v_pk_mul_f32 v[68:69], v[150:151], v[68:69]
	s_nop 0
	v_cvt_pk_bf16_f32 v67, v68, v69
	ds_read_b128 v[68:71], v145 offset:39296
	s_waitcnt lgkmcnt(0)
	v_lshlrev_b32_e32 v156, 16, v68
	v_and_b32_e32 v157, 0xffff0000, v68
	v_pk_mul_f32 v[72:73], v[72:73], v[156:157]
	s_nop 0
	v_cvt_pk_bf16_f32 v68, v72, v73
	v_lshlrev_b32_e32 v72, 16, v69
	v_and_b32_e32 v73, 0xffff0000, v69
	v_pk_mul_f32 v[72:73], v[74:75], v[72:73]
	s_nop 0
	v_cvt_pk_bf16_f32 v69, v72, v73
	v_lshlrev_b32_e32 v72, 16, v70
	v_and_b32_e32 v73, 0xffff0000, v70
	v_pk_mul_f32 v[72:73], v[148:149], v[72:73]
	s_nop 0
	v_cvt_pk_bf16_f32 v70, v72, v73
	v_lshlrev_b32_e32 v72, 16, v71
	v_and_b32_e32 v73, 0xffff0000, v71
	v_pk_mul_f32 v[72:73], v[150:151], v[72:73]
	s_nop 0
	v_cvt_pk_bf16_f32 v71, v72, v73
	ds_read_b128 v[72:75], v146 offset:128
	s_waitcnt lgkmcnt(0)
	v_mfma_f32_16x16x32_bf16 v[56:59], v[72:75], v[64:67], v[56:59]
	v_mfma_f32_16x16x32_bf16 v[60:63], v[72:75], v[68:71], v[60:63]
	ds_read_b128 v[72:75], v146 offset:4480
	s_waitcnt lgkmcnt(0)
	v_mfma_f32_16x16x32_bf16 v[48:51], v[72:75], v[64:67], v[48:51]
	v_mfma_f32_16x16x32_bf16 v[52:55], v[72:75], v[68:71], v[52:55]
	ds_read_b128 v[72:75], v146 offset:8832
	s_waitcnt lgkmcnt(0)
	v_mfma_f32_16x16x32_bf16 v[40:43], v[72:75], v[64:67], v[40:43]
	v_mfma_f32_16x16x32_bf16 v[44:47], v[72:75], v[68:71], v[44:47]
	ds_read_b128 v[72:75], v146 offset:13184
	s_waitcnt lgkmcnt(0)
	v_mfma_f32_16x16x32_bf16 v[32:35], v[72:75], v[64:67], v[32:35]
	v_mfma_f32_16x16x32_bf16 v[36:39], v[72:75], v[68:71], v[36:39]
	ds_read_b128 v[72:75], v146 offset:17536
	s_waitcnt lgkmcnt(0)
	v_mfma_f32_16x16x32_bf16 v[24:27], v[72:75], v[64:67], v[24:27]
	v_mfma_f32_16x16x32_bf16 v[28:31], v[72:75], v[68:71], v[28:31]
	ds_read_b128 v[72:75], v146 offset:21888
	s_waitcnt lgkmcnt(0)
	v_mfma_f32_16x16x32_bf16 v[16:19], v[72:75], v[64:67], v[16:19]
	v_mfma_f32_16x16x32_bf16 v[20:23], v[72:75], v[68:71], v[20:23]
	ds_read_b128 v[72:75], v146 offset:26240
	s_waitcnt lgkmcnt(0)
	v_mfma_f32_16x16x32_bf16 v[8:11], v[72:75], v[64:67], v[8:11]
	v_mfma_f32_16x16x32_bf16 v[12:15], v[72:75], v[68:71], v[12:15]
	ds_read_b128 v[72:75], v146 offset:30592
	s_waitcnt lgkmcnt(0)
	v_mfma_f32_16x16x32_bf16 v[0:3], v[72:75], v[64:67], v[0:3]
	v_cndmask_b32_e64 v64, v129, v130, s[8:9]
	v_cvt_f32_ubyte0_e32 v64, v64
	v_mul_f32_e64 v64, -v147, v64
	v_mfma_f32_16x16x32_bf16 v[4:7], v[72:75], v[68:71], v[4:7]
	v_exp_f32_e32 v68, v64
	v_cndmask_b32_e64 v64, v131, v132, s[8:9]
	v_cvt_f32_ubyte0_e32 v64, v64
	v_mul_f32_e64 v64, -v147, v64
	v_exp_f32_e32 v69, v64
	v_cndmask_b32_e64 v64, v133, v134, s[8:9]
	v_cvt_f32_ubyte0_e32 v64, v64
	v_mul_f32_e64 v64, -v147, v64
	v_exp_f32_e32 v70, v64
	v_cndmask_b32_e64 v64, v135, v136, s[8:9]
	v_cvt_f32_ubyte0_e32 v64, v64
	v_mul_f32_e64 v64, -v147, v64
	v_exp_f32_e32 v71, v64
	v_cndmask_b32_e64 v64, v137, v138, s[8:9]
	v_cvt_f32_ubyte0_e32 v64, v64
	v_mul_f32_e64 v64, -v147, v64
	v_exp_f32_e32 v72, v64
	v_cndmask_b32_e64 v64, v139, v140, s[8:9]
	v_cvt_f32_ubyte0_e32 v64, v64
	v_mul_f32_e64 v64, -v147, v64
	v_exp_f32_e32 v73, v64
	v_cndmask_b32_e64 v64, v141, v142, s[8:9]
	v_cvt_f32_ubyte0_e32 v64, v64
	v_mul_f32_e64 v64, -v147, v64
	v_exp_f32_e32 v74, v64
	v_cndmask_b32_e64 v64, v143, v144, s[8:9]
	v_cvt_f32_ubyte0_e32 v64, v64
	v_mul_f32_e64 v64, -v147, v64
	v_exp_f32_e32 v75, v64
	ds_read_b128 v[64:67], v145 offset:35008
	s_waitcnt lgkmcnt(0)
	v_lshlrev_b32_e32 v148, 16, v64
	v_and_b32_e32 v149, 0xffff0000, v64
	v_pk_mul_f32 v[148:149], v[68:69], v[148:149]
	s_nop 0
	v_cvt_pk_bf16_f32 v64, v148, v149
	v_lshlrev_b32_e32 v148, 16, v65
	v_and_b32_e32 v149, 0xffff0000, v65
	v_pk_mul_f32 v[148:149], v[70:71], v[148:149]
	s_nop 0
	v_cvt_pk_bf16_f32 v65, v148, v149
	v_lshlrev_b32_e32 v148, 16, v66
	v_and_b32_e32 v149, 0xffff0000, v66
	v_pk_mul_f32 v[148:149], v[72:73], v[148:149]
	s_nop 0
	v_cvt_pk_bf16_f32 v66, v148, v149
	v_lshlrev_b32_e32 v148, 16, v67
	v_and_b32_e32 v149, 0xffff0000, v67
	v_pk_mul_f32 v[148:149], v[74:75], v[148:149]
	s_nop 0
	v_cvt_pk_bf16_f32 v67, v148, v149
	ds_read_b128 v[148:151], v145 offset:39360
	s_waitcnt lgkmcnt(0)
	v_lshlrev_b32_e32 v156, 16, v148
	v_and_b32_e32 v157, 0xffff0000, v148
	v_lshlrev_b32_e32 v148, 16, v149
	v_and_b32_e32 v149, 0xffff0000, v149
	v_pk_mul_f32 v[68:69], v[68:69], v[156:157]
	v_pk_mul_f32 v[70:71], v[70:71], v[148:149]
	v_cvt_pk_bf16_f32 v68, v68, v69
	v_cvt_pk_bf16_f32 v69, v70, v71
	v_lshlrev_b32_e32 v70, 16, v150
	v_and_b32_e32 v71, 0xffff0000, v150
	v_pk_mul_f32 v[70:71], v[72:73], v[70:71]
	v_lshlrev_b32_e32 v72, 16, v151
	v_and_b32_e32 v73, 0xffff0000, v151
	ds_read_b128 v[148:151], v146 offset:192
	v_pk_mul_f32 v[72:73], v[74:75], v[72:73]
	v_cvt_pk_bf16_f32 v70, v70, v71
	v_cvt_pk_bf16_f32 v71, v72, v73
	s_waitcnt lgkmcnt(0)
	v_mfma_f32_16x16x32_bf16 v[72:75], v[148:151], v[64:67], v[56:59]
	v_mfma_f32_16x16x32_bf16 v[56:59], v[148:151], v[68:71], v[60:63]
	ds_read_b128 v[148:151], v146 offset:4544
	s_waitcnt lgkmcnt(0)
	v_mfma_f32_16x16x32_bf16 v[60:63], v[148:151], v[64:67], v[48:51]
	v_mfma_f32_16x16x32_bf16 v[48:51], v[148:151], v[68:71], v[52:55]
	ds_read_b128 v[148:151], v146 offset:8896
	s_waitcnt lgkmcnt(0)
	v_mfma_f32_16x16x32_bf16 v[52:55], v[148:151], v[64:67], v[40:43]
	v_mfma_f32_16x16x32_bf16 v[40:43], v[148:151], v[68:71], v[44:47]
	ds_read_b128 v[148:151], v146 offset:13248
	s_waitcnt lgkmcnt(0)
	v_mfma_f32_16x16x32_bf16 v[44:47], v[148:151], v[64:67], v[32:35]
	v_mfma_f32_16x16x32_bf16 v[32:35], v[148:151], v[68:71], v[36:39]
	ds_read_b128 v[148:151], v146 offset:17600
	s_waitcnt lgkmcnt(0)
	v_mfma_f32_16x16x32_bf16 v[36:39], v[148:151], v[64:67], v[24:27]
	v_mfma_f32_16x16x32_bf16 v[24:27], v[148:151], v[68:71], v[28:31]
	ds_read_b128 v[148:151], v146 offset:21952
	s_waitcnt lgkmcnt(0)
	v_mfma_f32_16x16x32_bf16 v[28:31], v[148:151], v[64:67], v[16:19]
	v_mfma_f32_16x16x32_bf16 v[16:19], v[148:151], v[68:71], v[20:23]
	ds_read_b128 v[148:151], v146 offset:26304
	s_waitcnt lgkmcnt(0)
	v_mfma_f32_16x16x32_bf16 v[20:23], v[148:151], v[64:67], v[8:11]
	v_mfma_f32_16x16x32_bf16 v[8:11], v[148:151], v[68:71], v[12:15]
	ds_read_b128 v[148:151], v146 offset:30656
	s_waitcnt lgkmcnt(0)
	v_mfma_f32_16x16x32_bf16 v[12:15], v[148:151], v[64:67], v[0:3]
	v_mfma_f32_16x16x32_bf16 v[0:3], v[148:151], v[68:71], v[4:7]
	s_cbranch_vccnz .LBB0_171
	v_lshlrev_b32_e32 v152, 1, v76
	s_nop 0
	v_lshl_add_u64 v[4:5], s[10:11], 0, v[152:153]
	v_lshl_add_u64 v[4:5], v[78:79], 1, v[4:5]
	v_cvt_pk_bf16_f32 v6, v72, v73
	v_cvt_pk_bf16_f32 v7, v74, v75
	global_store_dwordx2 v[4:5], v[6:7], off
	v_cvt_pk_bf16_f32 v6, v60, v61
	v_cvt_pk_bf16_f32 v7, v62, v63
	global_store_dwordx2 v[4:5], v[6:7], off offset:32
	v_cvt_pk_bf16_f32 v6, v52, v53
	v_cvt_pk_bf16_f32 v7, v54, v55
	global_store_dwordx2 v[4:5], v[6:7], off offset:64
	v_cvt_pk_bf16_f32 v6, v44, v45
	v_cvt_pk_bf16_f32 v7, v46, v47
	global_store_dwordx2 v[4:5], v[6:7], off offset:96
	v_cvt_pk_bf16_f32 v6, v36, v37
	v_cvt_pk_bf16_f32 v7, v38, v39
	global_store_dwordx2 v[4:5], v[6:7], off offset:128
	v_cvt_pk_bf16_f32 v6, v28, v29
	v_cvt_pk_bf16_f32 v7, v30, v31
	global_store_dwordx2 v[4:5], v[6:7], off offset:160
	v_cvt_pk_bf16_f32 v6, v20, v21
	v_cvt_pk_bf16_f32 v7, v22, v23
	global_store_dwordx2 v[4:5], v[6:7], off offset:192
	v_cvt_pk_bf16_f32 v6, v12, v13
	v_cvt_pk_bf16_f32 v7, v14, v15
	global_store_dwordx2 v[4:5], v[6:7], off offset:224
	v_add_co_u32_e32 v4, vcc, s27, v4
	v_cvt_pk_bf16_f32 v6, v56, v57
	v_cvt_pk_bf16_f32 v7, v58, v59
	v_addc_co_u32_e32 v5, vcc, 0, v5, vcc
	global_store_dwordx2 v[4:5], v[6:7], off
	v_cvt_pk_bf16_f32 v6, v48, v49
	v_cvt_pk_bf16_f32 v7, v50, v51
	global_store_dwordx2 v[4:5], v[6:7], off offset:32
	v_cvt_pk_bf16_f32 v6, v40, v41
	v_cvt_pk_bf16_f32 v7, v42, v43
	global_store_dwordx2 v[4:5], v[6:7], off offset:64
	v_cvt_pk_bf16_f32 v6, v32, v33
	v_cvt_pk_bf16_f32 v7, v34, v35
	global_store_dwordx2 v[4:5], v[6:7], off offset:96
	v_cvt_pk_bf16_f32 v6, v24, v25
	v_cvt_pk_bf16_f32 v7, v26, v27
	global_store_dwordx2 v[4:5], v[6:7], off offset:128
	v_cvt_pk_bf16_f32 v6, v16, v17
	v_cvt_pk_bf16_f32 v7, v18, v19
	global_store_dwordx2 v[4:5], v[6:7], off offset:160
	v_cvt_pk_bf16_f32 v6, v8, v9
	v_cvt_pk_bf16_f32 v7, v10, v11
	global_store_dwordx2 v[4:5], v[6:7], off offset:192
	v_cvt_pk_bf16_f32 v6, v0, v1
	v_cvt_pk_bf16_f32 v7, v2, v3
	s_mov_b64 s[16:17], 0
	global_store_dwordx2 v[4:5], v[6:7], off offset:224
.LBB0_171:
	s_andn2_b64 vcc, exec, s[16:17]
	s_cbranch_vccnz .LBB0_168
	v_lshlrev_b32_e32 v152, 2, v76
	v_lshl_add_u64 v[4:5], s[10:11], 0, v[152:153]
	v_lshl_add_u64 v[4:5], v[78:79], 2, v[4:5]
	global_store_dwordx4 v[4:5], v[72:75], off
	global_store_dwordx4 v[4:5], v[60:63], off offset:64
	global_store_dwordx4 v[4:5], v[52:55], off offset:128
	global_store_dwordx4 v[4:5], v[44:47], off offset:192
	global_store_dwordx4 v[4:5], v[36:39], off offset:256
	global_store_dwordx4 v[4:5], v[28:31], off offset:320
	global_store_dwordx4 v[4:5], v[20:23], off offset:384
	global_store_dwordx4 v[4:5], v[12:15], off offset:448
	v_add_co_u32_e32 v4, vcc, 0x2000, v4
	s_nop 1
	v_addc_co_u32_e32 v5, vcc, 0, v5, vcc
	global_store_dwordx4 v[4:5], v[56:59], off
	global_store_dwordx4 v[4:5], v[48:51], off offset:64
	global_store_dwordx4 v[4:5], v[40:43], off offset:128
	global_store_dwordx4 v[4:5], v[32:35], off offset:192
	global_store_dwordx4 v[4:5], v[24:27], off offset:256
	global_store_dwordx4 v[4:5], v[16:19], off offset:320
	global_store_dwordx4 v[4:5], v[8:11], off offset:384
	global_store_dwordx4 v[4:5], v[0:3], off offset:448
	s_branch .LBB0_168

.LBB0_188:
	v_ashrrev_i32_e32 v2, 10, v152
	v_add_u32_e32 v2, 1, v2
	v_cndmask_b32_e64 v2, v2, 0, s[8:9]
	v_ashrrev_i32_e32 v3, 31, v2
	v_lshl_add_u64 v[126:127], v[2:3], 0, s[28:29]
	v_lshlrev_b64 v[2:3], 11, v[138:139]
	v_lshl_add_u64 v[2:3], s[56:57], 0, v[2:3]
	s_mov_b64 s[4:5], 0x1000000
	v_lshlrev_b32_e32 v152, 2, v98
	v_lshl_add_u64 v[4:5], v[2:3], 0, s[4:5]
	v_lshl_add_u64 v[0:1], v[0:1], 0, v[152:153]
	v_mad_u64_u32 v[6:7], s[4:5], v126, s7, v[110:111]
	v_lshlrev_b32_e32 v146, 1, v98
	v_mov_b32_e32 v147, v153
	v_mad_i32_i24 v7, v127, s7, v7
	v_lshl_add_u64 v[2:3], v[2:3], 0, v[146:147]
	global_load_dwordx4 v[64:67], v[0:1], off
	global_load_dwordx4 v[52:55], v[0:1], off offset:1024
	global_load_dwordx4 v[68:71], v[6:7], off
	global_load_dwordx4 v[60:63], v[6:7], off offset:1024
	global_load_dwordx4 v[48:51], v[0:1], off offset:2048
	global_load_dwordx4 v[40:43], v[0:1], off offset:3072
	global_load_dwordx4 v[56:59], v[6:7], off offset:2048
	global_load_dwordx4 v[44:47], v[6:7], off offset:3072
	global_load_dwordx2 v[188:189], v[2:3], off
	global_load_dwordx2 v[184:185], v[2:3], off offset:512
	global_load_dwordx2 v[180:181], v[2:3], off offset:1024
	global_load_dwordx2 v[176:177], v[2:3], off offset:1536
	v_lshl_add_u64 v[8:9], v[4:5], 0, v[146:147]
	v_lshlrev_b32_e32 v144, 1, v100
	v_mov_b32_e32 v145, v153
	v_lshlrev_b32_e32 v148, 1, v102
	v_mov_b32_e32 v149, v153
	v_lshlrev_b32_e32 v142, 1, v104
	v_mov_b32_e32 v143, v153
	v_lshl_add_u64 v[10:11], v[4:5], 0, v[144:145]
	v_lshl_add_u64 v[12:13], v[4:5], 0, v[148:149]
	v_lshl_add_u64 v[0:1], v[4:5], 0, v[142:143]
	global_load_dwordx2 v[190:191], v[8:9], off
	global_load_dwordx2 v[186:187], v[10:11], off
	global_load_dwordx2 v[182:183], v[12:13], off
	global_load_dwordx2 v[178:179], v[0:1], off
	v_add_u32_e32 v0, s38, v96
	v_readlane_b32 s4, v254, 27
	v_cmp_lt_i32_e32 vcc, s6, v0
	v_readlane_b32 s5, v254, 28
	s_mov_b64 s[20:21], -1
	v_cndmask_b32_e32 v124, v0, v96, vcc
	v_cndmask_b32_e64 v0, 0, 1, s[4:5]
	v_cmp_gt_i32_e64 s[10:11], s27, v124
	v_cmp_lt_i32_e64 s[12:13], s33, v124
	v_cmp_ne_u32_e64 s[8:9], 1, v0
	s_andn2_b64 vcc, exec, s[4:5]
	v_ashrrev_i32_e32 v125, 31, v124
	s_cbranch_vccnz .LBB0_190
	v_readlane_b32 s4, v254, 18
	v_lshlrev_b64 v[0:1], 12, v[124:125]
	v_readlane_b32 s5, v254, 19
	s_mov_b64 s[20:21], 0
	v_mov_b64_e32 v[140:141], v[124:125]
	v_lshl_add_u64 v[0:1], s[4:5], 0, v[0:1]

.LBB0_196:
	v_ashrrev_i32_e32 v2, 10, v2
	v_add_u32_e32 v2, 1, v2
	v_cndmask_b32_e64 v2, v2, 0, s[10:11]
	v_ashrrev_i32_e32 v3, 31, v2
	v_lshl_add_u64 v[128:129], v[2:3], 0, s[28:29]
	v_lshlrev_b64 v[2:3], 11, v[140:141]
	v_lshl_add_u64 v[2:3], s[56:57], 0, v[2:3]
	s_mov_b64 s[4:5], 0x1000000
	v_lshl_add_u64 v[4:5], v[2:3], 0, s[4:5]
	v_lshl_add_u64 v[0:1], v[0:1], 0, v[152:153]
	v_mad_u64_u32 v[6:7], s[4:5], v128, s7, v[110:111]
	v_mov_b32_e32 v147, v153
	v_mad_i32_i24 v7, v129, s7, v7
	v_lshl_add_u64 v[2:3], v[2:3], 0, v[146:147]
	global_load_dwordx4 v[88:91], v[0:1], off
	global_load_dwordx4 v[76:79], v[0:1], off offset:1024
	global_load_dwordx4 v[92:95], v[6:7], off
	global_load_dwordx4 v[84:87], v[6:7], off offset:1024
	global_load_dwordx4 v[72:75], v[0:1], off offset:2048
	global_load_dwordx4 v[32:35], v[0:1], off offset:3072
	global_load_dwordx4 v[80:83], v[6:7], off offset:2048
	global_load_dwordx4 v[36:39], v[6:7], off offset:3072
	global_load_dwordx2 v[202:203], v[2:3], off
	global_load_dwordx2 v[198:199], v[2:3], off offset:512
	global_load_dwordx2 v[194:195], v[2:3], off offset:1024
	global_load_dwordx2 v[172:173], v[2:3], off offset:1536
	v_lshl_add_u64 v[8:9], v[4:5], 0, v[146:147]
	v_mov_b32_e32 v145, v153
	v_mov_b32_e32 v149, v153
	v_mov_b32_e32 v143, v153
	v_lshl_add_u64 v[10:11], v[4:5], 0, v[144:145]
	v_lshl_add_u64 v[12:13], v[4:5], 0, v[148:149]
	v_lshl_add_u64 v[0:1], v[4:5], 0, v[142:143]
	global_load_dwordx2 v[204:205], v[8:9], off
	global_load_dwordx2 v[200:201], v[10:11], off
	global_load_dwordx2 v[196:197], v[12:13], off
	global_load_dwordx2 v[174:175], v[0:1], off
	v_add_u32_e32 v0, s35, v96
	v_cmp_lt_i32_e32 vcc, s6, v0
	s_mov_b64 s[20:21], -1
	s_nop 0
	v_cndmask_b32_e32 v122, v0, v96, vcc
	v_cmp_gt_i32_e64 s[10:11], s27, v122
	v_cmp_lt_i32_e64 s[12:13], s33, v122
	s_and_b64 vcc, exec, s[8:9]
	v_ashrrev_i32_e32 v123, 31, v122
	s_cbranch_vccnz .LBB0_198
	v_readlane_b32 s4, v254, 18
	v_lshlrev_b64 v[0:1], 12, v[122:123]
	v_readlane_b32 s5, v254, 19
	s_mov_b64 s[20:21], 0
	v_mov_b64_e32 v[132:133], v[122:123]
	v_lshl_add_u64 v[0:1], s[4:5], 0, v[0:1]

.LBB0_204:
	v_ashrrev_i32_e32 v2, 10, v2
	v_add_u32_e32 v2, 1, v2
	v_cndmask_b32_e64 v2, v2, 0, s[10:11]
	v_ashrrev_i32_e32 v3, 31, v2
	v_lshl_add_u64 v[130:131], v[2:3], 0, s[28:29]
	v_lshlrev_b64 v[2:3], 11, v[132:133]
	v_lshl_add_u64 v[2:3], s[56:57], 0, v[2:3]
	s_mov_b64 s[4:5], 0x1000000
	v_lshl_add_u64 v[120:121], v[2:3], 0, s[4:5]
	v_mad_u64_u32 v[16:17], s[4:5], v130, s7, v[110:111]
	v_lshl_add_u64 v[12:13], v[0:1], 0, v[152:153]
	v_mad_i32_i24 v17, v131, s7, v17
	v_mov_b32_e32 v147, v153
	v_lshl_add_u64 v[134:135], v[2:3], 0, v[146:147]
	global_load_dwordx4 v[0:3], v[12:13], off
	global_load_dwordx4 v[4:7], v[12:13], off offset:1024
	global_load_dwordx4 v[28:31], v[16:17], off
	global_load_dwordx4 v[20:23], v[16:17], off offset:1024
	global_load_dwordx4 v[8:11], v[12:13], off offset:2048
	s_nop 0
	global_load_dwordx4 v[12:15], v[12:13], off offset:3072
	s_nop 0
	global_load_dwordx4 v[24:27], v[16:17], off offset:2048
	s_nop 0
	global_load_dwordx4 v[16:19], v[16:17], off offset:3072
	s_nop 0
	global_load_dwordx2 v[166:167], v[134:135], off
	global_load_dwordx2 v[162:163], v[134:135], off offset:512
	global_load_dwordx2 v[158:159], v[134:135], off offset:1024
	global_load_dwordx2 v[150:151], v[134:135], off offset:1536
	v_mov_b32_e32 v145, v153
	v_mov_b32_e32 v149, v153
	v_lshl_add_u64 v[136:137], v[120:121], 0, v[146:147]
	v_lshl_add_u64 v[156:157], v[120:121], 0, v[144:145]
	v_lshl_add_u64 v[160:161], v[120:121], 0, v[148:149]
	v_mov_b32_e32 v143, v153
	v_lshl_add_u64 v[120:121], v[120:121], 0, v[142:143]
	global_load_dwordx2 v[168:169], v[136:137], off
	global_load_dwordx2 v[164:165], v[156:157], off
	s_nop 0
	global_load_dwordx2 v[160:161], v[160:161], off
	s_nop 0
	global_load_dwordx2 v[156:157], v[120:121], off
	v_add_u32_e32 v120, s26, v96
	v_cmp_lt_i32_e32 vcc, s6, v120
	v_bfrev_b32_e32 v250, 0.5
	v_mov_b32_e32 v154, 0x3fc
	v_cndmask_b32_e32 v120, v120, v96, vcc
	v_cmp_gt_i32_e64 s[10:11], s27, v120
	v_cmp_lt_i32_e64 s[12:13], s33, v120
	s_mov_b64 s[20:21], -1
	s_and_b64 vcc, exec, s[8:9]
	v_ashrrev_i32_e32 v121, 31, v120
	s_cbranch_vccnz .LBB0_206
	v_readlane_b32 s4, v254, 18
	v_lshlrev_b64 v[134:135], 12, v[120:121]
	v_readlane_b32 s5, v254, 19
	s_mov_b64 s[20:21], 0
	v_mov_b64_e32 v[192:193], v[120:121]
	v_lshl_add_u64 v[170:171], s[4:5], 0, v[134:135]

.LBB0_212:
	s_waitcnt vmcnt(0) lgkmcnt(0)
	v_lshlrev_b32_e32 v228, 16, v202
	v_and_b32_e32 v229, 0xffff0000, v202
	v_lshlrev_b32_e32 v202, 16, v203
	v_and_b32_e32 v203, 0xffff0000, v203
	v_lshlrev_b32_e32 v230, 16, v204
	v_and_b32_e32 v231, 0xffff0000, v204
	v_lshlrev_b32_e32 v204, 16, v205
	v_and_b32_e32 v205, 0xffff0000, v205
	v_pk_mul_f32 v[94:95], v[94:95], 0.5 op_sel_hi:[1,0]
	v_pk_mul_f32 v[92:93], v[92:93], 0.5 op_sel_hi:[1,0]
	v_pk_add_f32 v[202:203], v[202:203], v[204:205]
	v_pk_add_f32 v[204:205], v[228:229], v[230:231]
	v_pk_mul_f32 v[94:95], v[94:95], v[202:203]
	v_pk_mul_f32 v[92:93], v[92:93], v[204:205]
	v_pk_fma_f32 v[90:91], v[90:91], s[42:43], v[94:95] op_sel_hi:[1,0,1]
	v_pk_fma_f32 v[88:89], v[88:89], s[42:43], v[92:93] op_sel_hi:[1,0,1]
	v_add_f32_e32 v93, v90, v91
	v_add_f32_e32 v92, v88, v89
	v_add_f32_e32 v92, v92, v93
	v_add_f32_e32 v143, 0, v92
	v_lshlrev_b32_e32 v92, 16, v198
	v_and_b32_e32 v93, 0xffff0000, v198
	v_lshlrev_b32_e32 v94, 16, v199
	v_and_b32_e32 v95, 0xffff0000, v199
	v_lshlrev_b32_e32 v198, 16, v200
	v_and_b32_e32 v199, 0xffff0000, v200
	v_lshlrev_b32_e32 v200, 16, v201
	v_and_b32_e32 v201, 0xffff0000, v201
	v_pk_mul_f32 v[86:87], v[86:87], 0.5 op_sel_hi:[1,0]
	v_pk_mul_f32 v[84:85], v[84:85], 0.5 op_sel_hi:[1,0]
	v_pk_add_f32 v[94:95], v[94:95], v[200:201]
	v_pk_add_f32 v[92:93], v[92:93], v[198:199]
	v_pk_mul_f32 v[86:87], v[86:87], v[94:95]
	v_pk_mul_f32 v[84:85], v[84:85], v[92:93]
	v_pk_fma_f32 v[86:87], v[78:79], s[42:43], v[86:87] op_sel_hi:[1,0,1]
	v_pk_fma_f32 v[84:85], v[76:77], s[42:43], v[84:85] op_sel_hi:[1,0,1]
	v_add_f32_e32 v77, v86, v87
	v_add_f32_e32 v76, v84, v85
	v_add_f32_e32 v76, v76, v77
	v_add_f32_e32 v143, v143, v76
	v_lshlrev_b32_e32 v76, 16, v194
	v_and_b32_e32 v77, 0xffff0000, v194
	v_lshlrev_b32_e32 v78, 16, v195
	v_and_b32_e32 v79, 0xffff0000, v195
	v_lshlrev_b32_e32 v92, 16, v196
	v_and_b32_e32 v93, 0xffff0000, v196
	v_lshlrev_b32_e32 v94, 16, v197
	v_and_b32_e32 v95, 0xffff0000, v197
	v_pk_mul_f32 v[82:83], v[82:83], 0.5 op_sel_hi:[1,0]
	v_pk_mul_f32 v[80:81], v[80:81], 0.5 op_sel_hi:[1,0]
	v_pk_add_f32 v[78:79], v[78:79], v[94:95]
	v_pk_add_f32 v[76:77], v[76:77], v[92:93]
	v_pk_mul_f32 v[78:79], v[82:83], v[78:79]
	v_pk_mul_f32 v[76:77], v[80:81], v[76:77]
	v_pk_fma_f32 v[82:83], v[74:75], s[42:43], v[78:79] op_sel_hi:[1,0,1]
	v_pk_fma_f32 v[80:81], v[72:73], s[42:43], v[76:77] op_sel_hi:[1,0,1]
	v_lshlrev_b32_e32 v72, 16, v188
	v_and_b32_e32 v73, 0xffff0000, v188
	v_lshlrev_b32_e32 v74, 16, v189
	v_and_b32_e32 v75, 0xffff0000, v189
	v_lshlrev_b32_e32 v76, 16, v190
	v_and_b32_e32 v77, 0xffff0000, v190
	v_lshlrev_b32_e32 v78, 16, v191
	v_and_b32_e32 v79, 0xffff0000, v191
	v_pk_mul_f32 v[70:71], v[70:71], 0.5 op_sel_hi:[1,0]
	v_pk_mul_f32 v[68:69], v[68:69], 0.5 op_sel_hi:[1,0]
	v_pk_add_f32 v[74:75], v[74:75], v[78:79]
	v_pk_add_f32 v[72:73], v[72:73], v[76:77]
	v_pk_mul_f32 v[70:71], v[70:71], v[74:75]
	v_pk_mul_f32 v[68:69], v[68:69], v[72:73]
	v_pk_fma_f32 v[188:189], v[66:67], s[42:43], v[70:71] op_sel_hi:[1,0,1]
	v_pk_fma_f32 v[190:191], v[64:65], s[42:43], v[68:69] op_sel_hi:[1,0,1]
	v_add_f32_e32 v65, v188, v189
	v_add_f32_e32 v64, v190, v191
	v_add_f32_e32 v64, v64, v65
	v_add_f32_e32 v72, 0, v64
	v_lshlrev_b32_e32 v64, 16, v184
	v_and_b32_e32 v65, 0xffff0000, v184
	v_lshlrev_b32_e32 v66, 16, v185
	v_and_b32_e32 v67, 0xffff0000, v185
	v_lshlrev_b32_e32 v68, 16, v186
	v_and_b32_e32 v69, 0xffff0000, v186
	v_lshlrev_b32_e32 v70, 16, v187
	v_and_b32_e32 v71, 0xffff0000, v187
	v_pk_mul_f32 v[62:63], v[62:63], 0.5 op_sel_hi:[1,0]
	v_pk_mul_f32 v[60:61], v[60:61], 0.5 op_sel_hi:[1,0]
	v_pk_add_f32 v[66:67], v[66:67], v[70:71]
	v_pk_add_f32 v[64:65], v[64:65], v[68:69]
	v_pk_mul_f32 v[62:63], v[62:63], v[66:67]
	v_pk_mul_f32 v[60:61], v[60:61], v[64:65]
	v_pk_fma_f32 v[186:187], v[54:55], s[42:43], v[62:63] op_sel_hi:[1,0,1]
	v_pk_fma_f32 v[184:185], v[52:53], s[42:43], v[60:61] op_sel_hi:[1,0,1]
	v_add_f32_e32 v53, v186, v187
	v_add_f32_e32 v52, v184, v185
	v_add_f32_e32 v52, v52, v53
	v_add_f32_e32 v64, v72, v52
	v_lshlrev_b32_e32 v52, 16, v180
	v_and_b32_e32 v53, 0xffff0000, v180
	v_lshlrev_b32_e32 v54, 16, v181
	v_and_b32_e32 v55, 0xffff0000, v181
	v_lshlrev_b32_e32 v60, 16, v182
	v_and_b32_e32 v61, 0xffff0000, v182
	v_lshlrev_b32_e32 v62, 16, v183
	v_and_b32_e32 v63, 0xffff0000, v183
	v_pk_mul_f32 v[58:59], v[58:59], 0.5 op_sel_hi:[1,0]
	v_pk_mul_f32 v[56:57], v[56:57], 0.5 op_sel_hi:[1,0]
	v_pk_add_f32 v[54:55], v[54:55], v[62:63]
	v_pk_add_f32 v[52:53], v[52:53], v[60:61]
	v_pk_mul_f32 v[54:55], v[58:59], v[54:55]
	v_pk_mul_f32 v[52:53], v[56:57], v[52:53]
	v_pk_fma_f32 v[50:51], v[50:51], s[42:43], v[54:55] op_sel_hi:[1,0,1]
	v_pk_fma_f32 v[48:49], v[48:49], s[42:43], v[52:53] op_sel_hi:[1,0,1]
	v_add_f32_e32 v53, v50, v51
	v_add_f32_e32 v52, v48, v49
	v_add_f32_e32 v52, v52, v53
	v_add_f32_e32 v60, v64, v52
	v_lshlrev_b32_e32 v52, 16, v176
	v_and_b32_e32 v53, 0xffff0000, v176
	v_lshlrev_b32_e32 v54, 16, v177
	v_and_b32_e32 v55, 0xffff0000, v177
	v_lshlrev_b32_e32 v56, 16, v178
	v_and_b32_e32 v57, 0xffff0000, v178
	v_lshlrev_b32_e32 v58, 16, v179
	v_and_b32_e32 v59, 0xffff0000, v179
	v_pk_mul_f32 v[46:47], v[46:47], 0.5 op_sel_hi:[1,0]
	v_pk_mul_f32 v[44:45], v[44:45], 0.5 op_sel_hi:[1,0]
	v_pk_add_f32 v[54:55], v[54:55], v[58:59]
	v_pk_add_f32 v[52:53], v[52:53], v[56:57]
	v_pk_mul_f32 v[46:47], v[46:47], v[54:55]
	v_pk_mul_f32 v[44:45], v[44:45], v[52:53]
	v_pk_fma_f32 v[178:179], v[42:43], s[42:43], v[46:47] op_sel_hi:[1,0,1]
	v_pk_fma_f32 v[176:177], v[40:41], s[42:43], v[44:45] op_sel_hi:[1,0,1]
	v_add_f32_e32 v41, v178, v179
	v_add_f32_e32 v40, v176, v177
	v_add_f32_e32 v40, v40, v41
	v_add_f32_e32 v42, v60, v40
	ds_bpermute_b32 v43, v99, v42
	v_add_f32_e32 v92, v80, v81
	v_add_f32_e32 v93, v82, v83
	v_add_f32_e32 v40, v92, v93
	v_add_f32_e32 v52, v143, v40
	s_waitcnt lgkmcnt(0)
	v_add_f32_e32 v46, v42, v43
	ds_bpermute_b32 v47, v101, v46
	v_lshlrev_b32_e32 v40, 16, v172
	v_and_b32_e32 v41, 0xffff0000, v172
	v_lshlrev_b32_e32 v44, 16, v174
	v_and_b32_e32 v45, 0xffff0000, v174
	s_waitcnt lgkmcnt(0)
	v_add_f32_e32 v53, v46, v47
	ds_bpermute_b32 v54, v103, v53
	v_pk_mul_f32 v[36:37], v[36:37], 0.5 op_sel_hi:[1,0]
	v_pk_add_f32 v[40:41], v[40:41], v[44:45]
	v_lshlrev_b32_e32 v42, 16, v173
	v_pk_mul_f32 v[36:37], v[36:37], v[40:41]
	s_waitcnt lgkmcnt(0)
	v_add_f32_e32 v53, v53, v54
	ds_bpermute_b32 v54, v105, v53
	v_and_b32_e32 v43, 0xffff0000, v173
	v_lshlrev_b32_e32 v46, 16, v175
	v_and_b32_e32 v47, 0xffff0000, v175
	v_pk_mul_f32 v[38:39], v[38:39], 0.5 op_sel_hi:[1,0]
	s_waitcnt lgkmcnt(0)
	v_add_f32_e32 v40, v53, v54
	ds_bpermute_b32 v41, v225, v40
	v_pk_add_f32 v[42:43], v[42:43], v[46:47]
	v_pk_fma_f32 v[92:93], v[32:33], s[42:43], v[36:37] op_sel_hi:[1,0,1]
	v_pk_mul_f32 v[38:39], v[38:39], v[42:43]
	v_add_f32_e32 v32, v92, v93
	v_pk_fma_f32 v[94:95], v[34:35], s[42:43], v[38:39] op_sel_hi:[1,0,1]
	s_waitcnt lgkmcnt(0)
	v_add_f32_e32 v34, v40, v41
	ds_bpermute_b32 v35, v226, v34
	v_add_f32_e32 v33, v94, v95
	v_add_f32_e32 v32, v32, v33
	v_add_f32_e32 v42, v52, v32
	v_lshlrev_b64 v[32:33], 11, v[192:193]
	s_waitcnt lgkmcnt(0)
	v_add_f32_e32 v43, v34, v35
	v_fmamk_f32 v191, v43, 0xba800000, v191
	v_fmac_f32_e32 v190, 0xba800000, v43
	v_fmamk_f32 v189, v43, 0xba800000, v189
	v_fmac_f32_e32 v188, 0xba800000, v43
	v_pk_mul_f32 v[34:35], v[188:189], v[188:189]
	v_pk_mul_f32 v[36:37], v[190:191], v[190:191]
	v_fmamk_f32 v185, v43, 0xba800000, v185
	v_pk_mov_b32 v[38:39], v[36:37], v[34:35] op_sel:[1,0]
	v_mov_b32_e32 v37, v35
	v_pk_add_f32 v[34:35], v[38:39], v[36:37]
	v_fmac_f32_e32 v184, 0xba800000, v43
	v_pk_add_f32 v[34:35], v[34:35], v[34:35] op_sel_hi:[0,1]
	v_fmamk_f32 v187, v43, 0xba800000, v187
	v_fmac_f32_e32 v186, 0xba800000, v43
	ds_bpermute_b32 v34, v99, v42
	v_pk_mul_f32 v[36:37], v[186:187], v[186:187]
	v_pk_mul_f32 v[38:39], v[184:185], v[184:185]
	v_fmac_f32_e32 v48, 0xba800000, v43
	v_pk_mov_b32 v[40:41], v[38:39], v[36:37] op_sel:[1,0]
	v_mov_b32_e32 v39, v37
	v_pk_add_f32 v[36:37], v[40:41], v[38:39]
	v_fmamk_f32 v49, v43, 0xba800000, v49
	v_pk_add_f32 v[36:37], v[36:37], v[36:37] op_sel_hi:[0,1]
	s_waitcnt lgkmcnt(0)
	v_add_f32_e32 v36, v42, v34
	ds_bpermute_b32 v38, v101, v36
	v_fmac_f32_e32 v50, 0xba800000, v43
	v_mul_f32_e32 v34, v48, v48
	v_fmamk_f32 v51, v43, 0xba800000, v51
	v_fmamk_f32 v179, v43, 0xba800000, v179
	s_waitcnt lgkmcnt(0)
	v_add_f32_e32 v36, v36, v38
	ds_bpermute_b32 v42, v103, v36
	v_pk_fma_f32 v[38:39], v[48:49], v[48:49], v[34:35] op_sel_hi:[1,1,0]
	v_mul_f32_e32 v34, v50, v50
	v_pk_fma_f32 v[40:41], v[50:51], v[50:51], v[34:35] op_sel_hi:[1,1,0]
	v_fmac_f32_e32 v178, 0xba800000, v43
	s_waitcnt lgkmcnt(0)
	v_add_f32_e32 v34, v36, v42
	ds_bpermute_b32 v36, v105, v34
	v_fmamk_f32 v177, v43, 0xba800000, v177
	v_fmac_f32_e32 v176, 0xba800000, v43
	v_mul_f32_e32 v38, v176, v176
	v_mul_f32_e32 v40, v177, v177
	s_waitcnt lgkmcnt(0)
	v_add_f32_e32 v42, v34, v36
	v_mul_f32_e32 v34, v178, v178
	v_mul_f32_e32 v36, v179, v179
	v_pk_add_f32 v[38:39], v[38:39], v[40:41]
	v_pk_add_f32 v[34:35], v[34:35], v[36:37]
	ds_bpermute_b32 v43, v225, v42
	v_pk_add_f32 v[34:35], v[38:39], v[34:35]
	ds_read_b128 v[36:39], v210
	ds_read_b128 v[56:59], v210 offset:4096
	v_lshl_add_u64 v[32:33], s[56:57], 0, v[32:33]
	s_mov_b64 s[4:5], 0x1000000
	s_waitcnt lgkmcnt(0)
	v_add_f32_e32 v40, v42, v43
	ds_bpermute_b32 v41, v226, v40
	v_ashrrev_i32_e32 v136, 10, v136
	v_lshl_add_u64 v[60:61], v[32:33], 0, s[4:5]
	v_mov_b32_e32 v145, v153
	v_add_u32_e32 v136, 1, v136
	s_waitcnt lgkmcnt(0)
	v_add_f32_e32 v52, v40, v41
	v_fmamk_f32 v89, v52, 0xba800000, v89
	v_fmac_f32_e32 v88, 0xba800000, v52
	v_fmamk_f32 v91, v52, 0xba800000, v91
	v_fmac_f32_e32 v90, 0xba800000, v52
	v_pk_mul_f32 v[40:41], v[90:91], v[90:91]
	v_pk_mul_f32 v[42:43], v[88:89], v[88:89]
	v_fmamk_f32 v85, v52, 0xba800000, v85
	v_pk_mov_b32 v[44:45], v[42:43], v[40:41] op_sel:[1,0]
	v_mov_b32_e32 v43, v41
	v_pk_add_f32 v[40:41], v[44:45], v[42:43]
	v_fmac_f32_e32 v84, 0xba800000, v52
	v_fmamk_f32 v87, v52, 0xba800000, v87
	v_fmac_f32_e32 v86, 0xba800000, v52
	v_pk_add_f32 v[40:41], v[40:41], v[40:41] op_sel_hi:[0,1]
	v_pk_mul_f32 v[42:43], v[86:87], v[86:87]
	v_pk_mul_f32 v[44:45], v[84:85], v[84:85]
	v_fmac_f32_e32 v80, 0xba800000, v52
	v_pk_mov_b32 v[46:47], v[44:45], v[42:43] op_sel:[1,0]
	v_mov_b32_e32 v45, v43
	v_fmamk_f32 v81, v52, 0xba800000, v81
	v_fmac_f32_e32 v82, 0xba800000, v52
	v_mul_f32_e32 v40, v80, v80
	v_pk_add_f32 v[42:43], v[46:47], v[44:45]
	v_fmamk_f32 v83, v52, 0xba800000, v83
	v_pk_fma_f32 v[44:45], v[80:81], v[80:81], v[40:41] op_sel_hi:[1,1,0]
	v_mul_f32_e32 v40, v82, v82
	v_pk_add_f32 v[42:43], v[42:43], v[42:43] op_sel_hi:[0,1]
	v_pk_fma_f32 v[46:47], v[82:83], v[82:83], v[40:41] op_sel_hi:[1,1,0]
	v_fmamk_f32 v95, v52, 0xba800000, v95
	v_fmac_f32_e32 v94, 0xba800000, v52
	v_fmamk_f32 v93, v52, 0xba800000, v93
	v_fmac_f32_e32 v92, 0xba800000, v52
	v_mul_f32_e32 v44, v92, v92
	v_mul_f32_e32 v46, v93, v93
	v_mul_f32_e32 v40, v94, v94
	v_mul_f32_e32 v42, v95, v95
	v_pk_add_f32 v[44:45], v[44:45], v[46:47]
	v_pk_add_f32 v[40:41], v[40:41], v[42:43]
	v_mov_b32_e32 v43, v34
	v_pk_add_f32 v[40:41], v[44:45], v[40:41]
	v_mov_b32_e32 v147, v153
	v_mov_b32_e32 v42, v40
	v_mov_b32_e32 v34, v41
	v_pk_add_f32 v[34:35], v[42:43], v[34:35]
	ds_bpermute_b32 v41, v99, v35
	ds_bpermute_b32 v40, v99, v34
	v_lshl_add_u64 v[192:193], v[60:61], 0, v[144:145]
	v_cndmask_b32_e64 v136, v136, 0, s[10:11]
	v_lshl_add_u64 v[172:173], v[32:33], 0, v[146:147]
	v_lshl_add_u64 v[180:181], v[60:61], 0, v[146:147]
	s_waitcnt lgkmcnt(0)
	v_pk_add_f32 v[34:35], v[34:35], v[40:41]
	ds_bpermute_b32 v41, v101, v35
	ds_bpermute_b32 v40, v101, v34
	v_ashrrev_i32_e32 v137, 31, v136
	v_lshl_add_u64 v[136:137], v[136:137], 0, s[28:29]
	v_mad_u64_u32 v[62:63], s[4:5], v136, s7, v[110:111]
	s_waitcnt lgkmcnt(0)
	v_pk_add_f32 v[46:47], v[34:35], v[40:41]
	ds_bpermute_b32 v53, v103, v47
	ds_bpermute_b32 v52, v103, v46
	v_lshl_add_u64 v[44:45], v[170:171], 0, v[152:153]
	v_mad_i32_i24 v63, v137, s7, v63
	global_load_dwordx4 v[40:43], v[44:45], off
	global_load_dwordx4 v[32:35], v[44:45], off offset:1024
	global_load_dwordx4 v[68:71], v[62:63], off
	global_load_dwordx4 v[64:67], v[62:63], off offset:1024
	v_mov_b32_e32 v149, v153
	s_waitcnt lgkmcnt(0)
	v_pk_add_f32 v[46:47], v[46:47], v[52:53]
	ds_bpermute_b32 v53, v105, v47
	ds_bpermute_b32 v52, v105, v46
	v_mov_b32_e32 v143, v153
	s_mov_b32 s2, 0x3727c5ac
	v_lshl_add_u64 v[148:149], v[60:61], 0, v[148:149]
	v_lshl_add_u64 v[60:61], v[60:61], 0, v[142:143]
	s_waitcnt lgkmcnt(0)
	v_pk_add_f32 v[144:145], v[46:47], v[52:53]
	ds_bpermute_b32 v147, v225, v145
	ds_bpermute_b32 v146, v225, v144
	global_load_dwordx4 v[52:55], v[44:45], off offset:2048
	s_nop 0
	global_load_dwordx4 v[44:47], v[44:45], off offset:3072
	s_nop 0
	global_load_dwordx4 v[76:79], v[62:63], off offset:2048
	global_load_dwordx4 v[72:75], v[62:63], off offset:3072
	v_mov_b64_e32 v[142:143], s[2:3]
	s_mov_b32 s2, 0x3a800000
	v_pk_mul_f32 v[230:231], v[24:25], 0.5 op_sel_hi:[1,0]
	s_waitcnt lgkmcnt(0)
	v_pk_add_f32 v[62:63], v[144:145], v[146:147]
	ds_bpermute_b32 v183, v226, v63
	ds_bpermute_b32 v182, v226, v62
	global_load_dwordx2 v[174:175], v[172:173], off
	global_load_dwordx2 v[170:171], v[172:173], off offset:512
	global_load_dwordx2 v[146:147], v[172:173], off offset:1024
	global_load_dwordx2 v[144:145], v[172:173], off offset:1536
	v_pk_mul_f32 v[228:229], v[26:27], 0.5 op_sel_hi:[1,0]
	v_pk_mul_f32 v[196:197], v[28:29], 0.5 op_sel_hi:[1,0]
	v_lshlrev_b32_e32 v198, 16, v162
	s_waitcnt lgkmcnt(0)
	v_pk_add_f32 v[62:63], v[62:63], v[182:183]
	global_load_dwordx2 v[182:183], v[180:181], off
	s_nop 0
	global_load_dwordx2 v[180:181], v[192:193], off
	global_load_dwordx2 v[172:173], v[148:149], off
	s_nop 0
	global_load_dwordx2 v[148:149], v[60:61], off
	v_pk_fma_f32 v[194:195], v[62:63], s[2:3], v[142:143] op_sel_hi:[1,0,0]
	v_lshlrev_b64 v[60:61], 12, v[138:139]
	v_mul_f32_e32 v62, 0x4b800000, v195
	v_cmp_gt_f32_e32 vcc, s68, v195
	v_lshl_add_u64 v[138:139], v[112:113], 0, v[60:61]
	v_mul_f32_e32 v24, 0x4b800000, v194
	v_cndmask_b32_e32 v62, v195, v62, vcc
	v_rsq_f32_e32 v62, v62
	v_and_b32_e32 v199, 0xffff0000, v162
	v_lshlrev_b32_e32 v162, 16, v163
	v_and_b32_e32 v163, 0xffff0000, v163
	v_mul_f32_e32 v60, 0x45800000, v62
	v_cndmask_b32_e32 v192, v62, v60, vcc
	v_pk_mul_f32 v[60:61], v[190:191], v[192:193] op_sel_hi:[1,0]
	v_pk_mul_f32 v[62:63], v[188:189], v[192:193] op_sel_hi:[1,0]
	s_waitcnt vmcnt(0) lgkmcnt(0)
	v_pk_fma_f32 v[60:61], v[36:37], v[60:61], v[56:57]
	v_pk_fma_f32 v[62:63], v[38:39], v[62:63], v[58:59]
	global_store_dwordx4 v[138:139], v[60:63], off
	ds_read_b128 v[36:39], v210 offset:1024
	ds_read_b128 v[56:59], v210 offset:5120
	v_pk_mul_f32 v[186:187], v[186:187], v[192:193] op_sel_hi:[1,0]
	v_pk_mul_f32 v[184:185], v[184:185], v[192:193] op_sel_hi:[1,0]
	v_pk_mul_f32 v[50:51], v[50:51], v[192:193] op_sel_hi:[1,0]
	v_pk_mul_f32 v[48:49], v[48:49], v[192:193] op_sel_hi:[1,0]
	v_pk_mul_f32 v[178:179], v[178:179], v[192:193] op_sel_hi:[1,0]
	v_pk_mul_f32 v[176:177], v[176:177], v[192:193] op_sel_hi:[1,0]
	v_cmp_gt_f32_e32 vcc, s68, v194
	v_pk_mul_f32 v[192:193], v[30:31], 0.5 op_sel_hi:[1,0]
	v_lshlrev_b32_e32 v188, 16, v166
	v_cndmask_b32_e32 v24, v194, v24, vcc
	v_rsq_f32_e32 v26, v24
	v_lshlrev_b64 v[24:25], 12, v[140:141]
	v_and_b32_e32 v189, 0xffff0000, v166
	v_lshlrev_b32_e32 v166, 16, v167
	v_and_b32_e32 v167, 0xffff0000, v167
	v_lshlrev_b32_e32 v190, 16, v168
	v_and_b32_e32 v191, 0xffff0000, v168
	v_lshlrev_b32_e32 v168, 16, v169
	v_and_b32_e32 v169, 0xffff0000, v169
	v_lshlrev_b32_e32 v200, 16, v164
	v_and_b32_e32 v201, 0xffff0000, v164
	v_lshlrev_b32_e32 v164, 16, v165
	v_and_b32_e32 v165, 0xffff0000, v165
	v_lshlrev_b32_e32 v202, 16, v158
	v_and_b32_e32 v203, 0xffff0000, v158
	v_lshlrev_b32_e32 v158, 16, v159
	v_and_b32_e32 v159, 0xffff0000, v159
	v_lshlrev_b32_e32 v204, 16, v160
	v_and_b32_e32 v205, 0xffff0000, v160
	v_lshlrev_b32_e32 v160, 16, v161
	v_and_b32_e32 v161, 0xffff0000, v161
	v_pk_add_f32 v[166:167], v[166:167], v[168:169]
	v_pk_add_f32 v[168:169], v[188:189], v[190:191]
	v_pk_mul_f32 v[22:23], v[22:23], 0.5 op_sel_hi:[1,0]
	v_pk_mul_f32 v[20:21], v[20:21], 0.5 op_sel_hi:[1,0]
	v_lshlrev_b32_e32 v232, 16, v150
	v_and_b32_e32 v233, 0xffff0000, v150
	v_lshlrev_b32_e32 v150, 16, v151
	v_and_b32_e32 v151, 0xffff0000, v151
	v_lshlrev_b32_e32 v234, 16, v156
	v_and_b32_e32 v235, 0xffff0000, v156
	v_lshlrev_b32_e32 v156, 16, v157
	v_and_b32_e32 v157, 0xffff0000, v157
	v_pk_add_f32 v[162:163], v[162:163], v[164:165]
	v_pk_add_f32 v[164:165], v[198:199], v[200:201]
	v_pk_add_f32 v[158:159], v[158:159], v[160:161]
	v_pk_add_f32 v[160:161], v[202:203], v[204:205]
	v_pk_mul_f32 v[168:169], v[196:197], v[168:169]
	v_pk_mul_f32 v[166:167], v[192:193], v[166:167]
	v_pk_mul_f32 v[18:19], v[18:19], 0.5 op_sel_hi:[1,0]
	v_pk_mul_f32 v[16:17], v[16:17], 0.5 op_sel_hi:[1,0]
	v_pk_add_f32 v[150:151], v[150:151], v[156:157]
	v_pk_add_f32 v[156:157], v[232:233], v[234:235]
	v_pk_mul_f32 v[164:165], v[20:21], v[164:165]
	v_pk_mul_f32 v[162:163], v[22:23], v[162:163]
	v_pk_mul_f32 v[160:161], v[230:231], v[160:161]
	v_pk_fma_f32 v[22:23], v[2:3], s[42:43], v[166:167] op_sel_hi:[1,0,1]
	v_pk_fma_f32 v[20:21], v[0:1], s[42:43], v[168:169] op_sel_hi:[1,0,1]
	v_pk_mul_f32 v[158:159], v[228:229], v[158:159]
	v_pk_mul_f32 v[156:157], v[16:17], v[156:157]
	v_pk_mul_f32 v[150:151], v[18:19], v[150:151]
	v_pk_fma_f32 v[18:19], v[6:7], s[42:43], v[162:163] op_sel_hi:[1,0,1]
	v_pk_fma_f32 v[16:17], v[4:5], s[42:43], v[164:165] op_sel_hi:[1,0,1]
	v_pk_fma_f32 v[4:5], v[8:9], s[42:43], v[160:161] op_sel_hi:[1,0,1]
	v_add_f32_e32 v8, v20, v21
	v_add_f32_e32 v9, v22, v23
	v_pk_fma_f32 v[6:7], v[10:11], s[42:43], v[158:159] op_sel_hi:[1,0,1]
	v_add_f32_e32 v10, v16, v17
	v_add_f32_e32 v11, v18, v19
	v_add_f32_e32 v8, v8, v9
	v_pk_fma_f32 v[2:3], v[14:15], s[42:43], v[150:151] op_sel_hi:[1,0,1]
	v_pk_fma_f32 v[0:1], v[12:13], s[42:43], v[156:157] op_sel_hi:[1,0,1]
	v_add_f32_e32 v12, v4, v5
	v_add_f32_e32 v13, v6, v7
	v_add_f32_e32 v9, v10, v11
	v_add_f32_e32 v8, 0, v8
	v_add_f32_e32 v14, v0, v1
	v_add_f32_e32 v15, v2, v3
	v_add_f32_e32 v10, v12, v13
	s_waitcnt vmcnt(1) lgkmcnt(0)
	v_pk_fma_f32 v[56:57], v[36:37], v[184:185], v[56:57]
	v_pk_fma_f32 v[58:59], v[38:39], v[186:187], v[58:59]
	global_store_dwordx4 v[138:139], v[56:59], off offset:1024
	ds_read_b128 v[36:39], v210 offset:2048
	ds_read_b128 v[184:187], v210 offset:6144
	v_add_f32_e32 v8, v8, v9
	v_add_f32_e32 v11, v14, v15
	v_add_f32_e32 v8, v8, v10
	v_add_f32_e32 v8, v8, v11
	ds_bpermute_b32 v9, v99, v8
	v_lshlrev_b32_e32 v14, 16, v171
	v_and_b32_e32 v15, 0xffff0000, v171
	s_waitcnt lgkmcnt(0)
	v_lshlrev_b32_e32 v162, 16, v182
	v_and_b32_e32 v163, 0xffff0000, v182
	v_add_f32_e32 v8, v8, v9
	ds_bpermute_b32 v9, v101, v8
	v_lshlrev_b32_e32 v164, 16, v183
	v_and_b32_e32 v165, 0xffff0000, v183
	v_lshlrev_b32_e32 v168, 16, v181
	v_and_b32_e32 v169, 0xffff0000, v181
	s_waitcnt lgkmcnt(0)
	v_add_f32_e32 v8, v8, v9
	ds_bpermute_b32 v9, v103, v8
	v_and_b32_e32 v13, 0xffff0000, v170
	v_lshlrev_b32_e32 v166, 16, v180
	v_and_b32_e32 v167, 0xffff0000, v180
	v_pk_add_f32 v[14:15], v[14:15], v[168:169]
	s_waitcnt lgkmcnt(0)
	v_add_f32_e32 v8, v8, v9
	ds_bpermute_b32 v9, v105, v8
	v_pk_mul_f32 v[70:71], v[70:71], 0.5 op_sel_hi:[1,0]
	v_pk_mul_f32 v[68:69], v[68:69], 0.5 op_sel_hi:[1,0]
	v_pk_mul_f32 v[66:67], v[66:67], 0.5 op_sel_hi:[1,0]
	v_pk_mul_f32 v[64:65], v[64:65], 0.5 op_sel_hi:[1,0]
	s_waitcnt lgkmcnt(0)
	v_add_f32_e32 v8, v8, v9
	ds_bpermute_b32 v9, v225, v8
	v_pk_mul_f32 v[66:67], v[66:67], v[14:15]
	v_lshlrev_b32_e32 v158, 16, v146
	v_and_b32_e32 v159, 0xffff0000, v146
	v_lshlrev_b32_e32 v146, 16, v147
	s_waitcnt lgkmcnt(0)
	v_add_f32_e32 v8, v8, v9
	ds_bpermute_b32 v9, v226, v8
	v_and_b32_e32 v147, 0xffff0000, v147
	v_lshlrev_b32_e32 v160, 16, v144
	v_and_b32_e32 v161, 0xffff0000, v144
	v_lshlrev_b32_e32 v144, 16, v145
	s_waitcnt lgkmcnt(0)
	v_add_f32_e32 v12, v8, v9
	v_fmamk_f32 v21, v12, 0xba800000, v21
	v_fmac_f32_e32 v20, 0xba800000, v12
	v_fmamk_f32 v23, v12, 0xba800000, v23
	v_fmac_f32_e32 v22, 0xba800000, v12
	v_fmamk_f32 v17, v12, 0xba800000, v17
	v_fmac_f32_e32 v16, 0xba800000, v12
	v_fmamk_f32 v19, v12, 0xba800000, v19
	v_fmac_f32_e32 v18, 0xba800000, v12
	v_fmamk_f32 v5, v12, 0xba800000, v5
	v_fmac_f32_e32 v4, 0xba800000, v12
	v_fmamk_f32 v7, v12, 0xba800000, v7
	v_fmac_f32_e32 v6, 0xba800000, v12
	v_fmamk_f32 v3, v12, 0xba800000, v3
	v_fmac_f32_e32 v2, 0xba800000, v12
	v_fmamk_f32 v1, v12, 0xba800000, v1
	v_fmac_f32_e32 v0, 0xba800000, v12
	v_lshlrev_b32_e32 v12, 16, v170
	v_pk_add_f32 v[12:13], v[12:13], v[166:167]
	v_and_b32_e32 v145, 0xffff0000, v145
	v_pk_mul_f32 v[64:65], v[64:65], v[12:13]
	v_lshlrev_b32_e32 v170, 16, v172
	v_and_b32_e32 v171, 0xffff0000, v172
	v_lshlrev_b32_e32 v172, 16, v173
	v_and_b32_e32 v173, 0xffff0000, v173
	v_pk_add_f32 v[158:159], v[158:159], v[170:171]
	v_pk_add_f32 v[146:147], v[146:147], v[172:173]
	v_pk_mul_f32 v[78:79], v[78:79], 0.5 op_sel_hi:[1,0]
	v_pk_mul_f32 v[76:77], v[76:77], 0.5 op_sel_hi:[1,0]
	v_pk_mul_f32 v[74:75], v[74:75], 0.5 op_sel_hi:[1,0]
	v_pk_mul_f32 v[72:73], v[72:73], 0.5 op_sel_hi:[1,0]
	v_pk_mul_f32 v[150:151], v[22:23], v[22:23]
	v_pk_mul_f32 v[156:157], v[20:21], v[20:21]
	v_readlane_b32 s4, v254, 33
	v_readlane_b32 s5, v254, 34
	s_waitcnt vmcnt(2) lgkmcnt(0)
	v_pk_fma_f32 v[48:49], v[36:37], v[48:49], v[184:185]
	v_pk_fma_f32 v[50:51], v[38:39], v[50:51], v[186:187]
	global_store_dwordx4 v[138:139], v[48:51], off offset:2048
	ds_read_b128 v[36:39], v210 offset:3072
	ds_read_b128 v[184:187], v210 offset:7168
	s_waitcnt vmcnt(3) lgkmcnt(0)
	v_pk_fma_f32 v[36:37], v[36:37], v[176:177], v[184:185]
	v_pk_fma_f32 v[38:39], v[38:39], v[178:179], v[186:187]
	global_store_dwordx4 v[138:139], v[36:39], off offset:3072
	ds_read_b128 v[176:179], v210
	ds_read_b128 v[184:187], v210 offset:4096
	v_lshl_add_u64 v[138:139], v[112:113], 0, v[24:25]
	v_mul_f32_e32 v24, 0x45800000, v26
	v_cndmask_b32_e32 v140, v26, v24, vcc
	v_pk_mul_f32 v[26:27], v[90:91], v[140:141] op_sel_hi:[1,0]
	v_pk_mul_f32 v[24:25], v[88:89], v[140:141] op_sel_hi:[1,0]
	v_pk_mul_f32 v[8:9], v[86:87], v[140:141] op_sel_hi:[1,0]
	v_pk_mul_f32 v[10:11], v[84:85], v[140:141] op_sel_hi:[1,0]
	s_waitcnt vmcnt(4) lgkmcnt(0)
	v_pk_fma_f32 v[24:25], v[176:177], v[24:25], v[184:185]
	v_pk_fma_f32 v[26:27], v[178:179], v[26:27], v[186:187]
	global_store_dwordx4 v[138:139], v[24:27], off
	ds_read_b128 v[28:31], v210 offset:1024
	ds_read_b128 v[88:91], v210 offset:5120
	s_waitcnt vmcnt(5) lgkmcnt(0)
	v_pk_fma_f32 v[28:29], v[28:29], v[10:11], v[88:89]
	v_pk_fma_f32 v[30:31], v[30:31], v[8:9], v[90:91]
	global_store_dwordx4 v[138:139], v[28:31], off offset:1024
	ds_read_b128 v[84:87], v210 offset:2048
	ds_read_b128 v[88:91], v210 offset:6144
	v_lshlrev_b32_e32 v8, 16, v174
	v_and_b32_e32 v9, 0xffff0000, v174
	v_lshlrev_b32_e32 v10, 16, v175
	v_and_b32_e32 v11, 0xffff0000, v175
	v_pk_add_f32 v[8:9], v[8:9], v[162:163]
	v_pk_add_f32 v[10:11], v[10:11], v[164:165]
	v_pk_mul_f32 v[8:9], v[68:69], v[8:9]
	v_pk_mul_f32 v[10:11], v[70:71], v[10:11]
	v_pk_fma_f32 v[12:13], v[40:41], s[42:43], v[8:9] op_sel_hi:[1,0,1]
	v_pk_fma_f32 v[14:15], v[42:43], s[42:43], v[10:11] op_sel_hi:[1,0,1]
	v_pk_fma_f32 v[8:9], v[34:35], s[42:43], v[66:67] op_sel_hi:[1,0,1]
	v_pk_mul_f32 v[10:11], v[82:83], v[140:141] op_sel_hi:[1,0]
	v_pk_mul_f32 v[34:35], v[80:81], v[140:141] op_sel_hi:[1,0]
	v_lshlrev_b32_e32 v174, 16, v148
	v_and_b32_e32 v175, 0xffff0000, v148
	v_lshlrev_b32_e32 v148, 16, v149
	v_and_b32_e32 v149, 0xffff0000, v149
	v_pk_add_f32 v[160:161], v[160:161], v[174:175]
	v_pk_add_f32 v[144:145], v[144:145], v[148:149]
	v_pk_mul_f32 v[68:69], v[78:79], v[146:147]
	v_pk_mul_f32 v[146:147], v[76:77], v[158:159]
	v_pk_mul_f32 v[144:145], v[74:75], v[144:145]
	v_pk_mul_f32 v[148:149], v[72:73], v[160:161]
	v_pk_fma_f32 v[66:67], v[46:47], s[42:43], v[144:145] op_sel_hi:[1,0,1]
	v_mov_b32_e32 v47, v9
	v_pk_fma_f32 v[70:71], v[54:55], s[42:43], v[68:69] op_sel_hi:[1,0,1]
	v_pk_fma_f32 v[68:69], v[52:53], s[42:43], v[146:147] op_sel_hi:[1,0,1]
	v_add_f32_e32 v54, v70, v71
	v_add_f32_e32 v52, v68, v69
	v_mov_b32_e32 v53, v66
	v_mov_b32_e32 v55, v67
	s_waitcnt vmcnt(6) lgkmcnt(0)
	v_pk_fma_f32 v[40:41], v[84:85], v[34:35], v[88:89]
	v_pk_fma_f32 v[42:43], v[86:87], v[10:11], v[90:91]
	global_store_dwordx4 v[138:139], v[40:43], off offset:2048
	ds_read_b128 v[72:75], v210 offset:3072
	ds_read_b128 v[76:79], v210 offset:7168
	v_pk_fma_f32 v[10:11], v[32:33], s[42:43], v[64:65] op_sel_hi:[1,0,1]
	v_pk_fma_f32 v[64:65], v[44:45], s[42:43], v[148:149] op_sel_hi:[1,0,1]
	v_pk_mov_b32 v[32:33], v[12:13], v[14:15] op_sel:[1,0]
	v_mov_b32_e32 v34, v12
	v_mov_b32_e32 v35, v15
	v_pk_mov_b32 v[44:45], v[10:11], v[8:9] op_sel:[1,0]
	v_mov_b32_e32 v46, v10
	v_pk_add_f32 v[32:33], v[32:33], v[34:35]
	v_pk_add_f32 v[34:35], v[44:45], v[46:47]
	v_add_f32_e32 v46, v32, v33
	v_pk_add_f32 v[32:33], v[34:35], v[34:35] op_sel:[0,1] op_sel_hi:[1,0]
	v_mov_b32_e32 v81, v64
	v_add_f32_e32 v80, 0, v46
	v_mov_b32_e32 v33, v65
	v_pk_add_f32 v[44:45], v[52:53], v[54:55]
	v_pk_add_f32 v[32:33], v[80:81], v[32:33]
	v_pk_mul_f32 v[34:35], v[16:17], v[16:17]
	v_pk_add_f32 v[32:33], v[32:33], v[44:45]
	v_mul_f32_e32 v44, v4, v4
	v_add_f32_e32 v45, v32, v33
	ds_bpermute_b32 v47, v99, v45
	v_pk_mul_f32 v[32:33], v[18:19], v[18:19]
	v_mul_f32_e32 v46, v6, v6
	v_pk_mov_b32 v[52:53], v[156:157], v[150:151] op_sel:[1,0]
	v_mov_b32_e32 v157, v151
	s_waitcnt lgkmcnt(0)
	v_add_f32_e32 v45, v45, v47
	ds_bpermute_b32 v47, v101, v45
	v_pk_mov_b32 v[54:55], v[34:35], v[32:33] op_sel:[1,0]
	v_mov_b32_e32 v35, v33
	v_pk_fma_f32 v[32:33], v[4:5], v[4:5], v[44:45] op_sel_hi:[1,1,0]
	v_pk_add_f32 v[34:35], v[54:55], v[34:35]
	s_waitcnt lgkmcnt(0)
	v_add_f32_e32 v80, v45, v47
	ds_bpermute_b32 v81, v103, v80
	v_pk_fma_f32 v[44:45], v[6:7], v[6:7], v[46:47] op_sel_hi:[1,1,0]
	v_pk_add_f32 v[46:47], v[52:53], v[156:157]
	v_mul_f32_e32 v32, v0, v0
	v_mul_f32_e32 v44, v1, v1
	s_waitcnt lgkmcnt(0)
	v_add_f32_e32 v52, v80, v81
	ds_bpermute_b32 v53, v105, v52
	v_pk_add_f32 v[32:33], v[32:33], v[44:45]
	v_pk_add_f32 v[46:47], v[46:47], v[46:47] op_sel_hi:[0,1]
	v_pk_add_f32 v[34:35], v[34:35], v[34:35] op_sel_hi:[0,1]
	v_mul_f32_e32 v46, v2, v2
	s_waitcnt lgkmcnt(0)
	v_add_f32_e32 v52, v52, v53
	ds_bpermute_b32 v53, v225, v52
	v_mul_f32_e32 v34, v3, v3
	v_pk_add_f32 v[34:35], v[46:47], v[34:35]
	s_waitcnt lgkmcnt(0)
	v_add_f32_e32 v44, v52, v53
	ds_bpermute_b32 v45, v226, v44
	v_pk_add_f32 v[80:81], v[32:33], v[34:35]
	v_pk_mul_f32 v[32:33], v[94:95], v[140:141] op_sel_hi:[1,0]
	v_pk_mul_f32 v[34:35], v[92:93], v[140:141] op_sel_hi:[1,0]
	v_mov_b32_e32 v83, v80
	s_waitcnt lgkmcnt(0)
	v_add_f32_e32 v44, v44, v45
	v_fmamk_f32 v13, v44, 0xba800000, v13
	v_fmac_f32_e32 v12, 0xba800000, v44
	v_fmamk_f32 v15, v44, 0xba800000, v15
	v_fmac_f32_e32 v14, 0xba800000, v44
	v_fmamk_f32 v11, v44, 0xba800000, v11
	v_fmac_f32_e32 v10, 0xba800000, v44
	v_fmamk_f32 v9, v44, 0xba800000, v9
	v_fmac_f32_e32 v8, 0xba800000, v44
	v_fmamk_f32 v69, v44, 0xba800000, v69
	v_fmac_f32_e32 v68, 0xba800000, v44
	v_fmamk_f32 v71, v44, 0xba800000, v71
	v_fmac_f32_e32 v70, 0xba800000, v44
	v_fmamk_f32 v67, v44, 0xba800000, v67
	v_fmac_f32_e32 v66, 0xba800000, v44
	v_fmamk_f32 v65, v44, 0xba800000, v65
	v_fmac_f32_e32 v64, 0xba800000, v44
	v_pk_mul_f32 v[84:85], v[14:15], v[14:15]
	v_mul_f32_e32 v80, v70, v70
	s_waitcnt vmcnt(7) lgkmcnt(0)
	v_pk_fma_f32 v[52:53], v[72:73], v[34:35], v[76:77]
	v_pk_fma_f32 v[54:55], v[74:75], v[32:33], v[78:79]
	global_store_dwordx4 v[138:139], v[52:55], off offset:3072
	ds_read_b128 v[32:35], v210
	ds_read_b128 v[44:47], v210 offset:4096
	v_pk_mul_f32 v[72:73], v[12:13], v[12:13]
	v_pk_mul_f32 v[74:75], v[8:9], v[8:9]
	v_pk_mul_f32 v[76:77], v[10:11], v[10:11]
	v_pk_mov_b32 v[86:87], v[72:73], v[84:85] op_sel:[1,0]
	v_mov_b32_e32 v73, v85
	v_pk_mov_b32 v[84:85], v[76:77], v[74:75] op_sel:[1,0]
	v_mov_b32_e32 v77, v75
	v_mul_f32_e32 v78, v68, v68
	v_pk_add_f32 v[72:73], v[86:87], v[72:73]
	v_pk_add_f32 v[76:77], v[84:85], v[76:77]
	v_pk_fma_f32 v[74:75], v[68:69], v[68:69], v[78:79] op_sel_hi:[1,1,0]
	v_pk_fma_f32 v[78:79], v[70:71], v[70:71], v[80:81] op_sel_hi:[1,1,0]
	v_pk_add_f32 v[72:73], v[72:73], v[72:73] op_sel_hi:[0,1]
	v_pk_add_f32 v[76:77], v[76:77], v[76:77] op_sel_hi:[0,1]
	v_mul_f32_e32 v74, v64, v64
	v_mul_f32_e32 v78, v65, v65
	v_mul_f32_e32 v72, v66, v66
	v_mul_f32_e32 v76, v67, v67
	v_pk_add_f32 v[74:75], v[74:75], v[78:79]
	v_pk_add_f32 v[72:73], v[72:73], v[76:77]
	s_nop 0
	v_pk_add_f32 v[72:73], v[74:75], v[72:73]
	s_nop 0
	v_mov_b32_e32 v82, v72
	v_mov_b32_e32 v80, v73
	v_pk_add_f32 v[72:73], v[82:83], v[80:81]
	ds_bpermute_b32 v75, v99, v73
	ds_bpermute_b32 v74, v99, v72
	s_waitcnt lgkmcnt(0)
	v_pk_add_f32 v[72:73], v[72:73], v[74:75]
	ds_bpermute_b32 v75, v101, v73
	ds_bpermute_b32 v74, v101, v72
	s_waitcnt lgkmcnt(0)
	v_pk_add_f32 v[72:73], v[72:73], v[74:75]
	ds_bpermute_b32 v75, v103, v73
	ds_bpermute_b32 v74, v103, v72
	s_waitcnt lgkmcnt(0)
	v_pk_add_f32 v[72:73], v[72:73], v[74:75]
	ds_bpermute_b32 v75, v105, v73
	ds_bpermute_b32 v74, v105, v72
	s_waitcnt lgkmcnt(0)
	v_pk_add_f32 v[72:73], v[72:73], v[74:75]
	ds_bpermute_b32 v75, v225, v73
	ds_bpermute_b32 v74, v225, v72
	s_waitcnt lgkmcnt(0)
	v_pk_add_f32 v[72:73], v[72:73], v[74:75]
	ds_bpermute_b32 v75, v226, v73
	ds_bpermute_b32 v74, v226, v72
	s_waitcnt lgkmcnt(0)
	v_pk_add_f32 v[72:73], v[72:73], v[74:75]
	s_nop 0
	v_pk_fma_f32 v[72:73], v[72:73], s[2:3], v[142:143] op_sel_hi:[1,0,0]
	s_nop 0
	v_mul_f32_e32 v74, 0x4b800000, v73
	v_cmp_gt_f32_e32 vcc, s68, v73
	s_nop 1
	v_cndmask_b32_e32 v73, v73, v74, vcc
	v_rsq_f32_e32 v73, v73
	v_lshlrev_b64 v[74:75], 12, v[132:133]
	v_lshl_add_u64 v[74:75], v[112:113], 0, v[74:75]
	v_mul_f32_e32 v76, 0x45800000, v73
	v_cndmask_b32_e32 v76, v73, v76, vcc
	v_pk_mul_f32 v[22:23], v[22:23], v[76:77] op_sel_hi:[1,0]
	v_pk_mul_f32 v[20:21], v[20:21], v[76:77] op_sel_hi:[1,0]
	s_waitcnt vmcnt(8) lgkmcnt(0)
	v_pk_fma_f32 v[46:47], v[34:35], v[22:23], v[46:47]
	v_pk_fma_f32 v[44:45], v[32:33], v[20:21], v[44:45]
	global_store_dwordx4 v[74:75], v[44:47], off
	ds_read_b128 v[20:23], v210 offset:1024
	ds_read_b128 v[32:35], v210 offset:5120
	v_pk_mul_f32 v[18:19], v[18:19], v[76:77] op_sel_hi:[1,0]
	v_pk_mul_f32 v[16:17], v[16:17], v[76:77] op_sel_hi:[1,0]
	v_pk_mul_f32 v[6:7], v[6:7], v[76:77] op_sel_hi:[1,0]
	v_pk_mul_f32 v[4:5], v[4:5], v[76:77] op_sel_hi:[1,0]
	v_pk_mul_f32 v[2:3], v[2:3], v[76:77] op_sel_hi:[1,0]
	v_pk_mul_f32 v[0:1], v[0:1], v[76:77] op_sel_hi:[1,0]
	v_mul_f32_e32 v73, 0x4b800000, v72
	v_cmp_gt_f32_e32 vcc, s68, v72
	s_waitcnt vmcnt(9) lgkmcnt(0)
	v_pk_fma_f32 v[32:33], v[20:21], v[16:17], v[32:33]
	v_pk_fma_f32 v[34:35], v[22:23], v[18:19], v[34:35]
	global_store_dwordx4 v[74:75], v[32:35], off offset:1024
	ds_read_b128 v[16:19], v210 offset:2048
	ds_read_b128 v[20:23], v210 offset:6144
	v_cndmask_b32_e32 v72, v72, v73, vcc
	s_waitcnt vmcnt(10) lgkmcnt(0)
	v_pk_fma_f32 v[20:21], v[16:17], v[4:5], v[20:21]
	v_pk_fma_f32 v[22:23], v[18:19], v[6:7], v[22:23]
	global_store_dwordx4 v[74:75], v[20:23], off offset:2048
	ds_read_b128 v[4:7], v210 offset:3072
	ds_read_b128 v[16:19], v210 offset:7168
	s_waitcnt vmcnt(11) lgkmcnt(0)
	v_pk_fma_f32 v[16:17], v[4:5], v[0:1], v[16:17]
	v_pk_fma_f32 v[18:19], v[6:7], v[2:3], v[18:19]
	global_store_dwordx4 v[74:75], v[16:19], off offset:3072
	ds_read_b128 v[0:3], v210
	ds_read_b128 v[4:7], v210 offset:4096
	v_rsq_f32_e32 v74, v72
	v_lshl_add_u64 v[72:73], v[112:113], 0, v[134:135]
	v_mul_f32_e32 v75, 0x45800000, v74
	v_cndmask_b32_e32 v74, v74, v75, vcc
	v_pk_mul_f32 v[14:15], v[14:15], v[74:75] op_sel_hi:[1,0]
	v_pk_mul_f32 v[12:13], v[12:13], v[74:75] op_sel_hi:[1,0]
	v_pk_mul_f32 v[76:77], v[8:9], v[74:75] op_sel_hi:[1,0]
	v_pk_mul_f32 v[8:9], v[10:11], v[74:75] op_sel_hi:[1,0]
	v_pk_mul_f32 v[70:71], v[70:71], v[74:75] op_sel_hi:[1,0]
	v_pk_mul_f32 v[68:69], v[68:69], v[74:75] op_sel_hi:[1,0]
	v_pk_mul_f32 v[66:67], v[66:67], v[74:75] op_sel_hi:[1,0]
	v_pk_mul_f32 v[64:65], v[64:65], v[74:75] op_sel_hi:[1,0]
	s_andn2_b64 vcc, exec, s[4:5]
	s_waitcnt vmcnt(12) lgkmcnt(0)
	v_pk_fma_f32 v[12:13], v[0:1], v[12:13], v[4:5]
	v_pk_fma_f32 v[14:15], v[2:3], v[14:15], v[6:7]
	global_store_dwordx4 v[72:73], v[12:15], off
	ds_read_b128 v[0:3], v210 offset:1024
	ds_read_b128 v[4:7], v210 offset:5120
	s_waitcnt vmcnt(13) lgkmcnt(0)
	v_pk_fma_f32 v[8:9], v[0:1], v[8:9], v[4:5]
	v_pk_fma_f32 v[10:11], v[2:3], v[76:77], v[6:7]
	global_store_dwordx4 v[72:73], v[8:11], off offset:1024
	ds_read_b128 v[0:3], v210 offset:2048
	ds_read_b128 v[4:7], v210 offset:6144
	s_waitcnt vmcnt(14) lgkmcnt(0)
	v_pk_fma_f32 v[4:5], v[0:1], v[68:69], v[4:5]
	v_pk_fma_f32 v[6:7], v[2:3], v[70:71], v[6:7]
	global_store_dwordx4 v[72:73], v[4:7], off offset:2048
	ds_read_b128 v[0:3], v210 offset:3072
	ds_read_b128 v[68:71], v210 offset:7168
	s_waitcnt vmcnt(15) lgkmcnt(0)
	v_pk_fma_f32 v[0:1], v[0:1], v[64:65], v[68:69]
	v_pk_fma_f32 v[2:3], v[2:3], v[66:67], v[70:71]
	global_store_dwordx4 v[72:73], v[0:3], off offset:3072
	s_cbranch_vccnz .LBB0_179
	v_mad_u64_u32 v[70:71], s[4:5], v126, s7, 0
	v_mad_i32_i24 v71, v127, s7, v71
	v_mad_u64_u32 v[68:69], s[4:5], v128, s7, 0
	v_mad_u64_u32 v[66:67], s[4:5], v130, s7, 0
	v_mad_u64_u32 v[64:65], s[4:5], v136, s7, 0
	v_lshl_add_u64 v[70:71], s[60:61], 0, v[70:71]
	s_mov_b64 s[4:5], 0x3000
	s_mov_b64 s[8:9], 0x4000
	v_lshl_add_u64 v[72:73], v[70:71], 0, s[4:5]
	v_lshl_add_u64 v[70:71], v[70:71], 0, s[8:9]
	v_lshl_add_u64 v[74:75], v[72:73], 0, v[152:153]
	v_lshl_add_u64 v[78:79], v[70:71], 0, v[152:153]
	global_load_dwordx4 v[214:217], v[74:75], off offset:1024
	global_load_dwordx4 v[218:221], v[74:75], off offset:2048
	global_load_dwordx4 v[74:77], v[74:75], off
	v_mad_i32_i24 v69, v129, s7, v69
	global_load_dwordx4 v[236:239], v[78:79], off offset:1024
	global_load_dwordx4 v[240:243], v[78:79], off offset:2048
	global_load_dwordx4 v[78:81], v[78:79], off
	v_mad_i32_i24 v67, v131, s7, v67
	v_mad_i32_i24 v65, v137, s7, v65
	s_waitcnt vmcnt(0) lgkmcnt(0)
	v_pk_add_f32 v[80:81], v[80:81], 1.0 op_sel_hi:[1,0]
	v_pk_add_f32 v[78:79], v[78:79], 1.0 op_sel_hi:[1,0]
	v_pk_fma_f32 v[62:63], v[62:63], v[80:81], v[76:77]
	v_pk_fma_f32 v[60:61], v[60:61], v[78:79], v[74:75]
	s_nop 0
	v_cvt_pk_bf16_f32 v60, v60, v61
	v_cvt_pk_bf16_f32 v61, v62, v63
	global_store_dwordx2 v[118:119], v[60:61], off
	v_lshlrev_b32_e32 v60, 2, v100
	v_mov_b32_e32 v61, v153
	v_lshl_add_u64 v[62:63], v[72:73], 0, v[60:61]
	v_mov_b64_e32 v[74:75], v[214:215]
	v_mov_b64_e32 v[76:77], v[216:217]
	v_lshl_add_u64 v[62:63], v[70:71], 0, v[60:61]
	v_mov_b64_e32 v[78:79], v[236:237]
	v_mov_b64_e32 v[80:81], v[238:239]
	v_pk_add_f32 v[62:63], v[80:81], 1.0 op_sel_hi:[1,0]
	v_pk_add_f32 v[78:79], v[78:79], 1.0 op_sel_hi:[1,0]
	v_pk_fma_f32 v[58:59], v[58:59], v[62:63], v[76:77]
	v_pk_fma_f32 v[56:57], v[56:57], v[78:79], v[74:75]
	s_nop 0
	v_cvt_pk_bf16_f32 v56, v56, v57
	v_cvt_pk_bf16_f32 v57, v58, v59
	global_store_dwordx2 v[118:119], v[56:57], off offset:512
	v_lshlrev_b32_e32 v56, 2, v102
	v_mov_b32_e32 v57, v153
	v_lshl_add_u64 v[58:59], v[72:73], 0, v[56:57]
	v_mov_b64_e32 v[74:75], v[218:219]
	v_mov_b64_e32 v[76:77], v[220:221]
	v_lshl_add_u64 v[58:59], v[70:71], 0, v[56:57]
	v_mov_b64_e32 v[78:79], v[240:241]
	v_mov_b64_e32 v[80:81], v[242:243]
	v_pk_add_f32 v[58:59], v[80:81], 1.0 op_sel_hi:[1,0]
	v_pk_add_f32 v[62:63], v[78:79], 1.0 op_sel_hi:[1,0]
	v_pk_fma_f32 v[50:51], v[50:51], v[58:59], v[76:77]
	v_pk_fma_f32 v[48:49], v[48:49], v[62:63], v[74:75]
	s_nop 0
	v_cvt_pk_bf16_f32 v48, v48, v49
	v_cvt_pk_bf16_f32 v49, v50, v51
	global_store_dwordx2 v[118:119], v[48:49], off offset:1024
	v_lshlrev_b32_e32 v48, 2, v104
	v_mov_b32_e32 v49, v153
	v_lshl_add_u64 v[50:51], v[72:73], 0, v[48:49]
	global_load_dwordx4 v[72:75], v[50:51], off
	v_lshl_add_u64 v[50:51], v[70:71], 0, v[48:49]
	global_load_dwordx4 v[76:79], v[50:51], off
	s_waitcnt vmcnt(0) lgkmcnt(0)
	v_pk_add_f32 v[50:51], v[78:79], 1.0 op_sel_hi:[1,0]
	v_pk_add_f32 v[58:59], v[76:77], 1.0 op_sel_hi:[1,0]
	v_pk_fma_f32 v[38:39], v[38:39], v[50:51], v[74:75]
	v_pk_fma_f32 v[36:37], v[36:37], v[58:59], v[72:73]
	v_lshlrev_b64 v[50:51], 11, v[124:125]
	v_cvt_pk_bf16_f32 v36, v36, v37
	v_cvt_pk_bf16_f32 v37, v38, v39
	global_store_dwordx2 v[118:119], v[36:37], off offset:1536
	v_lshl_add_u64 v[36:37], s[60:61], 0, v[68:69]
	v_lshl_add_u64 v[38:39], v[36:37], 0, s[4:5]
	v_lshl_add_u64 v[36:37], v[36:37], 0, s[8:9]
	v_lshl_add_u64 v[58:59], v[38:39], 0, v[152:153]
	global_load_dwordx4 v[214:217], v[58:59], off offset:1024
	global_load_dwordx4 v[218:221], v[58:59], off offset:2048
	global_load_dwordx4 v[68:71], v[58:59], off
	v_lshl_add_u64 v[58:59], v[36:37], 0, v[152:153]
	global_load_dwordx4 v[236:239], v[58:59], off offset:1024
	global_load_dwordx4 v[240:243], v[58:59], off offset:2048
	global_load_dwordx4 v[72:75], v[58:59], off
	v_lshl_add_u64 v[50:51], v[114:115], 0, v[50:51]
	s_waitcnt vmcnt(0) lgkmcnt(0)
	v_pk_add_f32 v[58:59], v[74:75], 1.0 op_sel_hi:[1,0]
	v_pk_add_f32 v[62:63], v[72:73], 1.0 op_sel_hi:[1,0]
	v_pk_fma_f32 v[26:27], v[26:27], v[58:59], v[70:71]
	v_pk_fma_f32 v[24:25], v[24:25], v[62:63], v[68:69]
	v_lshl_add_u64 v[58:59], v[36:37], 0, v[60:61]
	v_cvt_pk_bf16_f32 v24, v24, v25
	v_cvt_pk_bf16_f32 v25, v26, v27
	global_store_dwordx2 v[50:51], v[24:25], off
	v_lshl_add_u64 v[24:25], v[38:39], 0, v[60:61]
	v_mov_b64_e32 v[24:25], v[214:215]
	v_mov_b64_e32 v[26:27], v[216:217]
	s_nop 0
	v_mov_b64_e32 v[68:69], v[236:237]
	v_mov_b64_e32 v[70:71], v[238:239]
	v_pk_add_f32 v[58:59], v[70:71], 1.0 op_sel_hi:[1,0]
	v_pk_add_f32 v[62:63], v[68:69], 1.0 op_sel_hi:[1,0]
	v_pk_fma_f32 v[26:27], v[30:31], v[58:59], v[26:27]
	v_pk_fma_f32 v[24:25], v[28:29], v[62:63], v[24:25]
	v_lshl_add_u64 v[28:29], v[36:37], 0, v[56:57]
	v_cvt_pk_bf16_f32 v24, v24, v25
	v_cvt_pk_bf16_f32 v25, v26, v27
	global_store_dwordx2 v[50:51], v[24:25], off offset:512
	v_lshl_add_u64 v[24:25], v[38:39], 0, v[56:57]
	v_mov_b64_e32 v[24:25], v[218:219]
	v_mov_b64_e32 v[26:27], v[220:221]
	s_nop 0
	v_mov_b64_e32 v[28:29], v[240:241]
	v_mov_b64_e32 v[30:31], v[242:243]
	v_pk_add_f32 v[30:31], v[30:31], 1.0 op_sel_hi:[1,0]
	v_pk_add_f32 v[28:29], v[28:29], 1.0 op_sel_hi:[1,0]
	v_pk_fma_f32 v[26:27], v[42:43], v[30:31], v[26:27]
	v_pk_fma_f32 v[24:25], v[40:41], v[28:29], v[24:25]
	v_lshl_add_u64 v[28:29], v[36:37], 0, v[48:49]
	v_cvt_pk_bf16_f32 v24, v24, v25
	v_cvt_pk_bf16_f32 v25, v26, v27
	global_store_dwordx2 v[50:51], v[24:25], off offset:1024
	v_lshl_add_u64 v[24:25], v[38:39], 0, v[48:49]
	global_load_dwordx4 v[24:27], v[24:25], off
	s_nop 0
	global_load_dwordx4 v[28:31], v[28:29], off
	s_waitcnt vmcnt(0) lgkmcnt(0)
	v_pk_add_f32 v[30:31], v[30:31], 1.0 op_sel_hi:[1,0]
	v_pk_add_f32 v[28:29], v[28:29], 1.0 op_sel_hi:[1,0]
	v_pk_fma_f32 v[26:27], v[54:55], v[30:31], v[26:27]
	v_pk_fma_f32 v[24:25], v[52:53], v[28:29], v[24:25]
	v_lshlrev_b64 v[30:31], 11, v[122:123]
	v_cvt_pk_bf16_f32 v24, v24, v25
	v_cvt_pk_bf16_f32 v25, v26, v27
	global_store_dwordx2 v[50:51], v[24:25], off offset:1536
	v_lshl_add_u64 v[24:25], s[60:61], 0, v[66:67]
	v_lshl_add_u64 v[40:41], v[24:25], 0, s[4:5]
	v_lshl_add_u64 v[24:25], v[24:25], 0, s[8:9]
	v_lshl_add_u64 v[26:27], v[40:41], 0, v[152:153]
	v_lshl_add_u64 v[36:37], v[24:25], 0, v[152:153]
	global_load_dwordx4 v[214:217], v[26:27], off offset:1024
	global_load_dwordx4 v[218:221], v[26:27], off offset:2048
	global_load_dwordx4 v[26:29], v[26:27], off
	v_lshl_add_u64 v[42:43], v[114:115], 0, v[30:31]
	global_load_dwordx4 v[236:239], v[36:37], off offset:1024
	global_load_dwordx4 v[240:243], v[36:37], off offset:2048
	global_load_dwordx4 v[36:39], v[36:37], off
	v_lshl_add_u64 v[30:31], v[24:25], 0, v[60:61]
	s_waitcnt vmcnt(0) lgkmcnt(0)
	v_pk_add_f32 v[38:39], v[38:39], 1.0 op_sel_hi:[1,0]
	v_pk_add_f32 v[36:37], v[36:37], 1.0 op_sel_hi:[1,0]
	v_pk_fma_f32 v[28:29], v[46:47], v[38:39], v[28:29]
	v_pk_fma_f32 v[26:27], v[44:45], v[36:37], v[26:27]
	s_nop 0
	v_cvt_pk_bf16_f32 v26, v26, v27
	v_cvt_pk_bf16_f32 v27, v28, v29
	global_store_dwordx2 v[42:43], v[26:27], off
	v_lshl_add_u64 v[26:27], v[40:41], 0, v[60:61]
	v_mov_b64_e32 v[26:27], v[214:215]
	v_mov_b64_e32 v[28:29], v[216:217]
	s_nop 0
	v_mov_b64_e32 v[36:37], v[236:237]
	v_mov_b64_e32 v[38:39], v[238:239]
	v_pk_add_f32 v[30:31], v[38:39], 1.0 op_sel_hi:[1,0]
	v_pk_add_f32 v[36:37], v[36:37], 1.0 op_sel_hi:[1,0]
	v_pk_fma_f32 v[28:29], v[34:35], v[30:31], v[28:29]
	v_pk_fma_f32 v[26:27], v[32:33], v[36:37], v[26:27]
	v_lshl_add_u64 v[30:31], v[24:25], 0, v[56:57]
	v_cvt_pk_bf16_f32 v26, v26, v27
	v_cvt_pk_bf16_f32 v27, v28, v29
	global_store_dwordx2 v[42:43], v[26:27], off offset:512
	v_lshl_add_u64 v[26:27], v[40:41], 0, v[56:57]
	v_mov_b64_e32 v[26:27], v[218:219]
	v_mov_b64_e32 v[28:29], v[220:221]
	v_lshl_add_u64 v[24:25], v[24:25], 0, v[48:49]
	v_mov_b64_e32 v[30:31], v[240:241]
	v_mov_b64_e32 v[32:33], v[242:243]
	v_pk_add_f32 v[32:33], v[32:33], 1.0 op_sel_hi:[1,0]
	v_pk_add_f32 v[30:31], v[30:31], 1.0 op_sel_hi:[1,0]
	v_pk_fma_f32 v[22:23], v[22:23], v[32:33], v[28:29]
	v_pk_fma_f32 v[20:21], v[20:21], v[30:31], v[26:27]
	v_lshlrev_b64 v[28:29], 11, v[120:121]
	v_cvt_pk_bf16_f32 v20, v20, v21
	v_cvt_pk_bf16_f32 v21, v22, v23
	global_store_dwordx2 v[42:43], v[20:21], off offset:1024
	v_lshl_add_u64 v[20:21], v[40:41], 0, v[48:49]
	global_load_dwordx4 v[20:23], v[20:21], off
	s_nop 0
	global_load_dwordx4 v[24:27], v[24:25], off
	s_waitcnt vmcnt(0) lgkmcnt(0)
	v_pk_add_f32 v[26:27], v[26:27], 1.0 op_sel_hi:[1,0]
	v_pk_add_f32 v[24:25], v[24:25], 1.0 op_sel_hi:[1,0]
	v_pk_fma_f32 v[18:19], v[18:19], v[26:27], v[22:23]
	v_pk_fma_f32 v[16:17], v[16:17], v[24:25], v[20:21]
	s_nop 0
	v_cvt_pk_bf16_f32 v16, v16, v17
	v_cvt_pk_bf16_f32 v17, v18, v19
	global_store_dwordx2 v[42:43], v[16:17], off offset:1536
	v_lshl_add_u64 v[16:17], s[60:61], 0, v[64:65]
	v_lshl_add_u64 v[26:27], v[16:17], 0, s[4:5]
	v_lshl_add_u64 v[16:17], v[16:17], 0, s[8:9]
	v_lshl_add_u64 v[18:19], v[26:27], 0, v[152:153]
	v_lshl_add_u64 v[22:23], v[16:17], 0, v[152:153]
	global_load_dwordx4 v[214:217], v[18:19], off offset:1024
	global_load_dwordx4 v[218:221], v[18:19], off offset:2048
	global_load_dwordx4 v[18:21], v[18:19], off
	s_nop 0
	global_load_dwordx4 v[236:239], v[22:23], off offset:1024
	global_load_dwordx4 v[240:243], v[22:23], off offset:2048
	global_load_dwordx4 v[22:25], v[22:23], off
	s_waitcnt vmcnt(0) lgkmcnt(0)
	v_pk_add_f32 v[24:25], v[24:25], 1.0 op_sel_hi:[1,0]
	v_pk_add_f32 v[22:23], v[22:23], 1.0 op_sel_hi:[1,0]
	v_pk_fma_f32 v[14:15], v[14:15], v[24:25], v[20:21]
	v_pk_fma_f32 v[12:13], v[12:13], v[22:23], v[18:19]
	v_lshl_add_u64 v[22:23], v[114:115], 0, v[28:29]
	v_cvt_pk_bf16_f32 v12, v12, v13
	v_cvt_pk_bf16_f32 v13, v14, v15
	global_store_dwordx2 v[22:23], v[12:13], off
	v_lshl_add_u64 v[12:13], v[26:27], 0, v[60:61]
	v_lshl_add_u64 v[18:19], v[16:17], 0, v[60:61]
	v_mov_b64_e32 v[12:13], v[214:215]
	v_mov_b64_e32 v[14:15], v[216:217]
	s_nop 0
	v_mov_b64_e32 v[18:19], v[236:237]
	v_mov_b64_e32 v[20:21], v[238:239]
	v_pk_add_f32 v[20:21], v[20:21], 1.0 op_sel_hi:[1,0]
	v_pk_add_f32 v[18:19], v[18:19], 1.0 op_sel_hi:[1,0]
	v_pk_fma_f32 v[10:11], v[10:11], v[20:21], v[14:15]
	v_pk_fma_f32 v[8:9], v[8:9], v[18:19], v[12:13]
	v_lshl_add_u64 v[12:13], v[16:17], 0, v[56:57]
	v_cvt_pk_bf16_f32 v8, v8, v9
	v_cvt_pk_bf16_f32 v9, v10, v11
	global_store_dwordx2 v[22:23], v[8:9], off offset:512
	v_lshl_add_u64 v[8:9], v[26:27], 0, v[56:57]
	v_mov_b64_e32 v[8:9], v[218:219]
	v_mov_b64_e32 v[10:11], v[220:221]
	s_nop 0
	v_mov_b64_e32 v[12:13], v[240:241]
	v_mov_b64_e32 v[14:15], v[242:243]
	v_pk_add_f32 v[14:15], v[14:15], 1.0 op_sel_hi:[1,0]
	v_pk_add_f32 v[12:13], v[12:13], 1.0 op_sel_hi:[1,0]
	v_pk_fma_f32 v[6:7], v[6:7], v[14:15], v[10:11]
	v_pk_fma_f32 v[4:5], v[4:5], v[12:13], v[8:9]
	v_lshl_add_u64 v[8:9], v[16:17], 0, v[48:49]
	v_cvt_pk_bf16_f32 v4, v4, v5
	v_cvt_pk_bf16_f32 v5, v6, v7
	global_store_dwordx2 v[22:23], v[4:5], off offset:1024
	v_lshl_add_u64 v[4:5], v[26:27], 0, v[48:49]
	global_load_dwordx4 v[4:7], v[4:5], off
	s_nop 0
	global_load_dwordx4 v[8:11], v[8:9], off
	s_waitcnt vmcnt(0) lgkmcnt(0)
	v_pk_add_f32 v[10:11], v[10:11], 1.0 op_sel_hi:[1,0]
	v_pk_add_f32 v[8:9], v[8:9], 1.0 op_sel_hi:[1,0]
	v_pk_fma_f32 v[2:3], v[2:3], v[10:11], v[6:7]
	v_pk_fma_f32 v[0:1], v[0:1], v[8:9], v[4:5]
	s_nop 0
	v_cvt_pk_bf16_f32 v0, v0, v1
	v_cvt_pk_bf16_f32 v1, v2, v3
	global_store_dwordx2 v[22:23], v[0:1], off offset:1536
	s_branch .LBB0_179

.LBB0_225:
	global_load_dwordx4 v[154:157], v[74:75], off
	global_load_dwordx4 v[158:161], v[76:77], off
	global_load_dwordx4 v[162:165], v[74:75], off offset:1024
	global_load_dwordx4 v[166:169], v[76:77], off offset:1024
	global_load_dwordx4 v[170:173], v[74:75], off offset:2048
	global_load_dwordx4 v[174:177], v[76:77], off offset:2048
	global_load_dwordx4 v[178:181], v[74:75], off offset:3072
	global_load_dwordx4 v[182:185], v[76:77], off offset:3072
	v_add_u32_e32 v0, 0xfffff000, v64
	v_ashrrev_i32_e32 v0, 10, v0
	v_add_u32_e32 v0, 1, v0
	v_cmp_lt_i32_e32 vcc, s33, v64
	global_load_dwordx4 v[186:189], v[86:87], off offset:1024
	global_load_dwordx4 v[190:193], v[86:87], off offset:2048
	global_load_dwordx4 v[194:197], v[86:87], off offset:3072
	global_load_dwordx4 v[8:11], v[86:87], off
	s_mov_b64 s[8:9], 0x1000000
	v_cndmask_b32_e32 v94, 0, v0, vcc
	v_add_u32_e32 v0, s38, v64
	v_cmp_lt_i32_e32 vcc, s6, v0
	v_ashrrev_i32_e32 v95, 31, v94
	v_lshl_add_u64 v[4:5], v[94:95], 0, s[28:29]
	v_cndmask_b32_e32 v0, v0, v64, vcc
	v_add_u32_e32 v1, 0xfffff000, v0
	v_ashrrev_i32_e32 v1, 10, v1
	v_add_u32_e32 v1, 1, v1
	v_cmp_lt_i32_e32 vcc, s33, v0
	v_mad_u64_u32 v[2:3], s[4:5], v4, s7, v[78:79]
	s_nop 0
	v_cndmask_b32_e32 v92, 0, v1, vcc
	v_add_u32_e32 v1, s35, v64
	v_cmp_lt_i32_e32 vcc, s6, v1
	s_mov_b32 s4, 0x1000000
	v_mad_i32_i24 v3, v5, s7, v3
	v_cndmask_b32_e32 v18, v1, v64, vcc
	v_add_u32_e32 v1, 0xfffff000, v18
	v_ashrrev_i32_e32 v1, 10, v1
	v_add_u32_e32 v1, 1, v1
	v_cmp_lt_i32_e32 vcc, s33, v18
	global_load_dwordx4 v[198:201], v[2:3], off offset:1024
	global_load_dwordx4 v[202:205], v[2:3], off offset:2048
	global_load_dwordx4 v[224:227], v[2:3], off offset:3072
	global_load_dwordx4 v[12:15], v[2:3], off
	v_ashrrev_i32_e32 v93, 31, v92
	v_cndmask_b32_e32 v90, 0, v1, vcc
	v_add_u32_e32 v1, s26, v64
	v_cmp_lt_i32_e32 vcc, s6, v1
	v_lshlrev_b32_e32 v152, 1, v66
	v_lshlrev_b32_e32 v42, 1, v68
	v_cndmask_b32_e32 v16, v1, v64, vcc
	v_add_u32_e32 v1, 0xfffff000, v16
	v_ashrrev_i32_e32 v1, 10, v1
	v_add_u32_e32 v1, 1, v1
	v_cmp_lt_i32_e32 vcc, s33, v16
	v_mov_b32_e32 v43, v153
	v_lshlrev_b32_e32 v104, 1, v70
	v_cndmask_b32_e32 v88, 0, v1, vcc
	v_add_co_u32_e32 v4, vcc, s4, v84
	s_brev_b32 s4, 64
	s_nop 0
	v_addc_co_u32_e32 v5, vcc, 0, v85, vcc
	global_load_dwordx2 v[228:229], v[4:5], off offset:512
	global_load_dwordx2 v[230:231], v[4:5], off offset:1024
	global_load_dwordx2 v[232:233], v[4:5], off offset:1536
	global_load_dwordx2 v[6:7], v[4:5], off
	v_mov_b32_e32 v105, v153
	v_lshlrev_b32_e32 v106, 1, v72
	v_mov_b32_e32 v107, v153
	v_ashrrev_i32_e32 v19, 31, v18
	v_ashrrev_i32_e32 v91, 31, v90
	v_lshlrev_b64 v[100:101], 11, v[18:19]
	v_ashrrev_i32_e32 v17, 31, v16
	v_ashrrev_i32_e32 v89, 31, v88
	s_waitcnt vmcnt(0) lgkmcnt(0)
	v_pk_mul_f32 v[14:15], v[14:15], 0.5 op_sel_hi:[1,0]
	v_pk_mul_f32 v[12:13], v[12:13], 0.5 op_sel_hi:[1,0]
	v_lshlrev_b32_e32 v20, 16, v6
	v_and_b32_e32 v21, 0xffff0000, v6
	v_add_co_u32_e32 v6, vcc, s4, v84
	v_lshlrev_b32_e32 v22, 16, v7
	v_and_b32_e32 v23, 0xffff0000, v7
	v_addc_co_u32_e32 v7, vcc, 0, v85, vcc
	global_load_dwordx2 v[234:235], v[6:7], off offset:512
	global_load_dwordx2 v[236:237], v[6:7], off offset:1024
	global_load_dwordx2 v[238:239], v[6:7], off offset:1536
	global_load_dwordx2 v[24:25], v[6:7], off
	s_waitcnt vmcnt(0) lgkmcnt(0)
	v_lshlrev_b32_e32 v26, 16, v24
	v_and_b32_e32 v27, 0xffff0000, v24
	v_lshlrev_b32_e32 v24, 16, v25
	v_and_b32_e32 v25, 0xffff0000, v25
	v_pk_add_f32 v[20:21], v[20:21], v[26:27]
	v_pk_add_f32 v[22:23], v[22:23], v[24:25]
	v_pk_mul_f32 v[12:13], v[12:13], v[20:21]
	v_pk_mul_f32 v[14:15], v[14:15], v[22:23]
	v_pk_fma_f32 v[8:9], v[8:9], s[42:43], v[12:13] op_sel_hi:[1,0,1]
	v_pk_fma_f32 v[10:11], v[10:11], s[42:43], v[14:15] op_sel_hi:[1,0,1]
	v_mov_b32_e32 v14, v8
	v_pk_mov_b32 v[12:13], v[8:9], v[10:11] op_sel:[1,0]
	v_mov_b32_e32 v15, v11
	v_pk_add_f32 v[12:13], v[12:13], v[14:15]
	s_nop 0
	v_add_f32_e32 v1, v12, v13
	v_mov_b64_e32 v[12:13], v[186:187]
	v_mov_b64_e32 v[14:15], v[188:189]
	v_mov_b64_e32 v[20:21], v[198:199]
	v_mov_b64_e32 v[22:23], v[200:201]
	v_mov_b64_e32 v[24:25], v[228:229]
	v_mov_b64_e32 v[30:31], v[234:235]
	v_add_f32_e32 v28, 0, v1
	v_ashrrev_i32_e32 v1, 31, v0
	v_lshlrev_b64 v[96:97], 11, v[0:1]
	v_pk_mul_f32 v[22:23], v[22:23], 0.5 op_sel_hi:[1,0]
	v_lshlrev_b32_e32 v26, 16, v24
	v_and_b32_e32 v27, 0xffff0000, v24
	v_lshlrev_b32_e32 v24, 16, v25
	v_and_b32_e32 v25, 0xffff0000, v25
	v_lshlrev_b32_e32 v32, 16, v30
	v_and_b32_e32 v33, 0xffff0000, v30
	v_lshlrev_b32_e32 v30, 16, v31
	v_and_b32_e32 v31, 0xffff0000, v31
	v_pk_mul_f32 v[20:21], v[20:21], 0.5 op_sel_hi:[1,0]
	v_pk_add_f32 v[26:27], v[26:27], v[32:33]
	v_pk_add_f32 v[24:25], v[24:25], v[30:31]
	v_pk_mul_f32 v[20:21], v[20:21], v[26:27]
	v_pk_mul_f32 v[22:23], v[22:23], v[24:25]
	v_pk_fma_f32 v[12:13], v[12:13], s[42:43], v[20:21] op_sel_hi:[1,0,1]
	v_pk_fma_f32 v[14:15], v[14:15], s[42:43], v[22:23] op_sel_hi:[1,0,1]
	v_mov_b32_e32 v22, v12
	v_pk_mov_b32 v[20:21], v[12:13], v[14:15] op_sel:[1,0]
	v_mov_b32_e32 v23, v15
	v_pk_add_f32 v[20:21], v[20:21], v[22:23]
	s_nop 0
	v_pk_add_f32 v[30:31], v[20:21], v[20:21] op_sel:[0,1] op_sel_hi:[1,0]
	v_mov_b64_e32 v[20:21], v[190:191]
	v_mov_b64_e32 v[22:23], v[192:193]
	v_mov_b64_e32 v[24:25], v[202:203]
	v_mov_b64_e32 v[26:27], v[204:205]
	v_mov_b64_e32 v[32:33], v[230:231]
	v_mov_b64_e32 v[36:37], v[236:237]
	v_pk_mul_f32 v[26:27], v[26:27], 0.5 op_sel_hi:[1,0]
	v_lshlrev_b32_e32 v34, 16, v32
	v_and_b32_e32 v35, 0xffff0000, v32
	v_lshlrev_b32_e32 v32, 16, v33
	v_and_b32_e32 v33, 0xffff0000, v33
	v_lshlrev_b32_e32 v38, 16, v36
	v_and_b32_e32 v39, 0xffff0000, v36
	v_lshlrev_b32_e32 v36, 16, v37
	v_and_b32_e32 v37, 0xffff0000, v37
	v_pk_mul_f32 v[24:25], v[24:25], 0.5 op_sel_hi:[1,0]
	v_pk_add_f32 v[32:33], v[32:33], v[36:37]
	v_pk_add_f32 v[34:35], v[34:35], v[38:39]
	v_pk_mul_f32 v[26:27], v[26:27], v[32:33]
	v_pk_mul_f32 v[24:25], v[24:25], v[34:35]
	v_pk_fma_f32 v[22:23], v[22:23], s[42:43], v[26:27] op_sel_hi:[1,0,1]
	v_pk_fma_f32 v[20:21], v[20:21], s[42:43], v[24:25] op_sel_hi:[1,0,1]
	v_mov_b64_e32 v[24:25], v[194:195]
	v_mov_b64_e32 v[26:27], v[196:197]
	v_mov_b64_e32 v[32:33], v[224:225]
	v_mov_b64_e32 v[34:35], v[226:227]
	s_nop 0
	v_mov_b64_e32 v[2:3], v[232:233]
	v_add_f32_e32 v36, v20, v21
	v_mov_b64_e32 v[6:7], v[238:239]
	v_add_f32_e32 v38, v22, v23
	v_pk_mul_f32 v[34:35], v[34:35], 0.5 op_sel_hi:[1,0]
	v_lshlrev_b32_e32 v4, 16, v2
	v_and_b32_e32 v5, 0xffff0000, v2
	v_lshlrev_b32_e32 v2, 16, v3
	v_and_b32_e32 v3, 0xffff0000, v3
	v_lshlrev_b32_e32 v40, 16, v6
	v_and_b32_e32 v41, 0xffff0000, v6
	v_lshlrev_b32_e32 v6, 16, v7
	v_and_b32_e32 v7, 0xffff0000, v7
	v_pk_mul_f32 v[32:33], v[32:33], 0.5 op_sel_hi:[1,0]
	v_pk_add_f32 v[2:3], v[2:3], v[6:7]
	v_pk_add_f32 v[4:5], v[4:5], v[40:41]
	v_pk_mul_f32 v[2:3], v[34:35], v[2:3]
	v_pk_mul_f32 v[4:5], v[32:33], v[4:5]
	v_pk_fma_f32 v[26:27], v[26:27], s[42:43], v[2:3] op_sel_hi:[1,0,1]
	v_pk_fma_f32 v[24:25], v[24:25], s[42:43], v[4:5] op_sel_hi:[1,0,1]
	v_mov_b32_e32 v37, v26
	v_mov_b32_e32 v29, v24
	v_mov_b32_e32 v31, v25
	v_mov_b32_e32 v39, v27
	v_lshl_add_u64 v[34:35], s[56:57], 0, v[96:97]
	v_pk_add_f32 v[2:3], v[28:29], v[30:31]
	v_pk_add_f32 v[4:5], v[36:37], v[38:39]
	v_lshl_add_u64 v[6:7], v[92:93], 0, s[28:29]
	v_lshl_add_u64 v[46:47], v[34:35], 0, s[8:9]
	v_pk_add_f32 v[2:3], v[2:3], v[4:5]
	v_mad_u64_u32 v[4:5], s[4:5], v6, s7, v[78:79]
	v_lshl_add_u64 v[48:49], v[34:35], 0, v[152:153]
	v_lshl_add_u64 v[36:37], v[46:47], 0, v[152:153]
	v_mad_i32_i24 v5, v7, s7, v5
	global_load_dwordx2 v[228:229], v[48:49], off offset:512
	global_load_dwordx2 v[230:231], v[48:49], off offset:1024
	global_load_dwordx2 v[232:233], v[48:49], off offset:1536
	global_load_dwordx2 v[6:7], v[48:49], off
	v_add_f32_e32 v120, v2, v3
	global_load_dwordx2 v[234:235], v[36:37], off offset:512
	global_load_dwordx2 v[236:237], v[36:37], off offset:1024
	global_load_dwordx2 v[238:239], v[36:37], off offset:1536
	global_load_dwordx2 v[36:37], v[36:37], off
	v_lshlrev_b64 v[2:3], 12, v[0:1]
	global_load_dwordx4 v[186:189], v[4:5], off offset:1024
	global_load_dwordx4 v[190:193], v[4:5], off offset:2048
	global_load_dwordx4 v[194:197], v[4:5], off offset:3072
	global_load_dwordx4 v[28:31], v[4:5], off
	v_lshl_add_u64 v[32:33], v[80:81], 0, v[2:3]
	global_load_dwordx4 v[198:201], v[32:33], off offset:1024
	global_load_dwordx4 v[202:205], v[32:33], off offset:2048
	global_load_dwordx4 v[224:227], v[32:33], off offset:3072
	global_load_dwordx4 v[0:3], v[32:33], off
	v_lshl_add_u64 v[44:45], v[46:47], 0, v[42:43]
	v_lshl_add_u64 v[52:53], v[46:47], 0, v[104:105]
	v_lshl_add_u64 v[46:47], v[46:47], 0, v[106:107]
	s_waitcnt vmcnt(0) lgkmcnt(0)
	v_lshlrev_b32_e32 v34, 16, v6
	v_and_b32_e32 v35, 0xffff0000, v6
	v_lshlrev_b32_e32 v6, 16, v7
	v_and_b32_e32 v7, 0xffff0000, v7
	v_lshlrev_b32_e32 v38, 16, v36
	v_and_b32_e32 v39, 0xffff0000, v36
	v_lshlrev_b32_e32 v36, 16, v37
	v_and_b32_e32 v37, 0xffff0000, v37
	v_pk_mul_f32 v[30:31], v[30:31], 0.5 op_sel_hi:[1,0]
	v_pk_mul_f32 v[28:29], v[28:29], 0.5 op_sel_hi:[1,0]
	v_pk_add_f32 v[34:35], v[34:35], v[38:39]
	v_pk_add_f32 v[6:7], v[6:7], v[36:37]
	v_pk_mul_f32 v[28:29], v[28:29], v[34:35]
	v_pk_mul_f32 v[6:7], v[30:31], v[6:7]
	v_pk_fma_f32 v[34:35], v[0:1], s[42:43], v[28:29] op_sel_hi:[1,0,1]
	v_pk_fma_f32 v[36:37], v[2:3], s[42:43], v[6:7] op_sel_hi:[1,0,1]
	v_mov_b32_e32 v2, v34
	v_pk_mov_b32 v[0:1], v[34:35], v[36:37] op_sel:[1,0]
	v_mov_b32_e32 v3, v37
	v_pk_add_f32 v[0:1], v[0:1], v[2:3]
	s_nop 0
	v_add_f32_e32 v0, v0, v1
	v_add_f32_e32 v40, 0, v0
	v_mov_b64_e32 v[0:1], v[198:199]
	v_mov_b64_e32 v[2:3], v[200:201]
	v_mov_b64_e32 v[28:29], v[186:187]
	v_mov_b64_e32 v[30:31], v[188:189]
	v_mov_b64_e32 v[6:7], v[228:229]
	v_pk_mul_f32 v[30:31], v[30:31], 0.5 op_sel_hi:[1,0]
	v_mov_b64_e32 v[44:45], v[234:235]
	v_lshlrev_b32_e32 v38, 16, v6
	v_and_b32_e32 v39, 0xffff0000, v6
	v_lshlrev_b32_e32 v6, 16, v7
	v_and_b32_e32 v7, 0xffff0000, v7
	v_pk_mul_f32 v[28:29], v[28:29], 0.5 op_sel_hi:[1,0]
	v_lshlrev_b32_e32 v50, 16, v44
	v_and_b32_e32 v51, 0xffff0000, v44
	v_lshlrev_b32_e32 v44, 16, v45
	v_and_b32_e32 v45, 0xffff0000, v45
	v_pk_add_f32 v[38:39], v[38:39], v[50:51]
	v_pk_add_f32 v[6:7], v[6:7], v[44:45]
	v_pk_mul_f32 v[28:29], v[28:29], v[38:39]
	v_pk_mul_f32 v[6:7], v[30:31], v[6:7]
	v_pk_fma_f32 v[38:39], v[0:1], s[42:43], v[28:29] op_sel_hi:[1,0,1]
	v_pk_fma_f32 v[60:61], v[2:3], s[42:43], v[6:7] op_sel_hi:[1,0,1]
	v_mov_b32_e32 v2, v38
	v_pk_mov_b32 v[0:1], v[38:39], v[60:61] op_sel:[1,0]
	v_mov_b32_e32 v3, v61
	v_pk_add_f32 v[0:1], v[0:1], v[2:3]
	s_nop 0
	v_pk_add_f32 v[44:45], v[0:1], v[0:1] op_sel:[0,1] op_sel_hi:[1,0]
	v_mov_b64_e32 v[0:1], v[202:203]
	v_mov_b64_e32 v[2:3], v[204:205]
	v_mov_b64_e32 v[28:29], v[190:191]
	v_mov_b64_e32 v[30:31], v[192:193]
	v_mov_b64_e32 v[6:7], v[230:231]
	v_pk_mul_f32 v[30:31], v[30:31], 0.5 op_sel_hi:[1,0]
	v_mov_b64_e32 v[52:53], v[236:237]
	v_lshlrev_b32_e32 v50, 16, v6
	v_and_b32_e32 v51, 0xffff0000, v6
	v_lshlrev_b32_e32 v6, 16, v7
	v_and_b32_e32 v7, 0xffff0000, v7
	v_pk_mul_f32 v[28:29], v[28:29], 0.5 op_sel_hi:[1,0]
	v_lshlrev_b32_e32 v54, 16, v52
	v_and_b32_e32 v55, 0xffff0000, v52
	v_lshlrev_b32_e32 v52, 16, v53
	v_and_b32_e32 v53, 0xffff0000, v53
	v_pk_add_f32 v[6:7], v[6:7], v[52:53]
	v_pk_add_f32 v[50:51], v[50:51], v[54:55]
	v_pk_mul_f32 v[6:7], v[30:31], v[6:7]
	v_pk_mul_f32 v[28:29], v[28:29], v[50:51]
	v_pk_fma_f32 v[30:31], v[2:3], s[42:43], v[6:7] op_sel_hi:[1,0,1]
	v_pk_fma_f32 v[28:29], v[0:1], s[42:43], v[28:29] op_sel_hi:[1,0,1]
	v_mov_b64_e32 v[0:1], v[224:225]
	v_mov_b64_e32 v[2:3], v[226:227]
	s_nop 0
	v_mov_b64_e32 v[4:5], v[194:195]
	v_mov_b64_e32 v[6:7], v[196:197]
	s_nop 0
	v_mov_b64_e32 v[54:55], v[232:233]
	v_add_f32_e32 v50, v28, v29
	v_mov_b64_e32 v[46:47], v[238:239]
	v_add_f32_e32 v52, v30, v31
	v_pk_mul_f32 v[6:7], v[6:7], 0.5 op_sel_hi:[1,0]
	v_lshlrev_b32_e32 v48, 16, v54
	v_and_b32_e32 v49, 0xffff0000, v54
	v_lshlrev_b32_e32 v54, 16, v55
	v_and_b32_e32 v55, 0xffff0000, v55
	v_lshlrev_b32_e32 v56, 16, v46
	v_and_b32_e32 v57, 0xffff0000, v46
	v_lshlrev_b32_e32 v46, 16, v47
	v_and_b32_e32 v47, 0xffff0000, v47
	v_pk_mul_f32 v[4:5], v[4:5], 0.5 op_sel_hi:[1,0]
	v_pk_add_f32 v[46:47], v[54:55], v[46:47]
	v_pk_add_f32 v[48:49], v[48:49], v[56:57]
	v_pk_mul_f32 v[6:7], v[6:7], v[46:47]
	v_pk_mul_f32 v[4:5], v[4:5], v[48:49]
	v_pk_fma_f32 v[118:119], v[2:3], s[42:43], v[6:7] op_sel_hi:[1,0,1]
	v_pk_fma_f32 v[62:63], v[0:1], s[42:43], v[4:5] op_sel_hi:[1,0,1]
	v_mov_b32_e32 v51, v118
	v_mov_b32_e32 v41, v62
	v_mov_b32_e32 v45, v63
	v_mov_b32_e32 v53, v119
	v_pk_add_f32 v[0:1], v[40:41], v[44:45]
	v_pk_add_f32 v[2:3], v[50:51], v[52:53]
	v_lshl_add_u64 v[4:5], v[90:91], 0, s[28:29]
	v_pk_add_f32 v[0:1], v[0:1], v[2:3]
	v_mad_u64_u32 v[48:49], s[4:5], v4, s7, v[78:79]
	v_add_f32_e32 v121, v0, v1
	v_lshlrev_b64 v[0:1], 12, v[18:19]
	v_lshl_add_u64 v[18:19], s[56:57], 0, v[100:101]
	v_lshl_add_u64 v[46:47], v[18:19], 0, s[8:9]
	v_mad_i32_i24 v49, v5, s7, v49
	v_lshl_add_u64 v[18:19], v[18:19], 0, v[152:153]
	v_lshl_add_u64 v[52:53], v[46:47], 0, v[152:153]
	global_load_dwordx4 v[186:189], v[48:49], off offset:1024
	global_load_dwordx4 v[190:193], v[48:49], off offset:2048
	global_load_dwordx4 v[194:197], v[48:49], off offset:3072
	global_load_dwordx4 v[4:7], v[48:49], off
	global_load_dwordx2 v[228:229], v[18:19], off offset:512
	global_load_dwordx2 v[230:231], v[18:19], off offset:1024
	global_load_dwordx2 v[232:233], v[18:19], off offset:1536
	global_load_dwordx2 v[44:45], v[18:19], off
	v_lshl_add_u64 v[40:41], v[80:81], 0, v[0:1]
	global_load_dwordx2 v[234:235], v[52:53], off offset:512
	global_load_dwordx2 v[236:237], v[52:53], off offset:1024
	global_load_dwordx2 v[238:239], v[52:53], off offset:1536
	global_load_dwordx2 v[52:53], v[52:53], off
	v_lshl_add_u64 v[56:57], v[46:47], 0, v[42:43]
	global_load_dwordx4 v[198:201], v[40:41], off offset:1024
	global_load_dwordx4 v[202:205], v[40:41], off offset:2048
	global_load_dwordx4 v[224:227], v[40:41], off offset:3072
	global_load_dwordx4 v[0:3], v[40:41], off
	v_lshl_add_u64 v[108:109], v[46:47], 0, v[104:105]
	v_lshl_add_u64 v[46:47], v[46:47], 0, v[106:107]
	s_waitcnt vmcnt(0) lgkmcnt(0)
	v_pk_mul_f32 v[6:7], v[6:7], 0.5 op_sel_hi:[1,0]
	v_lshlrev_b32_e32 v50, 16, v44
	v_and_b32_e32 v51, 0xffff0000, v44
	v_lshlrev_b32_e32 v44, 16, v45
	v_and_b32_e32 v45, 0xffff0000, v45
	v_lshlrev_b32_e32 v54, 16, v52
	v_and_b32_e32 v55, 0xffff0000, v52
	v_lshlrev_b32_e32 v52, 16, v53
	v_and_b32_e32 v53, 0xffff0000, v53
	v_pk_mul_f32 v[4:5], v[4:5], 0.5 op_sel_hi:[1,0]
	v_pk_add_f32 v[50:51], v[50:51], v[54:55]
	v_pk_add_f32 v[44:45], v[44:45], v[52:53]
	v_pk_mul_f32 v[4:5], v[4:5], v[50:51]
	v_pk_mul_f32 v[6:7], v[6:7], v[44:45]
	v_pk_fma_f32 v[44:45], v[0:1], s[42:43], v[4:5] op_sel_hi:[1,0,1]
	v_pk_fma_f32 v[50:51], v[2:3], s[42:43], v[6:7] op_sel_hi:[1,0,1]
	v_mov_b32_e32 v2, v44
	v_pk_mov_b32 v[0:1], v[44:45], v[50:51] op_sel:[1,0]
	v_mov_b32_e32 v3, v51
	v_pk_add_f32 v[0:1], v[0:1], v[2:3]
	s_nop 0
	v_add_f32_e32 v0, v0, v1
	v_add_f32_e32 v98, 0, v0
	v_mov_b64_e32 v[0:1], v[198:199]
	v_mov_b64_e32 v[2:3], v[200:201]
	v_mov_b64_e32 v[4:5], v[186:187]
	v_mov_b64_e32 v[6:7], v[188:189]
	v_mov_b64_e32 v[52:53], v[228:229]
	v_pk_mul_f32 v[6:7], v[6:7], 0.5 op_sel_hi:[1,0]
	v_mov_b64_e32 v[56:57], v[234:235]
	v_lshlrev_b32_e32 v54, 16, v52
	v_and_b32_e32 v55, 0xffff0000, v52
	v_lshlrev_b32_e32 v52, 16, v53
	v_and_b32_e32 v53, 0xffff0000, v53
	v_pk_mul_f32 v[4:5], v[4:5], 0.5 op_sel_hi:[1,0]
	v_lshlrev_b32_e32 v58, 16, v56
	v_and_b32_e32 v59, 0xffff0000, v56
	v_lshlrev_b32_e32 v56, 16, v57
	v_and_b32_e32 v57, 0xffff0000, v57
	v_pk_add_f32 v[54:55], v[54:55], v[58:59]
	v_pk_add_f32 v[52:53], v[52:53], v[56:57]
	v_pk_mul_f32 v[4:5], v[4:5], v[54:55]
	v_pk_mul_f32 v[6:7], v[6:7], v[52:53]
	v_pk_fma_f32 v[56:57], v[0:1], s[42:43], v[4:5] op_sel_hi:[1,0,1]
	v_pk_fma_f32 v[58:59], v[2:3], s[42:43], v[6:7] op_sel_hi:[1,0,1]
	v_mov_b32_e32 v2, v56
	v_pk_mov_b32 v[0:1], v[56:57], v[58:59] op_sel:[1,0]
	v_mov_b32_e32 v3, v59
	v_pk_add_f32 v[0:1], v[0:1], v[2:3]
	s_nop 0
	v_pk_add_f32 v[102:103], v[0:1], v[0:1] op_sel:[0,1] op_sel_hi:[1,0]
	v_mov_b64_e32 v[0:1], v[202:203]
	v_mov_b64_e32 v[2:3], v[204:205]
	v_mov_b64_e32 v[4:5], v[190:191]
	v_mov_b64_e32 v[6:7], v[192:193]
	v_mov_b64_e32 v[52:53], v[230:231]
	v_pk_mul_f32 v[6:7], v[6:7], 0.5 op_sel_hi:[1,0]
	v_mov_b64_e32 v[108:109], v[236:237]
	v_lshlrev_b32_e32 v54, 16, v52
	v_and_b32_e32 v55, 0xffff0000, v52
	v_lshlrev_b32_e32 v52, 16, v53
	v_and_b32_e32 v53, 0xffff0000, v53
	v_pk_mul_f32 v[4:5], v[4:5], 0.5 op_sel_hi:[1,0]
	v_lshlrev_b32_e32 v110, 16, v108
	v_and_b32_e32 v111, 0xffff0000, v108
	v_lshlrev_b32_e32 v108, 16, v109
	v_and_b32_e32 v109, 0xffff0000, v109
	v_pk_add_f32 v[52:53], v[52:53], v[108:109]
	v_pk_add_f32 v[54:55], v[54:55], v[110:111]
	v_pk_mul_f32 v[6:7], v[6:7], v[52:53]
	v_pk_mul_f32 v[4:5], v[4:5], v[54:55]
	v_pk_fma_f32 v[54:55], v[2:3], s[42:43], v[6:7] op_sel_hi:[1,0,1]
	v_pk_fma_f32 v[52:53], v[0:1], s[42:43], v[4:5] op_sel_hi:[1,0,1]
	v_mov_b64_e32 v[0:1], v[224:225]
	v_mov_b64_e32 v[2:3], v[226:227]
	v_mov_b64_e32 v[4:5], v[194:195]
	v_mov_b64_e32 v[6:7], v[196:197]
	s_nop 0
	v_mov_b64_e32 v[18:19], v[232:233]
	v_add_f32_e32 v108, v52, v53
	v_mov_b64_e32 v[46:47], v[238:239]
	v_add_f32_e32 v110, v54, v55
	v_pk_mul_f32 v[6:7], v[6:7], 0.5 op_sel_hi:[1,0]
	v_lshlrev_b32_e32 v48, 16, v18
	v_and_b32_e32 v49, 0xffff0000, v18
	v_lshlrev_b32_e32 v18, 16, v19
	v_and_b32_e32 v19, 0xffff0000, v19
	v_lshlrev_b32_e32 v112, 16, v46
	v_and_b32_e32 v113, 0xffff0000, v46
	v_lshlrev_b32_e32 v46, 16, v47
	v_and_b32_e32 v47, 0xffff0000, v47
	v_pk_mul_f32 v[4:5], v[4:5], 0.5 op_sel_hi:[1,0]
	v_pk_add_f32 v[18:19], v[18:19], v[46:47]
	v_pk_add_f32 v[46:47], v[48:49], v[112:113]
	v_pk_mul_f32 v[6:7], v[6:7], v[18:19]
	v_pk_mul_f32 v[4:5], v[4:5], v[46:47]
	v_pk_fma_f32 v[48:49], v[2:3], s[42:43], v[6:7] op_sel_hi:[1,0,1]
	v_pk_fma_f32 v[46:47], v[0:1], s[42:43], v[4:5] op_sel_hi:[1,0,1]
	v_mov_b32_e32 v109, v48
	v_mov_b32_e32 v99, v46
	v_mov_b32_e32 v103, v47
	v_mov_b32_e32 v111, v49
	v_pk_add_f32 v[0:1], v[98:99], v[102:103]
	v_pk_add_f32 v[2:3], v[108:109], v[110:111]
	v_lshlrev_b64 v[98:99], 11, v[16:17]
	v_pk_add_f32 v[0:1], v[0:1], v[2:3]
	v_lshl_add_u64 v[4:5], v[88:89], 0, s[28:29]
	v_add_f32_e32 v125, v0, v1
	v_lshlrev_b64 v[0:1], 12, v[16:17]
	v_lshl_add_u64 v[16:17], s[56:57], 0, v[98:99]
	v_lshl_add_u64 v[18:19], v[16:17], 0, s[8:9]
	v_mad_u64_u32 v[126:127], s[4:5], v4, s7, v[78:79]
	v_mad_i32_i24 v127, v5, s7, v127
	v_lshl_add_u64 v[16:17], v[16:17], 0, v[152:153]
	v_lshl_add_u64 v[112:113], v[18:19], 0, v[152:153]
	global_load_dwordx4 v[186:189], v[126:127], off offset:1024
	global_load_dwordx4 v[190:193], v[126:127], off offset:2048
	global_load_dwordx4 v[194:197], v[126:127], off offset:3072
	global_load_dwordx4 v[4:7], v[126:127], off
	global_load_dwordx2 v[228:229], v[16:17], off offset:512
	global_load_dwordx2 v[230:231], v[16:17], off offset:1024
	global_load_dwordx2 v[232:233], v[16:17], off offset:1536
	global_load_dwordx2 v[108:109], v[16:17], off
	v_lshl_add_u64 v[102:103], v[80:81], 0, v[0:1]
	global_load_dwordx2 v[234:235], v[112:113], off offset:512
	global_load_dwordx2 v[236:237], v[112:113], off offset:1024
	global_load_dwordx2 v[238:239], v[112:113], off offset:1536
	global_load_dwordx2 v[112:113], v[112:113], off
	v_lshl_add_u64 v[42:43], v[18:19], 0, v[42:43]
	global_load_dwordx4 v[198:201], v[102:103], off offset:1024
	global_load_dwordx4 v[202:205], v[102:103], off offset:2048
	global_load_dwordx4 v[224:227], v[102:103], off offset:3072
	global_load_dwordx4 v[0:3], v[102:103], off
	v_lshl_add_u64 v[104:105], v[18:19], 0, v[104:105]
	v_lshl_add_u64 v[18:19], v[18:19], 0, v[106:107]
	s_mov_b32 s4, 0x3727c5ac
	s_waitcnt vmcnt(0) lgkmcnt(0)
	v_pk_mul_f32 v[6:7], v[6:7], 0.5 op_sel_hi:[1,0]
	v_lshlrev_b32_e32 v110, 16, v108
	v_and_b32_e32 v111, 0xffff0000, v108
	v_lshlrev_b32_e32 v108, 16, v109
	v_and_b32_e32 v109, 0xffff0000, v109
	v_lshlrev_b32_e32 v114, 16, v112
	v_and_b32_e32 v115, 0xffff0000, v112
	v_lshlrev_b32_e32 v112, 16, v113
	v_and_b32_e32 v113, 0xffff0000, v113
	v_pk_mul_f32 v[4:5], v[4:5], 0.5 op_sel_hi:[1,0]
	v_pk_add_f32 v[110:111], v[110:111], v[114:115]
	v_pk_add_f32 v[108:109], v[108:109], v[112:113]
	v_pk_mul_f32 v[4:5], v[4:5], v[110:111]
	v_pk_mul_f32 v[6:7], v[6:7], v[108:109]
	v_pk_fma_f32 v[114:115], v[0:1], s[42:43], v[4:5] op_sel_hi:[1,0,1]
	v_pk_fma_f32 v[116:117], v[2:3], s[42:43], v[6:7] op_sel_hi:[1,0,1]
	v_mov_b32_e32 v2, v114
	v_pk_mov_b32 v[0:1], v[114:115], v[116:117] op_sel:[1,0]
	v_mov_b32_e32 v3, v117
	v_pk_add_f32 v[0:1], v[0:1], v[2:3]
	s_nop 0
	v_add_f32_e32 v0, v0, v1
	v_add_f32_e32 v128, 0, v0
	v_mov_b64_e32 v[0:1], v[198:199]
	v_mov_b64_e32 v[2:3], v[200:201]
	v_mov_b64_e32 v[4:5], v[186:187]
	v_mov_b64_e32 v[6:7], v[188:189]
	v_mov_b64_e32 v[108:109], v[228:229]
	v_pk_mul_f32 v[6:7], v[6:7], 0.5 op_sel_hi:[1,0]
	v_mov_b64_e32 v[42:43], v[234:235]
	v_lshlrev_b32_e32 v110, 16, v108
	v_and_b32_e32 v111, 0xffff0000, v108
	v_lshlrev_b32_e32 v108, 16, v109
	v_and_b32_e32 v109, 0xffff0000, v109
	v_pk_mul_f32 v[4:5], v[4:5], 0.5 op_sel_hi:[1,0]
	v_lshlrev_b32_e32 v112, 16, v42
	v_and_b32_e32 v113, 0xffff0000, v42
	v_lshlrev_b32_e32 v42, 16, v43
	v_and_b32_e32 v43, 0xffff0000, v43
	v_pk_add_f32 v[110:111], v[110:111], v[112:113]
	v_pk_add_f32 v[42:43], v[108:109], v[42:43]
	v_pk_mul_f32 v[4:5], v[4:5], v[110:111]
	v_pk_mul_f32 v[6:7], v[6:7], v[42:43]
	v_pk_fma_f32 v[42:43], v[0:1], s[42:43], v[4:5] op_sel_hi:[1,0,1]
	v_pk_fma_f32 v[112:113], v[2:3], s[42:43], v[6:7] op_sel_hi:[1,0,1]
	v_mov_b32_e32 v2, v42
	v_pk_mov_b32 v[0:1], v[42:43], v[112:113] op_sel:[1,0]
	v_mov_b32_e32 v3, v113
	v_pk_add_f32 v[0:1], v[0:1], v[2:3]
	s_nop 0
	v_pk_add_f32 v[130:131], v[0:1], v[0:1] op_sel:[0,1] op_sel_hi:[1,0]
	v_mov_b64_e32 v[0:1], v[202:203]
	v_mov_b64_e32 v[2:3], v[204:205]
	v_mov_b64_e32 v[4:5], v[190:191]
	v_mov_b64_e32 v[6:7], v[192:193]
	v_mov_b64_e32 v[108:109], v[230:231]
	v_pk_mul_f32 v[6:7], v[6:7], 0.5 op_sel_hi:[1,0]
	v_mov_b64_e32 v[104:105], v[236:237]
	v_lshlrev_b32_e32 v110, 16, v108
	v_and_b32_e32 v111, 0xffff0000, v108
	v_lshlrev_b32_e32 v108, 16, v109
	v_and_b32_e32 v109, 0xffff0000, v109
	v_pk_mul_f32 v[4:5], v[4:5], 0.5 op_sel_hi:[1,0]
	v_lshlrev_b32_e32 v132, 16, v104
	v_and_b32_e32 v133, 0xffff0000, v104
	v_lshlrev_b32_e32 v104, 16, v105
	v_and_b32_e32 v105, 0xffff0000, v105
	v_pk_add_f32 v[104:105], v[108:109], v[104:105]
	v_pk_add_f32 v[108:109], v[110:111], v[132:133]
	v_pk_mul_f32 v[6:7], v[6:7], v[104:105]
	v_pk_mul_f32 v[4:5], v[4:5], v[108:109]
	v_pk_fma_f32 v[110:111], v[2:3], s[42:43], v[6:7] op_sel_hi:[1,0,1]
	v_pk_fma_f32 v[108:109], v[0:1], s[42:43], v[4:5] op_sel_hi:[1,0,1]
	v_mov_b64_e32 v[0:1], v[224:225]
	v_mov_b64_e32 v[2:3], v[226:227]
	v_mov_b64_e32 v[4:5], v[194:195]
	v_mov_b64_e32 v[6:7], v[196:197]
	s_nop 0
	v_mov_b64_e32 v[16:17], v[232:233]
	v_add_f32_e32 v132, v108, v109
	v_mov_b64_e32 v[18:19], v[238:239]
	v_add_f32_e32 v134, v110, v111
	v_pk_mul_f32 v[6:7], v[6:7], 0.5 op_sel_hi:[1,0]
	v_lshlrev_b32_e32 v104, 16, v16
	v_and_b32_e32 v105, 0xffff0000, v16
	v_lshlrev_b32_e32 v16, 16, v17
	v_and_b32_e32 v17, 0xffff0000, v17
	v_lshlrev_b32_e32 v106, 16, v18
	v_and_b32_e32 v107, 0xffff0000, v18
	v_lshlrev_b32_e32 v18, 16, v19
	v_and_b32_e32 v19, 0xffff0000, v19
	v_pk_mul_f32 v[4:5], v[4:5], 0.5 op_sel_hi:[1,0]
	v_pk_add_f32 v[16:17], v[16:17], v[18:19]
	v_pk_add_f32 v[18:19], v[104:105], v[106:107]
	v_pk_mul_f32 v[6:7], v[6:7], v[16:17]
	v_pk_mul_f32 v[4:5], v[4:5], v[18:19]
	v_pk_fma_f32 v[106:107], v[2:3], s[42:43], v[6:7] op_sel_hi:[1,0,1]
	v_pk_fma_f32 v[104:105], v[0:1], s[42:43], v[4:5] op_sel_hi:[1,0,1]
	v_mov_b32_e32 v133, v106
	v_mov_b32_e32 v129, v104
	v_mov_b32_e32 v131, v105
	v_mov_b32_e32 v135, v107
	v_pk_add_f32 v[0:1], v[128:129], v[130:131]
	v_pk_add_f32 v[2:3], v[132:133], v[134:135]
	ds_bpermute_b32 v18, v67, v121
	v_pk_add_f32 v[0:1], v[0:1], v[2:3]
	s_waitcnt lgkmcnt(0)
	v_add_f32_e32 v18, v121, v18
	v_add_f32_e32 v65, v0, v1
	ds_bpermute_b32 v0, v67, v120
	ds_bpermute_b32 v19, v69, v18
	s_waitcnt lgkmcnt(1)
	v_add_f32_e32 v0, v120, v0
	ds_bpermute_b32 v1, v69, v0
	s_waitcnt lgkmcnt(1)
	v_add_f32_e32 v18, v18, v19
	ds_bpermute_b32 v19, v71, v18
	s_waitcnt lgkmcnt(1)
	v_add_f32_e32 v0, v0, v1
	ds_bpermute_b32 v1, v71, v0
	s_waitcnt lgkmcnt(1)
	v_add_f32_e32 v18, v18, v19
	ds_bpermute_b32 v19, v73, v18
	s_waitcnt lgkmcnt(1)
	v_add_f32_e32 v0, v0, v1
	ds_bpermute_b32 v1, v73, v0
	s_waitcnt lgkmcnt(1)
	v_add_f32_e32 v18, v18, v19
	ds_bpermute_b32 v19, v123, v18
	s_waitcnt lgkmcnt(1)
	v_add_f32_e32 v0, v0, v1
	ds_bpermute_b32 v1, v123, v0
	s_waitcnt lgkmcnt(1)
	v_add_f32_e32 v18, v18, v19
	ds_bpermute_b32 v19, v124, v18
	s_waitcnt lgkmcnt(1)
	v_add_f32_e32 v0, v0, v1
	ds_bpermute_b32 v1, v124, v0
	s_waitcnt lgkmcnt(1)
	v_add_f32_e32 v122, v18, v19
	v_fmamk_f32 v35, v122, 0xba800000, v35
	v_fmac_f32_e32 v34, 0xba800000, v122
	v_fmamk_f32 v37, v122, 0xba800000, v37
	s_waitcnt lgkmcnt(0)
	v_add_f32_e32 v16, v0, v1
	v_fmamk_f32 v9, v16, 0xba800000, v9
	v_fmac_f32_e32 v8, 0xba800000, v16
	v_fmamk_f32 v11, v16, 0xba800000, v11
	v_fmac_f32_e32 v10, 0xba800000, v16
	v_pk_mul_f32 v[0:1], v[10:11], v[10:11]
	v_pk_mul_f32 v[2:3], v[8:9], v[8:9]
	v_fmamk_f32 v13, v16, 0xba800000, v13
	v_pk_mov_b32 v[4:5], v[2:3], v[0:1] op_sel:[1,0]
	v_mov_b32_e32 v3, v1
	v_pk_add_f32 v[0:1], v[4:5], v[2:3]
	v_fmac_f32_e32 v12, 0xba800000, v16
	v_fmamk_f32 v15, v16, 0xba800000, v15
	v_fmac_f32_e32 v14, 0xba800000, v16
	v_pk_add_f32 v[0:1], v[0:1], v[0:1] op_sel_hi:[0,1]
	v_pk_mul_f32 v[2:3], v[14:15], v[14:15]
	v_pk_mul_f32 v[4:5], v[12:13], v[12:13]
	v_fmac_f32_e32 v20, 0xba800000, v16
	v_pk_mov_b32 v[6:7], v[4:5], v[2:3] op_sel:[1,0]
	v_mov_b32_e32 v5, v3
	v_fmamk_f32 v21, v16, 0xba800000, v21
	v_fmac_f32_e32 v22, 0xba800000, v16
	v_mul_f32_e32 v0, v20, v20
	v_pk_add_f32 v[2:3], v[6:7], v[4:5]
	v_fmamk_f32 v23, v16, 0xba800000, v23
	v_pk_fma_f32 v[4:5], v[20:21], v[20:21], v[0:1] op_sel_hi:[1,1,0]
	v_mul_f32_e32 v0, v22, v22
	v_pk_add_f32 v[2:3], v[2:3], v[2:3] op_sel_hi:[0,1]
	v_pk_fma_f32 v[6:7], v[22:23], v[22:23], v[0:1] op_sel_hi:[1,1,0]
	v_fmamk_f32 v27, v16, 0xba800000, v27
	v_fmac_f32_e32 v26, 0xba800000, v16
	v_fmamk_f32 v25, v16, 0xba800000, v25
	v_fmac_f32_e32 v24, 0xba800000, v16
	v_mul_f32_e32 v4, v24, v24
	v_mul_f32_e32 v6, v25, v25
	v_mul_f32_e32 v0, v26, v26
	v_mul_f32_e32 v2, v27, v27
	v_pk_add_f32 v[4:5], v[4:5], v[6:7]
	v_pk_add_f32 v[0:1], v[0:1], v[2:3]
	v_fmac_f32_e32 v36, 0xba800000, v122
	v_pk_add_f32 v[16:17], v[4:5], v[0:1]
	v_mov_b64_e32 v[0:1], v[154:155]
	v_mov_b64_e32 v[2:3], v[156:157]
	v_mov_b64_e32 v[4:5], v[158:159]
	v_mov_b64_e32 v[6:7], v[160:161]
	v_pk_mul_f32 v[18:19], v[36:37], v[36:37]
	v_pk_mul_f32 v[120:121], v[34:35], v[34:35]
	v_fmamk_f32 v39, v122, 0xba800000, v39
	v_pk_mov_b32 v[126:127], v[120:121], v[18:19] op_sel:[1,0]
	v_mov_b32_e32 v121, v19
	v_pk_add_f32 v[18:19], v[126:127], v[120:121]
	v_fmac_f32_e32 v38, 0xba800000, v122
	v_fmamk_f32 v61, v122, 0xba800000, v61
	v_fmac_f32_e32 v60, 0xba800000, v122
	v_pk_add_f32 v[18:19], v[18:19], v[18:19] op_sel_hi:[0,1]
	v_pk_mul_f32 v[120:121], v[60:61], v[60:61]
	v_pk_mul_f32 v[126:127], v[38:39], v[38:39]
	v_fmac_f32_e32 v28, 0xba800000, v122
	v_pk_mov_b32 v[128:129], v[126:127], v[120:121] op_sel:[1,0]
	v_mov_b32_e32 v127, v121
	v_fmamk_f32 v29, v122, 0xba800000, v29
	v_fmac_f32_e32 v30, 0xba800000, v122
	v_mul_f32_e32 v18, v28, v28
	v_pk_add_f32 v[120:121], v[128:129], v[126:127]
	v_fmamk_f32 v31, v122, 0xba800000, v31
	v_pk_fma_f32 v[126:127], v[28:29], v[28:29], v[18:19] op_sel_hi:[1,1,0]
	v_mul_f32_e32 v18, v30, v30
	v_pk_add_f32 v[120:121], v[120:121], v[120:121] op_sel_hi:[0,1]
	v_pk_fma_f32 v[128:129], v[30:31], v[30:31], v[18:19] op_sel_hi:[1,1,0]
	v_fmamk_f32 v119, v122, 0xba800000, v119
	v_fmac_f32_e32 v118, 0xba800000, v122
	v_fmamk_f32 v63, v122, 0xba800000, v63
	v_fmac_f32_e32 v62, 0xba800000, v122
	v_mul_f32_e32 v126, v62, v62
	v_mul_f32_e32 v128, v63, v63
	v_mul_f32_e32 v18, v118, v118
	v_mul_f32_e32 v120, v119, v119
	v_pk_add_f32 v[126:127], v[126:127], v[128:129]
	v_pk_add_f32 v[18:19], v[18:19], v[120:121]
	v_mov_b32_e32 v121, v16
	v_pk_add_f32 v[18:19], v[126:127], v[18:19]
	s_nop 0
	v_mov_b32_e32 v120, v18
	v_mov_b32_e32 v16, v19
	v_pk_add_f32 v[16:17], v[120:121], v[16:17]
	ds_bpermute_b32 v19, v67, v17
	ds_bpermute_b32 v18, v67, v16
	v_mov_b64_e32 v[120:121], s[4:5]
	s_mov_b32 s4, 0x3a800000
	s_waitcnt lgkmcnt(0)
	v_pk_add_f32 v[16:17], v[16:17], v[18:19]
	ds_bpermute_b32 v19, v69, v17
	ds_bpermute_b32 v18, v69, v16
	s_waitcnt lgkmcnt(0)
	v_pk_add_f32 v[16:17], v[16:17], v[18:19]
	ds_bpermute_b32 v19, v71, v17
	ds_bpermute_b32 v18, v71, v16
	s_waitcnt lgkmcnt(0)
	v_pk_add_f32 v[16:17], v[16:17], v[18:19]
	ds_bpermute_b32 v19, v73, v17
	ds_bpermute_b32 v18, v73, v16
	s_waitcnt lgkmcnt(0)
	v_pk_add_f32 v[16:17], v[16:17], v[18:19]
	ds_bpermute_b32 v19, v123, v17
	ds_bpermute_b32 v18, v123, v16
	s_waitcnt lgkmcnt(0)
	v_pk_add_f32 v[16:17], v[16:17], v[18:19]
	ds_bpermute_b32 v19, v124, v17
	ds_bpermute_b32 v18, v124, v16
	s_waitcnt lgkmcnt(0)
	v_pk_add_f32 v[16:17], v[16:17], v[18:19]
	s_nop 0
	v_pk_fma_f32 v[126:127], v[16:17], s[4:5], v[120:121] op_sel_hi:[1,0,0]
	s_nop 0
	v_mul_f32_e32 v16, 0x4b800000, v127
	v_cmp_gt_f32_e64 s[8:9], s68, v127
	v_cmp_gt_f32_e32 vcc, s68, v126
	s_nop 0
	v_cndmask_b32_e64 v16, v127, v16, s[8:9]
	v_rsq_f32_e32 v16, v16
	s_nop 0
	v_mul_f32_e32 v17, 0x45800000, v16
	v_cndmask_b32_e64 v122, v16, v17, s[8:9]
	v_pk_mul_f32 v[8:9], v[8:9], v[122:123] op_sel_hi:[1,0]
	v_pk_mul_f32 v[10:11], v[10:11], v[122:123] op_sel_hi:[1,0]
	v_pk_fma_f32 v[16:17], v[0:1], v[8:9], v[4:5]
	v_pk_fma_f32 v[18:19], v[2:3], v[10:11], v[6:7]
	global_store_dwordx4 v[86:87], v[16:19], off
	v_mov_b64_e32 v[0:1], v[162:163]
	v_mov_b64_e32 v[2:3], v[164:165]
	v_mov_b64_e32 v[4:5], v[166:167]
	v_mov_b64_e32 v[6:7], v[168:169]
	v_pk_mul_f32 v[8:9], v[14:15], v[122:123] op_sel_hi:[1,0]
	v_pk_mul_f32 v[10:11], v[12:13], v[122:123] op_sel_hi:[1,0]
	v_pk_fma_f32 v[14:15], v[2:3], v[8:9], v[6:7]
	v_pk_fma_f32 v[12:13], v[0:1], v[10:11], v[4:5]
	global_store_dwordx4 v[86:87], v[12:15], off offset:1024
	v_mov_b64_e32 v[0:1], v[170:171]
	v_mov_b64_e32 v[2:3], v[172:173]
	v_mov_b64_e32 v[4:5], v[174:175]
	v_mov_b64_e32 v[6:7], v[176:177]
	v_pk_mul_f32 v[8:9], v[22:23], v[122:123] op_sel_hi:[1,0]
	v_pk_mul_f32 v[10:11], v[20:21], v[122:123] op_sel_hi:[1,0]
	v_pk_mul_f32 v[22:23], v[24:25], v[122:123] op_sel_hi:[1,0]
	v_pk_mul_f32 v[20:21], v[26:27], v[122:123] op_sel_hi:[1,0]
	v_pk_fma_f32 v[4:5], v[0:1], v[10:11], v[4:5]
	v_pk_fma_f32 v[6:7], v[2:3], v[8:9], v[6:7]
	global_store_dwordx4 v[86:87], v[4:7], off offset:2048
	v_mov_b64_e32 v[0:1], v[178:179]
	v_mov_b64_e32 v[2:3], v[180:181]
	v_mov_b64_e32 v[8:9], v[182:183]
	v_mov_b64_e32 v[10:11], v[184:185]
	v_pk_fma_f32 v[0:1], v[0:1], v[22:23], v[8:9]
	v_mul_f32_e32 v8, 0x4b800000, v126
	v_cndmask_b32_e32 v8, v126, v8, vcc
	v_rsq_f32_e32 v8, v8
	v_pk_fma_f32 v[2:3], v[2:3], v[20:21], v[10:11]
	global_store_dwordx4 v[86:87], v[0:3], off offset:3072
	v_mul_f32_e32 v9, 0x45800000, v8
	v_cndmask_b32_e32 v122, v8, v9, vcc
	v_mov_b64_e32 v[8:9], v[154:155]
	v_mov_b64_e32 v[10:11], v[156:157]
	v_mov_b64_e32 v[20:21], v[158:159]
	v_mov_b64_e32 v[22:23], v[160:161]
	v_pk_mul_f32 v[24:25], v[36:37], v[122:123] op_sel_hi:[1,0]
	v_pk_mul_f32 v[26:27], v[34:35], v[122:123] op_sel_hi:[1,0]
	v_pk_mul_f32 v[34:35], v[60:61], v[122:123] op_sel_hi:[1,0]
	v_pk_mul_f32 v[36:37], v[38:39], v[122:123] op_sel_hi:[1,0]
	v_pk_mul_f32 v[38:39], v[118:119], v[122:123] op_sel_hi:[1,0]
	v_pk_mul_f32 v[60:61], v[62:63], v[122:123] op_sel_hi:[1,0]
	ds_bpermute_b32 v62, v67, v65
	s_waitcnt lgkmcnt(0)
	v_add_f32_e32 v62, v65, v62
	ds_bpermute_b32 v63, v69, v62
	s_waitcnt lgkmcnt(0)
	v_add_f32_e32 v62, v62, v63
	ds_bpermute_b32 v63, v71, v62
	s_waitcnt lgkmcnt(0)
	v_add_f32_e32 v62, v62, v63
	ds_bpermute_b32 v63, v73, v62
	s_waitcnt lgkmcnt(0)
	v_add_f32_e32 v62, v62, v63
	ds_bpermute_b32 v63, v123, v62
	s_waitcnt lgkmcnt(0)
	v_add_f32_e32 v62, v62, v63
	ds_bpermute_b32 v63, v124, v62
	s_waitcnt lgkmcnt(0)
	v_add_f32_e32 v65, v62, v63
	v_fmamk_f32 v115, v65, 0xba800000, v115
	v_fmac_f32_e32 v114, 0xba800000, v65
	v_fmamk_f32 v117, v65, 0xba800000, v117
	v_fmac_f32_e32 v116, 0xba800000, v65
	v_pk_mul_f32 v[62:63], v[116:117], v[116:117]
	v_pk_mul_f32 v[118:119], v[114:115], v[114:115]
	v_fmamk_f32 v43, v65, 0xba800000, v43
	v_pk_mov_b32 v[126:127], v[118:119], v[62:63] op_sel:[1,0]
	v_mov_b32_e32 v119, v63
	v_pk_add_f32 v[62:63], v[126:127], v[118:119]
	v_fmac_f32_e32 v42, 0xba800000, v65
	v_fmamk_f32 v113, v65, 0xba800000, v113
	v_fmac_f32_e32 v112, 0xba800000, v65
	v_pk_add_f32 v[62:63], v[62:63], v[62:63] op_sel_hi:[0,1]
	v_pk_mul_f32 v[118:119], v[112:113], v[112:113]
	v_pk_mul_f32 v[126:127], v[42:43], v[42:43]
	v_fmac_f32_e32 v108, 0xba800000, v65
	v_pk_mov_b32 v[128:129], v[126:127], v[118:119] op_sel:[1,0]
	v_mov_b32_e32 v127, v119
	v_fmamk_f32 v109, v65, 0xba800000, v109
	v_fmac_f32_e32 v110, 0xba800000, v65
	v_mul_f32_e32 v62, v108, v108
	v_pk_add_f32 v[118:119], v[128:129], v[126:127]
	v_fmamk_f32 v111, v65, 0xba800000, v111
	v_pk_fma_f32 v[126:127], v[108:109], v[108:109], v[62:63] op_sel_hi:[1,1,0]
	v_mul_f32_e32 v62, v110, v110
	v_pk_add_f32 v[118:119], v[118:119], v[118:119] op_sel_hi:[0,1]
	v_pk_fma_f32 v[128:129], v[110:111], v[110:111], v[62:63] op_sel_hi:[1,1,0]
	v_fmamk_f32 v107, v65, 0xba800000, v107
	v_fmac_f32_e32 v106, 0xba800000, v65
	v_fmamk_f32 v105, v65, 0xba800000, v105
	v_fmac_f32_e32 v104, 0xba800000, v65
	v_mul_f32_e32 v126, v104, v104
	v_mul_f32_e32 v128, v105, v105
	v_mul_f32_e32 v62, v106, v106
	v_mul_f32_e32 v118, v107, v107
	v_pk_add_f32 v[126:127], v[126:127], v[128:129]
	v_pk_fma_f32 v[8:9], v[8:9], v[26:27], v[20:21]
	v_pk_fma_f32 v[10:11], v[10:11], v[24:25], v[22:23]
	global_store_dwordx4 v[32:33], v[8:11], off
	v_mov_b64_e32 v[20:21], v[162:163]
	v_mov_b64_e32 v[22:23], v[164:165]
	v_mov_b64_e32 v[24:25], v[166:167]
	v_mov_b64_e32 v[26:27], v[168:169]
	v_pk_add_f32 v[62:63], v[62:63], v[118:119]
	v_pk_fma_f32 v[20:21], v[20:21], v[36:37], v[24:25]
	v_pk_fma_f32 v[22:23], v[22:23], v[34:35], v[26:27]
	global_store_dwordx4 v[32:33], v[20:23], off offset:1024
	v_pk_mul_f32 v[34:35], v[30:31], v[122:123] op_sel_hi:[1,0]
	v_pk_mul_f32 v[36:37], v[28:29], v[122:123] op_sel_hi:[1,0]
	v_mov_b64_e32 v[24:25], v[170:171]
	v_mov_b64_e32 v[26:27], v[172:173]
	v_mov_b64_e32 v[28:29], v[174:175]
	v_mov_b64_e32 v[30:31], v[176:177]
	v_pk_add_f32 v[62:63], v[126:127], v[62:63]
	v_pk_fma_f32 v[28:29], v[24:25], v[36:37], v[28:29]
	v_pk_fma_f32 v[30:31], v[26:27], v[34:35], v[30:31]
	global_store_dwordx4 v[32:33], v[28:31], off offset:2048
	v_mov_b64_e32 v[24:25], v[178:179]
	v_mov_b64_e32 v[26:27], v[180:181]
	v_mov_b64_e32 v[34:35], v[182:183]
	v_mov_b64_e32 v[36:37], v[184:185]
	v_mov_b32_e32 v118, v62
	v_pk_fma_f32 v[24:25], v[24:25], v[60:61], v[34:35]
	v_pk_fma_f32 v[26:27], v[26:27], v[38:39], v[36:37]
	global_store_dwordx4 v[32:33], v[24:27], off offset:3072
	ds_bpermute_b32 v32, v67, v125
	s_waitcnt lgkmcnt(0)
	v_add_f32_e32 v32, v125, v32
	ds_bpermute_b32 v33, v69, v32
	s_waitcnt lgkmcnt(0)
	v_add_f32_e32 v32, v32, v33
	ds_bpermute_b32 v33, v71, v32
	s_waitcnt lgkmcnt(0)
	v_add_f32_e32 v32, v32, v33
	ds_bpermute_b32 v33, v73, v32
	s_waitcnt lgkmcnt(0)
	v_add_f32_e32 v32, v32, v33
	ds_bpermute_b32 v33, v123, v32
	s_waitcnt lgkmcnt(0)
	v_add_f32_e32 v32, v32, v33
	ds_bpermute_b32 v33, v124, v32
	s_waitcnt lgkmcnt(0)
	v_add_f32_e32 v60, v32, v33
	v_fmamk_f32 v45, v60, 0xba800000, v45
	v_fmac_f32_e32 v44, 0xba800000, v60
	v_fmamk_f32 v51, v60, 0xba800000, v51
	v_fmac_f32_e32 v50, 0xba800000, v60
	v_pk_mul_f32 v[32:33], v[50:51], v[50:51]
	v_pk_mul_f32 v[34:35], v[44:45], v[44:45]
	v_fmamk_f32 v57, v60, 0xba800000, v57
	v_pk_mov_b32 v[36:37], v[34:35], v[32:33] op_sel:[1,0]
	v_mov_b32_e32 v35, v33
	v_pk_add_f32 v[32:33], v[36:37], v[34:35]
	v_fmac_f32_e32 v56, 0xba800000, v60
	v_fmamk_f32 v59, v60, 0xba800000, v59
	v_fmac_f32_e32 v58, 0xba800000, v60
	v_pk_add_f32 v[32:33], v[32:33], v[32:33] op_sel_hi:[0,1]
	v_pk_mul_f32 v[34:35], v[58:59], v[58:59]
	v_pk_mul_f32 v[36:37], v[56:57], v[56:57]
	v_fmac_f32_e32 v52, 0xba800000, v60
	v_pk_mov_b32 v[38:39], v[36:37], v[34:35] op_sel:[1,0]
	v_mov_b32_e32 v37, v35
	v_fmamk_f32 v53, v60, 0xba800000, v53
	v_fmac_f32_e32 v54, 0xba800000, v60
	v_mul_f32_e32 v32, v52, v52
	v_pk_add_f32 v[34:35], v[38:39], v[36:37]
	v_fmamk_f32 v55, v60, 0xba800000, v55
	v_pk_fma_f32 v[36:37], v[52:53], v[52:53], v[32:33] op_sel_hi:[1,1,0]
	v_mul_f32_e32 v32, v54, v54
	v_pk_add_f32 v[34:35], v[34:35], v[34:35] op_sel_hi:[0,1]
	v_pk_fma_f32 v[38:39], v[54:55], v[54:55], v[32:33] op_sel_hi:[1,1,0]
	v_fmamk_f32 v49, v60, 0xba800000, v49
	v_fmac_f32_e32 v48, 0xba800000, v60
	v_fmamk_f32 v47, v60, 0xba800000, v47
	v_fmac_f32_e32 v46, 0xba800000, v60
	v_mul_f32_e32 v36, v46, v46
	v_mul_f32_e32 v38, v47, v47
	v_mul_f32_e32 v32, v48, v48
	v_mul_f32_e32 v34, v49, v49
	v_pk_add_f32 v[36:37], v[36:37], v[38:39]
	v_pk_add_f32 v[32:33], v[32:33], v[34:35]
	s_nop 0
	v_pk_add_f32 v[60:61], v[36:37], v[32:33]
	v_mov_b64_e32 v[32:33], v[154:155]
	v_mov_b64_e32 v[34:35], v[156:157]
	v_mov_b64_e32 v[36:37], v[158:159]
	v_mov_b64_e32 v[38:39], v[160:161]
	v_mov_b32_e32 v119, v60
	v_mov_b32_e32 v60, v63
	v_pk_add_f32 v[60:61], v[118:119], v[60:61]
	ds_bpermute_b32 v63, v67, v61
	ds_bpermute_b32 v62, v67, v60
	s_waitcnt lgkmcnt(0)
	v_pk_add_f32 v[60:61], v[60:61], v[62:63]
	ds_bpermute_b32 v63, v69, v61
	ds_bpermute_b32 v62, v69, v60
	s_waitcnt lgkmcnt(0)
	v_pk_add_f32 v[60:61], v[60:61], v[62:63]
	ds_bpermute_b32 v63, v71, v61
	ds_bpermute_b32 v62, v71, v60
	s_waitcnt lgkmcnt(0)
	v_pk_add_f32 v[60:61], v[60:61], v[62:63]
	ds_bpermute_b32 v63, v73, v61
	ds_bpermute_b32 v62, v73, v60
	s_waitcnt lgkmcnt(0)
	v_pk_add_f32 v[60:61], v[60:61], v[62:63]
	ds_bpermute_b32 v63, v123, v61
	ds_bpermute_b32 v62, v123, v60
	s_waitcnt lgkmcnt(0)
	v_pk_add_f32 v[60:61], v[60:61], v[62:63]
	ds_bpermute_b32 v63, v124, v61
	ds_bpermute_b32 v62, v124, v60
	s_waitcnt lgkmcnt(0)
	v_pk_add_f32 v[60:61], v[60:61], v[62:63]
	s_nop 0
	v_pk_fma_f32 v[118:119], v[60:61], s[4:5], v[120:121] op_sel_hi:[1,0,0]
	s_nop 0
	v_mul_f32_e32 v60, 0x4b800000, v119
	v_cmp_gt_f32_e64 s[8:9], s68, v119
	v_cmp_gt_f32_e32 vcc, s68, v118
	s_nop 0
	v_cndmask_b32_e64 v60, v119, v60, s[8:9]
	v_rsq_f32_e32 v60, v60
	s_nop 0
	v_mul_f32_e32 v61, 0x45800000, v60
	v_cndmask_b32_e64 v120, v60, v61, s[8:9]
	v_pk_mul_f32 v[50:51], v[50:51], v[120:121] op_sel_hi:[1,0]
	v_pk_mul_f32 v[44:45], v[44:45], v[120:121] op_sel_hi:[1,0]
	v_pk_mul_f32 v[46:47], v[46:47], v[120:121] op_sel_hi:[1,0]
	v_pk_fma_f32 v[60:61], v[32:33], v[44:45], v[36:37]
	v_pk_fma_f32 v[62:63], v[34:35], v[50:51], v[38:39]
	global_store_dwordx4 v[40:41], v[60:63], off
	v_mov_b64_e32 v[32:33], v[162:163]
	v_mov_b64_e32 v[34:35], v[164:165]
	v_mov_b64_e32 v[36:37], v[166:167]
	v_mov_b64_e32 v[38:39], v[168:169]
	v_pk_mul_f32 v[44:45], v[58:59], v[120:121] op_sel_hi:[1,0]
	v_pk_mul_f32 v[50:51], v[56:57], v[120:121] op_sel_hi:[1,0]
	v_pk_fma_f32 v[58:59], v[34:35], v[44:45], v[38:39]
	v_pk_fma_f32 v[56:57], v[32:33], v[50:51], v[36:37]
	global_store_dwordx4 v[40:41], v[56:59], off offset:1024
	v_mov_b64_e32 v[32:33], v[170:171]
	v_mov_b64_e32 v[34:35], v[172:173]
	v_mov_b64_e32 v[36:37], v[174:175]
	v_mov_b64_e32 v[38:39], v[176:177]
	v_pk_mul_f32 v[44:45], v[54:55], v[120:121] op_sel_hi:[1,0]
	v_pk_mul_f32 v[50:51], v[52:53], v[120:121] op_sel_hi:[1,0]
	v_pk_fma_f32 v[54:55], v[34:35], v[44:45], v[38:39]
	v_pk_fma_f32 v[52:53], v[32:33], v[50:51], v[36:37]
	global_store_dwordx4 v[40:41], v[52:55], off offset:2048
	v_mov_b64_e32 v[32:33], v[178:179]
	v_mov_b64_e32 v[34:35], v[180:181]
	v_mov_b64_e32 v[36:37], v[182:183]
	v_mov_b64_e32 v[38:39], v[184:185]
	v_pk_mul_f32 v[44:45], v[48:49], v[120:121] op_sel_hi:[1,0]
	v_pk_fma_f32 v[48:49], v[32:33], v[46:47], v[36:37]
	v_mul_f32_e32 v32, 0x4b800000, v118
	v_cndmask_b32_e32 v32, v118, v32, vcc
	v_rsq_f32_e32 v32, v32
	v_pk_fma_f32 v[50:51], v[34:35], v[44:45], v[38:39]
	global_store_dwordx4 v[40:41], v[48:51], off offset:3072
	v_mul_f32_e32 v33, 0x45800000, v32
	v_cndmask_b32_e32 v118, v32, v33, vcc
	v_mov_b64_e32 v[32:33], v[154:155]
	v_mov_b64_e32 v[34:35], v[156:157]
	v_mov_b64_e32 v[36:37], v[158:159]
	v_mov_b64_e32 v[38:39], v[160:161]
	v_pk_mul_f32 v[40:41], v[116:117], v[118:119] op_sel_hi:[1,0]
	v_pk_mul_f32 v[44:45], v[114:115], v[118:119] op_sel_hi:[1,0]
	v_pk_mul_f32 v[112:113], v[112:113], v[118:119] op_sel_hi:[1,0]
	v_pk_mul_f32 v[110:111], v[110:111], v[118:119] op_sel_hi:[1,0]
	v_pk_mul_f32 v[108:109], v[108:109], v[118:119] op_sel_hi:[1,0]
	s_andn2_b64 vcc, exec, s[14:15]
	v_pk_fma_f32 v[44:45], v[32:33], v[44:45], v[36:37]
	v_pk_fma_f32 v[46:47], v[34:35], v[40:41], v[38:39]
	global_store_dwordx4 v[102:103], v[44:47], off
	v_mov_b64_e32 v[32:33], v[162:163]
	v_mov_b64_e32 v[34:35], v[164:165]
	v_mov_b64_e32 v[36:37], v[166:167]
	v_mov_b64_e32 v[38:39], v[168:169]
	v_pk_mul_f32 v[40:41], v[42:43], v[118:119] op_sel_hi:[1,0]
	v_pk_fma_f32 v[42:43], v[34:35], v[112:113], v[38:39]
	v_pk_fma_f32 v[40:41], v[32:33], v[40:41], v[36:37]
	global_store_dwordx4 v[102:103], v[40:43], off offset:1024
	v_mov_b64_e32 v[32:33], v[170:171]
	v_mov_b64_e32 v[34:35], v[172:173]
	v_mov_b64_e32 v[36:37], v[174:175]
	v_mov_b64_e32 v[38:39], v[176:177]
	v_pk_fma_f32 v[36:37], v[32:33], v[108:109], v[36:37]
	v_pk_fma_f32 v[38:39], v[34:35], v[110:111], v[38:39]
	global_store_dwordx4 v[102:103], v[36:39], off offset:2048
	v_pk_mul_f32 v[108:109], v[106:107], v[118:119] op_sel_hi:[1,0]
	v_pk_mul_f32 v[110:111], v[104:105], v[118:119] op_sel_hi:[1,0]
	v_mov_b64_e32 v[32:33], v[178:179]
	v_mov_b64_e32 v[34:35], v[180:181]
	v_mov_b64_e32 v[104:105], v[182:183]
	v_mov_b64_e32 v[106:107], v[184:185]
	v_pk_fma_f32 v[32:33], v[32:33], v[110:111], v[104:105]
	v_pk_fma_f32 v[34:35], v[34:35], v[108:109], v[106:107]
	global_store_dwordx4 v[102:103], v[32:35], off offset:3072
	s_cbranch_vccnz .LBB0_224
	v_lshl_add_u64 v[102:103], v[94:95], 0, s[2:3]
	v_mov_b64_e32 v[94:95], s[60:61]
	v_mad_u64_u32 v[104:105], s[4:5], v102, s7, v[94:95]
	v_mad_i32_i24 v105, v103, s7, v105
	v_lshl_add_u64 v[110:111], v[104:105], 0, s[30:31]
	v_lshlrev_b32_e32 v152, 2, v66
	v_lshl_add_u64 v[112:113], v[104:105], 0, v[152:153]
	v_lshl_add_u64 v[106:107], v[110:111], 0, v[152:153]
	global_load_dwordx4 v[186:189], v[112:113], off offset:1024
	global_load_dwordx4 v[190:193], v[112:113], off offset:2048
	global_load_dwordx4 v[194:197], v[112:113], off offset:3072
	global_load_dwordx4 v[102:105], v[112:113], off
	s_nop 0
	global_load_dwordx4 v[198:201], v[106:107], off offset:1024
	global_load_dwordx4 v[202:205], v[106:107], off offset:2048
	global_load_dwordx4 v[224:227], v[106:107], off offset:3072
	global_load_dwordx4 v[106:109], v[106:107], off
	s_waitcnt vmcnt(0) lgkmcnt(0)
	v_pk_add_f32 v[108:109], v[108:109], 1.0 op_sel_hi:[1,0]
	v_pk_add_f32 v[106:107], v[106:107], 1.0 op_sel_hi:[1,0]
	v_pk_fma_f32 v[18:19], v[18:19], v[108:109], v[104:105]
	v_pk_fma_f32 v[16:17], v[16:17], v[106:107], v[102:103]
	s_nop 0
	v_cvt_pk_bf16_f32 v16, v16, v17
	v_cvt_pk_bf16_f32 v17, v18, v19
	global_store_dwordx2 v[84:85], v[16:17], off
	v_lshlrev_b32_e32 v16, 2, v68
	v_mov_b32_e32 v17, v153
	v_lshl_add_u64 v[18:19], v[110:111], 0, v[16:17]
	v_mov_b64_e32 v[102:103], v[186:187]
	v_mov_b64_e32 v[104:105], v[188:189]
	v_mov_b64_e32 v[106:107], v[198:199]
	v_mov_b64_e32 v[108:109], v[200:201]
	v_pk_add_f32 v[18:19], v[108:109], 1.0 op_sel_hi:[1,0]
	v_pk_add_f32 v[106:107], v[106:107], 1.0 op_sel_hi:[1,0]
	v_pk_fma_f32 v[14:15], v[14:15], v[18:19], v[104:105]
	v_pk_fma_f32 v[12:13], v[12:13], v[106:107], v[102:103]
	s_nop 0
	v_cvt_pk_bf16_f32 v12, v12, v13
	v_cvt_pk_bf16_f32 v13, v14, v15
	global_store_dwordx2 v[84:85], v[12:13], off offset:512
	v_lshlrev_b32_e32 v12, 2, v70
	v_mov_b32_e32 v13, v153
	v_lshl_add_u64 v[14:15], v[110:111], 0, v[12:13]
	v_mov_b64_e32 v[102:103], v[190:191]
	v_mov_b64_e32 v[104:105], v[192:193]
	v_mov_b64_e32 v[106:107], v[202:203]
	v_mov_b64_e32 v[108:109], v[204:205]
	v_pk_add_f32 v[14:15], v[108:109], 1.0 op_sel_hi:[1,0]
	v_pk_add_f32 v[18:19], v[106:107], 1.0 op_sel_hi:[1,0]
	v_pk_fma_f32 v[6:7], v[6:7], v[14:15], v[104:105]
	v_pk_fma_f32 v[4:5], v[4:5], v[18:19], v[102:103]
	s_nop 0
	v_cvt_pk_bf16_f32 v4, v4, v5
	v_cvt_pk_bf16_f32 v5, v6, v7
	global_store_dwordx2 v[84:85], v[4:5], off offset:1024
	v_lshlrev_b32_e32 v4, 2, v72
	v_mov_b32_e32 v5, v153
	v_lshl_add_u64 v[6:7], v[110:111], 0, v[4:5]
	v_mov_b64_e32 v[102:103], v[194:195]
	v_mov_b64_e32 v[104:105], v[196:197]
	v_mov_b64_e32 v[106:107], v[224:225]
	v_mov_b64_e32 v[108:109], v[226:227]
	v_pk_add_f32 v[6:7], v[108:109], 1.0 op_sel_hi:[1,0]
	v_pk_add_f32 v[14:15], v[106:107], 1.0 op_sel_hi:[1,0]
	v_pk_fma_f32 v[2:3], v[2:3], v[6:7], v[104:105]
	v_pk_fma_f32 v[0:1], v[0:1], v[14:15], v[102:103]
	s_nop 0
	v_cvt_pk_bf16_f32 v0, v0, v1
	v_cvt_pk_bf16_f32 v1, v2, v3
	global_store_dwordx2 v[84:85], v[0:1], off offset:1536
	v_lshl_add_u64 v[0:1], v[92:93], 0, s[2:3]
	v_mad_u64_u32 v[2:3], s[4:5], v0, s7, v[94:95]
	v_mad_i32_i24 v3, v1, s7, v3
	v_lshl_add_u64 v[0:1], v[2:3], 0, s[30:31]
	v_lshl_add_u64 v[2:3], v[2:3], 0, v[152:153]
	v_lshl_add_u64 v[6:7], v[0:1], 0, v[152:153]
	global_load_dwordx4 v[186:189], v[2:3], off offset:1024
	global_load_dwordx4 v[190:193], v[2:3], off offset:2048
	global_load_dwordx4 v[194:197], v[2:3], off offset:3072
	global_load_dwordx4 v[102:105], v[2:3], off
	global_load_dwordx4 v[198:201], v[6:7], off offset:1024
	global_load_dwordx4 v[202:205], v[6:7], off offset:2048
	global_load_dwordx4 v[224:227], v[6:7], off offset:3072
	global_load_dwordx4 v[106:109], v[6:7], off
	s_waitcnt vmcnt(0) lgkmcnt(0)
	v_pk_add_f32 v[6:7], v[108:109], 1.0 op_sel_hi:[1,0]
	v_pk_add_f32 v[14:15], v[106:107], 1.0 op_sel_hi:[1,0]
	v_pk_fma_f32 v[6:7], v[10:11], v[6:7], v[104:105]
	v_pk_fma_f32 v[8:9], v[8:9], v[14:15], v[102:103]
	v_lshl_add_u64 v[10:11], v[82:83], 0, v[96:97]
	v_cvt_pk_bf16_f32 v8, v8, v9
	v_cvt_pk_bf16_f32 v9, v6, v7
	global_store_dwordx2 v[10:11], v[8:9], off
	v_lshl_add_u64 v[14:15], v[0:1], 0, v[16:17]
	v_mov_b64_e32 v[6:7], v[186:187]
	v_mov_b64_e32 v[8:9], v[188:189]
	v_mov_b64_e32 v[102:103], v[198:199]
	v_mov_b64_e32 v[104:105], v[200:201]
	v_pk_add_f32 v[14:15], v[104:105], 1.0 op_sel_hi:[1,0]
	v_pk_add_f32 v[18:19], v[102:103], 1.0 op_sel_hi:[1,0]
	v_pk_fma_f32 v[8:9], v[22:23], v[14:15], v[8:9]
	v_pk_fma_f32 v[6:7], v[20:21], v[18:19], v[6:7]
	v_lshl_add_u64 v[14:15], v[0:1], 0, v[12:13]
	v_cvt_pk_bf16_f32 v6, v6, v7
	v_cvt_pk_bf16_f32 v7, v8, v9
	global_store_dwordx2 v[10:11], v[6:7], off offset:512
	v_mov_b64_e32 v[6:7], v[190:191]
	v_mov_b64_e32 v[8:9], v[192:193]
	v_lshl_add_u64 v[0:1], v[0:1], 0, v[4:5]
	v_mov_b64_e32 v[18:19], v[202:203]
	v_mov_b64_e32 v[20:21], v[204:205]
	v_pk_add_f32 v[14:15], v[20:21], 1.0 op_sel_hi:[1,0]
	v_pk_add_f32 v[18:19], v[18:19], 1.0 op_sel_hi:[1,0]
	v_pk_fma_f32 v[8:9], v[30:31], v[14:15], v[8:9]
	v_pk_fma_f32 v[6:7], v[28:29], v[18:19], v[6:7]
	s_nop 0
	v_cvt_pk_bf16_f32 v6, v6, v7
	v_cvt_pk_bf16_f32 v7, v8, v9
	global_store_dwordx2 v[10:11], v[6:7], off offset:1024
	v_mov_b64_e32 v[6:7], v[194:195]
	v_mov_b64_e32 v[8:9], v[196:197]
	s_nop 0
	v_mov_b64_e32 v[0:1], v[224:225]
	v_mov_b64_e32 v[2:3], v[226:227]
	v_pk_add_f32 v[2:3], v[2:3], 1.0 op_sel_hi:[1,0]
	v_pk_add_f32 v[0:1], v[0:1], 1.0 op_sel_hi:[1,0]
	v_pk_fma_f32 v[2:3], v[26:27], v[2:3], v[8:9]
	v_pk_fma_f32 v[0:1], v[24:25], v[0:1], v[6:7]
	s_nop 0
	v_cvt_pk_bf16_f32 v0, v0, v1
	v_cvt_pk_bf16_f32 v1, v2, v3
	global_store_dwordx2 v[10:11], v[0:1], off offset:1536
	v_lshl_add_u64 v[0:1], v[90:91], 0, s[2:3]
	v_mad_u64_u32 v[2:3], s[4:5], v0, s7, v[94:95]
	v_mad_i32_i24 v3, v1, s7, v3
	v_lshl_add_u64 v[0:1], v[2:3], 0, s[30:31]
	v_lshl_add_u64 v[2:3], v[2:3], 0, v[152:153]
	v_lshl_add_u64 v[10:11], v[0:1], 0, v[152:153]
	global_load_dwordx4 v[186:189], v[2:3], off offset:1024
	global_load_dwordx4 v[190:193], v[2:3], off offset:2048
	global_load_dwordx4 v[194:197], v[2:3], off offset:3072
	global_load_dwordx4 v[6:9], v[2:3], off
	global_load_dwordx4 v[198:201], v[10:11], off offset:1024
	global_load_dwordx4 v[202:205], v[10:11], off offset:2048
	global_load_dwordx4 v[224:227], v[10:11], off offset:3072
	global_load_dwordx4 v[18:21], v[10:11], off
	s_waitcnt vmcnt(0) lgkmcnt(0)
	v_pk_add_f32 v[10:11], v[20:21], 1.0 op_sel_hi:[1,0]
	v_pk_add_f32 v[14:15], v[18:19], 1.0 op_sel_hi:[1,0]
	v_pk_fma_f32 v[8:9], v[62:63], v[10:11], v[8:9]
	v_pk_fma_f32 v[6:7], v[60:61], v[14:15], v[6:7]
	v_lshl_add_u64 v[10:11], v[82:83], 0, v[100:101]
	v_cvt_pk_bf16_f32 v6, v6, v7
	v_cvt_pk_bf16_f32 v7, v8, v9
	global_store_dwordx2 v[10:11], v[6:7], off
	v_lshl_add_u64 v[14:15], v[0:1], 0, v[16:17]
	v_mov_b64_e32 v[6:7], v[186:187]
	v_mov_b64_e32 v[8:9], v[188:189]
	v_mov_b64_e32 v[18:19], v[198:199]
	v_mov_b64_e32 v[20:21], v[200:201]
	v_pk_add_f32 v[14:15], v[20:21], 1.0 op_sel_hi:[1,0]
	v_pk_add_f32 v[18:19], v[18:19], 1.0 op_sel_hi:[1,0]
	v_pk_fma_f32 v[8:9], v[58:59], v[14:15], v[8:9]
	v_pk_fma_f32 v[6:7], v[56:57], v[18:19], v[6:7]
	v_lshl_add_u64 v[14:15], v[0:1], 0, v[12:13]
	v_cvt_pk_bf16_f32 v6, v6, v7
	v_cvt_pk_bf16_f32 v7, v8, v9
	global_store_dwordx2 v[10:11], v[6:7], off offset:512
	v_mov_b64_e32 v[6:7], v[190:191]
	v_mov_b64_e32 v[8:9], v[192:193]
	v_lshl_add_u64 v[0:1], v[0:1], 0, v[4:5]
	v_mov_b64_e32 v[18:19], v[202:203]
	v_mov_b64_e32 v[20:21], v[204:205]
	v_pk_add_f32 v[14:15], v[20:21], 1.0 op_sel_hi:[1,0]
	v_pk_add_f32 v[18:19], v[18:19], 1.0 op_sel_hi:[1,0]
	v_pk_fma_f32 v[8:9], v[54:55], v[14:15], v[8:9]
	v_pk_fma_f32 v[6:7], v[52:53], v[18:19], v[6:7]
	s_nop 0
	v_cvt_pk_bf16_f32 v6, v6, v7
	v_cvt_pk_bf16_f32 v7, v8, v9
	global_store_dwordx2 v[10:11], v[6:7], off offset:1024
	v_mov_b64_e32 v[6:7], v[194:195]
	v_mov_b64_e32 v[8:9], v[196:197]
	s_nop 0
	v_mov_b64_e32 v[0:1], v[224:225]
	v_mov_b64_e32 v[2:3], v[226:227]
	v_pk_add_f32 v[2:3], v[2:3], 1.0 op_sel_hi:[1,0]
	v_pk_add_f32 v[0:1], v[0:1], 1.0 op_sel_hi:[1,0]
	v_pk_fma_f32 v[2:3], v[50:51], v[2:3], v[8:9]
	v_pk_fma_f32 v[0:1], v[48:49], v[0:1], v[6:7]
	s_nop 0
	v_cvt_pk_bf16_f32 v0, v0, v1
	v_cvt_pk_bf16_f32 v1, v2, v3
	global_store_dwordx2 v[10:11], v[0:1], off offset:1536
	v_lshl_add_u64 v[0:1], v[88:89], 0, s[2:3]
	v_mad_u64_u32 v[2:3], s[4:5], v0, s7, v[94:95]
	v_mad_i32_i24 v3, v1, s7, v3
	v_lshl_add_u64 v[0:1], v[2:3], 0, s[30:31]
	v_lshl_add_u64 v[2:3], v[2:3], 0, v[152:153]
	v_lshl_add_u64 v[10:11], v[0:1], 0, v[152:153]
	global_load_dwordx4 v[186:189], v[2:3], off offset:1024
	global_load_dwordx4 v[190:193], v[2:3], off offset:2048
	global_load_dwordx4 v[194:197], v[2:3], off offset:3072
	global_load_dwordx4 v[6:9], v[2:3], off
	global_load_dwordx4 v[198:201], v[10:11], off offset:1024
	global_load_dwordx4 v[202:205], v[10:11], off offset:2048
	global_load_dwordx4 v[224:227], v[10:11], off offset:3072
	global_load_dwordx4 v[18:21], v[10:11], off
	s_waitcnt vmcnt(0) lgkmcnt(0)
	v_pk_add_f32 v[10:11], v[20:21], 1.0 op_sel_hi:[1,0]
	v_pk_add_f32 v[14:15], v[18:19], 1.0 op_sel_hi:[1,0]
	v_pk_fma_f32 v[8:9], v[46:47], v[10:11], v[8:9]
	v_pk_fma_f32 v[6:7], v[44:45], v[14:15], v[6:7]
	v_lshl_add_u64 v[18:19], v[82:83], 0, v[98:99]
	v_cvt_pk_bf16_f32 v6, v6, v7
	v_cvt_pk_bf16_f32 v7, v8, v9
	global_store_dwordx2 v[18:19], v[6:7], off
	v_lshl_add_u64 v[10:11], v[0:1], 0, v[16:17]
	v_mov_b64_e32 v[6:7], v[186:187]
	v_mov_b64_e32 v[8:9], v[188:189]
	v_mov_b64_e32 v[14:15], v[198:199]
	v_mov_b64_e32 v[16:17], v[200:201]
	v_pk_add_f32 v[10:11], v[16:17], 1.0 op_sel_hi:[1,0]
	v_pk_add_f32 v[14:15], v[14:15], 1.0 op_sel_hi:[1,0]
	v_pk_fma_f32 v[8:9], v[42:43], v[10:11], v[8:9]
	v_pk_fma_f32 v[6:7], v[40:41], v[14:15], v[6:7]
	v_lshl_add_u64 v[10:11], v[0:1], 0, v[12:13]
	v_cvt_pk_bf16_f32 v6, v6, v7
	v_cvt_pk_bf16_f32 v7, v8, v9
	global_store_dwordx2 v[18:19], v[6:7], off offset:512
	v_mov_b64_e32 v[6:7], v[190:191]
	v_mov_b64_e32 v[8:9], v[192:193]
	v_lshl_add_u64 v[0:1], v[0:1], 0, v[4:5]
	v_mov_b64_e32 v[10:11], v[202:203]
	v_mov_b64_e32 v[12:13], v[204:205]
	v_pk_add_f32 v[12:13], v[12:13], 1.0 op_sel_hi:[1,0]
	v_pk_add_f32 v[10:11], v[10:11], 1.0 op_sel_hi:[1,0]
	v_pk_fma_f32 v[8:9], v[38:39], v[12:13], v[8:9]
	v_pk_fma_f32 v[6:7], v[36:37], v[10:11], v[6:7]
	s_nop 0
	v_cvt_pk_bf16_f32 v6, v6, v7
	v_cvt_pk_bf16_f32 v7, v8, v9
	global_store_dwordx2 v[18:19], v[6:7], off offset:1024
	v_mov_b64_e32 v[6:7], v[194:195]
	v_mov_b64_e32 v[8:9], v[196:197]
	s_nop 0
	v_mov_b64_e32 v[0:1], v[224:225]
	v_mov_b64_e32 v[2:3], v[226:227]
	v_pk_add_f32 v[2:3], v[2:3], 1.0 op_sel_hi:[1,0]
	v_pk_add_f32 v[0:1], v[0:1], 1.0 op_sel_hi:[1,0]
	v_pk_fma_f32 v[2:3], v[34:35], v[2:3], v[8:9]
	v_pk_fma_f32 v[0:1], v[32:33], v[0:1], v[6:7]
	s_nop 0
	v_cvt_pk_bf16_f32 v0, v0, v1
	v_cvt_pk_bf16_f32 v1, v2, v3
	global_store_dwordx2 v[18:19], v[0:1], off offset:1536
	s_branch .LBB0_224

.LBB0_588:
	s_add_i32 s10, 0, 0x10000
	v_add_u32_e32 v148, s10, v184
	s_waitcnt lgkmcnt(0)
	ds_read_b128 v[136:139], v148
	ds_read_b128 v[140:143], v148 offset:1024
	ds_read_b128 v[144:147], v148 offset:2048
	ds_read_b128 v[148:151], v148 offset:3072
	s_add_i32 s9, s8, 2
	s_cmp_eq_u32 s2, s8
	v_lshl_add_u64 v[154:155], v[130:131], 0, s[54:55]
	s_cselect_b64 vcc, -1, 0
	v_cndmask_b32_e32 v155, v155, v132, vcc
	v_cndmask_b32_e32 v154, v154, v133, vcc
	v_cndmask_b32_e32 v211, v129, v134, vcc
	v_cndmask_b32_e32 v210, v128, v135, vcc
	v_lshl_add_u64 v[214:215], v[130:131], 0, v[162:163]
	s_add_i32 m0, s28, 0xc000
	ds_read_b128 v[172:175], v185
	ds_read_b128 v[176:179], v185 offset:1024
	ds_read_b128 v[180:183], v185 offset:2048
	ds_read_b128 v[186:189], v185 offset:3072
	ds_read_b128 v[190:193], v185 offset:4096
	ds_read_b128 v[194:197], v185 offset:5120
	ds_read_b128 v[198:201], v185 offset:6144
	ds_read_b128 v[202:205], v185 offset:7168
	global_load_lds_dwordx4 v[214:215], off
	v_lshl_add_u64 v[214:215], v[130:131], 0, v[160:161]
	s_add_i32 m0, s28, 0xe000
	s_nop 0
	global_load_lds_dwordx4 v[214:215], off
	s_waitcnt lgkmcnt(8)
	s_barrier
	s_waitcnt lgkmcnt(0)
	v_mfma_f32_16x16x32_bf16 v[124:127], v[136:139], v[172:175], v[124:127]
	v_mfma_f32_16x16x32_bf16 v[120:123], v[144:147], v[172:175], v[120:123]
	v_mfma_f32_16x16x32_bf16 v[108:111], v[136:139], v[180:183], v[108:111]
	v_mfma_f32_16x16x32_bf16 v[104:107], v[144:147], v[180:183], v[104:107]
	v_mfma_f32_16x16x32_bf16 v[92:95], v[136:139], v[190:193], v[92:95]
	v_mfma_f32_16x16x32_bf16 v[88:91], v[144:147], v[190:193], v[88:91]
	v_mfma_f32_16x16x32_bf16 v[76:79], v[136:139], v[198:201], v[76:79]
	v_mfma_f32_16x16x32_bf16 v[72:75], v[144:147], v[198:201], v[72:75]
	v_mfma_f32_16x16x32_bf16 v[124:127], v[140:143], v[176:179], v[124:127]
	v_mfma_f32_16x16x32_bf16 v[120:123], v[148:151], v[176:179], v[120:123]
	v_mfma_f32_16x16x32_bf16 v[108:111], v[140:143], v[186:189], v[108:111]
	v_mfma_f32_16x16x32_bf16 v[104:107], v[148:151], v[186:189], v[104:107]
	v_mfma_f32_16x16x32_bf16 v[92:95], v[140:143], v[194:197], v[92:95]
	v_mfma_f32_16x16x32_bf16 v[88:91], v[148:151], v[194:197], v[88:91]
	v_mfma_f32_16x16x32_bf16 v[76:79], v[140:143], v[202:205], v[76:79]
	v_mfma_f32_16x16x32_bf16 v[72:75], v[148:151], v[202:205], v[72:75]
	s_barrier
	s_add_i32 s8, 0, 0x14000
	s_add_i32 s10, s10, s71
	v_add_u32_e32 v152, s8, v184
	v_lshl_add_u64 v[214:215], v[210:211], 0, v[156:157]
	s_mov_b32 m0, s10
	ds_read_b128 v[226:229], v152
	ds_read_b128 v[230:233], v152 offset:1024
	ds_read_b128 v[234:237], v152 offset:2048
	ds_read_b128 v[238:241], v152 offset:3072
	global_load_lds_dwordx4 v[214:215], off
	v_lshl_add_u64 v[216:217], v[210:211], 0, v[158:159]
	s_add_i32 m0, s10, 0x2000
	s_nop 0
	global_load_lds_dwordx4 v[216:217], off
	s_barrier
	s_waitcnt lgkmcnt(0)
	v_mfma_f32_16x16x32_bf16 v[116:119], v[226:229], v[172:175], v[116:119]
	v_mfma_f32_16x16x32_bf16 v[112:115], v[234:237], v[172:175], v[112:115]
	v_mfma_f32_16x16x32_bf16 v[100:103], v[226:229], v[180:183], v[100:103]
	v_mfma_f32_16x16x32_bf16 v[96:99], v[234:237], v[180:183], v[96:99]
	v_mfma_f32_16x16x32_bf16 v[84:87], v[226:229], v[190:193], v[84:87]
	v_mfma_f32_16x16x32_bf16 v[80:83], v[234:237], v[190:193], v[80:83]
	v_mfma_f32_16x16x32_bf16 v[68:71], v[226:229], v[198:201], v[68:71]
	v_mfma_f32_16x16x32_bf16 v[64:67], v[234:237], v[198:201], v[64:67]
	v_mfma_f32_16x16x32_bf16 v[116:119], v[230:233], v[176:179], v[116:119]
	v_mfma_f32_16x16x32_bf16 v[112:115], v[238:241], v[176:179], v[112:115]
	v_mfma_f32_16x16x32_bf16 v[100:103], v[230:233], v[186:189], v[100:103]
	v_mfma_f32_16x16x32_bf16 v[96:99], v[238:241], v[186:189], v[96:99]
	v_mfma_f32_16x16x32_bf16 v[84:87], v[230:233], v[194:197], v[84:87]
	v_mfma_f32_16x16x32_bf16 v[80:83], v[238:241], v[194:197], v[80:83]
	v_mfma_f32_16x16x32_bf16 v[68:71], v[230:233], v[202:205], v[68:71]
	v_mfma_f32_16x16x32_bf16 v[64:67], v[238:241], v[202:205], v[64:67]
	s_mov_b32 m0, s28
	v_lshl_add_u64 v[218:219], v[154:155], 0, v[156:157]
	s_barrier
	ds_read_b128 v[172:175], v185 offset:16384
	ds_read_b128 v[176:179], v185 offset:17408
	ds_read_b128 v[180:183], v185 offset:18432
	ds_read_b128 v[186:189], v185 offset:19456
	ds_read_b128 v[190:193], v185 offset:20480
	ds_read_b128 v[194:197], v185 offset:21504
	ds_read_b128 v[198:201], v185 offset:22528
	ds_read_b128 v[202:205], v185 offset:23552
	global_load_lds_dwordx4 v[218:219], off
	v_lshl_add_u64 v[220:221], v[154:155], 0, v[158:159]
	s_mov_b32 m0, s29
	s_nop 0
	global_load_lds_dwordx4 v[220:221], off
	s_barrier
	s_waitcnt lgkmcnt(0)
	v_mfma_f32_16x16x32_bf16 v[60:63], v[136:139], v[172:175], v[60:63]
	v_mfma_f32_16x16x32_bf16 v[56:59], v[144:147], v[172:175], v[56:59]
	v_mfma_f32_16x16x32_bf16 v[44:47], v[136:139], v[180:183], v[44:47]
	v_mfma_f32_16x16x32_bf16 v[40:43], v[144:147], v[180:183], v[40:43]
	v_mfma_f32_16x16x32_bf16 v[28:31], v[136:139], v[190:193], v[28:31]
	v_mfma_f32_16x16x32_bf16 v[24:27], v[144:147], v[190:193], v[24:27]
	v_mfma_f32_16x16x32_bf16 v[12:15], v[136:139], v[198:201], v[12:15]
	v_mfma_f32_16x16x32_bf16 v[8:11], v[144:147], v[198:201], v[8:11]
	v_mfma_f32_16x16x32_bf16 v[60:63], v[140:143], v[176:179], v[60:63]
	v_mfma_f32_16x16x32_bf16 v[56:59], v[148:151], v[176:179], v[56:59]
	v_mfma_f32_16x16x32_bf16 v[44:47], v[140:143], v[186:189], v[44:47]
	v_mfma_f32_16x16x32_bf16 v[40:43], v[148:151], v[186:189], v[40:43]
	v_mfma_f32_16x16x32_bf16 v[28:31], v[140:143], v[194:197], v[28:31]
	v_mfma_f32_16x16x32_bf16 v[24:27], v[148:151], v[194:197], v[24:27]
	v_mfma_f32_16x16x32_bf16 v[12:15], v[140:143], v[202:205], v[12:15]
	v_mfma_f32_16x16x32_bf16 v[8:11], v[148:151], v[202:205], v[8:11]
	s_barrier
	v_lshl_add_u64 v[136:137], v[210:211], 0, s[16:17]
	s_add_i32 s8, s8, s71
	v_lshl_add_u64 v[210:211], v[136:137], 0, v[156:157]
	s_mov_b32 m0, s8
	v_lshl_add_u64 v[224:225], v[136:137], 0, v[158:159]
	global_load_lds_dwordx4 v[210:211], off
	s_add_i32 m0, s8, 0x2000
	s_nop 0
	global_load_lds_dwordx4 v[224:225], off
	s_waitcnt vmcnt(6)
	s_barrier
	v_mfma_f32_16x16x32_bf16 v[52:55], v[226:229], v[172:175], v[52:55]
	v_mfma_f32_16x16x32_bf16 v[48:51], v[234:237], v[172:175], v[48:51]
	v_mfma_f32_16x16x32_bf16 v[36:39], v[226:229], v[180:183], v[36:39]
	v_mfma_f32_16x16x32_bf16 v[32:35], v[234:237], v[180:183], v[32:35]
	v_mfma_f32_16x16x32_bf16 v[20:23], v[226:229], v[190:193], v[20:23]
	v_mfma_f32_16x16x32_bf16 v[16:19], v[234:237], v[190:193], v[16:19]
	v_mfma_f32_16x16x32_bf16 v[4:7], v[226:229], v[198:201], v[4:7]
	v_mfma_f32_16x16x32_bf16 v[0:3], v[234:237], v[198:201], v[0:3]
	v_mfma_f32_16x16x32_bf16 v[52:55], v[230:233], v[176:179], v[52:55]
	v_mfma_f32_16x16x32_bf16 v[48:51], v[238:241], v[176:179], v[48:51]
	v_mfma_f32_16x16x32_bf16 v[36:39], v[230:233], v[186:189], v[36:39]
	v_mfma_f32_16x16x32_bf16 v[32:35], v[238:241], v[186:189], v[32:35]
	v_mfma_f32_16x16x32_bf16 v[20:23], v[230:233], v[194:197], v[20:23]
	v_mfma_f32_16x16x32_bf16 v[16:19], v[238:241], v[194:197], v[16:19]
	v_mfma_f32_16x16x32_bf16 v[4:7], v[230:233], v[202:205], v[4:7]
	v_mfma_f32_16x16x32_bf16 v[0:3], v[238:241], v[202:205], v[0:3]
	s_add_i32 s8, 0, 0x18000
	v_add_u32_e32 v148, s8, v184
	s_barrier
	ds_read_b128 v[136:139], v148
	ds_read_b128 v[140:143], v148 offset:1024
	ds_read_b128 v[144:147], v148 offset:2048
	ds_read_b128 v[148:151], v148 offset:3072
	v_lshl_add_u64 v[154:155], v[154:155], 0, s[16:17]
	s_mov_b32 m0, s35
	v_lshl_add_u64 v[226:227], v[154:155], 0, v[156:157]
	ds_read_b128 v[172:175], v185 offset:32768
	ds_read_b128 v[176:179], v185 offset:33792
	ds_read_b128 v[180:183], v185 offset:34816
	ds_read_b128 v[186:189], v185 offset:35840
	ds_read_b128 v[190:193], v185 offset:36864
	ds_read_b128 v[194:197], v185 offset:37888
	ds_read_b128 v[198:201], v185 offset:38912
	ds_read_b128 v[202:205], v185 offset:39936
	global_load_lds_dwordx4 v[226:227], off
	v_lshl_add_u64 v[154:155], v[154:155], 0, v[158:159]
	s_mov_b32 m0, s74
	s_nop 0
	global_load_lds_dwordx4 v[154:155], off
	s_waitcnt lgkmcnt(8)
	s_barrier
	s_waitcnt lgkmcnt(0)
	v_mfma_f32_16x16x32_bf16 v[124:127], v[136:139], v[172:175], v[124:127]
	v_mfma_f32_16x16x32_bf16 v[120:123], v[144:147], v[172:175], v[120:123]
	v_mfma_f32_16x16x32_bf16 v[108:111], v[136:139], v[180:183], v[108:111]
	v_mfma_f32_16x16x32_bf16 v[104:107], v[144:147], v[180:183], v[104:107]
	v_mfma_f32_16x16x32_bf16 v[92:95], v[136:139], v[190:193], v[92:95]
	v_mfma_f32_16x16x32_bf16 v[88:91], v[144:147], v[190:193], v[88:91]
	v_mfma_f32_16x16x32_bf16 v[76:79], v[136:139], v[198:201], v[76:79]
	v_mfma_f32_16x16x32_bf16 v[72:75], v[144:147], v[198:201], v[72:75]
	v_mfma_f32_16x16x32_bf16 v[124:127], v[140:143], v[176:179], v[124:127]
	v_mfma_f32_16x16x32_bf16 v[120:123], v[148:151], v[176:179], v[120:123]
	v_mfma_f32_16x16x32_bf16 v[108:111], v[140:143], v[186:189], v[108:111]
	v_mfma_f32_16x16x32_bf16 v[104:107], v[148:151], v[186:189], v[104:107]
	v_mfma_f32_16x16x32_bf16 v[92:95], v[140:143], v[194:197], v[92:95]
	v_mfma_f32_16x16x32_bf16 v[88:91], v[148:151], v[194:197], v[88:91]
	v_mfma_f32_16x16x32_bf16 v[76:79], v[140:143], v[202:205], v[76:79]
	v_mfma_f32_16x16x32_bf16 v[72:75], v[148:151], v[202:205], v[72:75]
	s_barrier
	s_add_i32 s10, 0, 0x1c000
	s_add_i32 s8, s8, s71
	v_add_u32_e32 v152, s10, v184
	v_lshl_add_u64 v[154:155], v[214:215], 0, s[54:55]
	s_mov_b32 m0, s8
	ds_read_b128 v[226:229], v152
	ds_read_b128 v[230:233], v152 offset:1024
	ds_read_b128 v[234:237], v152 offset:2048
	ds_read_b128 v[238:241], v152 offset:3072
	global_load_lds_dwordx4 v[154:155], off
	v_lshl_add_u64 v[154:155], v[216:217], 0, s[54:55]
	s_add_i32 m0, s8, 0x2000
	s_nop 0
	global_load_lds_dwordx4 v[154:155], off
	s_barrier
	s_waitcnt lgkmcnt(0)
	v_mfma_f32_16x16x32_bf16 v[116:119], v[226:229], v[172:175], v[116:119]
	v_mfma_f32_16x16x32_bf16 v[112:115], v[234:237], v[172:175], v[112:115]
	v_mfma_f32_16x16x32_bf16 v[100:103], v[226:229], v[180:183], v[100:103]
	v_mfma_f32_16x16x32_bf16 v[96:99], v[234:237], v[180:183], v[96:99]
	v_mfma_f32_16x16x32_bf16 v[84:87], v[226:229], v[190:193], v[84:87]
	v_mfma_f32_16x16x32_bf16 v[80:83], v[234:237], v[190:193], v[80:83]
	v_mfma_f32_16x16x32_bf16 v[68:71], v[226:229], v[198:201], v[68:71]
	v_mfma_f32_16x16x32_bf16 v[64:67], v[234:237], v[198:201], v[64:67]
	v_mfma_f32_16x16x32_bf16 v[116:119], v[230:233], v[176:179], v[116:119]
	v_mfma_f32_16x16x32_bf16 v[112:115], v[238:241], v[176:179], v[112:115]
	v_mfma_f32_16x16x32_bf16 v[100:103], v[230:233], v[186:189], v[100:103]
	v_mfma_f32_16x16x32_bf16 v[96:99], v[238:241], v[186:189], v[96:99]
	v_mfma_f32_16x16x32_bf16 v[84:87], v[230:233], v[194:197], v[84:87]
	v_mfma_f32_16x16x32_bf16 v[80:83], v[238:241], v[194:197], v[80:83]
	v_mfma_f32_16x16x32_bf16 v[68:71], v[230:233], v[202:205], v[68:71]
	v_mfma_f32_16x16x32_bf16 v[64:67], v[238:241], v[202:205], v[64:67]
	s_mov_b32 m0, s4
	v_lshl_add_u64 v[154:155], v[218:219], 0, s[54:55]
	s_barrier
	ds_read_b128 v[172:175], v185 offset:49152
	ds_read_b128 v[176:179], v185 offset:50176
	ds_read_b128 v[180:183], v185 offset:51200
	ds_read_b128 v[186:189], v185 offset:52224
	ds_read_b128 v[190:193], v185 offset:53248
	ds_read_b128 v[194:197], v185 offset:54272
	ds_read_b128 v[198:201], v185 offset:55296
	ds_read_b128 v[202:205], v185 offset:56320
	global_load_lds_dwordx4 v[154:155], off
	v_lshl_add_u64 v[154:155], v[220:221], 0, s[54:55]
	s_mov_b32 m0, s5
	s_nop 0
	global_load_lds_dwordx4 v[154:155], off
	s_barrier
	s_waitcnt lgkmcnt(0)
	v_mfma_f32_16x16x32_bf16 v[60:63], v[136:139], v[172:175], v[60:63]
	v_mfma_f32_16x16x32_bf16 v[56:59], v[144:147], v[172:175], v[56:59]
	v_mfma_f32_16x16x32_bf16 v[44:47], v[136:139], v[180:183], v[44:47]
	v_mfma_f32_16x16x32_bf16 v[40:43], v[144:147], v[180:183], v[40:43]
	v_mfma_f32_16x16x32_bf16 v[28:31], v[136:139], v[190:193], v[28:31]
	v_mfma_f32_16x16x32_bf16 v[24:27], v[144:147], v[190:193], v[24:27]
	v_mfma_f32_16x16x32_bf16 v[12:15], v[136:139], v[198:201], v[12:15]
	v_mfma_f32_16x16x32_bf16 v[8:11], v[144:147], v[198:201], v[8:11]
	v_mfma_f32_16x16x32_bf16 v[60:63], v[140:143], v[176:179], v[60:63]
	v_mfma_f32_16x16x32_bf16 v[56:59], v[148:151], v[176:179], v[56:59]
	v_mfma_f32_16x16x32_bf16 v[44:47], v[140:143], v[186:189], v[44:47]
	v_mfma_f32_16x16x32_bf16 v[40:43], v[148:151], v[186:189], v[40:43]
	v_mfma_f32_16x16x32_bf16 v[28:31], v[140:143], v[194:197], v[28:31]
	v_mfma_f32_16x16x32_bf16 v[24:27], v[148:151], v[194:197], v[24:27]
	v_mfma_f32_16x16x32_bf16 v[12:15], v[140:143], v[202:205], v[12:15]
	v_mfma_f32_16x16x32_bf16 v[8:11], v[148:151], v[202:205], v[8:11]
	s_barrier
	s_add_i32 s8, s10, s71
	v_lshl_add_u64 v[136:137], v[210:211], 0, s[54:55]
	s_mov_b32 m0, s8
	s_nop 0
	global_load_lds_dwordx4 v[136:137], off
	v_lshl_add_u64 v[136:137], v[224:225], 0, s[54:55]
	s_add_i32 m0, s8, 0x2000
	s_nop 0
	global_load_lds_dwordx4 v[136:137], off
	s_waitcnt vmcnt(6)
	s_barrier
	v_mfma_f32_16x16x32_bf16 v[52:55], v[226:229], v[172:175], v[52:55]
	v_mfma_f32_16x16x32_bf16 v[48:51], v[234:237], v[172:175], v[48:51]
	v_mfma_f32_16x16x32_bf16 v[36:39], v[226:229], v[180:183], v[36:39]
	v_mfma_f32_16x16x32_bf16 v[32:35], v[234:237], v[180:183], v[32:35]
	v_mfma_f32_16x16x32_bf16 v[20:23], v[226:229], v[190:193], v[20:23]
	v_mfma_f32_16x16x32_bf16 v[16:19], v[234:237], v[190:193], v[16:19]
	v_mfma_f32_16x16x32_bf16 v[4:7], v[226:229], v[198:201], v[4:7]
	v_mfma_f32_16x16x32_bf16 v[0:3], v[234:237], v[198:201], v[0:3]
	v_mfma_f32_16x16x32_bf16 v[52:55], v[230:233], v[176:179], v[52:55]
	v_mfma_f32_16x16x32_bf16 v[48:51], v[238:241], v[176:179], v[48:51]
	v_mfma_f32_16x16x32_bf16 v[36:39], v[230:233], v[186:189], v[36:39]
	v_mfma_f32_16x16x32_bf16 v[32:35], v[238:241], v[186:189], v[32:35]
	v_mfma_f32_16x16x32_bf16 v[20:23], v[230:233], v[194:197], v[20:23]
	v_mfma_f32_16x16x32_bf16 v[16:19], v[238:241], v[194:197], v[16:19]
	v_mfma_f32_16x16x32_bf16 v[4:7], v[230:233], v[202:205], v[4:7]
	v_mfma_f32_16x16x32_bf16 v[0:3], v[238:241], v[202:205], v[0:3]
	v_lshl_add_u64 v[128:129], v[128:129], 0, s[52:53]
	v_lshl_add_u64 v[130:131], v[130:131], 0, s[52:53]
	s_cmp_ge_i32 s9, s12
	s_mov_b32 s8, s9
	s_barrier
	s_cbranch_scc0 .LBB0_588
	s_setprio 0
	v_mov_b32_e32 v191, v206
	s_lshl_b32 s40, s27, 8
	v_readfirstlane_b32 s2, v191
	s_ashr_i32 s26, s2, 2
	s_bfe_u32 s89, s2, 0x20006
	v_bfe_u32 v188, v191, 4, 2
	s_andn2_b32 s26, s26, 63
	v_and_b32_e32 v189, 15, v191
	s_add_i32 s86, s26, s40
	s_lshl_b32 s41, s89, 5
	v_lshlrev_b32_e32 v190, 2, v188
	v_or_b32_e32 v172, s86, v189
	v_or_b32_e32 v187, s41, v190
	v_lshl_or_b32 v186, v188, 3, s41
	s_cmp_lt_i32 s93, 3
	s_mov_b64 s[8:9], -1
	s_cbranch_scc1 .LBB0_1004
	s_cmp_lt_i32 s93, 4
	s_cbranch_scc1 .LBB0_906
	s_cmp_lt_i32 s93, 6
	s_cbranch_scc1 .LBB0_731
	s_cmp_lt_i32 s93, 9
	s_cbranch_scc0 .LBB0_730
	s_cmp_eq_u32 s93, 7
	s_movk_i32 s2, 0x800
	s_cselect_b32 s2, 0x400, s2
	s_cmp_lg_u32 s93, 6
	s_cselect_b32 s2, s2, 0
	v_lshl_or_b32 v174, s14, 8, v186
	v_mov_b64_e32 v[128:129], s[44:45]
	s_movk_i32 s8, 0x1800
	v_mad_i64_i32 v[128:129], s[8:9], v172, s8, v[128:129]
	s_lshl_b32 s2, s2, 1
	v_ashrrev_i32_e32 v175, 31, v174
	v_lshl_add_u64 v[128:129], v[128:129], 0, s[2:3]
	v_lshlrev_b64 v[176:177], 1, v[174:175]
	v_lshl_add_u64 v[128:129], v[128:129], 0, v[176:177]
	v_mov_b64_e32 v[214:215], v[128:129]
	global_load_dwordx4 v[140:143], v[128:129], off
	v_ashrrev_i32_e32 v173, 31, v172
	v_readlane_b32 s8, v254, 43
	v_lshlrev_b64 v[178:179], 11, v[172:173]
	v_readlane_b32 s9, v254, 44
	s_cmp_eq_u32 s93, 8
	s_cselect_b64 s[10:11], -1, 0
	v_lshl_add_u64 v[130:131], s[8:9], 0, v[178:179]
	s_cmp_lg_u32 s93, 8
	v_lshl_add_u64 v[144:145], v[130:131], 0, v[176:177]
	v_mov_b64_e32 v[216:217], v[144:145]
	s_cbranch_scc1 .LBB0_595
	global_load_dwordx4 v[132:135], v[144:145], off
.LBB0_595:
	global_load_dwordx4 v[136:139], v[128:129], off offset:256
	v_cndmask_b32_e64 v128, 0, 1, s[10:11]
	v_cmp_ne_u32_e64 s[8:9], 1, v128
	s_andn2_b64 vcc, exec, s[10:11]
	s_cbranch_vccnz .LBB0_597
	global_load_dwordx4 v[128:131], v[144:145], off offset:256

.Lbrp_skip_0:
	s_waitcnt vmcnt(0) lgkmcnt(0)
	v_lshlrev_b32_e32 v146, 16, v140
	v_and_b32_e32 v147, 0xffff0000, v140
	v_lshlrev_b32_e32 v140, 16, v141
	v_and_b32_e32 v141, 0xffff0000, v141
	v_lshlrev_b32_e32 v148, 16, v142
	v_and_b32_e32 v149, 0xffff0000, v142
	v_lshlrev_b32_e32 v150, 16, v143
	v_and_b32_e32 v151, 0xffff0000, v143
	v_lshlrev_b64 v[180:181], 12, v[172:173]
	v_pk_mul_f32 v[140:141], v[126:127], v[140:141]
	v_pk_mul_f32 v[142:143], v[124:125], v[146:147]
	v_pk_mul_f32 v[146:147], v[122:123], v[150:151]
	v_pk_mul_f32 v[148:149], v[120:121], v[148:149]
	s_cmp_lt_i32 s93, 7
	s_mov_b64 s[10:11], -1
	s_cbranch_scc1 .LBB0_603
	s_cmp_lg_u32 s93, 7
	s_cbranch_scc0 .LBB0_600
	v_lshlrev_b32_e32 v150, 16, v132
	v_and_b32_e32 v151, 0xffff0000, v132
	v_pk_add_f32 v[150:151], v[142:143], v[150:151]
	v_lshlrev_b32_e32 v192, 16, v135
	v_and_b32_e32 v193, 0xffff0000, v135
	v_pk_add_f32 v[196:197], v[146:147], v[192:193]
	v_cvt_pk_bf16_f32 v192, v150, v151
	v_lshl_add_u64 v[150:151], s[18:19], 0, v[180:181]
	v_lshlrev_b32_e32 v154, 16, v133
	v_and_b32_e32 v155, 0xffff0000, v133
	v_lshlrev_b32_e32 v182, 16, v134
	v_and_b32_e32 v183, 0xffff0000, v134
	v_lshl_add_u64 v[150:151], v[174:175], 1, v[150:151]
	v_pk_add_f32 v[154:155], v[140:141], v[154:155]
	v_pk_add_f32 v[182:183], v[148:149], v[182:183]
	v_add_co_u32_e32 v150, vcc, 0xbf00000, v150
	v_cvt_pk_bf16_f32 v193, v154, v155
	v_cvt_pk_bf16_f32 v194, v182, v183
	v_cvt_pk_bf16_f32 v195, v196, v197
	v_addc_co_u32_e32 v151, vcc, 0, v151, vcc
	global_store_dwordx4 v[150:151], v[192:195], off offset:2048
	s_mov_b64 s[10:11], 0
.LBB0_600:
	s_andn2_b64 vcc, exec, s[10:11]
	s_cbranch_vccnz .LBB0_602
	v_readlane_b32 s10, v254, 35
	v_readlane_b32 s11, v254, 36
	v_cvt_pk_bf16_f32 v192, v142, v143
	v_cvt_pk_bf16_f32 v193, v140, v141
	v_lshl_add_u64 v[150:151], s[10:11], 0, v[180:181]
	v_cvt_pk_bf16_f32 v194, v148, v149
	v_cvt_pk_bf16_f32 v195, v146, v147
	v_lshl_add_u64 v[150:151], v[174:175], 1, v[150:151]
	global_store_dwordx4 v[150:151], v[192:195], off

.LBB0_603:
	s_andn2_b64 vcc, exec, s[10:11]
	s_cbranch_vccnz .LBB0_605
	v_cvt_pk_bf16_f32 v192, v142, v143
	v_cvt_pk_bf16_f32 v193, v140, v141
	v_cvt_pk_bf16_f32 v194, v148, v149
	v_cvt_pk_bf16_f32 v195, v146, v147
	global_store_dwordx4 v[144:145], v[192:195], off

.LBB0_610:
	v_lshl_add_u64 v[140:141], s[18:19], 0, v[180:181]
	v_lshl_add_u64 v[140:141], v[140:141], 0, v[182:183]
	v_cvt_pk_bf16_f32 v136, v144, v145
	v_cvt_pk_bf16_f32 v137, v146, v147
	v_cvt_pk_bf16_f32 v138, v148, v149
	v_cvt_pk_bf16_f32 v139, v150, v151
	v_lshl_add_u64 v[140:141], v[140:141], 0, v[176:177]
	global_store_dwordx4 v[140:141], v[136:139], off offset:256
	v_or_b32_e32 v146, 16, v172
	s_movk_i32 s10, 0x1800
	v_mov_b64_e32 v[136:137], s[44:45]
	v_mad_i64_i32 v[136:137], s[10:11], v146, s10, v[136:137]
	v_lshl_add_u64 v[136:137], v[136:137], 0, s[2:3]
	v_lshl_add_u64 v[136:137], v[136:137], 0, v[176:177]
	v_ashrrev_i32_e32 v147, 31, v146
	v_readlane_b32 s10, v254, 43
	v_lshlrev_b64 v[178:179], 11, v[146:147]
	v_readlane_b32 s11, v254, 44
	s_and_b64 vcc, exec, s[8:9]
	s_nop 0
	v_lshl_add_u64 v[138:139], s[10:11], 0, v[178:179]
	v_lshl_add_u64 v[144:145], v[138:139], 0, v[176:177]
	s_cbranch_vccnz .LBB0_612

.LBB0_614:
	v_lshlrev_b64 v[180:181], 12, v[146:147]
	v_mov_b64_e32 v[140:141], v[226:227]
	v_mov_b64_e32 v[142:143], v[228:229]
	v_mov_b64_e32 v[136:137], v[230:231]
	v_mov_b64_e32 v[138:139], v[232:233]
	v_mov_b64_e32 v[132:133], v[234:235]
	v_mov_b64_e32 v[134:135], v[236:237]
	v_mov_b64_e32 v[128:129], v[238:239]
	v_mov_b64_e32 v[130:131], v[240:241]
	v_lshlrev_b32_e32 v146, 16, v140
	v_and_b32_e32 v147, 0xffff0000, v140
	v_lshlrev_b32_e32 v140, 16, v141
	v_and_b32_e32 v141, 0xffff0000, v141
	v_lshlrev_b32_e32 v148, 16, v142
	v_and_b32_e32 v149, 0xffff0000, v142
	v_lshlrev_b32_e32 v150, 16, v143
	v_and_b32_e32 v151, 0xffff0000, v143
	v_pk_mul_f32 v[140:141], v[110:111], v[140:141]
	v_pk_mul_f32 v[142:143], v[108:109], v[146:147]
	v_pk_mul_f32 v[146:147], v[106:107], v[150:151]
	v_pk_mul_f32 v[148:149], v[104:105], v[148:149]
	s_cmp_lt_i32 s93, 7
	s_mov_b64 s[10:11], -1
	s_cbranch_scc1 .LBB0_620
	s_cmp_lg_u32 s93, 7
	s_cbranch_scc0 .LBB0_617
	v_lshlrev_b32_e32 v150, 16, v132
	v_and_b32_e32 v151, 0xffff0000, v132
	v_pk_add_f32 v[150:151], v[142:143], v[150:151]
	v_lshlrev_b32_e32 v192, 16, v135
	v_and_b32_e32 v193, 0xffff0000, v135
	v_pk_add_f32 v[196:197], v[146:147], v[192:193]
	v_cvt_pk_bf16_f32 v192, v150, v151
	v_lshl_add_u64 v[150:151], s[18:19], 0, v[180:181]
	v_lshlrev_b32_e32 v154, 16, v133
	v_and_b32_e32 v155, 0xffff0000, v133
	v_lshlrev_b32_e32 v182, 16, v134
	v_and_b32_e32 v183, 0xffff0000, v134
	v_lshl_add_u64 v[150:151], v[174:175], 1, v[150:151]
	v_pk_add_f32 v[154:155], v[140:141], v[154:155]
	v_pk_add_f32 v[182:183], v[148:149], v[182:183]
	v_add_co_u32_e32 v150, vcc, 0xbf00000, v150
	v_cvt_pk_bf16_f32 v193, v154, v155
	v_cvt_pk_bf16_f32 v194, v182, v183
	v_cvt_pk_bf16_f32 v195, v196, v197
	v_addc_co_u32_e32 v151, vcc, 0, v151, vcc
	global_store_dwordx4 v[150:151], v[192:195], off offset:2048
	s_mov_b64 s[10:11], 0

.LBB0_627:
	v_lshl_add_u64 v[140:141], s[18:19], 0, v[180:181]
	v_lshl_add_u64 v[140:141], v[140:141], 0, v[182:183]
	v_cvt_pk_bf16_f32 v136, v144, v145
	v_cvt_pk_bf16_f32 v137, v146, v147
	v_cvt_pk_bf16_f32 v138, v148, v149
	v_cvt_pk_bf16_f32 v139, v150, v151
	v_lshl_add_u64 v[140:141], v[140:141], 0, v[176:177]
	global_store_dwordx4 v[140:141], v[136:139], off offset:256
	v_or_b32_e32 v146, 32, v172
	s_movk_i32 s10, 0x1800
	v_mov_b64_e32 v[136:137], s[44:45]
	v_mad_i64_i32 v[136:137], s[10:11], v146, s10, v[136:137]
	v_lshl_add_u64 v[136:137], v[136:137], 0, s[2:3]
	v_lshl_add_u64 v[136:137], v[136:137], 0, v[176:177]
	global_load_dwordx4 v[140:143], v[136:137], off
	v_ashrrev_i32_e32 v147, 31, v146
	v_readlane_b32 s10, v254, 43
	v_lshlrev_b64 v[178:179], 11, v[146:147]
	v_readlane_b32 s11, v254, 44
	s_and_b64 vcc, exec, s[8:9]
	s_nop 0
	v_lshl_add_u64 v[138:139], s[10:11], 0, v[178:179]
	v_lshl_add_u64 v[144:145], v[138:139], 0, v[176:177]
	s_cbranch_vccnz .LBB0_629
	global_load_dwordx4 v[132:135], v[144:145], off
.LBB0_629:
	s_nop 0
	global_load_dwordx4 v[136:139], v[136:137], off offset:256
	s_and_b64 vcc, exec, s[8:9]
	s_cbranch_vccnz .LBB0_631
	global_load_dwordx4 v[128:131], v[144:145], off offset:256

.Lbrp_skip_2:
	s_waitcnt vmcnt(0) lgkmcnt(0)
	v_lshlrev_b32_e32 v146, 16, v140
	v_and_b32_e32 v147, 0xffff0000, v140
	v_lshlrev_b32_e32 v140, 16, v141
	v_and_b32_e32 v141, 0xffff0000, v141
	v_lshlrev_b32_e32 v148, 16, v142
	v_and_b32_e32 v149, 0xffff0000, v142
	v_lshlrev_b32_e32 v150, 16, v143
	v_and_b32_e32 v151, 0xffff0000, v143
	v_pk_mul_f32 v[140:141], v[94:95], v[140:141]
	v_pk_mul_f32 v[142:143], v[92:93], v[146:147]
	v_pk_mul_f32 v[146:147], v[90:91], v[150:151]
	v_pk_mul_f32 v[148:149], v[88:89], v[148:149]
	s_cmp_lt_i32 s93, 7
	s_mov_b64 s[10:11], -1
	s_cbranch_scc1 .LBB0_637
	s_cmp_lg_u32 s93, 7
	s_cbranch_scc0 .LBB0_634
	v_lshlrev_b32_e32 v150, 16, v132
	v_and_b32_e32 v151, 0xffff0000, v132
	v_pk_add_f32 v[150:151], v[142:143], v[150:151]
	v_lshlrev_b32_e32 v192, 16, v135
	v_and_b32_e32 v193, 0xffff0000, v135
	v_pk_add_f32 v[196:197], v[146:147], v[192:193]
	v_cvt_pk_bf16_f32 v192, v150, v151
	v_lshl_add_u64 v[150:151], s[18:19], 0, v[180:181]
	v_lshlrev_b32_e32 v154, 16, v133
	v_and_b32_e32 v155, 0xffff0000, v133
	v_lshlrev_b32_e32 v182, 16, v134
	v_and_b32_e32 v183, 0xffff0000, v134
	v_lshl_add_u64 v[150:151], v[174:175], 1, v[150:151]
	v_pk_add_f32 v[154:155], v[140:141], v[154:155]
	v_pk_add_f32 v[182:183], v[148:149], v[182:183]
	v_add_co_u32_e32 v150, vcc, 0xbf00000, v150
	v_cvt_pk_bf16_f32 v193, v154, v155
	v_cvt_pk_bf16_f32 v194, v182, v183
	v_cvt_pk_bf16_f32 v195, v196, v197
	v_addc_co_u32_e32 v151, vcc, 0, v151, vcc
	global_store_dwordx4 v[150:151], v[192:195], off offset:2048
	s_mov_b64 s[10:11], 0

.LBB0_644:
	v_lshl_add_u64 v[140:141], s[18:19], 0, v[180:181]
	v_lshl_add_u64 v[140:141], v[140:141], 0, v[182:183]
	v_cvt_pk_bf16_f32 v136, v144, v145
	v_cvt_pk_bf16_f32 v137, v146, v147
	v_cvt_pk_bf16_f32 v138, v148, v149
	v_cvt_pk_bf16_f32 v139, v150, v151
	v_lshl_add_u64 v[140:141], v[140:141], 0, v[176:177]
	global_store_dwordx4 v[140:141], v[136:139], off offset:256
	v_or_b32_e32 v146, 48, v172
	s_movk_i32 s10, 0x1800
	v_mov_b64_e32 v[136:137], s[44:45]
	v_mad_i64_i32 v[136:137], s[10:11], v146, s10, v[136:137]
	v_lshl_add_u64 v[136:137], v[136:137], 0, s[2:3]
	v_lshl_add_u64 v[136:137], v[136:137], 0, v[176:177]
	v_ashrrev_i32_e32 v147, 31, v146
	v_readlane_b32 s10, v254, 43
	v_lshlrev_b64 v[178:179], 11, v[146:147]
	v_readlane_b32 s11, v254, 44
	s_and_b64 vcc, exec, s[8:9]
	s_nop 0
	v_lshl_add_u64 v[138:139], s[10:11], 0, v[178:179]
	v_lshl_add_u64 v[144:145], v[138:139], 0, v[176:177]
	s_cbranch_vccnz .LBB0_646

.LBB0_648:
	v_lshlrev_b64 v[180:181], 12, v[146:147]
	v_mov_b64_e32 v[140:141], v[226:227]
	v_mov_b64_e32 v[142:143], v[228:229]
	v_mov_b64_e32 v[136:137], v[230:231]
	v_mov_b64_e32 v[138:139], v[232:233]
	v_mov_b64_e32 v[132:133], v[234:235]
	v_mov_b64_e32 v[134:135], v[236:237]
	v_mov_b64_e32 v[128:129], v[238:239]
	v_mov_b64_e32 v[130:131], v[240:241]
	v_lshlrev_b32_e32 v146, 16, v140
	v_and_b32_e32 v147, 0xffff0000, v140
	v_lshlrev_b32_e32 v140, 16, v141
	v_and_b32_e32 v141, 0xffff0000, v141
	v_lshlrev_b32_e32 v148, 16, v142
	v_and_b32_e32 v149, 0xffff0000, v142
	v_lshlrev_b32_e32 v150, 16, v143
	v_and_b32_e32 v151, 0xffff0000, v143
	v_pk_mul_f32 v[140:141], v[78:79], v[140:141]
	v_pk_mul_f32 v[142:143], v[76:77], v[146:147]
	v_pk_mul_f32 v[146:147], v[74:75], v[150:151]
	v_pk_mul_f32 v[148:149], v[72:73], v[148:149]
	s_cmp_lt_i32 s93, 7
	s_mov_b64 s[10:11], -1
	s_cbranch_scc1 .LBB0_654
	s_cmp_lg_u32 s93, 7
	s_cbranch_scc0 .LBB0_651
	v_lshlrev_b32_e32 v150, 16, v132
	v_and_b32_e32 v151, 0xffff0000, v132
	v_pk_add_f32 v[150:151], v[142:143], v[150:151]
	v_lshlrev_b32_e32 v192, 16, v135
	v_and_b32_e32 v193, 0xffff0000, v135
	v_pk_add_f32 v[196:197], v[146:147], v[192:193]
	v_cvt_pk_bf16_f32 v192, v150, v151
	v_lshl_add_u64 v[150:151], s[18:19], 0, v[180:181]
	v_lshlrev_b32_e32 v154, 16, v133
	v_and_b32_e32 v155, 0xffff0000, v133
	v_lshlrev_b32_e32 v182, 16, v134
	v_and_b32_e32 v183, 0xffff0000, v134
	v_lshl_add_u64 v[150:151], v[174:175], 1, v[150:151]
	v_pk_add_f32 v[154:155], v[140:141], v[154:155]
	v_pk_add_f32 v[182:183], v[148:149], v[182:183]
	v_add_co_u32_e32 v150, vcc, 0xbf00000, v150
	v_cvt_pk_bf16_f32 v193, v154, v155
	v_cvt_pk_bf16_f32 v194, v182, v183
	v_cvt_pk_bf16_f32 v195, v196, v197
	v_addc_co_u32_e32 v151, vcc, 0, v151, vcc
	global_store_dwordx4 v[150:151], v[192:195], off offset:2048
	s_mov_b64 s[10:11], 0

.LBB0_661:
	v_lshl_add_u64 v[140:141], s[18:19], 0, v[180:181]
	v_lshl_add_u64 v[140:141], v[140:141], 0, v[182:183]
	v_cvt_pk_bf16_f32 v136, v144, v145
	v_cvt_pk_bf16_f32 v137, v146, v147
	v_cvt_pk_bf16_f32 v138, v148, v149
	v_cvt_pk_bf16_f32 v139, v150, v151
	v_lshl_add_u64 v[140:141], v[140:141], 0, v[176:177]
	global_store_dwordx4 v[140:141], v[136:139], off offset:256
	v_add_u32_e32 v146, 0x80, v172
	s_movk_i32 s10, 0x1800
	v_mov_b64_e32 v[136:137], s[44:45]
	v_mad_i64_i32 v[136:137], s[10:11], v146, s10, v[136:137]
	v_lshl_add_u64 v[136:137], v[136:137], 0, s[2:3]
	v_lshl_add_u64 v[136:137], v[136:137], 0, v[176:177]
	global_load_dwordx4 v[140:143], v[136:137], off
	v_ashrrev_i32_e32 v147, 31, v146
	v_readlane_b32 s10, v254, 43
	v_lshlrev_b64 v[178:179], 11, v[146:147]
	v_readlane_b32 s11, v254, 44
	s_and_b64 vcc, exec, s[8:9]
	s_nop 0
	v_lshl_add_u64 v[138:139], s[10:11], 0, v[178:179]
	v_lshl_add_u64 v[144:145], v[138:139], 0, v[176:177]
	s_cbranch_vccnz .LBB0_663
	global_load_dwordx4 v[132:135], v[144:145], off

.Lbrp_skip_4:
	s_waitcnt vmcnt(0) lgkmcnt(0)
	v_lshlrev_b32_e32 v146, 16, v140
	v_and_b32_e32 v147, 0xffff0000, v140
	v_lshlrev_b32_e32 v140, 16, v141
	v_and_b32_e32 v141, 0xffff0000, v141
	v_lshlrev_b32_e32 v148, 16, v142
	v_and_b32_e32 v149, 0xffff0000, v142
	v_lshlrev_b32_e32 v150, 16, v143
	v_and_b32_e32 v151, 0xffff0000, v143
	v_pk_mul_f32 v[140:141], v[62:63], v[140:141]
	v_pk_mul_f32 v[142:143], v[60:61], v[146:147]
	v_pk_mul_f32 v[146:147], v[58:59], v[150:151]
	v_pk_mul_f32 v[148:149], v[56:57], v[148:149]
	s_cmp_lt_i32 s93, 7
	s_mov_b64 s[10:11], -1
	s_cbranch_scc1 .LBB0_671
	s_cmp_lg_u32 s93, 7
	s_cbranch_scc0 .LBB0_668
	v_lshlrev_b32_e32 v150, 16, v132
	v_and_b32_e32 v151, 0xffff0000, v132
	v_pk_add_f32 v[150:151], v[142:143], v[150:151]
	v_lshlrev_b32_e32 v192, 16, v135
	v_and_b32_e32 v193, 0xffff0000, v135
	v_pk_add_f32 v[196:197], v[146:147], v[192:193]
	v_cvt_pk_bf16_f32 v192, v150, v151
	v_lshl_add_u64 v[150:151], s[18:19], 0, v[180:181]
	v_lshlrev_b32_e32 v154, 16, v133
	v_and_b32_e32 v155, 0xffff0000, v133
	v_lshlrev_b32_e32 v182, 16, v134
	v_and_b32_e32 v183, 0xffff0000, v134
	v_lshl_add_u64 v[150:151], v[174:175], 1, v[150:151]
	v_pk_add_f32 v[154:155], v[140:141], v[154:155]
	v_pk_add_f32 v[182:183], v[148:149], v[182:183]
	v_add_co_u32_e32 v150, vcc, 0xbf00000, v150
	v_cvt_pk_bf16_f32 v193, v154, v155
	v_cvt_pk_bf16_f32 v194, v182, v183
	v_cvt_pk_bf16_f32 v195, v196, v197
	v_addc_co_u32_e32 v151, vcc, 0, v151, vcc
	global_store_dwordx4 v[150:151], v[192:195], off offset:2048
	s_mov_b64 s[10:11], 0

.LBB0_678:
	v_lshl_add_u64 v[140:141], s[18:19], 0, v[180:181]
	v_lshl_add_u64 v[140:141], v[140:141], 0, v[182:183]
	v_cvt_pk_bf16_f32 v136, v144, v145
	v_cvt_pk_bf16_f32 v137, v146, v147
	v_cvt_pk_bf16_f32 v138, v148, v149
	v_cvt_pk_bf16_f32 v139, v150, v151
	v_lshl_add_u64 v[140:141], v[140:141], 0, v[176:177]
	global_store_dwordx4 v[140:141], v[136:139], off offset:256
	v_add_u32_e32 v146, 0x90, v172
	s_movk_i32 s10, 0x1800
	v_mov_b64_e32 v[136:137], s[44:45]
	v_mad_i64_i32 v[136:137], s[10:11], v146, s10, v[136:137]
	v_lshl_add_u64 v[136:137], v[136:137], 0, s[2:3]
	v_lshl_add_u64 v[136:137], v[136:137], 0, v[176:177]
	v_ashrrev_i32_e32 v147, 31, v146
	v_readlane_b32 s10, v254, 43
	v_lshlrev_b64 v[178:179], 11, v[146:147]
	v_readlane_b32 s11, v254, 44
	s_and_b64 vcc, exec, s[8:9]
	s_nop 0
	v_lshl_add_u64 v[138:139], s[10:11], 0, v[178:179]
	v_lshl_add_u64 v[144:145], v[138:139], 0, v[176:177]
	s_cbranch_vccnz .LBB0_680

.LBB0_682:
	v_lshlrev_b64 v[180:181], 12, v[146:147]
	v_mov_b64_e32 v[140:141], v[226:227]
	v_mov_b64_e32 v[142:143], v[228:229]
	v_mov_b64_e32 v[136:137], v[230:231]
	v_mov_b64_e32 v[138:139], v[232:233]
	v_mov_b64_e32 v[132:133], v[234:235]
	v_mov_b64_e32 v[134:135], v[236:237]
	v_mov_b64_e32 v[128:129], v[238:239]
	v_mov_b64_e32 v[130:131], v[240:241]
	v_lshlrev_b32_e32 v146, 16, v140
	v_and_b32_e32 v147, 0xffff0000, v140
	v_lshlrev_b32_e32 v140, 16, v141
	v_and_b32_e32 v141, 0xffff0000, v141
	v_lshlrev_b32_e32 v148, 16, v142
	v_and_b32_e32 v149, 0xffff0000, v142
	v_lshlrev_b32_e32 v150, 16, v143
	v_and_b32_e32 v151, 0xffff0000, v143
	v_pk_mul_f32 v[140:141], v[46:47], v[140:141]
	v_pk_mul_f32 v[142:143], v[44:45], v[146:147]
	v_pk_mul_f32 v[146:147], v[42:43], v[150:151]
	v_pk_mul_f32 v[148:149], v[40:41], v[148:149]
	s_cmp_lt_i32 s93, 7
	s_mov_b64 s[10:11], -1
	s_cbranch_scc1 .LBB0_688
	s_cmp_lg_u32 s93, 7
	s_cbranch_scc0 .LBB0_685
	v_lshlrev_b32_e32 v150, 16, v132
	v_and_b32_e32 v151, 0xffff0000, v132
	v_pk_add_f32 v[150:151], v[142:143], v[150:151]
	v_lshlrev_b32_e32 v192, 16, v135
	v_and_b32_e32 v193, 0xffff0000, v135
	v_pk_add_f32 v[196:197], v[146:147], v[192:193]
	v_cvt_pk_bf16_f32 v192, v150, v151
	v_lshl_add_u64 v[150:151], s[18:19], 0, v[180:181]
	v_lshlrev_b32_e32 v154, 16, v133
	v_and_b32_e32 v155, 0xffff0000, v133
	v_lshlrev_b32_e32 v182, 16, v134
	v_and_b32_e32 v183, 0xffff0000, v134
	v_lshl_add_u64 v[150:151], v[174:175], 1, v[150:151]
	v_pk_add_f32 v[154:155], v[140:141], v[154:155]
	v_pk_add_f32 v[182:183], v[148:149], v[182:183]
	v_add_co_u32_e32 v150, vcc, 0xbf00000, v150
	v_cvt_pk_bf16_f32 v193, v154, v155
	v_cvt_pk_bf16_f32 v194, v182, v183
	v_cvt_pk_bf16_f32 v195, v196, v197
	v_addc_co_u32_e32 v151, vcc, 0, v151, vcc
	global_store_dwordx4 v[150:151], v[192:195], off offset:2048
	s_mov_b64 s[10:11], 0

.LBB0_695:
	v_lshl_add_u64 v[140:141], s[18:19], 0, v[180:181]
	v_lshl_add_u64 v[140:141], v[140:141], 0, v[182:183]
	v_cvt_pk_bf16_f32 v136, v144, v145
	v_cvt_pk_bf16_f32 v137, v146, v147
	v_cvt_pk_bf16_f32 v138, v148, v149
	v_cvt_pk_bf16_f32 v139, v150, v151
	v_lshl_add_u64 v[140:141], v[140:141], 0, v[176:177]
	global_store_dwordx4 v[140:141], v[136:139], off offset:256
	v_add_u32_e32 v146, 0xa0, v172
	s_movk_i32 s10, 0x1800
	v_mov_b64_e32 v[136:137], s[44:45]
	v_mad_i64_i32 v[136:137], s[10:11], v146, s10, v[136:137]
	v_lshl_add_u64 v[136:137], v[136:137], 0, s[2:3]
	v_lshl_add_u64 v[136:137], v[136:137], 0, v[176:177]
	global_load_dwordx4 v[140:143], v[136:137], off
	v_ashrrev_i32_e32 v147, 31, v146
	v_readlane_b32 s10, v254, 43
	v_lshlrev_b64 v[178:179], 11, v[146:147]
	v_readlane_b32 s11, v254, 44
	s_and_b64 vcc, exec, s[8:9]
	s_nop 0
	v_lshl_add_u64 v[138:139], s[10:11], 0, v[178:179]
	v_lshl_add_u64 v[144:145], v[138:139], 0, v[176:177]
	s_cbranch_vccnz .LBB0_697
	global_load_dwordx4 v[132:135], v[144:145], off

.Lbrp_skip_6:
	s_waitcnt vmcnt(0) lgkmcnt(0)
	v_lshlrev_b32_e32 v146, 16, v140
	v_and_b32_e32 v147, 0xffff0000, v140
	v_lshlrev_b32_e32 v140, 16, v141
	v_and_b32_e32 v141, 0xffff0000, v141
	v_lshlrev_b32_e32 v148, 16, v142
	v_and_b32_e32 v149, 0xffff0000, v142
	v_lshlrev_b32_e32 v150, 16, v143
	v_and_b32_e32 v151, 0xffff0000, v143
	v_pk_mul_f32 v[140:141], v[30:31], v[140:141]
	v_pk_mul_f32 v[142:143], v[28:29], v[146:147]
	v_pk_mul_f32 v[146:147], v[26:27], v[150:151]
	v_pk_mul_f32 v[148:149], v[24:25], v[148:149]
	s_cmp_lt_i32 s93, 7
	s_mov_b64 s[10:11], -1
	s_cbranch_scc1 .LBB0_705
	s_cmp_lg_u32 s93, 7
	s_cbranch_scc0 .LBB0_702
	v_lshlrev_b32_e32 v150, 16, v132
	v_and_b32_e32 v151, 0xffff0000, v132
	v_pk_add_f32 v[150:151], v[142:143], v[150:151]
	v_lshlrev_b32_e32 v192, 16, v135
	v_and_b32_e32 v193, 0xffff0000, v135
	v_pk_add_f32 v[196:197], v[146:147], v[192:193]
	v_cvt_pk_bf16_f32 v192, v150, v151
	v_lshl_add_u64 v[150:151], s[18:19], 0, v[180:181]
	v_lshlrev_b32_e32 v154, 16, v133
	v_and_b32_e32 v155, 0xffff0000, v133
	v_lshlrev_b32_e32 v182, 16, v134
	v_and_b32_e32 v183, 0xffff0000, v134
	v_lshl_add_u64 v[150:151], v[174:175], 1, v[150:151]
	v_pk_add_f32 v[154:155], v[140:141], v[154:155]
	v_pk_add_f32 v[182:183], v[148:149], v[182:183]
	v_add_co_u32_e32 v150, vcc, 0xbf00000, v150
	v_cvt_pk_bf16_f32 v193, v154, v155
	v_cvt_pk_bf16_f32 v194, v182, v183
	v_cvt_pk_bf16_f32 v195, v196, v197
	v_addc_co_u32_e32 v151, vcc, 0, v151, vcc
	global_store_dwordx4 v[150:151], v[192:195], off offset:2048
	s_mov_b64 s[10:11], 0

.LBB0_712:
	v_lshl_add_u64 v[140:141], s[18:19], 0, v[180:181]
	v_lshl_add_u64 v[140:141], v[140:141], 0, v[182:183]
	v_cvt_pk_bf16_f32 v136, v144, v145
	v_cvt_pk_bf16_f32 v137, v146, v147
	v_cvt_pk_bf16_f32 v138, v148, v149
	v_cvt_pk_bf16_f32 v139, v150, v151
	v_lshl_add_u64 v[140:141], v[140:141], 0, v[176:177]
	global_store_dwordx4 v[140:141], v[136:139], off offset:256
	v_add_u32_e32 v146, 0xb0, v172
	s_movk_i32 s10, 0x1800
	v_mov_b64_e32 v[136:137], s[44:45]
	v_mad_i64_i32 v[136:137], s[10:11], v146, s10, v[136:137]
	v_lshl_add_u64 v[136:137], v[136:137], 0, s[2:3]
	v_lshl_add_u64 v[136:137], v[136:137], 0, v[176:177]
	v_ashrrev_i32_e32 v147, 31, v146
	v_readlane_b32 s10, v254, 43
	v_lshlrev_b64 v[148:149], 11, v[146:147]
	v_readlane_b32 s11, v254, 44
	s_and_b64 vcc, exec, s[8:9]
	s_nop 0
	v_lshl_add_u64 v[138:139], s[10:11], 0, v[148:149]
	v_lshl_add_u64 v[144:145], v[138:139], 0, v[176:177]
	s_cbranch_vccnz .LBB0_714

.LBB0_716:
	v_lshlrev_b64 v[150:151], 12, v[146:147]
	v_mov_b64_e32 v[140:141], v[226:227]
	v_mov_b64_e32 v[142:143], v[228:229]
	v_mov_b64_e32 v[136:137], v[230:231]
	v_mov_b64_e32 v[138:139], v[232:233]
	v_mov_b64_e32 v[132:133], v[234:235]
	v_mov_b64_e32 v[134:135], v[236:237]
	v_mov_b64_e32 v[128:129], v[238:239]
	v_mov_b64_e32 v[130:131], v[240:241]
	v_lshlrev_b32_e32 v146, 16, v140
	v_and_b32_e32 v147, 0xffff0000, v140
	v_lshlrev_b32_e32 v140, 16, v141
	v_and_b32_e32 v141, 0xffff0000, v141
	v_lshlrev_b32_e32 v154, 16, v142
	v_and_b32_e32 v155, 0xffff0000, v142
	v_lshlrev_b32_e32 v176, 16, v143
	v_and_b32_e32 v177, 0xffff0000, v143
	v_pk_mul_f32 v[140:141], v[14:15], v[140:141]
	v_pk_mul_f32 v[142:143], v[12:13], v[146:147]
	v_pk_mul_f32 v[146:147], v[10:11], v[176:177]
	v_pk_mul_f32 v[176:177], v[8:9], v[154:155]
	s_cmp_lt_i32 s93, 7
	s_mov_b64 s[8:9], -1
	s_cbranch_scc1 .LBB0_722
	s_cmp_lg_u32 s93, 7
	s_cbranch_scc0 .LBB0_719
	v_lshlrev_b32_e32 v154, 16, v132
	v_and_b32_e32 v155, 0xffff0000, v132
	v_lshlrev_b32_e32 v132, 16, v133
	v_and_b32_e32 v133, 0xffff0000, v133
	v_pk_add_f32 v[178:179], v[140:141], v[132:133]
	v_pk_add_f32 v[132:133], v[142:143], v[154:155]
	v_lshlrev_b32_e32 v154, 16, v134
	v_and_b32_e32 v155, 0xffff0000, v134
	v_lshlrev_b32_e32 v134, 16, v135
	v_and_b32_e32 v135, 0xffff0000, v135
	v_pk_add_f32 v[180:181], v[146:147], v[134:135]
	v_pk_add_f32 v[134:135], v[176:177], v[154:155]
	v_lshl_add_u64 v[154:155], s[18:19], 0, v[150:151]
	v_lshl_add_u64 v[154:155], v[174:175], 1, v[154:155]
	v_add_co_u32_e32 v154, vcc, 0xbf00000, v154
	v_cvt_pk_bf16_f32 v132, v132, v133
	v_cvt_pk_bf16_f32 v133, v178, v179
	v_cvt_pk_bf16_f32 v134, v134, v135
	v_cvt_pk_bf16_f32 v135, v180, v181
	v_addc_co_u32_e32 v155, vcc, 0, v155, vcc
	global_store_dwordx4 v[154:155], v[132:135], off offset:2048
	s_mov_b64 s[8:9], 0
.LBB0_719:
	s_andn2_b64 vcc, exec, s[8:9]
	s_cbranch_vccnz .LBB0_721
	v_readlane_b32 s8, v254, 35
	v_readlane_b32 s9, v254, 36
	v_cvt_pk_bf16_f32 v132, v142, v143
	v_cvt_pk_bf16_f32 v133, v140, v141
	v_lshl_add_u64 v[154:155], s[8:9], 0, v[150:151]
	v_cvt_pk_bf16_f32 v134, v176, v177
	v_cvt_pk_bf16_f32 v135, v146, v147
	v_lshl_add_u64 v[154:155], v[174:175], 1, v[154:155]
	global_store_dwordx4 v[154:155], v[132:135], off

.LBB0_722:
	s_andn2_b64 vcc, exec, s[8:9]
	s_cbranch_vccnz .LBB0_724
	v_cvt_pk_bf16_f32 v132, v142, v143
	v_cvt_pk_bf16_f32 v133, v140, v141
	v_cvt_pk_bf16_f32 v134, v176, v177
	v_cvt_pk_bf16_f32 v135, v146, v147
	global_store_dwordx4 v[144:145], v[132:135], off

.LBB0_729:
	v_lshl_add_u64 v[132:133], s[18:19], 0, v[150:151]
	v_lshl_add_u64 v[132:133], v[132:133], 0, v[176:177]
	v_cvt_pk_bf16_f32 v128, v140, v141
	v_cvt_pk_bf16_f32 v129, v142, v143
	v_cvt_pk_bf16_f32 v130, v144, v145
	v_cvt_pk_bf16_f32 v131, v146, v147
	v_lshl_add_u64 v[132:133], v[174:175], 1, v[132:133]
	global_store_dwordx4 v[132:133], v[128:131], off offset:256

.LBB0_737:
	v_cndmask_b32_e64 v129, 0, 1, s[8:9]
	v_or_b32_e32 v128, s26, v189
	v_cmp_ne_u32_e64 s[10:11], 1, v129
	s_andn2_b64 vcc, exec, s[8:9]
	v_mov_b32_e32 v130, 1.0
	s_cbranch_vccnz .LBB0_742
	s_mov_b64 s[8:9], -1
	s_and_b64 vcc, exec, s[36:37]
	s_cbranch_vccz .LBB0_740
	v_add_u32_e32 v130, s40, v128
	v_readlane_b32 s8, v254, 50
	v_ashrrev_i32_e32 v131, 31, v130
	v_readlane_b32 s9, v254, 51
	s_nop 1
	v_lshl_add_u64 v[130:131], v[130:131], 4, s[8:9]
	global_load_dwordx4 v[130:133], v[130:131], off
	s_mov_b64 s[8:9], 0
	s_waitcnt vmcnt(0) lgkmcnt(0)
	v_mov_b32_e32 v134, v131
	v_mov_b32_e32 v135, v132
	v_mov_b32_e32 v131, v133
	v_pk_add_f32 v[130:131], v[134:135], v[130:131]
	s_nop 0
	v_add_f32_e32 v129, v130, v131
	v_fmamk_f32 v129, v129, 0x3b800000, v207
	v_mul_f32_e32 v130, 0x4b800000, v129
	v_cmp_gt_f32_e32 vcc, s68, v129
	s_nop 1
	v_cndmask_b32_e32 v129, v129, v130, vcc
	v_rsq_f32_e32 v129, v129
	s_nop 0
	v_mul_f32_e32 v130, 0x45800000, v129
	v_cndmask_b32_e32 v130, v129, v130, vcc

.LBB0_742:
	s_cmp_gt_u32 s89, 1
	v_add_u32_e32 v129, s41, v190
	s_mov_b64 s[90:91], s[78:79]
	s_cselect_b64 s[22:23], -1, 0
	v_subrev_u32_e32 v129, 64, v129
	s_lshl_b32 s78, s14, 7
	v_add_u32_e32 v143, s78, v129
	s_ashr_i32 s21, s20, 31
	v_add_u32_e32 v132, s64, v128
	s_waitcnt lgkmcnt(0)
	v_pk_mul_f32 v[134:135], v[126:127], v[130:131] op_sel_hi:[1,0]
	v_pk_mul_f32 v[136:137], v[124:125], v[130:131] op_sel_hi:[1,0]
	v_ashrrev_i32_e32 v131, 31, v143
	s_lshl_b64 s[66:67], s[20:21], 10
	v_ashrrev_i32_e32 v133, 31, v132
	v_cvt_pk_bf16_f32 v138, v136, v137
	v_cvt_pk_bf16_f32 v139, v134, v135
	s_mov_b64 s[8:9], -1
	s_and_b64 vcc, exec, s[22:23]
	v_mul_lo_u32 v145, s13, v143
	v_mul_lo_u32 v141, s12, v131
	s_cbranch_vccz .LBB0_744
	s_add_u32 s8, s63, s66
	v_mad_u64_u32 v[134:135], s[24:25], s12, v143, 0
	s_addc_u32 s9, s38, s67
	v_add3_u32 v135, v135, v141, v145
	v_lshl_add_u64 v[134:135], v[134:135], 1, s[8:9]
	v_lshl_add_u64 v[134:135], v[132:133], 1, v[134:135]
	s_lshl_b64 s[8:9], s[12:13], 1
	global_store_short v[134:135], v138, off
	v_lshl_add_u64 v[134:135], v[134:135], 0, s[8:9]
	global_store_short_d16_hi v[134:135], v138, off
	v_lshl_add_u64 v[134:135], v[134:135], 0, s[8:9]
	global_store_short v[134:135], v139, off
	v_lshl_add_u64 v[134:135], v[134:135], 0, s[8:9]
	global_store_short_d16_hi v[134:135], v139, off
	s_mov_b64 s[8:9], 0
.LBB0_744:
	v_add_u32_e32 v134, s20, v132
	v_ashrrev_i32_e32 v135, 31, v134
	v_lshlrev_b64 v[136:137], 10, v[134:135]
	s_ashr_i32 s79, s78, 31
	v_lshl_add_u64 v[134:135], s[96:97], 0, v[136:137]
	s_andn2_b64 vcc, exec, s[8:9]
	v_lshl_add_u64 v[134:135], s[78:79], 1, v[134:135]
	s_cbranch_vccnz .LBB0_746
	s_lshl_b32 s2, s41, 1
	v_lshl_add_u64 v[146:147], v[134:135], 0, s[2:3]
	v_lshlrev_b32_e32 v152, 1, v190
	v_lshl_add_u64 v[146:147], v[146:147], 0, v[152:153]
	global_store_dwordx2 v[146:147], v[138:139], off
.LBB0_746:
	v_mov_b32_e32 v131, v130
	v_mov_b32_e32 v138, v130
	v_mov_b32_e32 v139, v130
	v_pk_mul_f32 v[146:147], v[122:123], v[138:139]
	v_pk_mul_f32 v[138:139], v[120:121], v[130:131]
	v_cndmask_b32_e64 v140, 0, 1, s[22:23]
	v_cvt_pk_bf16_f32 v138, v138, v139
	v_cvt_pk_bf16_f32 v139, v146, v147
	v_or_b32_e32 v146, 16, v143
	s_mov_b64 s[24:25], -1
	v_cmp_ne_u32_e64 s[8:9], 1, v140
	s_andn2_b64 vcc, exec, s[22:23]
	v_mul_lo_u32 v147, s13, v146
	s_cbranch_vccnz .LBB0_748
	s_add_u32 s22, s63, s66
	v_mad_u64_u32 v[148:149], s[24:25], s12, v146, 0
	s_addc_u32 s23, s38, s67
	v_add3_u32 v149, v149, v141, v147
	v_lshl_add_u64 v[148:149], v[148:149], 1, s[22:23]
	v_lshl_add_u64 v[148:149], v[132:133], 1, v[148:149]
	s_lshl_b64 s[22:23], s[12:13], 1
	global_store_short v[148:149], v138, off
	v_lshl_add_u64 v[148:149], v[148:149], 0, s[22:23]
	global_store_short_d16_hi v[148:149], v138, off
	v_lshl_add_u64 v[148:149], v[148:149], 0, s[22:23]
	global_store_short v[148:149], v139, off
	v_lshl_add_u64 v[148:149], v[148:149], 0, s[22:23]
	s_mov_b64 s[24:25], 0
	global_store_short_d16_hi v[148:149], v139, off
.LBB0_748:
	v_lshl_add_u64 v[136:137], s[18:19], 0, v[136:137]
	s_andn2_b64 vcc, exec, s[24:25]
	v_lshl_add_u64 v[136:137], s[78:79], 1, v[136:137]
	s_cbranch_vccnz .LBB0_750
	s_lshl_b32 s2, s41, 1
	v_lshl_add_u64 v[148:149], v[136:137], 0, s[2:3]
	v_lshlrev_b32_e32 v152, 1, v190
	v_lshl_add_u64 v[148:149], v[148:149], 0, v[152:153]
	v_add_co_u32_e32 v148, vcc, 0xac00000, v148
	s_nop 1
	v_addc_co_u32_e32 v149, vcc, 0, v149, vcc
	global_store_dwordx2 v[148:149], v[138:139], off offset:32
.LBB0_750:
	v_add3_u32 v142, v129, s78, 64
	v_mov_b32_e32 v138, v130
	v_mov_b32_e32 v139, v130
	v_pk_mul_f32 v[148:149], v[118:119], v[138:139]
	v_pk_mul_f32 v[138:139], v[116:117], v[130:131]
	v_ashrrev_i32_e32 v129, 31, v142
	v_cvt_pk_bf16_f32 v138, v138, v139
	v_cvt_pk_bf16_f32 v139, v148, v149
	s_mov_b64 s[22:23], -1
	s_and_b64 vcc, exec, s[8:9]
	v_mul_lo_u32 v144, s13, v142
	v_mul_lo_u32 v140, s12, v129
	s_cbranch_vccnz .LBB0_752
	s_add_u32 s22, s63, s66
	v_mad_u64_u32 v[148:149], s[24:25], s12, v142, 0
	s_addc_u32 s23, s38, s67
	v_add3_u32 v149, v149, v140, v144
	v_lshl_add_u64 v[148:149], v[148:149], 1, s[22:23]
	v_lshl_add_u64 v[148:149], v[132:133], 1, v[148:149]
	s_lshl_b64 s[22:23], s[12:13], 1
	global_store_short v[148:149], v138, off
	v_lshl_add_u64 v[148:149], v[148:149], 0, s[22:23]
	global_store_short_d16_hi v[148:149], v138, off
	v_lshl_add_u64 v[148:149], v[148:149], 0, s[22:23]
	global_store_short v[148:149], v139, off
	v_lshl_add_u64 v[148:149], v[148:149], 0, s[22:23]
	s_mov_b64 s[22:23], 0
	global_store_short_d16_hi v[148:149], v139, off
.LBB0_752:
	s_andn2_b64 vcc, exec, s[22:23]
	s_cbranch_vccnz .LBB0_754
	s_lshl_b32 s2, s41, 1
	v_lshl_add_u64 v[134:135], v[134:135], 0, s[2:3]
	v_lshlrev_b32_e32 v152, 1, v190
	v_lshl_add_u64 v[134:135], v[134:135], 0, v[152:153]
	global_store_dwordx2 v[134:135], v[138:139], off offset:128
.LBB0_754:
	v_mov_b32_e32 v134, v130
	v_mov_b32_e32 v135, v130
	v_pk_mul_f32 v[134:135], v[114:115], v[134:135]
	v_pk_mul_f32 v[130:131], v[112:113], v[130:131]
	v_or_b32_e32 v138, 16, v142
	v_cvt_pk_bf16_f32 v130, v130, v131
	v_cvt_pk_bf16_f32 v131, v134, v135
	s_mov_b64 s[22:23], -1
	s_and_b64 vcc, exec, s[8:9]
	v_mul_lo_u32 v139, s13, v138
	s_cbranch_vccnz .LBB0_757
	s_add_u32 s22, s63, s66
	v_mad_u64_u32 v[134:135], s[24:25], s12, v138, 0
	s_addc_u32 s23, s38, s67
	v_add3_u32 v135, v135, v140, v139
	v_lshl_add_u64 v[134:135], v[134:135], 1, s[22:23]
	v_lshl_add_u64 v[132:133], v[132:133], 1, v[134:135]
	s_lshl_b64 s[22:23], s[12:13], 1
	global_store_short v[132:133], v130, off
	v_lshl_add_u64 v[132:133], v[132:133], 0, s[22:23]
	global_store_short_d16_hi v[132:133], v130, off
	v_lshl_add_u64 v[132:133], v[132:133], 0, s[22:23]
	global_store_short v[132:133], v131, off
	v_lshl_add_u64 v[132:133], v[132:133], 0, s[22:23]
	global_store_short_d16_hi v[132:133], v131, off
	s_cbranch_execz .LBB0_758

.LBB0_758:
	s_lshl_b32 s2, s41, 1
	v_lshl_add_u64 v[132:133], v[136:137], 0, s[2:3]
	v_lshlrev_b32_e32 v152, 1, v190
	v_lshl_add_u64 v[132:133], v[132:133], 0, v[152:153]
	v_add_co_u32_e32 v132, vcc, 0xac00000, v132
	s_nop 1
	v_addc_co_u32_e32 v133, vcc, 0, v133, vcc
	global_store_dwordx2 v[132:133], v[130:131], off offset:160
	v_or_b32_e32 v131, 16, v128
	s_and_b64 vcc, exec, s[10:11]
	v_mov_b32_e32 v130, 1.0
	s_cbranch_vccnz .LBB0_763
.LBB0_759:
	s_andn2_b64 vcc, exec, s[36:37]
	s_mov_b64 s[22:23], -1
	s_cbranch_vccnz .LBB0_761
	v_add_u32_e32 v132, s40, v131
	v_readlane_b32 s22, v254, 50
	v_ashrrev_i32_e32 v133, 31, v132
	v_readlane_b32 s23, v254, 51
	s_nop 1
	v_lshl_add_u64 v[132:133], v[132:133], 4, s[22:23]
	global_load_dwordx4 v[132:135], v[132:133], off
	s_mov_b64 s[22:23], 0
	s_waitcnt vmcnt(0) lgkmcnt(0)
	v_mov_b32_e32 v136, v133
	v_mov_b32_e32 v137, v134
	v_mov_b32_e32 v133, v135
	v_pk_add_f32 v[132:133], v[136:137], v[132:133]
	s_nop 0
	v_add_f32_e32 v129, v132, v133
	v_fmamk_f32 v129, v129, 0x3b800000, v207
	v_mul_f32_e32 v130, 0x4b800000, v129
	v_cmp_gt_f32_e32 vcc, s68, v129
	s_nop 1
	v_cndmask_b32_e32 v129, v129, v130, vcc
	v_rsq_f32_e32 v129, v129
	s_nop 0
	v_mul_f32_e32 v130, 0x45800000, v129
	v_cndmask_b32_e32 v130, v129, v130, vcc

.LBB0_763:
	s_waitcnt lgkmcnt(0)
	v_pk_mul_f32 v[132:133], v[110:111], v[130:131] op_sel_hi:[1,0]
	v_pk_mul_f32 v[134:135], v[108:109], v[130:131] op_sel_hi:[1,0]
	v_cvt_pk_bf16_f32 v137, v132, v133
	v_cvt_pk_bf16_f32 v136, v134, v135
	s_mov_b64 s[22:23], -1
	s_and_b64 vcc, exec, s[8:9]
	v_ashrrev_i32_e32 v129, 31, v128
	s_cbranch_vccnz .LBB0_765
	s_add_u32 s22, s63, s66
	v_mad_u64_u32 v[132:133], s[24:25], s12, v143, 0
	s_addc_u32 s23, s38, s67
	v_add3_u32 v133, v133, v141, v145
	s_ashr_i32 s65, s64, 31
	v_lshl_add_u64 v[132:133], v[132:133], 1, s[22:23]
	v_lshl_add_u64 v[134:135], s[64:65], 0, v[128:129]
	v_lshl_add_u64 v[132:133], v[134:135], 1, v[132:133]
	s_lshl_b64 s[22:23], s[12:13], 1
	global_store_short v[132:133], v136, off offset:32
	v_lshl_add_u64 v[132:133], v[132:133], 0, s[22:23]
	global_store_short_d16_hi v[132:133], v136, off offset:32
	v_lshl_add_u64 v[132:133], v[132:133], 0, s[22:23]
	global_store_short v[132:133], v137, off offset:32
	v_lshl_add_u64 v[132:133], v[132:133], 0, s[22:23]
	s_mov_b64 s[22:23], 0
	global_store_short_d16_hi v[132:133], v137, off offset:32
.LBB0_765:
	s_add_i32 s24, s20, s64
	v_add_u32_e32 v132, s24, v131
	v_ashrrev_i32_e32 v133, 31, v132
	v_lshlrev_b64 v[134:135], 10, v[132:133]
	v_lshl_add_u64 v[132:133], s[96:97], 0, v[134:135]
	s_andn2_b64 vcc, exec, s[22:23]
	v_lshl_add_u64 v[132:133], s[78:79], 1, v[132:133]
	s_cbranch_vccnz .LBB0_767
	s_lshl_b32 s2, s41, 1
	v_lshl_add_u64 v[148:149], v[132:133], 0, s[2:3]
	v_lshlrev_b32_e32 v152, 1, v190
	v_lshl_add_u64 v[148:149], v[148:149], 0, v[152:153]
	global_store_dwordx2 v[148:149], v[136:137], off
.LBB0_767:
	v_mov_b32_e32 v131, v130
	v_mov_b32_e32 v136, v130
	v_mov_b32_e32 v137, v130
	v_pk_mul_f32 v[148:149], v[106:107], v[136:137]
	v_pk_mul_f32 v[136:137], v[104:105], v[130:131]
	s_and_b64 vcc, exec, s[8:9]
	v_cvt_pk_bf16_f32 v136, v136, v137
	v_cvt_pk_bf16_f32 v137, v148, v149
	s_mov_b64 s[20:21], -1
	s_cbranch_vccnz .LBB0_769
	s_add_u32 s20, s63, s66
	v_mad_u64_u32 v[148:149], s[22:23], s12, v146, 0
	s_addc_u32 s21, s38, s67
	v_add3_u32 v149, v149, v141, v147
	s_ashr_i32 s65, s64, 31
	v_lshl_add_u64 v[148:149], v[148:149], 1, s[20:21]
	v_lshl_add_u64 v[150:151], s[64:65], 0, v[128:129]
	v_lshl_add_u64 v[148:149], v[150:151], 1, v[148:149]
	s_lshl_b64 s[20:21], s[12:13], 1
	global_store_short v[148:149], v136, off offset:32
	v_lshl_add_u64 v[148:149], v[148:149], 0, s[20:21]
	global_store_short_d16_hi v[148:149], v136, off offset:32
	v_lshl_add_u64 v[148:149], v[148:149], 0, s[20:21]
	global_store_short v[148:149], v137, off offset:32
	v_lshl_add_u64 v[148:149], v[148:149], 0, s[20:21]
	s_mov_b64 s[20:21], 0
	global_store_short_d16_hi v[148:149], v137, off offset:32
.LBB0_769:
	v_lshl_add_u64 v[134:135], s[18:19], 0, v[134:135]
	s_andn2_b64 vcc, exec, s[20:21]
	v_lshl_add_u64 v[134:135], s[78:79], 1, v[134:135]
	s_cbranch_vccnz .LBB0_771
	s_lshl_b32 s2, s41, 1
	v_lshl_add_u64 v[148:149], v[134:135], 0, s[2:3]
	v_lshlrev_b32_e32 v152, 1, v190
	v_lshl_add_u64 v[148:149], v[148:149], 0, v[152:153]
	v_add_co_u32_e32 v148, vcc, 0xac00000, v148
	s_nop 1
	v_addc_co_u32_e32 v149, vcc, 0, v149, vcc
	global_store_dwordx2 v[148:149], v[136:137], off offset:32
.LBB0_771:
	v_mov_b32_e32 v136, v130
	v_mov_b32_e32 v137, v130
	v_pk_mul_f32 v[148:149], v[102:103], v[136:137]
	v_pk_mul_f32 v[136:137], v[100:101], v[130:131]
	s_and_b64 vcc, exec, s[8:9]
	v_cvt_pk_bf16_f32 v136, v136, v137
	v_cvt_pk_bf16_f32 v137, v148, v149
	s_mov_b64 s[20:21], -1
	s_cbranch_vccnz .LBB0_773
	s_add_u32 s20, s63, s66
	v_mad_u64_u32 v[148:149], s[22:23], s12, v142, 0
	s_addc_u32 s21, s38, s67
	v_add3_u32 v149, v149, v140, v144
	s_ashr_i32 s65, s64, 31
	v_lshl_add_u64 v[148:149], v[148:149], 1, s[20:21]
	v_lshl_add_u64 v[150:151], s[64:65], 0, v[128:129]
	v_lshl_add_u64 v[148:149], v[150:151], 1, v[148:149]
	s_lshl_b64 s[20:21], s[12:13], 1
	global_store_short v[148:149], v136, off offset:32
	v_lshl_add_u64 v[148:149], v[148:149], 0, s[20:21]
	global_store_short_d16_hi v[148:149], v136, off offset:32
	v_lshl_add_u64 v[148:149], v[148:149], 0, s[20:21]
	global_store_short v[148:149], v137, off offset:32
	v_lshl_add_u64 v[148:149], v[148:149], 0, s[20:21]
	s_mov_b64 s[20:21], 0
	global_store_short_d16_hi v[148:149], v137, off offset:32
.LBB0_773:
	s_andn2_b64 vcc, exec, s[20:21]
	s_cbranch_vccnz .LBB0_775
	s_lshl_b32 s2, s41, 1
	v_lshl_add_u64 v[132:133], v[132:133], 0, s[2:3]
	v_lshlrev_b32_e32 v152, 1, v190
	v_lshl_add_u64 v[132:133], v[132:133], 0, v[152:153]
	global_store_dwordx2 v[132:133], v[136:137], off offset:128
.LBB0_775:
	v_mov_b32_e32 v132, v130
	v_mov_b32_e32 v133, v130
	v_pk_mul_f32 v[132:133], v[98:99], v[132:133]
	v_pk_mul_f32 v[130:131], v[96:97], v[130:131]
	s_and_b64 vcc, exec, s[8:9]
	v_cvt_pk_bf16_f32 v130, v130, v131
	v_cvt_pk_bf16_f32 v131, v132, v133
	s_mov_b64 s[20:21], -1
	s_cbranch_vccnz .LBB0_778
	s_add_u32 s20, s63, s66
	v_mad_u64_u32 v[132:133], s[22:23], s12, v138, 0
	s_addc_u32 s21, s38, s67
	v_add3_u32 v133, v133, v140, v139
	s_ashr_i32 s65, s64, 31
	v_lshl_add_u64 v[132:133], v[132:133], 1, s[20:21]
	v_lshl_add_u64 v[136:137], s[64:65], 0, v[128:129]
	v_lshl_add_u64 v[132:133], v[136:137], 1, v[132:133]
	s_lshl_b64 s[20:21], s[12:13], 1
	global_store_short v[132:133], v130, off offset:32
	v_lshl_add_u64 v[132:133], v[132:133], 0, s[20:21]
	global_store_short_d16_hi v[132:133], v130, off offset:32
	v_lshl_add_u64 v[132:133], v[132:133], 0, s[20:21]
	global_store_short v[132:133], v131, off offset:32
	v_lshl_add_u64 v[132:133], v[132:133], 0, s[20:21]
	global_store_short_d16_hi v[132:133], v131, off offset:32
	s_cbranch_execz .LBB0_779

.LBB0_779:
	s_lshl_b32 s2, s41, 1
	v_lshl_add_u64 v[132:133], v[134:135], 0, s[2:3]
	v_lshlrev_b32_e32 v152, 1, v190
	v_lshl_add_u64 v[132:133], v[132:133], 0, v[152:153]
	v_add_co_u32_e32 v132, vcc, 0xac00000, v132
	s_nop 1
	v_addc_co_u32_e32 v133, vcc, 0, v133, vcc
	global_store_dwordx2 v[132:133], v[130:131], off offset:160
	v_or_b32_e32 v131, 32, v128
	s_and_b64 vcc, exec, s[10:11]
	v_mov_b32_e32 v130, 1.0
	s_cbranch_vccnz .LBB0_784
.LBB0_780:
	s_andn2_b64 vcc, exec, s[36:37]
	s_mov_b64 s[20:21], -1
	s_cbranch_vccnz .LBB0_782
	v_add_u32_e32 v132, s40, v131
	v_readlane_b32 s20, v254, 50
	v_ashrrev_i32_e32 v133, 31, v132
	v_readlane_b32 s21, v254, 51
	s_nop 1
	v_lshl_add_u64 v[132:133], v[132:133], 4, s[20:21]
	global_load_dwordx4 v[132:135], v[132:133], off
	s_mov_b64 s[20:21], 0
	s_waitcnt vmcnt(0) lgkmcnt(0)
	v_mov_b32_e32 v136, v133
	v_mov_b32_e32 v137, v134
	v_mov_b32_e32 v133, v135
	v_pk_add_f32 v[132:133], v[136:137], v[132:133]
	s_nop 0
	v_add_f32_e32 v130, v132, v133
	v_fmamk_f32 v130, v130, 0x3b800000, v207
	v_mul_f32_e32 v132, 0x4b800000, v130
	v_cmp_gt_f32_e32 vcc, s68, v130
	s_nop 1
	v_cndmask_b32_e32 v130, v130, v132, vcc
	v_rsq_f32_e32 v130, v130
	s_nop 0
	v_mul_f32_e32 v132, 0x45800000, v130
	v_cndmask_b32_e32 v130, v130, v132, vcc

.LBB0_784:
	s_waitcnt lgkmcnt(0)
	v_pk_mul_f32 v[132:133], v[94:95], v[130:131] op_sel_hi:[1,0]
	v_pk_mul_f32 v[134:135], v[92:93], v[130:131] op_sel_hi:[1,0]
	v_cvt_pk_bf16_f32 v137, v132, v133
	v_cvt_pk_bf16_f32 v136, v134, v135
	s_and_b64 vcc, exec, s[8:9]
	s_mov_b64 s[20:21], -1
	s_cbranch_vccnz .LBB0_786
	s_add_u32 s20, s63, s66
	v_mad_u64_u32 v[132:133], s[22:23], s12, v143, 0
	s_addc_u32 s21, s38, s67
	v_add3_u32 v133, v133, v141, v145
	s_ashr_i32 s65, s64, 31
	v_lshl_add_u64 v[132:133], v[132:133], 1, s[20:21]
	v_lshl_add_u64 v[134:135], s[64:65], 0, v[128:129]
	v_lshl_add_u64 v[132:133], v[134:135], 1, v[132:133]
	s_lshl_b64 s[20:21], s[12:13], 1
	global_store_short v[132:133], v136, off offset:64
	v_lshl_add_u64 v[132:133], v[132:133], 0, s[20:21]
	global_store_short_d16_hi v[132:133], v136, off offset:64
	v_lshl_add_u64 v[132:133], v[132:133], 0, s[20:21]
	global_store_short v[132:133], v137, off offset:64
	v_lshl_add_u64 v[132:133], v[132:133], 0, s[20:21]
	s_mov_b64 s[20:21], 0
	global_store_short_d16_hi v[132:133], v137, off offset:64
.LBB0_786:
	v_add_u32_e32 v132, s24, v131
	v_ashrrev_i32_e32 v133, 31, v132
	v_lshlrev_b64 v[134:135], 10, v[132:133]
	v_lshl_add_u64 v[132:133], s[96:97], 0, v[134:135]
	s_andn2_b64 vcc, exec, s[20:21]
	v_lshl_add_u64 v[132:133], s[78:79], 1, v[132:133]
	s_cbranch_vccnz .LBB0_788
	s_lshl_b32 s2, s41, 1
	v_lshl_add_u64 v[148:149], v[132:133], 0, s[2:3]
	v_lshlrev_b32_e32 v152, 1, v190
	v_lshl_add_u64 v[148:149], v[148:149], 0, v[152:153]
	global_store_dwordx2 v[148:149], v[136:137], off
.LBB0_788:
	v_mov_b32_e32 v131, v130
	v_mov_b32_e32 v136, v130
	v_mov_b32_e32 v137, v130
	v_pk_mul_f32 v[148:149], v[90:91], v[136:137]
	v_pk_mul_f32 v[136:137], v[88:89], v[130:131]
	s_and_b64 vcc, exec, s[8:9]
	v_cvt_pk_bf16_f32 v136, v136, v137
	v_cvt_pk_bf16_f32 v137, v148, v149
	s_mov_b64 s[20:21], -1
	s_cbranch_vccnz .LBB0_790
	s_add_u32 s20, s63, s66
	v_mad_u64_u32 v[148:149], s[22:23], s12, v146, 0
	s_addc_u32 s21, s38, s67
	v_add3_u32 v149, v149, v141, v147
	s_ashr_i32 s65, s64, 31
	v_lshl_add_u64 v[148:149], v[148:149], 1, s[20:21]
	v_lshl_add_u64 v[150:151], s[64:65], 0, v[128:129]
	v_lshl_add_u64 v[148:149], v[150:151], 1, v[148:149]
	s_lshl_b64 s[20:21], s[12:13], 1
	global_store_short v[148:149], v136, off offset:64
	v_lshl_add_u64 v[148:149], v[148:149], 0, s[20:21]
	global_store_short_d16_hi v[148:149], v136, off offset:64
	v_lshl_add_u64 v[148:149], v[148:149], 0, s[20:21]
	global_store_short v[148:149], v137, off offset:64
	v_lshl_add_u64 v[148:149], v[148:149], 0, s[20:21]
	s_mov_b64 s[20:21], 0
	global_store_short_d16_hi v[148:149], v137, off offset:64

.LBB0_792:
	v_mov_b32_e32 v136, v130
	v_mov_b32_e32 v137, v130
	v_pk_mul_f32 v[148:149], v[86:87], v[136:137]
	v_pk_mul_f32 v[136:137], v[84:85], v[130:131]
	s_and_b64 vcc, exec, s[8:9]
	v_cvt_pk_bf16_f32 v136, v136, v137
	v_cvt_pk_bf16_f32 v137, v148, v149
	s_mov_b64 s[20:21], -1
	s_cbranch_vccnz .LBB0_794
	s_add_u32 s20, s63, s66
	v_mad_u64_u32 v[148:149], s[22:23], s12, v142, 0
	s_addc_u32 s21, s38, s67
	v_add3_u32 v149, v149, v140, v144
	s_ashr_i32 s65, s64, 31
	v_lshl_add_u64 v[148:149], v[148:149], 1, s[20:21]
	v_lshl_add_u64 v[150:151], s[64:65], 0, v[128:129]
	v_lshl_add_u64 v[148:149], v[150:151], 1, v[148:149]
	s_lshl_b64 s[20:21], s[12:13], 1
	global_store_short v[148:149], v136, off offset:64
	v_lshl_add_u64 v[148:149], v[148:149], 0, s[20:21]
	global_store_short_d16_hi v[148:149], v136, off offset:64
	v_lshl_add_u64 v[148:149], v[148:149], 0, s[20:21]
	global_store_short v[148:149], v137, off offset:64
	v_lshl_add_u64 v[148:149], v[148:149], 0, s[20:21]
	s_mov_b64 s[20:21], 0
	global_store_short_d16_hi v[148:149], v137, off offset:64

.LBB0_796:
	v_mov_b32_e32 v132, v130
	v_mov_b32_e32 v133, v130
	v_pk_mul_f32 v[132:133], v[82:83], v[132:133]
	v_pk_mul_f32 v[130:131], v[80:81], v[130:131]
	s_and_b64 vcc, exec, s[8:9]
	v_cvt_pk_bf16_f32 v130, v130, v131
	v_cvt_pk_bf16_f32 v131, v132, v133
	s_mov_b64 s[20:21], -1
	s_cbranch_vccnz .LBB0_799
	s_add_u32 s20, s63, s66
	v_mad_u64_u32 v[132:133], s[22:23], s12, v138, 0
	s_addc_u32 s21, s38, s67
	v_add3_u32 v133, v133, v140, v139
	s_ashr_i32 s65, s64, 31
	v_lshl_add_u64 v[132:133], v[132:133], 1, s[20:21]
	v_lshl_add_u64 v[136:137], s[64:65], 0, v[128:129]
	v_lshl_add_u64 v[132:133], v[136:137], 1, v[132:133]
	s_lshl_b64 s[20:21], s[12:13], 1
	global_store_short v[132:133], v130, off offset:64
	v_lshl_add_u64 v[132:133], v[132:133], 0, s[20:21]
	global_store_short_d16_hi v[132:133], v130, off offset:64
	v_lshl_add_u64 v[132:133], v[132:133], 0, s[20:21]
	global_store_short v[132:133], v131, off offset:64
	v_lshl_add_u64 v[132:133], v[132:133], 0, s[20:21]
	global_store_short_d16_hi v[132:133], v131, off offset:64
	s_cbranch_execz .LBB0_800

.LBB0_800:
	s_lshl_b32 s2, s41, 1
	v_lshl_add_u64 v[132:133], v[134:135], 0, s[2:3]
	v_lshlrev_b32_e32 v152, 1, v190
	v_lshl_add_u64 v[132:133], v[132:133], 0, v[152:153]
	v_add_co_u32_e32 v132, vcc, 0xac00000, v132
	s_nop 1
	v_addc_co_u32_e32 v133, vcc, 0, v133, vcc
	global_store_dwordx2 v[132:133], v[130:131], off offset:160
	v_or_b32_e32 v131, 48, v128
	s_and_b64 vcc, exec, s[10:11]
	v_mov_b32_e32 v130, 1.0
	s_cbranch_vccnz .LBB0_805

.LBB0_805:
	s_waitcnt lgkmcnt(0)
	v_pk_mul_f32 v[132:133], v[78:79], v[130:131] op_sel_hi:[1,0]
	v_pk_mul_f32 v[134:135], v[76:77], v[130:131] op_sel_hi:[1,0]
	v_cvt_pk_bf16_f32 v137, v132, v133
	v_cvt_pk_bf16_f32 v136, v134, v135
	s_and_b64 vcc, exec, s[8:9]
	s_mov_b64 s[20:21], -1
	s_cbranch_vccnz .LBB0_807
	s_add_u32 s20, s63, s66
	v_mad_u64_u32 v[132:133], s[22:23], s12, v143, 0
	s_addc_u32 s21, s38, s67
	v_add3_u32 v133, v133, v141, v145
	s_ashr_i32 s65, s64, 31
	v_lshl_add_u64 v[132:133], v[132:133], 1, s[20:21]
	v_lshl_add_u64 v[134:135], s[64:65], 0, v[128:129]
	v_lshl_add_u64 v[132:133], v[134:135], 1, v[132:133]
	s_lshl_b64 s[20:21], s[12:13], 1
	global_store_short v[132:133], v136, off offset:96
	v_lshl_add_u64 v[132:133], v[132:133], 0, s[20:21]
	global_store_short_d16_hi v[132:133], v136, off offset:96
	v_lshl_add_u64 v[132:133], v[132:133], 0, s[20:21]
	global_store_short v[132:133], v137, off offset:96
	v_lshl_add_u64 v[132:133], v[132:133], 0, s[20:21]
	s_mov_b64 s[20:21], 0
	global_store_short_d16_hi v[132:133], v137, off offset:96

.LBB0_809:
	v_mov_b32_e32 v131, v130
	v_mov_b32_e32 v136, v130
	v_mov_b32_e32 v137, v130
	v_pk_mul_f32 v[148:149], v[74:75], v[136:137]
	v_pk_mul_f32 v[136:137], v[72:73], v[130:131]
	s_and_b64 vcc, exec, s[8:9]
	v_cvt_pk_bf16_f32 v136, v136, v137
	v_cvt_pk_bf16_f32 v137, v148, v149
	s_mov_b64 s[20:21], -1
	s_cbranch_vccnz .LBB0_811
	s_add_u32 s20, s63, s66
	v_mad_u64_u32 v[148:149], s[22:23], s12, v146, 0
	s_addc_u32 s21, s38, s67
	v_add3_u32 v149, v149, v141, v147
	s_ashr_i32 s65, s64, 31
	v_lshl_add_u64 v[148:149], v[148:149], 1, s[20:21]
	v_lshl_add_u64 v[150:151], s[64:65], 0, v[128:129]
	v_lshl_add_u64 v[148:149], v[150:151], 1, v[148:149]
	s_lshl_b64 s[20:21], s[12:13], 1
	global_store_short v[148:149], v136, off offset:96
	v_lshl_add_u64 v[148:149], v[148:149], 0, s[20:21]
	global_store_short_d16_hi v[148:149], v136, off offset:96
	v_lshl_add_u64 v[148:149], v[148:149], 0, s[20:21]
	global_store_short v[148:149], v137, off offset:96
	v_lshl_add_u64 v[148:149], v[148:149], 0, s[20:21]
	s_mov_b64 s[20:21], 0
	global_store_short_d16_hi v[148:149], v137, off offset:96

.LBB0_813:
	v_mov_b32_e32 v136, v130
	v_mov_b32_e32 v137, v130
	v_pk_mul_f32 v[148:149], v[70:71], v[136:137]
	v_pk_mul_f32 v[136:137], v[68:69], v[130:131]
	s_and_b64 vcc, exec, s[8:9]
	v_cvt_pk_bf16_f32 v136, v136, v137
	v_cvt_pk_bf16_f32 v137, v148, v149
	s_mov_b64 s[20:21], -1
	s_cbranch_vccnz .LBB0_815
	s_add_u32 s20, s63, s66
	v_mad_u64_u32 v[148:149], s[22:23], s12, v142, 0
	s_addc_u32 s21, s38, s67
	v_add3_u32 v149, v149, v140, v144
	s_ashr_i32 s65, s64, 31
	v_lshl_add_u64 v[148:149], v[148:149], 1, s[20:21]
	v_lshl_add_u64 v[150:151], s[64:65], 0, v[128:129]
	v_lshl_add_u64 v[148:149], v[150:151], 1, v[148:149]
	s_lshl_b64 s[20:21], s[12:13], 1
	global_store_short v[148:149], v136, off offset:96
	v_lshl_add_u64 v[148:149], v[148:149], 0, s[20:21]
	global_store_short_d16_hi v[148:149], v136, off offset:96
	v_lshl_add_u64 v[148:149], v[148:149], 0, s[20:21]
	global_store_short v[148:149], v137, off offset:96
	v_lshl_add_u64 v[148:149], v[148:149], 0, s[20:21]
	s_mov_b64 s[20:21], 0
	global_store_short_d16_hi v[148:149], v137, off offset:96

.LBB0_817:
	v_mov_b32_e32 v132, v130
	v_mov_b32_e32 v133, v130
	v_pk_mul_f32 v[132:133], v[66:67], v[132:133]
	v_pk_mul_f32 v[130:131], v[64:65], v[130:131]
	s_and_b64 vcc, exec, s[8:9]
	v_cvt_pk_bf16_f32 v130, v130, v131
	v_cvt_pk_bf16_f32 v131, v132, v133
	s_mov_b64 s[20:21], -1
	s_cbranch_vccnz .LBB0_820
	s_add_u32 s20, s63, s66
	v_mad_u64_u32 v[132:133], s[22:23], s12, v138, 0
	s_addc_u32 s21, s38, s67
	v_add3_u32 v133, v133, v140, v139
	s_ashr_i32 s65, s64, 31
	v_lshl_add_u64 v[132:133], v[132:133], 1, s[20:21]
	v_lshl_add_u64 v[136:137], s[64:65], 0, v[128:129]
	v_lshl_add_u64 v[132:133], v[136:137], 1, v[132:133]
	s_lshl_b64 s[20:21], s[12:13], 1
	global_store_short v[132:133], v130, off offset:96
	v_lshl_add_u64 v[132:133], v[132:133], 0, s[20:21]
	global_store_short_d16_hi v[132:133], v130, off offset:96
	v_lshl_add_u64 v[132:133], v[132:133], 0, s[20:21]
	global_store_short v[132:133], v131, off offset:96
	v_lshl_add_u64 v[132:133], v[132:133], 0, s[20:21]
	global_store_short_d16_hi v[132:133], v131, off offset:96
	s_cbranch_execz .LBB0_821

.LBB0_821:
	s_lshl_b32 s2, s41, 1
	v_lshl_add_u64 v[132:133], v[134:135], 0, s[2:3]
	v_lshlrev_b32_e32 v152, 1, v190
	v_lshl_add_u64 v[132:133], v[132:133], 0, v[152:153]
	v_add_co_u32_e32 v132, vcc, 0xac00000, v132
	s_nop 1
	v_addc_co_u32_e32 v133, vcc, 0, v133, vcc
	global_store_dwordx2 v[132:133], v[130:131], off offset:160
	v_add_u32_e32 v131, 0x80, v128
	s_and_b64 vcc, exec, s[10:11]
	v_mov_b32_e32 v130, 1.0
	s_cbranch_vccnz .LBB0_826

.LBB0_826:
	s_waitcnt lgkmcnt(0)
	v_pk_mul_f32 v[132:133], v[62:63], v[130:131] op_sel_hi:[1,0]
	v_pk_mul_f32 v[134:135], v[60:61], v[130:131] op_sel_hi:[1,0]
	v_cvt_pk_bf16_f32 v137, v132, v133
	v_cvt_pk_bf16_f32 v136, v134, v135
	s_and_b64 vcc, exec, s[8:9]
	s_mov_b64 s[20:21], -1
	s_cbranch_vccnz .LBB0_828
	s_add_u32 s20, s63, s66
	v_mad_u64_u32 v[132:133], s[22:23], s12, v143, 0
	s_addc_u32 s21, s38, s67
	v_add3_u32 v133, v133, v141, v145
	s_ashr_i32 s65, s64, 31
	v_lshl_add_u64 v[132:133], v[132:133], 1, s[20:21]
	v_lshl_add_u64 v[134:135], s[64:65], 0, v[128:129]
	v_lshl_add_u64 v[132:133], v[134:135], 1, v[132:133]
	s_lshl_b64 s[20:21], s[12:13], 1
	global_store_short v[132:133], v136, off offset:256
	v_lshl_add_u64 v[132:133], v[132:133], 0, s[20:21]
	global_store_short_d16_hi v[132:133], v136, off offset:256
	v_lshl_add_u64 v[132:133], v[132:133], 0, s[20:21]
	global_store_short v[132:133], v137, off offset:256
	v_lshl_add_u64 v[132:133], v[132:133], 0, s[20:21]
	s_mov_b64 s[20:21], 0
	global_store_short_d16_hi v[132:133], v137, off offset:256

.LBB0_830:
	v_mov_b32_e32 v131, v130
	v_mov_b32_e32 v136, v130
	v_mov_b32_e32 v137, v130
	v_pk_mul_f32 v[148:149], v[58:59], v[136:137]
	v_pk_mul_f32 v[136:137], v[56:57], v[130:131]
	s_and_b64 vcc, exec, s[8:9]
	v_cvt_pk_bf16_f32 v136, v136, v137
	v_cvt_pk_bf16_f32 v137, v148, v149
	s_mov_b64 s[20:21], -1
	s_cbranch_vccnz .LBB0_832
	s_add_u32 s20, s63, s66
	v_mad_u64_u32 v[148:149], s[22:23], s12, v146, 0
	s_addc_u32 s21, s38, s67
	v_add3_u32 v149, v149, v141, v147
	s_ashr_i32 s65, s64, 31
	v_lshl_add_u64 v[148:149], v[148:149], 1, s[20:21]
	v_lshl_add_u64 v[150:151], s[64:65], 0, v[128:129]
	v_lshl_add_u64 v[148:149], v[150:151], 1, v[148:149]
	s_lshl_b64 s[20:21], s[12:13], 1
	global_store_short v[148:149], v136, off offset:256
	v_lshl_add_u64 v[148:149], v[148:149], 0, s[20:21]
	global_store_short_d16_hi v[148:149], v136, off offset:256
	v_lshl_add_u64 v[148:149], v[148:149], 0, s[20:21]
	global_store_short v[148:149], v137, off offset:256
	v_lshl_add_u64 v[148:149], v[148:149], 0, s[20:21]
	s_mov_b64 s[20:21], 0
	global_store_short_d16_hi v[148:149], v137, off offset:256

.LBB0_834:
	v_mov_b32_e32 v136, v130
	v_mov_b32_e32 v137, v130
	v_pk_mul_f32 v[148:149], v[54:55], v[136:137]
	v_pk_mul_f32 v[136:137], v[52:53], v[130:131]
	s_and_b64 vcc, exec, s[8:9]
	v_cvt_pk_bf16_f32 v136, v136, v137
	v_cvt_pk_bf16_f32 v137, v148, v149
	s_mov_b64 s[20:21], -1
	s_cbranch_vccnz .LBB0_836
	s_add_u32 s20, s63, s66
	v_mad_u64_u32 v[148:149], s[22:23], s12, v142, 0
	s_addc_u32 s21, s38, s67
	v_add3_u32 v149, v149, v140, v144
	s_ashr_i32 s65, s64, 31
	v_lshl_add_u64 v[148:149], v[148:149], 1, s[20:21]
	v_lshl_add_u64 v[150:151], s[64:65], 0, v[128:129]
	v_lshl_add_u64 v[148:149], v[150:151], 1, v[148:149]
	s_lshl_b64 s[20:21], s[12:13], 1
	global_store_short v[148:149], v136, off offset:256
	v_lshl_add_u64 v[148:149], v[148:149], 0, s[20:21]
	global_store_short_d16_hi v[148:149], v136, off offset:256
	v_lshl_add_u64 v[148:149], v[148:149], 0, s[20:21]
	global_store_short v[148:149], v137, off offset:256
	v_lshl_add_u64 v[148:149], v[148:149], 0, s[20:21]
	s_mov_b64 s[20:21], 0
	global_store_short_d16_hi v[148:149], v137, off offset:256

.LBB0_838:
	v_mov_b32_e32 v132, v130
	v_mov_b32_e32 v133, v130
	v_pk_mul_f32 v[132:133], v[50:51], v[132:133]
	v_pk_mul_f32 v[130:131], v[48:49], v[130:131]
	s_and_b64 vcc, exec, s[8:9]
	v_cvt_pk_bf16_f32 v130, v130, v131
	v_cvt_pk_bf16_f32 v131, v132, v133
	s_mov_b64 s[20:21], -1
	s_cbranch_vccnz .LBB0_841
	s_add_u32 s20, s63, s66
	v_mad_u64_u32 v[132:133], s[22:23], s12, v138, 0
	s_addc_u32 s21, s38, s67
	v_add3_u32 v133, v133, v140, v139
	s_ashr_i32 s65, s64, 31
	v_lshl_add_u64 v[132:133], v[132:133], 1, s[20:21]
	v_lshl_add_u64 v[136:137], s[64:65], 0, v[128:129]
	v_lshl_add_u64 v[132:133], v[136:137], 1, v[132:133]
	s_lshl_b64 s[20:21], s[12:13], 1
	global_store_short v[132:133], v130, off offset:256
	v_lshl_add_u64 v[132:133], v[132:133], 0, s[20:21]
	global_store_short_d16_hi v[132:133], v130, off offset:256
	v_lshl_add_u64 v[132:133], v[132:133], 0, s[20:21]
	global_store_short v[132:133], v131, off offset:256
	v_lshl_add_u64 v[132:133], v[132:133], 0, s[20:21]
	global_store_short_d16_hi v[132:133], v131, off offset:256
	s_cbranch_execz .LBB0_842

.LBB0_842:
	s_lshl_b32 s2, s41, 1
	v_lshl_add_u64 v[132:133], v[134:135], 0, s[2:3]
	v_lshlrev_b32_e32 v152, 1, v190
	v_lshl_add_u64 v[132:133], v[132:133], 0, v[152:153]
	v_add_co_u32_e32 v132, vcc, 0xac00000, v132
	s_nop 1
	v_addc_co_u32_e32 v133, vcc, 0, v133, vcc
	global_store_dwordx2 v[132:133], v[130:131], off offset:160
	v_add_u32_e32 v131, 0x90, v128
	s_and_b64 vcc, exec, s[10:11]
	v_mov_b32_e32 v130, 1.0
	s_cbranch_vccnz .LBB0_847

.LBB0_847:
	s_waitcnt lgkmcnt(0)
	v_pk_mul_f32 v[132:133], v[46:47], v[130:131] op_sel_hi:[1,0]
	v_pk_mul_f32 v[134:135], v[44:45], v[130:131] op_sel_hi:[1,0]
	v_cvt_pk_bf16_f32 v137, v132, v133
	v_cvt_pk_bf16_f32 v136, v134, v135
	s_and_b64 vcc, exec, s[8:9]
	s_mov_b64 s[20:21], -1
	s_cbranch_vccnz .LBB0_849
	s_add_u32 s20, s63, s66
	v_mad_u64_u32 v[132:133], s[22:23], s12, v143, 0
	s_addc_u32 s21, s38, s67
	v_add3_u32 v133, v133, v141, v145
	s_ashr_i32 s65, s64, 31
	v_lshl_add_u64 v[132:133], v[132:133], 1, s[20:21]
	v_lshl_add_u64 v[134:135], s[64:65], 0, v[128:129]
	v_lshl_add_u64 v[132:133], v[134:135], 1, v[132:133]
	s_lshl_b64 s[20:21], s[12:13], 1
	global_store_short v[132:133], v136, off offset:288
	v_lshl_add_u64 v[132:133], v[132:133], 0, s[20:21]
	global_store_short_d16_hi v[132:133], v136, off offset:288
	v_lshl_add_u64 v[132:133], v[132:133], 0, s[20:21]
	global_store_short v[132:133], v137, off offset:288
	v_lshl_add_u64 v[132:133], v[132:133], 0, s[20:21]
	s_mov_b64 s[20:21], 0
	global_store_short_d16_hi v[132:133], v137, off offset:288

.LBB0_851:
	v_mov_b32_e32 v131, v130
	v_mov_b32_e32 v136, v130
	v_mov_b32_e32 v137, v130
	v_pk_mul_f32 v[148:149], v[42:43], v[136:137]
	v_pk_mul_f32 v[136:137], v[40:41], v[130:131]
	s_and_b64 vcc, exec, s[8:9]
	v_cvt_pk_bf16_f32 v136, v136, v137
	v_cvt_pk_bf16_f32 v137, v148, v149
	s_mov_b64 s[20:21], -1
	s_cbranch_vccnz .LBB0_853
	s_add_u32 s20, s63, s66
	v_mad_u64_u32 v[148:149], s[22:23], s12, v146, 0
	s_addc_u32 s21, s38, s67
	v_add3_u32 v149, v149, v141, v147
	s_ashr_i32 s65, s64, 31
	v_lshl_add_u64 v[148:149], v[148:149], 1, s[20:21]
	v_lshl_add_u64 v[150:151], s[64:65], 0, v[128:129]
	v_lshl_add_u64 v[148:149], v[150:151], 1, v[148:149]
	s_lshl_b64 s[20:21], s[12:13], 1
	global_store_short v[148:149], v136, off offset:288
	v_lshl_add_u64 v[148:149], v[148:149], 0, s[20:21]
	global_store_short_d16_hi v[148:149], v136, off offset:288
	v_lshl_add_u64 v[148:149], v[148:149], 0, s[20:21]
	global_store_short v[148:149], v137, off offset:288
	v_lshl_add_u64 v[148:149], v[148:149], 0, s[20:21]
	s_mov_b64 s[20:21], 0
	global_store_short_d16_hi v[148:149], v137, off offset:288

.LBB0_855:
	v_mov_b32_e32 v136, v130
	v_mov_b32_e32 v137, v130
	v_pk_mul_f32 v[148:149], v[38:39], v[136:137]
	v_pk_mul_f32 v[136:137], v[36:37], v[130:131]
	s_and_b64 vcc, exec, s[8:9]
	v_cvt_pk_bf16_f32 v136, v136, v137
	v_cvt_pk_bf16_f32 v137, v148, v149
	s_mov_b64 s[20:21], -1
	s_cbranch_vccnz .LBB0_857
	s_add_u32 s20, s63, s66
	v_mad_u64_u32 v[148:149], s[22:23], s12, v142, 0
	s_addc_u32 s21, s38, s67
	v_add3_u32 v149, v149, v140, v144
	s_ashr_i32 s65, s64, 31
	v_lshl_add_u64 v[148:149], v[148:149], 1, s[20:21]
	v_lshl_add_u64 v[150:151], s[64:65], 0, v[128:129]
	v_lshl_add_u64 v[148:149], v[150:151], 1, v[148:149]
	s_lshl_b64 s[20:21], s[12:13], 1
	global_store_short v[148:149], v136, off offset:288
	v_lshl_add_u64 v[148:149], v[148:149], 0, s[20:21]
	global_store_short_d16_hi v[148:149], v136, off offset:288
	v_lshl_add_u64 v[148:149], v[148:149], 0, s[20:21]
	global_store_short v[148:149], v137, off offset:288
	v_lshl_add_u64 v[148:149], v[148:149], 0, s[20:21]
	s_mov_b64 s[20:21], 0
	global_store_short_d16_hi v[148:149], v137, off offset:288

.LBB0_859:
	v_mov_b32_e32 v132, v130
	v_mov_b32_e32 v133, v130
	v_pk_mul_f32 v[132:133], v[34:35], v[132:133]
	v_pk_mul_f32 v[130:131], v[32:33], v[130:131]
	s_and_b64 vcc, exec, s[8:9]
	v_cvt_pk_bf16_f32 v130, v130, v131
	v_cvt_pk_bf16_f32 v131, v132, v133
	s_mov_b64 s[20:21], -1
	s_cbranch_vccnz .LBB0_862
	s_add_u32 s20, s63, s66
	v_mad_u64_u32 v[132:133], s[22:23], s12, v138, 0
	s_addc_u32 s21, s38, s67
	v_add3_u32 v133, v133, v140, v139
	s_ashr_i32 s65, s64, 31
	v_lshl_add_u64 v[132:133], v[132:133], 1, s[20:21]
	v_lshl_add_u64 v[136:137], s[64:65], 0, v[128:129]
	v_lshl_add_u64 v[132:133], v[136:137], 1, v[132:133]
	s_lshl_b64 s[20:21], s[12:13], 1
	global_store_short v[132:133], v130, off offset:288
	v_lshl_add_u64 v[132:133], v[132:133], 0, s[20:21]
	global_store_short_d16_hi v[132:133], v130, off offset:288
	v_lshl_add_u64 v[132:133], v[132:133], 0, s[20:21]
	global_store_short v[132:133], v131, off offset:288
	v_lshl_add_u64 v[132:133], v[132:133], 0, s[20:21]
	global_store_short_d16_hi v[132:133], v131, off offset:288
	s_cbranch_execz .LBB0_863

.LBB0_863:
	s_lshl_b32 s2, s41, 1
	v_lshl_add_u64 v[132:133], v[134:135], 0, s[2:3]
	v_lshlrev_b32_e32 v152, 1, v190
	v_lshl_add_u64 v[132:133], v[132:133], 0, v[152:153]
	v_add_co_u32_e32 v132, vcc, 0xac00000, v132
	s_nop 1
	v_addc_co_u32_e32 v133, vcc, 0, v133, vcc
	global_store_dwordx2 v[132:133], v[130:131], off offset:160
	v_add_u32_e32 v131, 0xa0, v128
	s_and_b64 vcc, exec, s[10:11]
	v_mov_b32_e32 v130, 1.0
	s_cbranch_vccnz .LBB0_868

.LBB0_868:
	s_waitcnt lgkmcnt(0)
	v_pk_mul_f32 v[132:133], v[30:31], v[130:131] op_sel_hi:[1,0]
	v_pk_mul_f32 v[134:135], v[28:29], v[130:131] op_sel_hi:[1,0]
	v_cvt_pk_bf16_f32 v137, v132, v133
	v_cvt_pk_bf16_f32 v136, v134, v135
	s_and_b64 vcc, exec, s[8:9]
	s_mov_b64 s[20:21], -1
	s_cbranch_vccnz .LBB0_870
	s_add_u32 s20, s63, s66
	v_mad_u64_u32 v[132:133], s[22:23], s12, v143, 0
	s_addc_u32 s21, s38, s67
	v_add3_u32 v133, v133, v141, v145
	s_ashr_i32 s65, s64, 31
	v_lshl_add_u64 v[132:133], v[132:133], 1, s[20:21]
	v_lshl_add_u64 v[134:135], s[64:65], 0, v[128:129]
	v_lshl_add_u64 v[132:133], v[134:135], 1, v[132:133]
	s_lshl_b64 s[20:21], s[12:13], 1
	global_store_short v[132:133], v136, off offset:320
	v_lshl_add_u64 v[132:133], v[132:133], 0, s[20:21]
	global_store_short_d16_hi v[132:133], v136, off offset:320
	v_lshl_add_u64 v[132:133], v[132:133], 0, s[20:21]
	global_store_short v[132:133], v137, off offset:320
	v_lshl_add_u64 v[132:133], v[132:133], 0, s[20:21]
	s_mov_b64 s[20:21], 0
	global_store_short_d16_hi v[132:133], v137, off offset:320

.LBB0_872:
	v_mov_b32_e32 v131, v130
	v_mov_b32_e32 v136, v130
	v_mov_b32_e32 v137, v130
	v_pk_mul_f32 v[148:149], v[26:27], v[136:137]
	v_pk_mul_f32 v[136:137], v[24:25], v[130:131]
	s_and_b64 vcc, exec, s[8:9]
	v_cvt_pk_bf16_f32 v136, v136, v137
	v_cvt_pk_bf16_f32 v137, v148, v149
	s_mov_b64 s[20:21], -1
	s_cbranch_vccnz .LBB0_874
	s_add_u32 s20, s63, s66
	v_mad_u64_u32 v[148:149], s[22:23], s12, v146, 0
	s_addc_u32 s21, s38, s67
	v_add3_u32 v149, v149, v141, v147
	s_ashr_i32 s65, s64, 31
	v_lshl_add_u64 v[148:149], v[148:149], 1, s[20:21]
	v_lshl_add_u64 v[150:151], s[64:65], 0, v[128:129]
	v_lshl_add_u64 v[148:149], v[150:151], 1, v[148:149]
	s_lshl_b64 s[20:21], s[12:13], 1
	global_store_short v[148:149], v136, off offset:320
	v_lshl_add_u64 v[148:149], v[148:149], 0, s[20:21]
	global_store_short_d16_hi v[148:149], v136, off offset:320
	v_lshl_add_u64 v[148:149], v[148:149], 0, s[20:21]
	global_store_short v[148:149], v137, off offset:320
	v_lshl_add_u64 v[148:149], v[148:149], 0, s[20:21]
	s_mov_b64 s[20:21], 0
	global_store_short_d16_hi v[148:149], v137, off offset:320

.LBB0_876:
	v_mov_b32_e32 v136, v130
	v_mov_b32_e32 v137, v130
	v_pk_mul_f32 v[148:149], v[22:23], v[136:137]
	v_pk_mul_f32 v[136:137], v[20:21], v[130:131]
	s_and_b64 vcc, exec, s[8:9]
	v_cvt_pk_bf16_f32 v136, v136, v137
	v_cvt_pk_bf16_f32 v137, v148, v149
	s_mov_b64 s[20:21], -1
	s_cbranch_vccnz .LBB0_878
	s_add_u32 s20, s63, s66
	v_mad_u64_u32 v[148:149], s[22:23], s12, v142, 0
	s_addc_u32 s21, s38, s67
	v_add3_u32 v149, v149, v140, v144
	s_ashr_i32 s65, s64, 31
	v_lshl_add_u64 v[148:149], v[148:149], 1, s[20:21]
	v_lshl_add_u64 v[150:151], s[64:65], 0, v[128:129]
	v_lshl_add_u64 v[148:149], v[150:151], 1, v[148:149]
	s_lshl_b64 s[20:21], s[12:13], 1
	global_store_short v[148:149], v136, off offset:320
	v_lshl_add_u64 v[148:149], v[148:149], 0, s[20:21]
	global_store_short_d16_hi v[148:149], v136, off offset:320
	v_lshl_add_u64 v[148:149], v[148:149], 0, s[20:21]
	global_store_short v[148:149], v137, off offset:320
	v_lshl_add_u64 v[148:149], v[148:149], 0, s[20:21]
	s_mov_b64 s[20:21], 0
	global_store_short_d16_hi v[148:149], v137, off offset:320

.LBB0_880:
	v_mov_b32_e32 v132, v130
	v_mov_b32_e32 v133, v130
	v_pk_mul_f32 v[132:133], v[18:19], v[132:133]
	v_pk_mul_f32 v[130:131], v[16:17], v[130:131]
	s_and_b64 vcc, exec, s[8:9]
	v_cvt_pk_bf16_f32 v130, v130, v131
	v_cvt_pk_bf16_f32 v131, v132, v133
	s_mov_b64 s[20:21], -1
	s_cbranch_vccnz .LBB0_883
	s_add_u32 s20, s63, s66
	v_mad_u64_u32 v[132:133], s[22:23], s12, v138, 0
	s_addc_u32 s21, s38, s67
	v_add3_u32 v133, v133, v140, v139
	s_ashr_i32 s65, s64, 31
	v_lshl_add_u64 v[132:133], v[132:133], 1, s[20:21]
	v_lshl_add_u64 v[136:137], s[64:65], 0, v[128:129]
	v_lshl_add_u64 v[132:133], v[136:137], 1, v[132:133]
	s_lshl_b64 s[20:21], s[12:13], 1
	global_store_short v[132:133], v130, off offset:320
	v_lshl_add_u64 v[132:133], v[132:133], 0, s[20:21]
	global_store_short_d16_hi v[132:133], v130, off offset:320
	v_lshl_add_u64 v[132:133], v[132:133], 0, s[20:21]
	global_store_short v[132:133], v131, off offset:320
	v_lshl_add_u64 v[132:133], v[132:133], 0, s[20:21]
	global_store_short_d16_hi v[132:133], v131, off offset:320
	s_cbranch_execz .LBB0_884

.LBB0_884:
	s_lshl_b32 s2, s41, 1
	v_lshl_add_u64 v[132:133], v[134:135], 0, s[2:3]
	v_lshlrev_b32_e32 v152, 1, v190
	v_lshl_add_u64 v[132:133], v[132:133], 0, v[152:153]
	v_add_co_u32_e32 v132, vcc, 0xac00000, v132
	s_nop 1
	v_addc_co_u32_e32 v133, vcc, 0, v133, vcc
	global_store_dwordx2 v[132:133], v[130:131], off offset:160
	v_add_u32_e32 v131, 0xb0, v128
	s_and_b64 vcc, exec, s[10:11]
	v_mov_b32_e32 v130, 1.0
	s_cbranch_vccnz .LBB0_889
.LBB0_885:
	s_andn2_b64 vcc, exec, s[36:37]
	s_mov_b64 s[10:11], -1
	s_cbranch_vccnz .LBB0_887
	v_add_u32_e32 v132, s40, v131
	v_readlane_b32 s10, v254, 50
	v_ashrrev_i32_e32 v133, 31, v132
	v_readlane_b32 s11, v254, 51
	s_nop 1
	v_lshl_add_u64 v[132:133], v[132:133], 4, s[10:11]
	global_load_dwordx4 v[132:135], v[132:133], off
	s_mov_b64 s[10:11], 0
	s_waitcnt vmcnt(0) lgkmcnt(0)
	v_mov_b32_e32 v136, v133
	v_mov_b32_e32 v137, v134
	v_mov_b32_e32 v133, v135
	v_pk_add_f32 v[132:133], v[136:137], v[132:133]
	s_nop 0
	v_add_f32_e32 v130, v132, v133
	v_fmamk_f32 v130, v130, 0x3b800000, v207
	v_mul_f32_e32 v132, 0x4b800000, v130
	v_cmp_gt_f32_e32 vcc, s68, v130
	s_nop 1
	v_cndmask_b32_e32 v130, v130, v132, vcc
	v_rsq_f32_e32 v130, v130
	s_nop 0
	v_mul_f32_e32 v132, 0x45800000, v130
	v_cndmask_b32_e32 v130, v130, v132, vcc

.LBB0_889:
	s_waitcnt lgkmcnt(0)
	v_pk_mul_f32 v[132:133], v[14:15], v[130:131] op_sel_hi:[1,0]
	v_pk_mul_f32 v[134:135], v[12:13], v[130:131] op_sel_hi:[1,0]
	v_cvt_pk_bf16_f32 v137, v132, v133
	v_cvt_pk_bf16_f32 v136, v134, v135
	s_and_b64 vcc, exec, s[8:9]
	s_mov_b64 s[10:11], -1
	s_cbranch_vccnz .LBB0_891
	s_add_u32 s10, s63, s66
	v_mad_u64_u32 v[132:133], s[20:21], s12, v143, 0
	s_addc_u32 s11, s38, s67
	v_add3_u32 v133, v133, v141, v145
	s_ashr_i32 s65, s64, 31
	v_lshl_add_u64 v[132:133], v[132:133], 1, s[10:11]
	v_lshl_add_u64 v[134:135], s[64:65], 0, v[128:129]
	v_lshl_add_u64 v[132:133], v[134:135], 1, v[132:133]
	s_lshl_b64 s[10:11], s[12:13], 1
	global_store_short v[132:133], v136, off offset:352
	v_lshl_add_u64 v[132:133], v[132:133], 0, s[10:11]
	global_store_short_d16_hi v[132:133], v136, off offset:352
	v_lshl_add_u64 v[132:133], v[132:133], 0, s[10:11]
	global_store_short v[132:133], v137, off offset:352
	v_lshl_add_u64 v[132:133], v[132:133], 0, s[10:11]
	s_mov_b64 s[10:11], 0
	global_store_short_d16_hi v[132:133], v137, off offset:352
.LBB0_891:
	v_add_u32_e32 v132, s24, v131
	v_ashrrev_i32_e32 v133, 31, v132
	v_lshlrev_b64 v[134:135], 10, v[132:133]
	v_lshl_add_u64 v[132:133], s[96:97], 0, v[134:135]
	s_andn2_b64 vcc, exec, s[10:11]
	v_lshl_add_u64 v[132:133], s[78:79], 1, v[132:133]
	s_cbranch_vccnz .LBB0_893
	s_lshl_b32 s2, s41, 1
	v_lshl_add_u64 v[148:149], v[132:133], 0, s[2:3]
	v_lshlrev_b32_e32 v152, 1, v190
	v_lshl_add_u64 v[148:149], v[148:149], 0, v[152:153]
	global_store_dwordx2 v[148:149], v[136:137], off
.LBB0_893:
	v_mov_b32_e32 v131, v130
	v_mov_b32_e32 v136, v130
	v_mov_b32_e32 v137, v130
	v_pk_mul_f32 v[148:149], v[10:11], v[136:137]
	v_pk_mul_f32 v[136:137], v[8:9], v[130:131]
	s_and_b64 vcc, exec, s[8:9]
	v_cvt_pk_bf16_f32 v136, v136, v137
	v_cvt_pk_bf16_f32 v137, v148, v149
	s_mov_b64 s[10:11], -1
	s_cbranch_vccnz .LBB0_895
	s_add_u32 s10, s63, s66
	v_mad_u64_u32 v[148:149], s[20:21], s12, v146, 0
	s_addc_u32 s11, s38, s67
	v_add3_u32 v149, v149, v141, v147
	s_ashr_i32 s65, s64, 31
	v_lshl_add_u64 v[146:147], v[148:149], 1, s[10:11]
	v_lshl_add_u64 v[148:149], s[64:65], 0, v[128:129]
	v_lshl_add_u64 v[146:147], v[148:149], 1, v[146:147]
	s_lshl_b64 s[10:11], s[12:13], 1
	global_store_short v[146:147], v136, off offset:352
	v_lshl_add_u64 v[146:147], v[146:147], 0, s[10:11]
	global_store_short_d16_hi v[146:147], v136, off offset:352
	v_lshl_add_u64 v[146:147], v[146:147], 0, s[10:11]
	global_store_short v[146:147], v137, off offset:352
	v_lshl_add_u64 v[146:147], v[146:147], 0, s[10:11]
	s_mov_b64 s[10:11], 0
	global_store_short_d16_hi v[146:147], v137, off offset:352
.LBB0_895:
	v_lshl_add_u64 v[134:135], s[18:19], 0, v[134:135]
	s_andn2_b64 vcc, exec, s[10:11]
	v_lshl_add_u64 v[134:135], s[78:79], 1, v[134:135]
	s_cbranch_vccnz .LBB0_897
	s_lshl_b32 s2, s41, 1
	v_lshl_add_u64 v[146:147], v[134:135], 0, s[2:3]
	v_lshlrev_b32_e32 v152, 1, v190
	v_lshl_add_u64 v[146:147], v[146:147], 0, v[152:153]
	v_add_co_u32_e32 v146, vcc, 0xac00000, v146
	s_nop 1
	v_addc_co_u32_e32 v147, vcc, 0, v147, vcc
	global_store_dwordx2 v[146:147], v[136:137], off offset:32
.LBB0_897:
	v_mov_b32_e32 v136, v130
	v_mov_b32_e32 v137, v130
	v_pk_mul_f32 v[146:147], v[6:7], v[136:137]
	v_pk_mul_f32 v[136:137], v[4:5], v[130:131]
	v_readlane_b32 s96, v253, 54
	v_cvt_pk_bf16_f32 v136, v136, v137
	v_cvt_pk_bf16_f32 v137, v146, v147
	s_and_b64 vcc, exec, s[8:9]
	s_mov_b64 s[10:11], -1
	v_readlane_b32 s38, v253, 53
	v_readlane_b32 s97, v253, 55
	s_mov_b64 s[78:79], s[90:91]
	s_cbranch_vccnz .LBB0_899
	s_add_u32 s10, s63, s66
	v_readlane_b32 s2, v254, 47
	v_mad_u64_u32 v[142:143], s[20:21], s12, v142, 0
	s_addc_u32 s11, s2, s67
	v_add3_u32 v143, v143, v140, v144
	s_ashr_i32 s65, s64, 31
	v_lshl_add_u64 v[142:143], v[142:143], 1, s[10:11]
	v_lshl_add_u64 v[144:145], s[64:65], 0, v[128:129]
	v_lshl_add_u64 v[142:143], v[144:145], 1, v[142:143]
	s_lshl_b64 s[10:11], s[12:13], 1
	global_store_short v[142:143], v136, off offset:352
	v_lshl_add_u64 v[142:143], v[142:143], 0, s[10:11]
	global_store_short_d16_hi v[142:143], v136, off offset:352
	v_lshl_add_u64 v[142:143], v[142:143], 0, s[10:11]
	global_store_short v[142:143], v137, off offset:352
	v_lshl_add_u64 v[142:143], v[142:143], 0, s[10:11]
	s_mov_b64 s[10:11], 0
	global_store_short_d16_hi v[142:143], v137, off offset:352
.LBB0_899:
	s_andn2_b64 vcc, exec, s[10:11]
	s_cbranch_vccnz .LBB0_901
	s_lshl_b32 s2, s41, 1
	v_lshl_add_u64 v[132:133], v[132:133], 0, s[2:3]
	v_lshlrev_b32_e32 v152, 1, v190
	v_lshl_add_u64 v[132:133], v[132:133], 0, v[152:153]
	global_store_dwordx2 v[132:133], v[136:137], off offset:128
.LBB0_901:
	v_mov_b32_e32 v132, v130
	v_mov_b32_e32 v133, v130
	v_pk_mul_f32 v[132:133], v[2:3], v[132:133]
	v_pk_mul_f32 v[130:131], v[0:1], v[130:131]
	s_and_b64 vcc, exec, s[8:9]
	v_cvt_pk_bf16_f32 v130, v130, v131
	v_cvt_pk_bf16_f32 v131, v132, v133
	s_mov_b64 s[8:9], -1
	s_cbranch_vccnz .LBB0_903
	s_add_u32 s8, s63, s66
	v_readlane_b32 s2, v254, 47
	v_mad_u64_u32 v[132:133], s[10:11], s12, v138, 0
	s_addc_u32 s9, s2, s67
	v_add3_u32 v133, v133, v140, v139
	s_ashr_i32 s65, s64, 31
	v_lshl_add_u64 v[132:133], v[132:133], 1, s[8:9]
	v_lshl_add_u64 v[128:129], s[64:65], 0, v[128:129]
	v_lshl_add_u64 v[128:129], v[128:129], 1, v[132:133]
	s_lshl_b64 s[8:9], s[12:13], 1
	global_store_short v[128:129], v130, off offset:352
	v_lshl_add_u64 v[128:129], v[128:129], 0, s[8:9]
	global_store_short_d16_hi v[128:129], v130, off offset:352
	v_lshl_add_u64 v[128:129], v[128:129], 0, s[8:9]
	global_store_short v[128:129], v131, off offset:352
	v_lshl_add_u64 v[128:129], v[128:129], 0, s[8:9]
	s_mov_b64 s[8:9], 0
	global_store_short_d16_hi v[128:129], v131, off offset:352
.LBB0_903:
	v_readlane_b32 s64, v253, 62
	s_andn2_b64 vcc, exec, s[8:9]
	v_readlane_b32 s65, v253, 63
	s_movk_i32 s67, 0x600
	s_cbranch_vccnz .LBB0_905
	s_lshl_b32 s2, s41, 1
	v_lshl_add_u64 v[128:129], v[134:135], 0, s[2:3]
	v_lshlrev_b32_e32 v152, 1, v190
	v_lshl_add_u64 v[128:129], v[128:129], 0, v[152:153]
	v_add_co_u32_e32 v128, vcc, 0xac00000, v128
	s_nop 1
	v_addc_co_u32_e32 v129, vcc, 0, v129, vcc
	global_store_dwordx2 v[128:129], v[130:131], off offset:160

.LBB0_906:
	s_andn2_b64 vcc, exec, s[8:9]
	s_cbranch_vccnz .LBB0_1003
	s_mov_b64 s[8:9], -1
	s_and_b64 vcc, exec, s[36:37]
	s_cbranch_vccz .LBB0_909
	v_ashrrev_i32_e32 v173, 31, v172
	v_readlane_b32 s8, v254, 54
	v_lshlrev_b64 v[128:129], 5, v[172:173]
	v_readlane_b32 s9, v254, 55
	s_nop 1
	v_lshl_add_u64 v[132:133], s[8:9], 0, v[128:129]
	global_load_dwordx4 v[128:131], v[132:133], off
	s_nop 0
	global_load_dwordx4 v[132:135], v[132:133], off offset:16
	s_mov_b64 s[8:9], 0
	s_waitcnt vmcnt(0) lgkmcnt(0)
	v_mov_b32_e32 v136, v128
	v_mov_b32_e32 v137, v132
	v_mov_b32_e32 v132, v129
	v_mov_b32_e32 v128, v130
	v_mov_b32_e32 v129, v134
	v_mov_b32_e32 v134, v131
	v_pk_add_f32 v[130:131], v[136:137], v[132:133]
	v_pk_add_f32 v[128:129], v[128:129], v[134:135]
	s_nop 0
	v_pk_add_f32 v[128:129], v[130:131], v[128:129]
	s_nop 0
	v_add_f32_e32 v128, v128, v129
	v_fmamk_f32 v128, v128, 0x3b000000, v207
	v_mul_f32_e32 v129, 0x4b800000, v128
	v_cmp_gt_f32_e32 vcc, s68, v128
	s_nop 1
	v_cndmask_b32_e32 v128, v128, v129, vcc
	v_rsq_f32_e32 v128, v128
	s_nop 0
	v_mul_f32_e32 v129, 0x45800000, v128
	v_cndmask_b32_e32 v128, v128, v129, vcc
	v_mul_f32_e32 v130, 0x3e16c740, v128

.LBB0_914:
	s_or_b64 exec, exec, s[10:11]
	v_lshl_add_u64 v[144:145], v[132:133], 0, s[2:3]
	v_lshlrev_b32_e32 v152, 1, v190
	v_lshl_add_u64 v[144:145], v[144:145], 0, v[152:153]
	v_cvt_pk_bf16_f32 v150, v150, v151
	v_cvt_pk_bf16_f32 v151, v146, v147
	v_cvt_pk_bf16_f32 v146, v174, v175
	v_cvt_pk_bf16_f32 v147, v148, v149
	global_store_dwordx2 v[144:145], v[150:151], off offset:128
	global_store_dwordx2 v[144:145], v[146:147], off offset:160
	v_pk_mul_f32 v[146:147], v[118:119], v[142:143]
	v_pk_mul_f32 v[148:149], v[116:117], v[130:131]
	v_pk_mul_f32 v[142:143], v[114:115], v[142:143]
	v_pk_mul_f32 v[150:151], v[112:113], v[130:131]
	s_and_saveexec_b64 s[10:11], vcc
	s_cbranch_execz .LBB0_916
	v_pk_mul_f32 v[154:155], v[128:129], v[150:151]
	v_pk_mul_f32 v[150:151], v[138:139], v[150:151]
	v_mul_f32_e32 v178, v176, v142
	v_mul_f32_e32 v194, v173, v142
	v_mov_b32_e32 v142, v147
	v_pk_fma_f32 v[138:139], v[138:139], v[148:149], v[154:155] neg_lo:[0,0,1] neg_hi:[0,0,1]
	v_mov_b32_e32 v154, v141
	v_mov_b32_e32 v155, v140
	v_mul_f32_e32 v174, v173, v146
	v_mul_f32_e32 v176, v176, v146
	v_pk_mul_f32 v[146:147], v[140:141], v[142:143]
	v_pk_mul_f32 v[140:141], v[154:155], v[142:143]
	v_mov_b32_e32 v175, v146
	v_mov_b32_e32 v179, v147
	v_mov_b32_e32 v177, v140
	v_mov_b32_e32 v195, v141
	v_pk_add_f32 v[146:147], v[174:175], v[178:179] neg_lo:[0,1] neg_hi:[0,1]
	v_pk_fma_f32 v[150:151], v[128:129], v[148:149], v[150:151]
	v_pk_add_f32 v[142:143], v[176:177], v[194:195]
	v_mov_b32_e32 v148, v138
	v_mov_b32_e32 v149, v139
.LBB0_916:
	s_or_b64 exec, exec, s[10:11]
	v_cvt_pk_bf16_f32 v128, v148, v149
	v_cvt_pk_bf16_f32 v129, v146, v147
	global_store_dwordx2 v[144:145], v[128:129], off offset:896
	v_cvt_pk_bf16_f32 v128, v150, v151
	v_cvt_pk_bf16_f32 v129, v142, v143
	s_mov_b64 s[10:11], 0
	global_store_dwordx2 v[144:145], v[128:129], off offset:928
.LBB0_917:
	v_and_b32_e32 v128, 44, v187
	s_and_b64 vcc, exec, s[10:11]
	v_lshlrev_b32_e32 v128, 1, v128
	s_cbranch_vccz .LBB0_919
	s_lshl_b32 s12, s14, 8
	s_or_b32 s10, s41, s12
	s_ashr_i32 s10, s10, 6
	v_mov_b32_e32 v138, v130
	v_mov_b32_e32 v139, v130
	s_mulk_i32 s10, 0x60
	v_pk_mul_f32 v[140:141], v[126:127], v[138:139]
	s_ashr_i32 s11, s10, 31
	v_cvt_pk_bf16_f32 v136, v136, v137
	v_cvt_pk_bf16_f32 v137, v140, v141
	v_lshl_add_u64 v[140:141], s[10:11], 1, v[132:133]
	v_mov_b32_e32 v129, v153
	v_lshl_add_u64 v[140:141], v[140:141], 0, v[128:129]
	global_store_dwordx2 v[140:141], v[136:137], off
	v_pk_mul_f32 v[136:137], v[122:123], v[138:139]
	v_cvt_pk_bf16_f32 v134, v134, v135
	v_cvt_pk_bf16_f32 v135, v136, v137
	global_store_dwordx2 v[140:141], v[134:135], off offset:32
	v_pk_mul_f32 v[134:135], v[118:119], v[138:139]
	v_pk_mul_f32 v[136:137], v[116:117], v[130:131]
	v_or_b32_e32 v129, s12, v187
	v_cvt_pk_bf16_f32 v136, v136, v137
	v_cvt_pk_bf16_f32 v137, v134, v135
	global_store_dwordx2 v[140:141], v[136:137], off offset:384
	v_or_b32_e32 v136, 0x90, v129
	v_pk_mul_f32 v[134:135], v[114:115], v[138:139]
	v_pk_mul_f32 v[130:131], v[112:113], v[130:131]
	s_movk_i32 s10, 0x60
	v_cvt_pk_bf16_f32 v130, v130, v131
	v_cvt_pk_bf16_f32 v131, v134, v135
	v_ashrrev_i32_e32 v134, 6, v136
	v_mul_lo_u32 v134, v134, s10
	v_ashrrev_i32_e32 v135, 31, v134
	v_bitop3_b32 v129, v129, 60, v223 bitop3:0xc8
	v_lshl_add_u64 v[132:133], v[134:135], 1, v[132:133]
	v_lshlrev_b32_e32 v152, 1, v129
	v_lshl_add_u64 v[132:133], v[132:133], 0, v[152:153]
	global_store_dwordx2 v[132:133], v[130:131], off
.LBB0_919:
	v_or_b32_e32 v138, 16, v172
	v_cndmask_b32_e64 v129, 0, 1, s[36:37]
	s_mov_b64 s[12:13], -1
	v_cmp_ne_u32_e64 s[10:11], 1, v129
	s_andn2_b64 vcc, exec, s[36:37]
	v_ashrrev_i32_e32 v139, 31, v138
	s_cbranch_vccnz .LBB0_921
	v_readlane_b32 s12, v254, 54
	v_lshlrev_b64 v[130:131], 5, v[138:139]
	v_readlane_b32 s13, v254, 55
	s_nop 1
	v_lshl_add_u64 v[134:135], s[12:13], 0, v[130:131]
	global_load_dwordx4 v[130:133], v[134:135], off
	s_nop 0
	global_load_dwordx4 v[134:137], v[134:135], off offset:16
	s_mov_b64 s[12:13], 0
	s_waitcnt vmcnt(0) lgkmcnt(0)
	v_mov_b32_e32 v140, v130
	v_mov_b32_e32 v141, v134
	v_mov_b32_e32 v134, v131
	v_mov_b32_e32 v130, v132
	v_mov_b32_e32 v131, v136
	v_mov_b32_e32 v136, v133
	v_pk_add_f32 v[132:133], v[140:141], v[134:135]
	v_pk_add_f32 v[130:131], v[130:131], v[136:137]
	s_nop 0
	v_pk_add_f32 v[130:131], v[132:133], v[130:131]
	s_nop 0
	v_add_f32_e32 v129, v130, v131
	v_fmamk_f32 v129, v129, 0x3b000000, v207
	v_mul_f32_e32 v130, 0x4b800000, v129
	v_cmp_gt_f32_e32 vcc, s68, v129
	s_nop 1
	v_cndmask_b32_e32 v129, v129, v130, vcc
	v_rsq_f32_e32 v129, v129
	s_nop 0
	v_mul_f32_e32 v130, 0x45800000, v129
	v_cndmask_b32_e32 v129, v129, v130, vcc
	v_mul_f32_e32 v130, 0x3e16c740, v129

.LBB0_926:
	s_or_b64 exec, exec, s[20:21]
	v_lshl_add_u64 v[146:147], v[132:133], 0, s[2:3]
	v_lshlrev_b32_e32 v152, 1, v190
	v_lshl_add_u64 v[146:147], v[146:147], 0, v[152:153]
	v_cvt_pk_bf16_f32 v155, v148, v149
	v_cvt_pk_bf16_f32 v148, v176, v177
	v_cvt_pk_bf16_f32 v149, v150, v151
	v_cvt_pk_bf16_f32 v154, v174, v175
	global_store_dwordx2 v[146:147], v[148:149], off offset:160
	v_pk_mul_f32 v[148:149], v[102:103], v[144:145]
	v_pk_mul_f32 v[150:151], v[100:101], v[130:131]
	v_pk_mul_f32 v[144:145], v[98:99], v[144:145]
	v_pk_mul_f32 v[174:175], v[96:97], v[130:131]
	global_store_dwordx2 v[146:147], v[154:155], off offset:128
	s_and_saveexec_b64 s[20:21], vcc
	s_cbranch_execz .LBB0_928
	v_pk_mul_f32 v[154:155], v[138:139], v[174:175]
	v_pk_mul_f32 v[174:175], v[140:141], v[174:175]
	v_mul_f32_e32 v194, v178, v144
	v_mul_f32_e32 v196, v129, v144
	v_mov_b32_e32 v144, v149
	v_pk_fma_f32 v[140:141], v[140:141], v[150:151], v[154:155] neg_lo:[0,0,1] neg_hi:[0,0,1]
	v_mov_b32_e32 v154, v143
	v_mov_b32_e32 v155, v142
	v_mul_f32_e32 v176, v129, v148
	v_mul_f32_e32 v178, v178, v148
	v_pk_mul_f32 v[148:149], v[142:143], v[144:145]
	v_pk_mul_f32 v[142:143], v[154:155], v[144:145]
	v_mov_b32_e32 v177, v148
	v_mov_b32_e32 v195, v149
	v_mov_b32_e32 v179, v142
	v_mov_b32_e32 v197, v143
	v_pk_add_f32 v[148:149], v[176:177], v[194:195] neg_lo:[0,1] neg_hi:[0,1]
	v_pk_fma_f32 v[174:175], v[138:139], v[150:151], v[174:175]
	v_pk_add_f32 v[144:145], v[178:179], v[196:197]
	v_mov_b32_e32 v150, v140
	v_mov_b32_e32 v151, v141
.LBB0_928:
	s_or_b64 exec, exec, s[20:21]
	v_cvt_pk_bf16_f32 v138, v150, v151
	v_cvt_pk_bf16_f32 v139, v148, v149
	global_store_dwordx2 v[146:147], v[138:139], off offset:896
	v_cvt_pk_bf16_f32 v138, v174, v175
	v_cvt_pk_bf16_f32 v139, v144, v145
	s_mov_b64 s[22:23], 0
	global_store_dwordx2 v[146:147], v[138:139], off offset:928
.LBB0_929:
	s_and_b64 vcc, exec, s[22:23]
	s_cbranch_vccz .LBB0_931
	s_lshl_b32 s22, s14, 8
	s_or_b32 s20, s41, s22
	s_ashr_i32 s20, s20, 6
	v_mov_b32_e32 v138, v130
	v_mov_b32_e32 v139, v130
	s_mulk_i32 s20, 0x60
	v_pk_mul_f32 v[140:141], v[110:111], v[138:139]
	s_ashr_i32 s21, s20, 31
	v_cvt_pk_bf16_f32 v136, v136, v137
	v_cvt_pk_bf16_f32 v137, v140, v141
	v_lshl_add_u64 v[140:141], s[20:21], 1, v[132:133]
	v_mov_b32_e32 v129, v153
	v_lshl_add_u64 v[140:141], v[140:141], 0, v[128:129]
	global_store_dwordx2 v[140:141], v[136:137], off
	v_pk_mul_f32 v[136:137], v[106:107], v[138:139]
	v_cvt_pk_bf16_f32 v134, v134, v135
	v_cvt_pk_bf16_f32 v135, v136, v137
	global_store_dwordx2 v[140:141], v[134:135], off offset:32
	v_pk_mul_f32 v[134:135], v[102:103], v[138:139]
	v_pk_mul_f32 v[136:137], v[100:101], v[130:131]
	v_or_b32_e32 v129, s22, v187
	v_cvt_pk_bf16_f32 v136, v136, v137
	v_cvt_pk_bf16_f32 v137, v134, v135
	global_store_dwordx2 v[140:141], v[136:137], off offset:384
	v_or_b32_e32 v136, 0x90, v129
	v_pk_mul_f32 v[134:135], v[98:99], v[138:139]
	v_pk_mul_f32 v[130:131], v[96:97], v[130:131]
	s_movk_i32 s20, 0x60
	v_cvt_pk_bf16_f32 v130, v130, v131
	v_cvt_pk_bf16_f32 v131, v134, v135
	v_ashrrev_i32_e32 v134, 6, v136
	v_mul_lo_u32 v134, v134, s20
	v_ashrrev_i32_e32 v135, 31, v134
	v_bitop3_b32 v129, v129, 60, v223 bitop3:0xc8
	v_lshl_add_u64 v[132:133], v[134:135], 1, v[132:133]
	v_lshlrev_b32_e32 v152, 1, v129
	v_lshl_add_u64 v[132:133], v[132:133], 0, v[152:153]
	global_store_dwordx2 v[132:133], v[130:131], off
.LBB0_931:
	v_or_b32_e32 v138, 32, v172
	s_mov_b64 s[20:21], -1
	s_and_b64 vcc, exec, s[10:11]
	v_ashrrev_i32_e32 v139, 31, v138
	s_cbranch_vccnz .LBB0_933
	v_readlane_b32 s20, v254, 54
	v_lshlrev_b64 v[130:131], 5, v[138:139]
	v_readlane_b32 s21, v254, 55
	s_nop 1
	v_lshl_add_u64 v[134:135], s[20:21], 0, v[130:131]
	global_load_dwordx4 v[130:133], v[134:135], off
	s_nop 0
	global_load_dwordx4 v[134:137], v[134:135], off offset:16
	s_mov_b64 s[20:21], 0
	s_waitcnt vmcnt(0) lgkmcnt(0)
	v_mov_b32_e32 v140, v130
	v_mov_b32_e32 v141, v134
	v_mov_b32_e32 v134, v131
	v_mov_b32_e32 v130, v132
	v_mov_b32_e32 v131, v136
	v_mov_b32_e32 v136, v133
	v_pk_add_f32 v[132:133], v[140:141], v[134:135]
	v_pk_add_f32 v[130:131], v[130:131], v[136:137]
	s_nop 0
	v_pk_add_f32 v[130:131], v[132:133], v[130:131]
	s_nop 0
	v_add_f32_e32 v129, v130, v131
	v_fmamk_f32 v129, v129, 0x3b000000, v207
	v_mul_f32_e32 v130, 0x4b800000, v129
	v_cmp_gt_f32_e32 vcc, s68, v129
	s_nop 1
	v_cndmask_b32_e32 v129, v129, v130, vcc
	v_rsq_f32_e32 v129, v129
	s_nop 0
	v_mul_f32_e32 v130, 0x45800000, v129
	v_cndmask_b32_e32 v129, v129, v130, vcc
	v_mul_f32_e32 v130, 0x3e16c740, v129

.LBB0_938:
	s_or_b64 exec, exec, s[20:21]
	v_lshl_add_u64 v[146:147], v[132:133], 0, s[2:3]
	v_lshlrev_b32_e32 v152, 1, v190
	v_lshl_add_u64 v[146:147], v[146:147], 0, v[152:153]
	v_cvt_pk_bf16_f32 v155, v148, v149
	v_cvt_pk_bf16_f32 v148, v176, v177
	v_cvt_pk_bf16_f32 v149, v150, v151
	v_cvt_pk_bf16_f32 v154, v174, v175
	global_store_dwordx2 v[146:147], v[148:149], off offset:160
	v_pk_mul_f32 v[148:149], v[86:87], v[144:145]
	v_pk_mul_f32 v[150:151], v[84:85], v[130:131]
	v_pk_mul_f32 v[144:145], v[82:83], v[144:145]
	v_pk_mul_f32 v[174:175], v[80:81], v[130:131]
	global_store_dwordx2 v[146:147], v[154:155], off offset:128
	s_and_saveexec_b64 s[20:21], vcc
	s_cbranch_execz .LBB0_940
	v_pk_mul_f32 v[154:155], v[138:139], v[174:175]
	v_pk_mul_f32 v[174:175], v[140:141], v[174:175]
	v_mul_f32_e32 v194, v178, v144
	v_mul_f32_e32 v196, v129, v144
	v_mov_b32_e32 v144, v149
	v_pk_fma_f32 v[140:141], v[140:141], v[150:151], v[154:155] neg_lo:[0,0,1] neg_hi:[0,0,1]
	v_mov_b32_e32 v154, v143
	v_mov_b32_e32 v155, v142
	v_mul_f32_e32 v176, v129, v148
	v_mul_f32_e32 v178, v178, v148
	v_pk_mul_f32 v[148:149], v[142:143], v[144:145]
	v_pk_mul_f32 v[142:143], v[154:155], v[144:145]
	v_mov_b32_e32 v177, v148
	v_mov_b32_e32 v195, v149
	v_mov_b32_e32 v179, v142
	v_mov_b32_e32 v197, v143
	v_pk_add_f32 v[148:149], v[176:177], v[194:195] neg_lo:[0,1] neg_hi:[0,1]
	v_pk_fma_f32 v[174:175], v[138:139], v[150:151], v[174:175]
	v_pk_add_f32 v[144:145], v[178:179], v[196:197]
	v_mov_b32_e32 v150, v140
	v_mov_b32_e32 v151, v141
.LBB0_940:
	s_or_b64 exec, exec, s[20:21]
	v_cvt_pk_bf16_f32 v138, v150, v151
	v_cvt_pk_bf16_f32 v139, v148, v149
	global_store_dwordx2 v[146:147], v[138:139], off offset:896
	v_cvt_pk_bf16_f32 v138, v174, v175
	v_cvt_pk_bf16_f32 v139, v144, v145
	s_mov_b64 s[20:21], 0
	global_store_dwordx2 v[146:147], v[138:139], off offset:928
.LBB0_941:
	s_and_b64 vcc, exec, s[20:21]
	s_cbranch_vccz .LBB0_943
	s_lshl_b32 s22, s14, 8
	s_or_b32 s20, s41, s22
	s_ashr_i32 s20, s20, 6
	v_mov_b32_e32 v138, v130
	v_mov_b32_e32 v139, v130
	s_mulk_i32 s20, 0x60
	v_pk_mul_f32 v[140:141], v[94:95], v[138:139]
	s_ashr_i32 s21, s20, 31
	v_cvt_pk_bf16_f32 v136, v136, v137
	v_cvt_pk_bf16_f32 v137, v140, v141
	v_lshl_add_u64 v[140:141], s[20:21], 1, v[132:133]
	v_mov_b32_e32 v129, v153
	v_lshl_add_u64 v[140:141], v[140:141], 0, v[128:129]
	global_store_dwordx2 v[140:141], v[136:137], off
	v_pk_mul_f32 v[136:137], v[90:91], v[138:139]
	v_cvt_pk_bf16_f32 v134, v134, v135
	v_cvt_pk_bf16_f32 v135, v136, v137
	global_store_dwordx2 v[140:141], v[134:135], off offset:32
	v_pk_mul_f32 v[134:135], v[86:87], v[138:139]
	v_pk_mul_f32 v[136:137], v[84:85], v[130:131]
	v_or_b32_e32 v129, s22, v187
	v_cvt_pk_bf16_f32 v136, v136, v137
	v_cvt_pk_bf16_f32 v137, v134, v135
	global_store_dwordx2 v[140:141], v[136:137], off offset:384
	v_or_b32_e32 v136, 0x90, v129
	v_pk_mul_f32 v[134:135], v[82:83], v[138:139]
	v_pk_mul_f32 v[130:131], v[80:81], v[130:131]
	s_movk_i32 s20, 0x60
	v_cvt_pk_bf16_f32 v130, v130, v131
	v_cvt_pk_bf16_f32 v131, v134, v135
	v_ashrrev_i32_e32 v134, 6, v136
	v_mul_lo_u32 v134, v134, s20
	v_ashrrev_i32_e32 v135, 31, v134
	v_bitop3_b32 v129, v129, 60, v223 bitop3:0xc8
	v_lshl_add_u64 v[132:133], v[134:135], 1, v[132:133]
	v_lshlrev_b32_e32 v152, 1, v129
	v_lshl_add_u64 v[132:133], v[132:133], 0, v[152:153]
	global_store_dwordx2 v[132:133], v[130:131], off
.LBB0_943:
	v_or_b32_e32 v138, 48, v172
	s_mov_b64 s[20:21], -1
	s_and_b64 vcc, exec, s[10:11]
	v_ashrrev_i32_e32 v139, 31, v138
	s_cbranch_vccnz .LBB0_945
	v_readlane_b32 s20, v254, 54
	v_lshlrev_b64 v[130:131], 5, v[138:139]
	v_readlane_b32 s21, v254, 55
	s_nop 1
	v_lshl_add_u64 v[134:135], s[20:21], 0, v[130:131]
	global_load_dwordx4 v[130:133], v[134:135], off
	s_nop 0
	global_load_dwordx4 v[134:137], v[134:135], off offset:16
	s_mov_b64 s[20:21], 0
	s_waitcnt vmcnt(0) lgkmcnt(0)
	v_mov_b32_e32 v140, v130
	v_mov_b32_e32 v141, v134
	v_mov_b32_e32 v134, v131
	v_mov_b32_e32 v130, v132
	v_mov_b32_e32 v131, v136
	v_mov_b32_e32 v136, v133
	v_pk_add_f32 v[132:133], v[140:141], v[134:135]
	v_pk_add_f32 v[130:131], v[130:131], v[136:137]
	s_nop 0
	v_pk_add_f32 v[130:131], v[132:133], v[130:131]
	s_nop 0
	v_add_f32_e32 v129, v130, v131
	v_fmamk_f32 v129, v129, 0x3b000000, v207
	v_mul_f32_e32 v130, 0x4b800000, v129
	v_cmp_gt_f32_e32 vcc, s68, v129
	s_nop 1
	v_cndmask_b32_e32 v129, v129, v130, vcc
	v_rsq_f32_e32 v129, v129
	s_nop 0
	v_mul_f32_e32 v130, 0x45800000, v129
	v_cndmask_b32_e32 v129, v129, v130, vcc
	v_mul_f32_e32 v130, 0x3e16c740, v129

.LBB0_950:
	s_or_b64 exec, exec, s[20:21]
	v_lshl_add_u64 v[146:147], v[132:133], 0, s[2:3]
	v_lshlrev_b32_e32 v152, 1, v190
	v_lshl_add_u64 v[146:147], v[146:147], 0, v[152:153]
	v_cvt_pk_bf16_f32 v155, v148, v149
	v_cvt_pk_bf16_f32 v148, v176, v177
	v_cvt_pk_bf16_f32 v149, v150, v151
	v_cvt_pk_bf16_f32 v154, v174, v175
	global_store_dwordx2 v[146:147], v[148:149], off offset:160
	v_pk_mul_f32 v[148:149], v[70:71], v[144:145]
	v_pk_mul_f32 v[150:151], v[68:69], v[130:131]
	v_pk_mul_f32 v[144:145], v[66:67], v[144:145]
	v_pk_mul_f32 v[174:175], v[64:65], v[130:131]
	global_store_dwordx2 v[146:147], v[154:155], off offset:128
	s_and_saveexec_b64 s[20:21], vcc
	s_cbranch_execz .LBB0_952
	v_pk_mul_f32 v[154:155], v[138:139], v[174:175]
	v_pk_mul_f32 v[174:175], v[140:141], v[174:175]
	v_mul_f32_e32 v196, v178, v144
	v_mul_f32_e32 v198, v129, v144
	v_mov_b32_e32 v144, v149
	v_pk_fma_f32 v[140:141], v[140:141], v[150:151], v[154:155] neg_lo:[0,0,1] neg_hi:[0,0,1]
	v_mov_b32_e32 v154, v143
	v_mov_b32_e32 v155, v142
	v_mul_f32_e32 v176, v129, v148
	v_mul_f32_e32 v178, v178, v148
	v_pk_mul_f32 v[148:149], v[142:143], v[144:145]
	v_pk_mul_f32 v[142:143], v[154:155], v[144:145]
	v_mov_b32_e32 v177, v148
	v_mov_b32_e32 v197, v149
	v_mov_b32_e32 v179, v142
	v_mov_b32_e32 v199, v143
	v_pk_add_f32 v[148:149], v[176:177], v[196:197] neg_lo:[0,1] neg_hi:[0,1]
	v_pk_fma_f32 v[174:175], v[138:139], v[150:151], v[174:175]
	v_pk_add_f32 v[144:145], v[178:179], v[198:199]
	v_mov_b32_e32 v150, v140
	v_mov_b32_e32 v151, v141

.LBB0_953:
	s_and_b64 vcc, exec, s[20:21]
	s_cbranch_vccz .LBB0_955
	s_lshl_b32 s22, s14, 8
	s_or_b32 s20, s41, s22
	s_ashr_i32 s20, s20, 6
	v_mov_b32_e32 v138, v130
	v_mov_b32_e32 v139, v130
	s_mulk_i32 s20, 0x60
	v_pk_mul_f32 v[140:141], v[78:79], v[138:139]
	s_ashr_i32 s21, s20, 31
	v_cvt_pk_bf16_f32 v136, v136, v137
	v_cvt_pk_bf16_f32 v137, v140, v141
	v_lshl_add_u64 v[140:141], s[20:21], 1, v[132:133]
	v_mov_b32_e32 v129, v153
	v_lshl_add_u64 v[140:141], v[140:141], 0, v[128:129]
	global_store_dwordx2 v[140:141], v[136:137], off
	v_pk_mul_f32 v[136:137], v[74:75], v[138:139]
	v_cvt_pk_bf16_f32 v134, v134, v135
	v_cvt_pk_bf16_f32 v135, v136, v137
	global_store_dwordx2 v[140:141], v[134:135], off offset:32
	v_pk_mul_f32 v[134:135], v[70:71], v[138:139]
	v_pk_mul_f32 v[136:137], v[68:69], v[130:131]
	v_or_b32_e32 v129, s22, v187
	v_cvt_pk_bf16_f32 v136, v136, v137
	v_cvt_pk_bf16_f32 v137, v134, v135
	global_store_dwordx2 v[140:141], v[136:137], off offset:384
	v_or_b32_e32 v136, 0x90, v129
	v_pk_mul_f32 v[134:135], v[66:67], v[138:139]
	v_pk_mul_f32 v[130:131], v[64:65], v[130:131]
	s_movk_i32 s20, 0x60
	v_cvt_pk_bf16_f32 v130, v130, v131
	v_cvt_pk_bf16_f32 v131, v134, v135
	v_ashrrev_i32_e32 v134, 6, v136
	v_mul_lo_u32 v134, v134, s20
	v_ashrrev_i32_e32 v135, 31, v134
	v_bitop3_b32 v129, v129, 60, v223 bitop3:0xc8
	v_lshl_add_u64 v[132:133], v[134:135], 1, v[132:133]
	v_lshlrev_b32_e32 v152, 1, v129
	v_lshl_add_u64 v[132:133], v[132:133], 0, v[152:153]
	global_store_dwordx2 v[132:133], v[130:131], off
.LBB0_955:
	v_add_u32_e32 v130, 0x80, v172
	s_mov_b64 s[20:21], -1
	s_and_b64 vcc, exec, s[10:11]
	v_ashrrev_i32_e32 v131, 31, v130
	s_cbranch_vccnz .LBB0_957
	v_readlane_b32 s20, v254, 54
	v_lshlrev_b64 v[132:133], 5, v[130:131]
	v_readlane_b32 s21, v254, 55
	s_nop 1
	v_lshl_add_u64 v[136:137], s[20:21], 0, v[132:133]
	global_load_dwordx4 v[132:135], v[136:137], off
	s_nop 0
	global_load_dwordx4 v[136:139], v[136:137], off offset:16
	s_mov_b64 s[20:21], 0
	s_waitcnt vmcnt(0) lgkmcnt(0)
	v_mov_b32_e32 v140, v132
	v_mov_b32_e32 v141, v136
	v_mov_b32_e32 v136, v133
	v_mov_b32_e32 v132, v134
	v_mov_b32_e32 v133, v138
	v_mov_b32_e32 v138, v135
	v_pk_add_f32 v[134:135], v[140:141], v[136:137]
	v_pk_add_f32 v[132:133], v[132:133], v[138:139]
	s_nop 0
	v_pk_add_f32 v[132:133], v[134:135], v[132:133]
	s_nop 0
	v_add_f32_e32 v129, v132, v133
	v_fmamk_f32 v129, v129, 0x3b000000, v207
	v_mul_f32_e32 v132, 0x4b800000, v129
	v_cmp_gt_f32_e32 vcc, s68, v129
	s_nop 1
	v_cndmask_b32_e32 v129, v129, v132, vcc
	v_rsq_f32_e32 v129, v129
	s_nop 0
	v_mul_f32_e32 v132, 0x45800000, v129
	v_cndmask_b32_e32 v129, v129, v132, vcc
	v_mul_f32_e32 v132, 0x3e16c740, v129

.LBB0_962:
	s_or_b64 exec, exec, s[20:21]
	v_lshl_add_u64 v[148:149], v[134:135], 0, s[2:3]
	v_lshlrev_b32_e32 v152, 1, v190
	v_lshl_add_u64 v[148:149], v[148:149], 0, v[152:153]
	v_cvt_pk_bf16_f32 v155, v150, v151
	v_cvt_pk_bf16_f32 v150, v178, v179
	v_cvt_pk_bf16_f32 v151, v174, v175
	v_cvt_pk_bf16_f32 v154, v176, v177
	global_store_dwordx2 v[148:149], v[150:151], off offset:160
	v_pk_mul_f32 v[150:151], v[54:55], v[146:147]
	v_pk_mul_f32 v[174:175], v[52:53], v[132:133]
	v_pk_mul_f32 v[146:147], v[50:51], v[146:147]
	v_pk_mul_f32 v[176:177], v[48:49], v[132:133]
	global_store_dwordx2 v[148:149], v[154:155], off offset:128
	s_and_saveexec_b64 s[20:21], vcc
	s_cbranch_execz .LBB0_964
	v_pk_mul_f32 v[154:155], v[140:141], v[176:177]
	v_pk_mul_f32 v[176:177], v[142:143], v[176:177]
	v_mul_f32_e32 v196, v131, v146
	v_mul_f32_e32 v200, v129, v146
	v_mov_b32_e32 v146, v151
	v_pk_fma_f32 v[142:143], v[142:143], v[174:175], v[154:155] neg_lo:[0,0,1] neg_hi:[0,0,1]
	v_mov_b32_e32 v154, v145
	v_mov_b32_e32 v155, v144
	v_mul_f32_e32 v178, v129, v150
	v_mul_f32_e32 v198, v131, v150
	v_pk_mul_f32 v[150:151], v[144:145], v[146:147]
	v_pk_mul_f32 v[144:145], v[154:155], v[146:147]
	v_mov_b32_e32 v179, v150
	v_mov_b32_e32 v197, v151
	v_mov_b32_e32 v199, v144
	v_mov_b32_e32 v201, v145
	v_pk_add_f32 v[150:151], v[178:179], v[196:197] neg_lo:[0,1] neg_hi:[0,1]
	v_pk_fma_f32 v[176:177], v[140:141], v[174:175], v[176:177]
	v_pk_add_f32 v[146:147], v[198:199], v[200:201]
	v_mov_b32_e32 v174, v142
	v_mov_b32_e32 v175, v143
.LBB0_964:
	s_or_b64 exec, exec, s[20:21]
	v_cvt_pk_bf16_f32 v140, v174, v175
	v_cvt_pk_bf16_f32 v141, v150, v151
	global_store_dwordx2 v[148:149], v[140:141], off offset:896
	v_cvt_pk_bf16_f32 v140, v176, v177
	v_cvt_pk_bf16_f32 v141, v146, v147
	s_mov_b64 s[20:21], 0
	global_store_dwordx2 v[148:149], v[140:141], off offset:928
.LBB0_965:
	s_and_b64 vcc, exec, s[20:21]
	s_cbranch_vccz .LBB0_967
	s_lshl_b32 s22, s14, 8
	s_or_b32 s20, s41, s22
	s_ashr_i32 s20, s20, 6
	v_mov_b32_e32 v140, v132
	v_mov_b32_e32 v141, v132
	s_mulk_i32 s20, 0x60
	v_pk_mul_f32 v[142:143], v[62:63], v[140:141]
	s_ashr_i32 s21, s20, 31
	v_cvt_pk_bf16_f32 v138, v138, v139
	v_cvt_pk_bf16_f32 v139, v142, v143
	v_lshl_add_u64 v[142:143], s[20:21], 1, v[134:135]
	v_mov_b32_e32 v129, v153
	v_lshl_add_u64 v[142:143], v[142:143], 0, v[128:129]
	global_store_dwordx2 v[142:143], v[138:139], off
	v_pk_mul_f32 v[138:139], v[58:59], v[140:141]
	v_cvt_pk_bf16_f32 v136, v136, v137
	v_cvt_pk_bf16_f32 v137, v138, v139
	v_or_b32_e32 v129, s22, v187
	global_store_dwordx2 v[142:143], v[136:137], off offset:32
	v_pk_mul_f32 v[136:137], v[54:55], v[140:141]
	v_pk_mul_f32 v[138:139], v[52:53], v[132:133]
	v_or_b32_e32 v131, 0x90, v129
	v_cvt_pk_bf16_f32 v138, v138, v139
	v_cvt_pk_bf16_f32 v139, v136, v137
	v_pk_mul_f32 v[136:137], v[50:51], v[140:141]
	v_pk_mul_f32 v[132:133], v[48:49], v[132:133]
	v_ashrrev_i32_e32 v131, 6, v131
	s_movk_i32 s20, 0x60
	v_cvt_pk_bf16_f32 v132, v132, v133
	v_cvt_pk_bf16_f32 v133, v136, v137
	v_mul_lo_u32 v136, v131, s20
	v_ashrrev_i32_e32 v137, 31, v136
	v_bitop3_b32 v129, v129, 60, v223 bitop3:0xc8
	v_lshl_add_u64 v[134:135], v[136:137], 1, v[134:135]
	v_lshlrev_b32_e32 v152, 1, v129
	v_lshl_add_u64 v[134:135], v[134:135], 0, v[152:153]
	global_store_dwordx2 v[142:143], v[138:139], off offset:384
	global_store_dwordx2 v[134:135], v[132:133], off
.LBB0_967:
	v_or_b32_e32 v140, 16, v130
	s_mov_b64 s[20:21], -1
	s_and_b64 vcc, exec, s[10:11]
	v_ashrrev_i32_e32 v141, 31, v140
	s_cbranch_vccnz .LBB0_969
	v_readlane_b32 s20, v254, 54
	v_lshlrev_b64 v[132:133], 5, v[140:141]
	v_readlane_b32 s21, v254, 55
	s_nop 1
	v_lshl_add_u64 v[136:137], s[20:21], 0, v[132:133]
	global_load_dwordx4 v[132:135], v[136:137], off
	s_nop 0
	global_load_dwordx4 v[136:139], v[136:137], off offset:16
	s_mov_b64 s[20:21], 0
	s_waitcnt vmcnt(0) lgkmcnt(0)
	v_mov_b32_e32 v142, v132
	v_mov_b32_e32 v143, v136
	v_mov_b32_e32 v136, v133
	v_mov_b32_e32 v132, v134
	v_mov_b32_e32 v133, v138
	v_mov_b32_e32 v138, v135
	v_pk_add_f32 v[134:135], v[142:143], v[136:137]
	v_pk_add_f32 v[132:133], v[132:133], v[138:139]
	s_nop 0
	v_pk_add_f32 v[132:133], v[134:135], v[132:133]
	s_nop 0
	v_add_f32_e32 v129, v132, v133
	v_fmamk_f32 v129, v129, 0x3b000000, v207
	v_mul_f32_e32 v131, 0x4b800000, v129
	v_cmp_gt_f32_e32 vcc, s68, v129
	s_nop 1
	v_cndmask_b32_e32 v129, v129, v131, vcc
	v_rsq_f32_e32 v129, v129
	s_nop 0
	v_mul_f32_e32 v131, 0x45800000, v129
	v_cndmask_b32_e32 v129, v129, v131, vcc
	v_mul_f32_e32 v132, 0x3e16c740, v129

.LBB0_974:
	s_or_b64 exec, exec, s[20:21]
	v_lshl_add_u64 v[148:149], v[134:135], 0, s[2:3]
	v_lshlrev_b32_e32 v152, 1, v190
	v_lshl_add_u64 v[148:149], v[148:149], 0, v[152:153]
	v_cvt_pk_bf16_f32 v155, v150, v151
	v_cvt_pk_bf16_f32 v150, v178, v179
	v_cvt_pk_bf16_f32 v151, v174, v175
	v_cvt_pk_bf16_f32 v154, v176, v177
	global_store_dwordx2 v[148:149], v[150:151], off offset:160
	v_pk_mul_f32 v[150:151], v[38:39], v[146:147]
	v_pk_mul_f32 v[174:175], v[36:37], v[132:133]
	v_pk_mul_f32 v[146:147], v[34:35], v[146:147]
	v_pk_mul_f32 v[176:177], v[32:33], v[132:133]
	global_store_dwordx2 v[148:149], v[154:155], off offset:128
	s_and_saveexec_b64 s[20:21], vcc
	s_cbranch_execz .LBB0_976
	v_pk_mul_f32 v[154:155], v[140:141], v[176:177]
	v_pk_mul_f32 v[176:177], v[142:143], v[176:177]
	v_mul_f32_e32 v196, v131, v146
	v_mul_f32_e32 v200, v129, v146
	v_mov_b32_e32 v146, v151
	v_pk_fma_f32 v[142:143], v[142:143], v[174:175], v[154:155] neg_lo:[0,0,1] neg_hi:[0,0,1]
	v_mov_b32_e32 v154, v145
	v_mov_b32_e32 v155, v144
	v_mul_f32_e32 v178, v129, v150
	v_mul_f32_e32 v198, v131, v150
	v_pk_mul_f32 v[150:151], v[144:145], v[146:147]
	v_pk_mul_f32 v[144:145], v[154:155], v[146:147]
	v_mov_b32_e32 v179, v150
	v_mov_b32_e32 v197, v151
	v_mov_b32_e32 v199, v144
	v_mov_b32_e32 v201, v145
	v_pk_add_f32 v[150:151], v[178:179], v[196:197] neg_lo:[0,1] neg_hi:[0,1]
	v_pk_fma_f32 v[176:177], v[140:141], v[174:175], v[176:177]
	v_pk_add_f32 v[146:147], v[198:199], v[200:201]
	v_mov_b32_e32 v174, v142
	v_mov_b32_e32 v175, v143

.LBB0_977:
	s_and_b64 vcc, exec, s[20:21]
	s_cbranch_vccz .LBB0_979
	s_lshl_b32 s22, s14, 8
	s_or_b32 s20, s41, s22
	s_ashr_i32 s20, s20, 6
	v_mov_b32_e32 v140, v132
	v_mov_b32_e32 v141, v132
	s_mulk_i32 s20, 0x60
	v_pk_mul_f32 v[142:143], v[46:47], v[140:141]
	s_ashr_i32 s21, s20, 31
	v_cvt_pk_bf16_f32 v138, v138, v139
	v_cvt_pk_bf16_f32 v139, v142, v143
	v_lshl_add_u64 v[142:143], s[20:21], 1, v[134:135]
	v_mov_b32_e32 v129, v153
	v_lshl_add_u64 v[142:143], v[142:143], 0, v[128:129]
	global_store_dwordx2 v[142:143], v[138:139], off
	v_pk_mul_f32 v[138:139], v[42:43], v[140:141]
	v_cvt_pk_bf16_f32 v136, v136, v137
	v_cvt_pk_bf16_f32 v137, v138, v139
	v_or_b32_e32 v129, s22, v187
	global_store_dwordx2 v[142:143], v[136:137], off offset:32
	v_pk_mul_f32 v[136:137], v[38:39], v[140:141]
	v_pk_mul_f32 v[138:139], v[36:37], v[132:133]
	v_or_b32_e32 v131, 0x90, v129
	v_cvt_pk_bf16_f32 v138, v138, v139
	v_cvt_pk_bf16_f32 v139, v136, v137
	v_pk_mul_f32 v[136:137], v[34:35], v[140:141]
	v_pk_mul_f32 v[132:133], v[32:33], v[132:133]
	v_ashrrev_i32_e32 v131, 6, v131
	s_movk_i32 s20, 0x60
	v_cvt_pk_bf16_f32 v132, v132, v133
	v_cvt_pk_bf16_f32 v133, v136, v137
	v_mul_lo_u32 v136, v131, s20
	v_ashrrev_i32_e32 v137, 31, v136
	v_bitop3_b32 v129, v129, 60, v223 bitop3:0xc8
	v_lshl_add_u64 v[134:135], v[136:137], 1, v[134:135]
	v_lshlrev_b32_e32 v152, 1, v129
	v_lshl_add_u64 v[134:135], v[134:135], 0, v[152:153]
	global_store_dwordx2 v[142:143], v[138:139], off offset:384
	global_store_dwordx2 v[134:135], v[132:133], off
.LBB0_979:
	v_or_b32_e32 v140, 32, v130
	s_mov_b64 s[20:21], -1
	s_and_b64 vcc, exec, s[10:11]
	v_ashrrev_i32_e32 v141, 31, v140
	s_cbranch_vccnz .LBB0_981
	v_readlane_b32 s20, v254, 54
	v_lshlrev_b64 v[132:133], 5, v[140:141]
	v_readlane_b32 s21, v254, 55
	s_nop 1
	v_lshl_add_u64 v[136:137], s[20:21], 0, v[132:133]
	global_load_dwordx4 v[132:135], v[136:137], off
	s_nop 0
	global_load_dwordx4 v[136:139], v[136:137], off offset:16
	s_mov_b64 s[20:21], 0
	s_waitcnt vmcnt(0) lgkmcnt(0)
	v_mov_b32_e32 v142, v132
	v_mov_b32_e32 v143, v136
	v_mov_b32_e32 v136, v133
	v_mov_b32_e32 v132, v134
	v_mov_b32_e32 v133, v138
	v_mov_b32_e32 v138, v135
	v_pk_add_f32 v[134:135], v[142:143], v[136:137]
	v_pk_add_f32 v[132:133], v[132:133], v[138:139]
	s_nop 0
	v_pk_add_f32 v[132:133], v[134:135], v[132:133]
	s_nop 0
	v_add_f32_e32 v129, v132, v133
	v_fmamk_f32 v129, v129, 0x3b000000, v207
	v_mul_f32_e32 v131, 0x4b800000, v129
	v_cmp_gt_f32_e32 vcc, s68, v129
	s_nop 1
	v_cndmask_b32_e32 v129, v129, v131, vcc
	v_rsq_f32_e32 v129, v129
	s_nop 0
	v_mul_f32_e32 v131, 0x45800000, v129
	v_cndmask_b32_e32 v129, v129, v131, vcc
	v_mul_f32_e32 v132, 0x3e16c740, v129

.LBB0_986:
	s_or_b64 exec, exec, s[20:21]
	v_lshl_add_u64 v[148:149], v[134:135], 0, s[2:3]
	v_lshlrev_b32_e32 v152, 1, v190
	v_lshl_add_u64 v[148:149], v[148:149], 0, v[152:153]
	v_cvt_pk_bf16_f32 v155, v150, v151
	v_cvt_pk_bf16_f32 v150, v178, v179
	v_cvt_pk_bf16_f32 v151, v174, v175
	v_cvt_pk_bf16_f32 v154, v176, v177
	global_store_dwordx2 v[148:149], v[150:151], off offset:160
	v_pk_mul_f32 v[150:151], v[22:23], v[146:147]
	v_pk_mul_f32 v[174:175], v[20:21], v[132:133]
	v_pk_mul_f32 v[146:147], v[18:19], v[146:147]
	v_pk_mul_f32 v[176:177], v[16:17], v[132:133]
	global_store_dwordx2 v[148:149], v[154:155], off offset:128
	s_and_saveexec_b64 s[20:21], vcc
	s_cbranch_execz .LBB0_988
	v_pk_mul_f32 v[154:155], v[140:141], v[176:177]
	v_pk_mul_f32 v[176:177], v[142:143], v[176:177]
	v_mul_f32_e32 v196, v131, v146
	v_mul_f32_e32 v200, v129, v146
	v_mov_b32_e32 v146, v151
	v_pk_fma_f32 v[142:143], v[142:143], v[174:175], v[154:155] neg_lo:[0,0,1] neg_hi:[0,0,1]
	v_mov_b32_e32 v154, v145
	v_mov_b32_e32 v155, v144
	v_mul_f32_e32 v178, v129, v150
	v_mul_f32_e32 v198, v131, v150
	v_pk_mul_f32 v[150:151], v[144:145], v[146:147]
	v_pk_mul_f32 v[144:145], v[154:155], v[146:147]
	v_mov_b32_e32 v179, v150
	v_mov_b32_e32 v197, v151
	v_mov_b32_e32 v199, v144
	v_mov_b32_e32 v201, v145
	v_pk_add_f32 v[150:151], v[178:179], v[196:197] neg_lo:[0,1] neg_hi:[0,1]
	v_pk_fma_f32 v[176:177], v[140:141], v[174:175], v[176:177]
	v_pk_add_f32 v[146:147], v[198:199], v[200:201]
	v_mov_b32_e32 v174, v142
	v_mov_b32_e32 v175, v143

.LBB0_989:
	s_and_b64 vcc, exec, s[20:21]
	s_cbranch_vccz .LBB0_991
	s_lshl_b32 s22, s14, 8
	s_or_b32 s20, s41, s22
	s_ashr_i32 s20, s20, 6
	v_mov_b32_e32 v140, v132
	v_mov_b32_e32 v141, v132
	s_mulk_i32 s20, 0x60
	v_pk_mul_f32 v[142:143], v[30:31], v[140:141]
	s_ashr_i32 s21, s20, 31
	v_cvt_pk_bf16_f32 v138, v138, v139
	v_cvt_pk_bf16_f32 v139, v142, v143
	v_lshl_add_u64 v[142:143], s[20:21], 1, v[134:135]
	v_mov_b32_e32 v129, v153
	v_lshl_add_u64 v[142:143], v[142:143], 0, v[128:129]
	global_store_dwordx2 v[142:143], v[138:139], off
	v_pk_mul_f32 v[138:139], v[26:27], v[140:141]
	v_cvt_pk_bf16_f32 v136, v136, v137
	v_cvt_pk_bf16_f32 v137, v138, v139
	v_or_b32_e32 v129, s22, v187
	global_store_dwordx2 v[142:143], v[136:137], off offset:32
	v_pk_mul_f32 v[136:137], v[22:23], v[140:141]
	v_pk_mul_f32 v[138:139], v[20:21], v[132:133]
	v_or_b32_e32 v131, 0x90, v129
	v_cvt_pk_bf16_f32 v138, v138, v139
	v_cvt_pk_bf16_f32 v139, v136, v137
	v_pk_mul_f32 v[136:137], v[18:19], v[140:141]
	v_pk_mul_f32 v[132:133], v[16:17], v[132:133]
	v_ashrrev_i32_e32 v131, 6, v131
	s_movk_i32 s20, 0x60
	v_cvt_pk_bf16_f32 v132, v132, v133
	v_cvt_pk_bf16_f32 v133, v136, v137
	v_mul_lo_u32 v136, v131, s20
	v_ashrrev_i32_e32 v137, 31, v136
	v_bitop3_b32 v129, v129, 60, v223 bitop3:0xc8
	v_lshl_add_u64 v[134:135], v[136:137], 1, v[134:135]
	v_lshlrev_b32_e32 v152, 1, v129
	v_lshl_add_u64 v[134:135], v[134:135], 0, v[152:153]
	global_store_dwordx2 v[142:143], v[138:139], off offset:384
	global_store_dwordx2 v[134:135], v[132:133], off
.LBB0_991:
	v_or_b32_e32 v138, 48, v130
	s_mov_b64 s[20:21], -1
	s_and_b64 vcc, exec, s[10:11]
	v_ashrrev_i32_e32 v139, 31, v138
	s_cbranch_vccnz .LBB0_993
	v_readlane_b32 s10, v254, 54
	v_lshlrev_b64 v[130:131], 5, v[138:139]
	v_readlane_b32 s11, v254, 55
	s_mov_b64 s[20:21], 0
	s_nop 0
	v_lshl_add_u64 v[134:135], s[10:11], 0, v[130:131]
	global_load_dwordx4 v[130:133], v[134:135], off
	s_nop 0
	global_load_dwordx4 v[134:137], v[134:135], off offset:16
	s_waitcnt vmcnt(0) lgkmcnt(0)
	v_mov_b32_e32 v140, v130
	v_mov_b32_e32 v141, v134
	v_mov_b32_e32 v134, v131
	v_mov_b32_e32 v130, v132
	v_mov_b32_e32 v131, v136
	v_mov_b32_e32 v136, v133
	v_pk_add_f32 v[132:133], v[140:141], v[134:135]
	v_pk_add_f32 v[130:131], v[130:131], v[136:137]
	s_nop 0
	v_pk_add_f32 v[130:131], v[132:133], v[130:131]
	s_nop 0
	v_add_f32_e32 v129, v130, v131
	v_fmamk_f32 v129, v129, 0x3b000000, v207
	v_mul_f32_e32 v130, 0x4b800000, v129
	v_cmp_gt_f32_e32 vcc, s68, v129
	s_nop 1
	v_cndmask_b32_e32 v129, v129, v130, vcc
	v_rsq_f32_e32 v129, v129
	s_nop 0
	v_mul_f32_e32 v130, 0x45800000, v129
	v_cndmask_b32_e32 v129, v129, v130, vcc
	v_mul_f32_e32 v130, 0x3e16c740, v129

.LBB0_998:
	s_or_b64 exec, exec, s[8:9]
	v_lshl_add_u64 v[146:147], v[132:133], 0, s[2:3]
	v_lshlrev_b32_e32 v152, 1, v190
	v_lshl_add_u64 v[146:147], v[146:147], 0, v[152:153]
	v_cvt_pk_bf16_f32 v155, v148, v149
	v_cvt_pk_bf16_f32 v148, v176, v177
	v_cvt_pk_bf16_f32 v149, v150, v151
	v_cvt_pk_bf16_f32 v154, v174, v175
	global_store_dwordx2 v[146:147], v[148:149], off offset:160
	v_pk_mul_f32 v[148:149], v[6:7], v[144:145]
	v_pk_mul_f32 v[150:151], v[4:5], v[130:131]
	v_pk_mul_f32 v[144:145], v[2:3], v[144:145]
	v_pk_mul_f32 v[174:175], v[0:1], v[130:131]
	global_store_dwordx2 v[146:147], v[154:155], off offset:128
	s_and_saveexec_b64 s[8:9], vcc
	s_cbranch_execz .LBB0_1000
	v_pk_mul_f32 v[154:155], v[138:139], v[174:175]
	v_pk_mul_f32 v[174:175], v[140:141], v[174:175]
	v_mul_f32_e32 v178, v173, v144
	v_mul_f32_e32 v182, v129, v144
	v_mov_b32_e32 v144, v149
	v_pk_fma_f32 v[140:141], v[140:141], v[150:151], v[154:155] neg_lo:[0,0,1] neg_hi:[0,0,1]
	v_mov_b32_e32 v154, v143
	v_mov_b32_e32 v155, v142
	v_mul_f32_e32 v176, v129, v148
	v_mul_f32_e32 v180, v173, v148
	v_pk_mul_f32 v[148:149], v[142:143], v[144:145]
	v_pk_mul_f32 v[142:143], v[154:155], v[144:145]
	v_mov_b32_e32 v177, v148
	v_mov_b32_e32 v179, v149
	v_mov_b32_e32 v181, v142
	v_mov_b32_e32 v183, v143
	v_pk_add_f32 v[148:149], v[176:177], v[178:179] neg_lo:[0,1] neg_hi:[0,1]
	v_pk_fma_f32 v[174:175], v[138:139], v[150:151], v[174:175]
	v_pk_add_f32 v[144:145], v[180:181], v[182:183]
	v_mov_b32_e32 v150, v140
	v_mov_b32_e32 v151, v141
.LBB0_1000:
	s_or_b64 exec, exec, s[8:9]
	v_cvt_pk_bf16_f32 v138, v150, v151
	v_cvt_pk_bf16_f32 v139, v148, v149
	global_store_dwordx2 v[146:147], v[138:139], off offset:896
	v_cvt_pk_bf16_f32 v138, v174, v175
	v_cvt_pk_bf16_f32 v139, v144, v145
	s_mov_b64 s[10:11], 0
	global_store_dwordx2 v[146:147], v[138:139], off offset:928
.LBB0_1001:
	s_and_b64 vcc, exec, s[10:11]
	s_cbranch_vccz .LBB0_1003
	s_lshl_b32 s2, s14, 8
	s_or_b32 s8, s41, s2
	s_ashr_i32 s8, s8, 6
	v_mov_b32_e32 v138, v130
	v_mov_b32_e32 v139, v130
	s_mulk_i32 s8, 0x60
	v_pk_mul_f32 v[140:141], v[14:15], v[138:139]
	s_ashr_i32 s9, s8, 31
	v_cvt_pk_bf16_f32 v136, v136, v137
	v_cvt_pk_bf16_f32 v137, v140, v141
	v_lshl_add_u64 v[140:141], s[8:9], 1, v[132:133]
	v_mov_b32_e32 v129, v153
	v_lshl_add_u64 v[128:129], v[140:141], 0, v[128:129]
	global_store_dwordx2 v[128:129], v[136:137], off
	v_pk_mul_f32 v[136:137], v[10:11], v[138:139]
	v_cvt_pk_bf16_f32 v134, v134, v135
	v_cvt_pk_bf16_f32 v135, v136, v137
	global_store_dwordx2 v[128:129], v[134:135], off offset:32
	v_pk_mul_f32 v[134:135], v[6:7], v[138:139]
	v_pk_mul_f32 v[136:137], v[4:5], v[130:131]
	v_pk_mul_f32 v[130:131], v[0:1], v[130:131]
	v_cvt_pk_bf16_f32 v136, v136, v137
	v_cvt_pk_bf16_f32 v137, v134, v135
	v_or_b32_e32 v134, s2, v187
	global_store_dwordx2 v[128:129], v[136:137], off offset:384
	v_or_b32_e32 v135, 0x90, v134
	v_pk_mul_f32 v[128:129], v[2:3], v[138:139]
	v_cvt_pk_bf16_f32 v130, v130, v131
	v_cvt_pk_bf16_f32 v131, v128, v129
	v_ashrrev_i32_e32 v128, 6, v135
	s_movk_i32 s2, 0x60
	v_mul_lo_u32 v128, v128, s2
	v_ashrrev_i32_e32 v129, 31, v128
	v_lshl_add_u64 v[128:129], v[128:129], 1, v[132:133]
	v_bitop3_b32 v132, v134, 60, v223 bitop3:0xc8
	v_lshlrev_b32_e32 v152, 1, v132
	v_lshl_add_u64 v[128:129], v[128:129], 0, v[152:153]
	global_store_dwordx2 v[128:129], v[130:131], off

.LBB0_1004:
	s_andn2_b64 vcc, exec, s[8:9]
	s_cbranch_vccnz .LBB0_535
	s_cmp_lt_i32 s93, 1
	s_mov_b64 s[8:9], -1
	s_cbranch_scc1 .LBB0_1136
	s_cmp_gt_i32 s93, 1
	s_cbranch_scc0 .LBB0_1133
	s_cmp_gt_i32 s14, 3
	s_cbranch_scc0 .LBB0_1130
	s_cmp_gt_u32 s14, 5
	s_cbranch_scc0 .LBB0_1127
	s_and_b32 s2, s40, 0xfffffc00
	s_cmp_lt_i32 s27, 16
	s_cselect_b64 s[12:13], -1, 0
	s_and_b64 s[8:9], s[12:13], exec
	s_cselect_b32 s64, s40, s2
	s_movk_i32 s2, 0x400
	s_cselect_b32 s66, 0x100, s2
	s_cmp_gt_u32 s14, 7
	s_mov_b64 s[8:9], -1
	s_cbranch_scc0 .LBB0_1124
	v_readlane_b32 s40, v254, 59
	s_cmp_gt_u32 s14, 11
	v_readlane_b32 s41, v254, 60
	s_cbranch_scc0 .LBB0_1121
	s_cmp_gt_u32 s14, 15
	s_cbranch_scc0 .LBB0_1118
	s_cmp_gt_u32 s14, 18
	s_cbranch_scc0 .LBB0_1051
	s_cmp_eq_u32 s14, 19
	s_cbranch_scc1 .LBB0_1015
	v_mul_f32_e32 v132, 0xbfb8aa3b, v124
	v_mul_f32_e32 v133, 0xbfb8aa3b, v125
	s_lshl_b32 s2, s14, 8
	v_mov_b64_e32 v[128:129], s[44:45]
	s_movk_i32 s20, 0x1800
	v_exp_f32_e32 v132, v132
	v_exp_f32_e32 v133, v133
	s_addk_i32 s2, 0xec00
	v_mad_i64_i32 v[130:131], s[8:9], v172, s20, v[128:129]
	s_lshl_b64 s[8:9], s[2:3], 1
	s_nop 0
	v_lshl_add_u64 v[130:131], v[130:131], 0, s[8:9]
	v_lshlrev_b32_e32 v152, 1, v186
	v_lshl_add_u64 v[134:135], v[130:131], 0, v[152:153]
	v_add_f32_e32 v130, 1.0, v132
	v_add_f32_e32 v131, 1.0, v133
	v_mul_f32_e32 v132, 0xbfb8aa3b, v126
	v_mul_f32_e32 v133, 0xbfb8aa3b, v127
	v_mul_f32_e32 v136, 0xbfb8aa3b, v120
	v_mul_f32_e32 v137, 0xbfb8aa3b, v121
	v_exp_f32_e32 v132, v132
	v_exp_f32_e32 v133, v133
	v_exp_f32_e32 v136, v136
	v_exp_f32_e32 v137, v137
	v_mul_f32_e32 v138, 0xbfb8aa3b, v122
	v_mul_f32_e32 v139, 0xbfb8aa3b, v123
	v_add_f32_e32 v132, 1.0, v132
	v_add_f32_e32 v133, 1.0, v133
	v_add_f32_e32 v136, 1.0, v136
	v_add_f32_e32 v137, 1.0, v137
	v_exp_f32_e32 v138, v138
	v_exp_f32_e32 v139, v139
	v_rcp_f32_e32 v130, v130
	v_rcp_f32_e32 v131, v131
	v_rcp_f32_e32 v132, v132
	v_rcp_f32_e32 v133, v133
	v_rcp_f32_e32 v136, v136
	v_rcp_f32_e32 v137, v137
	v_add_f32_e32 v138, 1.0, v138
	v_add_f32_e32 v139, 1.0, v139
	v_rcp_f32_e32 v138, v138
	v_rcp_f32_e32 v139, v139
	v_cvt_pk_bf16_f32 v130, v130, v131
	v_cvt_pk_bf16_f32 v131, v132, v133
	v_cvt_pk_bf16_f32 v132, v136, v137
	v_mul_f32_e32 v136, 0xbfb8aa3b, v116
	v_mul_f32_e32 v137, 0xbfb8aa3b, v117
	v_exp_f32_e32 v136, v136
	v_exp_f32_e32 v137, v137
	v_cvt_pk_bf16_f32 v133, v138, v139
	global_store_dwordx4 v[134:135], v[130:133], off
	v_mul_f32_e32 v138, 0xbfb8aa3b, v114
	v_mul_f32_e32 v139, 0xbfb8aa3b, v115
	v_add_f32_e32 v130, 1.0, v136
	v_add_f32_e32 v131, 1.0, v137
	v_mul_f32_e32 v132, 0xbfb8aa3b, v118
	v_mul_f32_e32 v133, 0xbfb8aa3b, v119
	v_mul_f32_e32 v136, 0xbfb8aa3b, v112
	v_mul_f32_e32 v137, 0xbfb8aa3b, v113
	v_exp_f32_e32 v132, v132
	v_exp_f32_e32 v133, v133
	v_exp_f32_e32 v136, v136
	v_exp_f32_e32 v137, v137
	v_exp_f32_e32 v138, v138
	v_exp_f32_e32 v139, v139
	v_add_f32_e32 v132, 1.0, v132
	v_add_f32_e32 v133, 1.0, v133
	v_add_f32_e32 v136, 1.0, v136
	v_add_f32_e32 v137, 1.0, v137
	v_add_f32_e32 v138, 1.0, v138
	v_add_f32_e32 v139, 1.0, v139
	v_rcp_f32_e32 v130, v130
	v_rcp_f32_e32 v131, v131
	v_rcp_f32_e32 v132, v132
	v_rcp_f32_e32 v133, v133
	v_rcp_f32_e32 v136, v136
	v_rcp_f32_e32 v137, v137
	v_rcp_f32_e32 v138, v138
	v_rcp_f32_e32 v139, v139
	v_cvt_pk_bf16_f32 v130, v130, v131
	v_cvt_pk_bf16_f32 v131, v132, v133
	v_cvt_pk_bf16_f32 v132, v136, v137
	v_cvt_pk_bf16_f32 v133, v138, v139
	global_store_dwordx4 v[134:135], v[130:133], off offset:256
	v_mul_f32_e32 v136, 0xbfb8aa3b, v104
	v_mul_f32_e32 v137, 0xbfb8aa3b, v105
	v_mul_f32_e32 v132, 0xbfb8aa3b, v108
	v_mul_f32_e32 v133, 0xbfb8aa3b, v109
	v_exp_f32_e32 v132, v132
	v_exp_f32_e32 v133, v133
	v_or_b32_e32 v130, 16, v172
	v_mad_i64_i32 v[130:131], s[10:11], v130, s20, v[128:129]
	v_lshl_add_u64 v[130:131], v[130:131], 0, s[8:9]
	v_lshl_add_u64 v[134:135], v[130:131], 0, v[152:153]
	v_add_f32_e32 v130, 1.0, v132
	v_add_f32_e32 v131, 1.0, v133
	v_mul_f32_e32 v132, 0xbfb8aa3b, v110
	v_mul_f32_e32 v133, 0xbfb8aa3b, v111
	v_exp_f32_e32 v132, v132
	v_exp_f32_e32 v133, v133
	v_exp_f32_e32 v136, v136
	v_exp_f32_e32 v137, v137
	v_mul_f32_e32 v138, 0xbfb8aa3b, v106
	v_mul_f32_e32 v139, 0xbfb8aa3b, v107
	v_add_f32_e32 v132, 1.0, v132
	v_add_f32_e32 v133, 1.0, v133
	v_add_f32_e32 v136, 1.0, v136
	v_add_f32_e32 v137, 1.0, v137
	v_exp_f32_e32 v138, v138
	v_exp_f32_e32 v139, v139
	v_rcp_f32_e32 v130, v130
	v_rcp_f32_e32 v131, v131
	v_rcp_f32_e32 v132, v132
	v_rcp_f32_e32 v133, v133
	v_rcp_f32_e32 v136, v136
	v_rcp_f32_e32 v137, v137
	v_add_f32_e32 v138, 1.0, v138
	v_add_f32_e32 v139, 1.0, v139
	v_rcp_f32_e32 v138, v138
	v_rcp_f32_e32 v139, v139
	v_cvt_pk_bf16_f32 v130, v130, v131
	v_cvt_pk_bf16_f32 v131, v132, v133
	v_cvt_pk_bf16_f32 v132, v136, v137
	v_mul_f32_e32 v136, 0xbfb8aa3b, v100
	v_mul_f32_e32 v137, 0xbfb8aa3b, v101
	v_exp_f32_e32 v136, v136
	v_exp_f32_e32 v137, v137
	v_cvt_pk_bf16_f32 v133, v138, v139
	global_store_dwordx4 v[134:135], v[130:133], off
	v_mul_f32_e32 v138, 0xbfb8aa3b, v98
	v_mul_f32_e32 v139, 0xbfb8aa3b, v99
	v_add_f32_e32 v130, 1.0, v136
	v_add_f32_e32 v131, 1.0, v137
	v_mul_f32_e32 v132, 0xbfb8aa3b, v102
	v_mul_f32_e32 v133, 0xbfb8aa3b, v103
	v_mul_f32_e32 v136, 0xbfb8aa3b, v96
	v_mul_f32_e32 v137, 0xbfb8aa3b, v97
	v_exp_f32_e32 v132, v132
	v_exp_f32_e32 v133, v133
	v_exp_f32_e32 v136, v136
	v_exp_f32_e32 v137, v137
	v_exp_f32_e32 v138, v138
	v_exp_f32_e32 v139, v139
	v_add_f32_e32 v132, 1.0, v132
	v_add_f32_e32 v133, 1.0, v133
	v_add_f32_e32 v136, 1.0, v136
	v_add_f32_e32 v137, 1.0, v137
	v_add_f32_e32 v138, 1.0, v138
	v_add_f32_e32 v139, 1.0, v139
	v_rcp_f32_e32 v130, v130
	v_rcp_f32_e32 v131, v131
	v_rcp_f32_e32 v132, v132
	v_rcp_f32_e32 v133, v133
	v_rcp_f32_e32 v136, v136
	v_rcp_f32_e32 v137, v137
	v_rcp_f32_e32 v138, v138
	v_rcp_f32_e32 v139, v139
	v_cvt_pk_bf16_f32 v130, v130, v131
	v_cvt_pk_bf16_f32 v131, v132, v133
	v_cvt_pk_bf16_f32 v132, v136, v137
	v_cvt_pk_bf16_f32 v133, v138, v139
	global_store_dwordx4 v[134:135], v[130:133], off offset:256
	v_mul_f32_e32 v136, 0xbfb8aa3b, v88
	v_mul_f32_e32 v137, 0xbfb8aa3b, v89
	v_mul_f32_e32 v132, 0xbfb8aa3b, v92
	v_mul_f32_e32 v133, 0xbfb8aa3b, v93
	v_exp_f32_e32 v132, v132
	v_exp_f32_e32 v133, v133
	v_or_b32_e32 v130, 32, v172
	v_mad_i64_i32 v[130:131], s[10:11], v130, s20, v[128:129]
	v_lshl_add_u64 v[130:131], v[130:131], 0, s[8:9]
	v_lshl_add_u64 v[134:135], v[130:131], 0, v[152:153]
	v_add_f32_e32 v130, 1.0, v132
	v_add_f32_e32 v131, 1.0, v133
	v_mul_f32_e32 v132, 0xbfb8aa3b, v94
	v_mul_f32_e32 v133, 0xbfb8aa3b, v95
	v_exp_f32_e32 v132, v132
	v_exp_f32_e32 v133, v133
	v_exp_f32_e32 v136, v136
	v_exp_f32_e32 v137, v137
	v_mul_f32_e32 v138, 0xbfb8aa3b, v90
	v_mul_f32_e32 v139, 0xbfb8aa3b, v91
	v_add_f32_e32 v132, 1.0, v132
	v_add_f32_e32 v133, 1.0, v133
	v_add_f32_e32 v136, 1.0, v136
	v_add_f32_e32 v137, 1.0, v137
	v_exp_f32_e32 v138, v138
	v_exp_f32_e32 v139, v139
	v_rcp_f32_e32 v130, v130
	v_rcp_f32_e32 v131, v131
	v_rcp_f32_e32 v132, v132
	v_rcp_f32_e32 v133, v133
	v_rcp_f32_e32 v136, v136
	v_rcp_f32_e32 v137, v137
	v_add_f32_e32 v138, 1.0, v138
	v_add_f32_e32 v139, 1.0, v139
	v_rcp_f32_e32 v138, v138
	v_rcp_f32_e32 v139, v139
	v_cvt_pk_bf16_f32 v130, v130, v131
	v_cvt_pk_bf16_f32 v131, v132, v133
	v_cvt_pk_bf16_f32 v132, v136, v137
	v_mul_f32_e32 v136, 0xbfb8aa3b, v84
	v_mul_f32_e32 v137, 0xbfb8aa3b, v85
	v_exp_f32_e32 v136, v136
	v_exp_f32_e32 v137, v137
	v_cvt_pk_bf16_f32 v133, v138, v139
	global_store_dwordx4 v[134:135], v[130:133], off
	v_mul_f32_e32 v138, 0xbfb8aa3b, v82
	v_mul_f32_e32 v139, 0xbfb8aa3b, v83
	v_add_f32_e32 v130, 1.0, v136
	v_add_f32_e32 v131, 1.0, v137
	v_mul_f32_e32 v132, 0xbfb8aa3b, v86
	v_mul_f32_e32 v133, 0xbfb8aa3b, v87
	v_mul_f32_e32 v136, 0xbfb8aa3b, v80
	v_mul_f32_e32 v137, 0xbfb8aa3b, v81
	v_exp_f32_e32 v132, v132
	v_exp_f32_e32 v133, v133
	v_exp_f32_e32 v136, v136
	v_exp_f32_e32 v137, v137
	v_exp_f32_e32 v138, v138
	v_exp_f32_e32 v139, v139
	v_add_f32_e32 v132, 1.0, v132
	v_add_f32_e32 v133, 1.0, v133
	v_add_f32_e32 v136, 1.0, v136
	v_add_f32_e32 v137, 1.0, v137
	v_add_f32_e32 v138, 1.0, v138
	v_add_f32_e32 v139, 1.0, v139
	v_rcp_f32_e32 v130, v130
	v_rcp_f32_e32 v131, v131
	v_rcp_f32_e32 v132, v132
	v_rcp_f32_e32 v133, v133
	v_rcp_f32_e32 v136, v136
	v_rcp_f32_e32 v137, v137
	v_rcp_f32_e32 v138, v138
	v_rcp_f32_e32 v139, v139
	v_cvt_pk_bf16_f32 v130, v130, v131
	v_cvt_pk_bf16_f32 v131, v132, v133
	v_cvt_pk_bf16_f32 v132, v136, v137
	v_cvt_pk_bf16_f32 v133, v138, v139
	global_store_dwordx4 v[134:135], v[130:133], off offset:256
	v_mul_f32_e32 v136, 0xbfb8aa3b, v72
	v_mul_f32_e32 v137, 0xbfb8aa3b, v73
	v_mul_f32_e32 v132, 0xbfb8aa3b, v76
	v_mul_f32_e32 v133, 0xbfb8aa3b, v77
	v_exp_f32_e32 v132, v132
	v_exp_f32_e32 v133, v133
	v_or_b32_e32 v130, 48, v172
	v_mad_i64_i32 v[130:131], s[10:11], v130, s20, v[128:129]
	v_lshl_add_u64 v[130:131], v[130:131], 0, s[8:9]
	v_lshl_add_u64 v[134:135], v[130:131], 0, v[152:153]
	v_add_f32_e32 v130, 1.0, v132
	v_add_f32_e32 v131, 1.0, v133
	v_mul_f32_e32 v132, 0xbfb8aa3b, v78
	v_mul_f32_e32 v133, 0xbfb8aa3b, v79
	v_exp_f32_e32 v132, v132
	v_exp_f32_e32 v133, v133
	v_exp_f32_e32 v136, v136
	v_exp_f32_e32 v137, v137
	v_mul_f32_e32 v138, 0xbfb8aa3b, v74
	v_mul_f32_e32 v139, 0xbfb8aa3b, v75
	v_add_f32_e32 v132, 1.0, v132
	v_add_f32_e32 v133, 1.0, v133
	v_add_f32_e32 v136, 1.0, v136
	v_add_f32_e32 v137, 1.0, v137
	v_exp_f32_e32 v138, v138
	v_exp_f32_e32 v139, v139
	v_rcp_f32_e32 v130, v130
	v_rcp_f32_e32 v131, v131
	v_rcp_f32_e32 v132, v132
	v_rcp_f32_e32 v133, v133
	v_rcp_f32_e32 v136, v136
	v_rcp_f32_e32 v137, v137
	v_add_f32_e32 v138, 1.0, v138
	v_add_f32_e32 v139, 1.0, v139
	v_rcp_f32_e32 v138, v138
	v_rcp_f32_e32 v139, v139
	v_cvt_pk_bf16_f32 v130, v130, v131
	v_cvt_pk_bf16_f32 v131, v132, v133
	v_cvt_pk_bf16_f32 v132, v136, v137
	v_mul_f32_e32 v136, 0xbfb8aa3b, v68
	v_mul_f32_e32 v137, 0xbfb8aa3b, v69
	v_exp_f32_e32 v136, v136
	v_exp_f32_e32 v137, v137
	v_cvt_pk_bf16_f32 v133, v138, v139
	global_store_dwordx4 v[134:135], v[130:133], off
	v_mul_f32_e32 v138, 0xbfb8aa3b, v66
	v_mul_f32_e32 v139, 0xbfb8aa3b, v67
	v_add_f32_e32 v130, 1.0, v136
	v_add_f32_e32 v131, 1.0, v137
	v_mul_f32_e32 v132, 0xbfb8aa3b, v70
	v_mul_f32_e32 v133, 0xbfb8aa3b, v71
	v_mul_f32_e32 v136, 0xbfb8aa3b, v64
	v_mul_f32_e32 v137, 0xbfb8aa3b, v65
	v_exp_f32_e32 v132, v132
	v_exp_f32_e32 v133, v133
	v_exp_f32_e32 v136, v136
	v_exp_f32_e32 v137, v137
	v_exp_f32_e32 v138, v138
	v_exp_f32_e32 v139, v139
	v_add_f32_e32 v132, 1.0, v132
	v_add_f32_e32 v133, 1.0, v133
	v_add_f32_e32 v136, 1.0, v136
	v_add_f32_e32 v137, 1.0, v137
	v_add_f32_e32 v138, 1.0, v138
	v_add_f32_e32 v139, 1.0, v139
	v_rcp_f32_e32 v130, v130
	v_rcp_f32_e32 v131, v131
	v_rcp_f32_e32 v132, v132
	v_rcp_f32_e32 v133, v133
	v_rcp_f32_e32 v136, v136
	v_rcp_f32_e32 v137, v137
	v_rcp_f32_e32 v138, v138
	v_rcp_f32_e32 v139, v139
	v_cvt_pk_bf16_f32 v130, v130, v131
	v_cvt_pk_bf16_f32 v131, v132, v133
	v_cvt_pk_bf16_f32 v132, v136, v137
	v_cvt_pk_bf16_f32 v133, v138, v139
	global_store_dwordx4 v[134:135], v[130:133], off offset:256
	v_mul_f32_e32 v136, 0xbfb8aa3b, v56
	v_mul_f32_e32 v137, 0xbfb8aa3b, v57
	v_mul_f32_e32 v132, 0xbfb8aa3b, v60
	v_mul_f32_e32 v133, 0xbfb8aa3b, v61
	v_exp_f32_e32 v132, v132
	v_exp_f32_e32 v133, v133
	v_add_u32_e32 v130, 0x80, v172
	v_mad_i64_i32 v[130:131], s[10:11], v130, s20, v[128:129]
	v_lshl_add_u64 v[130:131], v[130:131], 0, s[8:9]
	v_lshl_add_u64 v[134:135], v[130:131], 0, v[152:153]
	v_add_f32_e32 v130, 1.0, v132
	v_add_f32_e32 v131, 1.0, v133
	v_mul_f32_e32 v132, 0xbfb8aa3b, v62
	v_mul_f32_e32 v133, 0xbfb8aa3b, v63
	v_exp_f32_e32 v132, v132
	v_exp_f32_e32 v133, v133
	v_exp_f32_e32 v136, v136
	v_exp_f32_e32 v137, v137
	v_mul_f32_e32 v138, 0xbfb8aa3b, v58
	v_mul_f32_e32 v139, 0xbfb8aa3b, v59
	v_add_f32_e32 v132, 1.0, v132
	v_add_f32_e32 v133, 1.0, v133
	v_add_f32_e32 v136, 1.0, v136
	v_add_f32_e32 v137, 1.0, v137
	v_exp_f32_e32 v138, v138
	v_exp_f32_e32 v139, v139
	v_rcp_f32_e32 v130, v130
	v_rcp_f32_e32 v131, v131
	v_rcp_f32_e32 v132, v132
	v_rcp_f32_e32 v133, v133
	v_rcp_f32_e32 v136, v136
	v_rcp_f32_e32 v137, v137
	v_add_f32_e32 v138, 1.0, v138
	v_add_f32_e32 v139, 1.0, v139
	v_rcp_f32_e32 v138, v138
	v_rcp_f32_e32 v139, v139
	v_cvt_pk_bf16_f32 v130, v130, v131
	v_cvt_pk_bf16_f32 v131, v132, v133
	v_cvt_pk_bf16_f32 v132, v136, v137
	v_mul_f32_e32 v136, 0xbfb8aa3b, v52
	v_mul_f32_e32 v137, 0xbfb8aa3b, v53
	v_exp_f32_e32 v136, v136
	v_exp_f32_e32 v137, v137
	v_cvt_pk_bf16_f32 v133, v138, v139
	global_store_dwordx4 v[134:135], v[130:133], off
	v_mul_f32_e32 v138, 0xbfb8aa3b, v50
	v_mul_f32_e32 v139, 0xbfb8aa3b, v51
	v_add_f32_e32 v130, 1.0, v136
	v_add_f32_e32 v131, 1.0, v137
	v_mul_f32_e32 v132, 0xbfb8aa3b, v54
	v_mul_f32_e32 v133, 0xbfb8aa3b, v55
	v_mul_f32_e32 v136, 0xbfb8aa3b, v48
	v_mul_f32_e32 v137, 0xbfb8aa3b, v49
	v_exp_f32_e32 v132, v132
	v_exp_f32_e32 v133, v133
	v_exp_f32_e32 v136, v136
	v_exp_f32_e32 v137, v137
	v_exp_f32_e32 v138, v138
	v_exp_f32_e32 v139, v139
	v_add_f32_e32 v132, 1.0, v132
	v_add_f32_e32 v133, 1.0, v133
	v_add_f32_e32 v136, 1.0, v136
	v_add_f32_e32 v137, 1.0, v137
	v_add_f32_e32 v138, 1.0, v138
	v_add_f32_e32 v139, 1.0, v139
	v_rcp_f32_e32 v130, v130
	v_rcp_f32_e32 v131, v131
	v_rcp_f32_e32 v132, v132
	v_rcp_f32_e32 v133, v133
	v_rcp_f32_e32 v136, v136
	v_rcp_f32_e32 v137, v137
	v_rcp_f32_e32 v138, v138
	v_rcp_f32_e32 v139, v139
	v_cvt_pk_bf16_f32 v130, v130, v131
	v_cvt_pk_bf16_f32 v131, v132, v133
	v_cvt_pk_bf16_f32 v132, v136, v137
	v_cvt_pk_bf16_f32 v133, v138, v139
	global_store_dwordx4 v[134:135], v[130:133], off offset:256
	v_mul_f32_e32 v136, 0xbfb8aa3b, v40
	v_mul_f32_e32 v137, 0xbfb8aa3b, v41
	v_mul_f32_e32 v132, 0xbfb8aa3b, v44
	v_mul_f32_e32 v133, 0xbfb8aa3b, v45
	v_exp_f32_e32 v132, v132
	v_exp_f32_e32 v133, v133
	v_add_u32_e32 v130, 0x90, v172
	v_mad_i64_i32 v[130:131], s[10:11], v130, s20, v[128:129]
	v_lshl_add_u64 v[130:131], v[130:131], 0, s[8:9]
	v_lshl_add_u64 v[134:135], v[130:131], 0, v[152:153]
	v_add_f32_e32 v130, 1.0, v132
	v_add_f32_e32 v131, 1.0, v133
	v_mul_f32_e32 v132, 0xbfb8aa3b, v46
	v_mul_f32_e32 v133, 0xbfb8aa3b, v47
	v_exp_f32_e32 v132, v132
	v_exp_f32_e32 v133, v133
	v_exp_f32_e32 v136, v136
	v_exp_f32_e32 v137, v137
	v_mul_f32_e32 v138, 0xbfb8aa3b, v42
	v_mul_f32_e32 v139, 0xbfb8aa3b, v43
	v_add_f32_e32 v132, 1.0, v132
	v_add_f32_e32 v133, 1.0, v133
	v_add_f32_e32 v136, 1.0, v136
	v_add_f32_e32 v137, 1.0, v137
	v_exp_f32_e32 v138, v138
	v_exp_f32_e32 v139, v139
	v_rcp_f32_e32 v130, v130
	v_rcp_f32_e32 v131, v131
	v_rcp_f32_e32 v132, v132
	v_rcp_f32_e32 v133, v133
	v_rcp_f32_e32 v136, v136
	v_rcp_f32_e32 v137, v137
	v_add_f32_e32 v138, 1.0, v138
	v_add_f32_e32 v139, 1.0, v139
	v_rcp_f32_e32 v138, v138
	v_rcp_f32_e32 v139, v139
	v_cvt_pk_bf16_f32 v130, v130, v131
	v_cvt_pk_bf16_f32 v131, v132, v133
	v_cvt_pk_bf16_f32 v132, v136, v137
	v_mul_f32_e32 v136, 0xbfb8aa3b, v36
	v_mul_f32_e32 v137, 0xbfb8aa3b, v37
	v_exp_f32_e32 v136, v136
	v_exp_f32_e32 v137, v137
	v_cvt_pk_bf16_f32 v133, v138, v139
	global_store_dwordx4 v[134:135], v[130:133], off
	v_mul_f32_e32 v138, 0xbfb8aa3b, v34
	v_mul_f32_e32 v139, 0xbfb8aa3b, v35
	v_add_f32_e32 v130, 1.0, v136
	v_add_f32_e32 v131, 1.0, v137
	v_mul_f32_e32 v132, 0xbfb8aa3b, v38
	v_mul_f32_e32 v133, 0xbfb8aa3b, v39
	v_mul_f32_e32 v136, 0xbfb8aa3b, v32
	v_mul_f32_e32 v137, 0xbfb8aa3b, v33
	v_exp_f32_e32 v132, v132
	v_exp_f32_e32 v133, v133
	v_exp_f32_e32 v136, v136
	v_exp_f32_e32 v137, v137
	v_exp_f32_e32 v138, v138
	v_exp_f32_e32 v139, v139
	v_add_f32_e32 v132, 1.0, v132
	v_add_f32_e32 v133, 1.0, v133
	v_add_f32_e32 v136, 1.0, v136
	v_add_f32_e32 v137, 1.0, v137
	v_add_f32_e32 v138, 1.0, v138
	v_add_f32_e32 v139, 1.0, v139
	v_rcp_f32_e32 v130, v130
	v_rcp_f32_e32 v131, v131
	v_rcp_f32_e32 v132, v132
	v_rcp_f32_e32 v133, v133
	v_rcp_f32_e32 v136, v136
	v_rcp_f32_e32 v137, v137
	v_rcp_f32_e32 v138, v138
	v_rcp_f32_e32 v139, v139
	v_cvt_pk_bf16_f32 v130, v130, v131
	v_cvt_pk_bf16_f32 v131, v132, v133
	v_cvt_pk_bf16_f32 v132, v136, v137
	v_cvt_pk_bf16_f32 v133, v138, v139
	global_store_dwordx4 v[134:135], v[130:133], off offset:256
	v_mul_f32_e32 v136, 0xbfb8aa3b, v24
	v_mul_f32_e32 v137, 0xbfb8aa3b, v25
	v_mul_f32_e32 v132, 0xbfb8aa3b, v28
	v_mul_f32_e32 v133, 0xbfb8aa3b, v29
	v_exp_f32_e32 v132, v132
	v_exp_f32_e32 v133, v133
	v_add_u32_e32 v130, 0xa0, v172
	v_mad_i64_i32 v[130:131], s[10:11], v130, s20, v[128:129]
	v_lshl_add_u64 v[130:131], v[130:131], 0, s[8:9]
	v_lshl_add_u64 v[134:135], v[130:131], 0, v[152:153]
	v_add_f32_e32 v130, 1.0, v132
	v_add_f32_e32 v131, 1.0, v133
	v_mul_f32_e32 v132, 0xbfb8aa3b, v30
	v_mul_f32_e32 v133, 0xbfb8aa3b, v31
	v_exp_f32_e32 v132, v132
	v_exp_f32_e32 v133, v133
	v_exp_f32_e32 v136, v136
	v_exp_f32_e32 v137, v137
	v_mul_f32_e32 v138, 0xbfb8aa3b, v26
	v_mul_f32_e32 v139, 0xbfb8aa3b, v27
	v_add_f32_e32 v132, 1.0, v132
	v_add_f32_e32 v133, 1.0, v133
	v_add_f32_e32 v136, 1.0, v136
	v_add_f32_e32 v137, 1.0, v137
	v_exp_f32_e32 v138, v138
	v_exp_f32_e32 v139, v139
	v_rcp_f32_e32 v130, v130
	v_rcp_f32_e32 v131, v131
	v_rcp_f32_e32 v132, v132
	v_rcp_f32_e32 v133, v133
	v_rcp_f32_e32 v136, v136
	v_rcp_f32_e32 v137, v137
	v_add_f32_e32 v138, 1.0, v138
	v_add_f32_e32 v139, 1.0, v139
	v_rcp_f32_e32 v138, v138
	v_rcp_f32_e32 v139, v139
	v_cvt_pk_bf16_f32 v130, v130, v131
	v_cvt_pk_bf16_f32 v131, v132, v133
	v_cvt_pk_bf16_f32 v132, v136, v137
	v_mul_f32_e32 v136, 0xbfb8aa3b, v20
	v_mul_f32_e32 v137, 0xbfb8aa3b, v21
	v_exp_f32_e32 v136, v136
	v_exp_f32_e32 v137, v137
	v_cvt_pk_bf16_f32 v133, v138, v139
	global_store_dwordx4 v[134:135], v[130:133], off
	v_mul_f32_e32 v138, 0xbfb8aa3b, v18
	v_mul_f32_e32 v139, 0xbfb8aa3b, v19
	v_add_f32_e32 v130, 1.0, v136
	v_add_f32_e32 v131, 1.0, v137
	v_mul_f32_e32 v132, 0xbfb8aa3b, v22
	v_mul_f32_e32 v133, 0xbfb8aa3b, v23
	v_mul_f32_e32 v136, 0xbfb8aa3b, v16
	v_mul_f32_e32 v137, 0xbfb8aa3b, v17
	v_exp_f32_e32 v132, v132
	v_exp_f32_e32 v133, v133
	v_exp_f32_e32 v136, v136
	v_exp_f32_e32 v137, v137
	v_exp_f32_e32 v138, v138
	v_exp_f32_e32 v139, v139
	v_add_f32_e32 v132, 1.0, v132
	v_add_f32_e32 v133, 1.0, v133
	v_add_f32_e32 v136, 1.0, v136
	v_add_f32_e32 v137, 1.0, v137
	v_add_f32_e32 v138, 1.0, v138
	v_add_f32_e32 v139, 1.0, v139
	v_rcp_f32_e32 v130, v130
	v_rcp_f32_e32 v131, v131
	v_rcp_f32_e32 v132, v132
	v_rcp_f32_e32 v133, v133
	v_rcp_f32_e32 v136, v136
	v_rcp_f32_e32 v137, v137
	v_rcp_f32_e32 v138, v138
	v_rcp_f32_e32 v139, v139
	v_cvt_pk_bf16_f32 v130, v130, v131
	v_cvt_pk_bf16_f32 v131, v132, v133
	v_cvt_pk_bf16_f32 v132, v136, v137
	v_cvt_pk_bf16_f32 v133, v138, v139
	global_store_dwordx4 v[134:135], v[130:133], off offset:256
	v_mul_f32_e32 v134, 0xbfb8aa3b, v8
	v_mul_f32_e32 v135, 0xbfb8aa3b, v9
	v_add_u32_e32 v130, 0xb0, v172
	v_mad_i64_i32 v[128:129], s[10:11], v130, s20, v[128:129]
	v_mul_f32_e32 v130, 0xbfb8aa3b, v12
	v_mul_f32_e32 v131, 0xbfb8aa3b, v13
	v_exp_f32_e32 v130, v130
	v_exp_f32_e32 v131, v131
	v_lshl_add_u64 v[128:129], v[128:129], 0, s[8:9]
	v_lshl_add_u64 v[132:133], v[128:129], 0, v[152:153]
	v_add_f32_e32 v128, 1.0, v130
	v_add_f32_e32 v129, 1.0, v131
	v_mul_f32_e32 v130, 0xbfb8aa3b, v14
	v_mul_f32_e32 v131, 0xbfb8aa3b, v15
	v_exp_f32_e32 v130, v130
	v_exp_f32_e32 v131, v131
	v_exp_f32_e32 v134, v134
	v_exp_f32_e32 v135, v135
	v_mul_f32_e32 v136, 0xbfb8aa3b, v10
	v_mul_f32_e32 v137, 0xbfb8aa3b, v11
	v_add_f32_e32 v130, 1.0, v130
	v_add_f32_e32 v131, 1.0, v131
	v_add_f32_e32 v134, 1.0, v134
	v_add_f32_e32 v135, 1.0, v135
	v_exp_f32_e32 v136, v136
	v_exp_f32_e32 v137, v137
	v_rcp_f32_e32 v128, v128
	v_rcp_f32_e32 v129, v129
	v_rcp_f32_e32 v130, v130
	v_rcp_f32_e32 v131, v131
	v_rcp_f32_e32 v134, v134
	v_rcp_f32_e32 v135, v135
	v_add_f32_e32 v136, 1.0, v136
	v_add_f32_e32 v137, 1.0, v137
	v_rcp_f32_e32 v136, v136
	v_rcp_f32_e32 v137, v137
	v_cvt_pk_bf16_f32 v128, v128, v129
	v_cvt_pk_bf16_f32 v129, v130, v131
	v_cvt_pk_bf16_f32 v130, v134, v135
	v_mul_f32_e32 v134, 0xbfb8aa3b, v4
	v_mul_f32_e32 v135, 0xbfb8aa3b, v5
	v_exp_f32_e32 v134, v134
	v_exp_f32_e32 v135, v135
	v_cvt_pk_bf16_f32 v131, v136, v137
	global_store_dwordx4 v[132:133], v[128:131], off
	v_mul_f32_e32 v136, 0xbfb8aa3b, v2
	v_mul_f32_e32 v137, 0xbfb8aa3b, v3
	v_add_f32_e32 v128, 1.0, v134
	v_add_f32_e32 v129, 1.0, v135
	v_mul_f32_e32 v130, 0xbfb8aa3b, v6
	v_mul_f32_e32 v131, 0xbfb8aa3b, v7
	v_mul_f32_e32 v134, 0xbfb8aa3b, v0
	v_mul_f32_e32 v135, 0xbfb8aa3b, v1
	v_exp_f32_e32 v130, v130
	v_exp_f32_e32 v131, v131
	v_exp_f32_e32 v134, v134
	v_exp_f32_e32 v135, v135
	v_exp_f32_e32 v136, v136
	v_exp_f32_e32 v137, v137
	v_add_f32_e32 v130, 1.0, v130
	v_add_f32_e32 v131, 1.0, v131
	v_add_f32_e32 v134, 1.0, v134
	v_add_f32_e32 v135, 1.0, v135
	v_add_f32_e32 v136, 1.0, v136
	v_add_f32_e32 v137, 1.0, v137
	v_rcp_f32_e32 v128, v128
	v_rcp_f32_e32 v129, v129
	v_rcp_f32_e32 v130, v130
	v_rcp_f32_e32 v131, v131
	v_rcp_f32_e32 v134, v134
	v_rcp_f32_e32 v135, v135
	v_rcp_f32_e32 v136, v136
	v_rcp_f32_e32 v137, v137
	v_cvt_pk_bf16_f32 v128, v128, v129
	v_cvt_pk_bf16_f32 v129, v130, v131
	v_cvt_pk_bf16_f32 v130, v134, v135
	v_cvt_pk_bf16_f32 v131, v136, v137
	s_mov_b64 s[8:9], 0
	global_store_dwordx4 v[132:133], v[128:131], off offset:256

.LBB0_1019:
	s_or_saveexec_b64 s[8:9], s[8:9]
	s_ashr_i32 s2, s86, 7
	v_lshrrev_b32_e32 v128, 4, v191
	s_and_b32 s2, s2, -2
	v_readlane_b32 s10, v254, 22
	v_lshlrev_b32_e32 v129, 3, v128
	v_lshlrev_b32_e32 v128, 2, v128
	s_add_i32 s10, s2, s10
	v_and_b32_e32 v129, 16, v129
	v_and_b32_e32 v130, 4, v128
	s_ashr_i32 s11, s10, 31
	s_lshl_b64 s[10:11], s[10:11], 15
	v_lshlrev_b32_e32 v128, 2, v129
	v_lshlrev_b32_e32 v130, 2, v130
	s_xor_b64 exec, exec, s[8:9]
	s_cbranch_execz .LBB0_1021
	v_readlane_b32 s20, v254, 37
	v_readlane_b32 s21, v254, 38
	s_add_u32 s20, s20, s10
	v_lshlrev_b32_e32 v129, 7, v172
	s_addc_u32 s21, s21, s11
	v_and_b32_e32 v152, 0x6780, v129
	v_lshl_add_u64 v[134:135], s[20:21], 0, v[152:153]
	v_mov_b32_e32 v129, v153
	v_lshl_add_u64 v[134:135], v[134:135], 0, v[128:129]
	v_mov_b32_e32 v131, v153
	v_lshl_add_u64 v[134:135], v[134:135], 0, v[130:131]
	v_ashrrev_i32_e32 v173, 31, v172
	global_store_dwordx4 v[134:135], v[124:127], off
	global_store_dwordx4 v[134:135], v[120:123], off offset:32
	v_mov_b64_e32 v[142:143], v[172:173]
	v_mov_b32_e32 v138, v120
	v_mov_b32_e32 v139, v121
	v_mov_b32_e32 v140, v122
	v_mov_b32_e32 v141, v123
	v_mov_b32_e32 v134, v124
	v_mov_b32_e32 v135, v125
	v_mov_b32_e32 v136, v126
	v_mov_b32_e32 v137, v127
.LBB0_1021:
	s_or_b64 exec, exec, s[8:9]
	v_readlane_b32 s8, v254, 48
	v_lshlrev_b64 v[142:143], 6, v[142:143]
	v_readlane_b32 s9, v254, 49
	v_lshlrev_b32_e32 v152, 1, v190
	v_cvt_pk_bf16_f32 v134, v134, v135
	v_lshl_add_u64 v[142:143], s[8:9], 0, v[142:143]
	v_lshl_add_u64 v[142:143], v[142:143], 0, v[152:153]
	v_cvt_pk_bf16_f32 v135, v136, v137
	global_store_dwordx2 v[142:143], v[134:135], off
	v_cvt_pk_bf16_f32 v134, v138, v139
	v_cvt_pk_bf16_f32 v135, v140, v141
	global_store_dwordx2 v[142:143], v[134:135], off offset:32
	v_or_b32_e32 v134, 16, v172
	v_or_b32_e32 v173, 16, v189
	v_cmp_lt_i32_e64 s[8:9], s84, v134
	s_and_saveexec_b64 s[20:21], s[8:9]
	s_xor_b64 s[8:9], exec, s[20:21]
	s_cbranch_execz .LBB0_1023
	v_bfe_u32 v129, v134, 6, 4
	v_cndmask_b32_e32 v129, v173, v129, vcc
	v_cvt_f32_ubyte0_e32 v129, v129
	v_mul_f32_e32 v131, v148, v129
	v_mul_f32_e32 v131, 0.15915494, v131
	v_and_b32_e32 v144, 0x3df, v134
	v_cos_f32_e32 v134, v131
	v_sin_f32_e32 v140, v131
	v_mul_f32_e32 v131, v149, v129
	v_mul_f32_e32 v131, 0.15915494, v131
	v_cos_f32_e32 v135, v131
	v_sin_f32_e32 v141, v131
	v_mul_f32_e32 v131, v150, v129
	v_mul_f32_e32 v129, v151, v129
	v_mul_f32_e32 v129, 0.15915494, v129
	v_cos_f32_e32 v174, v129
	v_sin_f32_e32 v175, v129
	v_mul_f32_e32 v131, 0.15915494, v131
	v_cos_f32_e32 v139, v131
	v_sin_f32_e32 v131, v131
	v_pk_mul_f32 v[136:137], v[104:105], v[140:141]
	v_pk_mul_f32 v[142:143], v[104:105], v[134:135]
	v_mov_b32_e32 v178, v111
	v_mov_b32_e32 v179, v107
	v_pk_fma_f32 v[136:137], v[108:109], v[134:135], v[136:137] neg_lo:[0,0,1] neg_hi:[0,0,1]
	v_mov_b32_e32 v134, v175
	v_mov_b32_e32 v135, v174
	v_pk_mul_f32 v[180:181], v[178:179], v[174:175]
	v_pk_mul_f32 v[134:135], v[178:179], v[134:135]
	v_mul_f32_e32 v138, v110, v139
	v_mul_f32_e32 v146, v106, v131
	v_mul_f32_e32 v154, v110, v131
	v_mul_f32_e32 v176, v106, v139
	v_mov_b32_e32 v139, v180
	v_mov_b32_e32 v147, v181
	v_mov_b32_e32 v155, v134
	v_mov_b32_e32 v177, v135
	v_mov_b32_e32 v145, v153
	v_pk_add_f32 v[138:139], v[138:139], v[146:147] neg_lo:[0,1] neg_hi:[0,1]
	v_pk_fma_f32 v[140:141], v[108:109], v[140:141], v[142:143]
	v_pk_add_f32 v[142:143], v[154:155], v[176:177]
	v_lshl_add_u64 v[134:135], v[132:133], 0, v[144:145]
.LBB0_1023:
	s_andn2_saveexec_b64 s[8:9], s[8:9]
	s_cbranch_execz .LBB0_1025
	v_readlane_b32 s20, v254, 37
	v_readlane_b32 s21, v254, 38
	s_add_u32 s20, s20, s10
	v_lshlrev_b32_e32 v129, 7, v134
	s_addc_u32 s21, s21, s11
	v_and_b32_e32 v136, 0x6f80, v129
	v_mov_b32_e32 v137, v153
	v_lshl_add_u64 v[136:137], s[20:21], 0, v[136:137]
	v_mov_b32_e32 v129, v153
	v_lshl_add_u64 v[136:137], v[136:137], 0, v[128:129]
	v_mov_b32_e32 v131, v153
	v_lshl_add_u64 v[136:137], v[136:137], 0, v[130:131]
	global_store_dwordx4 v[136:137], v[108:111], off
	global_store_dwordx4 v[136:137], v[104:107], off offset:32
	v_ashrrev_i32_e32 v135, 31, v134
	v_mov_b32_e32 v140, v104
	v_mov_b32_e32 v141, v105
	v_mov_b32_e32 v142, v106
	v_mov_b32_e32 v143, v107
	v_mov_b32_e32 v136, v108
	v_mov_b32_e32 v137, v109
	v_mov_b32_e32 v138, v110
	v_mov_b32_e32 v139, v111
.LBB0_1025:
	s_or_b64 exec, exec, s[8:9]
	v_readlane_b32 s8, v254, 48
	v_lshlrev_b64 v[134:135], 6, v[134:135]
	v_readlane_b32 s9, v254, 49
	v_cvt_pk_bf16_f32 v136, v136, v137
	v_cvt_pk_bf16_f32 v137, v138, v139
	v_lshl_add_u64 v[134:135], s[8:9], 0, v[134:135]
	v_lshl_add_u64 v[134:135], v[134:135], 0, v[152:153]
	global_store_dwordx2 v[134:135], v[136:137], off
	v_cvt_pk_bf16_f32 v136, v140, v141
	v_cvt_pk_bf16_f32 v137, v142, v143
	global_store_dwordx2 v[134:135], v[136:137], off offset:32
	v_or_b32_e32 v134, 32, v172
	v_or_b32_e32 v174, 32, v189
	v_cmp_lt_i32_e64 s[8:9], s84, v134
	s_and_saveexec_b64 s[20:21], s[8:9]
	s_xor_b64 s[8:9], exec, s[20:21]
	s_cbranch_execz .LBB0_1027
	v_bfe_u32 v129, v134, 6, 4
	v_cndmask_b32_e32 v129, v174, v129, vcc
	v_cvt_f32_ubyte0_e32 v129, v129
	v_mul_f32_e32 v131, v148, v129
	v_mul_f32_e32 v131, 0.15915494, v131
	v_and_b32_e32 v144, 0x3ef, v134
	v_cos_f32_e32 v134, v131
	v_sin_f32_e32 v140, v131
	v_mul_f32_e32 v131, v149, v129
	v_mul_f32_e32 v131, 0.15915494, v131
	v_cos_f32_e32 v135, v131
	v_sin_f32_e32 v141, v131
	v_mul_f32_e32 v131, v150, v129
	v_mul_f32_e32 v129, v151, v129
	v_mul_f32_e32 v129, 0.15915494, v129
	v_cos_f32_e32 v176, v129
	v_sin_f32_e32 v177, v129
	v_mul_f32_e32 v131, 0.15915494, v131
	v_cos_f32_e32 v139, v131
	v_sin_f32_e32 v131, v131
	v_pk_mul_f32 v[136:137], v[88:89], v[140:141]
	v_pk_mul_f32 v[142:143], v[88:89], v[134:135]
	v_mov_b32_e32 v180, v95
	v_mov_b32_e32 v181, v91
	v_pk_fma_f32 v[136:137], v[92:93], v[134:135], v[136:137] neg_lo:[0,0,1] neg_hi:[0,0,1]
	v_mov_b32_e32 v134, v177
	v_mov_b32_e32 v135, v176
	v_pk_mul_f32 v[182:183], v[180:181], v[176:177]
	v_pk_mul_f32 v[134:135], v[180:181], v[134:135]
	v_mul_f32_e32 v138, v94, v139
	v_mul_f32_e32 v146, v90, v131
	v_mul_f32_e32 v154, v94, v131
	v_mul_f32_e32 v178, v90, v139
	v_mov_b32_e32 v139, v182
	v_mov_b32_e32 v147, v183
	v_mov_b32_e32 v155, v134
	v_mov_b32_e32 v179, v135
	v_mov_b32_e32 v145, v153
	v_pk_add_f32 v[138:139], v[138:139], v[146:147] neg_lo:[0,1] neg_hi:[0,1]
	v_pk_fma_f32 v[140:141], v[92:93], v[140:141], v[142:143]
	v_pk_add_f32 v[142:143], v[154:155], v[178:179]
	v_lshl_add_u64 v[134:135], v[132:133], 0, v[144:145]
.LBB0_1027:
	s_andn2_saveexec_b64 s[8:9], s[8:9]
	s_cbranch_execz .LBB0_1029
	v_readlane_b32 s20, v254, 37
	v_readlane_b32 s21, v254, 38
	s_add_u32 s20, s20, s10
	v_lshlrev_b32_e32 v129, 7, v134
	s_addc_u32 s21, s21, s11
	v_and_b32_e32 v136, 0x7780, v129
	v_mov_b32_e32 v137, v153
	v_lshl_add_u64 v[136:137], s[20:21], 0, v[136:137]
	v_mov_b32_e32 v129, v153
	v_lshl_add_u64 v[136:137], v[136:137], 0, v[128:129]
	v_mov_b32_e32 v131, v153
	v_lshl_add_u64 v[136:137], v[136:137], 0, v[130:131]
	global_store_dwordx4 v[136:137], v[92:95], off
	global_store_dwordx4 v[136:137], v[88:91], off offset:32
	v_ashrrev_i32_e32 v135, 31, v134
	v_mov_b32_e32 v140, v88
	v_mov_b32_e32 v141, v89
	v_mov_b32_e32 v142, v90
	v_mov_b32_e32 v143, v91
	v_mov_b32_e32 v136, v92
	v_mov_b32_e32 v137, v93
	v_mov_b32_e32 v138, v94
	v_mov_b32_e32 v139, v95
.LBB0_1029:
	s_or_b64 exec, exec, s[8:9]
	v_readlane_b32 s8, v254, 48
	v_lshlrev_b64 v[134:135], 6, v[134:135]
	v_readlane_b32 s9, v254, 49
	v_cvt_pk_bf16_f32 v136, v136, v137
	v_cvt_pk_bf16_f32 v137, v138, v139
	v_lshl_add_u64 v[134:135], s[8:9], 0, v[134:135]
	v_lshl_add_u64 v[134:135], v[134:135], 0, v[152:153]
	global_store_dwordx2 v[134:135], v[136:137], off
	v_cvt_pk_bf16_f32 v136, v140, v141
	v_cvt_pk_bf16_f32 v137, v142, v143
	global_store_dwordx2 v[134:135], v[136:137], off offset:32
	v_or_b32_e32 v134, 48, v172
	v_or_b32_e32 v175, 48, v189
	v_cmp_lt_i32_e64 s[8:9], s84, v134
	s_and_saveexec_b64 s[20:21], s[8:9]
	s_xor_b64 s[8:9], exec, s[20:21]
	s_cbranch_execz .LBB0_1031
	v_bfe_u32 v129, v134, 6, 4
	v_cndmask_b32_e32 v129, v175, v129, vcc
	v_cvt_f32_ubyte0_e32 v129, v129
	v_mul_f32_e32 v131, v148, v129
	v_mul_f32_e32 v131, 0.15915494, v131
	v_and_b32_e32 v144, 0x3ff, v134
	v_cos_f32_e32 v134, v131
	v_sin_f32_e32 v140, v131
	v_mul_f32_e32 v131, v149, v129
	v_mul_f32_e32 v131, 0.15915494, v131
	v_cos_f32_e32 v135, v131
	v_sin_f32_e32 v141, v131
	v_mul_f32_e32 v131, v150, v129
	v_mul_f32_e32 v129, v151, v129
	v_mul_f32_e32 v129, 0.15915494, v129
	v_cos_f32_e32 v176, v129
	v_sin_f32_e32 v177, v129
	v_mul_f32_e32 v131, 0.15915494, v131
	v_cos_f32_e32 v139, v131
	v_sin_f32_e32 v131, v131
	v_pk_mul_f32 v[136:137], v[72:73], v[140:141]
	v_pk_mul_f32 v[142:143], v[72:73], v[134:135]
	v_mov_b32_e32 v180, v79
	v_mov_b32_e32 v181, v75
	v_pk_fma_f32 v[136:137], v[76:77], v[134:135], v[136:137] neg_lo:[0,0,1] neg_hi:[0,0,1]
	v_mov_b32_e32 v134, v177
	v_mov_b32_e32 v135, v176
	v_pk_mul_f32 v[182:183], v[180:181], v[176:177]
	v_pk_mul_f32 v[134:135], v[180:181], v[134:135]
	v_mul_f32_e32 v138, v78, v139
	v_mul_f32_e32 v146, v74, v131
	v_mul_f32_e32 v154, v78, v131
	v_mul_f32_e32 v178, v74, v139
	v_mov_b32_e32 v139, v182
	v_mov_b32_e32 v147, v183
	v_mov_b32_e32 v155, v134
	v_mov_b32_e32 v179, v135
	v_mov_b32_e32 v145, v153
	v_pk_add_f32 v[138:139], v[138:139], v[146:147] neg_lo:[0,1] neg_hi:[0,1]
	v_pk_fma_f32 v[140:141], v[76:77], v[140:141], v[142:143]
	v_pk_add_f32 v[142:143], v[154:155], v[178:179]
	v_lshl_add_u64 v[134:135], v[132:133], 0, v[144:145]
.LBB0_1031:
	s_andn2_saveexec_b64 s[8:9], s[8:9]
	s_cbranch_execz .LBB0_1033
	v_readlane_b32 s20, v254, 37
	v_readlane_b32 s21, v254, 38
	s_add_u32 s10, s20, s10
	v_lshlrev_b32_e32 v129, 7, v134
	s_addc_u32 s11, s21, s11
	v_and_b32_e32 v132, 0x7f80, v129
	v_mov_b32_e32 v133, v153
	v_lshl_add_u64 v[132:133], s[10:11], 0, v[132:133]
	v_mov_b32_e32 v129, v153
	v_lshl_add_u64 v[132:133], v[132:133], 0, v[128:129]
	v_mov_b32_e32 v131, v153
	v_lshl_add_u64 v[132:133], v[132:133], 0, v[130:131]
	v_ashrrev_i32_e32 v135, 31, v134
	v_mov_b32_e32 v140, v72
	v_mov_b32_e32 v141, v73
	v_mov_b32_e32 v142, v74
	v_mov_b32_e32 v143, v75
	v_mov_b32_e32 v136, v76
	v_mov_b32_e32 v137, v77
	v_mov_b32_e32 v138, v78
	v_mov_b32_e32 v139, v79
	global_store_dwordx4 v[132:133], v[76:79], off
	global_store_dwordx4 v[132:133], v[72:75], off offset:32
.LBB0_1033:
	s_or_b64 exec, exec, s[8:9]
	v_readlane_b32 s8, v254, 48
	v_lshlrev_b64 v[132:133], 6, v[134:135]
	v_readlane_b32 s9, v254, 49
	v_cvt_pk_bf16_f32 v134, v136, v137
	v_cvt_pk_bf16_f32 v135, v138, v139
	v_lshl_add_u64 v[132:133], s[8:9], 0, v[132:133]
	v_lshl_add_u64 v[132:133], v[132:133], 0, v[152:153]
	global_store_dwordx2 v[132:133], v[134:135], off
	v_cvt_pk_bf16_f32 v134, v140, v141
	v_cvt_pk_bf16_f32 v135, v142, v143
	s_add_i32 s2, s86, 0xfffff080
	global_store_dwordx2 v[132:133], v[134:135], off offset:32
	s_lshr_b32 s2, s2, 10
	v_mov_b32_e32 v129, 0x500
	v_mov_b64_e32 v[132:133], 0x1100
	v_mad_u64_u32 v[132:133], s[8:9], s2, v129, v[132:133]
	s_movk_i32 s2, 0xf7f
	v_add_u32_e32 v136, 0x80, v172
	v_cmp_lt_i32_e64 s[8:9], s2, v172
	s_and_saveexec_b64 s[10:11], s[8:9]
	s_xor_b64 s[8:9], exec, s[10:11]
	s_cbranch_execz .LBB0_1035
	v_bfe_u32 v129, v136, 6, 4
	v_cndmask_b32_e32 v129, v189, v129, vcc
	v_cvt_f32_ubyte0_e32 v129, v129
	v_mul_f32_e32 v131, v148, v129
	v_mul_f32_e32 v131, 0.15915494, v131
	v_cos_f32_e32 v138, v131
	v_sin_f32_e32 v142, v131
	v_mul_f32_e32 v131, v149, v129
	v_mul_f32_e32 v131, 0.15915494, v131
	v_cos_f32_e32 v139, v131
	v_sin_f32_e32 v143, v131
	v_mul_f32_e32 v131, v150, v129
	v_mul_f32_e32 v129, v151, v129
	v_mul_f32_e32 v129, 0.15915494, v129
	v_mul_f32_e32 v131, 0.15915494, v131
	v_cos_f32_e32 v178, v129
	v_sin_f32_e32 v179, v129
	v_cos_f32_e32 v135, v131
	v_sin_f32_e32 v131, v131
	v_mov_b32_e32 v182, v63
	v_mov_b32_e32 v183, v59
	v_pk_mul_f32 v[190:191], v[182:183], v[178:179]
	v_pk_mul_f32 v[140:141], v[56:57], v[142:143]
	v_mul_f32_e32 v146, v62, v135
	v_mul_f32_e32 v154, v58, v131
	v_mov_b32_e32 v147, v190
	v_mov_b32_e32 v155, v191
	v_pk_mul_f32 v[144:145], v[56:57], v[138:139]
	v_pk_fma_f32 v[138:139], v[60:61], v[138:139], v[140:141] neg_lo:[0,0,1] neg_hi:[0,0,1]
	v_pk_add_f32 v[140:141], v[146:147], v[154:155] neg_lo:[0,1] neg_hi:[0,1]
	v_mov_b32_e32 v146, v179
	v_mov_b32_e32 v147, v178
	v_pk_mul_f32 v[146:147], v[182:183], v[146:147]
	v_and_b32_e32 v134, 0x3cf, v136
	v_mul_f32_e32 v176, v62, v131
	v_mul_f32_e32 v180, v58, v135
	v_mov_b32_e32 v177, v146
	v_mov_b32_e32 v181, v147
	v_mov_b32_e32 v135, v153
	v_pk_fma_f32 v[142:143], v[60:61], v[142:143], v[144:145]
	v_pk_add_f32 v[144:145], v[176:177], v[180:181]
	v_lshl_add_u64 v[146:147], v[132:133], 0, v[134:135]
.LBB0_1035:
	s_or_saveexec_b64 s[8:9], s[8:9]
	v_ashrrev_i32_e32 v129, 7, v136
	v_and_b32_e32 v129, -2, v129
	v_readlane_b32 s2, v254, 22
	v_readlane_b32 s10, v254, 37
	v_readlane_b32 s11, v254, 38
	v_add_u32_e32 v134, s2, v129
	v_ashrrev_i32_e32 v135, 31, v134
	v_lshlrev_b64 v[134:135], 15, v[134:135]
	v_lshl_add_u64 v[134:135], s[10:11], 0, v[134:135]
	s_xor_b64 exec, exec, s[8:9]
	s_cbranch_execz .LBB0_1037
	v_lshlrev_b32_e32 v129, 7, v136
	v_and_b32_e32 v138, 0x6780, v129
	v_mov_b32_e32 v139, v153
	v_lshl_add_u64 v[138:139], v[134:135], 0, v[138:139]
	v_mov_b32_e32 v129, v153
	v_lshl_add_u64 v[138:139], v[138:139], 0, v[128:129]
	v_mov_b32_e32 v131, v153
	v_lshl_add_u64 v[138:139], v[138:139], 0, v[130:131]
	v_ashrrev_i32_e32 v137, 31, v136
	global_store_dwordx4 v[138:139], v[60:63], off
	global_store_dwordx4 v[138:139], v[56:59], off offset:32
	v_mov_b64_e32 v[146:147], v[136:137]
	v_mov_b32_e32 v142, v56
	v_mov_b32_e32 v143, v57
	v_mov_b32_e32 v144, v58
	v_mov_b32_e32 v145, v59
	v_mov_b32_e32 v138, v60
	v_mov_b32_e32 v139, v61
	v_mov_b32_e32 v140, v62
	v_mov_b32_e32 v141, v63
.LBB0_1037:
	s_or_b64 exec, exec, s[8:9]
	v_readlane_b32 s8, v254, 48
	v_lshlrev_b64 v[136:137], 6, v[146:147]
	v_readlane_b32 s9, v254, 49
	v_cvt_pk_bf16_f32 v138, v138, v139
	v_cvt_pk_bf16_f32 v139, v140, v141
	v_lshl_add_u64 v[136:137], s[8:9], 0, v[136:137]
	v_lshl_add_u64 v[136:137], v[136:137], 0, v[152:153]
	global_store_dwordx2 v[136:137], v[138:139], off
	v_cvt_pk_bf16_f32 v138, v142, v143
	v_cvt_pk_bf16_f32 v139, v144, v145
	s_movk_i32 s2, 0xf6f
	global_store_dwordx2 v[136:137], v[138:139], off offset:32
	v_add_u32_e32 v136, 0x90, v172
	v_cmp_lt_i32_e64 s[8:9], s2, v172
	s_and_saveexec_b64 s[10:11], s[8:9]
	s_xor_b64 s[8:9], exec, s[10:11]
	s_cbranch_execz .LBB0_1039
	v_bfe_u32 v129, v136, 6, 4
	v_cndmask_b32_e32 v129, v173, v129, vcc
	v_cvt_f32_ubyte0_e32 v129, v129
	v_mul_f32_e32 v131, v148, v129
	v_mul_f32_e32 v131, 0.15915494, v131
	v_and_b32_e32 v146, 0x3df, v136
	v_cos_f32_e32 v136, v131
	v_sin_f32_e32 v142, v131
	v_mul_f32_e32 v131, v149, v129
	v_mul_f32_e32 v131, 0.15915494, v131
	v_cos_f32_e32 v137, v131
	v_sin_f32_e32 v143, v131
	v_mul_f32_e32 v131, v150, v129
	v_mul_f32_e32 v129, v151, v129
	v_mul_f32_e32 v129, 0.15915494, v129
	v_cos_f32_e32 v178, v129
	v_sin_f32_e32 v179, v129
	v_mul_f32_e32 v131, 0.15915494, v131
	v_cos_f32_e32 v141, v131
	v_sin_f32_e32 v131, v131
	v_pk_mul_f32 v[138:139], v[40:41], v[142:143]
	v_pk_mul_f32 v[144:145], v[40:41], v[136:137]
	v_mov_b32_e32 v182, v47
	v_mov_b32_e32 v183, v43
	v_pk_fma_f32 v[138:139], v[44:45], v[136:137], v[138:139] neg_lo:[0,0,1] neg_hi:[0,0,1]
	v_mov_b32_e32 v136, v179
	v_mov_b32_e32 v137, v178
	v_pk_mul_f32 v[190:191], v[182:183], v[178:179]
	v_pk_mul_f32 v[136:137], v[182:183], v[136:137]
	v_mul_f32_e32 v140, v46, v141
	v_mul_f32_e32 v154, v42, v131
	v_mul_f32_e32 v176, v46, v131
	v_mul_f32_e32 v180, v42, v141
	v_mov_b32_e32 v141, v190
	v_mov_b32_e32 v155, v191
	v_mov_b32_e32 v177, v136
	v_mov_b32_e32 v181, v137
	v_mov_b32_e32 v147, v153
	v_pk_add_f32 v[140:141], v[140:141], v[154:155] neg_lo:[0,1] neg_hi:[0,1]
	v_pk_fma_f32 v[142:143], v[44:45], v[142:143], v[144:145]
	v_pk_add_f32 v[144:145], v[176:177], v[180:181]
	v_lshl_add_u64 v[136:137], v[132:133], 0, v[146:147]
.LBB0_1039:
	s_andn2_saveexec_b64 s[8:9], s[8:9]
	s_cbranch_execz .LBB0_1041
	v_lshlrev_b32_e32 v129, 7, v136
	v_and_b32_e32 v138, 0x6f80, v129
	v_mov_b32_e32 v139, v153
	v_lshl_add_u64 v[138:139], v[134:135], 0, v[138:139]
	v_mov_b32_e32 v129, v153
	v_lshl_add_u64 v[138:139], v[138:139], 0, v[128:129]
	v_mov_b32_e32 v131, v153
	v_lshl_add_u64 v[138:139], v[138:139], 0, v[130:131]
	global_store_dwordx4 v[138:139], v[44:47], off
	global_store_dwordx4 v[138:139], v[40:43], off offset:32
	v_ashrrev_i32_e32 v137, 31, v136
	v_mov_b32_e32 v142, v40
	v_mov_b32_e32 v143, v41
	v_mov_b32_e32 v144, v42
	v_mov_b32_e32 v145, v43
	v_mov_b32_e32 v138, v44
	v_mov_b32_e32 v139, v45
	v_mov_b32_e32 v140, v46
	v_mov_b32_e32 v141, v47
.LBB0_1041:
	s_or_b64 exec, exec, s[8:9]
	v_readlane_b32 s8, v254, 48
	v_lshlrev_b64 v[136:137], 6, v[136:137]
	v_readlane_b32 s9, v254, 49
	v_cvt_pk_bf16_f32 v138, v138, v139
	v_cvt_pk_bf16_f32 v139, v140, v141
	v_lshl_add_u64 v[136:137], s[8:9], 0, v[136:137]
	v_lshl_add_u64 v[136:137], v[136:137], 0, v[152:153]
	global_store_dwordx2 v[136:137], v[138:139], off
	v_cvt_pk_bf16_f32 v138, v142, v143
	v_cvt_pk_bf16_f32 v139, v144, v145
	s_movk_i32 s2, 0xf5f
	global_store_dwordx2 v[136:137], v[138:139], off offset:32
	v_add_u32_e32 v136, 0xa0, v172
	v_cmp_lt_i32_e64 s[8:9], s2, v172
	s_and_saveexec_b64 s[10:11], s[8:9]
	s_xor_b64 s[8:9], exec, s[10:11]
	s_cbranch_execz .LBB0_1043
	v_bfe_u32 v129, v136, 6, 4
	v_cndmask_b32_e32 v129, v174, v129, vcc
	v_cvt_f32_ubyte0_e32 v129, v129
	v_mul_f32_e32 v131, v148, v129
	v_mul_f32_e32 v131, 0.15915494, v131
	v_and_b32_e32 v146, 0x3ef, v136
	v_cos_f32_e32 v136, v131
	v_sin_f32_e32 v142, v131
	v_mul_f32_e32 v131, v149, v129
	v_mul_f32_e32 v131, 0.15915494, v131
	v_cos_f32_e32 v137, v131
	v_sin_f32_e32 v143, v131
	v_mul_f32_e32 v131, v150, v129
	v_mul_f32_e32 v129, v151, v129
	v_mul_f32_e32 v129, 0.15915494, v129
	v_cos_f32_e32 v178, v129
	v_sin_f32_e32 v179, v129
	v_mul_f32_e32 v131, 0.15915494, v131
	v_cos_f32_e32 v141, v131
	v_sin_f32_e32 v131, v131
	v_pk_mul_f32 v[138:139], v[24:25], v[142:143]
	v_pk_mul_f32 v[144:145], v[24:25], v[136:137]
	v_mov_b32_e32 v182, v31
	v_mov_b32_e32 v183, v27
	v_pk_fma_f32 v[138:139], v[28:29], v[136:137], v[138:139] neg_lo:[0,0,1] neg_hi:[0,0,1]
	v_mov_b32_e32 v136, v179
	v_mov_b32_e32 v137, v178
	v_pk_mul_f32 v[190:191], v[182:183], v[178:179]
	v_pk_mul_f32 v[136:137], v[182:183], v[136:137]
	v_mul_f32_e32 v140, v30, v141
	v_mul_f32_e32 v154, v26, v131
	v_mul_f32_e32 v176, v30, v131
	v_mul_f32_e32 v180, v26, v141
	v_mov_b32_e32 v141, v190
	v_mov_b32_e32 v155, v191
	v_mov_b32_e32 v177, v136
	v_mov_b32_e32 v181, v137
	v_mov_b32_e32 v147, v153
	v_pk_add_f32 v[140:141], v[140:141], v[154:155] neg_lo:[0,1] neg_hi:[0,1]
	v_pk_fma_f32 v[142:143], v[28:29], v[142:143], v[144:145]
	v_pk_add_f32 v[144:145], v[176:177], v[180:181]
	v_lshl_add_u64 v[136:137], v[132:133], 0, v[146:147]
.LBB0_1043:
	s_andn2_saveexec_b64 s[8:9], s[8:9]
	s_cbranch_execz .LBB0_1045
	v_lshlrev_b32_e32 v129, 7, v136
	v_and_b32_e32 v138, 0x7780, v129
	v_mov_b32_e32 v139, v153
	v_lshl_add_u64 v[138:139], v[134:135], 0, v[138:139]
	v_mov_b32_e32 v129, v153
	v_lshl_add_u64 v[138:139], v[138:139], 0, v[128:129]
	v_mov_b32_e32 v131, v153
	v_lshl_add_u64 v[138:139], v[138:139], 0, v[130:131]
	global_store_dwordx4 v[138:139], v[28:31], off
	global_store_dwordx4 v[138:139], v[24:27], off offset:32
	v_ashrrev_i32_e32 v137, 31, v136
	v_mov_b32_e32 v142, v24
	v_mov_b32_e32 v143, v25
	v_mov_b32_e32 v144, v26
	v_mov_b32_e32 v145, v27
	v_mov_b32_e32 v138, v28
	v_mov_b32_e32 v139, v29
	v_mov_b32_e32 v140, v30
	v_mov_b32_e32 v141, v31
.LBB0_1045:
	s_or_b64 exec, exec, s[8:9]
	v_readlane_b32 s8, v254, 48
	v_lshlrev_b64 v[136:137], 6, v[136:137]
	v_readlane_b32 s9, v254, 49
	v_cvt_pk_bf16_f32 v138, v138, v139
	v_cvt_pk_bf16_f32 v139, v140, v141
	v_lshl_add_u64 v[136:137], s[8:9], 0, v[136:137]
	v_lshl_add_u64 v[136:137], v[136:137], 0, v[152:153]
	global_store_dwordx2 v[136:137], v[138:139], off
	v_cvt_pk_bf16_f32 v138, v142, v143
	v_cvt_pk_bf16_f32 v139, v144, v145
	s_movk_i32 s2, 0xf4f
	global_store_dwordx2 v[136:137], v[138:139], off offset:32
	v_add_u32_e32 v136, 0xb0, v172
	v_cmp_lt_i32_e64 s[8:9], s2, v172
	s_and_saveexec_b64 s[10:11], s[8:9]
	s_xor_b64 s[8:9], exec, s[10:11]
	s_cbranch_execz .LBB0_1047
	v_bfe_u32 v129, v136, 6, 4
	v_cndmask_b32_e32 v129, v175, v129, vcc
	v_cvt_f32_ubyte0_e32 v129, v129
	v_mul_f32_e32 v130, v148, v129
	v_mul_f32_e32 v131, 0.15915494, v130
	v_and_b32_e32 v128, 0x3ff, v136
	v_cos_f32_e32 v130, v131
	v_sin_f32_e32 v134, v131
	v_mul_f32_e32 v131, v149, v129
	v_mul_f32_e32 v136, v150, v129
	v_mul_f32_e32 v129, v151, v129
	v_mul_f32_e32 v135, 0.15915494, v131
	v_mul_f32_e32 v136, 0.15915494, v136
	v_mul_f32_e32 v129, 0.15915494, v129
	v_cos_f32_e32 v131, v135
	v_sin_f32_e32 v135, v135
	v_cos_f32_e32 v138, v136
	v_sin_f32_e32 v139, v136
	v_cos_f32_e32 v148, v129
	v_sin_f32_e32 v149, v129
	v_mov_b32_e32 v154, v15
	v_mov_b32_e32 v155, v11
	v_pk_mul_f32 v[136:137], v[8:9], v[134:135]
	v_mul_f32_e32 v140, v14, v138
	v_mul_f32_e32 v144, v10, v139
	v_mul_f32_e32 v146, v14, v139
	v_mul_f32_e32 v150, v10, v138
	v_pk_mul_f32 v[138:139], v[154:155], v[148:149]
	v_pk_mul_f32 v[142:143], v[8:9], v[130:131]
	v_mov_b32_e32 v141, v138
	v_mov_b32_e32 v145, v139
	v_pk_fma_f32 v[138:139], v[12:13], v[130:131], v[136:137] neg_lo:[0,0,1] neg_hi:[0,0,1]
	v_mov_b32_e32 v130, v149
	v_mov_b32_e32 v131, v148
	v_pk_mul_f32 v[130:131], v[154:155], v[130:131]
	v_mov_b32_e32 v129, v153
	v_mov_b32_e32 v147, v130
	v_mov_b32_e32 v151, v131
	v_pk_add_f32 v[140:141], v[140:141], v[144:145] neg_lo:[0,1] neg_hi:[0,1]
	v_pk_fma_f32 v[142:143], v[12:13], v[134:135], v[142:143]
	v_pk_add_f32 v[144:145], v[146:147], v[150:151]
	v_lshl_add_u64 v[136:137], v[132:133], 0, v[128:129]
.LBB0_1047:
	s_andn2_saveexec_b64 s[8:9], s[8:9]
	s_cbranch_execz .LBB0_1049
	v_lshlrev_b32_e32 v129, 7, v136
	v_and_b32_e32 v132, 0x7f80, v129
	v_mov_b32_e32 v133, v153
	v_lshl_add_u64 v[132:133], v[134:135], 0, v[132:133]
	v_mov_b32_e32 v129, v153
	v_lshl_add_u64 v[128:129], v[132:133], 0, v[128:129]
	v_mov_b32_e32 v131, v153
	v_lshl_add_u64 v[128:129], v[128:129], 0, v[130:131]
	v_ashrrev_i32_e32 v137, 31, v136
	v_mov_b32_e32 v142, v8
	v_mov_b32_e32 v143, v9
	v_mov_b32_e32 v144, v10
	v_mov_b32_e32 v145, v11
	v_mov_b32_e32 v138, v12
	v_mov_b32_e32 v139, v13
	v_mov_b32_e32 v140, v14
	v_mov_b32_e32 v141, v15
	global_store_dwordx4 v[128:129], v[12:15], off
	global_store_dwordx4 v[128:129], v[8:11], off offset:32
.LBB0_1049:
	s_or_b64 exec, exec, s[8:9]
	v_readlane_b32 s8, v254, 48
	v_lshlrev_b64 v[128:129], 6, v[136:137]
	v_readlane_b32 s9, v254, 49
	v_cvt_pk_bf16_f32 v130, v138, v139
	v_cvt_pk_bf16_f32 v131, v140, v141
	v_lshl_add_u64 v[128:129], s[8:9], 0, v[128:129]
	v_lshl_add_u64 v[128:129], v[128:129], 0, v[152:153]
	global_store_dwordx2 v[128:129], v[130:131], off
	v_cvt_pk_bf16_f32 v130, v142, v143
	v_cvt_pk_bf16_f32 v131, v144, v145
	global_store_dwordx2 v[128:129], v[130:131], off offset:32

.LBB0_1051:
	s_andn2_b64 vcc, exec, s[8:9]
	s_cbranch_vccnz .LBB0_1117
	v_and_b32_e32 v129, 64, v209
	v_xor_b32_e32 v128, 16, v209
	v_add_u32_e32 v129, 64, v129
	v_cmp_lt_i32_e32 vcc, v128, v129
	v_readlane_b32 s22, v254, 56
	s_cmp_eq_u32 s14, 18
	v_cndmask_b32_e32 v128, v209, v128, vcc
	v_lshlrev_b32_e32 v137, 2, v128
	v_xor_b32_e32 v128, 32, v209
	v_cmp_lt_i32_e32 vcc, v128, v129
	v_readlane_b32 s23, v254, 57
	s_cselect_b64 s[20:21], -1, 0
	v_cndmask_b32_e32 v128, v209, v128, vcc
	s_cmp_lg_u32 s14, 18
	v_lshlrev_b32_e32 v136, 2, v128
	v_mov_b64_e32 v[128:129], s[22:23]
	s_cselect_b64 s[10:11], -1, 0
	s_add_i32 s26, s14, -16
	v_mad_i64_i32 v[128:129], s[22:23], v172, s67, v[128:129]
	s_lshl_b32 s22, s26, 9
	s_mov_b32 s23, s3
	v_mul_f32_e32 v130, v125, v125
	v_mul_f32_e32 v131, v127, v127
	v_lshl_add_u64 v[128:129], v[128:129], 0, s[22:23]
	v_lshlrev_b32_e32 v152, 1, v187
	v_fmac_f32_e32 v130, v124, v124
	v_fmac_f32_e32 v131, v126, v126
	v_lshl_add_u64 v[128:129], v[128:129], 0, v[152:153]
	v_add_f32_e32 v132, v130, v131
	v_cvt_pk_bf16_f32 v130, v124, v125
	v_cvt_pk_bf16_f32 v131, v126, v127
	global_store_dwordx2 v[128:129], v[130:131], off
	v_mul_f32_e32 v130, v121, v121
	v_mul_f32_e32 v131, v123, v123
	v_fmac_f32_e32 v130, v120, v120
	v_fmac_f32_e32 v131, v122, v122
	v_add_f32_e32 v130, v130, v131
	v_add_f32_e32 v132, v132, v130
	v_cvt_pk_bf16_f32 v130, v120, v121
	v_cvt_pk_bf16_f32 v131, v122, v123
	global_store_dwordx2 v[128:129], v[130:131], off offset:32
	v_mul_f32_e32 v130, v117, v117
	v_mul_f32_e32 v131, v119, v119
	v_fmac_f32_e32 v130, v116, v116
	v_fmac_f32_e32 v131, v118, v118
	v_add_f32_e32 v130, v130, v131
	v_add_f32_e32 v130, v132, v130
	v_mul_f32_e32 v131, v113, v113
	v_mul_f32_e32 v132, v115, v115
	v_fmac_f32_e32 v131, v112, v112
	v_fmac_f32_e32 v132, v114, v114
	v_add_f32_e32 v131, v131, v132
	v_add_f32_e32 v133, v130, v131
	ds_bpermute_b32 v134, v137, v133
	v_cvt_pk_bf16_f32 v130, v116, v117
	v_cvt_pk_bf16_f32 v131, v118, v119
	global_store_dwordx2 v[128:129], v[130:131], off offset:256
	v_cvt_pk_bf16_f32 v132, v112, v113
	s_waitcnt lgkmcnt(0)
	v_add_f32_e32 v130, v133, v134
	ds_bpermute_b32 v131, v136, v130
	v_cvt_pk_bf16_f32 v133, v114, v115
	global_store_dwordx2 v[128:129], v[132:133], off offset:288
	v_cndmask_b32_e64 v128, 0, 1, s[10:11]
	v_cmp_eq_u32_e64 s[8:9], 0, v188
	s_lshl_b32 s2, s26, 2
	v_cmp_ne_u32_e64 s[10:11], 1, v128
	s_and_saveexec_b64 s[22:23], s[8:9]
	s_cbranch_execz .LBB0_1058
	v_ashrrev_i32_e32 v173, 31, v172
	s_and_b64 vcc, exec, s[10:11]
	s_mov_b64 s[24:25], -1
	s_cbranch_vccnz .LBB0_1055
	v_readlane_b32 s24, v254, 54
	v_lshlrev_b64 v[128:129], 5, v[172:173]
	v_readlane_b32 s25, v254, 55
	s_nop 1
	v_lshl_add_u64 v[128:129], s[24:25], 0, v[128:129]
	v_lshl_add_u64 v[128:129], s[2:3], 2, v[128:129]
	s_mov_b64 s[24:25], 0

.LBB0_1057:
	s_lshl_b32 s24, s89, 2
	s_mov_b32 s25, s3
	s_waitcnt lgkmcnt(0)
	v_add_f32_e32 v130, v130, v131
	v_lshl_add_u64 v[128:129], v[128:129], 0, s[24:25]
	global_store_dword v[128:129], v130, off
.LBB0_1058:
	s_or_b64 exec, exec, s[22:23]
	s_ashr_i32 s22, s86, 7
	s_and_b32 s22, s22, -2
	v_readlane_b32 s23, v254, 22
	s_add_i32 s22, s22, s23
	s_ashr_i32 s23, s22, 31
	v_cmp_gt_i32_e32 vcc, s43, v172
	s_lshl_b32 s26, s26, 8
	s_lshl_b64 s[24:25], s[22:23], 18
	s_and_b64 s[36:37], s[20:21], vcc
	v_lshlrev_b32_e32 v128, 2, v187
	s_and_saveexec_b64 s[22:23], s[36:37]
	s_cbranch_execz .LBB0_1060
	s_add_u32 s36, s40, s24
	v_lshlrev_b32_e32 v129, 10, v172
	s_addc_u32 s37, s41, s25
	v_and_b32_e32 v130, 0x33c00, v129
	s_waitcnt lgkmcnt(0)
	v_mov_b32_e32 v131, v153
	v_lshl_add_u64 v[130:131], s[36:37], 0, v[130:131]
	v_mov_b32_e32 v129, v153
	v_lshl_add_u64 v[130:131], v[130:131], 0, v[128:129]
	global_store_dwordx4 v[130:131], v[124:127], off
	global_store_dwordx4 v[130:131], v[120:123], off offset:64
	global_store_dwordx4 v[130:131], v[116:119], off offset:512
	global_store_dwordx4 v[130:131], v[112:115], off offset:576
.LBB0_1060:
	s_or_b64 exec, exec, s[22:23]
	v_readlane_b32 s22, v254, 56
	v_readlane_b32 s23, v254, 57
	v_or_b32_e32 v130, 16, v172
	v_mul_f32_e32 v129, v109, v109
	v_mov_b64_e32 v[132:133], s[22:23]
	v_mad_i64_i32 v[132:133], s[22:23], v130, s67, v[132:133]
	s_lshl_b32 s22, s26, 1
	s_mov_b32 s23, s3
	v_mul_f32_e32 v134, v111, v111
	v_lshl_add_u64 v[132:133], v[132:133], 0, s[22:23]
	v_fmac_f32_e32 v129, v108, v108
	v_fmac_f32_e32 v134, v110, v110
	v_lshl_add_u64 v[132:133], v[132:133], 0, v[152:153]
	v_add_f32_e32 v129, v129, v134
	v_cvt_pk_bf16_f32 v134, v108, v109
	v_cvt_pk_bf16_f32 v135, v110, v111
	global_store_dwordx2 v[132:133], v[134:135], off
	v_mul_f32_e32 v134, v105, v105
	v_mul_f32_e32 v135, v107, v107
	v_fmac_f32_e32 v134, v104, v104
	v_fmac_f32_e32 v135, v106, v106
	v_add_f32_e32 v134, v134, v135
	v_add_f32_e32 v129, v129, v134
	v_cvt_pk_bf16_f32 v134, v104, v105
	v_cvt_pk_bf16_f32 v135, v106, v107
	global_store_dwordx2 v[132:133], v[134:135], off offset:32
	v_mul_f32_e32 v134, v101, v101
	v_mul_f32_e32 v135, v103, v103
	v_fmac_f32_e32 v134, v100, v100
	v_fmac_f32_e32 v135, v102, v102
	v_add_f32_e32 v134, v134, v135
	v_add_f32_e32 v129, v129, v134
	v_cvt_pk_bf16_f32 v134, v100, v101
	v_cvt_pk_bf16_f32 v135, v102, v103
	global_store_dwordx2 v[132:133], v[134:135], off offset:256
	v_mul_f32_e32 v134, v97, v97
	v_mul_f32_e32 v135, v99, v99
	v_fmac_f32_e32 v134, v96, v96
	v_fmac_f32_e32 v135, v98, v98
	v_add_f32_e32 v134, v134, v135
	v_add_f32_e32 v129, v129, v134
	v_cvt_pk_bf16_f32 v134, v96, v97
	v_cvt_pk_bf16_f32 v135, v98, v99
	global_store_dwordx2 v[132:133], v[134:135], off offset:288
	ds_bpermute_b32 v132, v137, v129
	s_waitcnt lgkmcnt(0)
	v_ashrrev_i32_e32 v131, 31, v130
	v_add_f32_e32 v129, v129, v132
	ds_bpermute_b32 v134, v136, v129
	s_and_saveexec_b64 s[26:27], s[8:9]
	s_cbranch_execz .LBB0_1066
	s_and_b64 vcc, exec, s[10:11]
	s_mov_b64 s[40:41], -1
	s_cbranch_vccnz .LBB0_1063
	v_readlane_b32 s36, v254, 54
	v_lshlrev_b64 v[132:133], 5, v[130:131]
	v_readlane_b32 s37, v254, 55
	s_mov_b64 s[40:41], 0
	s_nop 0
	v_lshl_add_u64 v[132:133], s[36:37], 0, v[132:133]
	v_lshl_add_u64 v[132:133], s[2:3], 2, v[132:133]

.LBB0_1065:
	s_lshl_b32 s36, s89, 2
	s_mov_b32 s37, s3
	v_readlane_b32 s40, v254, 59
	s_waitcnt lgkmcnt(0)
	v_add_f32_e32 v129, v129, v134
	v_lshl_add_u64 v[132:133], v[132:133], 0, s[36:37]
	v_readlane_b32 s41, v254, 60
	global_store_dword v[132:133], v129, off
.LBB0_1066:
	s_or_b64 exec, exec, s[26:27]
	v_cmp_gt_i32_e32 vcc, s43, v130
	s_and_b64 s[36:37], s[20:21], vcc
	s_and_saveexec_b64 s[26:27], s[36:37]
	s_cbranch_execz .LBB0_1068
	s_add_u32 s36, s40, s24
	v_lshlrev_b32_e32 v129, 10, v130
	s_addc_u32 s37, s41, s25
	v_and_b32_e32 v130, 0x37c00, v129
	v_mov_b32_e32 v131, v153
	v_lshl_add_u64 v[130:131], s[36:37], 0, v[130:131]
	v_mov_b32_e32 v129, v153
	v_lshl_add_u64 v[130:131], v[130:131], 0, v[128:129]
	global_store_dwordx4 v[130:131], v[108:111], off
	global_store_dwordx4 v[130:131], v[104:107], off offset:64
	global_store_dwordx4 v[130:131], v[100:103], off offset:512
	global_store_dwordx4 v[130:131], v[96:99], off offset:576
.LBB0_1068:
	s_or_b64 exec, exec, s[26:27]
	v_readlane_b32 s26, v254, 56
	v_readlane_b32 s27, v254, 57
	v_or_b32_e32 v130, 32, v172
	s_mov_b32 s23, s3
	v_mov_b64_e32 v[132:133], s[26:27]
	v_mad_i64_i32 v[132:133], s[26:27], v130, s67, v[132:133]
	v_mul_f32_e32 v129, v93, v93
	s_waitcnt lgkmcnt(0)
	v_mul_f32_e32 v134, v95, v95
	v_lshl_add_u64 v[132:133], v[132:133], 0, s[22:23]
	v_fmac_f32_e32 v129, v92, v92
	v_fmac_f32_e32 v134, v94, v94
	v_lshl_add_u64 v[132:133], v[132:133], 0, v[152:153]
	v_add_f32_e32 v129, v129, v134
	v_cvt_pk_bf16_f32 v134, v92, v93
	v_cvt_pk_bf16_f32 v135, v94, v95
	global_store_dwordx2 v[132:133], v[134:135], off
	v_mul_f32_e32 v134, v89, v89
	v_mul_f32_e32 v135, v91, v91
	v_fmac_f32_e32 v134, v88, v88
	v_fmac_f32_e32 v135, v90, v90
	v_add_f32_e32 v134, v134, v135
	v_add_f32_e32 v129, v129, v134
	v_cvt_pk_bf16_f32 v134, v88, v89
	v_cvt_pk_bf16_f32 v135, v90, v91
	global_store_dwordx2 v[132:133], v[134:135], off offset:32
	v_mul_f32_e32 v134, v85, v85
	v_mul_f32_e32 v135, v87, v87
	v_fmac_f32_e32 v134, v84, v84
	v_fmac_f32_e32 v135, v86, v86
	v_add_f32_e32 v134, v134, v135
	v_add_f32_e32 v129, v129, v134
	v_cvt_pk_bf16_f32 v134, v84, v85
	v_cvt_pk_bf16_f32 v135, v86, v87
	global_store_dwordx2 v[132:133], v[134:135], off offset:256
	v_mul_f32_e32 v134, v81, v81
	v_mul_f32_e32 v135, v83, v83
	v_fmac_f32_e32 v134, v80, v80
	v_fmac_f32_e32 v135, v82, v82
	v_add_f32_e32 v134, v134, v135
	v_add_f32_e32 v129, v129, v134
	v_cvt_pk_bf16_f32 v134, v80, v81
	v_cvt_pk_bf16_f32 v135, v82, v83
	global_store_dwordx2 v[132:133], v[134:135], off offset:288
	ds_bpermute_b32 v132, v137, v129
	v_ashrrev_i32_e32 v131, 31, v130
	s_waitcnt lgkmcnt(0)
	v_add_f32_e32 v129, v129, v132
	ds_bpermute_b32 v134, v136, v129
	s_and_saveexec_b64 s[26:27], s[8:9]
	s_cbranch_execz .LBB0_1074
	s_and_b64 vcc, exec, s[10:11]
	s_mov_b64 s[40:41], -1
	s_cbranch_vccnz .LBB0_1071
	v_readlane_b32 s36, v254, 54
	v_lshlrev_b64 v[132:133], 5, v[130:131]
	v_readlane_b32 s37, v254, 55
	s_mov_b64 s[40:41], 0
	s_nop 0
	v_lshl_add_u64 v[132:133], s[36:37], 0, v[132:133]
	v_lshl_add_u64 v[132:133], s[2:3], 2, v[132:133]

.LBB0_1074:
	s_or_b64 exec, exec, s[26:27]
	v_cmp_gt_i32_e32 vcc, s43, v130
	s_and_b64 s[36:37], s[20:21], vcc
	s_and_saveexec_b64 s[26:27], s[36:37]
	s_cbranch_execz .LBB0_1076
	s_add_u32 s36, s40, s24
	v_lshlrev_b32_e32 v129, 10, v130
	s_addc_u32 s37, s41, s25
	v_and_b32_e32 v130, 0x3bc00, v129
	v_mov_b32_e32 v131, v153
	v_lshl_add_u64 v[130:131], s[36:37], 0, v[130:131]
	v_mov_b32_e32 v129, v153
	v_lshl_add_u64 v[130:131], v[130:131], 0, v[128:129]
	global_store_dwordx4 v[130:131], v[92:95], off
	global_store_dwordx4 v[130:131], v[88:91], off offset:64
	global_store_dwordx4 v[130:131], v[84:87], off offset:512
	global_store_dwordx4 v[130:131], v[80:83], off offset:576
.LBB0_1076:
	s_or_b64 exec, exec, s[26:27]
	v_readlane_b32 s26, v254, 56
	v_readlane_b32 s27, v254, 57
	v_or_b32_e32 v130, 48, v172
	s_mov_b32 s23, s3
	v_mov_b64_e32 v[132:133], s[26:27]
	v_mad_i64_i32 v[132:133], s[26:27], v130, s67, v[132:133]
	v_mul_f32_e32 v129, v77, v77
	s_waitcnt lgkmcnt(0)
	v_mul_f32_e32 v134, v79, v79
	v_lshl_add_u64 v[132:133], v[132:133], 0, s[22:23]
	v_fmac_f32_e32 v129, v76, v76
	v_fmac_f32_e32 v134, v78, v78
	v_lshl_add_u64 v[132:133], v[132:133], 0, v[152:153]
	v_add_f32_e32 v129, v129, v134
	v_cvt_pk_bf16_f32 v134, v76, v77
	v_cvt_pk_bf16_f32 v135, v78, v79
	global_store_dwordx2 v[132:133], v[134:135], off
	v_mul_f32_e32 v134, v73, v73
	v_mul_f32_e32 v135, v75, v75
	v_fmac_f32_e32 v134, v72, v72
	v_fmac_f32_e32 v135, v74, v74
	v_add_f32_e32 v134, v134, v135
	v_add_f32_e32 v129, v129, v134
	v_cvt_pk_bf16_f32 v134, v72, v73
	v_cvt_pk_bf16_f32 v135, v74, v75
	global_store_dwordx2 v[132:133], v[134:135], off offset:32
	v_mul_f32_e32 v134, v69, v69
	v_mul_f32_e32 v135, v71, v71
	v_fmac_f32_e32 v134, v68, v68
	v_fmac_f32_e32 v135, v70, v70
	v_add_f32_e32 v134, v134, v135
	v_add_f32_e32 v129, v129, v134
	v_cvt_pk_bf16_f32 v134, v68, v69
	v_cvt_pk_bf16_f32 v135, v70, v71
	global_store_dwordx2 v[132:133], v[134:135], off offset:256
	v_mul_f32_e32 v134, v65, v65
	v_mul_f32_e32 v135, v67, v67
	v_fmac_f32_e32 v134, v64, v64
	v_fmac_f32_e32 v135, v66, v66
	v_add_f32_e32 v134, v134, v135
	v_add_f32_e32 v129, v129, v134
	v_cvt_pk_bf16_f32 v134, v64, v65
	v_cvt_pk_bf16_f32 v135, v66, v67
	global_store_dwordx2 v[132:133], v[134:135], off offset:288
	ds_bpermute_b32 v132, v137, v129
	v_ashrrev_i32_e32 v131, 31, v130
	s_waitcnt lgkmcnt(0)
	v_add_f32_e32 v129, v129, v132
	ds_bpermute_b32 v134, v136, v129
	s_and_saveexec_b64 s[26:27], s[8:9]
	s_cbranch_execz .LBB0_1082
	s_and_b64 vcc, exec, s[10:11]
	s_mov_b64 s[40:41], -1
	s_cbranch_vccnz .LBB0_1079
	v_readlane_b32 s36, v254, 54
	v_lshlrev_b64 v[132:133], 5, v[130:131]
	v_readlane_b32 s37, v254, 55
	s_mov_b64 s[40:41], 0
	s_nop 0
	v_lshl_add_u64 v[132:133], s[36:37], 0, v[132:133]
	v_lshl_add_u64 v[132:133], s[2:3], 2, v[132:133]

.LBB0_1082:
	s_or_b64 exec, exec, s[26:27]
	v_cmp_gt_i32_e32 vcc, s43, v130
	s_and_b64 s[36:37], s[20:21], vcc
	s_and_saveexec_b64 s[26:27], s[36:37]
	s_cbranch_execz .LBB0_1084
	s_add_u32 s24, s40, s24
	v_lshlrev_b32_e32 v129, 10, v130
	s_addc_u32 s25, s41, s25
	v_and_b32_e32 v130, 0x3fc00, v129
	v_mov_b32_e32 v131, v153
	v_lshl_add_u64 v[130:131], s[24:25], 0, v[130:131]
	v_mov_b32_e32 v129, v153
	v_lshl_add_u64 v[130:131], v[130:131], 0, v[128:129]
	global_store_dwordx4 v[130:131], v[76:79], off
	global_store_dwordx4 v[130:131], v[72:75], off offset:64
	global_store_dwordx4 v[130:131], v[68:71], off offset:512
	global_store_dwordx4 v[130:131], v[64:67], off offset:576
.LBB0_1084:
	s_or_b64 exec, exec, s[26:27]
	v_readlane_b32 s24, v254, 56
	v_readlane_b32 s25, v254, 57
	v_add_u32_e32 v132, 0x80, v172
	s_mov_b32 s23, s3
	v_mov_b64_e32 v[130:131], s[24:25]
	v_mad_i64_i32 v[130:131], s[24:25], v132, s67, v[130:131]
	v_mul_f32_e32 v129, v61, v61
	s_waitcnt lgkmcnt(0)
	v_mul_f32_e32 v134, v63, v63
	v_lshl_add_u64 v[130:131], v[130:131], 0, s[22:23]
	v_fmac_f32_e32 v129, v60, v60
	v_fmac_f32_e32 v134, v62, v62
	v_lshl_add_u64 v[130:131], v[130:131], 0, v[152:153]
	v_add_f32_e32 v129, v129, v134
	v_cvt_pk_bf16_f32 v134, v60, v61
	v_cvt_pk_bf16_f32 v135, v62, v63
	global_store_dwordx2 v[130:131], v[134:135], off
	v_mul_f32_e32 v134, v57, v57
	v_mul_f32_e32 v135, v59, v59
	v_fmac_f32_e32 v134, v56, v56
	v_fmac_f32_e32 v135, v58, v58
	v_add_f32_e32 v134, v134, v135
	v_add_f32_e32 v129, v129, v134
	v_cvt_pk_bf16_f32 v134, v56, v57
	v_cvt_pk_bf16_f32 v135, v58, v59
	global_store_dwordx2 v[130:131], v[134:135], off offset:32
	v_mul_f32_e32 v134, v53, v53
	v_mul_f32_e32 v135, v55, v55
	v_fmac_f32_e32 v134, v52, v52
	v_fmac_f32_e32 v135, v54, v54
	v_add_f32_e32 v134, v134, v135
	v_add_f32_e32 v129, v129, v134
	v_cvt_pk_bf16_f32 v134, v52, v53
	v_cvt_pk_bf16_f32 v135, v54, v55
	global_store_dwordx2 v[130:131], v[134:135], off offset:256
	v_mul_f32_e32 v134, v49, v49
	v_mul_f32_e32 v135, v51, v51
	v_fmac_f32_e32 v134, v48, v48
	v_fmac_f32_e32 v135, v50, v50
	v_add_f32_e32 v134, v134, v135
	v_add_f32_e32 v129, v129, v134
	v_cvt_pk_bf16_f32 v134, v48, v49
	v_cvt_pk_bf16_f32 v135, v50, v51
	global_store_dwordx2 v[130:131], v[134:135], off offset:288
	ds_bpermute_b32 v130, v137, v129
	v_ashrrev_i32_e32 v133, 31, v132
	s_waitcnt lgkmcnt(0)
	v_add_f32_e32 v129, v129, v130
	ds_bpermute_b32 v134, v136, v129
	s_and_saveexec_b64 s[24:25], s[8:9]
	v_readlane_b32 s36, v252, 3
	v_readlane_b32 s37, v252, 4
	s_cbranch_execz .LBB0_1090
	s_and_b64 vcc, exec, s[10:11]
	s_mov_b64 s[26:27], -1
	s_cbranch_vccnz .LBB0_1087
	v_readlane_b32 s26, v254, 54
	v_lshlrev_b64 v[130:131], 5, v[132:133]
	v_readlane_b32 s27, v254, 55
	s_nop 1
	v_lshl_add_u64 v[130:131], s[26:27], 0, v[130:131]
	v_lshl_add_u64 v[130:131], s[2:3], 2, v[130:131]
	s_mov_b64 s[26:27], 0

.LBB0_1089:
	s_lshl_b32 s26, s89, 2
	s_mov_b32 s27, s3
	s_waitcnt lgkmcnt(0)
	v_add_f32_e32 v129, v129, v134
	v_lshl_add_u64 v[130:131], v[130:131], 0, s[26:27]
	global_store_dword v[130:131], v129, off
.LBB0_1090:
	s_or_b64 exec, exec, s[24:25]
	v_ashrrev_i32_e32 v129, 7, v132
	v_and_b32_e32 v129, -2, v129
	v_readlane_b32 s23, v254, 22
	s_nop 1
	v_add_u32_e32 v130, s23, v129
	v_ashrrev_i32_e32 v131, 31, v130
	s_movk_i32 s23, 0xf80
	v_lshlrev_b64 v[130:131], 18, v[130:131]
	v_cmp_gt_i32_e32 vcc, s23, v172
	s_and_b64 s[26:27], s[20:21], vcc
	v_lshl_add_u64 v[130:131], s[40:41], 0, v[130:131]
	s_and_saveexec_b64 s[24:25], s[26:27]
	s_cbranch_execz .LBB0_1092
	v_lshlrev_b32_e32 v129, 10, v132
	v_and_b32_e32 v132, 0x33c00, v129
	v_mov_b32_e32 v133, v153
	v_lshl_add_u64 v[132:133], v[130:131], 0, v[132:133]
	v_mov_b32_e32 v129, v153
	v_lshl_add_u64 v[132:133], v[132:133], 0, v[128:129]
	global_store_dwordx4 v[132:133], v[60:63], off
	global_store_dwordx4 v[132:133], v[56:59], off offset:64
	global_store_dwordx4 v[132:133], v[52:55], off offset:512
	global_store_dwordx4 v[132:133], v[48:51], off offset:576
.LBB0_1092:
	s_or_b64 exec, exec, s[24:25]
	v_readlane_b32 s24, v254, 56
	v_readlane_b32 s25, v254, 57
	v_add_u32_e32 v132, 0x90, v172
	s_mov_b32 s23, s3
	s_waitcnt lgkmcnt(0)
	v_mov_b64_e32 v[134:135], s[24:25]
	v_mad_i64_i32 v[134:135], s[24:25], v132, s67, v[134:135]
	v_mul_f32_e32 v129, v45, v45
	v_mul_f32_e32 v138, v47, v47
	v_lshl_add_u64 v[134:135], v[134:135], 0, s[22:23]
	v_fmac_f32_e32 v129, v44, v44
	v_fmac_f32_e32 v138, v46, v46
	v_lshl_add_u64 v[134:135], v[134:135], 0, v[152:153]
	v_add_f32_e32 v129, v129, v138
	v_cvt_pk_bf16_f32 v138, v44, v45
	v_cvt_pk_bf16_f32 v139, v46, v47
	global_store_dwordx2 v[134:135], v[138:139], off
	v_mul_f32_e32 v138, v41, v41
	v_mul_f32_e32 v139, v43, v43
	v_fmac_f32_e32 v138, v40, v40
	v_fmac_f32_e32 v139, v42, v42
	v_add_f32_e32 v138, v138, v139
	v_add_f32_e32 v129, v129, v138
	v_cvt_pk_bf16_f32 v138, v40, v41
	v_cvt_pk_bf16_f32 v139, v42, v43
	global_store_dwordx2 v[134:135], v[138:139], off offset:32
	v_mul_f32_e32 v138, v37, v37
	v_mul_f32_e32 v139, v39, v39
	v_fmac_f32_e32 v138, v36, v36
	v_fmac_f32_e32 v139, v38, v38
	v_add_f32_e32 v138, v138, v139
	v_add_f32_e32 v129, v129, v138
	v_cvt_pk_bf16_f32 v138, v36, v37
	v_cvt_pk_bf16_f32 v139, v38, v39
	global_store_dwordx2 v[134:135], v[138:139], off offset:256
	v_mul_f32_e32 v138, v33, v33
	v_mul_f32_e32 v139, v35, v35
	v_fmac_f32_e32 v138, v32, v32
	v_fmac_f32_e32 v139, v34, v34
	v_add_f32_e32 v138, v138, v139
	v_add_f32_e32 v129, v129, v138
	v_cvt_pk_bf16_f32 v138, v32, v33
	v_cvt_pk_bf16_f32 v139, v34, v35
	global_store_dwordx2 v[134:135], v[138:139], off offset:288
	ds_bpermute_b32 v134, v137, v129
	v_ashrrev_i32_e32 v133, 31, v132
	s_waitcnt lgkmcnt(0)
	v_add_f32_e32 v129, v129, v134
	ds_bpermute_b32 v138, v136, v129
	s_and_saveexec_b64 s[24:25], s[8:9]
	s_cbranch_execz .LBB0_1098
	s_and_b64 vcc, exec, s[10:11]
	s_mov_b64 s[26:27], -1
	s_cbranch_vccnz .LBB0_1095
	v_readlane_b32 s26, v254, 54
	v_lshlrev_b64 v[134:135], 5, v[132:133]
	v_readlane_b32 s27, v254, 55
	s_nop 1
	v_lshl_add_u64 v[134:135], s[26:27], 0, v[134:135]
	v_lshl_add_u64 v[134:135], s[2:3], 2, v[134:135]
	s_mov_b64 s[26:27], 0

.LBB0_1097:
	s_lshl_b32 s26, s89, 2
	s_mov_b32 s27, s3
	s_waitcnt lgkmcnt(0)
	v_add_f32_e32 v129, v129, v138
	v_lshl_add_u64 v[134:135], v[134:135], 0, s[26:27]
	global_store_dword v[134:135], v129, off
.LBB0_1098:
	s_or_b64 exec, exec, s[24:25]
	s_movk_i32 s23, 0xf70
	v_cmp_gt_i32_e32 vcc, s23, v172
	s_and_b64 s[26:27], s[20:21], vcc
	s_and_saveexec_b64 s[24:25], s[26:27]
	s_cbranch_execz .LBB0_1100
	v_lshlrev_b32_e32 v129, 10, v132
	v_and_b32_e32 v132, 0x37c00, v129
	v_mov_b32_e32 v133, v153
	v_lshl_add_u64 v[132:133], v[130:131], 0, v[132:133]
	v_mov_b32_e32 v129, v153
	v_lshl_add_u64 v[132:133], v[132:133], 0, v[128:129]
	global_store_dwordx4 v[132:133], v[44:47], off
	global_store_dwordx4 v[132:133], v[40:43], off offset:64
	global_store_dwordx4 v[132:133], v[36:39], off offset:512
	global_store_dwordx4 v[132:133], v[32:35], off offset:576
.LBB0_1100:
	s_or_b64 exec, exec, s[24:25]
	v_readlane_b32 s24, v254, 56
	v_readlane_b32 s25, v254, 57
	v_add_u32_e32 v132, 0xa0, v172
	s_mov_b32 s23, s3
	v_mov_b64_e32 v[134:135], s[24:25]
	v_mad_i64_i32 v[134:135], s[24:25], v132, s67, v[134:135]
	v_mul_f32_e32 v129, v29, v29
	s_waitcnt lgkmcnt(0)
	v_mul_f32_e32 v138, v31, v31
	v_lshl_add_u64 v[134:135], v[134:135], 0, s[22:23]
	v_fmac_f32_e32 v129, v28, v28
	v_fmac_f32_e32 v138, v30, v30
	v_lshl_add_u64 v[134:135], v[134:135], 0, v[152:153]
	v_add_f32_e32 v129, v129, v138
	v_cvt_pk_bf16_f32 v138, v28, v29
	v_cvt_pk_bf16_f32 v139, v30, v31
	global_store_dwordx2 v[134:135], v[138:139], off
	v_mul_f32_e32 v138, v25, v25
	v_mul_f32_e32 v139, v27, v27
	v_fmac_f32_e32 v138, v24, v24
	v_fmac_f32_e32 v139, v26, v26
	v_add_f32_e32 v138, v138, v139
	v_add_f32_e32 v129, v129, v138
	v_cvt_pk_bf16_f32 v138, v24, v25
	v_cvt_pk_bf16_f32 v139, v26, v27
	global_store_dwordx2 v[134:135], v[138:139], off offset:32
	v_mul_f32_e32 v138, v21, v21
	v_mul_f32_e32 v139, v23, v23
	v_fmac_f32_e32 v138, v20, v20
	v_fmac_f32_e32 v139, v22, v22
	v_add_f32_e32 v138, v138, v139
	v_add_f32_e32 v129, v129, v138
	v_cvt_pk_bf16_f32 v138, v20, v21
	v_cvt_pk_bf16_f32 v139, v22, v23
	global_store_dwordx2 v[134:135], v[138:139], off offset:256
	v_mul_f32_e32 v138, v17, v17
	v_mul_f32_e32 v139, v19, v19
	v_fmac_f32_e32 v138, v16, v16
	v_fmac_f32_e32 v139, v18, v18
	v_add_f32_e32 v138, v138, v139
	v_add_f32_e32 v129, v129, v138
	v_cvt_pk_bf16_f32 v138, v16, v17
	v_cvt_pk_bf16_f32 v139, v18, v19
	global_store_dwordx2 v[134:135], v[138:139], off offset:288
	ds_bpermute_b32 v134, v137, v129
	v_ashrrev_i32_e32 v133, 31, v132
	s_waitcnt lgkmcnt(0)
	v_add_f32_e32 v129, v129, v134
	ds_bpermute_b32 v138, v136, v129
	s_and_saveexec_b64 s[24:25], s[8:9]
	s_cbranch_execz .LBB0_1106
	s_and_b64 vcc, exec, s[10:11]
	s_mov_b64 s[26:27], -1
	s_cbranch_vccnz .LBB0_1103
	v_readlane_b32 s26, v254, 54
	v_lshlrev_b64 v[134:135], 5, v[132:133]
	v_readlane_b32 s27, v254, 55
	s_nop 1
	v_lshl_add_u64 v[134:135], s[26:27], 0, v[134:135]
	v_lshl_add_u64 v[134:135], s[2:3], 2, v[134:135]
	s_mov_b64 s[26:27], 0

.LBB0_1106:
	s_or_b64 exec, exec, s[24:25]
	s_movk_i32 s23, 0xf60
	v_cmp_gt_i32_e32 vcc, s23, v172
	s_and_b64 s[26:27], s[20:21], vcc
	s_and_saveexec_b64 s[24:25], s[26:27]
	s_cbranch_execz .LBB0_1108
	v_lshlrev_b32_e32 v129, 10, v132
	v_and_b32_e32 v132, 0x3bc00, v129
	v_mov_b32_e32 v133, v153
	v_lshl_add_u64 v[132:133], v[130:131], 0, v[132:133]
	v_mov_b32_e32 v129, v153
	v_lshl_add_u64 v[132:133], v[132:133], 0, v[128:129]
	global_store_dwordx4 v[132:133], v[28:31], off
	global_store_dwordx4 v[132:133], v[24:27], off offset:64
	global_store_dwordx4 v[132:133], v[20:23], off offset:512
	global_store_dwordx4 v[132:133], v[16:19], off offset:576
.LBB0_1108:
	s_or_b64 exec, exec, s[24:25]
	v_readlane_b32 s24, v254, 56
	v_readlane_b32 s25, v254, 57
	v_add_u32_e32 v132, 0xb0, v172
	s_mov_b32 s23, s3
	v_mov_b64_e32 v[134:135], s[24:25]
	v_mad_i64_i32 v[134:135], s[24:25], v132, s67, v[134:135]
	v_mul_f32_e32 v129, v13, v13
	s_waitcnt lgkmcnt(0)
	v_mul_f32_e32 v138, v15, v15
	v_lshl_add_u64 v[134:135], v[134:135], 0, s[22:23]
	v_fmac_f32_e32 v129, v12, v12
	v_fmac_f32_e32 v138, v14, v14
	v_lshl_add_u64 v[134:135], v[134:135], 0, v[152:153]
	v_add_f32_e32 v129, v129, v138
	v_cvt_pk_bf16_f32 v138, v12, v13
	v_cvt_pk_bf16_f32 v139, v14, v15
	global_store_dwordx2 v[134:135], v[138:139], off
	v_mul_f32_e32 v138, v9, v9
	v_mul_f32_e32 v139, v11, v11
	v_fmac_f32_e32 v138, v8, v8
	v_fmac_f32_e32 v139, v10, v10
	v_add_f32_e32 v138, v138, v139
	v_add_f32_e32 v129, v129, v138
	v_cvt_pk_bf16_f32 v138, v8, v9
	v_cvt_pk_bf16_f32 v139, v10, v11
	global_store_dwordx2 v[134:135], v[138:139], off offset:32
	v_mul_f32_e32 v138, v5, v5
	v_mul_f32_e32 v139, v7, v7
	v_fmac_f32_e32 v138, v4, v4
	v_fmac_f32_e32 v139, v6, v6
	v_add_f32_e32 v138, v138, v139
	v_add_f32_e32 v129, v129, v138
	v_cvt_pk_bf16_f32 v138, v4, v5
	v_cvt_pk_bf16_f32 v139, v6, v7
	global_store_dwordx2 v[134:135], v[138:139], off offset:256
	v_mul_f32_e32 v138, v1, v1
	v_mul_f32_e32 v139, v3, v3
	v_fmac_f32_e32 v138, v0, v0
	v_fmac_f32_e32 v139, v2, v2
	v_add_f32_e32 v138, v138, v139
	v_add_f32_e32 v129, v129, v138
	v_cvt_pk_bf16_f32 v138, v0, v1
	v_cvt_pk_bf16_f32 v139, v2, v3
	global_store_dwordx2 v[134:135], v[138:139], off offset:288
	ds_bpermute_b32 v134, v137, v129
	v_ashrrev_i32_e32 v133, 31, v132
	s_waitcnt lgkmcnt(0)
	v_add_f32_e32 v129, v129, v134
	ds_bpermute_b32 v136, v136, v129
	s_and_saveexec_b64 s[22:23], s[8:9]
	v_readlane_b32 s24, v254, 50
	v_readlane_b32 s25, v254, 51
	s_cbranch_execz .LBB0_1114
	s_and_b64 vcc, exec, s[10:11]
	s_mov_b64 s[8:9], -1
	s_cbranch_vccnz .LBB0_1111
	v_readlane_b32 s8, v254, 54
	v_lshlrev_b64 v[134:135], 5, v[132:133]
	v_readlane_b32 s9, v254, 55
	s_nop 1
	v_lshl_add_u64 v[134:135], s[8:9], 0, v[134:135]
	v_lshl_add_u64 v[134:135], s[2:3], 2, v[134:135]
	s_mov_b64 s[8:9], 0

.LBB0_1113:
	s_lshl_b32 s2, s89, 2
	s_waitcnt lgkmcnt(0)
	v_add_f32_e32 v129, v129, v136
	v_lshl_add_u64 v[134:135], v[134:135], 0, s[2:3]
	global_store_dword v[134:135], v129, off
.LBB0_1114:
	s_or_b64 exec, exec, s[22:23]
	s_movk_i32 s2, 0xf50
	v_cmp_gt_i32_e32 vcc, s2, v172
	s_and_b64 s[10:11], s[20:21], vcc
	s_and_saveexec_b64 s[8:9], s[10:11]
	s_cbranch_execz .LBB0_1116
	v_lshlrev_b32_e32 v129, 10, v132
	v_and_b32_e32 v152, 0x3fc00, v129
	v_lshl_add_u64 v[130:131], v[130:131], 0, v[152:153]
	v_mov_b32_e32 v129, v153
	v_lshl_add_u64 v[128:129], v[130:131], 0, v[128:129]
	global_store_dwordx4 v[128:129], v[12:15], off
	global_store_dwordx4 v[128:129], v[8:11], off offset:64
	global_store_dwordx4 v[128:129], v[4:7], off offset:512
	global_store_dwordx4 v[128:129], v[0:3], off offset:576

.LBB0_1118:
	s_andn2_b64 vcc, exec, s[8:9]
	s_cbranch_vccnz .LBB0_1120
	v_mul_f32_e32 v130, 0xbfb8aa3b, v124
	v_mul_f32_e32 v131, 0xbfb8aa3b, v125
	v_mul_f32_e32 v132, 0xbfb8aa3b, v126
	v_mul_f32_e32 v133, 0xbfb8aa3b, v127
	v_mul_f32_e32 v138, 0xbfb8aa3b, v122
	v_mul_f32_e32 v139, 0xbfb8aa3b, v123
	v_exp_f32_e32 v130, v130
	v_exp_f32_e32 v131, v131
	v_exp_f32_e32 v132, v132
	v_exp_f32_e32 v133, v133
	v_exp_f32_e32 v138, v138
	v_exp_f32_e32 v139, v139
	s_waitcnt lgkmcnt(0)
	v_mul_f32_e32 v136, 0xbfb8aa3b, v120
	v_mul_f32_e32 v137, 0xbfb8aa3b, v121
	v_exp_f32_e32 v136, v136
	v_exp_f32_e32 v137, v137
	v_add_f32_e32 v130, 1.0, v130
	v_add_f32_e32 v131, 1.0, v131
	v_add_f32_e32 v132, 1.0, v132
	v_add_f32_e32 v133, 1.0, v133
	v_add_f32_e32 v138, 1.0, v138
	v_add_f32_e32 v139, 1.0, v139
	v_rcp_f32_e32 v130, v130
	v_rcp_f32_e32 v131, v131
	v_rcp_f32_e32 v132, v132
	v_rcp_f32_e32 v133, v133
	v_rcp_f32_e32 v138, v138
	v_rcp_f32_e32 v139, v139
	v_add_f32_e32 v136, 1.0, v136
	v_add_f32_e32 v137, 1.0, v137
	v_ashrrev_i32_e32 v173, 31, v172
	v_rcp_f32_e32 v136, v136
	v_rcp_f32_e32 v137, v137
	v_lshlrev_b64 v[128:129], 11, v[172:173]
	v_pk_mul_f32 v[130:131], v[124:125], v[130:131]
	v_pk_mul_f32 v[132:133], v[126:127], v[132:133]
	v_pk_mul_f32 v[138:139], v[122:123], v[138:139]
	v_lshl_add_u64 v[128:129], s[18:19], 0, v[128:129]
	s_lshl_b32 s2, s14, 9
	v_cvt_pk_bf16_f32 v130, v130, v131
	v_cvt_pk_bf16_f32 v131, v132, v133
	v_cvt_pk_bf16_f32 v133, v138, v139
	v_mul_f32_e32 v138, 0xbfb8aa3b, v116
	v_mul_f32_e32 v139, 0xbfb8aa3b, v117
	v_lshl_add_u64 v[128:129], v[128:129], 0, s[2:3]
	v_lshlrev_b32_e32 v152, 1, v186
	v_exp_f32_e32 v138, v138
	v_exp_f32_e32 v139, v139
	v_lshl_add_u64 v[128:129], v[128:129], 0, v[152:153]
	v_pk_mul_f32 v[136:137], v[120:121], v[136:137]
	s_mov_b32 s8, 0xeefe000
	v_cvt_pk_bf16_f32 v132, v136, v137
	v_add_co_u32_e32 v136, vcc, s8, v128
	s_mov_b64 s[10:11], 0xeefe800
	s_nop 0
	v_addc_co_u32_e32 v137, vcc, 0, v129, vcc
	global_store_dwordx4 v[136:137], v[130:133], off offset:2048
	v_mul_f32_e32 v136, 0xbfb8aa3b, v112
	v_mul_f32_e32 v137, 0xbfb8aa3b, v113
	v_add_f32_e32 v130, 1.0, v138
	v_add_f32_e32 v131, 1.0, v139
	v_mul_f32_e32 v132, 0xbfb8aa3b, v118
	v_mul_f32_e32 v133, 0xbfb8aa3b, v119
	v_mul_f32_e32 v138, 0xbfb8aa3b, v114
	v_mul_f32_e32 v139, 0xbfb8aa3b, v115
	v_exp_f32_e32 v132, v132
	v_exp_f32_e32 v133, v133
	v_exp_f32_e32 v136, v136
	v_exp_f32_e32 v137, v137
	v_exp_f32_e32 v138, v138
	v_exp_f32_e32 v139, v139
	v_add_f32_e32 v132, 1.0, v132
	v_add_f32_e32 v133, 1.0, v133
	v_add_f32_e32 v136, 1.0, v136
	v_add_f32_e32 v137, 1.0, v137
	v_add_f32_e32 v138, 1.0, v138
	v_add_f32_e32 v139, 1.0, v139
	v_rcp_f32_e32 v130, v130
	v_rcp_f32_e32 v131, v131
	v_rcp_f32_e32 v132, v132
	v_rcp_f32_e32 v133, v133
	v_rcp_f32_e32 v136, v136
	v_rcp_f32_e32 v137, v137
	v_rcp_f32_e32 v138, v138
	v_rcp_f32_e32 v139, v139
	v_pk_mul_f32 v[130:131], v[116:117], v[130:131]
	v_pk_mul_f32 v[132:133], v[118:119], v[132:133]
	v_pk_mul_f32 v[136:137], v[112:113], v[136:137]
	v_pk_mul_f32 v[138:139], v[114:115], v[138:139]
	v_lshl_add_u64 v[134:135], v[128:129], 0, s[10:11]
	v_cvt_pk_bf16_f32 v130, v130, v131
	v_cvt_pk_bf16_f32 v131, v132, v133
	v_cvt_pk_bf16_f32 v132, v136, v137
	v_cvt_pk_bf16_f32 v133, v138, v139
	global_store_dwordx4 v[134:135], v[130:133], off offset:256
	v_mul_f32_e32 v138, 0xbfb8aa3b, v104
	v_mul_f32_e32 v139, 0xbfb8aa3b, v105
	v_or_b32_e32 v130, 16, v172
	v_ashrrev_i32_e32 v131, 31, v130
	v_lshlrev_b64 v[130:131], 11, v[130:131]
	v_lshl_add_u64 v[130:131], s[18:19], 0, v[130:131]
	v_lshl_add_u64 v[130:131], v[130:131], 0, s[2:3]
	v_lshl_add_u64 v[134:135], v[130:131], 0, v[152:153]
	v_mul_f32_e32 v130, 0xbfb8aa3b, v108
	v_mul_f32_e32 v131, 0xbfb8aa3b, v109
	v_mul_f32_e32 v132, 0xbfb8aa3b, v110
	v_mul_f32_e32 v133, 0xbfb8aa3b, v111
	v_exp_f32_e32 v130, v130
	v_exp_f32_e32 v131, v131
	v_exp_f32_e32 v132, v132
	v_exp_f32_e32 v133, v133
	v_exp_f32_e32 v138, v138
	v_exp_f32_e32 v139, v139
	v_mul_f32_e32 v140, 0xbfb8aa3b, v106
	v_mul_f32_e32 v141, 0xbfb8aa3b, v107
	v_add_f32_e32 v130, 1.0, v130
	v_add_f32_e32 v131, 1.0, v131
	v_add_f32_e32 v132, 1.0, v132
	v_add_f32_e32 v133, 1.0, v133
	v_add_f32_e32 v138, 1.0, v138
	v_add_f32_e32 v139, 1.0, v139
	v_exp_f32_e32 v140, v140
	v_exp_f32_e32 v141, v141
	v_rcp_f32_e32 v130, v130
	v_rcp_f32_e32 v131, v131
	v_rcp_f32_e32 v132, v132
	v_rcp_f32_e32 v133, v133
	v_rcp_f32_e32 v138, v138
	v_rcp_f32_e32 v139, v139
	v_add_f32_e32 v140, 1.0, v140
	v_add_f32_e32 v141, 1.0, v141
	v_rcp_f32_e32 v140, v140
	v_rcp_f32_e32 v141, v141
	v_pk_mul_f32 v[130:131], v[108:109], v[130:131]
	v_pk_mul_f32 v[132:133], v[110:111], v[132:133]
	v_pk_mul_f32 v[138:139], v[104:105], v[138:139]
	v_cvt_pk_bf16_f32 v130, v130, v131
	v_cvt_pk_bf16_f32 v131, v132, v133
	v_cvt_pk_bf16_f32 v132, v138, v139
	v_mul_f32_e32 v138, 0xbfb8aa3b, v100
	v_mul_f32_e32 v139, 0xbfb8aa3b, v101
	v_exp_f32_e32 v138, v138
	v_exp_f32_e32 v139, v139
	v_lshl_add_u64 v[136:137], v[134:135], 0, s[10:11]
	v_pk_mul_f32 v[140:141], v[106:107], v[140:141]
	v_add_co_u32_e32 v134, vcc, s8, v134
	v_cvt_pk_bf16_f32 v133, v140, v141
	s_nop 0
	v_addc_co_u32_e32 v135, vcc, 0, v135, vcc
	global_store_dwordx4 v[134:135], v[130:133], off offset:2048
	v_mul_f32_e32 v134, 0xbfb8aa3b, v96
	v_mul_f32_e32 v135, 0xbfb8aa3b, v97
	v_add_f32_e32 v130, 1.0, v138
	v_add_f32_e32 v131, 1.0, v139
	v_mul_f32_e32 v132, 0xbfb8aa3b, v102
	v_mul_f32_e32 v133, 0xbfb8aa3b, v103
	v_mul_f32_e32 v138, 0xbfb8aa3b, v98
	v_mul_f32_e32 v139, 0xbfb8aa3b, v99
	v_exp_f32_e32 v132, v132
	v_exp_f32_e32 v133, v133
	v_exp_f32_e32 v134, v134
	v_exp_f32_e32 v135, v135
	v_exp_f32_e32 v138, v138
	v_exp_f32_e32 v139, v139
	v_add_f32_e32 v132, 1.0, v132
	v_add_f32_e32 v133, 1.0, v133
	v_add_f32_e32 v134, 1.0, v134
	v_add_f32_e32 v135, 1.0, v135
	v_add_f32_e32 v138, 1.0, v138
	v_add_f32_e32 v139, 1.0, v139
	v_rcp_f32_e32 v130, v130
	v_rcp_f32_e32 v131, v131
	v_rcp_f32_e32 v132, v132
	v_rcp_f32_e32 v133, v133
	v_rcp_f32_e32 v134, v134
	v_rcp_f32_e32 v135, v135
	v_rcp_f32_e32 v138, v138
	v_rcp_f32_e32 v139, v139
	v_pk_mul_f32 v[130:131], v[100:101], v[130:131]
	v_pk_mul_f32 v[132:133], v[102:103], v[132:133]
	v_pk_mul_f32 v[134:135], v[96:97], v[134:135]
	v_pk_mul_f32 v[138:139], v[98:99], v[138:139]
	v_cvt_pk_bf16_f32 v130, v130, v131
	v_cvt_pk_bf16_f32 v131, v132, v133
	v_cvt_pk_bf16_f32 v132, v134, v135
	v_cvt_pk_bf16_f32 v133, v138, v139
	global_store_dwordx4 v[136:137], v[130:133], off offset:256
	v_mul_f32_e32 v138, 0xbfb8aa3b, v88
	v_mul_f32_e32 v139, 0xbfb8aa3b, v89
	v_or_b32_e32 v130, 32, v172
	v_ashrrev_i32_e32 v131, 31, v130
	v_lshlrev_b64 v[130:131], 11, v[130:131]
	v_lshl_add_u64 v[130:131], s[18:19], 0, v[130:131]
	v_lshl_add_u64 v[130:131], v[130:131], 0, s[2:3]
	v_lshl_add_u64 v[134:135], v[130:131], 0, v[152:153]
	v_mul_f32_e32 v130, 0xbfb8aa3b, v92
	v_mul_f32_e32 v131, 0xbfb8aa3b, v93
	v_mul_f32_e32 v132, 0xbfb8aa3b, v94
	v_mul_f32_e32 v133, 0xbfb8aa3b, v95
	v_exp_f32_e32 v130, v130
	v_exp_f32_e32 v131, v131
	v_exp_f32_e32 v132, v132
	v_exp_f32_e32 v133, v133
	v_exp_f32_e32 v138, v138
	v_exp_f32_e32 v139, v139
	v_mul_f32_e32 v140, 0xbfb8aa3b, v90
	v_mul_f32_e32 v141, 0xbfb8aa3b, v91
	v_add_f32_e32 v130, 1.0, v130
	v_add_f32_e32 v131, 1.0, v131
	v_add_f32_e32 v132, 1.0, v132
	v_add_f32_e32 v133, 1.0, v133
	v_add_f32_e32 v138, 1.0, v138
	v_add_f32_e32 v139, 1.0, v139
	v_exp_f32_e32 v140, v140
	v_exp_f32_e32 v141, v141
	v_rcp_f32_e32 v130, v130
	v_rcp_f32_e32 v131, v131
	v_rcp_f32_e32 v132, v132
	v_rcp_f32_e32 v133, v133
	v_rcp_f32_e32 v138, v138
	v_rcp_f32_e32 v139, v139
	v_add_f32_e32 v140, 1.0, v140
	v_add_f32_e32 v141, 1.0, v141
	v_rcp_f32_e32 v140, v140
	v_rcp_f32_e32 v141, v141
	v_pk_mul_f32 v[130:131], v[92:93], v[130:131]
	v_pk_mul_f32 v[132:133], v[94:95], v[132:133]
	v_pk_mul_f32 v[138:139], v[88:89], v[138:139]
	v_cvt_pk_bf16_f32 v130, v130, v131
	v_cvt_pk_bf16_f32 v131, v132, v133
	v_cvt_pk_bf16_f32 v132, v138, v139
	v_mul_f32_e32 v138, 0xbfb8aa3b, v84
	v_mul_f32_e32 v139, 0xbfb8aa3b, v85
	v_exp_f32_e32 v138, v138
	v_exp_f32_e32 v139, v139
	v_lshl_add_u64 v[136:137], v[134:135], 0, s[10:11]
	v_pk_mul_f32 v[140:141], v[90:91], v[140:141]
	v_add_co_u32_e32 v134, vcc, s8, v134
	v_cvt_pk_bf16_f32 v133, v140, v141
	s_nop 0
	v_addc_co_u32_e32 v135, vcc, 0, v135, vcc
	global_store_dwordx4 v[134:135], v[130:133], off offset:2048
	v_mul_f32_e32 v134, 0xbfb8aa3b, v80
	v_mul_f32_e32 v135, 0xbfb8aa3b, v81
	v_add_f32_e32 v130, 1.0, v138
	v_add_f32_e32 v131, 1.0, v139
	v_mul_f32_e32 v132, 0xbfb8aa3b, v86
	v_mul_f32_e32 v133, 0xbfb8aa3b, v87
	v_mul_f32_e32 v138, 0xbfb8aa3b, v82
	v_mul_f32_e32 v139, 0xbfb8aa3b, v83
	v_exp_f32_e32 v132, v132
	v_exp_f32_e32 v133, v133
	v_exp_f32_e32 v134, v134
	v_exp_f32_e32 v135, v135
	v_exp_f32_e32 v138, v138
	v_exp_f32_e32 v139, v139
	v_add_f32_e32 v132, 1.0, v132
	v_add_f32_e32 v133, 1.0, v133
	v_add_f32_e32 v134, 1.0, v134
	v_add_f32_e32 v135, 1.0, v135
	v_add_f32_e32 v138, 1.0, v138
	v_add_f32_e32 v139, 1.0, v139
	v_rcp_f32_e32 v130, v130
	v_rcp_f32_e32 v131, v131
	v_rcp_f32_e32 v132, v132
	v_rcp_f32_e32 v133, v133
	v_rcp_f32_e32 v134, v134
	v_rcp_f32_e32 v135, v135
	v_rcp_f32_e32 v138, v138
	v_rcp_f32_e32 v139, v139
	v_pk_mul_f32 v[130:131], v[84:85], v[130:131]
	v_pk_mul_f32 v[132:133], v[86:87], v[132:133]
	v_pk_mul_f32 v[134:135], v[80:81], v[134:135]
	v_pk_mul_f32 v[138:139], v[82:83], v[138:139]
	v_cvt_pk_bf16_f32 v130, v130, v131
	v_cvt_pk_bf16_f32 v131, v132, v133
	v_cvt_pk_bf16_f32 v132, v134, v135
	v_cvt_pk_bf16_f32 v133, v138, v139
	global_store_dwordx4 v[136:137], v[130:133], off offset:256
	v_mul_f32_e32 v138, 0xbfb8aa3b, v72
	v_mul_f32_e32 v139, 0xbfb8aa3b, v73
	v_or_b32_e32 v130, 48, v172
	v_ashrrev_i32_e32 v131, 31, v130
	v_lshlrev_b64 v[130:131], 11, v[130:131]
	v_lshl_add_u64 v[130:131], s[18:19], 0, v[130:131]
	v_lshl_add_u64 v[130:131], v[130:131], 0, s[2:3]
	v_lshl_add_u64 v[134:135], v[130:131], 0, v[152:153]
	v_mul_f32_e32 v130, 0xbfb8aa3b, v76
	v_mul_f32_e32 v131, 0xbfb8aa3b, v77
	v_mul_f32_e32 v132, 0xbfb8aa3b, v78
	v_mul_f32_e32 v133, 0xbfb8aa3b, v79
	v_exp_f32_e32 v130, v130
	v_exp_f32_e32 v131, v131
	v_exp_f32_e32 v132, v132
	v_exp_f32_e32 v133, v133
	v_exp_f32_e32 v138, v138
	v_exp_f32_e32 v139, v139
	v_mul_f32_e32 v140, 0xbfb8aa3b, v74
	v_mul_f32_e32 v141, 0xbfb8aa3b, v75
	v_add_f32_e32 v130, 1.0, v130
	v_add_f32_e32 v131, 1.0, v131
	v_add_f32_e32 v132, 1.0, v132
	v_add_f32_e32 v133, 1.0, v133
	v_add_f32_e32 v138, 1.0, v138
	v_add_f32_e32 v139, 1.0, v139
	v_exp_f32_e32 v140, v140
	v_exp_f32_e32 v141, v141
	v_rcp_f32_e32 v130, v130
	v_rcp_f32_e32 v131, v131
	v_rcp_f32_e32 v132, v132
	v_rcp_f32_e32 v133, v133
	v_rcp_f32_e32 v138, v138
	v_rcp_f32_e32 v139, v139
	v_add_f32_e32 v140, 1.0, v140
	v_add_f32_e32 v141, 1.0, v141
	v_rcp_f32_e32 v140, v140
	v_rcp_f32_e32 v141, v141
	v_pk_mul_f32 v[130:131], v[76:77], v[130:131]
	v_pk_mul_f32 v[132:133], v[78:79], v[132:133]
	v_pk_mul_f32 v[138:139], v[72:73], v[138:139]
	v_cvt_pk_bf16_f32 v130, v130, v131
	v_cvt_pk_bf16_f32 v131, v132, v133
	v_cvt_pk_bf16_f32 v132, v138, v139
	v_mul_f32_e32 v138, 0xbfb8aa3b, v68
	v_mul_f32_e32 v139, 0xbfb8aa3b, v69
	v_exp_f32_e32 v138, v138
	v_exp_f32_e32 v139, v139
	v_lshl_add_u64 v[136:137], v[134:135], 0, s[10:11]
	v_pk_mul_f32 v[140:141], v[74:75], v[140:141]
	v_add_co_u32_e32 v134, vcc, s8, v134
	v_cvt_pk_bf16_f32 v133, v140, v141
	s_nop 0
	v_addc_co_u32_e32 v135, vcc, 0, v135, vcc
	global_store_dwordx4 v[134:135], v[130:133], off offset:2048
	v_mul_f32_e32 v134, 0xbfb8aa3b, v64
	v_mul_f32_e32 v135, 0xbfb8aa3b, v65
	v_add_f32_e32 v130, 1.0, v138
	v_add_f32_e32 v131, 1.0, v139
	v_mul_f32_e32 v132, 0xbfb8aa3b, v70
	v_mul_f32_e32 v133, 0xbfb8aa3b, v71
	v_mul_f32_e32 v138, 0xbfb8aa3b, v66
	v_mul_f32_e32 v139, 0xbfb8aa3b, v67
	v_exp_f32_e32 v132, v132
	v_exp_f32_e32 v133, v133
	v_exp_f32_e32 v134, v134
	v_exp_f32_e32 v135, v135
	v_exp_f32_e32 v138, v138
	v_exp_f32_e32 v139, v139
	v_add_f32_e32 v132, 1.0, v132
	v_add_f32_e32 v133, 1.0, v133
	v_add_f32_e32 v134, 1.0, v134
	v_add_f32_e32 v135, 1.0, v135
	v_add_f32_e32 v138, 1.0, v138
	v_add_f32_e32 v139, 1.0, v139
	v_rcp_f32_e32 v130, v130
	v_rcp_f32_e32 v131, v131
	v_rcp_f32_e32 v132, v132
	v_rcp_f32_e32 v133, v133
	v_rcp_f32_e32 v134, v134
	v_rcp_f32_e32 v135, v135
	v_rcp_f32_e32 v138, v138
	v_rcp_f32_e32 v139, v139
	v_pk_mul_f32 v[130:131], v[68:69], v[130:131]
	v_pk_mul_f32 v[132:133], v[70:71], v[132:133]
	v_pk_mul_f32 v[134:135], v[64:65], v[134:135]
	v_pk_mul_f32 v[138:139], v[66:67], v[138:139]
	v_cvt_pk_bf16_f32 v130, v130, v131
	v_cvt_pk_bf16_f32 v131, v132, v133
	v_cvt_pk_bf16_f32 v132, v134, v135
	v_cvt_pk_bf16_f32 v133, v138, v139
	global_store_dwordx4 v[136:137], v[130:133], off offset:256
	v_mul_f32_e32 v138, 0xbfb8aa3b, v58
	v_mul_f32_e32 v139, 0xbfb8aa3b, v59
	v_mul_f32_e32 v130, 0xbfb8aa3b, v60
	v_mul_f32_e32 v131, 0xbfb8aa3b, v61
	v_mul_f32_e32 v132, 0xbfb8aa3b, v62
	v_mul_f32_e32 v133, 0xbfb8aa3b, v63
	v_exp_f32_e32 v130, v130
	v_exp_f32_e32 v131, v131
	v_exp_f32_e32 v132, v132
	v_exp_f32_e32 v133, v133
	v_exp_f32_e32 v138, v138
	v_exp_f32_e32 v139, v139
	v_mul_f32_e32 v136, 0xbfb8aa3b, v56
	v_mul_f32_e32 v137, 0xbfb8aa3b, v57
	v_exp_f32_e32 v136, v136
	v_exp_f32_e32 v137, v137
	v_add_f32_e32 v130, 1.0, v130
	v_add_f32_e32 v131, 1.0, v131
	v_add_f32_e32 v132, 1.0, v132
	v_add_f32_e32 v133, 1.0, v133
	v_add_f32_e32 v138, 1.0, v138
	v_add_f32_e32 v139, 1.0, v139
	v_rcp_f32_e32 v130, v130
	v_rcp_f32_e32 v131, v131
	v_rcp_f32_e32 v132, v132
	v_rcp_f32_e32 v133, v133
	v_rcp_f32_e32 v138, v138
	v_rcp_f32_e32 v139, v139
	v_add_f32_e32 v136, 1.0, v136
	v_add_f32_e32 v137, 1.0, v137
	v_rcp_f32_e32 v136, v136
	v_rcp_f32_e32 v137, v137
	v_pk_mul_f32 v[130:131], v[60:61], v[130:131]
	v_pk_mul_f32 v[132:133], v[62:63], v[132:133]
	v_pk_mul_f32 v[138:139], v[58:59], v[138:139]
	v_cvt_pk_bf16_f32 v130, v130, v131
	v_cvt_pk_bf16_f32 v131, v132, v133
	v_cvt_pk_bf16_f32 v133, v138, v139
	v_mul_f32_e32 v138, 0xbfb8aa3b, v52
	v_mul_f32_e32 v139, 0xbfb8aa3b, v53
	v_exp_f32_e32 v138, v138
	v_exp_f32_e32 v139, v139
	v_pk_mul_f32 v[136:137], v[56:57], v[136:137]
	s_mov_b32 s2, 0xef3e000
	v_cvt_pk_bf16_f32 v132, v136, v137
	v_add_co_u32_e32 v136, vcc, s2, v128
	s_mov_b64 s[8:9], 0xef3e800
	s_nop 0
	v_addc_co_u32_e32 v137, vcc, 0, v129, vcc
	global_store_dwordx4 v[136:137], v[130:133], off offset:2048
	v_mul_f32_e32 v136, 0xbfb8aa3b, v48
	v_mul_f32_e32 v137, 0xbfb8aa3b, v49
	v_add_f32_e32 v130, 1.0, v138
	v_add_f32_e32 v131, 1.0, v139
	v_mul_f32_e32 v132, 0xbfb8aa3b, v54
	v_mul_f32_e32 v133, 0xbfb8aa3b, v55
	v_mul_f32_e32 v138, 0xbfb8aa3b, v50
	v_mul_f32_e32 v139, 0xbfb8aa3b, v51
	v_exp_f32_e32 v132, v132
	v_exp_f32_e32 v133, v133
	v_exp_f32_e32 v136, v136
	v_exp_f32_e32 v137, v137
	v_exp_f32_e32 v138, v138
	v_exp_f32_e32 v139, v139
	v_add_f32_e32 v132, 1.0, v132
	v_add_f32_e32 v133, 1.0, v133
	v_add_f32_e32 v136, 1.0, v136
	v_add_f32_e32 v137, 1.0, v137
	v_add_f32_e32 v138, 1.0, v138
	v_add_f32_e32 v139, 1.0, v139
	v_rcp_f32_e32 v130, v130
	v_rcp_f32_e32 v131, v131
	v_rcp_f32_e32 v132, v132
	v_rcp_f32_e32 v133, v133
	v_rcp_f32_e32 v136, v136
	v_rcp_f32_e32 v137, v137
	v_rcp_f32_e32 v138, v138
	v_rcp_f32_e32 v139, v139
	v_pk_mul_f32 v[130:131], v[52:53], v[130:131]
	v_pk_mul_f32 v[132:133], v[54:55], v[132:133]
	v_pk_mul_f32 v[136:137], v[48:49], v[136:137]
	v_pk_mul_f32 v[138:139], v[50:51], v[138:139]
	v_lshl_add_u64 v[134:135], v[128:129], 0, s[8:9]
	v_cvt_pk_bf16_f32 v130, v130, v131
	v_cvt_pk_bf16_f32 v131, v132, v133
	v_cvt_pk_bf16_f32 v132, v136, v137
	v_cvt_pk_bf16_f32 v133, v138, v139
	global_store_dwordx4 v[134:135], v[130:133], off offset:256
	v_mul_f32_e32 v138, 0xbfb8aa3b, v42
	v_mul_f32_e32 v139, 0xbfb8aa3b, v43
	v_mul_f32_e32 v130, 0xbfb8aa3b, v44
	v_mul_f32_e32 v131, 0xbfb8aa3b, v45
	v_mul_f32_e32 v132, 0xbfb8aa3b, v46
	v_mul_f32_e32 v133, 0xbfb8aa3b, v47
	v_exp_f32_e32 v130, v130
	v_exp_f32_e32 v131, v131
	v_exp_f32_e32 v132, v132
	v_exp_f32_e32 v133, v133
	v_exp_f32_e32 v138, v138
	v_exp_f32_e32 v139, v139
	v_mul_f32_e32 v136, 0xbfb8aa3b, v40
	v_mul_f32_e32 v137, 0xbfb8aa3b, v41
	v_exp_f32_e32 v136, v136
	v_exp_f32_e32 v137, v137
	v_add_f32_e32 v130, 1.0, v130
	v_add_f32_e32 v131, 1.0, v131
	v_add_f32_e32 v132, 1.0, v132
	v_add_f32_e32 v133, 1.0, v133
	v_add_f32_e32 v138, 1.0, v138
	v_add_f32_e32 v139, 1.0, v139
	v_rcp_f32_e32 v130, v130
	v_rcp_f32_e32 v131, v131
	v_rcp_f32_e32 v132, v132
	v_rcp_f32_e32 v133, v133
	v_rcp_f32_e32 v138, v138
	v_rcp_f32_e32 v139, v139
	v_add_f32_e32 v136, 1.0, v136
	v_add_f32_e32 v137, 1.0, v137
	v_rcp_f32_e32 v136, v136
	v_rcp_f32_e32 v137, v137
	v_pk_mul_f32 v[130:131], v[44:45], v[130:131]
	v_pk_mul_f32 v[132:133], v[46:47], v[132:133]
	v_pk_mul_f32 v[138:139], v[42:43], v[138:139]
	v_cvt_pk_bf16_f32 v130, v130, v131
	v_cvt_pk_bf16_f32 v131, v132, v133
	v_cvt_pk_bf16_f32 v133, v138, v139
	v_mul_f32_e32 v138, 0xbfb8aa3b, v36
	v_mul_f32_e32 v139, 0xbfb8aa3b, v37
	v_exp_f32_e32 v138, v138
	v_exp_f32_e32 v139, v139
	v_pk_mul_f32 v[136:137], v[40:41], v[136:137]
	s_mov_b32 s2, 0xef46000
	v_cvt_pk_bf16_f32 v132, v136, v137
	v_add_co_u32_e32 v136, vcc, s2, v128
	s_mov_b64 s[8:9], 0xef46800
	s_nop 0
	v_addc_co_u32_e32 v137, vcc, 0, v129, vcc
	global_store_dwordx4 v[136:137], v[130:133], off offset:2048
	v_mul_f32_e32 v136, 0xbfb8aa3b, v32
	v_mul_f32_e32 v137, 0xbfb8aa3b, v33
	v_add_f32_e32 v130, 1.0, v138
	v_add_f32_e32 v131, 1.0, v139
	v_mul_f32_e32 v132, 0xbfb8aa3b, v38
	v_mul_f32_e32 v133, 0xbfb8aa3b, v39
	v_mul_f32_e32 v138, 0xbfb8aa3b, v34
	v_mul_f32_e32 v139, 0xbfb8aa3b, v35
	v_exp_f32_e32 v132, v132
	v_exp_f32_e32 v133, v133
	v_exp_f32_e32 v136, v136
	v_exp_f32_e32 v137, v137
	v_exp_f32_e32 v138, v138
	v_exp_f32_e32 v139, v139
	v_add_f32_e32 v132, 1.0, v132
	v_add_f32_e32 v133, 1.0, v133
	v_add_f32_e32 v136, 1.0, v136
	v_add_f32_e32 v137, 1.0, v137
	v_add_f32_e32 v138, 1.0, v138
	v_add_f32_e32 v139, 1.0, v139
	v_rcp_f32_e32 v130, v130
	v_rcp_f32_e32 v131, v131
	v_rcp_f32_e32 v132, v132
	v_rcp_f32_e32 v133, v133
	v_rcp_f32_e32 v136, v136
	v_rcp_f32_e32 v137, v137
	v_rcp_f32_e32 v138, v138
	v_rcp_f32_e32 v139, v139
	v_pk_mul_f32 v[130:131], v[36:37], v[130:131]
	v_pk_mul_f32 v[132:133], v[38:39], v[132:133]
	v_pk_mul_f32 v[136:137], v[32:33], v[136:137]
	v_pk_mul_f32 v[138:139], v[34:35], v[138:139]
	v_lshl_add_u64 v[134:135], v[128:129], 0, s[8:9]
	v_cvt_pk_bf16_f32 v130, v130, v131
	v_cvt_pk_bf16_f32 v131, v132, v133
	v_cvt_pk_bf16_f32 v132, v136, v137
	v_cvt_pk_bf16_f32 v133, v138, v139
	global_store_dwordx4 v[134:135], v[130:133], off offset:256
	v_mul_f32_e32 v138, 0xbfb8aa3b, v26
	v_mul_f32_e32 v139, 0xbfb8aa3b, v27
	v_mul_f32_e32 v130, 0xbfb8aa3b, v28
	v_mul_f32_e32 v131, 0xbfb8aa3b, v29
	v_mul_f32_e32 v132, 0xbfb8aa3b, v30
	v_mul_f32_e32 v133, 0xbfb8aa3b, v31
	v_exp_f32_e32 v130, v130
	v_exp_f32_e32 v131, v131
	v_exp_f32_e32 v132, v132
	v_exp_f32_e32 v133, v133
	v_exp_f32_e32 v138, v138
	v_exp_f32_e32 v139, v139
	v_mul_f32_e32 v136, 0xbfb8aa3b, v24
	v_mul_f32_e32 v137, 0xbfb8aa3b, v25
	v_exp_f32_e32 v136, v136
	v_exp_f32_e32 v137, v137
	v_add_f32_e32 v130, 1.0, v130
	v_add_f32_e32 v131, 1.0, v131
	v_add_f32_e32 v132, 1.0, v132
	v_add_f32_e32 v133, 1.0, v133
	v_add_f32_e32 v138, 1.0, v138
	v_add_f32_e32 v139, 1.0, v139
	v_rcp_f32_e32 v130, v130
	v_rcp_f32_e32 v131, v131
	v_rcp_f32_e32 v132, v132
	v_rcp_f32_e32 v133, v133
	v_rcp_f32_e32 v138, v138
	v_rcp_f32_e32 v139, v139
	v_add_f32_e32 v136, 1.0, v136
	v_add_f32_e32 v137, 1.0, v137
	v_rcp_f32_e32 v136, v136
	v_rcp_f32_e32 v137, v137
	v_pk_mul_f32 v[130:131], v[28:29], v[130:131]
	v_pk_mul_f32 v[132:133], v[30:31], v[132:133]
	v_pk_mul_f32 v[138:139], v[26:27], v[138:139]
	v_cvt_pk_bf16_f32 v130, v130, v131
	v_cvt_pk_bf16_f32 v131, v132, v133
	v_cvt_pk_bf16_f32 v133, v138, v139
	v_mul_f32_e32 v138, 0xbfb8aa3b, v20
	v_mul_f32_e32 v139, 0xbfb8aa3b, v21
	v_exp_f32_e32 v138, v138
	v_exp_f32_e32 v139, v139
	v_pk_mul_f32 v[136:137], v[24:25], v[136:137]
	s_mov_b32 s2, 0xef4e000
	v_cvt_pk_bf16_f32 v132, v136, v137
	v_add_co_u32_e32 v136, vcc, s2, v128
	s_mov_b64 s[8:9], 0xef4e800
	s_nop 0
	v_addc_co_u32_e32 v137, vcc, 0, v129, vcc
	global_store_dwordx4 v[136:137], v[130:133], off offset:2048
	v_mul_f32_e32 v136, 0xbfb8aa3b, v16
	v_mul_f32_e32 v137, 0xbfb8aa3b, v17
	v_add_f32_e32 v130, 1.0, v138
	v_add_f32_e32 v131, 1.0, v139
	v_mul_f32_e32 v132, 0xbfb8aa3b, v22
	v_mul_f32_e32 v133, 0xbfb8aa3b, v23
	v_mul_f32_e32 v138, 0xbfb8aa3b, v18
	v_mul_f32_e32 v139, 0xbfb8aa3b, v19
	v_exp_f32_e32 v132, v132
	v_exp_f32_e32 v133, v133
	v_exp_f32_e32 v136, v136
	v_exp_f32_e32 v137, v137
	v_exp_f32_e32 v138, v138
	v_exp_f32_e32 v139, v139
	v_add_f32_e32 v132, 1.0, v132
	v_add_f32_e32 v133, 1.0, v133
	v_add_f32_e32 v136, 1.0, v136
	v_add_f32_e32 v137, 1.0, v137
	v_add_f32_e32 v138, 1.0, v138
	v_add_f32_e32 v139, 1.0, v139
	v_rcp_f32_e32 v130, v130
	v_rcp_f32_e32 v131, v131
	v_rcp_f32_e32 v132, v132
	v_rcp_f32_e32 v133, v133
	v_rcp_f32_e32 v136, v136
	v_rcp_f32_e32 v137, v137
	v_rcp_f32_e32 v138, v138
	v_rcp_f32_e32 v139, v139
	v_pk_mul_f32 v[130:131], v[20:21], v[130:131]
	v_pk_mul_f32 v[132:133], v[22:23], v[132:133]
	v_pk_mul_f32 v[136:137], v[16:17], v[136:137]
	v_pk_mul_f32 v[138:139], v[18:19], v[138:139]
	v_lshl_add_u64 v[134:135], v[128:129], 0, s[8:9]
	v_cvt_pk_bf16_f32 v130, v130, v131
	v_cvt_pk_bf16_f32 v131, v132, v133
	v_cvt_pk_bf16_f32 v132, v136, v137
	v_cvt_pk_bf16_f32 v133, v138, v139
	global_store_dwordx4 v[134:135], v[130:133], off offset:256
	v_mul_f32_e32 v136, 0xbfb8aa3b, v8
	v_mul_f32_e32 v137, 0xbfb8aa3b, v9
	v_mul_f32_e32 v130, 0xbfb8aa3b, v12
	v_mul_f32_e32 v131, 0xbfb8aa3b, v13
	v_mul_f32_e32 v132, 0xbfb8aa3b, v14
	v_mul_f32_e32 v133, 0xbfb8aa3b, v15
	v_exp_f32_e32 v130, v130
	v_exp_f32_e32 v131, v131
	v_exp_f32_e32 v132, v132
	v_exp_f32_e32 v133, v133
	v_exp_f32_e32 v136, v136
	v_exp_f32_e32 v137, v137
	v_mul_f32_e32 v138, 0xbfb8aa3b, v10
	v_mul_f32_e32 v139, 0xbfb8aa3b, v11
	v_add_f32_e32 v130, 1.0, v130
	v_add_f32_e32 v131, 1.0, v131
	v_add_f32_e32 v132, 1.0, v132
	v_add_f32_e32 v133, 1.0, v133
	v_add_f32_e32 v136, 1.0, v136
	v_add_f32_e32 v137, 1.0, v137
	v_exp_f32_e32 v138, v138
	v_exp_f32_e32 v139, v139
	v_rcp_f32_e32 v130, v130
	v_rcp_f32_e32 v131, v131
	v_rcp_f32_e32 v132, v132
	v_rcp_f32_e32 v133, v133
	v_rcp_f32_e32 v136, v136
	v_rcp_f32_e32 v137, v137
	v_add_f32_e32 v138, 1.0, v138
	v_add_f32_e32 v139, 1.0, v139
	v_rcp_f32_e32 v138, v138
	v_rcp_f32_e32 v139, v139
	v_pk_mul_f32 v[130:131], v[12:13], v[130:131]
	v_pk_mul_f32 v[132:133], v[14:15], v[132:133]
	v_pk_mul_f32 v[136:137], v[8:9], v[136:137]
	v_cvt_pk_bf16_f32 v130, v130, v131
	v_cvt_pk_bf16_f32 v131, v132, v133
	v_cvt_pk_bf16_f32 v132, v136, v137
	v_mul_f32_e32 v136, 0xbfb8aa3b, v4
	v_mul_f32_e32 v137, 0xbfb8aa3b, v5
	v_exp_f32_e32 v136, v136
	v_exp_f32_e32 v137, v137
	s_mov_b64 s[8:9], 0xef56800
	s_mov_b32 s2, 0xef56000
	v_lshl_add_u64 v[134:135], v[128:129], 0, s[8:9]
	v_pk_mul_f32 v[138:139], v[10:11], v[138:139]
	v_add_co_u32_e32 v128, vcc, s2, v128
	v_cvt_pk_bf16_f32 v133, v138, v139
	s_nop 0
	v_addc_co_u32_e32 v129, vcc, 0, v129, vcc
	global_store_dwordx4 v[128:129], v[130:133], off offset:2048
	v_add_f32_e32 v128, 1.0, v136
	v_add_f32_e32 v129, 1.0, v137
	v_mul_f32_e32 v130, 0xbfb8aa3b, v6
	v_mul_f32_e32 v131, 0xbfb8aa3b, v7
	v_mul_f32_e32 v132, 0xbfb8aa3b, v0
	v_mul_f32_e32 v133, 0xbfb8aa3b, v1
	v_mul_f32_e32 v136, 0xbfb8aa3b, v2
	v_mul_f32_e32 v137, 0xbfb8aa3b, v3
	v_exp_f32_e32 v130, v130
	v_exp_f32_e32 v131, v131
	v_exp_f32_e32 v132, v132
	v_exp_f32_e32 v133, v133
	v_exp_f32_e32 v136, v136
	v_exp_f32_e32 v137, v137
	v_add_f32_e32 v130, 1.0, v130
	v_add_f32_e32 v131, 1.0, v131
	v_add_f32_e32 v132, 1.0, v132
	v_add_f32_e32 v133, 1.0, v133
	v_add_f32_e32 v136, 1.0, v136
	v_add_f32_e32 v137, 1.0, v137
	v_rcp_f32_e32 v128, v128
	v_rcp_f32_e32 v129, v129
	v_rcp_f32_e32 v130, v130
	v_rcp_f32_e32 v131, v131
	v_rcp_f32_e32 v132, v132
	v_rcp_f32_e32 v133, v133
	v_rcp_f32_e32 v136, v136
	v_rcp_f32_e32 v137, v137
	v_pk_mul_f32 v[128:129], v[4:5], v[128:129]
	v_pk_mul_f32 v[130:131], v[6:7], v[130:131]
	v_pk_mul_f32 v[132:133], v[0:1], v[132:133]
	v_pk_mul_f32 v[136:137], v[2:3], v[136:137]
	v_cvt_pk_bf16_f32 v128, v128, v129
	v_cvt_pk_bf16_f32 v129, v130, v131
	v_cvt_pk_bf16_f32 v130, v132, v133
	v_cvt_pk_bf16_f32 v131, v136, v137
	global_store_dwordx4 v[134:135], v[128:131], off offset:256

.LBB0_1121:
	s_andn2_b64 vcc, exec, s[8:9]
	s_cbranch_vccnz .LBB0_1123
	s_ashr_i32 s65, s64, 31
	s_lshl_b64 s[8:9], s[64:65], 11
	v_readlane_b32 s2, v254, 41
	s_add_u32 s10, s2, s8
	v_readlane_b32 s2, v254, 42
	s_addc_u32 s11, s2, s9
	s_lshl_b32 s2, s14, 8
	s_addk_i32 s2, 0xf800
	s_and_b64 s[8:9], s[12:13], exec
	v_or_b32_e32 v152, s2, v187
	v_subrev_u32_e32 v128, s64, v172
	s_cselect_b32 s20, 8, 10
	v_ashrrev_i32_e32 v129, 31, v128
	v_lshlrev_b64 v[130:131], s20, v[152:153]
	s_movk_i32 s2, 0x1800
	v_lshl_add_u64 v[138:139], v[128:129], 1, s[10:11]
	v_lshlrev_b64 v[130:131], 1, v[130:131]
	s_cselect_b32 s2, 0x600, s2
	v_lshl_add_u64 v[140:141], v[138:139], 0, v[130:131]
	s_lshl_b32 s8, s66, 1
	s_mov_b32 s9, s3
	v_cvt_pk_bf16_f32 v129, v124, v125
	v_lshl_add_u64 v[132:133], v[140:141], 0, s[8:9]
	global_store_short_d16_hi v[132:133], v129, off
	v_lshl_add_u64 v[142:143], v[132:133], 0, s[8:9]
	v_or_b32_e32 v132, 16, v152
	v_mov_b32_e32 v133, v153
	v_lshlrev_b64 v[132:133], s20, v[132:133]
	v_lshlrev_b64 v[132:133], 1, v[132:133]
	v_cvt_pk_bf16_f32 v134, v126, v127
	v_lshl_add_u64 v[144:145], v[140:141], 0, s[2:3]
	v_lshl_add_u64 v[146:147], v[138:139], 0, v[132:133]
	global_store_short v[140:141], v129, off
	global_store_short v[142:143], v134, off
	global_store_short_d16_hi v[144:145], v134, off
	v_cvt_pk_bf16_f32 v129, v120, v121
	v_lshl_add_u64 v[134:135], v[146:147], 0, s[8:9]
	global_store_short_d16_hi v[134:135], v129, off
	v_lshl_add_u64 v[148:149], v[134:135], 0, s[8:9]
	v_or_b32_e32 v134, 0x80, v152
	v_mov_b32_e32 v135, v153
	v_lshlrev_b64 v[134:135], s20, v[134:135]
	v_lshlrev_b64 v[134:135], 1, v[134:135]
	s_waitcnt lgkmcnt(0)
	v_cvt_pk_bf16_f32 v136, v122, v123
	v_lshl_add_u64 v[150:151], v[146:147], 0, s[2:3]
	v_lshl_add_u64 v[154:155], v[138:139], 0, v[134:135]
	global_store_short v[146:147], v129, off
	global_store_short v[148:149], v136, off
	global_store_short_d16_hi v[150:151], v136, off
	v_cvt_pk_bf16_f32 v129, v116, v117
	v_lshl_add_u64 v[136:137], v[154:155], 0, s[8:9]
	v_or_b32_e32 v152, 0x90, v152
	global_store_short_d16_hi v[136:137], v129, off
	v_lshl_add_u64 v[174:175], v[136:137], 0, s[8:9]
	v_lshlrev_b64 v[136:137], s20, v[152:153]
	v_lshlrev_b64 v[136:137], 1, v[136:137]
	v_lshl_add_u64 v[138:139], v[138:139], 0, v[136:137]
	s_sub_u32 s20, 0, s8
	v_cvt_pk_bf16_f32 v173, v118, v119
	global_store_short v[154:155], v129, off
	v_lshl_add_u64 v[176:177], v[154:155], 0, s[2:3]
	v_cvt_pk_bf16_f32 v129, v112, v113
	v_lshl_add_u64 v[178:179], v[138:139], 0, s[8:9]
	s_subb_u32 s21, 0, 0
	global_store_short v[174:175], v173, off
	global_store_short_d16_hi v[176:177], v173, off
	v_cvt_pk_bf16_f32 v173, v114, v115
	global_store_short v[138:139], v129, off
	global_store_short_d16_hi v[178:179], v129, off
	v_lshl_add_u64 v[178:179], v[178:179], 0, s[8:9]
	v_lshl_add_u64 v[180:181], v[138:139], 0, s[2:3]
	v_cvt_pk_bf16_f32 v129, v108, v109
	v_lshl_add_u64 v[142:143], v[142:143], 0, s[20:21]
	global_store_short v[178:179], v173, off
	global_store_short_d16_hi v[180:181], v173, off
	v_cvt_pk_bf16_f32 v152, v110, v111
	global_store_short v[140:141], v129, off offset:32
	global_store_short_d16_hi v[142:143], v129, off offset:32
	v_lshl_add_u64 v[142:143], v[142:143], 0, s[8:9]
	v_cvt_pk_bf16_f32 v129, v104, v105
	v_lshl_add_u64 v[148:149], v[148:149], 0, s[20:21]
	global_store_short v[142:143], v152, off offset:32
	global_store_short_d16_hi v[144:145], v152, off offset:32
	v_cvt_pk_bf16_f32 v152, v106, v107
	global_store_short v[146:147], v129, off offset:32
	global_store_short_d16_hi v[148:149], v129, off offset:32
	v_lshl_add_u64 v[148:149], v[148:149], 0, s[8:9]
	v_cvt_pk_bf16_f32 v129, v100, v101
	v_lshl_add_u64 v[174:175], v[174:175], 0, s[20:21]
	global_store_short v[148:149], v152, off offset:32
	global_store_short_d16_hi v[150:151], v152, off offset:32
	v_cvt_pk_bf16_f32 v152, v102, v103
	global_store_short v[154:155], v129, off offset:32
	global_store_short_d16_hi v[174:175], v129, off offset:32
	v_lshl_add_u64 v[174:175], v[174:175], 0, s[8:9]
	v_cvt_pk_bf16_f32 v129, v96, v97
	v_lshl_add_u64 v[178:179], v[178:179], 0, s[20:21]
	global_store_short v[174:175], v152, off offset:32
	global_store_short_d16_hi v[176:177], v152, off offset:32
	v_cvt_pk_bf16_f32 v152, v98, v99
	global_store_short v[138:139], v129, off offset:32
	global_store_short_d16_hi v[178:179], v129, off offset:32
	v_lshl_add_u64 v[178:179], v[178:179], 0, s[8:9]
	v_cvt_pk_bf16_f32 v129, v92, v93
	v_lshl_add_u64 v[142:143], v[142:143], 0, s[20:21]
	global_store_short v[178:179], v152, off offset:32
	global_store_short_d16_hi v[180:181], v152, off offset:32
	v_cvt_pk_bf16_f32 v152, v94, v95
	global_store_short v[140:141], v129, off offset:64
	global_store_short_d16_hi v[142:143], v129, off offset:64
	v_lshl_add_u64 v[142:143], v[142:143], 0, s[8:9]
	v_cvt_pk_bf16_f32 v129, v88, v89
	v_lshl_add_u64 v[148:149], v[148:149], 0, s[20:21]
	global_store_short v[142:143], v152, off offset:64
	global_store_short_d16_hi v[144:145], v152, off offset:64
	v_cvt_pk_bf16_f32 v152, v90, v91
	global_store_short v[146:147], v129, off offset:64
	global_store_short_d16_hi v[148:149], v129, off offset:64
	v_lshl_add_u64 v[148:149], v[148:149], 0, s[8:9]
	v_cvt_pk_bf16_f32 v129, v84, v85
	v_lshl_add_u64 v[174:175], v[174:175], 0, s[20:21]
	global_store_short v[148:149], v152, off offset:64
	global_store_short_d16_hi v[150:151], v152, off offset:64
	v_cvt_pk_bf16_f32 v152, v86, v87
	global_store_short v[154:155], v129, off offset:64
	global_store_short_d16_hi v[174:175], v129, off offset:64
	v_lshl_add_u64 v[174:175], v[174:175], 0, s[8:9]
	v_cvt_pk_bf16_f32 v129, v80, v81
	v_lshl_add_u64 v[178:179], v[178:179], 0, s[20:21]
	global_store_short v[174:175], v152, off offset:64
	global_store_short_d16_hi v[176:177], v152, off offset:64
	v_cvt_pk_bf16_f32 v152, v82, v83
	global_store_short v[138:139], v129, off offset:64
	global_store_short_d16_hi v[178:179], v129, off offset:64
	v_lshl_add_u64 v[178:179], v[178:179], 0, s[8:9]
	v_cvt_pk_bf16_f32 v129, v76, v77
	global_store_short v[178:179], v152, off offset:64
	global_store_short_d16_hi v[180:181], v152, off offset:64
	global_store_short v[140:141], v129, off offset:96
	v_lshl_add_u64 v[140:141], v[142:143], 0, s[20:21]
	v_cvt_pk_bf16_f32 v152, v78, v79
	global_store_short_d16_hi v[140:141], v129, off offset:96
	v_lshl_add_u64 v[140:141], v[140:141], 0, s[8:9]
	global_store_short v[140:141], v152, off offset:96
	global_store_short_d16_hi v[144:145], v152, off offset:96
	v_cvt_pk_bf16_f32 v129, v72, v73
	v_lshl_add_u64 v[140:141], v[148:149], 0, s[20:21]
	v_cvt_pk_bf16_f32 v142, v74, v75
	global_store_short v[146:147], v129, off offset:96
	global_store_short_d16_hi v[140:141], v129, off offset:96
	v_lshl_add_u64 v[140:141], v[140:141], 0, s[8:9]
	global_store_short v[140:141], v142, off offset:96
	global_store_short_d16_hi v[150:151], v142, off offset:96
	v_cvt_pk_bf16_f32 v129, v68, v69
	v_lshl_add_u64 v[140:141], v[174:175], 0, s[20:21]
	v_cvt_pk_bf16_f32 v142, v70, v71
	global_store_short v[154:155], v129, off offset:96
	global_store_short_d16_hi v[140:141], v129, off offset:96
	v_lshl_add_u64 v[140:141], v[140:141], 0, s[8:9]
	v_cvt_pk_bf16_f32 v129, v64, v65
	global_store_short v[140:141], v142, off offset:96
	global_store_short_d16_hi v[176:177], v142, off offset:96
	global_store_short v[138:139], v129, off offset:96
	v_lshl_add_u64 v[138:139], v[178:179], 0, s[20:21]
	v_cvt_pk_bf16_f32 v140, v66, v67
	global_store_short_d16_hi v[138:139], v129, off offset:96
	v_lshl_add_u64 v[138:139], v[138:139], 0, s[8:9]
	global_store_short v[138:139], v140, off offset:96
	global_store_short_d16_hi v[180:181], v140, off offset:96
	v_add_u32_e32 v138, 0x80, v128
	v_ashrrev_i32_e32 v139, 31, v138
	v_lshl_add_u64 v[138:139], v[138:139], 1, s[10:11]
	v_lshl_add_u64 v[140:141], v[138:139], 0, v[130:131]
	v_cvt_pk_bf16_f32 v129, v60, v61
	v_lshl_add_u64 v[142:143], v[140:141], 0, s[8:9]
	v_cvt_pk_bf16_f32 v144, v62, v63
	global_store_short v[140:141], v129, off
	global_store_short_d16_hi v[142:143], v129, off
	v_lshl_add_u64 v[142:143], v[142:143], 0, s[8:9]
	v_lshl_add_u64 v[140:141], v[140:141], 0, s[2:3]
	global_store_short v[142:143], v144, off
	global_store_short_d16_hi v[140:141], v144, off
	v_lshl_add_u64 v[140:141], v[138:139], 0, v[132:133]
	v_cvt_pk_bf16_f32 v129, v56, v57
	v_lshl_add_u64 v[142:143], v[140:141], 0, s[8:9]
	v_cvt_pk_bf16_f32 v144, v58, v59
	global_store_short v[140:141], v129, off
	global_store_short_d16_hi v[142:143], v129, off
	v_lshl_add_u64 v[142:143], v[142:143], 0, s[8:9]
	v_lshl_add_u64 v[140:141], v[140:141], 0, s[2:3]
	global_store_short v[142:143], v144, off
	global_store_short_d16_hi v[140:141], v144, off
	v_lshl_add_u64 v[140:141], v[138:139], 0, v[134:135]
	v_cvt_pk_bf16_f32 v129, v52, v53
	v_lshl_add_u64 v[142:143], v[140:141], 0, s[8:9]
	v_cvt_pk_bf16_f32 v144, v54, v55
	global_store_short v[140:141], v129, off
	global_store_short_d16_hi v[142:143], v129, off
	v_lshl_add_u64 v[142:143], v[142:143], 0, s[8:9]
	v_lshl_add_u64 v[140:141], v[140:141], 0, s[2:3]
	v_lshl_add_u64 v[138:139], v[138:139], 0, v[136:137]
	global_store_short v[142:143], v144, off
	global_store_short_d16_hi v[140:141], v144, off
	v_cvt_pk_bf16_f32 v129, v48, v49
	v_lshl_add_u64 v[140:141], v[138:139], 0, s[8:9]
	v_cvt_pk_bf16_f32 v142, v50, v51
	global_store_short v[138:139], v129, off
	global_store_short_d16_hi v[140:141], v129, off
	v_lshl_add_u64 v[140:141], v[140:141], 0, s[8:9]
	v_lshl_add_u64 v[138:139], v[138:139], 0, s[2:3]
	global_store_short v[140:141], v142, off
	global_store_short_d16_hi v[138:139], v142, off
	v_add_u32_e32 v138, 0x90, v128
	v_ashrrev_i32_e32 v139, 31, v138
	v_lshl_add_u64 v[138:139], v[138:139], 1, s[10:11]
	v_lshl_add_u64 v[140:141], v[138:139], 0, v[130:131]
	v_cvt_pk_bf16_f32 v129, v44, v45
	v_lshl_add_u64 v[142:143], v[140:141], 0, s[8:9]
	v_cvt_pk_bf16_f32 v144, v46, v47
	global_store_short v[140:141], v129, off
	global_store_short_d16_hi v[142:143], v129, off
	v_lshl_add_u64 v[142:143], v[142:143], 0, s[8:9]
	v_lshl_add_u64 v[140:141], v[140:141], 0, s[2:3]
	global_store_short v[142:143], v144, off
	global_store_short_d16_hi v[140:141], v144, off
	v_lshl_add_u64 v[140:141], v[138:139], 0, v[132:133]
	v_cvt_pk_bf16_f32 v129, v40, v41
	v_lshl_add_u64 v[142:143], v[140:141], 0, s[8:9]
	v_cvt_pk_bf16_f32 v144, v42, v43
	global_store_short v[140:141], v129, off
	global_store_short_d16_hi v[142:143], v129, off
	v_lshl_add_u64 v[142:143], v[142:143], 0, s[8:9]
	v_lshl_add_u64 v[140:141], v[140:141], 0, s[2:3]
	global_store_short v[142:143], v144, off
	global_store_short_d16_hi v[140:141], v144, off
	v_lshl_add_u64 v[140:141], v[138:139], 0, v[134:135]
	v_cvt_pk_bf16_f32 v129, v36, v37
	v_lshl_add_u64 v[142:143], v[140:141], 0, s[8:9]
	v_cvt_pk_bf16_f32 v144, v38, v39
	global_store_short v[140:141], v129, off
	global_store_short_d16_hi v[142:143], v129, off
	v_lshl_add_u64 v[142:143], v[142:143], 0, s[8:9]
	v_lshl_add_u64 v[140:141], v[140:141], 0, s[2:3]
	v_lshl_add_u64 v[138:139], v[138:139], 0, v[136:137]
	global_store_short v[142:143], v144, off
	global_store_short_d16_hi v[140:141], v144, off
	v_cvt_pk_bf16_f32 v129, v32, v33
	v_lshl_add_u64 v[140:141], v[138:139], 0, s[8:9]
	v_cvt_pk_bf16_f32 v142, v34, v35
	global_store_short v[138:139], v129, off
	global_store_short_d16_hi v[140:141], v129, off
	v_lshl_add_u64 v[140:141], v[140:141], 0, s[8:9]
	v_lshl_add_u64 v[138:139], v[138:139], 0, s[2:3]
	global_store_short v[140:141], v142, off
	global_store_short_d16_hi v[138:139], v142, off
	v_add_u32_e32 v138, 0xa0, v128
	v_ashrrev_i32_e32 v139, 31, v138
	v_lshl_add_u64 v[138:139], v[138:139], 1, s[10:11]
	v_lshl_add_u64 v[140:141], v[138:139], 0, v[130:131]
	v_cvt_pk_bf16_f32 v129, v28, v29
	v_lshl_add_u64 v[142:143], v[140:141], 0, s[8:9]
	v_cvt_pk_bf16_f32 v144, v30, v31
	global_store_short v[140:141], v129, off
	global_store_short_d16_hi v[142:143], v129, off
	v_lshl_add_u64 v[142:143], v[142:143], 0, s[8:9]
	v_lshl_add_u64 v[140:141], v[140:141], 0, s[2:3]
	global_store_short v[142:143], v144, off
	global_store_short_d16_hi v[140:141], v144, off
	v_lshl_add_u64 v[140:141], v[138:139], 0, v[132:133]
	v_cvt_pk_bf16_f32 v129, v24, v25
	v_lshl_add_u64 v[142:143], v[140:141], 0, s[8:9]
	v_cvt_pk_bf16_f32 v144, v26, v27
	global_store_short v[140:141], v129, off
	global_store_short_d16_hi v[142:143], v129, off
	v_lshl_add_u64 v[142:143], v[142:143], 0, s[8:9]
	v_lshl_add_u64 v[140:141], v[140:141], 0, s[2:3]
	global_store_short v[142:143], v144, off
	global_store_short_d16_hi v[140:141], v144, off
	v_lshl_add_u64 v[140:141], v[138:139], 0, v[134:135]
	v_cvt_pk_bf16_f32 v129, v20, v21
	v_lshl_add_u64 v[142:143], v[140:141], 0, s[8:9]
	v_cvt_pk_bf16_f32 v144, v22, v23
	global_store_short v[140:141], v129, off
	global_store_short_d16_hi v[142:143], v129, off
	v_lshl_add_u64 v[142:143], v[142:143], 0, s[8:9]
	v_lshl_add_u64 v[140:141], v[140:141], 0, s[2:3]
	v_lshl_add_u64 v[138:139], v[138:139], 0, v[136:137]
	global_store_short v[142:143], v144, off
	global_store_short_d16_hi v[140:141], v144, off
	v_cvt_pk_bf16_f32 v129, v16, v17
	v_lshl_add_u64 v[140:141], v[138:139], 0, s[8:9]
	v_add_u32_e32 v128, 0xb0, v128
	global_store_short v[138:139], v129, off
	global_store_short_d16_hi v[140:141], v129, off
	v_ashrrev_i32_e32 v129, 31, v128
	v_lshl_add_u64 v[128:129], v[128:129], 1, s[10:11]
	v_cvt_pk_bf16_f32 v142, v18, v19
	v_lshl_add_u64 v[140:141], v[140:141], 0, s[8:9]
	v_lshl_add_u64 v[138:139], v[138:139], 0, s[2:3]
	v_lshl_add_u64 v[130:131], v[128:129], 0, v[130:131]
	global_store_short v[140:141], v142, off
	global_store_short_d16_hi v[138:139], v142, off
	v_cvt_pk_bf16_f32 v140, v12, v13
	v_lshl_add_u64 v[138:139], v[130:131], 0, s[8:9]
	v_cvt_pk_bf16_f32 v141, v14, v15
	global_store_short v[130:131], v140, off
	global_store_short_d16_hi v[138:139], v140, off
	v_lshl_add_u64 v[138:139], v[138:139], 0, s[8:9]
	v_lshl_add_u64 v[130:131], v[130:131], 0, s[2:3]
	global_store_short v[138:139], v141, off
	global_store_short_d16_hi v[130:131], v141, off
	v_lshl_add_u64 v[130:131], v[128:129], 0, v[132:133]
	v_cvt_pk_bf16_f32 v138, v8, v9
	v_lshl_add_u64 v[132:133], v[130:131], 0, s[8:9]
	v_cvt_pk_bf16_f32 v139, v10, v11
	global_store_short v[130:131], v138, off
	global_store_short_d16_hi v[132:133], v138, off
	v_lshl_add_u64 v[132:133], v[132:133], 0, s[8:9]
	v_lshl_add_u64 v[130:131], v[130:131], 0, s[2:3]
	global_store_short v[132:133], v139, off
	global_store_short_d16_hi v[130:131], v139, off
	v_lshl_add_u64 v[130:131], v[128:129], 0, v[134:135]
	v_cvt_pk_bf16_f32 v138, v4, v5
	v_lshl_add_u64 v[132:133], v[130:131], 0, s[8:9]
	v_cvt_pk_bf16_f32 v139, v6, v7
	global_store_short v[130:131], v138, off
	global_store_short_d16_hi v[132:133], v138, off
	v_lshl_add_u64 v[132:133], v[132:133], 0, s[8:9]
	v_lshl_add_u64 v[130:131], v[130:131], 0, s[2:3]
	v_lshl_add_u64 v[128:129], v[128:129], 0, v[136:137]
	global_store_short v[132:133], v139, off
	global_store_short_d16_hi v[130:131], v139, off
	v_cvt_pk_bf16_f32 v132, v0, v1
	v_lshl_add_u64 v[130:131], v[128:129], 0, s[8:9]
	v_cvt_pk_bf16_f32 v133, v2, v3
	global_store_short v[128:129], v132, off
	global_store_short_d16_hi v[130:131], v132, off
	v_lshl_add_u64 v[130:131], v[130:131], 0, s[8:9]
	v_lshl_add_u64 v[128:129], v[128:129], 0, s[2:3]
	global_store_short v[130:131], v133, off
	global_store_short_d16_hi v[128:129], v133, off

.LBB0_1124:
	s_andn2_b64 vcc, exec, s[8:9]
	s_cbranch_vccnz .LBB0_1126
	s_ashr_i32 s65, s64, 31
	s_lshl_b64 s[8:9], s[64:65], 10
	v_readlane_b32 s2, v254, 52
	s_add_u32 s20, s2, s8
	v_readlane_b32 s2, v254, 53
	s_addc_u32 s21, s2, s9
	s_lshl_b32 s2, s14, 8
	s_addk_i32 s2, 0xfa00
	s_and_b64 s[8:9], s[12:13], exec
	s_movk_i32 s8, 0x1800
	v_subrev_u32_e32 v130, s64, v172
	s_cselect_b32 s8, 0x600, s8
	s_lshl_b64 s[10:11], s[2:3], 1
	v_ashrrev_i32_e32 v131, 31, v130
	v_ashrrev_i32_e32 v173, 31, v172
	v_readlane_b32 s22, v254, 39
	v_lshl_add_u64 v[144:145], v[130:131], 1, s[20:21]
	s_mov_b32 s20, 0x3db504f3
	s_and_b64 s[12:13], s[12:13], exec
	v_or_b32_e32 v142, s2, v187
	v_lshlrev_b64 v[128:129], 10, v[172:173]
	v_readlane_b32 s23, v254, 40
	v_pk_mul_f32 v[130:131], v[126:127], s[20:21] op_sel_hi:[1,0]
	v_mov_b32_e32 v143, v153
	s_cselect_b32 s12, 8, 10
	v_lshl_add_u64 v[128:129], s[22:23], 0, v[128:129]
	v_cvt_pk_bf16_f32 v135, v130, v131
	v_lshlrev_b64 v[130:131], s12, v[142:143]
	v_lshl_add_u64 v[128:129], v[128:129], 0, s[10:11]
	v_lshlrev_b32_e32 v152, 1, v187
	v_pk_mul_f32 v[132:133], v[124:125], s[20:21] op_sel_hi:[1,0]
	v_lshl_add_u64 v[130:131], v[130:131], 1, v[144:145]
	s_lshl_b32 s2, s66, 1
	s_mov_b32 s9, s3
	v_lshl_add_u64 v[128:129], v[128:129], 0, v[152:153]
	v_cvt_pk_bf16_f32 v134, v132, v133
	v_lshl_add_u64 v[132:133], v[130:131], 0, s[2:3]
	global_store_dwordx2 v[128:129], v[134:135], off
	global_store_short_d16_hi v[132:133], v134, off
	v_lshl_add_u64 v[146:147], v[132:133], 0, s[2:3]
	v_lshl_add_u64 v[132:133], v[130:131], 0, s[8:9]
	global_store_short v[130:131], v134, off
	global_store_short v[146:147], v135, off
	global_store_short_d16_hi v[132:133], v135, off
	v_pk_mul_f32 v[134:135], v[122:123], s[20:21] op_sel_hi:[1,0]
	s_waitcnt lgkmcnt(0)
	v_pk_mul_f32 v[136:137], v[120:121], s[20:21] op_sel_hi:[1,0]
	v_cvt_pk_bf16_f32 v139, v134, v135
	v_or_b32_e32 v134, 16, v142
	v_mov_b32_e32 v135, v153
	v_lshlrev_b64 v[134:135], s12, v[134:135]
	v_lshl_add_u64 v[134:135], v[134:135], 1, v[144:145]
	v_cvt_pk_bf16_f32 v138, v136, v137
	v_lshl_add_u64 v[136:137], v[134:135], 0, s[2:3]
	global_store_dwordx2 v[128:129], v[138:139], off offset:32
	global_store_short_d16_hi v[136:137], v138, off
	v_lshl_add_u64 v[148:149], v[136:137], 0, s[2:3]
	v_lshl_add_u64 v[136:137], v[134:135], 0, s[8:9]
	global_store_short v[134:135], v138, off
	global_store_short v[148:149], v139, off
	global_store_short_d16_hi v[136:137], v139, off
	v_or_b32_e32 v138, 0x80, v142
	v_mov_b32_e32 v139, v153
	v_lshlrev_b64 v[138:139], s12, v[138:139]
	v_pk_mul_f32 v[140:141], v[118:119], s[20:21] op_sel_hi:[1,0]
	v_pk_mul_f32 v[150:151], v[116:117], s[20:21] op_sel_hi:[1,0]
	v_lshl_add_u64 v[138:139], v[138:139], 1, v[144:145]
	v_cvt_pk_bf16_f32 v150, v150, v151
	v_cvt_pk_bf16_f32 v151, v140, v141
	v_lshl_add_u64 v[140:141], v[138:139], 0, s[2:3]
	v_or_b32_e32 v142, 0x90, v142
	global_store_dwordx2 v[128:129], v[150:151], off offset:256
	global_store_short_d16_hi v[140:141], v150, off
	v_lshl_add_u64 v[154:155], v[140:141], 0, s[2:3]
	v_lshl_add_u64 v[140:141], v[138:139], 0, s[8:9]
	v_lshlrev_b64 v[142:143], s12, v[142:143]
	global_store_short v[138:139], v150, off
	global_store_short v[154:155], v151, off
	global_store_short_d16_hi v[140:141], v151, off
	v_pk_mul_f32 v[150:151], v[114:115], s[20:21] op_sel_hi:[1,0]
	v_pk_mul_f32 v[174:175], v[112:113], s[20:21] op_sel_hi:[1,0]
	v_lshl_add_u64 v[142:143], v[142:143], 1, v[144:145]
	v_cvt_pk_bf16_f32 v174, v174, v175
	v_cvt_pk_bf16_f32 v175, v150, v151
	v_lshl_add_u64 v[144:145], v[142:143], 0, s[2:3]
	global_store_dwordx2 v[128:129], v[174:175], off offset:288
	global_store_short v[142:143], v174, off
	global_store_short_d16_hi v[144:145], v174, off
	v_lshl_add_u64 v[150:151], v[144:145], 0, s[2:3]
	v_lshl_add_u64 v[144:145], v[142:143], 0, s[8:9]
	v_or_b32_e32 v174, 16, v172
	global_store_short v[150:151], v175, off
	global_store_short_d16_hi v[144:145], v175, off
	v_ashrrev_i32_e32 v175, 31, v174
	v_lshlrev_b64 v[174:175], 10, v[174:175]
	v_lshl_add_u64 v[174:175], s[22:23], 0, v[174:175]
	s_sub_u32 s8, 0, s2
	v_lshl_add_u64 v[174:175], v[174:175], 0, s[10:11]
	v_pk_mul_f32 v[176:177], v[110:111], s[20:21] op_sel_hi:[1,0]
	v_pk_mul_f32 v[178:179], v[108:109], s[20:21] op_sel_hi:[1,0]
	s_subb_u32 s9, 0, 0
	v_lshl_add_u64 v[174:175], v[174:175], 0, v[152:153]
	v_cvt_pk_bf16_f32 v178, v178, v179
	v_cvt_pk_bf16_f32 v179, v176, v177
	v_lshl_add_u64 v[146:147], v[146:147], 0, s[8:9]
	global_store_dwordx2 v[174:175], v[178:179], off
	global_store_short v[130:131], v178, off offset:32
	global_store_short_d16_hi v[146:147], v178, off offset:32
	v_lshl_add_u64 v[146:147], v[146:147], 0, s[2:3]
	global_store_short v[146:147], v179, off offset:32
	global_store_short_d16_hi v[132:133], v179, off offset:32
	v_pk_mul_f32 v[176:177], v[106:107], s[20:21] op_sel_hi:[1,0]
	v_pk_mul_f32 v[178:179], v[104:105], s[20:21] op_sel_hi:[1,0]
	v_lshl_add_u64 v[148:149], v[148:149], 0, s[8:9]
	v_cvt_pk_bf16_f32 v178, v178, v179
	v_cvt_pk_bf16_f32 v179, v176, v177
	global_store_dwordx2 v[174:175], v[178:179], off offset:32
	global_store_short v[134:135], v178, off offset:32
	global_store_short_d16_hi v[148:149], v178, off offset:32
	v_lshl_add_u64 v[148:149], v[148:149], 0, s[2:3]
	global_store_short v[148:149], v179, off offset:32
	global_store_short_d16_hi v[136:137], v179, off offset:32
	v_pk_mul_f32 v[176:177], v[102:103], s[20:21] op_sel_hi:[1,0]
	v_pk_mul_f32 v[178:179], v[100:101], s[20:21] op_sel_hi:[1,0]
	v_lshl_add_u64 v[154:155], v[154:155], 0, s[8:9]
	v_cvt_pk_bf16_f32 v178, v178, v179
	v_cvt_pk_bf16_f32 v179, v176, v177
	global_store_dwordx2 v[174:175], v[178:179], off offset:256
	global_store_short v[138:139], v178, off offset:32
	global_store_short_d16_hi v[154:155], v178, off offset:32
	v_lshl_add_u64 v[154:155], v[154:155], 0, s[2:3]
	global_store_short v[154:155], v179, off offset:32
	global_store_short_d16_hi v[140:141], v179, off offset:32
	v_pk_mul_f32 v[176:177], v[98:99], s[20:21] op_sel_hi:[1,0]
	v_pk_mul_f32 v[178:179], v[96:97], s[20:21] op_sel_hi:[1,0]
	v_lshl_add_u64 v[150:151], v[150:151], 0, s[8:9]
	v_cvt_pk_bf16_f32 v178, v178, v179
	v_cvt_pk_bf16_f32 v179, v176, v177
	global_store_dwordx2 v[174:175], v[178:179], off offset:288
	global_store_short v[142:143], v178, off offset:32
	v_or_b32_e32 v174, 32, v172
	v_ashrrev_i32_e32 v175, 31, v174
	v_lshlrev_b64 v[174:175], 10, v[174:175]
	global_store_short_d16_hi v[150:151], v178, off offset:32
	v_lshl_add_u64 v[150:151], v[150:151], 0, s[2:3]
	v_lshl_add_u64 v[174:175], s[22:23], 0, v[174:175]
	global_store_short v[150:151], v179, off offset:32
	global_store_short_d16_hi v[144:145], v179, off offset:32
	v_lshl_add_u64 v[174:175], v[174:175], 0, s[10:11]
	v_pk_mul_f32 v[176:177], v[94:95], s[20:21] op_sel_hi:[1,0]
	v_pk_mul_f32 v[178:179], v[92:93], s[20:21] op_sel_hi:[1,0]
	v_lshl_add_u64 v[174:175], v[174:175], 0, v[152:153]
	v_cvt_pk_bf16_f32 v178, v178, v179
	v_cvt_pk_bf16_f32 v179, v176, v177
	v_lshl_add_u64 v[146:147], v[146:147], 0, s[8:9]
	global_store_dwordx2 v[174:175], v[178:179], off
	global_store_short v[130:131], v178, off offset:64
	global_store_short_d16_hi v[146:147], v178, off offset:64
	v_lshl_add_u64 v[146:147], v[146:147], 0, s[2:3]
	global_store_short v[146:147], v179, off offset:64
	global_store_short_d16_hi v[132:133], v179, off offset:64
	v_pk_mul_f32 v[176:177], v[90:91], s[20:21] op_sel_hi:[1,0]
	v_pk_mul_f32 v[178:179], v[88:89], s[20:21] op_sel_hi:[1,0]
	v_lshl_add_u64 v[148:149], v[148:149], 0, s[8:9]
	v_cvt_pk_bf16_f32 v178, v178, v179
	v_cvt_pk_bf16_f32 v179, v176, v177
	global_store_dwordx2 v[174:175], v[178:179], off offset:32
	global_store_short v[134:135], v178, off offset:64
	global_store_short_d16_hi v[148:149], v178, off offset:64
	v_lshl_add_u64 v[148:149], v[148:149], 0, s[2:3]
	global_store_short v[148:149], v179, off offset:64
	global_store_short_d16_hi v[136:137], v179, off offset:64
	v_pk_mul_f32 v[176:177], v[86:87], s[20:21] op_sel_hi:[1,0]
	v_pk_mul_f32 v[178:179], v[84:85], s[20:21] op_sel_hi:[1,0]
	v_lshl_add_u64 v[154:155], v[154:155], 0, s[8:9]
	v_cvt_pk_bf16_f32 v178, v178, v179
	v_cvt_pk_bf16_f32 v179, v176, v177
	global_store_dwordx2 v[174:175], v[178:179], off offset:256
	global_store_short v[138:139], v178, off offset:64
	global_store_short_d16_hi v[154:155], v178, off offset:64
	v_lshl_add_u64 v[154:155], v[154:155], 0, s[2:3]
	global_store_short v[154:155], v179, off offset:64
	global_store_short_d16_hi v[140:141], v179, off offset:64
	v_pk_mul_f32 v[176:177], v[82:83], s[20:21] op_sel_hi:[1,0]
	v_pk_mul_f32 v[178:179], v[80:81], s[20:21] op_sel_hi:[1,0]
	v_lshl_add_u64 v[150:151], v[150:151], 0, s[8:9]
	v_cvt_pk_bf16_f32 v178, v178, v179
	v_cvt_pk_bf16_f32 v179, v176, v177
	global_store_dwordx2 v[174:175], v[178:179], off offset:288
	global_store_short v[142:143], v178, off offset:64
	v_or_b32_e32 v174, 48, v172
	v_ashrrev_i32_e32 v175, 31, v174
	v_lshlrev_b64 v[174:175], 10, v[174:175]
	global_store_short_d16_hi v[150:151], v178, off offset:64
	v_lshl_add_u64 v[150:151], v[150:151], 0, s[2:3]
	v_lshl_add_u64 v[174:175], s[22:23], 0, v[174:175]
	global_store_short v[150:151], v179, off offset:64
	global_store_short_d16_hi v[144:145], v179, off offset:64
	v_lshl_add_u64 v[174:175], v[174:175], 0, s[10:11]
	v_pk_mul_f32 v[176:177], v[78:79], s[20:21] op_sel_hi:[1,0]
	v_pk_mul_f32 v[178:179], v[76:77], s[20:21] op_sel_hi:[1,0]
	v_lshl_add_u64 v[174:175], v[174:175], 0, v[152:153]
	v_cvt_pk_bf16_f32 v178, v178, v179
	v_cvt_pk_bf16_f32 v179, v176, v177
	v_lshl_add_u64 v[146:147], v[146:147], 0, s[8:9]
	global_store_dwordx2 v[174:175], v[178:179], off
	global_store_short v[130:131], v178, off offset:96
	global_store_short_d16_hi v[146:147], v178, off offset:96
	v_lshl_add_u64 v[146:147], v[146:147], 0, s[2:3]
	global_store_short v[146:147], v179, off offset:96
	global_store_short_d16_hi v[132:133], v179, off offset:96
	v_pk_mul_f32 v[176:177], v[74:75], s[20:21] op_sel_hi:[1,0]
	v_pk_mul_f32 v[178:179], v[72:73], s[20:21] op_sel_hi:[1,0]
	v_lshl_add_u64 v[148:149], v[148:149], 0, s[8:9]
	v_cvt_pk_bf16_f32 v178, v178, v179
	v_cvt_pk_bf16_f32 v179, v176, v177
	global_store_dwordx2 v[174:175], v[178:179], off offset:32
	global_store_short v[134:135], v178, off offset:96
	global_store_short_d16_hi v[148:149], v178, off offset:96
	v_lshl_add_u64 v[148:149], v[148:149], 0, s[2:3]
	global_store_short v[148:149], v179, off offset:96
	global_store_short_d16_hi v[136:137], v179, off offset:96
	v_pk_mul_f32 v[176:177], v[70:71], s[20:21] op_sel_hi:[1,0]
	v_pk_mul_f32 v[178:179], v[68:69], s[20:21] op_sel_hi:[1,0]
	v_lshl_add_u64 v[154:155], v[154:155], 0, s[8:9]
	v_cvt_pk_bf16_f32 v178, v178, v179
	v_cvt_pk_bf16_f32 v179, v176, v177
	global_store_dwordx2 v[174:175], v[178:179], off offset:256
	global_store_short v[138:139], v178, off offset:96
	global_store_short_d16_hi v[154:155], v178, off offset:96
	v_lshl_add_u64 v[154:155], v[154:155], 0, s[2:3]
	global_store_short v[154:155], v179, off offset:96
	global_store_short_d16_hi v[140:141], v179, off offset:96
	v_pk_mul_f32 v[176:177], v[66:67], s[20:21] op_sel_hi:[1,0]
	v_pk_mul_f32 v[178:179], v[64:65], s[20:21] op_sel_hi:[1,0]
	v_lshl_add_u64 v[150:151], v[150:151], 0, s[8:9]
	v_cvt_pk_bf16_f32 v178, v178, v179
	v_cvt_pk_bf16_f32 v179, v176, v177
	global_store_dwordx2 v[174:175], v[178:179], off offset:288
	global_store_short v[142:143], v178, off offset:96
	global_store_short_d16_hi v[150:151], v178, off offset:96
	v_lshl_add_u64 v[150:151], v[150:151], 0, s[2:3]
	s_mov_b64 s[10:11], 0x20000
	global_store_short v[150:151], v179, off offset:96
	global_store_short_d16_hi v[144:145], v179, off offset:96
	v_lshl_add_u64 v[174:175], v[128:129], 0, s[10:11]
	v_pk_mul_f32 v[176:177], v[62:63], s[20:21] op_sel_hi:[1,0]
	v_pk_mul_f32 v[178:179], v[60:61], s[20:21] op_sel_hi:[1,0]
	s_mov_b32 s10, 0x20000
	v_cvt_pk_bf16_f32 v178, v178, v179
	v_cvt_pk_bf16_f32 v179, v176, v177
	v_add_co_u32_e32 v176, vcc, s10, v128
	v_lshl_add_u64 v[146:147], v[146:147], 0, s[8:9]
	s_nop 0
	v_addc_co_u32_e32 v177, vcc, 0, v129, vcc
	global_store_dwordx2 v[176:177], v[178:179], off
	global_store_short v[130:131], v178, off offset:256
	global_store_short_d16_hi v[146:147], v178, off offset:256
	v_lshl_add_u64 v[146:147], v[146:147], 0, s[2:3]
	global_store_short v[146:147], v179, off offset:256
	global_store_short_d16_hi v[132:133], v179, off offset:256
	v_pk_mul_f32 v[176:177], v[58:59], s[20:21] op_sel_hi:[1,0]
	v_pk_mul_f32 v[178:179], v[56:57], s[20:21] op_sel_hi:[1,0]
	v_lshl_add_u64 v[148:149], v[148:149], 0, s[8:9]
	v_cvt_pk_bf16_f32 v178, v178, v179
	v_cvt_pk_bf16_f32 v179, v176, v177
	global_store_dwordx2 v[174:175], v[178:179], off offset:32
	global_store_short v[134:135], v178, off offset:256
	global_store_short_d16_hi v[148:149], v178, off offset:256
	v_lshl_add_u64 v[148:149], v[148:149], 0, s[2:3]
	global_store_short v[148:149], v179, off offset:256
	global_store_short_d16_hi v[136:137], v179, off offset:256
	v_pk_mul_f32 v[176:177], v[54:55], s[20:21] op_sel_hi:[1,0]
	v_pk_mul_f32 v[178:179], v[52:53], s[20:21] op_sel_hi:[1,0]
	v_lshl_add_u64 v[154:155], v[154:155], 0, s[8:9]
	v_cvt_pk_bf16_f32 v178, v178, v179
	v_cvt_pk_bf16_f32 v179, v176, v177
	global_store_dwordx2 v[174:175], v[178:179], off offset:256
	global_store_short v[138:139], v178, off offset:256
	global_store_short_d16_hi v[154:155], v178, off offset:256
	v_lshl_add_u64 v[154:155], v[154:155], 0, s[2:3]
	global_store_short v[154:155], v179, off offset:256
	global_store_short_d16_hi v[140:141], v179, off offset:256
	v_pk_mul_f32 v[176:177], v[50:51], s[20:21] op_sel_hi:[1,0]
	v_pk_mul_f32 v[178:179], v[48:49], s[20:21] op_sel_hi:[1,0]
	v_lshl_add_u64 v[150:151], v[150:151], 0, s[8:9]
	v_cvt_pk_bf16_f32 v178, v178, v179
	v_cvt_pk_bf16_f32 v179, v176, v177
	global_store_dwordx2 v[174:175], v[178:179], off offset:288
	global_store_short v[142:143], v178, off offset:256
	global_store_short_d16_hi v[150:151], v178, off offset:256
	v_lshl_add_u64 v[150:151], v[150:151], 0, s[2:3]
	s_mov_b64 s[10:11], 0x24000
	global_store_short v[150:151], v179, off offset:256
	global_store_short_d16_hi v[144:145], v179, off offset:256
	v_lshl_add_u64 v[174:175], v[128:129], 0, s[10:11]
	v_pk_mul_f32 v[176:177], v[46:47], s[20:21] op_sel_hi:[1,0]
	v_pk_mul_f32 v[178:179], v[44:45], s[20:21] op_sel_hi:[1,0]
	s_mov_b32 s10, 0x24000
	v_cvt_pk_bf16_f32 v178, v178, v179
	v_cvt_pk_bf16_f32 v179, v176, v177
	v_add_co_u32_e32 v176, vcc, s10, v128
	v_lshl_add_u64 v[146:147], v[146:147], 0, s[8:9]
	s_nop 0
	v_addc_co_u32_e32 v177, vcc, 0, v129, vcc
	global_store_dwordx2 v[176:177], v[178:179], off
	global_store_short v[130:131], v178, off offset:288
	global_store_short_d16_hi v[146:147], v178, off offset:288
	v_lshl_add_u64 v[146:147], v[146:147], 0, s[2:3]
	global_store_short v[146:147], v179, off offset:288
	global_store_short_d16_hi v[132:133], v179, off offset:288
	v_pk_mul_f32 v[176:177], v[42:43], s[20:21] op_sel_hi:[1,0]
	v_pk_mul_f32 v[178:179], v[40:41], s[20:21] op_sel_hi:[1,0]
	v_lshl_add_u64 v[148:149], v[148:149], 0, s[8:9]
	v_cvt_pk_bf16_f32 v178, v178, v179
	v_cvt_pk_bf16_f32 v179, v176, v177
	global_store_dwordx2 v[174:175], v[178:179], off offset:32
	global_store_short v[134:135], v178, off offset:288
	global_store_short_d16_hi v[148:149], v178, off offset:288
	v_lshl_add_u64 v[148:149], v[148:149], 0, s[2:3]
	global_store_short v[148:149], v179, off offset:288
	global_store_short_d16_hi v[136:137], v179, off offset:288
	v_pk_mul_f32 v[176:177], v[38:39], s[20:21] op_sel_hi:[1,0]
	v_pk_mul_f32 v[178:179], v[36:37], s[20:21] op_sel_hi:[1,0]
	v_lshl_add_u64 v[154:155], v[154:155], 0, s[8:9]
	v_cvt_pk_bf16_f32 v178, v178, v179
	v_cvt_pk_bf16_f32 v179, v176, v177
	global_store_dwordx2 v[174:175], v[178:179], off offset:256
	global_store_short v[138:139], v178, off offset:288
	global_store_short_d16_hi v[154:155], v178, off offset:288
	v_lshl_add_u64 v[154:155], v[154:155], 0, s[2:3]
	global_store_short v[154:155], v179, off offset:288
	global_store_short_d16_hi v[140:141], v179, off offset:288
	v_pk_mul_f32 v[176:177], v[34:35], s[20:21] op_sel_hi:[1,0]
	v_pk_mul_f32 v[178:179], v[32:33], s[20:21] op_sel_hi:[1,0]
	v_lshl_add_u64 v[150:151], v[150:151], 0, s[8:9]
	v_cvt_pk_bf16_f32 v178, v178, v179
	v_cvt_pk_bf16_f32 v179, v176, v177
	global_store_dwordx2 v[174:175], v[178:179], off offset:288
	global_store_short v[142:143], v178, off offset:288
	global_store_short_d16_hi v[150:151], v178, off offset:288
	v_lshl_add_u64 v[150:151], v[150:151], 0, s[2:3]
	s_mov_b64 s[10:11], 0x28000
	global_store_short v[150:151], v179, off offset:288
	global_store_short_d16_hi v[144:145], v179, off offset:288
	v_lshl_add_u64 v[174:175], v[128:129], 0, s[10:11]
	v_pk_mul_f32 v[176:177], v[30:31], s[20:21] op_sel_hi:[1,0]
	v_pk_mul_f32 v[178:179], v[28:29], s[20:21] op_sel_hi:[1,0]
	s_mov_b32 s10, 0x28000
	v_cvt_pk_bf16_f32 v178, v178, v179
	v_cvt_pk_bf16_f32 v179, v176, v177
	v_add_co_u32_e32 v176, vcc, s10, v128
	v_lshl_add_u64 v[146:147], v[146:147], 0, s[8:9]
	s_nop 0
	v_addc_co_u32_e32 v177, vcc, 0, v129, vcc
	global_store_dwordx2 v[176:177], v[178:179], off
	global_store_short v[130:131], v178, off offset:320
	global_store_short_d16_hi v[146:147], v178, off offset:320
	v_lshl_add_u64 v[146:147], v[146:147], 0, s[2:3]
	global_store_short v[146:147], v179, off offset:320
	global_store_short_d16_hi v[132:133], v179, off offset:320
	v_pk_mul_f32 v[176:177], v[26:27], s[20:21] op_sel_hi:[1,0]
	v_pk_mul_f32 v[178:179], v[24:25], s[20:21] op_sel_hi:[1,0]
	v_lshl_add_u64 v[148:149], v[148:149], 0, s[8:9]
	v_cvt_pk_bf16_f32 v178, v178, v179
	v_cvt_pk_bf16_f32 v179, v176, v177
	global_store_dwordx2 v[174:175], v[178:179], off offset:32
	global_store_short v[134:135], v178, off offset:320
	global_store_short_d16_hi v[148:149], v178, off offset:320
	v_lshl_add_u64 v[148:149], v[148:149], 0, s[2:3]
	global_store_short v[148:149], v179, off offset:320
	global_store_short_d16_hi v[136:137], v179, off offset:320
	v_pk_mul_f32 v[176:177], v[22:23], s[20:21] op_sel_hi:[1,0]
	v_pk_mul_f32 v[178:179], v[20:21], s[20:21] op_sel_hi:[1,0]
	v_lshl_add_u64 v[154:155], v[154:155], 0, s[8:9]
	v_cvt_pk_bf16_f32 v178, v178, v179
	v_cvt_pk_bf16_f32 v179, v176, v177
	global_store_dwordx2 v[174:175], v[178:179], off offset:256
	global_store_short v[138:139], v178, off offset:320
	global_store_short_d16_hi v[154:155], v178, off offset:320
	v_lshl_add_u64 v[154:155], v[154:155], 0, s[2:3]
	global_store_short v[154:155], v179, off offset:320
	global_store_short_d16_hi v[140:141], v179, off offset:320
	v_pk_mul_f32 v[176:177], v[18:19], s[20:21] op_sel_hi:[1,0]
	v_pk_mul_f32 v[178:179], v[16:17], s[20:21] op_sel_hi:[1,0]
	v_lshl_add_u64 v[150:151], v[150:151], 0, s[8:9]
	v_cvt_pk_bf16_f32 v178, v178, v179
	v_cvt_pk_bf16_f32 v179, v176, v177
	s_mov_b64 s[10:11], 0x2c000
	global_store_dwordx2 v[174:175], v[178:179], off offset:288
	global_store_short v[142:143], v178, off offset:320
	global_store_short_d16_hi v[150:151], v178, off offset:320
	v_lshl_add_u64 v[150:151], v[150:151], 0, s[2:3]
	v_lshl_add_u64 v[174:175], v[128:129], 0, s[10:11]
	s_mov_b32 s10, 0x2c000
	global_store_short v[150:151], v179, off offset:320
	global_store_short_d16_hi v[144:145], v179, off offset:320
	v_pk_mul_f32 v[176:177], v[14:15], s[20:21] op_sel_hi:[1,0]
	v_pk_mul_f32 v[178:179], v[12:13], s[20:21] op_sel_hi:[1,0]
	v_add_co_u32_e32 v128, vcc, s10, v128
	v_cvt_pk_bf16_f32 v178, v178, v179
	v_cvt_pk_bf16_f32 v179, v176, v177
	v_addc_co_u32_e32 v129, vcc, 0, v129, vcc
	global_store_dwordx2 v[128:129], v[178:179], off
	global_store_short v[130:131], v178, off offset:352
	v_lshl_add_u64 v[128:129], v[146:147], 0, s[8:9]
	global_store_short_d16_hi v[128:129], v178, off offset:352
	v_lshl_add_u64 v[128:129], v[128:129], 0, s[2:3]
	global_store_short v[128:129], v179, off offset:352
	global_store_short_d16_hi v[132:133], v179, off offset:352
	v_pk_mul_f32 v[128:129], v[10:11], s[20:21] op_sel_hi:[1,0]
	v_pk_mul_f32 v[130:131], v[8:9], s[20:21] op_sel_hi:[1,0]
	s_nop 0
	v_cvt_pk_bf16_f32 v130, v130, v131
	v_cvt_pk_bf16_f32 v131, v128, v129
	v_lshl_add_u64 v[128:129], v[148:149], 0, s[8:9]
	global_store_dwordx2 v[174:175], v[130:131], off offset:32
	global_store_short v[134:135], v130, off offset:352
	global_store_short_d16_hi v[128:129], v130, off offset:352
	v_lshl_add_u64 v[128:129], v[128:129], 0, s[2:3]
	global_store_short v[128:129], v131, off offset:352
	global_store_short_d16_hi v[136:137], v131, off offset:352
	v_pk_mul_f32 v[128:129], v[6:7], s[20:21] op_sel_hi:[1,0]
	v_pk_mul_f32 v[130:131], v[4:5], s[20:21] op_sel_hi:[1,0]
	s_nop 0
	v_cvt_pk_bf16_f32 v130, v130, v131
	v_cvt_pk_bf16_f32 v131, v128, v129
	v_lshl_add_u64 v[128:129], v[154:155], 0, s[8:9]
	global_store_dwordx2 v[174:175], v[130:131], off offset:256
	global_store_short v[138:139], v130, off offset:352
	global_store_short_d16_hi v[128:129], v130, off offset:352
	v_lshl_add_u64 v[128:129], v[128:129], 0, s[2:3]
	global_store_short v[128:129], v131, off offset:352
	global_store_short_d16_hi v[140:141], v131, off offset:352
	v_pk_mul_f32 v[128:129], v[2:3], s[20:21] op_sel_hi:[1,0]
	v_pk_mul_f32 v[130:131], v[0:1], s[20:21] op_sel_hi:[1,0]
	s_nop 0
	v_cvt_pk_bf16_f32 v130, v130, v131
	v_cvt_pk_bf16_f32 v131, v128, v129
	v_lshl_add_u64 v[128:129], v[150:151], 0, s[8:9]
	global_store_dwordx2 v[174:175], v[130:131], off offset:288
	global_store_short v[142:143], v130, off offset:352
	global_store_short_d16_hi v[128:129], v130, off offset:352
	v_lshl_add_u64 v[128:129], v[128:129], 0, s[2:3]
	global_store_short v[128:129], v131, off offset:352
	global_store_short_d16_hi v[144:145], v131, off offset:352

.LBB0_1127:
	s_andn2_b64 vcc, exec, s[8:9]
	s_cbranch_vccnz .LBB0_1129
	v_ashrrev_i32_e32 v173, 31, v172
	v_lshlrev_b64 v[128:129], 10, v[172:173]
	v_lshl_add_u64 v[128:129], s[18:19], 0, v[128:129]
	s_lshl_b32 s2, s14, 9
	v_lshl_add_u64 v[128:129], v[128:129], 0, s[2:3]
	v_lshlrev_b32_e32 v152, 1, v186
	v_lshl_add_u64 v[132:133], v[128:129], 0, v[152:153]
	s_mov_b32 s8, 0xc6ff000
	s_waitcnt lgkmcnt(0)
	v_add_co_u32_e32 v136, vcc, s8, v132
	s_mov_b64 s[10:11], 0xc6ff800
	v_cvt_pk_bf16_f32 v128, v124, v125
	v_cvt_pk_bf16_f32 v129, v126, v127
	v_cvt_pk_bf16_f32 v130, v120, v121
	v_cvt_pk_bf16_f32 v131, v122, v123
	v_addc_co_u32_e32 v137, vcc, 0, v133, vcc
	v_lshl_add_u64 v[134:135], v[132:133], 0, s[10:11]
	global_store_dwordx4 v[136:137], v[128:131], off offset:2048
	s_nop 1
	v_cvt_pk_bf16_f32 v128, v116, v117
	v_cvt_pk_bf16_f32 v129, v118, v119
	v_cvt_pk_bf16_f32 v130, v112, v113
	v_cvt_pk_bf16_f32 v131, v114, v115
	global_store_dwordx4 v[134:135], v[128:131], off offset:256
	s_nop 1
	v_or_b32_e32 v128, 16, v172
	v_ashrrev_i32_e32 v129, 31, v128
	v_lshlrev_b64 v[128:129], 10, v[128:129]
	v_lshl_add_u64 v[128:129], s[18:19], 0, v[128:129]
	v_lshl_add_u64 v[128:129], v[128:129], 0, s[2:3]
	v_lshl_add_u64 v[134:135], v[128:129], 0, v[152:153]
	v_lshl_add_u64 v[136:137], v[134:135], 0, s[10:11]
	v_add_co_u32_e32 v134, vcc, s8, v134
	v_cvt_pk_bf16_f32 v128, v108, v109
	v_cvt_pk_bf16_f32 v129, v110, v111
	v_cvt_pk_bf16_f32 v130, v104, v105
	v_cvt_pk_bf16_f32 v131, v106, v107
	v_addc_co_u32_e32 v135, vcc, 0, v135, vcc
	global_store_dwordx4 v[134:135], v[128:131], off offset:2048
	s_nop 1
	v_cvt_pk_bf16_f32 v128, v100, v101
	v_cvt_pk_bf16_f32 v129, v102, v103
	v_cvt_pk_bf16_f32 v130, v96, v97
	v_cvt_pk_bf16_f32 v131, v98, v99
	global_store_dwordx4 v[136:137], v[128:131], off offset:256
	s_nop 1
	v_or_b32_e32 v128, 32, v172
	v_ashrrev_i32_e32 v129, 31, v128
	v_lshlrev_b64 v[128:129], 10, v[128:129]
	v_lshl_add_u64 v[128:129], s[18:19], 0, v[128:129]
	v_lshl_add_u64 v[128:129], v[128:129], 0, s[2:3]
	v_lshl_add_u64 v[134:135], v[128:129], 0, v[152:153]
	v_lshl_add_u64 v[136:137], v[134:135], 0, s[10:11]
	v_add_co_u32_e32 v134, vcc, s8, v134
	v_cvt_pk_bf16_f32 v128, v92, v93
	v_cvt_pk_bf16_f32 v129, v94, v95
	v_cvt_pk_bf16_f32 v130, v88, v89
	v_cvt_pk_bf16_f32 v131, v90, v91
	v_addc_co_u32_e32 v135, vcc, 0, v135, vcc
	global_store_dwordx4 v[134:135], v[128:131], off offset:2048
	s_nop 1
	v_cvt_pk_bf16_f32 v128, v84, v85
	v_cvt_pk_bf16_f32 v129, v86, v87
	v_cvt_pk_bf16_f32 v130, v80, v81
	v_cvt_pk_bf16_f32 v131, v82, v83
	global_store_dwordx4 v[136:137], v[128:131], off offset:256
	s_nop 1
	v_or_b32_e32 v128, 48, v172
	v_ashrrev_i32_e32 v129, 31, v128
	v_lshlrev_b64 v[128:129], 10, v[128:129]
	v_lshl_add_u64 v[128:129], s[18:19], 0, v[128:129]
	v_lshl_add_u64 v[128:129], v[128:129], 0, s[2:3]
	v_lshl_add_u64 v[134:135], v[128:129], 0, v[152:153]
	v_lshl_add_u64 v[136:137], v[134:135], 0, s[10:11]
	v_add_co_u32_e32 v134, vcc, s8, v134
	v_cvt_pk_bf16_f32 v128, v76, v77
	v_cvt_pk_bf16_f32 v129, v78, v79
	v_cvt_pk_bf16_f32 v130, v72, v73
	v_cvt_pk_bf16_f32 v131, v74, v75
	v_addc_co_u32_e32 v135, vcc, 0, v135, vcc
	global_store_dwordx4 v[134:135], v[128:131], off offset:2048
	s_mov_b32 s2, 0xc71f000
	s_mov_b64 s[8:9], 0xc71f800
	v_cvt_pk_bf16_f32 v128, v68, v69
	v_cvt_pk_bf16_f32 v129, v70, v71
	v_cvt_pk_bf16_f32 v130, v64, v65
	v_cvt_pk_bf16_f32 v131, v66, v67
	global_store_dwordx4 v[136:137], v[128:131], off offset:256
	v_add_co_u32_e32 v136, vcc, s2, v132
	s_nop 0
	v_cvt_pk_bf16_f32 v128, v60, v61
	v_cvt_pk_bf16_f32 v129, v62, v63
	v_cvt_pk_bf16_f32 v130, v56, v57
	v_cvt_pk_bf16_f32 v131, v58, v59
	v_addc_co_u32_e32 v137, vcc, 0, v133, vcc
	s_mov_b32 s2, 0xc723000
	v_lshl_add_u64 v[134:135], v[132:133], 0, s[8:9]
	global_store_dwordx4 v[136:137], v[128:131], off offset:2048
	v_add_co_u32_e32 v136, vcc, s2, v132
	s_nop 0
	v_cvt_pk_bf16_f32 v128, v52, v53
	v_cvt_pk_bf16_f32 v129, v54, v55
	v_cvt_pk_bf16_f32 v130, v48, v49
	v_cvt_pk_bf16_f32 v131, v50, v51
	global_store_dwordx4 v[134:135], v[128:131], off offset:256
	s_mov_b64 s[8:9], 0xc723800
	v_addc_co_u32_e32 v137, vcc, 0, v133, vcc
	v_cvt_pk_bf16_f32 v128, v44, v45
	v_cvt_pk_bf16_f32 v129, v46, v47
	v_cvt_pk_bf16_f32 v130, v40, v41
	v_cvt_pk_bf16_f32 v131, v42, v43
	s_mov_b32 s2, 0xc727000
	v_lshl_add_u64 v[134:135], v[132:133], 0, s[8:9]
	global_store_dwordx4 v[136:137], v[128:131], off offset:2048
	v_add_co_u32_e32 v136, vcc, s2, v132
	s_nop 0
	v_cvt_pk_bf16_f32 v128, v36, v37
	v_cvt_pk_bf16_f32 v129, v38, v39
	v_cvt_pk_bf16_f32 v130, v32, v33
	v_cvt_pk_bf16_f32 v131, v34, v35
	global_store_dwordx4 v[134:135], v[128:131], off offset:256
	s_mov_b64 s[8:9], 0xc727800
	v_addc_co_u32_e32 v137, vcc, 0, v133, vcc
	v_cvt_pk_bf16_f32 v128, v28, v29
	v_cvt_pk_bf16_f32 v129, v30, v31
	v_cvt_pk_bf16_f32 v130, v24, v25
	v_cvt_pk_bf16_f32 v131, v26, v27
	v_lshl_add_u64 v[134:135], v[132:133], 0, s[8:9]
	global_store_dwordx4 v[136:137], v[128:131], off offset:2048
	s_mov_b64 s[8:9], 0xc72b800
	s_mov_b32 s2, 0xc72b000
	v_cvt_pk_bf16_f32 v128, v20, v21
	v_cvt_pk_bf16_f32 v129, v22, v23
	v_cvt_pk_bf16_f32 v130, v16, v17
	v_cvt_pk_bf16_f32 v131, v18, v19
	global_store_dwordx4 v[134:135], v[128:131], off offset:256
	v_lshl_add_u64 v[134:135], v[132:133], 0, s[8:9]
	v_add_co_u32_e32 v132, vcc, s2, v132
	v_cvt_pk_bf16_f32 v128, v12, v13
	v_cvt_pk_bf16_f32 v129, v14, v15
	v_cvt_pk_bf16_f32 v130, v8, v9
	v_cvt_pk_bf16_f32 v131, v10, v11
	v_addc_co_u32_e32 v133, vcc, 0, v133, vcc
	global_store_dwordx4 v[132:133], v[128:131], off offset:2048
	s_nop 1
	v_cvt_pk_bf16_f32 v128, v4, v5
	v_cvt_pk_bf16_f32 v129, v6, v7
	v_cvt_pk_bf16_f32 v130, v0, v1
	v_cvt_pk_bf16_f32 v131, v2, v3
	global_store_dwordx4 v[134:135], v[128:131], off offset:256

.LBB0_1130:
	s_andn2_b64 vcc, exec, s[8:9]
	s_cbranch_vccnz .LBB0_1132
	v_mul_f32_e32 v130, 0xbfb8aa3b, v116
	v_mul_f32_e32 v131, 0xbfb8aa3b, v117
	v_mul_f32_e32 v132, 0xbfb8aa3b, v118
	v_mul_f32_e32 v133, 0xbfb8aa3b, v119
	v_mul_f32_e32 v134, 0xbfb8aa3b, v112
	v_mul_f32_e32 v135, 0xbfb8aa3b, v113
	s_waitcnt lgkmcnt(0)
	v_mul_f32_e32 v136, 0xbfb8aa3b, v114
	v_mul_f32_e32 v137, 0xbfb8aa3b, v115
	v_exp_f32_e32 v130, v130
	v_exp_f32_e32 v131, v131
	v_exp_f32_e32 v132, v132
	v_exp_f32_e32 v133, v133
	v_exp_f32_e32 v134, v134
	v_exp_f32_e32 v135, v135
	v_exp_f32_e32 v136, v136
	v_exp_f32_e32 v137, v137
	v_add_f32_e32 v130, 1.0, v130
	v_add_f32_e32 v131, 1.0, v131
	v_add_f32_e32 v132, 1.0, v132
	v_add_f32_e32 v133, 1.0, v133
	v_add_f32_e32 v134, 1.0, v134
	v_add_f32_e32 v135, 1.0, v135
	v_add_f32_e32 v136, 1.0, v136
	v_add_f32_e32 v137, 1.0, v137
	v_rcp_f32_e32 v130, v130
	v_rcp_f32_e32 v131, v131
	v_rcp_f32_e32 v132, v132
	v_rcp_f32_e32 v133, v133
	v_rcp_f32_e32 v134, v134
	v_rcp_f32_e32 v135, v135
	v_rcp_f32_e32 v136, v136
	v_rcp_f32_e32 v137, v137
	s_lshl_b32 s8, s14, 7
	v_ashrrev_i32_e32 v173, 31, v172
	v_readlane_b32 s10, v254, 35
	s_ashr_i32 s9, s8, 31
	v_lshlrev_b64 v[128:129], 10, v[172:173]
	v_readlane_b32 s11, v254, 36
	s_lshl_b64 s[8:9], s[8:9], 1
	v_pk_mul_f32 v[130:131], v[124:125], v[130:131]
	v_lshl_add_u64 v[128:129], s[10:11], 0, v[128:129]
	v_lshl_add_u64 v[128:129], v[128:129], 0, s[8:9]
	v_pk_mul_f32 v[132:133], v[126:127], v[132:133]
	v_pk_mul_f32 v[134:135], v[120:121], v[134:135]
	v_pk_mul_f32 v[136:137], v[122:123], v[136:137]
	v_lshlrev_b32_e32 v152, 1, v186
	v_lshl_add_u64 v[128:129], v[128:129], 0, v[152:153]
	v_cvt_pk_bf16_f32 v130, v130, v131
	v_cvt_pk_bf16_f32 v131, v132, v133
	v_cvt_pk_bf16_f32 v132, v134, v135
	v_cvt_pk_bf16_f32 v133, v136, v137
	global_store_dwordx4 v[128:129], v[130:133], off
	v_mul_f32_e32 v134, 0xbfb8aa3b, v102
	v_mul_f32_e32 v135, 0xbfb8aa3b, v103
	v_mul_f32_e32 v132, 0xbfb8aa3b, v100
	v_mul_f32_e32 v133, 0xbfb8aa3b, v101
	v_mul_f32_e32 v136, 0xbfb8aa3b, v96
	v_mul_f32_e32 v137, 0xbfb8aa3b, v97
	v_mul_f32_e32 v138, 0xbfb8aa3b, v98
	v_mul_f32_e32 v139, 0xbfb8aa3b, v99
	v_exp_f32_e32 v132, v132
	v_exp_f32_e32 v133, v133
	v_exp_f32_e32 v134, v134
	v_exp_f32_e32 v135, v135
	v_exp_f32_e32 v136, v136
	v_exp_f32_e32 v137, v137
	v_exp_f32_e32 v138, v138
	v_exp_f32_e32 v139, v139
	v_add_f32_e32 v132, 1.0, v132
	v_add_f32_e32 v133, 1.0, v133
	v_add_f32_e32 v134, 1.0, v134
	v_add_f32_e32 v135, 1.0, v135
	v_add_f32_e32 v136, 1.0, v136
	v_add_f32_e32 v137, 1.0, v137
	v_add_f32_e32 v138, 1.0, v138
	v_add_f32_e32 v139, 1.0, v139
	v_or_b32_e32 v130, 16, v172
	v_rcp_f32_e32 v132, v132
	v_rcp_f32_e32 v133, v133
	v_rcp_f32_e32 v134, v134
	v_rcp_f32_e32 v135, v135
	v_rcp_f32_e32 v136, v136
	v_rcp_f32_e32 v137, v137
	v_rcp_f32_e32 v138, v138
	v_rcp_f32_e32 v139, v139
	v_ashrrev_i32_e32 v131, 31, v130
	v_lshlrev_b64 v[130:131], 10, v[130:131]
	v_lshl_add_u64 v[130:131], s[10:11], 0, v[130:131]
	v_lshl_add_u64 v[130:131], v[130:131], 0, s[8:9]
	v_pk_mul_f32 v[132:133], v[108:109], v[132:133]
	v_pk_mul_f32 v[134:135], v[110:111], v[134:135]
	v_pk_mul_f32 v[136:137], v[104:105], v[136:137]
	v_pk_mul_f32 v[138:139], v[106:107], v[138:139]
	v_lshl_add_u64 v[140:141], v[130:131], 0, v[152:153]
	v_cvt_pk_bf16_f32 v130, v132, v133
	v_cvt_pk_bf16_f32 v131, v134, v135
	v_cvt_pk_bf16_f32 v132, v136, v137
	v_cvt_pk_bf16_f32 v133, v138, v139
	global_store_dwordx4 v[140:141], v[130:133], off
	v_mul_f32_e32 v134, 0xbfb8aa3b, v86
	v_mul_f32_e32 v135, 0xbfb8aa3b, v87
	v_mul_f32_e32 v132, 0xbfb8aa3b, v84
	v_mul_f32_e32 v133, 0xbfb8aa3b, v85
	v_mul_f32_e32 v136, 0xbfb8aa3b, v80
	v_mul_f32_e32 v137, 0xbfb8aa3b, v81
	v_mul_f32_e32 v138, 0xbfb8aa3b, v82
	v_mul_f32_e32 v139, 0xbfb8aa3b, v83
	v_exp_f32_e32 v132, v132
	v_exp_f32_e32 v133, v133
	v_exp_f32_e32 v134, v134
	v_exp_f32_e32 v135, v135
	v_exp_f32_e32 v136, v136
	v_exp_f32_e32 v137, v137
	v_exp_f32_e32 v138, v138
	v_exp_f32_e32 v139, v139
	v_add_f32_e32 v132, 1.0, v132
	v_add_f32_e32 v133, 1.0, v133
	v_add_f32_e32 v134, 1.0, v134
	v_add_f32_e32 v135, 1.0, v135
	v_add_f32_e32 v136, 1.0, v136
	v_add_f32_e32 v137, 1.0, v137
	v_add_f32_e32 v138, 1.0, v138
	v_add_f32_e32 v139, 1.0, v139
	v_or_b32_e32 v130, 32, v172
	v_rcp_f32_e32 v132, v132
	v_rcp_f32_e32 v133, v133
	v_rcp_f32_e32 v134, v134
	v_rcp_f32_e32 v135, v135
	v_rcp_f32_e32 v136, v136
	v_rcp_f32_e32 v137, v137
	v_rcp_f32_e32 v138, v138
	v_rcp_f32_e32 v139, v139
	v_ashrrev_i32_e32 v131, 31, v130
	v_lshlrev_b64 v[130:131], 10, v[130:131]
	v_lshl_add_u64 v[130:131], s[10:11], 0, v[130:131]
	v_lshl_add_u64 v[130:131], v[130:131], 0, s[8:9]
	v_pk_mul_f32 v[132:133], v[92:93], v[132:133]
	v_pk_mul_f32 v[134:135], v[94:95], v[134:135]
	v_pk_mul_f32 v[136:137], v[88:89], v[136:137]
	v_pk_mul_f32 v[138:139], v[90:91], v[138:139]
	v_lshl_add_u64 v[140:141], v[130:131], 0, v[152:153]
	v_cvt_pk_bf16_f32 v130, v132, v133
	v_cvt_pk_bf16_f32 v131, v134, v135
	v_cvt_pk_bf16_f32 v132, v136, v137
	v_cvt_pk_bf16_f32 v133, v138, v139
	v_mul_f32_e32 v134, 0xbfb8aa3b, v70
	v_mul_f32_e32 v135, 0xbfb8aa3b, v71
	global_store_dwordx4 v[140:141], v[130:133], off
	v_exp_f32_e32 v134, v134
	v_exp_f32_e32 v135, v135
	v_mul_f32_e32 v132, 0xbfb8aa3b, v68
	v_mul_f32_e32 v133, 0xbfb8aa3b, v69
	v_mul_f32_e32 v136, 0xbfb8aa3b, v64
	v_mul_f32_e32 v137, 0xbfb8aa3b, v65
	v_mul_f32_e32 v138, 0xbfb8aa3b, v66
	v_mul_f32_e32 v139, 0xbfb8aa3b, v67
	v_exp_f32_e32 v132, v132
	v_exp_f32_e32 v133, v133
	v_exp_f32_e32 v136, v136
	v_exp_f32_e32 v137, v137
	v_exp_f32_e32 v138, v138
	v_exp_f32_e32 v139, v139
	v_add_f32_e32 v134, 1.0, v134
	v_add_f32_e32 v135, 1.0, v135
	v_or_b32_e32 v130, 48, v172
	v_add_f32_e32 v132, 1.0, v132
	v_add_f32_e32 v133, 1.0, v133
	v_rcp_f32_e32 v134, v134
	v_rcp_f32_e32 v135, v135
	v_add_f32_e32 v136, 1.0, v136
	v_add_f32_e32 v137, 1.0, v137
	v_add_f32_e32 v138, 1.0, v138
	v_add_f32_e32 v139, 1.0, v139
	v_ashrrev_i32_e32 v131, 31, v130
	v_rcp_f32_e32 v132, v132
	v_rcp_f32_e32 v133, v133
	v_rcp_f32_e32 v136, v136
	v_rcp_f32_e32 v137, v137
	v_rcp_f32_e32 v138, v138
	v_rcp_f32_e32 v139, v139
	v_lshlrev_b64 v[130:131], 10, v[130:131]
	v_lshl_add_u64 v[130:131], s[10:11], 0, v[130:131]
	v_lshl_add_u64 v[130:131], v[130:131], 0, s[8:9]
	v_pk_mul_f32 v[134:135], v[78:79], v[134:135]
	v_pk_mul_f32 v[132:133], v[76:77], v[132:133]
	v_pk_mul_f32 v[136:137], v[72:73], v[136:137]
	v_pk_mul_f32 v[138:139], v[74:75], v[138:139]
	v_lshl_add_u64 v[140:141], v[130:131], 0, v[152:153]
	v_cvt_pk_bf16_f32 v131, v134, v135
	v_mul_f32_e32 v134, 0xbfb8aa3b, v52
	v_mul_f32_e32 v135, 0xbfb8aa3b, v53
	v_cvt_pk_bf16_f32 v130, v132, v133
	v_cvt_pk_bf16_f32 v132, v136, v137
	v_cvt_pk_bf16_f32 v133, v138, v139
	v_exp_f32_e32 v134, v134
	v_exp_f32_e32 v135, v135
	global_store_dwordx4 v[140:141], v[130:133], off
	v_mul_f32_e32 v136, 0xbfb8aa3b, v50
	v_mul_f32_e32 v137, 0xbfb8aa3b, v51
	v_mul_f32_e32 v132, 0xbfb8aa3b, v54
	v_mul_f32_e32 v133, 0xbfb8aa3b, v55
	v_exp_f32_e32 v132, v132
	v_exp_f32_e32 v133, v133
	v_exp_f32_e32 v136, v136
	v_exp_f32_e32 v137, v137
	v_add_f32_e32 v130, 1.0, v134
	v_add_f32_e32 v131, 1.0, v135
	v_mul_f32_e32 v134, 0xbfb8aa3b, v48
	v_mul_f32_e32 v135, 0xbfb8aa3b, v49
	v_exp_f32_e32 v134, v134
	v_exp_f32_e32 v135, v135
	v_add_f32_e32 v132, 1.0, v132
	v_add_f32_e32 v133, 1.0, v133
	v_add_f32_e32 v136, 1.0, v136
	v_add_f32_e32 v137, 1.0, v137
	v_rcp_f32_e32 v130, v130
	v_rcp_f32_e32 v131, v131
	v_rcp_f32_e32 v132, v132
	v_rcp_f32_e32 v133, v133
	v_rcp_f32_e32 v136, v136
	v_rcp_f32_e32 v137, v137
	v_add_f32_e32 v134, 1.0, v134
	v_add_f32_e32 v135, 1.0, v135
	v_rcp_f32_e32 v134, v134
	v_rcp_f32_e32 v135, v135
	v_pk_mul_f32 v[130:131], v[60:61], v[130:131]
	v_pk_mul_f32 v[132:133], v[62:63], v[132:133]
	v_pk_mul_f32 v[136:137], v[58:59], v[136:137]
	v_cvt_pk_bf16_f32 v130, v130, v131
	v_cvt_pk_bf16_f32 v131, v132, v133
	v_cvt_pk_bf16_f32 v133, v136, v137
	v_mul_f32_e32 v136, 0xbfb8aa3b, v36
	v_mul_f32_e32 v137, 0xbfb8aa3b, v37
	v_exp_f32_e32 v136, v136
	v_exp_f32_e32 v137, v137
	v_pk_mul_f32 v[134:135], v[56:57], v[134:135]
	s_mov_b32 s2, 0x20000
	v_cvt_pk_bf16_f32 v132, v134, v135
	v_add_co_u32_e32 v134, vcc, s2, v128
	s_mov_b32 s2, 0x24000
	s_nop 0
	v_addc_co_u32_e32 v135, vcc, 0, v129, vcc
	global_store_dwordx4 v[134:135], v[130:133], off
	v_mul_f32_e32 v134, 0xbfb8aa3b, v32
	v_mul_f32_e32 v135, 0xbfb8aa3b, v33
	v_add_f32_e32 v130, 1.0, v136
	v_add_f32_e32 v131, 1.0, v137
	v_mul_f32_e32 v132, 0xbfb8aa3b, v38
	v_mul_f32_e32 v133, 0xbfb8aa3b, v39
	v_mul_f32_e32 v136, 0xbfb8aa3b, v34
	v_mul_f32_e32 v137, 0xbfb8aa3b, v35
	v_exp_f32_e32 v132, v132
	v_exp_f32_e32 v133, v133
	v_exp_f32_e32 v136, v136
	v_exp_f32_e32 v137, v137
	v_exp_f32_e32 v134, v134
	v_exp_f32_e32 v135, v135
	v_add_f32_e32 v132, 1.0, v132
	v_add_f32_e32 v133, 1.0, v133
	v_add_f32_e32 v136, 1.0, v136
	v_add_f32_e32 v137, 1.0, v137
	v_rcp_f32_e32 v130, v130
	v_rcp_f32_e32 v131, v131
	v_rcp_f32_e32 v132, v132
	v_rcp_f32_e32 v133, v133
	v_rcp_f32_e32 v136, v136
	v_rcp_f32_e32 v137, v137
	v_add_f32_e32 v134, 1.0, v134
	v_add_f32_e32 v135, 1.0, v135
	v_rcp_f32_e32 v134, v134
	v_rcp_f32_e32 v135, v135
	v_pk_mul_f32 v[130:131], v[44:45], v[130:131]
	v_pk_mul_f32 v[132:133], v[46:47], v[132:133]
	v_pk_mul_f32 v[136:137], v[42:43], v[136:137]
	v_cvt_pk_bf16_f32 v130, v130, v131
	v_cvt_pk_bf16_f32 v131, v132, v133
	v_cvt_pk_bf16_f32 v133, v136, v137
	v_mul_f32_e32 v136, 0xbfb8aa3b, v20
	v_mul_f32_e32 v137, 0xbfb8aa3b, v21
	v_exp_f32_e32 v136, v136
	v_exp_f32_e32 v137, v137
	v_pk_mul_f32 v[134:135], v[40:41], v[134:135]
	s_nop 0
	v_cvt_pk_bf16_f32 v132, v134, v135
	v_add_co_u32_e32 v134, vcc, s2, v128
	s_mov_b32 s2, 0x28000
	s_nop 0
	v_addc_co_u32_e32 v135, vcc, 0, v129, vcc
	global_store_dwordx4 v[134:135], v[130:133], off
	v_mul_f32_e32 v134, 0xbfb8aa3b, v16
	v_mul_f32_e32 v135, 0xbfb8aa3b, v17
	v_add_f32_e32 v130, 1.0, v136
	v_add_f32_e32 v131, 1.0, v137
	v_mul_f32_e32 v132, 0xbfb8aa3b, v22
	v_mul_f32_e32 v133, 0xbfb8aa3b, v23
	v_mul_f32_e32 v136, 0xbfb8aa3b, v18
	v_mul_f32_e32 v137, 0xbfb8aa3b, v19
	v_exp_f32_e32 v132, v132
	v_exp_f32_e32 v133, v133
	v_exp_f32_e32 v136, v136
	v_exp_f32_e32 v137, v137
	v_exp_f32_e32 v134, v134
	v_exp_f32_e32 v135, v135
	v_add_f32_e32 v132, 1.0, v132
	v_add_f32_e32 v133, 1.0, v133
	v_add_f32_e32 v136, 1.0, v136
	v_add_f32_e32 v137, 1.0, v137
	v_rcp_f32_e32 v130, v130
	v_rcp_f32_e32 v131, v131
	v_rcp_f32_e32 v132, v132
	v_rcp_f32_e32 v133, v133
	v_rcp_f32_e32 v136, v136
	v_rcp_f32_e32 v137, v137
	v_add_f32_e32 v134, 1.0, v134
	v_add_f32_e32 v135, 1.0, v135
	v_rcp_f32_e32 v134, v134
	v_rcp_f32_e32 v135, v135
	v_pk_mul_f32 v[130:131], v[28:29], v[130:131]
	v_pk_mul_f32 v[132:133], v[30:31], v[132:133]
	v_pk_mul_f32 v[136:137], v[26:27], v[136:137]
	v_cvt_pk_bf16_f32 v130, v130, v131
	v_cvt_pk_bf16_f32 v131, v132, v133
	v_cvt_pk_bf16_f32 v133, v136, v137
	v_mul_f32_e32 v136, 0xbfb8aa3b, v4
	v_mul_f32_e32 v137, 0xbfb8aa3b, v5
	v_exp_f32_e32 v136, v136
	v_exp_f32_e32 v137, v137
	v_pk_mul_f32 v[134:135], v[24:25], v[134:135]
	s_nop 0
	v_cvt_pk_bf16_f32 v132, v134, v135
	v_add_co_u32_e32 v134, vcc, s2, v128
	s_nop 1
	v_addc_co_u32_e32 v135, vcc, 0, v129, vcc
	global_store_dwordx4 v[134:135], v[130:133], off
	v_mul_f32_e32 v134, 0xbfb8aa3b, v0
	v_mul_f32_e32 v135, 0xbfb8aa3b, v1
	v_add_f32_e32 v130, 1.0, v136
	v_add_f32_e32 v131, 1.0, v137
	v_mul_f32_e32 v132, 0xbfb8aa3b, v6
	v_mul_f32_e32 v133, 0xbfb8aa3b, v7
	v_mul_f32_e32 v136, 0xbfb8aa3b, v2
	v_mul_f32_e32 v137, 0xbfb8aa3b, v3
	v_exp_f32_e32 v132, v132
	v_exp_f32_e32 v133, v133
	v_exp_f32_e32 v134, v134
	v_exp_f32_e32 v135, v135
	v_exp_f32_e32 v136, v136
	v_exp_f32_e32 v137, v137
	v_add_f32_e32 v132, 1.0, v132
	v_add_f32_e32 v133, 1.0, v133
	v_add_f32_e32 v134, 1.0, v134
	v_add_f32_e32 v135, 1.0, v135
	v_add_f32_e32 v136, 1.0, v136
	v_add_f32_e32 v137, 1.0, v137
	v_rcp_f32_e32 v130, v130
	v_rcp_f32_e32 v131, v131
	v_rcp_f32_e32 v132, v132
	v_rcp_f32_e32 v133, v133
	v_rcp_f32_e32 v134, v134
	v_rcp_f32_e32 v135, v135
	v_rcp_f32_e32 v136, v136
	v_rcp_f32_e32 v137, v137
	v_pk_mul_f32 v[130:131], v[12:13], v[130:131]
	v_pk_mul_f32 v[132:133], v[14:15], v[132:133]
	v_pk_mul_f32 v[134:135], v[8:9], v[134:135]
	v_pk_mul_f32 v[136:137], v[10:11], v[136:137]
	v_add_co_u32_e32 v128, vcc, 0x2c000, v128
	v_cvt_pk_bf16_f32 v130, v130, v131
	v_cvt_pk_bf16_f32 v131, v132, v133
	v_cvt_pk_bf16_f32 v132, v134, v135
	v_cvt_pk_bf16_f32 v133, v136, v137
	v_addc_co_u32_e32 v129, vcc, 0, v129, vcc
	global_store_dwordx4 v[128:129], v[130:133], off

.LBB0_1133:
	s_andn2_b64 vcc, exec, s[8:9]
	s_cbranch_vccnz .LBB0_1135
	s_mov_b32 s89, s3
	s_lshl_b64 s[8:9], s[88:89], 24
	s_add_u32 s8, s56, s8
	v_ashrrev_i32_e32 v173, 31, v172
	s_addc_u32 s9, s57, s9
	s_lshl_b32 s10, s14, 8
	v_lshlrev_b64 v[128:129], 11, v[172:173]
	s_ashr_i32 s11, s10, 31
	v_lshl_add_u64 v[128:129], s[8:9], 0, v[128:129]
	s_lshl_b64 s[10:11], s[10:11], 1
	v_lshl_add_u64 v[128:129], v[128:129], 0, s[10:11]
	v_lshlrev_b32_e32 v152, 1, v186
	v_lshl_add_u64 v[132:133], v[128:129], 0, v[152:153]
	v_cvt_pk_bf16_f32 v128, v124, v125
	v_cvt_pk_bf16_f32 v129, v126, v127
	v_cvt_pk_bf16_f32 v130, v120, v121
	v_cvt_pk_bf16_f32 v131, v122, v123
	global_store_dwordx4 v[132:133], v[128:131], off
	s_mov_b32 s2, 0x40000
	s_waitcnt lgkmcnt(0)
	v_add_co_u32_e32 v136, vcc, s2, v132
	v_cvt_pk_bf16_f32 v128, v116, v117
	v_cvt_pk_bf16_f32 v129, v118, v119
	v_cvt_pk_bf16_f32 v130, v112, v113
	v_cvt_pk_bf16_f32 v131, v114, v115
	global_store_dwordx4 v[132:133], v[128:131], off offset:256
	v_addc_co_u32_e32 v137, vcc, 0, v133, vcc
	s_nop 0
	v_or_b32_e32 v128, 16, v172
	v_ashrrev_i32_e32 v129, 31, v128
	v_lshlrev_b64 v[128:129], 11, v[128:129]
	v_lshl_add_u64 v[128:129], s[8:9], 0, v[128:129]
	v_lshl_add_u64 v[128:129], v[128:129], 0, s[10:11]
	v_lshl_add_u64 v[134:135], v[128:129], 0, v[152:153]
	v_cvt_pk_bf16_f32 v128, v108, v109
	v_cvt_pk_bf16_f32 v129, v110, v111
	v_cvt_pk_bf16_f32 v130, v104, v105
	v_cvt_pk_bf16_f32 v131, v106, v107
	global_store_dwordx4 v[134:135], v[128:131], off
	s_mov_b32 s2, 0x48000
	s_nop 0
	v_cvt_pk_bf16_f32 v128, v100, v101
	v_cvt_pk_bf16_f32 v129, v102, v103
	v_cvt_pk_bf16_f32 v130, v96, v97
	v_cvt_pk_bf16_f32 v131, v98, v99
	global_store_dwordx4 v[134:135], v[128:131], off offset:256
	s_nop 1
	v_or_b32_e32 v128, 32, v172
	v_ashrrev_i32_e32 v129, 31, v128
	v_lshlrev_b64 v[128:129], 11, v[128:129]
	v_lshl_add_u64 v[128:129], s[8:9], 0, v[128:129]
	v_lshl_add_u64 v[128:129], v[128:129], 0, s[10:11]
	v_lshl_add_u64 v[134:135], v[128:129], 0, v[152:153]
	v_cvt_pk_bf16_f32 v128, v92, v93
	v_cvt_pk_bf16_f32 v129, v94, v95
	v_cvt_pk_bf16_f32 v130, v88, v89
	v_cvt_pk_bf16_f32 v131, v90, v91
	global_store_dwordx4 v[134:135], v[128:131], off
	s_nop 1
	v_cvt_pk_bf16_f32 v128, v84, v85
	v_cvt_pk_bf16_f32 v129, v86, v87
	v_cvt_pk_bf16_f32 v130, v80, v81
	v_cvt_pk_bf16_f32 v131, v82, v83
	global_store_dwordx4 v[134:135], v[128:131], off offset:256
	s_nop 1
	v_or_b32_e32 v128, 48, v172
	v_ashrrev_i32_e32 v129, 31, v128
	v_lshlrev_b64 v[128:129], 11, v[128:129]
	v_lshl_add_u64 v[128:129], s[8:9], 0, v[128:129]
	v_lshl_add_u64 v[128:129], v[128:129], 0, s[10:11]
	v_lshl_add_u64 v[134:135], v[128:129], 0, v[152:153]
	v_cvt_pk_bf16_f32 v128, v76, v77
	v_cvt_pk_bf16_f32 v129, v78, v79
	v_cvt_pk_bf16_f32 v130, v72, v73
	v_cvt_pk_bf16_f32 v131, v74, v75
	global_store_dwordx4 v[134:135], v[128:131], off
	s_mov_b64 s[8:9], 0x40000
	s_nop 0
	v_cvt_pk_bf16_f32 v128, v68, v69
	v_cvt_pk_bf16_f32 v129, v70, v71
	v_cvt_pk_bf16_f32 v130, v64, v65
	v_cvt_pk_bf16_f32 v131, v66, v67
	global_store_dwordx4 v[134:135], v[128:131], off offset:256
	v_lshl_add_u64 v[134:135], v[132:133], 0, s[8:9]
	s_mov_b64 s[8:9], 0x48000
	v_cvt_pk_bf16_f32 v128, v60, v61
	v_cvt_pk_bf16_f32 v129, v62, v63
	v_cvt_pk_bf16_f32 v130, v56, v57
	v_cvt_pk_bf16_f32 v131, v58, v59
	global_store_dwordx4 v[136:137], v[128:131], off
	v_add_co_u32_e32 v136, vcc, s2, v132
	s_nop 0
	v_cvt_pk_bf16_f32 v128, v52, v53
	v_cvt_pk_bf16_f32 v129, v54, v55
	v_cvt_pk_bf16_f32 v130, v48, v49
	v_cvt_pk_bf16_f32 v131, v50, v51
	global_store_dwordx4 v[134:135], v[128:131], off offset:256
	v_addc_co_u32_e32 v137, vcc, 0, v133, vcc
	s_nop 0
	v_cvt_pk_bf16_f32 v128, v44, v45
	v_cvt_pk_bf16_f32 v129, v46, v47
	v_cvt_pk_bf16_f32 v130, v40, v41
	v_cvt_pk_bf16_f32 v131, v42, v43
	s_mov_b32 s2, 0x50000
	v_lshl_add_u64 v[134:135], v[132:133], 0, s[8:9]
	global_store_dwordx4 v[136:137], v[128:131], off
	v_add_co_u32_e32 v136, vcc, s2, v132
	s_nop 0
	v_cvt_pk_bf16_f32 v128, v36, v37
	v_cvt_pk_bf16_f32 v129, v38, v39
	v_cvt_pk_bf16_f32 v130, v32, v33
	v_cvt_pk_bf16_f32 v131, v34, v35
	global_store_dwordx4 v[134:135], v[128:131], off offset:256
	s_mov_b64 s[8:9], 0x50000
	v_addc_co_u32_e32 v137, vcc, 0, v133, vcc
	v_cvt_pk_bf16_f32 v128, v28, v29
	v_cvt_pk_bf16_f32 v129, v30, v31
	v_cvt_pk_bf16_f32 v130, v24, v25
	v_cvt_pk_bf16_f32 v131, v26, v27
	v_lshl_add_u64 v[134:135], v[132:133], 0, s[8:9]
	global_store_dwordx4 v[136:137], v[128:131], off
	s_mov_b64 s[8:9], 0x58000
	s_mov_b32 s2, 0x58000
	v_cvt_pk_bf16_f32 v128, v20, v21
	v_cvt_pk_bf16_f32 v129, v22, v23
	v_cvt_pk_bf16_f32 v130, v16, v17
	v_cvt_pk_bf16_f32 v131, v18, v19
	global_store_dwordx4 v[134:135], v[128:131], off offset:256
	v_lshl_add_u64 v[134:135], v[132:133], 0, s[8:9]
	v_add_co_u32_e32 v132, vcc, s2, v132
	v_cvt_pk_bf16_f32 v128, v12, v13
	v_cvt_pk_bf16_f32 v129, v14, v15
	v_cvt_pk_bf16_f32 v130, v8, v9
	v_cvt_pk_bf16_f32 v131, v10, v11
	v_addc_co_u32_e32 v133, vcc, 0, v133, vcc
	global_store_dwordx4 v[132:133], v[128:131], off
	s_nop 1
	v_cvt_pk_bf16_f32 v128, v4, v5
	v_cvt_pk_bf16_f32 v129, v6, v7
	v_cvt_pk_bf16_f32 v130, v0, v1
	v_cvt_pk_bf16_f32 v131, v2, v3
	global_store_dwordx4 v[134:135], v[128:131], off offset:256

.LBB0_1136:
	s_andn2_b64 vcc, exec, s[8:9]
	s_cbranch_vccnz .LBB0_535
	s_cmp_eq_u32 s93, 0
	s_cbranch_scc0 .LBB0_535
	v_mul_f32_e32 v132, 0xbfb8aa3b, v124
	v_mul_f32_e32 v133, 0xbfb8aa3b, v125
	v_exp_f32_e32 v132, v132
	v_exp_f32_e32 v133, v133
	v_mov_b64_e32 v[128:129], s[58:59]
	s_movk_i32 s2, 0x1600
	v_add_f32_e32 v132, 1.0, v132
	v_add_f32_e32 v133, 1.0, v133
	v_rcp_f32_e32 v132, v132
	v_rcp_f32_e32 v133, v133
	v_mad_i64_i32 v[130:131], s[8:9], v172, s2, v[128:129]
	s_lshl_b32 s8, s14, 7
	v_pk_mul_f32 v[124:125], v[124:125], v[132:133]
	v_mul_f32_e32 v132, 0xbfb8aa3b, v126
	v_mul_f32_e32 v133, 0xbfb8aa3b, v127
	v_exp_f32_e32 v132, v132
	v_exp_f32_e32 v133, v133
	v_pk_mul_f32 v[116:117], v[124:125], v[116:117]
	s_ashr_i32 s9, s8, 31
	v_add_f32_e32 v124, 1.0, v132
	v_add_f32_e32 v125, 1.0, v133
	v_mul_f32_e32 v132, 0xbfb8aa3b, v120
	v_mul_f32_e32 v133, 0xbfb8aa3b, v121
	v_rcp_f32_e32 v124, v124
	v_rcp_f32_e32 v125, v125
	v_exp_f32_e32 v132, v132
	v_exp_f32_e32 v133, v133
	s_lshl_b64 s[8:9], s[8:9], 1
	v_pk_mul_f32 v[124:125], v[126:127], v[124:125]
	v_add_f32_e32 v126, 1.0, v132
	v_add_f32_e32 v127, 1.0, v133
	v_mul_f32_e32 v132, 0xbfb8aa3b, v122
	v_mul_f32_e32 v133, 0xbfb8aa3b, v123
	v_exp_f32_e32 v132, v132
	v_exp_f32_e32 v133, v133
	v_rcp_f32_e32 v126, v126
	v_rcp_f32_e32 v127, v127
	v_add_f32_e32 v132, 1.0, v132
	v_add_f32_e32 v133, 1.0, v133
	v_rcp_f32_e32 v132, v132
	v_rcp_f32_e32 v133, v133
	v_pk_mul_f32 v[120:121], v[120:121], v[126:127]
	v_lshl_add_u64 v[130:131], v[130:131], 0, s[8:9]
	v_pk_mul_f32 v[120:121], v[120:121], v[112:113]
	v_pk_mul_f32 v[112:113], v[122:123], v[132:133]
	v_pk_mul_f32 v[118:119], v[124:125], v[118:119]
	v_pk_mul_f32 v[122:123], v[112:113], v[114:115]
	v_lshlrev_b32_e32 v152, 1, v186
	v_lshl_add_u64 v[124:125], v[130:131], 0, v[152:153]
	v_cvt_pk_bf16_f32 v112, v116, v117
	v_cvt_pk_bf16_f32 v113, v118, v119
	v_cvt_pk_bf16_f32 v114, v120, v121
	v_cvt_pk_bf16_f32 v115, v122, v123
	global_store_dwordx4 v[124:125], v[112:115], off
	s_nop 1
	v_mul_f32_e32 v112, 0xbfb8aa3b, v108
	v_mul_f32_e32 v113, 0xbfb8aa3b, v109
	v_exp_f32_e32 v112, v112
	v_exp_f32_e32 v113, v113
	v_or_b32_e32 v114, 16, v172
	v_mad_i64_i32 v[114:115], s[10:11], v114, s2, v[128:129]
	v_add_f32_e32 v112, 1.0, v112
	v_add_f32_e32 v113, 1.0, v113
	v_rcp_f32_e32 v112, v112
	v_rcp_f32_e32 v113, v113
	v_lshl_add_u64 v[114:115], v[114:115], 0, s[8:9]
	v_pk_mul_f32 v[108:109], v[108:109], v[112:113]
	v_mul_f32_e32 v112, 0xbfb8aa3b, v110
	v_mul_f32_e32 v113, 0xbfb8aa3b, v111
	v_exp_f32_e32 v112, v112
	v_exp_f32_e32 v113, v113
	v_pk_mul_f32 v[100:101], v[108:109], v[100:101]
	v_add_f32_e32 v108, 1.0, v112
	v_add_f32_e32 v109, 1.0, v113
	v_mul_f32_e32 v112, 0xbfb8aa3b, v104
	v_mul_f32_e32 v113, 0xbfb8aa3b, v105
	v_rcp_f32_e32 v108, v108
	v_rcp_f32_e32 v109, v109
	v_exp_f32_e32 v112, v112
	v_exp_f32_e32 v113, v113
	v_pk_mul_f32 v[108:109], v[110:111], v[108:109]
	v_add_f32_e32 v110, 1.0, v112
	v_add_f32_e32 v111, 1.0, v113
	v_mul_f32_e32 v112, 0xbfb8aa3b, v106
	v_mul_f32_e32 v113, 0xbfb8aa3b, v107
	v_exp_f32_e32 v112, v112
	v_exp_f32_e32 v113, v113
	v_rcp_f32_e32 v110, v110
	v_rcp_f32_e32 v111, v111
	v_add_f32_e32 v112, 1.0, v112
	v_add_f32_e32 v113, 1.0, v113
	v_rcp_f32_e32 v112, v112
	v_rcp_f32_e32 v113, v113
	v_pk_mul_f32 v[104:105], v[104:105], v[110:111]
	v_pk_mul_f32 v[102:103], v[108:109], v[102:103]
	v_pk_mul_f32 v[104:105], v[104:105], v[96:97]
	v_pk_mul_f32 v[96:97], v[106:107], v[112:113]
	v_lshl_add_u64 v[108:109], v[114:115], 0, v[152:153]
	v_pk_mul_f32 v[106:107], v[96:97], v[98:99]
	v_cvt_pk_bf16_f32 v96, v100, v101
	v_cvt_pk_bf16_f32 v97, v102, v103
	v_cvt_pk_bf16_f32 v98, v104, v105
	v_cvt_pk_bf16_f32 v99, v106, v107
	global_store_dwordx4 v[108:109], v[96:99], off
	s_nop 1
	v_mul_f32_e32 v96, 0xbfb8aa3b, v92
	v_mul_f32_e32 v97, 0xbfb8aa3b, v93
	v_exp_f32_e32 v96, v96
	v_exp_f32_e32 v97, v97
	v_or_b32_e32 v98, 32, v172
	v_mad_i64_i32 v[98:99], s[10:11], v98, s2, v[128:129]
	v_add_f32_e32 v96, 1.0, v96
	v_add_f32_e32 v97, 1.0, v97
	v_rcp_f32_e32 v96, v96
	v_rcp_f32_e32 v97, v97
	v_lshl_add_u64 v[98:99], v[98:99], 0, s[8:9]
	v_pk_mul_f32 v[92:93], v[92:93], v[96:97]
	v_mul_f32_e32 v96, 0xbfb8aa3b, v94
	v_mul_f32_e32 v97, 0xbfb8aa3b, v95
	v_exp_f32_e32 v96, v96
	v_exp_f32_e32 v97, v97
	v_pk_mul_f32 v[84:85], v[92:93], v[84:85]
	v_add_f32_e32 v92, 1.0, v96
	v_add_f32_e32 v93, 1.0, v97
	v_mul_f32_e32 v96, 0xbfb8aa3b, v88
	v_mul_f32_e32 v97, 0xbfb8aa3b, v89
	v_rcp_f32_e32 v92, v92
	v_rcp_f32_e32 v93, v93
	v_exp_f32_e32 v96, v96
	v_exp_f32_e32 v97, v97
	v_pk_mul_f32 v[92:93], v[94:95], v[92:93]
	v_add_f32_e32 v94, 1.0, v96
	v_add_f32_e32 v95, 1.0, v97
	v_mul_f32_e32 v96, 0xbfb8aa3b, v90
	v_mul_f32_e32 v97, 0xbfb8aa3b, v91
	v_exp_f32_e32 v96, v96
	v_exp_f32_e32 v97, v97
	v_rcp_f32_e32 v94, v94
	v_rcp_f32_e32 v95, v95
	v_add_f32_e32 v96, 1.0, v96
	v_add_f32_e32 v97, 1.0, v97
	v_rcp_f32_e32 v96, v96
	v_rcp_f32_e32 v97, v97
	v_pk_mul_f32 v[88:89], v[88:89], v[94:95]
	v_pk_mul_f32 v[86:87], v[92:93], v[86:87]
	v_pk_mul_f32 v[88:89], v[88:89], v[80:81]
	v_pk_mul_f32 v[80:81], v[90:91], v[96:97]
	v_lshl_add_u64 v[92:93], v[98:99], 0, v[152:153]
	v_pk_mul_f32 v[90:91], v[80:81], v[82:83]
	v_cvt_pk_bf16_f32 v80, v84, v85
	v_cvt_pk_bf16_f32 v81, v86, v87
	v_cvt_pk_bf16_f32 v82, v88, v89
	v_cvt_pk_bf16_f32 v83, v90, v91
	global_store_dwordx4 v[92:93], v[80:83], off
	s_nop 1
	v_mul_f32_e32 v80, 0xbfb8aa3b, v76
	v_mul_f32_e32 v81, 0xbfb8aa3b, v77
	v_exp_f32_e32 v80, v80
	v_exp_f32_e32 v81, v81
	v_or_b32_e32 v82, 48, v172
	v_mad_i64_i32 v[82:83], s[10:11], v82, s2, v[128:129]
	v_add_f32_e32 v80, 1.0, v80
	v_add_f32_e32 v81, 1.0, v81
	v_rcp_f32_e32 v80, v80
	v_rcp_f32_e32 v81, v81
	v_lshl_add_u64 v[82:83], v[82:83], 0, s[8:9]
	v_pk_mul_f32 v[76:77], v[76:77], v[80:81]
	v_mul_f32_e32 v80, 0xbfb8aa3b, v78
	v_mul_f32_e32 v81, 0xbfb8aa3b, v79
	v_exp_f32_e32 v80, v80
	v_exp_f32_e32 v81, v81
	v_pk_mul_f32 v[68:69], v[76:77], v[68:69]
	v_add_f32_e32 v76, 1.0, v80
	v_add_f32_e32 v77, 1.0, v81
	v_mul_f32_e32 v80, 0xbfb8aa3b, v72
	v_mul_f32_e32 v81, 0xbfb8aa3b, v73
	v_rcp_f32_e32 v76, v76
	v_rcp_f32_e32 v77, v77
	v_exp_f32_e32 v80, v80
	v_exp_f32_e32 v81, v81
	v_pk_mul_f32 v[76:77], v[78:79], v[76:77]
	v_add_f32_e32 v78, 1.0, v80
	v_add_f32_e32 v79, 1.0, v81
	v_mul_f32_e32 v80, 0xbfb8aa3b, v74
	v_mul_f32_e32 v81, 0xbfb8aa3b, v75
	v_exp_f32_e32 v80, v80
	v_exp_f32_e32 v81, v81
	v_rcp_f32_e32 v78, v78
	v_rcp_f32_e32 v79, v79
	v_add_f32_e32 v80, 1.0, v80
	v_add_f32_e32 v81, 1.0, v81
	v_rcp_f32_e32 v80, v80
	v_rcp_f32_e32 v81, v81
	v_pk_mul_f32 v[72:73], v[72:73], v[78:79]
	v_pk_mul_f32 v[70:71], v[76:77], v[70:71]
	v_pk_mul_f32 v[72:73], v[72:73], v[64:65]
	v_pk_mul_f32 v[64:65], v[74:75], v[80:81]
	v_lshl_add_u64 v[76:77], v[82:83], 0, v[152:153]
	v_pk_mul_f32 v[74:75], v[64:65], v[66:67]
	v_cvt_pk_bf16_f32 v64, v68, v69
	v_cvt_pk_bf16_f32 v65, v70, v71
	v_cvt_pk_bf16_f32 v66, v72, v73
	v_cvt_pk_bf16_f32 v67, v74, v75
	global_store_dwordx4 v[76:77], v[64:67], off
	s_nop 1
	v_mul_f32_e32 v64, 0xbfb8aa3b, v60
	v_mul_f32_e32 v65, 0xbfb8aa3b, v61
	v_exp_f32_e32 v64, v64
	v_exp_f32_e32 v65, v65
	v_add_u32_e32 v66, 0x80, v172
	v_mad_i64_i32 v[66:67], s[10:11], v66, s2, v[128:129]
	v_add_f32_e32 v64, 1.0, v64
	v_add_f32_e32 v65, 1.0, v65
	v_rcp_f32_e32 v64, v64
	v_rcp_f32_e32 v65, v65
	v_lshl_add_u64 v[66:67], v[66:67], 0, s[8:9]
	v_pk_mul_f32 v[60:61], v[60:61], v[64:65]
	v_mul_f32_e32 v64, 0xbfb8aa3b, v62
	v_mul_f32_e32 v65, 0xbfb8aa3b, v63
	v_exp_f32_e32 v64, v64
	v_exp_f32_e32 v65, v65
	v_pk_mul_f32 v[52:53], v[60:61], v[52:53]
	v_add_f32_e32 v60, 1.0, v64
	v_add_f32_e32 v61, 1.0, v65
	v_mul_f32_e32 v64, 0xbfb8aa3b, v56
	v_mul_f32_e32 v65, 0xbfb8aa3b, v57
	v_rcp_f32_e32 v60, v60
	v_rcp_f32_e32 v61, v61
	v_exp_f32_e32 v64, v64
	v_exp_f32_e32 v65, v65
	v_pk_mul_f32 v[60:61], v[62:63], v[60:61]
	v_add_f32_e32 v62, 1.0, v64
	v_add_f32_e32 v63, 1.0, v65
	v_mul_f32_e32 v64, 0xbfb8aa3b, v58
	v_mul_f32_e32 v65, 0xbfb8aa3b, v59
	v_exp_f32_e32 v64, v64
	v_exp_f32_e32 v65, v65
	v_rcp_f32_e32 v62, v62
	v_rcp_f32_e32 v63, v63
	v_add_f32_e32 v64, 1.0, v64
	v_add_f32_e32 v65, 1.0, v65
	v_rcp_f32_e32 v64, v64
	v_rcp_f32_e32 v65, v65
	v_pk_mul_f32 v[56:57], v[56:57], v[62:63]
	v_pk_mul_f32 v[54:55], v[60:61], v[54:55]
	v_pk_mul_f32 v[56:57], v[56:57], v[48:49]
	v_pk_mul_f32 v[48:49], v[58:59], v[64:65]
	v_lshl_add_u64 v[60:61], v[66:67], 0, v[152:153]
	v_pk_mul_f32 v[58:59], v[48:49], v[50:51]
	v_cvt_pk_bf16_f32 v48, v52, v53
	v_cvt_pk_bf16_f32 v49, v54, v55
	v_cvt_pk_bf16_f32 v50, v56, v57
	v_cvt_pk_bf16_f32 v51, v58, v59
	global_store_dwordx4 v[60:61], v[48:51], off
	s_nop 1
	v_mul_f32_e32 v48, 0xbfb8aa3b, v44
	v_mul_f32_e32 v49, 0xbfb8aa3b, v45
	v_exp_f32_e32 v48, v48
	v_exp_f32_e32 v49, v49
	v_add_u32_e32 v50, 0x90, v172
	v_mad_i64_i32 v[50:51], s[10:11], v50, s2, v[128:129]
	v_add_f32_e32 v48, 1.0, v48
	v_add_f32_e32 v49, 1.0, v49
	v_rcp_f32_e32 v48, v48
	v_rcp_f32_e32 v49, v49
	v_lshl_add_u64 v[50:51], v[50:51], 0, s[8:9]
	v_pk_mul_f32 v[44:45], v[44:45], v[48:49]
	v_mul_f32_e32 v48, 0xbfb8aa3b, v46
	v_mul_f32_e32 v49, 0xbfb8aa3b, v47
	v_exp_f32_e32 v48, v48
	v_exp_f32_e32 v49, v49
	v_pk_mul_f32 v[36:37], v[44:45], v[36:37]
	v_add_f32_e32 v44, 1.0, v48
	v_add_f32_e32 v45, 1.0, v49
	v_mul_f32_e32 v48, 0xbfb8aa3b, v40
	v_mul_f32_e32 v49, 0xbfb8aa3b, v41
	v_rcp_f32_e32 v44, v44
	v_rcp_f32_e32 v45, v45
	v_exp_f32_e32 v48, v48
	v_exp_f32_e32 v49, v49
	v_pk_mul_f32 v[44:45], v[46:47], v[44:45]
	v_add_f32_e32 v46, 1.0, v48
	v_add_f32_e32 v47, 1.0, v49
	v_mul_f32_e32 v48, 0xbfb8aa3b, v42
	v_mul_f32_e32 v49, 0xbfb8aa3b, v43
	v_exp_f32_e32 v48, v48
	v_exp_f32_e32 v49, v49
	v_rcp_f32_e32 v46, v46
	v_rcp_f32_e32 v47, v47
	v_add_f32_e32 v48, 1.0, v48
	v_add_f32_e32 v49, 1.0, v49
	v_rcp_f32_e32 v48, v48
	v_rcp_f32_e32 v49, v49
	v_pk_mul_f32 v[40:41], v[40:41], v[46:47]
	v_pk_mul_f32 v[38:39], v[44:45], v[38:39]
	v_pk_mul_f32 v[40:41], v[40:41], v[32:33]
	v_pk_mul_f32 v[32:33], v[42:43], v[48:49]
	v_lshl_add_u64 v[44:45], v[50:51], 0, v[152:153]
	v_pk_mul_f32 v[42:43], v[32:33], v[34:35]
	v_cvt_pk_bf16_f32 v32, v36, v37
	v_cvt_pk_bf16_f32 v33, v38, v39
	v_cvt_pk_bf16_f32 v34, v40, v41
	v_cvt_pk_bf16_f32 v35, v42, v43
	global_store_dwordx4 v[44:45], v[32:35], off
	s_nop 1
	v_mul_f32_e32 v32, 0xbfb8aa3b, v28
	v_mul_f32_e32 v33, 0xbfb8aa3b, v29
	v_exp_f32_e32 v32, v32
	v_exp_f32_e32 v33, v33
	v_add_u32_e32 v34, 0xa0, v172
	v_mad_i64_i32 v[34:35], s[10:11], v34, s2, v[128:129]
	v_add_f32_e32 v32, 1.0, v32
	v_add_f32_e32 v33, 1.0, v33
	v_rcp_f32_e32 v32, v32
	v_rcp_f32_e32 v33, v33
	v_lshl_add_u64 v[34:35], v[34:35], 0, s[8:9]
	v_pk_mul_f32 v[28:29], v[28:29], v[32:33]
	v_mul_f32_e32 v32, 0xbfb8aa3b, v30
	v_mul_f32_e32 v33, 0xbfb8aa3b, v31
	v_exp_f32_e32 v32, v32
	v_exp_f32_e32 v33, v33
	v_pk_mul_f32 v[20:21], v[28:29], v[20:21]
	v_add_f32_e32 v28, 1.0, v32
	v_add_f32_e32 v29, 1.0, v33
	v_mul_f32_e32 v32, 0xbfb8aa3b, v24
	v_mul_f32_e32 v33, 0xbfb8aa3b, v25
	v_rcp_f32_e32 v28, v28
	v_rcp_f32_e32 v29, v29
	v_exp_f32_e32 v32, v32
	v_exp_f32_e32 v33, v33
	v_pk_mul_f32 v[28:29], v[30:31], v[28:29]
	v_add_f32_e32 v30, 1.0, v32
	v_add_f32_e32 v31, 1.0, v33
	v_mul_f32_e32 v32, 0xbfb8aa3b, v26
	v_mul_f32_e32 v33, 0xbfb8aa3b, v27
	v_exp_f32_e32 v32, v32
	v_exp_f32_e32 v33, v33
	v_rcp_f32_e32 v30, v30
	v_rcp_f32_e32 v31, v31
	v_add_f32_e32 v32, 1.0, v32
	v_add_f32_e32 v33, 1.0, v33
	v_rcp_f32_e32 v32, v32
	v_rcp_f32_e32 v33, v33
	v_pk_mul_f32 v[24:25], v[24:25], v[30:31]
	v_pk_mul_f32 v[22:23], v[28:29], v[22:23]
	v_pk_mul_f32 v[24:25], v[24:25], v[16:17]
	v_pk_mul_f32 v[16:17], v[26:27], v[32:33]
	v_lshl_add_u64 v[28:29], v[34:35], 0, v[152:153]
	v_pk_mul_f32 v[26:27], v[16:17], v[18:19]
	v_cvt_pk_bf16_f32 v16, v20, v21
	v_cvt_pk_bf16_f32 v17, v22, v23
	v_cvt_pk_bf16_f32 v18, v24, v25
	v_cvt_pk_bf16_f32 v19, v26, v27
	global_store_dwordx4 v[28:29], v[16:19], off
	s_nop 1
	v_mul_f32_e32 v16, 0xbfb8aa3b, v12
	v_mul_f32_e32 v17, 0xbfb8aa3b, v13
	v_exp_f32_e32 v16, v16
	v_exp_f32_e32 v17, v17
	v_add_u32_e32 v18, 0xb0, v172
	v_mad_i64_i32 v[18:19], s[10:11], v18, s2, v[128:129]
	v_add_f32_e32 v16, 1.0, v16
	v_add_f32_e32 v17, 1.0, v17
	v_rcp_f32_e32 v16, v16
	v_rcp_f32_e32 v17, v17
	v_lshl_add_u64 v[18:19], v[18:19], 0, s[8:9]
	v_pk_mul_f32 v[12:13], v[12:13], v[16:17]
	v_mul_f32_e32 v16, 0xbfb8aa3b, v14
	v_mul_f32_e32 v17, 0xbfb8aa3b, v15
	v_exp_f32_e32 v16, v16
	v_exp_f32_e32 v17, v17
	v_pk_mul_f32 v[4:5], v[12:13], v[4:5]
	v_add_f32_e32 v12, 1.0, v16
	v_add_f32_e32 v13, 1.0, v17
	v_mul_f32_e32 v16, 0xbfb8aa3b, v8
	v_mul_f32_e32 v17, 0xbfb8aa3b, v9
	v_rcp_f32_e32 v12, v12
	v_rcp_f32_e32 v13, v13
	v_exp_f32_e32 v16, v16
	v_exp_f32_e32 v17, v17
	v_pk_mul_f32 v[12:13], v[14:15], v[12:13]
	v_add_f32_e32 v14, 1.0, v16
	v_add_f32_e32 v15, 1.0, v17
	v_mul_f32_e32 v16, 0xbfb8aa3b, v10
	v_mul_f32_e32 v17, 0xbfb8aa3b, v11
	v_exp_f32_e32 v16, v16
	v_exp_f32_e32 v17, v17
	v_rcp_f32_e32 v14, v14
	v_rcp_f32_e32 v15, v15
	v_add_f32_e32 v16, 1.0, v16
	v_add_f32_e32 v17, 1.0, v17
	v_rcp_f32_e32 v16, v16
	v_rcp_f32_e32 v17, v17
	v_pk_mul_f32 v[8:9], v[8:9], v[14:15]
	v_pk_mul_f32 v[6:7], v[12:13], v[6:7]
	v_pk_mul_f32 v[8:9], v[8:9], v[0:1]
	v_pk_mul_f32 v[0:1], v[10:11], v[16:17]
	v_lshl_add_u64 v[12:13], v[18:19], 0, v[152:153]
	v_pk_mul_f32 v[10:11], v[0:1], v[2:3]
	v_cvt_pk_bf16_f32 v0, v4, v5
	v_cvt_pk_bf16_f32 v1, v6, v7
	v_cvt_pk_bf16_f32 v2, v8, v9
	v_cvt_pk_bf16_f32 v3, v10, v11
	global_store_dwordx4 v[12:13], v[0:3], off
	s_branch .LBB0_535

.LBB0_1493:
	v_lshl_add_u64 v[36:37], v[26:27], 0, s[12:13]
	v_add_co_u32_e64 v38, s[8:9], s7, v36
	s_mov_b32 s5, 0x12000
	s_nop 0
	v_addc_co_u32_e64 v39, s[8:9], 0, v37, s[8:9]
	v_add_co_u32_e64 v40, s[8:9], s5, v36
	global_load_dwordx4 v[32:35], v[36:37], off
	s_nop 0
	v_addc_co_u32_e64 v41, s[8:9], 0, v37, s[8:9]
	s_mov_b32 s5, 0x1b000
	v_add_co_u32_e64 v44, s[8:9], s5, v36
	s_add_u32 s12, s12, 0x24000
	s_nop 0
	v_addc_co_u32_e64 v45, s[8:9], 0, v37, s[8:9]
	global_load_dwordx4 v[36:39], v[38:39], off
	s_nop 0
	global_load_dwordx4 v[40:43], v[40:41], off
	s_nop 0
	global_load_dwordx4 v[44:47], v[44:45], off
	ds_read_b128 v[48:51], v25
	ds_read_b128 v[52:55], v25 offset:4096
	ds_read_b128 v[56:59], v25 offset:8192
	ds_read_b128 v[60:63], v25 offset:12288
	ds_read_b128 v[64:67], v25 offset:16384
	s_addc_u32 s13, s13, 0
	s_waitcnt lgkmcnt(0)
	v_mov_b32_e32 v68, v51
	s_waitcnt lgkmcnt(3)
	v_mov_b32_e32 v70, v55
	s_waitcnt lgkmcnt(2)
	v_mov_b32_e32 v72, v59
	s_waitcnt lgkmcnt(1)
	v_mov_b32_e32 v74, v63
	s_waitcnt lgkmcnt(0)
	v_mov_b32_e32 v76, v67
	v_add_u32_e32 v25, 16, v25
	s_cmp_eq_u32 s12, 0x120000
	s_waitcnt vmcnt(0)
	v_pk_fma_f32 v[6:7], v[34:35], v[48:49], v[6:7] op_sel_hi:[1,0,1]
	v_pk_fma_f32 v[4:5], v[32:33], v[48:49], v[4:5] op_sel_hi:[1,0,1]
	v_pk_fma_f32 v[10:11], v[34:35], v[52:53], v[10:11] op_sel_hi:[1,0,1]
	v_pk_fma_f32 v[8:9], v[32:33], v[52:53], v[8:9] op_sel_hi:[1,0,1]
	v_pk_fma_f32 v[14:15], v[34:35], v[56:57], v[14:15] op_sel_hi:[1,0,1]
	v_pk_fma_f32 v[12:13], v[32:33], v[56:57], v[12:13] op_sel_hi:[1,0,1]
	v_pk_fma_f32 v[18:19], v[34:35], v[60:61], v[18:19] op_sel_hi:[1,0,1]
	v_pk_fma_f32 v[16:17], v[32:33], v[60:61], v[16:17] op_sel_hi:[1,0,1]
	v_pk_fma_f32 v[2:3], v[34:35], v[64:65], v[2:3] op_sel_hi:[1,0,1]
	v_pk_fma_f32 v[0:1], v[32:33], v[64:65], v[0:1] op_sel_hi:[1,0,1]
	s_waitcnt vmcnt(2)
	v_pk_fma_f32 v[4:5], v[36:37], v[48:49], v[4:5] op_sel:[0,1,0]
	v_pk_fma_f32 v[6:7], v[38:39], v[48:49], v[6:7] op_sel:[0,1,0]
	v_pk_fma_f32 v[8:9], v[36:37], v[52:53], v[8:9] op_sel:[0,1,0]
	v_pk_fma_f32 v[10:11], v[38:39], v[52:53], v[10:11] op_sel:[0,1,0]
	v_pk_fma_f32 v[12:13], v[36:37], v[56:57], v[12:13] op_sel:[0,1,0]
	v_pk_fma_f32 v[14:15], v[38:39], v[56:57], v[14:15] op_sel:[0,1,0]
	v_pk_fma_f32 v[16:17], v[36:37], v[60:61], v[16:17] op_sel:[0,1,0]
	v_pk_fma_f32 v[18:19], v[38:39], v[60:61], v[18:19] op_sel:[0,1,0]
	v_pk_fma_f32 v[0:1], v[36:37], v[64:65], v[0:1] op_sel:[0,1,0]
	v_pk_fma_f32 v[2:3], v[38:39], v[64:65], v[2:3] op_sel:[0,1,0]
	s_waitcnt vmcnt(1)
	v_pk_fma_f32 v[6:7], v[42:43], v[50:51], v[6:7] op_sel_hi:[1,0,1]
	v_pk_fma_f32 v[4:5], v[40:41], v[50:51], v[4:5] op_sel_hi:[1,0,1]
	v_pk_fma_f32 v[10:11], v[42:43], v[54:55], v[10:11] op_sel_hi:[1,0,1]
	v_pk_fma_f32 v[8:9], v[40:41], v[54:55], v[8:9] op_sel_hi:[1,0,1]
	v_pk_fma_f32 v[14:15], v[42:43], v[58:59], v[14:15] op_sel_hi:[1,0,1]
	v_pk_fma_f32 v[12:13], v[40:41], v[58:59], v[12:13] op_sel_hi:[1,0,1]
	v_pk_fma_f32 v[18:19], v[42:43], v[62:63], v[18:19] op_sel_hi:[1,0,1]
	v_pk_fma_f32 v[16:17], v[40:41], v[62:63], v[16:17] op_sel_hi:[1,0,1]
	v_pk_fma_f32 v[2:3], v[42:43], v[66:67], v[2:3] op_sel_hi:[1,0,1]
	v_pk_fma_f32 v[0:1], v[40:41], v[66:67], v[0:1] op_sel_hi:[1,0,1]
	s_waitcnt vmcnt(0)
	v_pk_fma_f32 v[6:7], v[46:47], v[68:69], v[6:7] op_sel_hi:[1,0,1]
	v_pk_fma_f32 v[4:5], v[44:45], v[68:69], v[4:5] op_sel_hi:[1,0,1]
	v_pk_fma_f32 v[10:11], v[46:47], v[70:71], v[10:11] op_sel_hi:[1,0,1]
	v_pk_fma_f32 v[8:9], v[44:45], v[70:71], v[8:9] op_sel_hi:[1,0,1]
	v_pk_fma_f32 v[14:15], v[46:47], v[72:73], v[14:15] op_sel_hi:[1,0,1]
	v_pk_fma_f32 v[12:13], v[44:45], v[72:73], v[12:13] op_sel_hi:[1,0,1]
	v_pk_fma_f32 v[18:19], v[46:47], v[74:75], v[18:19] op_sel_hi:[1,0,1]
	v_pk_fma_f32 v[16:17], v[44:45], v[74:75], v[16:17] op_sel_hi:[1,0,1]
	v_pk_fma_f32 v[2:3], v[46:47], v[76:77], v[2:3] op_sel_hi:[1,0,1]
	v_pk_fma_f32 v[0:1], v[44:45], v[76:77], v[0:1] op_sel_hi:[1,0,1]
	s_cbranch_scc0 .LBB0_1493
	ds_write_b128 v29, v[4:7] offset:20480
	ds_write_b128 v29, v[8:11] offset:20736
	ds_write_b128 v29, v[12:15] offset:20992
	ds_write_b128 v29, v[16:19] offset:21248
	ds_write_b128 v29, v[0:3] offset:21504
	s_waitcnt lgkmcnt(0)
	s_barrier
	s_and_saveexec_b64 s[8:9], vcc
	s_cbranch_execz .LBB0_1491
	s_load_dwordx8 s[16:23], s[0:1], 0x30
	s_mul_i32 s12, s4, 0x9000
	s_mul_hi_i32 s5, s4, 0x9000
	v_mov_b64_e32 v[44:45], s[60:61]
	v_mov_b32_e32 v25, v153
	s_waitcnt lgkmcnt(0)
	s_add_u32 s12, s22, s12
	s_addc_u32 s5, s23, s5
	s_lshl_b64 s[10:11], s[10:11], 2
	s_add_u32 s12, s12, s10
	s_addc_u32 s13, s5, s11
	global_load_dword v31, v24, s[12:13]
	ds_read2st64_b32 v[0:1], v30 offset0:80 offset1:85
	ds_read2st64_b32 v[2:3], v30 offset0:90 offset1:95
	ds_read2st64_b32 v[4:5], v30 offset0:100 offset1:105
	ds_read2st64_b32 v[6:7], v30 offset0:110 offset1:115
	ds_read2st64_b32 v[8:9], v30 offset0:120 offset1:125
	ds_read2st64_b32 v[10:11], v30 offset0:130 offset1:135
	ds_read2st64_b32 v[12:13], v30 offset0:140 offset1:145
	ds_read2st64_b32 v[14:15], v30 offset0:150 offset1:155
	ds_read2st64_b32 v[16:17], v30 offset0:160 offset1:165
	ds_read2st64_b32 v[18:19], v30 offset0:170 offset1:175
	ds_read2st64_b32 v[26:27], v30 offset0:180 offset1:185
	ds_read2st64_b32 v[32:33], v30 offset0:190 offset1:195
	ds_read2st64_b32 v[34:35], v30 offset0:200 offset1:205
	ds_read2st64_b32 v[36:37], v30 offset0:210 offset1:215
	ds_read2st64_b32 v[38:39], v30 offset0:220 offset1:225
	ds_read2st64_b32 v[40:41], v30 offset0:230 offset1:235
	s_waitcnt lgkmcnt(14)
	v_add_f32_e32 v0, 0, v0
	v_add_f32_e32 v0, v0, v1
	v_add_f32_e32 v0, v0, v2
	v_add_f32_e32 v0, v0, v3
	s_waitcnt lgkmcnt(13)
	v_add_f32_e32 v0, v0, v4
	v_add_f32_e32 v0, v0, v5
	s_waitcnt lgkmcnt(12)
	v_add_f32_e32 v0, v0, v6
	v_add_f32_e32 v0, v0, v7
	s_waitcnt lgkmcnt(11)
	v_add_f32_e32 v0, v0, v8
	v_add_f32_e32 v0, v0, v9
	s_waitcnt lgkmcnt(10)
	v_add_f32_e32 v0, v0, v10
	v_add_f32_e32 v0, v0, v11
	s_waitcnt lgkmcnt(9)
	v_add_f32_e32 v0, v0, v12
	v_add_f32_e32 v0, v0, v13
	s_waitcnt lgkmcnt(8)
	v_add_f32_e32 v0, v0, v14
	v_add_f32_e32 v0, v0, v15
	s_waitcnt lgkmcnt(7)
	v_add_f32_e32 v0, v0, v16
	v_add_f32_e32 v0, v0, v17
	s_waitcnt lgkmcnt(6)
	v_add_f32_e32 v0, v0, v18
	v_add_f32_e32 v0, v0, v19
	s_waitcnt lgkmcnt(5)
	v_add_f32_e32 v0, v0, v26
	v_add_f32_e32 v0, v0, v27
	s_waitcnt lgkmcnt(4)
	v_add_f32_e32 v0, v0, v32
	v_add_f32_e32 v0, v0, v33
	s_waitcnt lgkmcnt(3)
	v_add_f32_e32 v0, v0, v34
	v_add_f32_e32 v0, v0, v35
	s_waitcnt lgkmcnt(2)
	v_add_f32_e32 v0, v0, v36
	v_add_f32_e32 v0, v0, v37
	v_mad_i64_i32 v[42:43], s[4:5], s4, 5, v[22:23]
	s_waitcnt lgkmcnt(1)
	v_add_f32_e32 v0, v0, v38
	v_mad_u64_u32 v[44:45], s[4:5], v42, s7, v[44:45]
	v_add_f32_e32 v0, v0, v39
	v_mad_i32_i24 v45, v43, s7, v45
	s_waitcnt lgkmcnt(0)
	v_add_f32_e32 v0, v0, v40
	v_lshl_add_u64 v[42:43], v[44:45], 0, s[10:11]
	v_add_f32_e32 v0, v0, v41
	s_waitcnt vmcnt(0)
	v_add_f32_e32 v2, v0, v31
	v_lshl_add_u64 v[0:1], v[42:43], 0, v[24:25]
	global_store_dword v[0:1], v2, off
	s_branch .LBB0_1491
